# all packed f32 VALU ops (v_pk_mul/add/fma_f32) split into two scalar f32 ops (bit-identical), on top of rstd lane-distribution and conv nw batching
# baseline (speedup 1.0000x reference)
; __global__ void __launch_bounds__(512, 2) fwd_megakernel(Args a) {
;     ...
;     for (int id = bx * 512 + tid; id < SEQ * 8; id += G * 512) { const int pos = id >> 3, i = id & 7;
;         const float inv = powf(500000.0f, -(float)(2 * i) / 16.0f); const float ang = (float)pos * inv; ropeC[id] = cosf(ang); ropeS[id] = sinf(ang); }
.LBB0_58:
	v_and_b32_e32 v15, 14, v1
	v_cvt_f32_ubyte0_e32 v15, v15
	v_mul_f32_e32 v15, 0xbd800000, v15
	v_cmp_eq_f32_e32 vcc, 0, v15
	v_ashrrev_i32_e32 v4, 3, v34
	v_cvt_f32_i32_e32 v4, v4
	v_cndmask_b32_e64 v26, v6, 1.0, vcc
	v_frexp_mant_f32_e32 v16, v26
	v_cmp_gt_f32_e64 s[0:1], s15, v16
	s_nop 1
	v_cndmask_b32_e64 v17, 1.0, 2.0, s[0:1]
	v_mul_f32_e32 v16, v16, v17
	v_add_f32_e32 v19, 1.0, v16
	v_rcp_f32_e32 v24, v19
	v_add_f32_e32 v17, -1.0, v19
	v_sub_f32_e32 v21, v16, v17
	v_add_f32_e32 v17, -1.0, v16
	v_mul_f32_e32 v25, v17, v24
	v_mul_f32_e32 v18, v19, v25
	v_fma_f32 v20, v25, v19, -v18
	v_fmac_f32_e32 v20, v25, v21
	v_add_f32_e32 v16, v18, v20
	v_sub_f32_e32 v19, v17, v16
	v_add_f32_e64 v22, v16, -v18
	v_add_f32_e64 v23, v17, -v19
	v_mov_b32_e32 v21, v16
	v_add_f32_e64 v16, v22, -v20
	v_add_f32_e64 v17, v23, -v21
	s_nop 0
	v_add_f32_e32 v16, v16, v17
	v_add_f32_e32 v16, v19, v16
	v_mul_f32_e32 v17, v24, v16
	v_add_f32_e32 v16, v25, v17
	v_sub_f32_e32 v18, v16, v25
	v_sub_f32_e32 v27, v17, v18
	v_mul_f32_e32 v17, v16, v16
	v_fma_f32 v19, v16, v16, -v17
	v_add_f32_e32 v18, v27, v27
	v_fmac_f32_e32 v19, v16, v18
	v_add_f32_e32 v18, v17, v19
	v_fmamk_f32 v20, v18, 0x3e76c4e1, v7
	v_fmaak_f32 v20, v18, v20, 0x3ecccdef
	v_sub_f32_e32 v17, v18, v17
	v_sub_f32_e32 v28, v19, v17
	v_mul_f32_e32 v17, v18, v20
	v_fma_f32 v19, v18, v20, -v17
	v_fmac_f32_e32 v19, v28, v20
	v_add_f32_e32 v20, v17, v19
	v_add_f32_e32 v21, 0x3f2aaaaa, v20
	v_sub_f32_e32 v17, v20, v17
	v_sub_f32_e32 v17, v19, v17
	v_add_f32_e32 v19, 0xbf2aaaaa, v21
	v_add_f32_e32 v17, 0x31739010, v17
	v_sub_f32_e32 v19, v20, v19
	v_mul_f32_e32 v22, v16, v18
	v_mul_f32_e32 v23, v17, v19
	v_add_f32_e32 v24, v16, v18
	v_add_f32_e32 v25, v17, v19
	v_fma_f32 v20, v18, v16, -v22
	v_fmac_f32_e32 v20, v18, v27
	v_mov_b32_e32 v23, v25
	v_fmac_f32_e32 v20, v28, v16
	v_add_f32_e32 v18, v22, v20
	v_add_f32_e32 v19, v23, v21
	v_ldexp_f32 v28, v27, 1
	v_sub_f32_e32 v17, v18, v22
	v_sub_f32_e32 v17, v20, v17
	v_sub_f32_e32 v20, v21, v19
	v_add_f32_e32 v24, v25, v20
	v_mul_f32_e32 v20, v18, v19
	v_mul_f32_e32 v21, v19, v18
	v_cvt_f64_f32_e32 v[22:23], v26
	v_frexp_exp_i32_f64_e32 v21, v[22:23]
	v_subbrev_co_u32_e64 v21, s[0:1], 0, v21, s[0:1]
	v_cvt_f32_i32_e32 v21, v21
	v_fma_f32 v22, v18, v19, -v20
	v_fmac_f32_e32 v22, v18, v24
	v_fmac_f32_e32 v22, v17, v19
	v_mul_f32_e32 v18, 0x3f317218, v21
	v_fma_f32 v24, v21, s26, -v18
	v_fmac_f32_e32 v24, 0xb102e308, v21
	v_ldexp_f32 v25, v16, 1
	v_add_f32_e32 v19, v20, v22
	v_add_f32_e32 v16, v18, v24
	v_add_f32_e32 v17, v19, v25
	v_mov_b32_e32 v26, v19
	v_mov_b32_e32 v27, v17
	v_mov_b32_e32 v21, v25
	v_add_f32_e64 v20, v26, -v20
	v_add_f32_e64 v21, v27, -v21
	v_mov_b32_e32 v23, v19
	v_add_f32_e64 v20, v22, -v20
	v_add_f32_e64 v21, v23, -v21
	v_mov_b32_e32 v25, v16
	v_add_f32_e32 v19, v28, v20
	v_add_f32_e32 v19, v19, v21
	v_add_f32_e64 v20, v16, -v18
	v_add_f32_e64 v21, v17, -v19
	v_add_f32_e32 v22, v16, v18
	v_add_f32_e32 v23, v17, v19
	v_mov_b32_e32 v18, v19
	v_mov_b32_e32 v21, v23
	v_add_f32_e64 v26, v24, -v20
	v_add_f32_e64 v27, v25, -v21
	v_add_f32_e32 v20, v24, v20
	v_add_f32_e32 v21, v25, v21
	v_mov_b32_e32 v19, v16
	v_add_f32_e64 v24, v21, -v16
	v_add_f32_e64 v25, v20, -v17
	v_add_f32_e64 v28, v22, -v24
	v_add_f32_e64 v29, v23, -v24
	v_mov_b32_e32 v22, v23
	v_mov_b32_e32 v23, v21
	v_pk_mov_b32 v[24:25], v[16:17], v[24:25] op_sel:[1,0]
	v_mov_b32_e32 v28, v26
	v_add_f32_e64 v22, v22, -v24
	v_add_f32_e64 v23, v23, -v25
	v_mov_b32_e32 v27, v21
	v_add_f32_e64 v16, v18, -v22
	v_add_f32_e64 v17, v19, -v23
	s_nop 0
	v_add_f32_e32 v18, v28, v16
	v_add_f32_e32 v19, v29, v17
	s_nop 0
	v_add_f32_e32 v22, v18, v19
	v_add_f32_e32 v23, v19, v18
	s_nop 0
	v_pk_add_f32 v[20:21], v[20:21], v[22:23] op_sel:[1,0] op_sel_hi:[0,1]
	v_mov_b32_e32 v19, v20
	v_add_f32_e64 v24, v18, -v26
	v_add_f32_e64 v25, v19, -v27
	v_mov_b32_e32 v17, v22
	v_sub_f32_e32 v18, v18, v24
	v_add_f32_e64 v16, v16, -v24
	v_add_f32_e64 v17, v17, -v25
	v_sub_f32_e32 v18, v26, v18
	v_add_f32_e32 v16, v16, v18
	v_add_f32_e32 v16, v16, v17
	v_add_f32_e32 v17, v20, v16
	v_sub_f32_e32 v18, v17, v20
	v_sub_f32_e32 v16, v16, v18
	v_mul_f32_e32 v18, v15, v17
	v_fma_f32 v17, v15, v17, -v18
	v_fmac_f32_e32 v17, v15, v16
	v_add_f32_e32 v16, v18, v17
	v_cmp_class_f32_e64 s[0:1], v18, s27
	v_sub_f32_e32 v19, v16, v18
	v_sub_f32_e32 v17, v17, v19
	v_cndmask_b32_e64 v16, v16, v18, s[0:1]
	v_cmp_eq_f32_e64 s[0:1], s35, v16
	s_nop 1
	v_cndmask_b32_e64 v18, 0, v8, s[0:1]
	v_sub_f32_e32 v19, v16, v18
	v_mul_f32_e32 v20, 0x3fb8aa3b, v19
	v_fma_f32 v21, v19, s36, -v20
	v_rndne_f32_e32 v22, v20
	v_fmac_f32_e32 v21, 0x32a5705f, v19
	v_sub_f32_e32 v20, v20, v22
	v_add_f32_e32 v20, v20, v21
	v_exp_f32_e32 v20, v20
	v_cvt_i32_f32_e32 v21, v22
	v_cmp_neq_f32_e64 s[0:1], |v16|, s33
	s_nop 1
	v_cndmask_b32_e64 v16, 0, v17, s[0:1]
	v_ldexp_f32 v17, v20, v21
	v_cmp_ngt_f32_e64 s[0:1], s37, v19
	v_add_f32_e32 v16, v18, v16
	s_nop 0
	v_cndmask_b32_e64 v17, 0, v17, s[0:1]
	v_cmp_nlt_f32_e64 s[0:1], s35, v19
	s_nop 1
	v_cndmask_b32_e64 v17, v9, v17, s[0:1]
	v_fma_f32 v16, v17, v16, v17
	v_cmp_class_f32_e64 s[0:1], v17, s27
	s_nop 1
	v_cndmask_b32_e64 v16, v16, v17, s[0:1]
	v_cmp_neq_f32_e64 s[0:1], v15, |v15|
	s_nop 1
	v_cndmask_b32_e64 v17, v9, 0, s[0:1]
	v_cndmask_b32_e64 v17, v17, 1.0, vcc
	v_cmp_class_f32_e64 s[0:1], v15, s27
	s_nop 1
	v_cndmask_b32_e64 v15, |v16|, v17, s[0:1]
	v_mul_f32_e32 v15, v15, v4
	v_and_b32_e32 v16, 0x7fffffff, v15
	v_lshrrev_b32_e32 v4, 23, v16
	v_and_b32_e32 v17, 0x7fffff, v16
	v_cmp_nlt_f32_e64 s[10:11], |v15|, s38
	v_add_u32_e32 v18, 0xffffff88, v4
	v_or_b32_e32 v17, 0x800000, v17
	s_and_saveexec_b64 s[0:1], s[10:11]
	s_xor_b64 s[24:25], exec, s[0:1]
	s_cbranch_execz .LBB0_60
; __global__ void __launch_bounds__(512, 2) fwd_megakernel(Args a) {
;     ...
;         const float inv = powf(500000.0f, -(float)(2 * i) / 16.0f); const float ang = (float)pos * inv; ropeC[id] = cosf(ang); ropeS[id] = sinf(ang); }
	v_cmp_lt_u32_e32 vcc, 63, v18
	v_mad_u64_u32 v[20:21], s[8:9], v17, s39, 0
	s_nop 0
	v_cndmask_b32_e32 v4, 0, v12, vcc
	v_add_u32_e32 v4, v4, v18
	v_cmp_lt_u32_e64 s[0:1], 31, v4
	s_nop 1
	v_cndmask_b32_e64 v19, 0, v13, s[0:1]
	v_add_u32_e32 v4, v19, v4
	v_cmp_lt_u32_e64 s[6:7], 31, v4
	s_nop 1
	v_cndmask_b32_e64 v19, 0, v13, s[6:7]
	v_add_u32_e32 v19, v19, v4
	v_mov_b32_e32 v4, v21
	v_mad_u64_u32 v[22:23], s[8:9], v17, s40, v[4:5]
	v_mov_b32_e32 v4, v23
	v_mad_u64_u32 v[24:25], s[8:9], v17, s41, v[4:5]
	v_mov_b32_e32 v4, v25
	v_mad_u64_u32 v[26:27], s[8:9], v17, s42, v[4:5]
	v_mov_b32_e32 v4, v27
	v_mad_u64_u32 v[28:29], s[8:9], v17, s43, v[4:5]
	v_mov_b32_e32 v4, v29
	v_mad_u64_u32 v[30:31], s[8:9], v17, s44, v[4:5]
	v_mov_b32_e32 v4, v31
	v_mad_u64_u32 v[32:33], s[8:9], v17, s45, v[4:5]
	v_cndmask_b32_e32 v21, v30, v26, vcc
	v_cndmask_b32_e32 v4, v32, v28, vcc
	v_cndmask_b32_e32 v25, v33, v30, vcc
	v_cndmask_b32_e64 v23, v4, v21, s[0:1]
	v_cndmask_b32_e64 v4, v25, v4, s[0:1]
	v_cndmask_b32_e32 v25, v28, v24, vcc
	v_cndmask_b32_e64 v21, v21, v25, s[0:1]
	v_sub_u32_e32 v27, 32, v19
	v_cmp_eq_u32_e64 s[8:9], 0, v19
	v_cndmask_b32_e32 v19, v26, v22, vcc
	v_cndmask_b32_e64 v4, v4, v23, s[6:7]
	v_cndmask_b32_e64 v23, v23, v21, s[6:7]
	v_cndmask_b32_e64 v22, v25, v19, s[0:1]
	v_alignbit_b32 v28, v4, v23, v27
	v_cndmask_b32_e64 v21, v21, v22, s[6:7]
	v_cndmask_b32_e64 v4, v28, v4, s[8:9]
	v_alignbit_b32 v25, v23, v21, v27
	v_cndmask_b32_e32 v20, v24, v20, vcc
	v_cndmask_b32_e64 v23, v25, v23, s[8:9]
	v_bfe_u32 v28, v4, 29, 1
	v_cndmask_b32_e64 v19, v19, v20, s[0:1]
	v_alignbit_b32 v25, v4, v23, 30
	v_sub_u32_e32 v29, 0, v28
	v_cndmask_b32_e64 v19, v22, v19, s[6:7]
	v_xor_b32_e32 v25, v25, v29
	v_alignbit_b32 v20, v21, v19, v27
	v_cndmask_b32_e64 v20, v20, v21, s[8:9]
	v_ffbh_u32_e32 v22, v25
	v_alignbit_b32 v21, v23, v20, 30
	v_min_u32_e32 v22, 32, v22
	v_alignbit_b32 v19, v20, v19, 30
	v_xor_b32_e32 v21, v21, v29
	v_sub_u32_e32 v23, 31, v22
	v_xor_b32_e32 v19, v19, v29
	v_alignbit_b32 v24, v25, v21, v23
	v_alignbit_b32 v19, v21, v19, v23
	v_alignbit_b32 v20, v24, v19, 9
	v_ffbh_u32_e32 v21, v20
	v_min_u32_e32 v21, 32, v21
	v_lshrrev_b32_e32 v26, 29, v4
	v_not_b32_e32 v23, v21
	v_alignbit_b32 v19, v20, v19, v23
	v_lshlrev_b32_e32 v20, 31, v26
	v_or_b32_e32 v23, 0x33000000, v20
	v_add_lshl_u32 v21, v21, v22, 23
	v_lshrrev_b32_e32 v19, 9, v19
	v_sub_u32_e32 v21, v23, v21
	v_or_b32_e32 v20, 0.5, v20
	v_lshlrev_b32_e32 v22, 23, v22
	v_or_b32_e32 v19, v21, v19
	v_lshrrev_b32_e32 v21, 9, v24
	v_sub_u32_e32 v20, v20, v22
	v_or_b32_e32 v20, v21, v20
	v_mul_f32_e32 v21, 0x3fc90fda, v20
	v_fma_f32 v22, v20, s46, -v21
	v_fmac_f32_e32 v22, 0x33a22168, v20
	v_fmac_f32_e32 v22, 0x3fc90fda, v19
	v_lshrrev_b32_e32 v4, 30, v4
	v_add_f32_e32 v20, v21, v22
	v_add_u32_e32 v19, v28, v4

; __device__ __forceinline__ float silu(float x) { return x * sigm(x); }
; __device__ __forceinline__ unsigned pkbf(float lo, float hi) { const f32x2_m v = {lo, hi}; const bf16x2_m b = __builtin_convertvector(v, bf16x2_m); return __builtin_bit_cast(unsigned, b); }
; template <int RSM> __device__ __forceinline__ float row_scale(const float* p, int row) { const float v = __hip_atomic_load(p + row, __ATOMIC_RELAXED, __HIP_MEMORY_SCOPE_AGENT); return RSM == 0 ? v : 1.0f / sqrtf(v * (1.f / DM) + EPS); }
;     __device__ __forceinline__ void operator()(const f32x4 (&acc)[2][2][4][2], const Unit& u, int wr, int wc, int fr, int fq) const {
;     ...
;             for (int m = 0; m < 4; ++m) { const int row = row0 + ai * HALF + m * 16; bf16* rowp = O + (size_t)row * ldc + col0; const float sc = row_scale<RSM>(rs, row);
;                 const f32x4 g0 = acc[ai][0][m][0] * sc, g1 = acc[ai][0][m][1] * sc, u0 = acc[ai][1][m][0] * sc, u1 = acc[ai][1][m][1] * sc;
;                 v4u w; w.x = pkbf(silu(g0[0]) * u0[0], silu(g0[1]) * u0[1]); w.y = pkbf(silu(g0[2]) * u0[2], silu(g0[3]) * u0[3]);
;                 w.z = pkbf(silu(g1[0]) * u1[0], silu(g1[1]) * u1[1]); w.w = pkbf(silu(g1[2]) * u1[2], silu(g1[3]) * u1[3]);
;                 *(v4u*)rowp = w; }
.LBB0_98:
	v_lshl_add_u32 v144, s50, 8, v152
	v_ashrrev_i32_e32 v145, 31, v144
	v_lshl_add_u64 v[150:151], v[144:145], 2, s[10:11]
	global_load_dword v158, v[150:151], off sc1
	v_or_b32_e32 v162, 16, v144
	v_ashrrev_i32_e32 v163, 31, v162
	v_lshl_add_u64 v[164:165], v[162:163], 2, s[10:11]
	v_lshl_or_b32 v148, s51, 7, v154
	v_mov_b64_e32 v[146:147], s[26:27]
	v_ashrrev_i32_e32 v149, 31, v148
	v_mad_i64_i32 v[160:161], s[0:1], v144, s47, v[146:147]
	v_lshlrev_b64 v[148:149], 1, v[148:149]
	v_lshl_add_u64 v[160:161], v[160:161], 0, v[148:149]
	s_andn2_b64 vcc, exec, s[6:7]
	s_waitcnt vmcnt(0)
	v_mul_f32_e32 v126, v126, v158
	v_mul_f32_e32 v127, v127, v158
	v_mul_f32_e32 v124, v124, v158
	v_mul_f32_e32 v125, v125, v158
	v_mul_f32_e32 v122, v122, v158
	v_mul_f32_e32 v123, v123, v158
	v_mul_f32_e32 v120, v120, v158
	v_mul_f32_e32 v121, v121, v158
	v_mul_f32_e32 v118, v118, v158
	v_mul_f32_e32 v119, v119, v158
	v_mul_f32_e32 v116, v116, v158
	v_mul_f32_e32 v117, v117, v158
	v_mul_f32_e32 v114, v114, v158
	v_mul_f32_e32 v115, v115, v158
	v_mul_f32_e32 v112, v112, v158
	v_mul_f32_e32 v113, v113, v158
	v_mul_f32_e32 v145, 0xbfb8aa3b, v124
	v_mul_f32_e32 v158, 0xbfb8aa3b, v125
	v_mul_f32_e32 v159, 0xbfb8aa3b, v126
	v_mul_f32_e32 v163, 0xbfb8aa3b, v127
	v_mul_f32_e32 v166, 0xbfb8aa3b, v120
	v_mul_f32_e32 v167, 0xbfb8aa3b, v121
	v_mul_f32_e32 v168, 0xbfb8aa3b, v122
	v_mul_f32_e32 v169, 0xbfb8aa3b, v123
	v_exp_f32_e32 v145, v145
	v_exp_f32_e32 v158, v158
	v_exp_f32_e32 v159, v159
	v_exp_f32_e32 v163, v163
	v_exp_f32_e32 v166, v166
	v_exp_f32_e32 v167, v167
	v_exp_f32_e32 v168, v168
	v_exp_f32_e32 v169, v169
	v_add_f32_e32 v145, 1.0, v145
	v_add_f32_e32 v170, 1.0, v158
	v_add_f32_e32 v171, 1.0, v159
	v_add_f32_e32 v163, 1.0, v163
	v_add_f32_e32 v172, 1.0, v166
	v_add_f32_e32 v173, 1.0, v167
	v_add_f32_e32 v174, 1.0, v168
	v_add_f32_e32 v175, 1.0, v169
	v_rcp_f32_e32 v158, v145
	v_rcp_f32_e32 v159, v170
	v_rcp_f32_e32 v166, v171
	v_rcp_f32_e32 v167, v163
	v_rcp_f32_e32 v168, v172
	v_rcp_f32_e32 v169, v173
	v_rcp_f32_e32 v170, v174
	v_rcp_f32_e32 v171, v175
	v_mul_f32_e32 v124, v124, v158
	v_mul_f32_e32 v125, v125, v159
	v_mul_f32_e32 v126, v126, v166
	v_mul_f32_e32 v127, v127, v167
	v_mul_f32_e32 v120, v120, v168
	v_mul_f32_e32 v121, v121, v169
	v_mul_f32_e32 v122, v122, v170
	v_mul_f32_e32 v123, v123, v171
	v_mul_f32_e32 v116, v116, v124
	v_mul_f32_e32 v117, v117, v125
	v_mul_f32_e32 v118, v118, v126
	v_mul_f32_e32 v119, v119, v127
	v_mul_f32_e32 v120, v112, v120
	v_mul_f32_e32 v121, v113, v121
	v_mul_f32_e32 v122, v114, v122
	v_mul_f32_e32 v123, v115, v123
	v_cvt_pk_bf16_f32 v112, v116, v117
	v_cvt_pk_bf16_f32 v113, v118, v119
	v_cvt_pk_bf16_f32 v114, v120, v121
	v_cvt_pk_bf16_f32 v115, v122, v123
	global_store_dwordx4 v[160:161], v[112:115], off
	global_load_dword v112, v[164:165], off sc1
	v_mad_i64_i32 v[116:117], s[0:1], v162, s47, v[146:147]
	v_or_b32_e32 v114, 32, v144
	v_ashrrev_i32_e32 v115, 31, v114
	v_lshl_add_u64 v[118:119], v[114:115], 2, s[10:11]
	v_lshl_add_u64 v[116:117], v[116:117], 0, v[148:149]
	s_waitcnt vmcnt(0)
	v_mul_f32_e32 v110, v110, v112
	v_mul_f32_e32 v111, v111, v112
	v_mul_f32_e32 v108, v108, v112
	v_mul_f32_e32 v109, v109, v112
	v_mul_f32_e32 v106, v106, v112
	v_mul_f32_e32 v107, v107, v112
	v_mul_f32_e32 v104, v104, v112
	v_mul_f32_e32 v105, v105, v112
	v_mul_f32_e32 v102, v102, v112
	v_mul_f32_e32 v103, v103, v112
	v_mul_f32_e32 v100, v100, v112
	v_mul_f32_e32 v101, v101, v112
	v_mul_f32_e32 v98, v98, v112
	v_mul_f32_e32 v99, v99, v112
	v_mul_f32_e32 v96, v96, v112
	v_mul_f32_e32 v97, v97, v112
	v_mul_f32_e32 v112, 0xbfb8aa3b, v108
	v_mul_f32_e32 v113, 0xbfb8aa3b, v109
	v_mul_f32_e32 v115, 0xbfb8aa3b, v110
	v_mul_f32_e32 v120, 0xbfb8aa3b, v111
	v_mul_f32_e32 v121, 0xbfb8aa3b, v104
	v_mul_f32_e32 v122, 0xbfb8aa3b, v105
	v_mul_f32_e32 v123, 0xbfb8aa3b, v106
	v_mul_f32_e32 v124, 0xbfb8aa3b, v107
	v_exp_f32_e32 v112, v112
	v_exp_f32_e32 v113, v113
	v_exp_f32_e32 v115, v115
	v_exp_f32_e32 v120, v120
	v_exp_f32_e32 v121, v121
	v_exp_f32_e32 v122, v122
	v_exp_f32_e32 v123, v123
	v_exp_f32_e32 v124, v124
	v_add_f32_e32 v112, 1.0, v112
	v_add_f32_e32 v113, 1.0, v113
	v_add_f32_e32 v115, 1.0, v115
	v_add_f32_e32 v125, 1.0, v120
	v_add_f32_e32 v126, 1.0, v121
	v_add_f32_e32 v127, 1.0, v122
	v_add_f32_e32 v145, 1.0, v123
	v_add_f32_e32 v158, 1.0, v124
	v_rcp_f32_e32 v112, v112
	v_rcp_f32_e32 v113, v113
	v_rcp_f32_e32 v120, v115
	v_rcp_f32_e32 v121, v125
	v_rcp_f32_e32 v122, v126
	v_rcp_f32_e32 v123, v127
	v_rcp_f32_e32 v124, v145
	v_rcp_f32_e32 v125, v158
	v_mul_f32_e32 v108, v108, v112
	v_mul_f32_e32 v109, v109, v113
	v_mul_f32_e32 v110, v110, v120
	v_mul_f32_e32 v111, v111, v121
	v_mul_f32_e32 v104, v104, v122
	v_mul_f32_e32 v105, v105, v123
	v_mul_f32_e32 v106, v106, v124
	v_mul_f32_e32 v107, v107, v125
	v_mul_f32_e32 v100, v100, v108
	v_mul_f32_e32 v101, v101, v109
	v_mul_f32_e32 v102, v102, v110
	v_mul_f32_e32 v103, v103, v111
	v_mul_f32_e32 v104, v96, v104
	v_mul_f32_e32 v105, v97, v105
	v_mul_f32_e32 v106, v98, v106
	v_mul_f32_e32 v107, v99, v107
	v_cvt_pk_bf16_f32 v96, v100, v101
	v_cvt_pk_bf16_f32 v97, v102, v103
	v_cvt_pk_bf16_f32 v98, v104, v105
	v_cvt_pk_bf16_f32 v99, v106, v107
	global_store_dwordx4 v[116:117], v[96:99], off
	global_load_dword v96, v[118:119], off sc1
	v_mad_i64_i32 v[100:101], s[0:1], v114, s47, v[146:147]
	v_or_b32_e32 v98, 48, v144
	v_ashrrev_i32_e32 v99, 31, v98
	v_lshl_add_u64 v[102:103], v[98:99], 2, s[10:11]
	v_lshl_add_u64 v[100:101], v[100:101], 0, v[148:149]
	s_waitcnt vmcnt(0)
; __device__ __forceinline__ float silu(float x) { return x * sigm(x); }
; __device__ __forceinline__ unsigned pkbf(float lo, float hi) { const f32x2_m v = {lo, hi}; const bf16x2_m b = __builtin_convertvector(v, bf16x2_m); return __builtin_bit_cast(unsigned, b); }
; template <int RSM> __device__ __forceinline__ float row_scale(const float* p, int row) { const float v = __hip_atomic_load(p + row, __ATOMIC_RELAXED, __HIP_MEMORY_SCOPE_AGENT); return RSM == 0 ? v : 1.0f / sqrtf(v * (1.f / DM) + EPS); }
;     __device__ __forceinline__ void operator()(const f32x4 (&acc)[2][2][4][2], const Unit& u, int wr, int wc, int fr, int fq) const {
;     ...
;             for (int m = 0; m < 4; ++m) { const int row = row0 + ai * HALF + m * 16; bf16* rowp = O + (size_t)row * ldc + col0; const float sc = row_scale<RSM>(rs, row);
;                 const f32x4 g0 = acc[ai][0][m][0] * sc, g1 = acc[ai][0][m][1] * sc, u0 = acc[ai][1][m][0] * sc, u1 = acc[ai][1][m][1] * sc;
;                 v4u w; w.x = pkbf(silu(g0[0]) * u0[0], silu(g0[1]) * u0[1]); w.y = pkbf(silu(g0[2]) * u0[2], silu(g0[3]) * u0[3]);
;                 w.z = pkbf(silu(g1[0]) * u1[0], silu(g1[1]) * u1[1]); w.w = pkbf(silu(g1[2]) * u1[2], silu(g1[3]) * u1[3]);
;                 *(v4u*)rowp = w; }
	v_mul_f32_e32 v94, v94, v96
	v_mul_f32_e32 v95, v95, v96
	v_mul_f32_e32 v92, v92, v96
	v_mul_f32_e32 v93, v93, v96
	v_mul_f32_e32 v90, v90, v96
	v_mul_f32_e32 v91, v91, v96
	v_mul_f32_e32 v88, v88, v96
	v_mul_f32_e32 v89, v89, v96
	v_mul_f32_e32 v86, v86, v96
	v_mul_f32_e32 v87, v87, v96
	v_mul_f32_e32 v84, v84, v96
	v_mul_f32_e32 v85, v85, v96
	v_mul_f32_e32 v82, v82, v96
	v_mul_f32_e32 v83, v83, v96
	v_mul_f32_e32 v80, v80, v96
	v_mul_f32_e32 v81, v81, v96
	v_mul_f32_e32 v96, 0xbfb8aa3b, v92
	v_mul_f32_e32 v97, 0xbfb8aa3b, v93
	v_mul_f32_e32 v99, 0xbfb8aa3b, v94
	v_mul_f32_e32 v104, 0xbfb8aa3b, v95
	v_mul_f32_e32 v105, 0xbfb8aa3b, v88
	v_mul_f32_e32 v106, 0xbfb8aa3b, v89
	v_mul_f32_e32 v107, 0xbfb8aa3b, v90
	v_mul_f32_e32 v108, 0xbfb8aa3b, v91
	v_exp_f32_e32 v96, v96
	v_exp_f32_e32 v97, v97
	v_exp_f32_e32 v99, v99
	v_exp_f32_e32 v104, v104
	v_exp_f32_e32 v105, v105
	v_exp_f32_e32 v106, v106
	v_exp_f32_e32 v107, v107
	v_exp_f32_e32 v108, v108
	v_add_f32_e32 v96, 1.0, v96
	v_add_f32_e32 v97, 1.0, v97
	v_add_f32_e32 v99, 1.0, v99
	v_add_f32_e32 v109, 1.0, v104
	v_add_f32_e32 v110, 1.0, v105
	v_add_f32_e32 v111, 1.0, v106
	v_add_f32_e32 v112, 1.0, v107
	v_add_f32_e32 v113, 1.0, v108
	v_rcp_f32_e32 v96, v96
	v_rcp_f32_e32 v97, v97
	v_rcp_f32_e32 v104, v99
	v_rcp_f32_e32 v105, v109
	v_rcp_f32_e32 v106, v110
	v_rcp_f32_e32 v107, v111
	v_rcp_f32_e32 v108, v112
	v_rcp_f32_e32 v109, v113
	v_mul_f32_e32 v92, v92, v96
	v_mul_f32_e32 v93, v93, v97
	v_mul_f32_e32 v94, v94, v104
	v_mul_f32_e32 v95, v95, v105
	v_mul_f32_e32 v88, v88, v106
	v_mul_f32_e32 v89, v89, v107
	v_mul_f32_e32 v90, v90, v108
	v_mul_f32_e32 v91, v91, v109
	v_mul_f32_e32 v84, v84, v92
	v_mul_f32_e32 v85, v85, v93
	v_mul_f32_e32 v86, v86, v94
	v_mul_f32_e32 v87, v87, v95
	v_mul_f32_e32 v88, v80, v88
	v_mul_f32_e32 v89, v81, v89
	v_mul_f32_e32 v90, v82, v90
	v_mul_f32_e32 v91, v83, v91
	v_cvt_pk_bf16_f32 v80, v84, v85
	v_cvt_pk_bf16_f32 v81, v86, v87
	v_cvt_pk_bf16_f32 v82, v88, v89
	v_cvt_pk_bf16_f32 v83, v90, v91
	global_store_dwordx4 v[100:101], v[80:83], off
	global_load_dword v80, v[102:103], off sc1
	s_waitcnt vmcnt(0)
	v_mul_f32_e32 v78, v78, v80
	v_mul_f32_e32 v79, v79, v80
	v_mul_f32_e32 v76, v76, v80
	v_mul_f32_e32 v77, v77, v80
	v_mul_f32_e32 v74, v74, v80
	v_mul_f32_e32 v75, v75, v80
	v_mul_f32_e32 v72, v72, v80
	v_mul_f32_e32 v73, v73, v80
	v_mul_f32_e32 v70, v70, v80
	v_mul_f32_e32 v71, v71, v80
	v_mul_f32_e32 v68, v68, v80
	v_mul_f32_e32 v69, v69, v80
	v_mul_f32_e32 v66, v66, v80
	v_mul_f32_e32 v67, v67, v80
	v_mul_f32_e32 v64, v64, v80
	v_mul_f32_e32 v65, v65, v80
	v_mul_f32_e32 v80, 0xbfb8aa3b, v76
	v_mul_f32_e32 v81, 0xbfb8aa3b, v77
	v_mul_f32_e32 v84, 0xbfb8aa3b, v78
	v_mul_f32_e32 v85, 0xbfb8aa3b, v79
	v_mul_f32_e32 v86, 0xbfb8aa3b, v72
	v_mul_f32_e32 v87, 0xbfb8aa3b, v73
	v_mul_f32_e32 v88, 0xbfb8aa3b, v74
	v_mul_f32_e32 v89, 0xbfb8aa3b, v75
	v_exp_f32_e32 v80, v80
	v_exp_f32_e32 v81, v81
	v_exp_f32_e32 v84, v84
	v_exp_f32_e32 v85, v85
	v_exp_f32_e32 v86, v86
	v_exp_f32_e32 v87, v87
	v_exp_f32_e32 v88, v88
	v_exp_f32_e32 v89, v89
	v_add_f32_e32 v80, 1.0, v80
	v_add_f32_e32 v81, 1.0, v81
	v_add_f32_e32 v84, 1.0, v84
	v_add_f32_e32 v85, 1.0, v85
	v_add_f32_e32 v86, 1.0, v86
	v_add_f32_e32 v87, 1.0, v87
	v_add_f32_e32 v88, 1.0, v88
	v_add_f32_e32 v89, 1.0, v89
	v_rcp_f32_e32 v80, v80
	v_rcp_f32_e32 v81, v81
	v_rcp_f32_e32 v84, v84
	v_rcp_f32_e32 v85, v85
	v_rcp_f32_e32 v86, v86
	v_rcp_f32_e32 v87, v87
	v_rcp_f32_e32 v88, v88
	v_rcp_f32_e32 v89, v89
	v_mul_f32_e32 v76, v76, v80
	v_mul_f32_e32 v77, v77, v81
	v_mul_f32_e32 v78, v78, v84
	v_mul_f32_e32 v79, v79, v85
	v_mul_f32_e32 v72, v72, v86
	v_mul_f32_e32 v73, v73, v87
	v_mul_f32_e32 v74, v74, v88
	v_mul_f32_e32 v75, v75, v89
	v_mad_i64_i32 v[82:83], s[0:1], v98, s47, v[146:147]
	v_mul_f32_e32 v68, v68, v76
	v_mul_f32_e32 v69, v69, v77
	v_mul_f32_e32 v70, v70, v78
	v_mul_f32_e32 v71, v71, v79
	v_mul_f32_e32 v72, v64, v72
	v_mul_f32_e32 v73, v65, v73
	v_mul_f32_e32 v74, v66, v74
	v_mul_f32_e32 v75, v67, v75
	v_lshl_add_u64 v[82:83], v[82:83], 0, v[148:149]
	v_cvt_pk_bf16_f32 v64, v68, v69
	v_cvt_pk_bf16_f32 v65, v70, v71
	v_cvt_pk_bf16_f32 v66, v72, v73
	v_cvt_pk_bf16_f32 v67, v74, v75
	global_store_dwordx4 v[82:83], v[64:67], off
	global_load_dword v64, v[150:151], off offset:512 sc1
	s_nop 0
	v_add_u32_e32 v65, 0x80, v144
	v_mad_i64_i32 v[66:67], s[0:1], v65, s47, v[146:147]
	v_lshl_add_u64 v[66:67], v[66:67], 0, v[148:149]
	s_waitcnt vmcnt(0)
	v_mul_f32_e32 v62, v62, v64
	v_mul_f32_e32 v63, v63, v64
	v_mul_f32_e32 v60, v60, v64
	v_mul_f32_e32 v61, v61, v64
	v_mul_f32_e32 v58, v58, v64
	v_mul_f32_e32 v59, v59, v64
	v_mul_f32_e32 v56, v56, v64
	v_mul_f32_e32 v57, v57, v64
	v_mul_f32_e32 v54, v54, v64
	v_mul_f32_e32 v55, v55, v64
	v_mul_f32_e32 v52, v52, v64
	v_mul_f32_e32 v53, v53, v64
	v_mul_f32_e32 v50, v50, v64
	v_mul_f32_e32 v51, v51, v64
	v_mul_f32_e32 v48, v48, v64
	v_mul_f32_e32 v49, v49, v64
	v_mul_f32_e32 v64, 0xbfb8aa3b, v60
	v_mul_f32_e32 v65, 0xbfb8aa3b, v61
	v_mul_f32_e32 v68, 0xbfb8aa3b, v62
	v_mul_f32_e32 v69, 0xbfb8aa3b, v63
	v_mul_f32_e32 v70, 0xbfb8aa3b, v56
	v_mul_f32_e32 v71, 0xbfb8aa3b, v57
	v_mul_f32_e32 v72, 0xbfb8aa3b, v58
	v_mul_f32_e32 v73, 0xbfb8aa3b, v59
	v_exp_f32_e32 v64, v64
	v_exp_f32_e32 v65, v65
	v_exp_f32_e32 v68, v68
	v_exp_f32_e32 v69, v69
	v_exp_f32_e32 v70, v70
	v_exp_f32_e32 v71, v71
	v_exp_f32_e32 v72, v72
	v_exp_f32_e32 v73, v73
	v_add_f32_e32 v64, 1.0, v64
	v_add_f32_e32 v65, 1.0, v65
	v_add_f32_e32 v68, 1.0, v68
	v_add_f32_e32 v69, 1.0, v69
	v_add_f32_e32 v70, 1.0, v70
	v_add_f32_e32 v71, 1.0, v71
	v_add_f32_e32 v72, 1.0, v72
	v_add_f32_e32 v73, 1.0, v73
	v_rcp_f32_e32 v64, v64
	v_rcp_f32_e32 v65, v65
	v_rcp_f32_e32 v68, v68
	v_rcp_f32_e32 v69, v69
	v_rcp_f32_e32 v70, v70
	v_rcp_f32_e32 v71, v71
	v_rcp_f32_e32 v72, v72
	v_rcp_f32_e32 v73, v73
	v_mul_f32_e32 v60, v60, v64
	v_mul_f32_e32 v61, v61, v65
	v_mul_f32_e32 v62, v62, v68
	v_mul_f32_e32 v63, v63, v69
	v_mul_f32_e32 v56, v56, v70
	v_mul_f32_e32 v57, v57, v71
	v_mul_f32_e32 v58, v58, v72
	v_mul_f32_e32 v59, v59, v73
	v_mul_f32_e32 v52, v52, v60
	v_mul_f32_e32 v53, v53, v61
	v_mul_f32_e32 v54, v54, v62
	v_mul_f32_e32 v55, v55, v63
	v_mul_f32_e32 v56, v48, v56
	v_mul_f32_e32 v57, v49, v57
	v_mul_f32_e32 v58, v50, v58
	v_mul_f32_e32 v59, v51, v59
	v_cvt_pk_bf16_f32 v48, v52, v53
	v_cvt_pk_bf16_f32 v49, v54, v55
	v_cvt_pk_bf16_f32 v50, v56, v57
	v_cvt_pk_bf16_f32 v51, v58, v59
	global_store_dwordx4 v[66:67], v[48:51], off
	global_load_dword v48, v[150:151], off offset:576 sc1
	s_nop 0
	v_add_u32_e32 v49, 0x90, v144
	v_mad_i64_i32 v[50:51], s[0:1], v49, s47, v[146:147]
	v_lshl_add_u64 v[50:51], v[50:51], 0, v[148:149]
	s_waitcnt vmcnt(0)
; #define PG8_BAR __builtin_amdgcn_s_barrier()
; __device__ __forceinline__ float silu(float x) { return x * sigm(x); }
; __device__ __forceinline__ unsigned pkbf(float lo, float hi) { const f32x2_m v = {lo, hi}; const bf16x2_m b = __builtin_convertvector(v, bf16x2_m); return __builtin_bit_cast(unsigned, b); }
; template <int RSM> __device__ __forceinline__ float row_scale(const float* p, int row) { const float v = __hip_atomic_load(p + row, __ATOMIC_RELAXED, __HIP_MEMORY_SCOPE_AGENT); return RSM == 0 ? v : 1.0f / sqrtf(v * (1.f / DM) + EPS); }
; template <class Epi, class Sched, bool ALIGN_EPI = false, bool SP2 = false>
; __device__ __forceinline__ void gemm_phase(PG8_LAS unsigned char* lds, const Gemm g, const Sched& S, const Epi& E) {
;     ...
;         if constexpr (ALIGN_EPI) { if (wr == 0) PG8_BAR; }
;         if constexpr (!Epi::AFTER_DRAIN) { E(acc, cur, wr, wc, fr, fq); S.done(cur); }
;         if (!has_next) break;
; #pragma unroll
;         for (int a = 0; a < 2; ++a)
; #pragma unroll
;             for (int b = 0; b < 2; ++b)
; #pragma unroll
;                 for (int m = 0; m < 4; ++m)
; #pragma unroll
;                     for (int n = 0; n < 2; ++n) acc[a][b][m][n] = (f32x4){0.f, 0.f, 0.f, 0.f};
;         cur = nxt; cA = nA; cB = nB; ++ui;
;         if constexpr (ALIGN_EPI) { if (wr == 1) PG8_BAR; }
;     __device__ __forceinline__ void operator()(const f32x4 (&acc)[2][2][4][2], const Unit& u, int wr, int wc, int fr, int fq) const {
;     ...
;             for (int m = 0; m < 4; ++m) { const int row = row0 + ai * HALF + m * 16; bf16* rowp = O + (size_t)row * ldc + col0; const float sc = row_scale<RSM>(rs, row);
;                 const f32x4 g0 = acc[ai][0][m][0] * sc, g1 = acc[ai][0][m][1] * sc, u0 = acc[ai][1][m][0] * sc, u1 = acc[ai][1][m][1] * sc;
;                 v4u w; w.x = pkbf(silu(g0[0]) * u0[0], silu(g0[1]) * u0[1]); w.y = pkbf(silu(g0[2]) * u0[2], silu(g0[3]) * u0[3]);
;                 w.z = pkbf(silu(g1[0]) * u1[0], silu(g1[1]) * u1[1]); w.w = pkbf(silu(g1[2]) * u1[2], silu(g1[3]) * u1[3]);
;                 *(v4u*)rowp = w; }
	v_mul_f32_e32 v46, v46, v48
	v_mul_f32_e32 v47, v47, v48
	v_mul_f32_e32 v44, v44, v48
	v_mul_f32_e32 v45, v45, v48
	v_mul_f32_e32 v42, v42, v48
	v_mul_f32_e32 v43, v43, v48
	v_mul_f32_e32 v40, v40, v48
	v_mul_f32_e32 v41, v41, v48
	v_mul_f32_e32 v38, v38, v48
	v_mul_f32_e32 v39, v39, v48
	v_mul_f32_e32 v36, v36, v48
	v_mul_f32_e32 v37, v37, v48
	v_mul_f32_e32 v34, v34, v48
	v_mul_f32_e32 v35, v35, v48
	v_mul_f32_e32 v32, v32, v48
	v_mul_f32_e32 v33, v33, v48
	v_mul_f32_e32 v48, 0xbfb8aa3b, v44
	v_mul_f32_e32 v49, 0xbfb8aa3b, v45
	v_mul_f32_e32 v52, 0xbfb8aa3b, v46
	v_mul_f32_e32 v53, 0xbfb8aa3b, v47
	v_mul_f32_e32 v54, 0xbfb8aa3b, v40
	v_mul_f32_e32 v55, 0xbfb8aa3b, v41
	v_mul_f32_e32 v56, 0xbfb8aa3b, v42
	v_mul_f32_e32 v57, 0xbfb8aa3b, v43
	v_exp_f32_e32 v48, v48
	v_exp_f32_e32 v49, v49
	v_exp_f32_e32 v52, v52
	v_exp_f32_e32 v53, v53
	v_exp_f32_e32 v54, v54
	v_exp_f32_e32 v55, v55
	v_exp_f32_e32 v56, v56
	v_exp_f32_e32 v57, v57
	v_add_f32_e32 v48, 1.0, v48
	v_add_f32_e32 v49, 1.0, v49
	v_add_f32_e32 v52, 1.0, v52
	v_add_f32_e32 v53, 1.0, v53
	v_add_f32_e32 v54, 1.0, v54
	v_add_f32_e32 v55, 1.0, v55
	v_add_f32_e32 v56, 1.0, v56
	v_add_f32_e32 v57, 1.0, v57
	v_rcp_f32_e32 v48, v48
	v_rcp_f32_e32 v49, v49
	v_rcp_f32_e32 v52, v52
	v_rcp_f32_e32 v53, v53
	v_rcp_f32_e32 v54, v54
	v_rcp_f32_e32 v55, v55
	v_rcp_f32_e32 v56, v56
	v_rcp_f32_e32 v57, v57
	v_mul_f32_e32 v44, v44, v48
	v_mul_f32_e32 v45, v45, v49
	v_mul_f32_e32 v46, v46, v52
	v_mul_f32_e32 v47, v47, v53
	v_mul_f32_e32 v40, v40, v54
	v_mul_f32_e32 v41, v41, v55
	v_mul_f32_e32 v42, v42, v56
	v_mul_f32_e32 v43, v43, v57
	v_mul_f32_e32 v36, v36, v44
	v_mul_f32_e32 v37, v37, v45
	v_mul_f32_e32 v38, v38, v46
	v_mul_f32_e32 v39, v39, v47
	v_mul_f32_e32 v40, v32, v40
	v_mul_f32_e32 v41, v33, v41
	v_mul_f32_e32 v42, v34, v42
	v_mul_f32_e32 v43, v35, v43
	v_cvt_pk_bf16_f32 v32, v36, v37
	v_cvt_pk_bf16_f32 v33, v38, v39
	v_cvt_pk_bf16_f32 v34, v40, v41
	v_cvt_pk_bf16_f32 v35, v42, v43
	global_store_dwordx4 v[50:51], v[32:35], off
	global_load_dword v32, v[150:151], off offset:640 sc1
	s_nop 0
	v_add_u32_e32 v33, 0xa0, v144
	v_mad_i64_i32 v[34:35], s[0:1], v33, s47, v[146:147]
	v_lshl_add_u64 v[34:35], v[34:35], 0, v[148:149]
	s_waitcnt vmcnt(0)
	v_mul_f32_e32 v30, v30, v32
	v_mul_f32_e32 v31, v31, v32
	v_mul_f32_e32 v28, v28, v32
	v_mul_f32_e32 v29, v29, v32
	v_mul_f32_e32 v26, v26, v32
	v_mul_f32_e32 v27, v27, v32
	v_mul_f32_e32 v24, v24, v32
	v_mul_f32_e32 v25, v25, v32
	v_mul_f32_e32 v22, v22, v32
	v_mul_f32_e32 v23, v23, v32
	v_mul_f32_e32 v20, v20, v32
	v_mul_f32_e32 v21, v21, v32
	v_mul_f32_e32 v18, v18, v32
	v_mul_f32_e32 v19, v19, v32
	v_mul_f32_e32 v16, v16, v32
	v_mul_f32_e32 v17, v17, v32
	v_mul_f32_e32 v32, 0xbfb8aa3b, v28
	v_mul_f32_e32 v33, 0xbfb8aa3b, v29
	v_mul_f32_e32 v36, 0xbfb8aa3b, v30
	v_mul_f32_e32 v37, 0xbfb8aa3b, v31
	v_mul_f32_e32 v38, 0xbfb8aa3b, v24
	v_mul_f32_e32 v39, 0xbfb8aa3b, v25
	v_mul_f32_e32 v40, 0xbfb8aa3b, v26
	v_mul_f32_e32 v41, 0xbfb8aa3b, v27
	v_exp_f32_e32 v32, v32
	v_exp_f32_e32 v33, v33
	v_exp_f32_e32 v36, v36
	v_exp_f32_e32 v37, v37
	v_exp_f32_e32 v38, v38
	v_exp_f32_e32 v39, v39
	v_exp_f32_e32 v40, v40
	v_exp_f32_e32 v41, v41
	v_add_f32_e32 v32, 1.0, v32
	v_add_f32_e32 v33, 1.0, v33
	v_add_f32_e32 v36, 1.0, v36
	v_add_f32_e32 v37, 1.0, v37
	v_add_f32_e32 v38, 1.0, v38
	v_add_f32_e32 v39, 1.0, v39
	v_add_f32_e32 v40, 1.0, v40
	v_add_f32_e32 v41, 1.0, v41
	v_rcp_f32_e32 v32, v32
	v_rcp_f32_e32 v33, v33
	v_rcp_f32_e32 v36, v36
	v_rcp_f32_e32 v37, v37
	v_rcp_f32_e32 v38, v38
	v_rcp_f32_e32 v39, v39
	v_rcp_f32_e32 v40, v40
	v_rcp_f32_e32 v41, v41
	v_mul_f32_e32 v28, v28, v32
	v_mul_f32_e32 v29, v29, v33
	v_mul_f32_e32 v30, v30, v36
	v_mul_f32_e32 v31, v31, v37
	v_mul_f32_e32 v24, v24, v38
	v_mul_f32_e32 v25, v25, v39
	v_mul_f32_e32 v26, v26, v40
	v_mul_f32_e32 v27, v27, v41
	v_mul_f32_e32 v20, v20, v28
	v_mul_f32_e32 v21, v21, v29
	v_mul_f32_e32 v22, v22, v30
	v_mul_f32_e32 v23, v23, v31
	v_mul_f32_e32 v24, v16, v24
	v_mul_f32_e32 v25, v17, v25
	v_mul_f32_e32 v26, v18, v26
	v_mul_f32_e32 v27, v19, v27
	v_cvt_pk_bf16_f32 v16, v20, v21
	v_cvt_pk_bf16_f32 v17, v22, v23
	v_cvt_pk_bf16_f32 v18, v24, v25
	v_cvt_pk_bf16_f32 v19, v26, v27
	global_store_dwordx4 v[34:35], v[16:19], off
	global_load_dword v16, v[150:151], off offset:704 sc1
	s_nop 0
	v_add_u32_e32 v17, 0xb0, v144
	v_mad_i64_i32 v[18:19], s[0:1], v17, s47, v[146:147]
	v_lshl_add_u64 v[18:19], v[18:19], 0, v[148:149]
	s_mov_b64 s[0:1], -1
	s_waitcnt vmcnt(0)
	v_mul_f32_e32 v14, v14, v16
	v_mul_f32_e32 v15, v15, v16
	v_mul_f32_e32 v12, v12, v16
	v_mul_f32_e32 v13, v13, v16
	v_mul_f32_e32 v10, v10, v16
	v_mul_f32_e32 v11, v11, v16
	v_mul_f32_e32 v8, v8, v16
	v_mul_f32_e32 v9, v9, v16
	v_mul_f32_e32 v6, v6, v16
	v_mul_f32_e32 v7, v7, v16
	v_mul_f32_e32 v4, v4, v16
	v_mul_f32_e32 v5, v5, v16
	v_mul_f32_e32 v2, v2, v16
	v_mul_f32_e32 v3, v3, v16
	v_mul_f32_e32 v0, v0, v16
	v_mul_f32_e32 v1, v1, v16
	v_mul_f32_e32 v16, 0xbfb8aa3b, v12
	v_mul_f32_e32 v17, 0xbfb8aa3b, v13
	v_mul_f32_e32 v20, 0xbfb8aa3b, v14
	v_mul_f32_e32 v21, 0xbfb8aa3b, v15
	v_mul_f32_e32 v22, 0xbfb8aa3b, v8
	v_mul_f32_e32 v23, 0xbfb8aa3b, v9
	v_mul_f32_e32 v24, 0xbfb8aa3b, v10
	v_mul_f32_e32 v25, 0xbfb8aa3b, v11
	v_exp_f32_e32 v16, v16
	v_exp_f32_e32 v17, v17
	v_exp_f32_e32 v20, v20
	v_exp_f32_e32 v21, v21
	v_exp_f32_e32 v22, v22
	v_exp_f32_e32 v23, v23
	v_exp_f32_e32 v24, v24
	v_exp_f32_e32 v25, v25
	v_add_f32_e32 v16, 1.0, v16
	v_add_f32_e32 v17, 1.0, v17
	v_add_f32_e32 v20, 1.0, v20
	v_add_f32_e32 v21, 1.0, v21
	v_add_f32_e32 v22, 1.0, v22
	v_add_f32_e32 v23, 1.0, v23
	v_add_f32_e32 v24, 1.0, v24
	v_add_f32_e32 v25, 1.0, v25
	v_rcp_f32_e32 v16, v16
	v_rcp_f32_e32 v17, v17
	v_rcp_f32_e32 v20, v20
	v_rcp_f32_e32 v21, v21
	v_rcp_f32_e32 v22, v22
	v_rcp_f32_e32 v23, v23
	v_rcp_f32_e32 v24, v24
	v_rcp_f32_e32 v25, v25
	v_mul_f32_e32 v12, v12, v16
	v_mul_f32_e32 v13, v13, v17
	v_mul_f32_e32 v14, v14, v20
	v_mul_f32_e32 v15, v15, v21
	v_mul_f32_e32 v8, v8, v22
	v_mul_f32_e32 v9, v9, v23
	v_mul_f32_e32 v10, v10, v24
	v_mul_f32_e32 v11, v11, v25
	v_mul_f32_e32 v4, v4, v12
	v_mul_f32_e32 v5, v5, v13
	v_mul_f32_e32 v6, v6, v14
	v_mul_f32_e32 v7, v7, v15
	v_mul_f32_e32 v8, v0, v8
	v_mul_f32_e32 v9, v1, v9
	v_mul_f32_e32 v10, v2, v10
	v_mul_f32_e32 v11, v3, v11
	v_cvt_pk_bf16_f32 v0, v4, v5
	v_cvt_pk_bf16_f32 v1, v6, v7
	v_cvt_pk_bf16_f32 v2, v8, v9
	v_cvt_pk_bf16_f32 v3, v10, v11
	global_store_dwordx4 v[18:19], v[0:3], off
	s_cbranch_vccnz .LBB0_91
	s_andn2_b64 vcc, exec, s[8:9]
	s_cbranch_vccnz .LBB0_90
	s_barrier
	s_branch .LBB0_90

; __device__ __forceinline__ unsigned pkbf(float lo, float hi) { const f32x2_m v = {lo, hi}; const bf16x2_m b = __builtin_convertvector(v, bf16x2_m); return __builtin_bit_cast(unsigned, b); }
;     __device__ __forceinline__ void operator()(const f32x4 (&acc)[2][2][4][2], const Unit& u, int wr, int wc, int fr, int fq) const {
;     ...
;         for (int ai = 0; ai < 2; ++ai) { f32x4 pre[4][2][2];
; #pragma unroll
;             for (int m = 0; m < 4; ++m)
; #pragma unroll
;                 for (int bj = 0; bj < 2; ++bj)
; #pragma unroll
;                     for (int n = 0; n < 2; ++n) pre[m][bj][n] = *(const f32x4*)(base + (size_t)(row0 + ai * HALF + m * 16) * ldc + col0 + bj * HALF + n * 16);
;             asm volatile("" ::: "memory");
; #pragma unroll
;             for (int m = 0; m < 4; ++m) { const int row = row0 + ai * HALF + m * 16; const size_t off = (size_t)row * ldc + col0; float sq = 0.f;
; #pragma unroll
;                 for (int bj = 0; bj < 2; ++bj)
; #pragma unroll
;                     for (int n = 0; n < 2; ++n) { const size_t p = off + bj * HALF + n * 16; const f32x4 o = pre[m][bj][n] + acc[ai][bj][m][n] * scale; *(f32x4*)(out + p) = o;
;                         if (NORM == 1) *(v2u*)(xb + p) = (v2u){pkbf(o[0], o[1]), pkbf(o[2], o[3])};
;                         if (NORM) sq += (o[0] * o[0] + o[1] * o[1]) + (o[2] * o[2] + o[3] * o[3]); }
;                 if (NORM) { sq += __shfl_xor(sq, 16); sq += __shfl_xor(sq, 32); if (fq == 0) __hip_atomic_fetch_add(ss + row, sq, __ATOMIC_RELAXED, __HIP_MEMORY_SCOPE_AGENT); } } }
.LBB0_180:
	v_lshl_add_u32 v192, s52, 8, v200
	v_lshl_or_b32 v188, s53, 8, v202
	v_ashrrev_i32_e32 v189, 31, v188
	v_ashrrev_i32_e32 v193, 31, v192
	v_lshl_add_u64 v[190:191], v[188:189], 2, s[16:17]
	v_lshlrev_b64 v[128:129], 13, v[192:193]
	v_lshl_add_u64 v[128:129], v[190:191], 0, v[128:129]
	global_load_dwordx4 v[210:213], v[128:129], off
	global_load_dwordx4 v[214:217], v[128:129], off offset:64
	global_load_dwordx4 v[218:221], v[128:129], off offset:512
	global_load_dwordx4 v[228:231], v[128:129], off offset:576
	v_or_b32_e32 v198, 16, v192
	v_or_b32_e32 v196, 32, v192
	v_or_b32_e32 v194, 48, v192
	v_ashrrev_i32_e32 v199, 31, v198
	v_ashrrev_i32_e32 v197, 31, v196
	v_ashrrev_i32_e32 v195, 31, v194
	v_lshlrev_b64 v[128:129], 13, v[198:199]
	v_lshlrev_b64 v[130:131], 13, v[196:197]
	v_lshlrev_b64 v[132:133], 13, v[194:195]
	v_lshl_add_u64 v[128:129], v[190:191], 0, v[128:129]
	v_lshl_add_u64 v[130:131], v[190:191], 0, v[130:131]
	v_lshl_add_u64 v[208:209], v[190:191], 0, v[132:133]
	global_load_dwordx4 v[172:175], v[128:129], off
	global_load_dwordx4 v[168:171], v[128:129], off offset:64
	global_load_dwordx4 v[164:167], v[128:129], off offset:512
	global_load_dwordx4 v[160:163], v[128:129], off offset:576
	global_load_dwordx4 v[156:159], v[130:131], off
	global_load_dwordx4 v[152:155], v[130:131], off offset:64
	global_load_dwordx4 v[148:151], v[130:131], off offset:512
	global_load_dwordx4 v[144:147], v[130:131], off offset:576
	global_load_dwordx4 v[140:143], v[208:209], off
	global_load_dwordx4 v[136:139], v[208:209], off offset:64
	global_load_dwordx4 v[132:135], v[208:209], off offset:512
	s_nop 0
	global_load_dwordx4 v[128:131], v[208:209], off offset:576
	v_and_b32_e32 v208, 64, v206
	v_xor_b32_e32 v207, 16, v206
	v_add_u32_e32 v208, 64, v208
	v_xor_b32_e32 v209, 32, v206
	v_cmp_lt_i32_e32 vcc, v207, v208
	v_lshlrev_b64 v[232:233], 11, v[192:193]
	v_lshl_add_u64 v[232:233], v[232:233], 0, v[188:189]
	v_cndmask_b32_e32 v207, v206, v207, vcc
	v_cmp_lt_i32_e32 vcc, v209, v208
	v_lshl_add_u64 v[234:235], v[232:233], 2, s[60:61]
	v_lshlrev_b32_e32 v208, 2, v207
	v_cndmask_b32_e32 v209, v206, v209, vcc
	v_lshlrev_b32_e32 v207, 2, v209
	v_lshlrev_b64 v[232:233], 1, v[232:233]
	v_lshl_add_u64 v[236:237], s[70:71], 0, v[232:233]
	v_or_b32_e32 v238, 32, v232
	v_mov_b32_e32 v239, v233
	v_lshl_add_u64 v[238:239], s[70:71], 0, v[238:239]
	v_or_b32_e32 v240, 0x100, v232
	v_mov_b32_e32 v241, v233
	v_or_b32_e32 v232, 0x120, v232
	s_waitcnt vmcnt(0)
	v_fma_f32 v126, v126, 0.5, v212
	v_fma_f32 v127, v127, 0.5, v213
	v_fma_f32 v124, v124, 0.5, v210
	v_fma_f32 v125, v125, 0.5, v211
	v_fma_f32 v122, v122, 0.5, v216
	v_fma_f32 v123, v123, 0.5, v217
	v_fma_f32 v120, v120, 0.5, v214
	v_fma_f32 v121, v121, 0.5, v215
	v_fma_f32 v118, v118, 0.5, v220
	v_fma_f32 v119, v119, 0.5, v221
	v_fma_f32 v116, v116, 0.5, v218
	v_fma_f32 v117, v117, 0.5, v219
	global_store_dwordx4 v[234:235], v[124:127], off
	v_cvt_pk_bf16_f32 v210, v124, v125
	v_cvt_pk_bf16_f32 v211, v126, v127
	v_mul_f32_e32 v125, v125, v125
	v_mul_f32_e32 v127, v127, v127
	v_mul_f32_e32 v209, v121, v121
	v_mul_f32_e32 v216, v123, v123
	v_mul_f32_e32 v217, v117, v117
	v_mul_f32_e32 v218, v119, v119
	v_fmac_f32_e32 v125, v124, v124
	v_fmac_f32_e32 v127, v126, v126
	v_fmac_f32_e32 v209, v120, v120
	v_fmac_f32_e32 v216, v122, v122
	v_cvt_pk_bf16_f32 v212, v120, v121
	v_cvt_pk_bf16_f32 v213, v122, v123
	v_cvt_pk_bf16_f32 v214, v116, v117
	global_store_dwordx2 v[236:237], v[210:211], off
	global_store_dwordx4 v[234:235], v[120:123], off offset:64
	global_store_dwordx2 v[238:239], v[212:213], off
	global_store_dwordx4 v[234:235], v[116:119], off offset:512
	v_fmac_f32_e32 v217, v116, v116
	v_fmac_f32_e32 v218, v118, v118
	v_add_f32_e32 v116, v125, v127
	v_add_f32_e32 v117, v209, v216
	v_cvt_pk_bf16_f32 v215, v118, v119
	v_add_f32_e32 v118, v217, v218
	v_add_f32_e32 v116, v116, v117
	v_fma_f32 v114, v114, 0.5, v230
	v_fma_f32 v115, v115, 0.5, v231
	v_fma_f32 v112, v112, 0.5, v228
	v_fma_f32 v113, v113, 0.5, v229
	v_add_f32_e32 v116, v116, v118
	v_mul_f32_e32 v117, v113, v113
	v_mul_f32_e32 v118, v115, v115
	v_fmac_f32_e32 v117, v112, v112
	v_fmac_f32_e32 v118, v114, v114
	v_add_f32_e32 v117, v117, v118
	v_add_f32_e32 v118, v116, v117
	ds_bpermute_b32 v119, v208, v118
	v_lshl_add_u64 v[116:117], s[70:71], 0, v[240:241]
	global_store_dwordx2 v[116:117], v[214:215], off
	global_store_dwordx4 v[234:235], v[112:115], off offset:576
	v_cvt_pk_bf16_f32 v116, v112, v113
	v_cvt_pk_bf16_f32 v117, v114, v115
	s_waitcnt lgkmcnt(0)
	v_add_f32_e32 v112, v118, v119
	ds_bpermute_b32 v113, v207, v112
	v_lshl_add_u64 v[114:115], s[70:71], 0, v[232:233]
	global_store_dwordx2 v[114:115], v[116:117], off
	s_and_saveexec_b64 s[0:1], s[6:7]
	s_cbranch_execz .LBB0_182
	v_lshl_add_u64 v[114:115], v[192:193], 2, s[22:23]
	s_waitcnt lgkmcnt(0)
	v_add_f32_e32 v112, v112, v113
	global_atomic_add_f32 v[114:115], v112, off
; __device__ __forceinline__ unsigned pkbf(float lo, float hi) { const f32x2_m v = {lo, hi}; const bf16x2_m b = __builtin_convertvector(v, bf16x2_m); return __builtin_bit_cast(unsigned, b); }
;     __device__ __forceinline__ void operator()(const f32x4 (&acc)[2][2][4][2], const Unit& u, int wr, int wc, int fr, int fq) const {
;     ...
;             for (int m = 0; m < 4; ++m) { const int row = row0 + ai * HALF + m * 16; const size_t off = (size_t)row * ldc + col0; float sq = 0.f;
; #pragma unroll
;                 for (int bj = 0; bj < 2; ++bj)
; #pragma unroll
;                     for (int n = 0; n < 2; ++n) { const size_t p = off + bj * HALF + n * 16; const f32x4 o = pre[m][bj][n] + acc[ai][bj][m][n] * scale; *(f32x4*)(out + p) = o;
;                         if (NORM == 1) *(v2u*)(xb + p) = (v2u){pkbf(o[0], o[1]), pkbf(o[2], o[3])};
;                         if (NORM) sq += (o[0] * o[0] + o[1] * o[1]) + (o[2] * o[2] + o[3] * o[3]); }
;                 if (NORM) { sq += __shfl_xor(sq, 16); sq += __shfl_xor(sq, 32); if (fq == 0) __hip_atomic_fetch_add(ss + row, sq, __ATOMIC_RELAXED, __HIP_MEMORY_SCOPE_AGENT); } } }
.LBB0_182:
	s_or_b64 exec, exec, s[0:1]
	s_waitcnt lgkmcnt(0)
	v_lshlrev_b64 v[112:113], 11, v[198:199]
	v_lshl_add_u64 v[112:113], v[112:113], 0, v[188:189]
	v_fma_f32 v110, v110, 0.5, v174
	v_fma_f32 v111, v111, 0.5, v175
	v_fma_f32 v108, v108, 0.5, v172
	v_fma_f32 v109, v109, 0.5, v173
	v_lshl_add_u64 v[114:115], v[112:113], 2, s[60:61]
	global_store_dwordx4 v[114:115], v[108:111], off
	v_cvt_pk_bf16_f32 v116, v108, v109
	v_lshlrev_b64 v[112:113], 1, v[112:113]
	v_mul_f32_e32 v109, v109, v109
	v_fmac_f32_e32 v109, v108, v108
	v_mul_f32_e32 v108, v111, v111
	v_cvt_pk_bf16_f32 v117, v110, v111
	v_lshl_add_u64 v[118:119], s[70:71], 0, v[112:113]
	v_fmac_f32_e32 v108, v110, v110
	v_fma_f32 v106, v106, 0.5, v170
	v_fma_f32 v107, v107, 0.5, v171
	v_fma_f32 v104, v104, 0.5, v168
	v_fma_f32 v105, v105, 0.5, v169
	global_store_dwordx2 v[118:119], v[116:117], off
	v_add_f32_e32 v116, v109, v108
	global_store_dwordx4 v[114:115], v[104:107], off offset:64
	v_cvt_pk_bf16_f32 v108, v104, v105
	v_or_b32_e32 v110, 32, v112
	v_mul_f32_e32 v105, v105, v105
	v_fmac_f32_e32 v105, v104, v104
	v_mul_f32_e32 v104, v107, v107
	v_mov_b32_e32 v111, v113
	v_fmac_f32_e32 v104, v106, v106
	v_cvt_pk_bf16_f32 v109, v106, v107
	v_lshl_add_u64 v[110:111], s[70:71], 0, v[110:111]
	v_add_f32_e32 v104, v105, v104
	v_fma_f32 v102, v102, 0.5, v166
	v_fma_f32 v103, v103, 0.5, v167
	v_fma_f32 v100, v100, 0.5, v164
	v_fma_f32 v101, v101, 0.5, v165
	global_store_dwordx2 v[110:111], v[108:109], off
	v_add_f32_e32 v108, v116, v104
	global_store_dwordx4 v[114:115], v[100:103], off offset:512
	v_cvt_pk_bf16_f32 v104, v100, v101
	v_fma_f32 v98, v98, 0.5, v162
	v_fma_f32 v99, v99, 0.5, v163
	v_mul_f32_e32 v101, v101, v101
	v_fmac_f32_e32 v101, v100, v100
	v_mul_f32_e32 v100, v103, v103
	v_fmac_f32_e32 v100, v102, v102
	v_fma_f32 v96, v96, 0.5, v160
	v_fma_f32 v97, v97, 0.5, v161
	v_cvt_pk_bf16_f32 v105, v102, v103
	v_add_f32_e32 v100, v101, v100
	v_mul_f32_e32 v101, v97, v97
	v_mul_f32_e32 v102, v99, v99
	v_fmac_f32_e32 v101, v96, v96
	v_fmac_f32_e32 v102, v98, v98
	v_add_f32_e32 v100, v108, v100
	v_add_f32_e32 v101, v101, v102
	v_add_f32_e32 v102, v100, v101
	ds_bpermute_b32 v103, v208, v102
	v_or_b32_e32 v106, 0x100, v112
	v_mov_b32_e32 v107, v113
	v_lshl_add_u64 v[100:101], s[70:71], 0, v[106:107]
	global_store_dwordx2 v[100:101], v[104:105], off
	global_store_dwordx4 v[114:115], v[96:99], off offset:576
	v_cvt_pk_bf16_f32 v100, v96, v97
	v_or_b32_e32 v112, 0x120, v112
	s_waitcnt lgkmcnt(0)
	v_add_f32_e32 v96, v102, v103
	ds_bpermute_b32 v97, v207, v96
	v_cvt_pk_bf16_f32 v101, v98, v99
	v_lshl_add_u64 v[98:99], s[70:71], 0, v[112:113]
	global_store_dwordx2 v[98:99], v[100:101], off
	s_and_saveexec_b64 s[0:1], s[6:7]
	s_cbranch_execz .LBB0_184
	v_lshl_add_u64 v[98:99], v[198:199], 2, s[22:23]
	s_waitcnt lgkmcnt(0)
	v_add_f32_e32 v96, v96, v97
	global_atomic_add_f32 v[98:99], v96, off
.LBB0_184:
	s_or_b64 exec, exec, s[0:1]
	s_waitcnt lgkmcnt(0)
	v_lshlrev_b64 v[96:97], 11, v[196:197]
	v_lshl_add_u64 v[96:97], v[96:97], 0, v[188:189]
	v_fma_f32 v94, v94, 0.5, v158
	v_fma_f32 v95, v95, 0.5, v159
	v_fma_f32 v92, v92, 0.5, v156
	v_fma_f32 v93, v93, 0.5, v157
	v_lshl_add_u64 v[98:99], v[96:97], 2, s[60:61]
	global_store_dwordx4 v[98:99], v[92:95], off
	v_cvt_pk_bf16_f32 v100, v92, v93
	v_lshlrev_b64 v[96:97], 1, v[96:97]
	v_mul_f32_e32 v93, v93, v93
	v_fmac_f32_e32 v93, v92, v92
	v_mul_f32_e32 v92, v95, v95
	v_cvt_pk_bf16_f32 v101, v94, v95
	v_lshl_add_u64 v[102:103], s[70:71], 0, v[96:97]
	v_fmac_f32_e32 v92, v94, v94
	v_fma_f32 v90, v90, 0.5, v154
	v_fma_f32 v91, v91, 0.5, v155
	v_fma_f32 v88, v88, 0.5, v152
	v_fma_f32 v89, v89, 0.5, v153
	global_store_dwordx2 v[102:103], v[100:101], off
	v_add_f32_e32 v100, v93, v92
	global_store_dwordx4 v[98:99], v[88:91], off offset:64
	v_cvt_pk_bf16_f32 v92, v88, v89
	v_or_b32_e32 v94, 32, v96
	v_mul_f32_e32 v89, v89, v89
	v_fmac_f32_e32 v89, v88, v88
	v_mul_f32_e32 v88, v91, v91
	v_mov_b32_e32 v95, v97
	v_fmac_f32_e32 v88, v90, v90
	v_cvt_pk_bf16_f32 v93, v90, v91
	v_lshl_add_u64 v[94:95], s[70:71], 0, v[94:95]
	v_add_f32_e32 v88, v89, v88
	v_fma_f32 v86, v86, 0.5, v150
	v_fma_f32 v87, v87, 0.5, v151
	v_fma_f32 v84, v84, 0.5, v148
	v_fma_f32 v85, v85, 0.5, v149
	global_store_dwordx2 v[94:95], v[92:93], off
	v_add_f32_e32 v92, v100, v88
	global_store_dwordx4 v[98:99], v[84:87], off offset:512
	v_cvt_pk_bf16_f32 v88, v84, v85
	v_fma_f32 v82, v82, 0.5, v146
	v_fma_f32 v83, v83, 0.5, v147
	v_mul_f32_e32 v85, v85, v85
	v_fmac_f32_e32 v85, v84, v84
	v_mul_f32_e32 v84, v87, v87
	v_fmac_f32_e32 v84, v86, v86
	v_fma_f32 v80, v80, 0.5, v144
	v_fma_f32 v81, v81, 0.5, v145
	v_cvt_pk_bf16_f32 v89, v86, v87
	v_add_f32_e32 v84, v85, v84
	v_mul_f32_e32 v85, v81, v81
	v_mul_f32_e32 v86, v83, v83
	v_fmac_f32_e32 v85, v80, v80
	v_fmac_f32_e32 v86, v82, v82
	v_add_f32_e32 v84, v92, v84
	v_add_f32_e32 v85, v85, v86
	v_add_f32_e32 v86, v84, v85
	ds_bpermute_b32 v87, v208, v86
	v_or_b32_e32 v90, 0x100, v96
	v_mov_b32_e32 v91, v97
	v_lshl_add_u64 v[84:85], s[70:71], 0, v[90:91]
	global_store_dwordx2 v[84:85], v[88:89], off
	global_store_dwordx4 v[98:99], v[80:83], off offset:576
	v_cvt_pk_bf16_f32 v84, v80, v81
	v_or_b32_e32 v96, 0x120, v96
	s_waitcnt lgkmcnt(0)
	v_add_f32_e32 v80, v86, v87
	ds_bpermute_b32 v81, v207, v80
	v_cvt_pk_bf16_f32 v85, v82, v83
	v_lshl_add_u64 v[82:83], s[70:71], 0, v[96:97]
	global_store_dwordx2 v[82:83], v[84:85], off
	s_and_saveexec_b64 s[0:1], s[6:7]
	s_cbranch_execz .LBB0_186
	v_lshl_add_u64 v[82:83], v[196:197], 2, s[22:23]
	s_waitcnt lgkmcnt(0)
	v_add_f32_e32 v80, v80, v81
	global_atomic_add_f32 v[82:83], v80, off
; __device__ __forceinline__ unsigned pkbf(float lo, float hi) { const f32x2_m v = {lo, hi}; const bf16x2_m b = __builtin_convertvector(v, bf16x2_m); return __builtin_bit_cast(unsigned, b); }
;     __device__ __forceinline__ void operator()(const f32x4 (&acc)[2][2][4][2], const Unit& u, int wr, int wc, int fr, int fq) const {
;     ...
;         for (int ai = 0; ai < 2; ++ai) { f32x4 pre[4][2][2];
; #pragma unroll
;             for (int m = 0; m < 4; ++m)
; #pragma unroll
;                 for (int bj = 0; bj < 2; ++bj)
; #pragma unroll
;                     for (int n = 0; n < 2; ++n) pre[m][bj][n] = *(const f32x4*)(base + (size_t)(row0 + ai * HALF + m * 16) * ldc + col0 + bj * HALF + n * 16);
;             asm volatile("" ::: "memory");
; #pragma unroll
;             for (int m = 0; m < 4; ++m) { const int row = row0 + ai * HALF + m * 16; const size_t off = (size_t)row * ldc + col0; float sq = 0.f;
; #pragma unroll
;                 for (int bj = 0; bj < 2; ++bj)
; #pragma unroll
;                     for (int n = 0; n < 2; ++n) { const size_t p = off + bj * HALF + n * 16; const f32x4 o = pre[m][bj][n] + acc[ai][bj][m][n] * scale; *(f32x4*)(out + p) = o;
;                         if (NORM == 1) *(v2u*)(xb + p) = (v2u){pkbf(o[0], o[1]), pkbf(o[2], o[3])};
;                         if (NORM) sq += (o[0] * o[0] + o[1] * o[1]) + (o[2] * o[2] + o[3] * o[3]); }
;                 if (NORM) { sq += __shfl_xor(sq, 16); sq += __shfl_xor(sq, 32); if (fq == 0) __hip_atomic_fetch_add(ss + row, sq, __ATOMIC_RELAXED, __HIP_MEMORY_SCOPE_AGENT); } } }
.LBB0_186:
	s_or_b64 exec, exec, s[0:1]
	s_waitcnt lgkmcnt(0)
	v_lshlrev_b64 v[80:81], 11, v[194:195]
	v_lshl_add_u64 v[80:81], v[80:81], 0, v[188:189]
	v_fma_f32 v78, v78, 0.5, v142
	v_fma_f32 v79, v79, 0.5, v143
	v_fma_f32 v76, v76, 0.5, v140
	v_fma_f32 v77, v77, 0.5, v141
	v_lshl_add_u64 v[82:83], v[80:81], 2, s[60:61]
	global_store_dwordx4 v[82:83], v[76:79], off
	v_cvt_pk_bf16_f32 v84, v76, v77
	v_lshlrev_b64 v[80:81], 1, v[80:81]
	v_mul_f32_e32 v77, v77, v77
	v_fmac_f32_e32 v77, v76, v76
	v_mul_f32_e32 v76, v79, v79
	v_cvt_pk_bf16_f32 v85, v78, v79
	v_lshl_add_u64 v[86:87], s[70:71], 0, v[80:81]
	v_fmac_f32_e32 v76, v78, v78
	v_fma_f32 v74, v74, 0.5, v138
	v_fma_f32 v75, v75, 0.5, v139
	v_fma_f32 v72, v72, 0.5, v136
	v_fma_f32 v73, v73, 0.5, v137
	global_store_dwordx2 v[86:87], v[84:85], off
	v_add_f32_e32 v84, v77, v76
	global_store_dwordx4 v[82:83], v[72:75], off offset:64
	v_cvt_pk_bf16_f32 v76, v72, v73
	v_or_b32_e32 v78, 32, v80
	v_mul_f32_e32 v73, v73, v73
	v_fmac_f32_e32 v73, v72, v72
	v_mul_f32_e32 v72, v75, v75
	v_mov_b32_e32 v79, v81
	v_fmac_f32_e32 v72, v74, v74
	v_cvt_pk_bf16_f32 v77, v74, v75
	v_lshl_add_u64 v[78:79], s[70:71], 0, v[78:79]
	v_add_f32_e32 v72, v73, v72
	v_fma_f32 v70, v70, 0.5, v134
	v_fma_f32 v71, v71, 0.5, v135
	v_fma_f32 v68, v68, 0.5, v132
	v_fma_f32 v69, v69, 0.5, v133
	global_store_dwordx2 v[78:79], v[76:77], off
	v_add_f32_e32 v76, v84, v72
	global_store_dwordx4 v[82:83], v[68:71], off offset:512
	v_cvt_pk_bf16_f32 v72, v68, v69
	v_fma_f32 v66, v66, 0.5, v130
	v_fma_f32 v67, v67, 0.5, v131
	v_mul_f32_e32 v69, v69, v69
	v_fmac_f32_e32 v69, v68, v68
	v_mul_f32_e32 v68, v71, v71
	v_fmac_f32_e32 v68, v70, v70
	v_fma_f32 v64, v64, 0.5, v128
	v_fma_f32 v65, v65, 0.5, v129
	v_cvt_pk_bf16_f32 v73, v70, v71
	v_add_f32_e32 v68, v69, v68
	v_mul_f32_e32 v69, v65, v65
	v_mul_f32_e32 v70, v67, v67
	v_fmac_f32_e32 v69, v64, v64
	v_fmac_f32_e32 v70, v66, v66
	v_add_f32_e32 v68, v76, v68
	v_add_f32_e32 v69, v69, v70
	v_add_f32_e32 v70, v68, v69
	ds_bpermute_b32 v71, v208, v70
	v_or_b32_e32 v74, 0x100, v80
	v_mov_b32_e32 v75, v81
	v_lshl_add_u64 v[68:69], s[70:71], 0, v[74:75]
	global_store_dwordx2 v[68:69], v[72:73], off
	global_store_dwordx4 v[82:83], v[64:67], off offset:576
	v_cvt_pk_bf16_f32 v68, v64, v65
	v_or_b32_e32 v80, 0x120, v80
	s_waitcnt lgkmcnt(0)
	v_add_f32_e32 v64, v70, v71
	ds_bpermute_b32 v65, v207, v64
	v_cvt_pk_bf16_f32 v69, v66, v67
	v_lshl_add_u64 v[66:67], s[70:71], 0, v[80:81]
	global_store_dwordx2 v[66:67], v[68:69], off
	s_and_saveexec_b64 s[0:1], s[6:7]
	s_cbranch_execz .LBB0_188
	v_lshl_add_u64 v[66:67], v[194:195], 2, s[22:23]
	s_waitcnt lgkmcnt(0)
	v_add_f32_e32 v64, v64, v65
	global_atomic_add_f32 v[66:67], v64, off
.LBB0_188:
	s_or_b64 exec, exec, s[0:1]
	v_add_u32_e32 v118, 0x80, v192
	v_ashrrev_i32_e32 v119, 31, v118
	s_waitcnt lgkmcnt(0)
	v_lshlrev_b64 v[64:65], 13, v[118:119]
	v_lshl_add_u64 v[64:65], v[190:191], 0, v[64:65]
	global_load_dwordx4 v[120:123], v[64:65], off
	global_load_dwordx4 v[124:127], v[64:65], off offset:64
	global_load_dwordx4 v[128:131], v[64:65], off offset:512
	global_load_dwordx4 v[132:135], v[64:65], off offset:576
	v_add_u32_e32 v116, 0x90, v192
	v_add_u32_e32 v114, 0xa0, v192
	v_add_u32_e32 v112, 0xb0, v192
	v_ashrrev_i32_e32 v117, 31, v116
	v_ashrrev_i32_e32 v115, 31, v114
	v_ashrrev_i32_e32 v113, 31, v112
	v_lshlrev_b64 v[64:65], 13, v[116:117]
	v_lshlrev_b64 v[66:67], 13, v[114:115]
	v_lshlrev_b64 v[68:69], 13, v[112:113]
	v_lshl_add_u64 v[64:65], v[190:191], 0, v[64:65]
	v_lshl_add_u64 v[66:67], v[190:191], 0, v[66:67]
	v_lshl_add_u64 v[136:137], v[190:191], 0, v[68:69]
	global_load_dwordx4 v[108:111], v[64:65], off
	global_load_dwordx4 v[104:107], v[64:65], off offset:64
	global_load_dwordx4 v[100:103], v[64:65], off offset:512
	global_load_dwordx4 v[96:99], v[64:65], off offset:576
	global_load_dwordx4 v[92:95], v[66:67], off
	global_load_dwordx4 v[88:91], v[66:67], off offset:64
	global_load_dwordx4 v[84:87], v[66:67], off offset:512
	global_load_dwordx4 v[80:83], v[66:67], off offset:576
	global_load_dwordx4 v[76:79], v[136:137], off
	global_load_dwordx4 v[72:75], v[136:137], off offset:64
	global_load_dwordx4 v[68:71], v[136:137], off offset:512
	s_nop 0
	global_load_dwordx4 v[64:67], v[136:137], off offset:576
	v_lshlrev_b64 v[136:137], 11, v[118:119]
	v_lshl_add_u64 v[136:137], v[136:137], 0, v[188:189]
	v_lshl_add_u64 v[138:139], v[136:137], 2, s[60:61]
	v_lshlrev_b64 v[136:137], 1, v[136:137]
	v_lshl_add_u64 v[140:141], s[70:71], 0, v[136:137]
	v_or_b32_e32 v142, 32, v136
	v_mov_b32_e32 v143, v137
	v_lshl_add_u64 v[142:143], s[70:71], 0, v[142:143]
	v_or_b32_e32 v144, 0x100, v136
	v_mov_b32_e32 v145, v137
	v_or_b32_e32 v136, 0x120, v136
	s_waitcnt vmcnt(15)
	v_fma_f32 v62, v62, 0.5, v122
	v_fma_f32 v63, v63, 0.5, v123
	v_fma_f32 v60, v60, 0.5, v120
	v_fma_f32 v61, v61, 0.5, v121
	s_waitcnt vmcnt(14)
	v_fma_f32 v58, v58, 0.5, v126
	v_fma_f32 v59, v59, 0.5, v127
	v_fma_f32 v56, v56, 0.5, v124
	v_fma_f32 v57, v57, 0.5, v125
	s_waitcnt vmcnt(13)
	v_fma_f32 v54, v54, 0.5, v130
	v_fma_f32 v55, v55, 0.5, v131
	v_fma_f32 v52, v52, 0.5, v128
	v_fma_f32 v53, v53, 0.5, v129
	global_store_dwordx4 v[138:139], v[60:63], off
	v_cvt_pk_bf16_f32 v120, v60, v61
	v_cvt_pk_bf16_f32 v121, v62, v63
	v_mul_f32_e32 v61, v61, v61
	v_mul_f32_e32 v63, v63, v63
	v_mul_f32_e32 v126, v57, v57
	v_mul_f32_e32 v127, v59, v59
	s_waitcnt vmcnt(13)
	v_fma_f32 v50, v50, 0.5, v134
	v_fma_f32 v51, v51, 0.5, v135
	v_fma_f32 v48, v48, 0.5, v132
	v_fma_f32 v49, v49, 0.5, v133
	v_mul_f32_e32 v128, v53, v53
	v_mul_f32_e32 v129, v55, v55
	v_fmac_f32_e32 v61, v60, v60
	v_fmac_f32_e32 v63, v62, v62
	v_fmac_f32_e32 v126, v56, v56
	v_fmac_f32_e32 v127, v58, v58
	v_cvt_pk_bf16_f32 v122, v56, v57
	v_cvt_pk_bf16_f32 v123, v58, v59
	v_cvt_pk_bf16_f32 v124, v52, v53
	v_mul_f32_e32 v130, v49, v49
	v_mul_f32_e32 v131, v51, v51
	global_store_dwordx2 v[140:141], v[120:121], off
	global_store_dwordx4 v[138:139], v[56:59], off offset:64
	global_store_dwordx2 v[142:143], v[122:123], off
	global_store_dwordx4 v[138:139], v[52:55], off offset:512
	v_fmac_f32_e32 v128, v52, v52
	v_fmac_f32_e32 v129, v54, v54
	v_add_f32_e32 v52, v61, v63
	v_add_f32_e32 v53, v126, v127
	v_cvt_pk_bf16_f32 v125, v54, v55
	v_fmac_f32_e32 v130, v48, v48
	v_fmac_f32_e32 v131, v50, v50
	v_add_f32_e32 v54, v128, v129
	v_add_f32_e32 v52, v52, v53
	v_add_f32_e32 v52, v52, v54
	v_add_f32_e32 v53, v130, v131
	v_add_f32_e32 v54, v52, v53
	ds_bpermute_b32 v55, v208, v54
	v_lshl_add_u64 v[52:53], s[70:71], 0, v[144:145]
	global_store_dwordx2 v[52:53], v[124:125], off
	global_store_dwordx4 v[138:139], v[48:51], off offset:576
	v_cvt_pk_bf16_f32 v52, v48, v49
	v_cvt_pk_bf16_f32 v53, v50, v51
	s_waitcnt lgkmcnt(0)
	v_add_f32_e32 v48, v54, v55
	ds_bpermute_b32 v49, v207, v48
	v_lshl_add_u64 v[50:51], s[70:71], 0, v[136:137]
	global_store_dwordx2 v[50:51], v[52:53], off
	s_and_saveexec_b64 s[0:1], s[6:7]
	s_cbranch_execz .LBB0_190
; __device__ __forceinline__ unsigned pkbf(float lo, float hi) { const f32x2_m v = {lo, hi}; const bf16x2_m b = __builtin_convertvector(v, bf16x2_m); return __builtin_bit_cast(unsigned, b); }
;     __device__ __forceinline__ void operator()(const f32x4 (&acc)[2][2][4][2], const Unit& u, int wr, int wc, int fr, int fq) const {
;     ...
;             for (int m = 0; m < 4; ++m) { const int row = row0 + ai * HALF + m * 16; const size_t off = (size_t)row * ldc + col0; float sq = 0.f;
; #pragma unroll
;                 for (int bj = 0; bj < 2; ++bj)
; #pragma unroll
;                     for (int n = 0; n < 2; ++n) { const size_t p = off + bj * HALF + n * 16; const f32x4 o = pre[m][bj][n] + acc[ai][bj][m][n] * scale; *(f32x4*)(out + p) = o;
;                         if (NORM == 1) *(v2u*)(xb + p) = (v2u){pkbf(o[0], o[1]), pkbf(o[2], o[3])};
;                         if (NORM) sq += (o[0] * o[0] + o[1] * o[1]) + (o[2] * o[2] + o[3] * o[3]); }
;                 if (NORM) { sq += __shfl_xor(sq, 16); sq += __shfl_xor(sq, 32); if (fq == 0) __hip_atomic_fetch_add(ss + row, sq, __ATOMIC_RELAXED, __HIP_MEMORY_SCOPE_AGENT); } } }
	v_lshl_add_u64 v[50:51], v[118:119], 2, s[22:23]
	s_waitcnt lgkmcnt(0)
	v_add_f32_e32 v48, v48, v49
	global_atomic_add_f32 v[50:51], v48, off
.LBB0_190:
	s_or_b64 exec, exec, s[0:1]
	s_waitcnt lgkmcnt(0)
	v_lshlrev_b64 v[48:49], 11, v[116:117]
	v_lshl_add_u64 v[48:49], v[48:49], 0, v[188:189]
	s_waitcnt vmcnt(19)
	v_fma_f32 v46, v46, 0.5, v110
	v_fma_f32 v47, v47, 0.5, v111
	v_fma_f32 v44, v44, 0.5, v108
	v_fma_f32 v45, v45, 0.5, v109
	v_lshl_add_u64 v[50:51], v[48:49], 2, s[60:61]
	global_store_dwordx4 v[50:51], v[44:47], off
	v_cvt_pk_bf16_f32 v52, v44, v45
	v_lshlrev_b64 v[48:49], 1, v[48:49]
	v_mul_f32_e32 v45, v45, v45
	v_fmac_f32_e32 v45, v44, v44
	v_mul_f32_e32 v44, v47, v47
	v_cvt_pk_bf16_f32 v53, v46, v47
	v_lshl_add_u64 v[54:55], s[70:71], 0, v[48:49]
	v_fmac_f32_e32 v44, v46, v46
	s_waitcnt vmcnt(19)
	v_fma_f32 v42, v42, 0.5, v106
	v_fma_f32 v43, v43, 0.5, v107
	v_fma_f32 v40, v40, 0.5, v104
	v_fma_f32 v41, v41, 0.5, v105
	global_store_dwordx2 v[54:55], v[52:53], off
	v_add_f32_e32 v52, v45, v44
	global_store_dwordx4 v[50:51], v[40:43], off offset:64
	v_cvt_pk_bf16_f32 v44, v40, v41
	v_or_b32_e32 v46, 32, v48
	v_mul_f32_e32 v41, v41, v41
	v_fmac_f32_e32 v41, v40, v40
	v_mul_f32_e32 v40, v43, v43
	v_mov_b32_e32 v47, v49
	v_fmac_f32_e32 v40, v42, v42
	v_cvt_pk_bf16_f32 v45, v42, v43
	v_lshl_add_u64 v[46:47], s[70:71], 0, v[46:47]
	v_add_f32_e32 v40, v41, v40
	s_waitcnt vmcnt(20)
	v_fma_f32 v38, v38, 0.5, v102
	v_fma_f32 v39, v39, 0.5, v103
	v_fma_f32 v36, v36, 0.5, v100
	v_fma_f32 v37, v37, 0.5, v101
	global_store_dwordx2 v[46:47], v[44:45], off
	v_add_f32_e32 v44, v52, v40
	global_store_dwordx4 v[50:51], v[36:39], off offset:512
	v_cvt_pk_bf16_f32 v40, v36, v37
	s_waitcnt vmcnt(21)
	v_fma_f32 v34, v34, 0.5, v98
	v_fma_f32 v35, v35, 0.5, v99
	v_mul_f32_e32 v37, v37, v37
	v_fmac_f32_e32 v37, v36, v36
	v_mul_f32_e32 v36, v39, v39
	v_fmac_f32_e32 v36, v38, v38
	v_fma_f32 v32, v32, 0.5, v96
	v_fma_f32 v33, v33, 0.5, v97
	v_cvt_pk_bf16_f32 v41, v38, v39
	v_add_f32_e32 v36, v37, v36
	v_mul_f32_e32 v37, v33, v33
	v_mul_f32_e32 v38, v35, v35
	v_fmac_f32_e32 v37, v32, v32
	v_fmac_f32_e32 v38, v34, v34
	v_add_f32_e32 v36, v44, v36
	v_add_f32_e32 v37, v37, v38
	v_add_f32_e32 v38, v36, v37
	ds_bpermute_b32 v39, v208, v38
	v_or_b32_e32 v42, 0x100, v48
	v_mov_b32_e32 v43, v49
	v_lshl_add_u64 v[36:37], s[70:71], 0, v[42:43]
	global_store_dwordx2 v[36:37], v[40:41], off
	global_store_dwordx4 v[50:51], v[32:35], off offset:576
	v_cvt_pk_bf16_f32 v36, v32, v33
	v_or_b32_e32 v48, 0x120, v48
	s_waitcnt lgkmcnt(0)
	v_add_f32_e32 v32, v38, v39
	ds_bpermute_b32 v33, v207, v32
	v_cvt_pk_bf16_f32 v37, v34, v35
	v_lshl_add_u64 v[34:35], s[70:71], 0, v[48:49]
	global_store_dwordx2 v[34:35], v[36:37], off
	s_and_saveexec_b64 s[0:1], s[6:7]
	s_cbranch_execz .LBB0_192
	v_lshl_add_u64 v[34:35], v[116:117], 2, s[22:23]
	s_waitcnt lgkmcnt(0)
	v_add_f32_e32 v32, v32, v33
	global_atomic_add_f32 v[34:35], v32, off
; __device__ __forceinline__ unsigned pkbf(float lo, float hi) { const f32x2_m v = {lo, hi}; const bf16x2_m b = __builtin_convertvector(v, bf16x2_m); return __builtin_bit_cast(unsigned, b); }
;     __device__ __forceinline__ void operator()(const f32x4 (&acc)[2][2][4][2], const Unit& u, int wr, int wc, int fr, int fq) const {
;     ...
;             for (int m = 0; m < 4; ++m) { const int row = row0 + ai * HALF + m * 16; const size_t off = (size_t)row * ldc + col0; float sq = 0.f;
; #pragma unroll
;                 for (int bj = 0; bj < 2; ++bj)
; #pragma unroll
;                     for (int n = 0; n < 2; ++n) { const size_t p = off + bj * HALF + n * 16; const f32x4 o = pre[m][bj][n] + acc[ai][bj][m][n] * scale; *(f32x4*)(out + p) = o;
;                         if (NORM == 1) *(v2u*)(xb + p) = (v2u){pkbf(o[0], o[1]), pkbf(o[2], o[3])};
;                         if (NORM) sq += (o[0] * o[0] + o[1] * o[1]) + (o[2] * o[2] + o[3] * o[3]); }
;                 if (NORM) { sq += __shfl_xor(sq, 16); sq += __shfl_xor(sq, 32); if (fq == 0) __hip_atomic_fetch_add(ss + row, sq, __ATOMIC_RELAXED, __HIP_MEMORY_SCOPE_AGENT); } } }
.LBB0_192:
	s_or_b64 exec, exec, s[0:1]
	s_waitcnt lgkmcnt(0)
	v_lshlrev_b64 v[32:33], 11, v[114:115]
	v_lshl_add_u64 v[32:33], v[32:33], 0, v[188:189]
	s_waitcnt vmcnt(23)
	v_fma_f32 v30, v30, 0.5, v94
	v_fma_f32 v31, v31, 0.5, v95
	v_fma_f32 v28, v28, 0.5, v92
	v_fma_f32 v29, v29, 0.5, v93
	v_lshl_add_u64 v[34:35], v[32:33], 2, s[60:61]
	global_store_dwordx4 v[34:35], v[28:31], off
	v_cvt_pk_bf16_f32 v36, v28, v29
	v_lshlrev_b64 v[32:33], 1, v[32:33]
	v_mul_f32_e32 v29, v29, v29
	v_fmac_f32_e32 v29, v28, v28
	v_mul_f32_e32 v28, v31, v31
	v_cvt_pk_bf16_f32 v37, v30, v31
	v_lshl_add_u64 v[38:39], s[70:71], 0, v[32:33]
	v_fmac_f32_e32 v28, v30, v30
	s_waitcnt vmcnt(23)
	v_fma_f32 v26, v26, 0.5, v90
	v_fma_f32 v27, v27, 0.5, v91
	v_fma_f32 v24, v24, 0.5, v88
	v_fma_f32 v25, v25, 0.5, v89
	global_store_dwordx2 v[38:39], v[36:37], off
	v_add_f32_e32 v36, v29, v28
	global_store_dwordx4 v[34:35], v[24:27], off offset:64
	v_cvt_pk_bf16_f32 v28, v24, v25
	v_or_b32_e32 v30, 32, v32
	v_mul_f32_e32 v25, v25, v25
	v_fmac_f32_e32 v25, v24, v24
	v_mul_f32_e32 v24, v27, v27
	v_mov_b32_e32 v31, v33
	v_fmac_f32_e32 v24, v26, v26
	v_cvt_pk_bf16_f32 v29, v26, v27
	v_lshl_add_u64 v[30:31], s[70:71], 0, v[30:31]
	v_add_f32_e32 v24, v25, v24
	s_waitcnt vmcnt(24)
	v_fma_f32 v22, v22, 0.5, v86
	v_fma_f32 v23, v23, 0.5, v87
	v_fma_f32 v20, v20, 0.5, v84
	v_fma_f32 v21, v21, 0.5, v85
	global_store_dwordx2 v[30:31], v[28:29], off
	v_add_f32_e32 v28, v36, v24
	global_store_dwordx4 v[34:35], v[20:23], off offset:512
	v_cvt_pk_bf16_f32 v24, v20, v21
	s_waitcnt vmcnt(25)
	v_fma_f32 v18, v18, 0.5, v82
	v_fma_f32 v19, v19, 0.5, v83
	v_mul_f32_e32 v21, v21, v21
	v_fmac_f32_e32 v21, v20, v20
	v_mul_f32_e32 v20, v23, v23
	v_fmac_f32_e32 v20, v22, v22
	v_fma_f32 v16, v16, 0.5, v80
	v_fma_f32 v17, v17, 0.5, v81
	v_cvt_pk_bf16_f32 v25, v22, v23
	v_add_f32_e32 v20, v21, v20
	v_mul_f32_e32 v21, v17, v17
	v_mul_f32_e32 v22, v19, v19
	v_fmac_f32_e32 v21, v16, v16
	v_fmac_f32_e32 v22, v18, v18
	v_add_f32_e32 v20, v28, v20
	v_add_f32_e32 v21, v21, v22
	v_add_f32_e32 v22, v20, v21
	ds_bpermute_b32 v23, v208, v22
	v_or_b32_e32 v26, 0x100, v32
	v_mov_b32_e32 v27, v33
	v_lshl_add_u64 v[20:21], s[70:71], 0, v[26:27]
	global_store_dwordx2 v[20:21], v[24:25], off
	global_store_dwordx4 v[34:35], v[16:19], off offset:576
	v_cvt_pk_bf16_f32 v20, v16, v17
	v_or_b32_e32 v32, 0x120, v32
	s_waitcnt lgkmcnt(0)
	v_add_f32_e32 v16, v22, v23
	ds_bpermute_b32 v17, v207, v16
	v_cvt_pk_bf16_f32 v21, v18, v19
	v_lshl_add_u64 v[18:19], s[70:71], 0, v[32:33]
	global_store_dwordx2 v[18:19], v[20:21], off
	s_and_saveexec_b64 s[0:1], s[6:7]
	s_cbranch_execz .LBB0_194
	v_lshl_add_u64 v[18:19], v[114:115], 2, s[22:23]
	s_waitcnt lgkmcnt(0)
	v_add_f32_e32 v16, v16, v17
	global_atomic_add_f32 v[18:19], v16, off
.LBB0_194:
	s_or_b64 exec, exec, s[0:1]
	s_waitcnt lgkmcnt(0)
	v_lshlrev_b64 v[16:17], 11, v[112:113]
	v_lshl_add_u64 v[16:17], v[16:17], 0, v[188:189]
	s_waitcnt vmcnt(27)
	v_fma_f32 v14, v14, 0.5, v78
	v_fma_f32 v15, v15, 0.5, v79
	v_fma_f32 v12, v12, 0.5, v76
	v_fma_f32 v13, v13, 0.5, v77
	v_lshl_add_u64 v[18:19], v[16:17], 2, s[60:61]
	global_store_dwordx4 v[18:19], v[12:15], off
	v_cvt_pk_bf16_f32 v20, v12, v13
	v_lshlrev_b64 v[16:17], 1, v[16:17]
	v_mul_f32_e32 v13, v13, v13
	v_fmac_f32_e32 v13, v12, v12
	v_mul_f32_e32 v12, v15, v15
	v_cvt_pk_bf16_f32 v21, v14, v15
	v_lshl_add_u64 v[22:23], s[70:71], 0, v[16:17]
	v_fmac_f32_e32 v12, v14, v14
	s_waitcnt vmcnt(27)
	v_fma_f32 v10, v10, 0.5, v74
	v_fma_f32 v11, v11, 0.5, v75
	v_fma_f32 v8, v8, 0.5, v72
	v_fma_f32 v9, v9, 0.5, v73
	global_store_dwordx2 v[22:23], v[20:21], off
	v_add_f32_e32 v20, v13, v12
	global_store_dwordx4 v[18:19], v[8:11], off offset:64
	v_cvt_pk_bf16_f32 v12, v8, v9
	v_or_b32_e32 v14, 32, v16
	v_mul_f32_e32 v9, v9, v9
	v_fmac_f32_e32 v9, v8, v8
	v_mul_f32_e32 v8, v11, v11
	v_mov_b32_e32 v15, v17
	v_fmac_f32_e32 v8, v10, v10
	v_cvt_pk_bf16_f32 v13, v10, v11
	v_lshl_add_u64 v[14:15], s[70:71], 0, v[14:15]
	v_add_f32_e32 v8, v9, v8
	s_waitcnt vmcnt(28)
	v_fma_f32 v6, v6, 0.5, v70
	v_fma_f32 v7, v7, 0.5, v71
	v_fma_f32 v4, v4, 0.5, v68
	v_fma_f32 v5, v5, 0.5, v69
	global_store_dwordx2 v[14:15], v[12:13], off
	v_add_f32_e32 v12, v20, v8
	global_store_dwordx4 v[18:19], v[4:7], off offset:512
	v_cvt_pk_bf16_f32 v8, v4, v5
	s_waitcnt vmcnt(29)
	v_fma_f32 v2, v2, 0.5, v66
	v_fma_f32 v3, v3, 0.5, v67
	v_mul_f32_e32 v5, v5, v5
	v_fmac_f32_e32 v5, v4, v4
	v_mul_f32_e32 v4, v7, v7
	v_fmac_f32_e32 v4, v6, v6
	v_fma_f32 v0, v0, 0.5, v64
	v_fma_f32 v1, v1, 0.5, v65
	v_cvt_pk_bf16_f32 v9, v6, v7
	v_add_f32_e32 v4, v5, v4
	v_mul_f32_e32 v5, v1, v1
	v_mul_f32_e32 v6, v3, v3
	v_fmac_f32_e32 v5, v0, v0
	v_fmac_f32_e32 v6, v2, v2
	v_add_f32_e32 v4, v12, v4
	v_add_f32_e32 v5, v5, v6
	v_add_f32_e32 v6, v4, v5
	ds_bpermute_b32 v7, v208, v6
	v_or_b32_e32 v10, 0x100, v16
	v_mov_b32_e32 v11, v17
	v_lshl_add_u64 v[4:5], s[70:71], 0, v[10:11]
	global_store_dwordx2 v[4:5], v[8:9], off
	global_store_dwordx4 v[18:19], v[0:3], off offset:576
	v_cvt_pk_bf16_f32 v4, v0, v1
	v_or_b32_e32 v16, 0x120, v16
	s_waitcnt lgkmcnt(0)
	v_add_f32_e32 v0, v6, v7
	ds_bpermute_b32 v1, v207, v0
	v_cvt_pk_bf16_f32 v5, v2, v3
	v_lshl_add_u64 v[2:3], s[70:71], 0, v[16:17]
	global_store_dwordx2 v[2:3], v[4:5], off
	s_and_saveexec_b64 s[0:1], s[6:7]
	s_cbranch_execz .LBB0_196
	v_lshl_add_u64 v[2:3], v[112:113], 2, s[22:23]
	s_waitcnt lgkmcnt(0)
	v_add_f32_e32 v0, v0, v1
	global_atomic_add_f32 v[2:3], v0, off

; __device__ __forceinline__ float sigm(float x) { return __builtin_amdgcn_rcpf(1.f + fexp(-x)); }
; template <int RSM> __device__ __forceinline__ float row_scale(const float* p, int row) { const float v = __hip_atomic_load(p + row, __ATOMIC_RELAXED, __HIP_MEMORY_SCOPE_AGENT); return RSM == 0 ? v : 1.0f / sqrtf(v * (1.f / DM) + EPS); }
;     __device__ __forceinline__ void operator()(const f32x4 (&acc)[2][2][4][2], const Unit& u, int wr, int wc, int fr, int fq) const {
;         bf16* P = (bf16*)(wsb + WS_BIG); const float* ropeC = (const float*)(wsb + WS_ROPE); const float* ropeS = ropeC + SEQ * 8; const float* rs = (const float*)(wsb + WS_SS) + M;
;         const int reg = u.pn >> 2; bf16* base = P + (size_t)reg * PBUF;
;         const int row0 = u.pm * BM + wr * 64 + fr, lc0 = (u.pn & 3) * 256 + wc * 32 + 8 * fq;
;         const bool rope = (reg <= 1) && ((wc & 1) == 0);
;         const float qs = (reg == 0) ? attn_body::C2 : 1.f;
;         float lb[2][8];
;         if (reg == PB_LF) {
; #pragma unroll
;             for (int bj = 0; bj < 2; ++bj)
; #pragma unroll
;                 for (int j = 0; j < 8; ++j) { const int c = lc0 + bj * HALF + j; lb[bj][j] = sigm(lbraw[c] - lbraw[1024 + c]); }
;         }
; #pragma unroll
;         for (int ai = 0; ai < 2; ++ai)
; #pragma unroll
;             for (int m = 0; m < 4; ++m) { const int row = row0 + ai * HALF + m * 16; const float sc = row_scale<1>(rs, row);
;                 f32x4 c0, c1, s0, s1;
;                 if (rope) { const int pos = row & (SEQ - 1); c0 = *(const f32x4*)(ropeC + pos * 8); c1 = *(const f32x4*)(ropeC + pos * 8 + 4); s0 = *(const f32x4*)(ropeS + pos * 8); s1 = *(const f32x4*)(ropeS + pos * 8 + 4); }
; #pragma unroll
;                 for (int bj = 0; bj < 2; ++bj) { const f32x4 a0 = acc[ai][bj][m][0] * sc, a1 = acc[ai][bj][m][1] * sc;
;                     float v[8] = {a0[0], a0[1], a0[2], a0[3], a1[0], a1[1], a1[2], a1[3]};
.LBB0_270:
	s_ashr_i32 s7, s6, 31
	s_lshl_b64 s[0:1], s[6:7], 25
	s_add_u32 s0, s26, s0
	s_addc_u32 s1, s27, s1
	v_lshlrev_b32_e32 v152, 1, v184
	v_lshl_add_u64 v[184:185], s[0:1], 0, v[152:153]
	s_waitcnt vmcnt(0)
	s_cmp_lt_i32 s6, 7
	s_cselect_b64 s[50:51], -1, 0
	s_cmp_gt_u32 s6, 8
	s_cselect_b32 s58, 0x2000000, 0
	s_cmp_lt_u32 s14, 4
	s_mov_b64 s[0:1], -1
	v_mov_b32_e32 v190, v247
	s_cselect_b64 vcc, -1, 0
	v_lshlrev_b64 v[186:187], 11, v[180:181]
	v_cndmask_b32_e32 v152, 1.0, v213, vcc
	v_lshl_add_u64 v[188:189], v[184:185], 0, v[186:187]
	v_mul_f32_e32 v192, v142, v190
	v_mul_f32_e32 v193, v143, v190
	v_mul_f32_e32 v194, v140, v190
	v_mul_f32_e32 v195, v141, v190
	v_mul_f32_e32 v140, v138, v190
	v_mul_f32_e32 v141, v139, v190
	v_mul_f32_e32 v142, v136, v190
	v_mul_f32_e32 v143, v137, v190
	s_and_b64 vcc, exec, s[50:51]
	s_cbranch_vccz .LBB0_277
	s_and_b64 vcc, exec, s[16:17]
	s_cbranch_vccnz .LBB0_431
	s_and_b64 vcc, exec, s[0:1]
	s_cbranch_vccnz .LBB0_436

; __device__ __forceinline__ float sigm(float x) { return __builtin_amdgcn_rcpf(1.f + fexp(-x)); }
; __device__ __forceinline__ unsigned pkh(float lo, float hi) { const _Float16 a = (_Float16)lo, b = (_Float16)hi; return (unsigned)__builtin_bit_cast(unsigned short, a) | ((unsigned)__builtin_bit_cast(unsigned short, b) << 16); }
;     __device__ __forceinline__ void operator()(const f32x4 (&acc)[2][2][4][2], const Unit& u, int wr, int wc, int fr, int fq) const {
;     ...
;                     if (reg == PB_LF) {
; #pragma unroll
;                         for (int j = 0; j < 8; ++j) v[j] = (1.f - lb[bj][j]) * sigm(-v[j]);
;                         w.x = pkh(v[0], v[1]); w.y = pkh(v[2], v[3]); w.z = pkh(v[4], v[5]); w.w = pkh(v[6], v[7]);
.LBB0_275:
	v_mul_f32_e32 v137, 0x3fb8aa3b, v203
	v_mul_f32_e32 v138, 0x3fb8aa3b, v196
	v_exp_f32_e32 v137, v137
	v_exp_f32_e32 v139, v138
	v_mul_f32_e32 v138, 0x3fb8aa3b, v197
	v_exp_f32_e32 v181, v138
	v_add_f32_e32 v137, 1.0, v137
	v_rcp_f32_e32 v138, v137
	v_add_f32_e32 v137, 1.0, v139
	v_add_f32_e32 v139, 1.0, v181
	v_mul_f32_e32 v181, 0x3fb8aa3b, v198
	v_mul_f32_e32 v136, 0x3fb8aa3b, v202
	v_exp_f32_e32 v181, v181
	v_mul_f32_e32 v191, 0x3fb8aa3b, v199
	v_exp_f32_e32 v136, v136
	v_exp_f32_e32 v191, v191
	v_add_f32_e32 v181, 1.0, v181
	v_rcp_f32_e32 v196, v181
	v_add_f32_e32 v136, 1.0, v136
	v_add_f32_e32 v181, 1.0, v191
	v_mul_f32_e32 v191, 0x3fb8aa3b, v200
	v_rcp_f32_e32 v136, v136
	v_rcp_f32_e32 v137, v137
	v_exp_f32_e32 v191, v191
	v_mul_f32_e32 v197, 0x3fb8aa3b, v201
	v_rcp_f32_e32 v139, v139
	v_exp_f32_e32 v199, v197
	v_add_f32_e64 v200, -v178, 1.0
	v_add_f32_e64 v201, -v179, 1.0
	v_rcp_f32_e32 v198, v181
	v_add_f32_e32 v181, 1.0, v191
	v_mul_f32_e32 v136, v200, v136
	v_mul_f32_e32 v137, v201, v137
	v_add_f32_e64 v200, -v174, 1.0
	v_add_f32_e64 v201, -v175, 1.0
	v_rcp_f32_e32 v197, v181
	v_add_f32_e32 v181, 1.0, v199
	v_mul_f32_e32 v138, v200, v138
	v_mul_f32_e32 v139, v201, v139
	v_rcp_f32_e32 v199, v181
	v_cvt_pk_f16_f32 v136, v136, v137
	v_cvt_pk_f16_f32 v137, v138, v139
	v_and_b32_e32 v138, 0xffff0000, v137
	v_lshlrev_b32_e32 v139, 16, v137
	v_or_b32_sdwa v137, v138, v136 dst_sel:DWORD dst_unused:UNUSED_PAD src0_sel:DWORD src1_sel:WORD_1
	v_or_b32_sdwa v136, v139, v136 dst_sel:DWORD dst_unused:UNUSED_PAD src0_sel:DWORD src1_sel:WORD_0
	v_add_f32_e64 v138, -v176, 1.0
	v_add_f32_e64 v139, -v177, 1.0
	s_nop 0
	v_mul_f32_e32 v138, v138, v196
	v_mul_f32_e32 v139, v139, v197
	v_add_f32_e64 v196, -v172, 1.0
	v_add_f32_e64 v197, -v173, 1.0
	v_cvt_pk_f16_f32 v138, v138, v139
	v_mul_f32_e32 v196, v196, v198
	v_mul_f32_e32 v197, v197, v199
	s_nop 0
	v_cvt_pk_f16_f32 v139, v196, v197
	v_and_b32_e32 v181, 0xffff0000, v139
	v_lshlrev_b32_e32 v191, 16, v139
	v_or_b32_sdwa v139, v181, v138 dst_sel:DWORD dst_unused:UNUSED_PAD src0_sel:DWORD src1_sel:WORD_1
	v_or_b32_sdwa v138, v191, v138 dst_sel:DWORD dst_unused:UNUSED_PAD src0_sel:DWORD src1_sel:WORD_0

;     __device__ __forceinline__ void operator()(const f32x4 (&acc)[2][2][4][2], const Unit& u, int wr, int wc, int fr, int fq) const {
;     ...
;                 for (int bj = 0; bj < 2; ++bj) { const f32x4 a0 = acc[ai][bj][m][0] * sc, a1 = acc[ai][bj][m][1] * sc;
;                     float v[8] = {a0[0], a0[1], a0[2], a0[3], a1[0], a1[1], a1[2], a1[3]};
.LBB0_279:
	v_mov_b32_e32 v191, v190
	v_mov_b32_e32 v140, v190
	v_mov_b32_e32 v141, v190
	v_mul_f32_e32 v136, v134, v140
	v_mul_f32_e32 v137, v135, v141
	v_mul_f32_e32 v134, v128, v190
	v_mul_f32_e32 v135, v129, v191
	v_cndmask_b32_e64 v128, 0, 1, s[50:51]
	v_cmp_ne_u32_e64 s[14:15], 1, v128
	v_cndmask_b32_e64 v128, 0, 1, s[16:17]
	v_mul_f32_e32 v138, v132, v190
	v_mul_f32_e32 v139, v133, v191
	v_mul_f32_e32 v132, v130, v140
	v_mul_f32_e32 v133, v131, v141
	s_mov_b64 s[0:1], -1
	s_andn2_b64 vcc, exec, s[50:51]
	v_cmp_ne_u32_e64 s[12:13], 1, v128
	s_cbranch_vccnz .LBB0_286
	s_and_b64 vcc, exec, s[12:13]
	s_cbranch_vccz .LBB0_486
	s_and_b64 vcc, exec, s[0:1]
	s_cbranch_vccnz .LBB0_491

; __device__ __forceinline__ float sigm(float x) { return __builtin_amdgcn_rcpf(1.f + fexp(-x)); }
; __device__ __forceinline__ unsigned pkh(float lo, float hi) { const _Float16 a = (_Float16)lo, b = (_Float16)hi; return (unsigned)__builtin_bit_cast(unsigned short, a) | ((unsigned)__builtin_bit_cast(unsigned short, b) << 16); }
;     __device__ __forceinline__ void operator()(const f32x4 (&acc)[2][2][4][2], const Unit& u, int wr, int wc, int fr, int fq) const {
;     ...
;                     if (reg == PB_LF) {
; #pragma unroll
;                         for (int j = 0; j < 8; ++j) v[j] = (1.f - lb[bj][j]) * sigm(-v[j]);
;                         w.x = pkh(v[0], v[1]); w.y = pkh(v[2], v[3]); w.z = pkh(v[4], v[5]); w.w = pkh(v[6], v[7]);
.LBB0_284:
	v_mul_f32_e32 v129, 0x3fb8aa3b, v193
	v_mul_f32_e32 v130, 0x3fb8aa3b, v140
	v_mul_f32_e32 v128, 0x3fb8aa3b, v192
	v_exp_f32_e32 v129, v129
	v_exp_f32_e32 v131, v130
	v_mul_f32_e32 v130, 0x3fb8aa3b, v141
	v_exp_f32_e32 v128, v128
	v_exp_f32_e32 v140, v130
	v_add_f32_e32 v129, 1.0, v129
	v_mul_f32_e32 v141, 0x3fb8aa3b, v143
	v_add_f32_e32 v128, 1.0, v128
	v_rcp_f32_e32 v130, v129
	v_add_f32_e32 v129, 1.0, v131
	v_add_f32_e32 v131, 1.0, v140
	v_mul_f32_e32 v140, 0x3fb8aa3b, v142
	v_exp_f32_e32 v141, v141
	v_mul_f32_e32 v142, 0x3fb8aa3b, v190
	v_rcp_f32_e32 v128, v128
	v_rcp_f32_e32 v129, v129
	v_exp_f32_e32 v140, v140
	v_exp_f32_e32 v143, v142
	v_mul_f32_e32 v142, 0x3fb8aa3b, v191
	v_rcp_f32_e32 v131, v131
	v_exp_f32_e32 v181, v142
	v_add_f32_e32 v141, 1.0, v141
	v_add_f32_e64 v190, -v164, 1.0
	v_add_f32_e64 v191, -v165, 1.0
	v_add_f32_e32 v140, 1.0, v140
	v_rcp_f32_e32 v142, v141
	v_add_f32_e32 v141, 1.0, v143
	v_mul_f32_e32 v128, v190, v128
	v_mul_f32_e32 v129, v191, v129
	v_add_f32_e64 v190, -v166, 1.0
	v_add_f32_e64 v191, -v167, 1.0
	v_rcp_f32_e32 v140, v140
	v_rcp_f32_e32 v141, v141
	v_add_f32_e32 v143, 1.0, v181
	v_mul_f32_e32 v130, v190, v130
	v_mul_f32_e32 v131, v191, v131
	v_rcp_f32_e32 v143, v143
	v_cvt_pk_f16_f32 v128, v128, v129
	v_cvt_pk_f16_f32 v129, v130, v131
	v_and_b32_e32 v130, 0xffff0000, v129
	v_lshlrev_b32_e32 v131, 16, v129
	v_or_b32_sdwa v129, v130, v128 dst_sel:DWORD dst_unused:UNUSED_PAD src0_sel:DWORD src1_sel:WORD_1
	v_or_b32_sdwa v128, v131, v128 dst_sel:DWORD dst_unused:UNUSED_PAD src0_sel:DWORD src1_sel:WORD_0
	v_add_f32_e64 v130, -v168, 1.0
	v_add_f32_e64 v131, -v169, 1.0
	s_nop 0
	v_mul_f32_e32 v130, v130, v140
	v_mul_f32_e32 v131, v131, v141
	v_add_f32_e64 v140, -v170, 1.0
	v_add_f32_e64 v141, -v171, 1.0
	v_cvt_pk_f16_f32 v130, v130, v131
	v_mul_f32_e32 v140, v140, v142
	v_mul_f32_e32 v141, v141, v143
	s_nop 0
	v_cvt_pk_f16_f32 v131, v140, v141
	v_and_b32_e32 v140, 0xffff0000, v131
	v_lshlrev_b32_e32 v141, 16, v131
	v_or_b32_sdwa v131, v140, v130 dst_sel:DWORD dst_unused:UNUSED_PAD src0_sel:DWORD src1_sel:WORD_1
	v_or_b32_sdwa v130, v141, v130 dst_sel:DWORD dst_unused:UNUSED_PAD src0_sel:DWORD src1_sel:WORD_0

; template <int RSM> __device__ __forceinline__ float row_scale(const float* p, int row) { const float v = __hip_atomic_load(p + row, __ATOMIC_RELAXED, __HIP_MEMORY_SCOPE_AGENT); return RSM == 0 ? v : 1.0f / sqrtf(v * (1.f / DM) + EPS); }
;     __device__ __forceinline__ void operator()(const f32x4 (&acc)[2][2][4][2], const Unit& u, int wr, int wc, int fr, int fq) const {
;     ...
;             for (int m = 0; m < 4; ++m) { const int row = row0 + ai * HALF + m * 16; const float sc = row_scale<1>(rs, row);
;                 f32x4 c0, c1, s0, s1;
;                 if (rope) { const int pos = row & (SEQ - 1); c0 = *(const f32x4*)(ropeC + pos * 8); c1 = *(const f32x4*)(ropeC + pos * 8 + 4); s0 = *(const f32x4*)(ropeS + pos * 8); s1 = *(const f32x4*)(ropeS + pos * 8 + 4); }
; #pragma unroll
;                 for (int bj = 0; bj < 2; ++bj) { const f32x4 a0 = acc[ai][bj][m][0] * sc, a1 = acc[ai][bj][m][1] * sc;
;                     float v[8] = {a0[0], a0[1], a0[2], a0[3], a1[0], a1[1], a1[2], a1[3]};
.LBB0_290:
	s_waitcnt vmcnt(0)
	v_lshlrev_b64 v[128:129], 11, v[128:129]
	s_nop 0
	s_mov_b64 s[0:1], -1
	v_mov_b32_e32 v132, v248
	v_lshl_add_u64 v[130:131], v[184:185], 0, v[128:129]
	v_mul_f32_e32 v134, v126, v132
	v_mul_f32_e32 v135, v127, v132
	v_mul_f32_e32 v136, v124, v132
	v_mul_f32_e32 v137, v125, v132
	v_mul_f32_e32 v124, v122, v132
	v_mul_f32_e32 v125, v123, v132
	v_mul_f32_e32 v126, v120, v132
	v_mul_f32_e32 v127, v121, v132
	s_and_b64 vcc, exec, s[14:15]
	s_cbranch_vccnz .LBB0_297
	s_and_b64 vcc, exec, s[12:13]
	s_cbranch_vccz .LBB0_541
	s_and_b64 vcc, exec, s[0:1]
	s_cbranch_vccnz .LBB0_546

; __device__ __forceinline__ float sigm(float x) { return __builtin_amdgcn_rcpf(1.f + fexp(-x)); }
; __device__ __forceinline__ unsigned pkh(float lo, float hi) { const _Float16 a = (_Float16)lo, b = (_Float16)hi; return (unsigned)__builtin_bit_cast(unsigned short, a) | ((unsigned)__builtin_bit_cast(unsigned short, b) << 16); }
;     __device__ __forceinline__ void operator()(const f32x4 (&acc)[2][2][4][2], const Unit& u, int wr, int wc, int fr, int fq) const {
;     ...
;                     if (reg == PB_LF) {
; #pragma unroll
;                         for (int j = 0; j < 8; ++j) v[j] = (1.f - lb[bj][j]) * sigm(-v[j]);
;                         w.x = pkh(v[0], v[1]); w.y = pkh(v[2], v[3]); w.z = pkh(v[4], v[5]); w.w = pkh(v[6], v[7]);
.LBB0_295:
	v_mul_f32_e32 v121, 0x3fb8aa3b, v187
	v_mul_f32_e32 v122, 0x3fb8aa3b, v138
	v_exp_f32_e32 v121, v121
	v_exp_f32_e32 v123, v122
	v_mul_f32_e32 v122, 0x3fb8aa3b, v139
	v_exp_f32_e32 v133, v122
	v_add_f32_e32 v121, 1.0, v121
	v_rcp_f32_e32 v122, v121
	v_add_f32_e32 v121, 1.0, v123
	v_add_f32_e32 v123, 1.0, v133
	v_mul_f32_e32 v133, 0x3fb8aa3b, v140
	v_mul_f32_e32 v120, 0x3fb8aa3b, v186
	v_exp_f32_e32 v133, v133
	v_mul_f32_e32 v138, 0x3fb8aa3b, v141
	v_exp_f32_e32 v120, v120
	v_exp_f32_e32 v139, v138
	v_add_f32_e32 v133, 1.0, v133
	v_rcp_f32_e32 v138, v133
	v_add_f32_e32 v120, 1.0, v120
	v_add_f32_e32 v133, 1.0, v139
	v_mul_f32_e32 v139, 0x3fb8aa3b, v142
	v_rcp_f32_e32 v120, v120
	v_rcp_f32_e32 v121, v121
	v_exp_f32_e32 v139, v139
	v_mul_f32_e32 v140, 0x3fb8aa3b, v143
	v_rcp_f32_e32 v123, v123
	v_exp_f32_e32 v141, v140
	v_add_f32_e64 v142, -v178, 1.0
	v_add_f32_e64 v143, -v179, 1.0
	v_rcp_f32_e32 v140, v133
	v_add_f32_e32 v133, 1.0, v139
	v_mul_f32_e32 v120, v142, v120
	v_mul_f32_e32 v121, v143, v121
	v_add_f32_e64 v142, -v174, 1.0
	v_add_f32_e64 v143, -v175, 1.0
	v_rcp_f32_e32 v139, v133
	v_add_f32_e32 v133, 1.0, v141
	v_mul_f32_e32 v122, v142, v122
	v_mul_f32_e32 v123, v143, v123
	v_rcp_f32_e32 v141, v133
	v_cvt_pk_f16_f32 v120, v120, v121
	v_cvt_pk_f16_f32 v121, v122, v123
	v_and_b32_e32 v122, 0xffff0000, v121
	v_lshlrev_b32_e32 v123, 16, v121
	v_or_b32_sdwa v121, v122, v120 dst_sel:DWORD dst_unused:UNUSED_PAD src0_sel:DWORD src1_sel:WORD_1
	v_or_b32_sdwa v120, v123, v120 dst_sel:DWORD dst_unused:UNUSED_PAD src0_sel:DWORD src1_sel:WORD_0
	v_add_f32_e64 v122, -v176, 1.0
	v_add_f32_e64 v123, -v177, 1.0
	s_nop 0
	v_mul_f32_e32 v122, v122, v138
	v_mul_f32_e32 v123, v123, v139
	v_add_f32_e64 v138, -v172, 1.0
	v_add_f32_e64 v139, -v173, 1.0
	v_cvt_pk_f16_f32 v122, v122, v123
	v_mul_f32_e32 v138, v138, v140
	v_mul_f32_e32 v139, v139, v141
	s_nop 0
	v_cvt_pk_f16_f32 v123, v138, v139
	v_and_b32_e32 v133, 0xffff0000, v123
	v_lshlrev_b32_e32 v138, 16, v123
	v_or_b32_sdwa v123, v133, v122 dst_sel:DWORD dst_unused:UNUSED_PAD src0_sel:DWORD src1_sel:WORD_1
	v_or_b32_sdwa v122, v138, v122 dst_sel:DWORD dst_unused:UNUSED_PAD src0_sel:DWORD src1_sel:WORD_0

;     __device__ __forceinline__ void operator()(const f32x4 (&acc)[2][2][4][2], const Unit& u, int wr, int wc, int fr, int fq) const {
;     ...
;                 for (int bj = 0; bj < 2; ++bj) { const f32x4 a0 = acc[ai][bj][m][0] * sc, a1 = acc[ai][bj][m][1] * sc;
;                     float v[8] = {a0[0], a0[1], a0[2], a0[3], a1[0], a1[1], a1[2], a1[3]};
.LBB0_299:
	v_mov_b32_e32 v133, v132
	v_mov_b32_e32 v124, v132
	v_mov_b32_e32 v125, v132
	v_mul_f32_e32 v120, v118, v124
	v_mul_f32_e32 v121, v119, v125
	v_mul_f32_e32 v122, v116, v132
	v_mul_f32_e32 v123, v117, v133
	v_mul_f32_e32 v116, v114, v124
	v_mul_f32_e32 v117, v115, v125
	v_mul_f32_e32 v118, v112, v132
	v_mul_f32_e32 v119, v113, v133
	s_and_b64 vcc, exec, s[14:15]
	s_mov_b64 s[0:1], -1
	s_cbranch_vccnz .LBB0_306
	s_and_b64 vcc, exec, s[12:13]
	s_cbranch_vccz .LBB0_596
	s_and_b64 vcc, exec, s[0:1]
	s_cbranch_vccnz .LBB0_601

; __device__ __forceinline__ float sigm(float x) { return __builtin_amdgcn_rcpf(1.f + fexp(-x)); }
; __device__ __forceinline__ unsigned pkh(float lo, float hi) { const _Float16 a = (_Float16)lo, b = (_Float16)hi; return (unsigned)__builtin_bit_cast(unsigned short, a) | ((unsigned)__builtin_bit_cast(unsigned short, b) << 16); }
;     __device__ __forceinline__ void operator()(const f32x4 (&acc)[2][2][4][2], const Unit& u, int wr, int wc, int fr, int fq) const {
;     ...
;                     if (reg == PB_LF) {
; #pragma unroll
;                         for (int j = 0; j < 8; ++j) v[j] = (1.f - lb[bj][j]) * sigm(-v[j]);
;                         w.x = pkh(v[0], v[1]); w.y = pkh(v[2], v[3]); w.z = pkh(v[4], v[5]); w.w = pkh(v[6], v[7]);
.LBB0_304:
	v_mul_f32_e32 v113, 0x3fb8aa3b, v135
	v_mul_f32_e32 v114, 0x3fb8aa3b, v124
	v_exp_f32_e32 v113, v113
	v_exp_f32_e32 v115, v114
	v_mul_f32_e32 v114, 0x3fb8aa3b, v125
	v_exp_f32_e32 v124, v114
	v_mul_f32_e32 v112, 0x3fb8aa3b, v134
	v_exp_f32_e32 v112, v112
	v_add_f32_e32 v113, 1.0, v113
	v_rcp_f32_e32 v114, v113
	v_add_f32_e32 v113, 1.0, v115
	v_add_f32_e32 v115, 1.0, v124
	v_mul_f32_e32 v124, 0x3fb8aa3b, v126
	v_mul_f32_e32 v125, 0x3fb8aa3b, v127
	v_mul_f32_e32 v126, 0x3fb8aa3b, v132
	v_exp_f32_e32 v125, v125
	v_exp_f32_e32 v127, v126
	v_mul_f32_e32 v126, 0x3fb8aa3b, v133
	v_add_f32_e32 v112, 1.0, v112
	v_exp_f32_e32 v132, v126
	v_rcp_f32_e32 v112, v112
	v_rcp_f32_e32 v113, v113
	v_exp_f32_e32 v124, v124
	v_rcp_f32_e32 v115, v115
	v_add_f32_e32 v125, 1.0, v125
	v_rcp_f32_e32 v126, v125
	v_add_f32_e32 v125, 1.0, v127
	v_add_f32_e32 v127, 1.0, v132
	v_add_f32_e64 v132, -v164, 1.0
	v_add_f32_e64 v133, -v165, 1.0
	v_add_f32_e32 v124, 1.0, v124
	v_mul_f32_e32 v112, v132, v112
	v_mul_f32_e32 v113, v133, v113
	v_add_f32_e64 v132, -v166, 1.0
	v_add_f32_e64 v133, -v167, 1.0
	v_rcp_f32_e32 v124, v124
	v_rcp_f32_e32 v125, v125
	v_mul_f32_e32 v114, v132, v114
	v_mul_f32_e32 v115, v133, v115
	v_rcp_f32_e32 v127, v127
	v_cvt_pk_f16_f32 v112, v112, v113
	v_cvt_pk_f16_f32 v113, v114, v115
	v_and_b32_e32 v114, 0xffff0000, v113
	v_lshlrev_b32_e32 v115, 16, v113
	v_or_b32_sdwa v113, v114, v112 dst_sel:DWORD dst_unused:UNUSED_PAD src0_sel:DWORD src1_sel:WORD_1
	v_or_b32_sdwa v112, v115, v112 dst_sel:DWORD dst_unused:UNUSED_PAD src0_sel:DWORD src1_sel:WORD_0
	v_add_f32_e64 v114, -v168, 1.0
	v_add_f32_e64 v115, -v169, 1.0
	s_nop 0
	v_mul_f32_e32 v114, v114, v124
	v_mul_f32_e32 v115, v115, v125
	v_add_f32_e64 v124, -v170, 1.0
	v_add_f32_e64 v125, -v171, 1.0
	v_cvt_pk_f16_f32 v114, v114, v115
	v_mul_f32_e32 v124, v124, v126
	v_mul_f32_e32 v125, v125, v127
	s_nop 0
	v_cvt_pk_f16_f32 v115, v124, v125
	v_and_b32_e32 v124, 0xffff0000, v115
	v_lshlrev_b32_e32 v125, 16, v115
	v_or_b32_sdwa v115, v124, v114 dst_sel:DWORD dst_unused:UNUSED_PAD src0_sel:DWORD src1_sel:WORD_1
	v_or_b32_sdwa v114, v125, v114 dst_sel:DWORD dst_unused:UNUSED_PAD src0_sel:DWORD src1_sel:WORD_0

; template <int RSM> __device__ __forceinline__ float row_scale(const float* p, int row) { const float v = __hip_atomic_load(p + row, __ATOMIC_RELAXED, __HIP_MEMORY_SCOPE_AGENT); return RSM == 0 ? v : 1.0f / sqrtf(v * (1.f / DM) + EPS); }
;     __device__ __forceinline__ void operator()(const f32x4 (&acc)[2][2][4][2], const Unit& u, int wr, int wc, int fr, int fq) const {
;     ...
;             for (int m = 0; m < 4; ++m) { const int row = row0 + ai * HALF + m * 16; const float sc = row_scale<1>(rs, row);
;                 f32x4 c0, c1, s0, s1;
;                 if (rope) { const int pos = row & (SEQ - 1); c0 = *(const f32x4*)(ropeC + pos * 8); c1 = *(const f32x4*)(ropeC + pos * 8 + 4); s0 = *(const f32x4*)(ropeS + pos * 8); s1 = *(const f32x4*)(ropeS + pos * 8 + 4); }
; #pragma unroll
;                 for (int bj = 0; bj < 2; ++bj) { const f32x4 a0 = acc[ai][bj][m][0] * sc, a1 = acc[ai][bj][m][1] * sc;
;                     float v[8] = {a0[0], a0[1], a0[2], a0[3], a1[0], a1[1], a1[2], a1[3]};
.LBB0_310:
	s_waitcnt vmcnt(0)
	v_lshlrev_b64 v[112:113], 11, v[112:113]
	s_nop 0
	s_mov_b64 s[0:1], -1
	v_mov_b32_e32 v116, v249
	v_lshl_add_u64 v[114:115], v[184:185], 0, v[112:113]
	v_mul_f32_e32 v118, v110, v116
	v_mul_f32_e32 v119, v111, v116
	v_mul_f32_e32 v120, v108, v116
	v_mul_f32_e32 v121, v109, v116
	v_mul_f32_e32 v108, v106, v116
	v_mul_f32_e32 v109, v107, v116
	v_mul_f32_e32 v110, v104, v116
	v_mul_f32_e32 v111, v105, v116
	s_and_b64 vcc, exec, s[14:15]
	s_cbranch_vccnz .LBB0_317
	s_and_b64 vcc, exec, s[12:13]
	s_cbranch_vccz .LBB0_651
	s_and_b64 vcc, exec, s[0:1]
	s_cbranch_vccnz .LBB0_656

; __device__ __forceinline__ float sigm(float x) { return __builtin_amdgcn_rcpf(1.f + fexp(-x)); }
; __device__ __forceinline__ unsigned pkh(float lo, float hi) { const _Float16 a = (_Float16)lo, b = (_Float16)hi; return (unsigned)__builtin_bit_cast(unsigned short, a) | ((unsigned)__builtin_bit_cast(unsigned short, b) << 16); }
;     __device__ __forceinline__ void operator()(const f32x4 (&acc)[2][2][4][2], const Unit& u, int wr, int wc, int fr, int fq) const {
;     ...
;                     if (reg == PB_LF) {
; #pragma unroll
;                         for (int j = 0; j < 8; ++j) v[j] = (1.f - lb[bj][j]) * sigm(-v[j]);
;                         w.x = pkh(v[0], v[1]); w.y = pkh(v[2], v[3]); w.z = pkh(v[4], v[5]); w.w = pkh(v[6], v[7]);
.LBB0_315:
	v_mul_f32_e32 v105, 0x3fb8aa3b, v129
	v_mul_f32_e32 v106, 0x3fb8aa3b, v122
	v_exp_f32_e32 v105, v105
	v_exp_f32_e32 v107, v106
	v_mul_f32_e32 v106, 0x3fb8aa3b, v123
	v_exp_f32_e32 v117, v106
	v_add_f32_e32 v105, 1.0, v105
	v_rcp_f32_e32 v106, v105
	v_add_f32_e32 v105, 1.0, v107
	v_add_f32_e32 v107, 1.0, v117
	v_mul_f32_e32 v117, 0x3fb8aa3b, v124
	v_mul_f32_e32 v104, 0x3fb8aa3b, v128
	v_exp_f32_e32 v117, v117
	v_mul_f32_e32 v122, 0x3fb8aa3b, v125
	v_exp_f32_e32 v104, v104
	v_exp_f32_e32 v123, v122
	v_add_f32_e32 v117, 1.0, v117
	v_rcp_f32_e32 v122, v117
	v_add_f32_e32 v104, 1.0, v104
	v_add_f32_e32 v117, 1.0, v123
	v_mul_f32_e32 v123, 0x3fb8aa3b, v126
	v_rcp_f32_e32 v104, v104
	v_rcp_f32_e32 v105, v105
	v_exp_f32_e32 v123, v123
	v_mul_f32_e32 v124, 0x3fb8aa3b, v127
	v_rcp_f32_e32 v107, v107
	v_exp_f32_e32 v125, v124
	v_add_f32_e64 v126, -v178, 1.0
	v_add_f32_e64 v127, -v179, 1.0
	v_rcp_f32_e32 v124, v117
	v_add_f32_e32 v117, 1.0, v123
	v_mul_f32_e32 v104, v126, v104
	v_mul_f32_e32 v105, v127, v105
	v_add_f32_e64 v126, -v174, 1.0
	v_add_f32_e64 v127, -v175, 1.0
	v_rcp_f32_e32 v123, v117
	v_add_f32_e32 v117, 1.0, v125
	v_mul_f32_e32 v106, v126, v106
	v_mul_f32_e32 v107, v127, v107
	v_rcp_f32_e32 v125, v117
	v_cvt_pk_f16_f32 v104, v104, v105
	v_cvt_pk_f16_f32 v105, v106, v107
	v_and_b32_e32 v106, 0xffff0000, v105
	v_lshlrev_b32_e32 v107, 16, v105
	v_or_b32_sdwa v105, v106, v104 dst_sel:DWORD dst_unused:UNUSED_PAD src0_sel:DWORD src1_sel:WORD_1
	v_or_b32_sdwa v104, v107, v104 dst_sel:DWORD dst_unused:UNUSED_PAD src0_sel:DWORD src1_sel:WORD_0
	v_add_f32_e64 v106, -v176, 1.0
	v_add_f32_e64 v107, -v177, 1.0
	s_nop 0
	v_mul_f32_e32 v106, v106, v122
	v_mul_f32_e32 v107, v107, v123
	v_add_f32_e64 v122, -v172, 1.0
	v_add_f32_e64 v123, -v173, 1.0
	v_cvt_pk_f16_f32 v106, v106, v107
	v_mul_f32_e32 v122, v122, v124
	v_mul_f32_e32 v123, v123, v125
	s_nop 0
	v_cvt_pk_f16_f32 v107, v122, v123
	v_and_b32_e32 v117, 0xffff0000, v107
	v_lshlrev_b32_e32 v122, 16, v107
	v_or_b32_sdwa v107, v117, v106 dst_sel:DWORD dst_unused:UNUSED_PAD src0_sel:DWORD src1_sel:WORD_1
	v_or_b32_sdwa v106, v122, v106 dst_sel:DWORD dst_unused:UNUSED_PAD src0_sel:DWORD src1_sel:WORD_0

;     __device__ __forceinline__ void operator()(const f32x4 (&acc)[2][2][4][2], const Unit& u, int wr, int wc, int fr, int fq) const {
;     ...
;                 for (int bj = 0; bj < 2; ++bj) { const f32x4 a0 = acc[ai][bj][m][0] * sc, a1 = acc[ai][bj][m][1] * sc;
;                     float v[8] = {a0[0], a0[1], a0[2], a0[3], a1[0], a1[1], a1[2], a1[3]};
.LBB0_319:
	v_mov_b32_e32 v117, v116
	v_mov_b32_e32 v108, v116
	v_mov_b32_e32 v109, v116
	v_mul_f32_e32 v104, v102, v108
	v_mul_f32_e32 v105, v103, v109
	v_mul_f32_e32 v106, v100, v116
	v_mul_f32_e32 v107, v101, v117
	v_mul_f32_e32 v100, v98, v108
	v_mul_f32_e32 v101, v99, v109
	v_mul_f32_e32 v102, v96, v116
	v_mul_f32_e32 v103, v97, v117
	s_and_b64 vcc, exec, s[14:15]
	s_mov_b64 s[0:1], -1
	s_cbranch_vccnz .LBB0_326
	s_and_b64 vcc, exec, s[12:13]
	s_cbranch_vccz .LBB0_706
	s_and_b64 vcc, exec, s[0:1]
	s_cbranch_vccnz .LBB0_711

; __device__ __forceinline__ float sigm(float x) { return __builtin_amdgcn_rcpf(1.f + fexp(-x)); }
; __device__ __forceinline__ unsigned pkh(float lo, float hi) { const _Float16 a = (_Float16)lo, b = (_Float16)hi; return (unsigned)__builtin_bit_cast(unsigned short, a) | ((unsigned)__builtin_bit_cast(unsigned short, b) << 16); }
;     __device__ __forceinline__ void operator()(const f32x4 (&acc)[2][2][4][2], const Unit& u, int wr, int wc, int fr, int fq) const {
;     ...
;                     if (reg == PB_LF) {
; #pragma unroll
;                         for (int j = 0; j < 8; ++j) v[j] = (1.f - lb[bj][j]) * sigm(-v[j]);
;                         w.x = pkh(v[0], v[1]); w.y = pkh(v[2], v[3]); w.z = pkh(v[4], v[5]); w.w = pkh(v[6], v[7]);
.LBB0_324:
	v_mul_f32_e32 v97, 0x3fb8aa3b, v119
	v_mul_f32_e32 v98, 0x3fb8aa3b, v108
	v_exp_f32_e32 v97, v97
	v_exp_f32_e32 v99, v98
	v_mul_f32_e32 v98, 0x3fb8aa3b, v109
	v_exp_f32_e32 v108, v98
	v_mul_f32_e32 v96, 0x3fb8aa3b, v118
	v_exp_f32_e32 v96, v96
	v_add_f32_e32 v97, 1.0, v97
	v_rcp_f32_e32 v98, v97
	v_add_f32_e32 v97, 1.0, v99
	v_add_f32_e32 v99, 1.0, v108
	v_mul_f32_e32 v108, 0x3fb8aa3b, v110
	v_mul_f32_e32 v109, 0x3fb8aa3b, v111
	v_mul_f32_e32 v110, 0x3fb8aa3b, v116
	v_exp_f32_e32 v109, v109
	v_exp_f32_e32 v111, v110
	v_mul_f32_e32 v110, 0x3fb8aa3b, v117
	v_add_f32_e32 v96, 1.0, v96
	v_exp_f32_e32 v116, v110
	v_rcp_f32_e32 v96, v96
	v_rcp_f32_e32 v97, v97
	v_exp_f32_e32 v108, v108
	v_rcp_f32_e32 v99, v99
	v_add_f32_e32 v109, 1.0, v109
	v_rcp_f32_e32 v110, v109
	v_add_f32_e32 v109, 1.0, v111
	v_add_f32_e32 v111, 1.0, v116
	v_add_f32_e64 v116, -v164, 1.0
	v_add_f32_e64 v117, -v165, 1.0
	v_add_f32_e32 v108, 1.0, v108
	v_mul_f32_e32 v96, v116, v96
	v_mul_f32_e32 v97, v117, v97
	v_add_f32_e64 v116, -v166, 1.0
	v_add_f32_e64 v117, -v167, 1.0
	v_rcp_f32_e32 v108, v108
	v_rcp_f32_e32 v109, v109
	v_mul_f32_e32 v98, v116, v98
	v_mul_f32_e32 v99, v117, v99
	v_rcp_f32_e32 v111, v111
	v_cvt_pk_f16_f32 v96, v96, v97
	v_cvt_pk_f16_f32 v97, v98, v99
	v_and_b32_e32 v98, 0xffff0000, v97
	v_lshlrev_b32_e32 v99, 16, v97
	v_or_b32_sdwa v97, v98, v96 dst_sel:DWORD dst_unused:UNUSED_PAD src0_sel:DWORD src1_sel:WORD_1
	v_or_b32_sdwa v96, v99, v96 dst_sel:DWORD dst_unused:UNUSED_PAD src0_sel:DWORD src1_sel:WORD_0
	v_add_f32_e64 v98, -v168, 1.0
	v_add_f32_e64 v99, -v169, 1.0
	s_nop 0
	v_mul_f32_e32 v98, v98, v108
	v_mul_f32_e32 v99, v99, v109
	v_add_f32_e64 v108, -v170, 1.0
	v_add_f32_e64 v109, -v171, 1.0
	v_cvt_pk_f16_f32 v98, v98, v99
	v_mul_f32_e32 v108, v108, v110
	v_mul_f32_e32 v109, v109, v111
	s_nop 0
	v_cvt_pk_f16_f32 v99, v108, v109
	v_and_b32_e32 v108, 0xffff0000, v99
	v_lshlrev_b32_e32 v109, 16, v99
	v_or_b32_sdwa v99, v108, v98 dst_sel:DWORD dst_unused:UNUSED_PAD src0_sel:DWORD src1_sel:WORD_1
	v_or_b32_sdwa v98, v109, v98 dst_sel:DWORD dst_unused:UNUSED_PAD src0_sel:DWORD src1_sel:WORD_0

; template <int RSM> __device__ __forceinline__ float row_scale(const float* p, int row) { const float v = __hip_atomic_load(p + row, __ATOMIC_RELAXED, __HIP_MEMORY_SCOPE_AGENT); return RSM == 0 ? v : 1.0f / sqrtf(v * (1.f / DM) + EPS); }
;     __device__ __forceinline__ void operator()(const f32x4 (&acc)[2][2][4][2], const Unit& u, int wr, int wc, int fr, int fq) const {
;     ...
;             for (int m = 0; m < 4; ++m) { const int row = row0 + ai * HALF + m * 16; const float sc = row_scale<1>(rs, row);
;                 f32x4 c0, c1, s0, s1;
;                 if (rope) { const int pos = row & (SEQ - 1); c0 = *(const f32x4*)(ropeC + pos * 8); c1 = *(const f32x4*)(ropeC + pos * 8 + 4); s0 = *(const f32x4*)(ropeS + pos * 8); s1 = *(const f32x4*)(ropeS + pos * 8 + 4); }
; #pragma unroll
;                 for (int bj = 0; bj < 2; ++bj) { const f32x4 a0 = acc[ai][bj][m][0] * sc, a1 = acc[ai][bj][m][1] * sc;
;                     float v[8] = {a0[0], a0[1], a0[2], a0[3], a1[0], a1[1], a1[2], a1[3]};
.LBB0_330:
	s_waitcnt vmcnt(0)
	v_lshlrev_b64 v[96:97], 11, v[96:97]
	s_nop 0
	s_mov_b64 s[0:1], -1
	v_mov_b32_e32 v100, v251
	v_lshl_add_u64 v[98:99], v[184:185], 0, v[96:97]
	v_mul_f32_e32 v102, v94, v100
	v_mul_f32_e32 v103, v95, v100
	v_mul_f32_e32 v104, v92, v100
	v_mul_f32_e32 v105, v93, v100
	v_mul_f32_e32 v92, v90, v100
	v_mul_f32_e32 v93, v91, v100
	v_mul_f32_e32 v94, v88, v100
	v_mul_f32_e32 v95, v89, v100
	s_and_b64 vcc, exec, s[14:15]
	s_cbranch_vccnz .LBB0_337
	s_and_b64 vcc, exec, s[12:13]
	s_cbranch_vccz .LBB0_761
	s_and_b64 vcc, exec, s[0:1]
	s_cbranch_vccnz .LBB0_766

; __device__ __forceinline__ float sigm(float x) { return __builtin_amdgcn_rcpf(1.f + fexp(-x)); }
; __device__ __forceinline__ unsigned pkh(float lo, float hi) { const _Float16 a = (_Float16)lo, b = (_Float16)hi; return (unsigned)__builtin_bit_cast(unsigned short, a) | ((unsigned)__builtin_bit_cast(unsigned short, b) << 16); }
;     __device__ __forceinline__ void operator()(const f32x4 (&acc)[2][2][4][2], const Unit& u, int wr, int wc, int fr, int fq) const {
;     ...
;                     if (reg == PB_LF) {
; #pragma unroll
;                         for (int j = 0; j < 8; ++j) v[j] = (1.f - lb[bj][j]) * sigm(-v[j]);
;                         w.x = pkh(v[0], v[1]); w.y = pkh(v[2], v[3]); w.z = pkh(v[4], v[5]); w.w = pkh(v[6], v[7]);
.LBB0_335:
	v_mul_f32_e32 v89, 0x3fb8aa3b, v113
	v_mul_f32_e32 v90, 0x3fb8aa3b, v106
	v_exp_f32_e32 v89, v89
	v_exp_f32_e32 v91, v90
	v_mul_f32_e32 v90, 0x3fb8aa3b, v107
	v_exp_f32_e32 v101, v90
	v_add_f32_e32 v89, 1.0, v89
	v_rcp_f32_e32 v90, v89
	v_add_f32_e32 v89, 1.0, v91
	v_add_f32_e32 v91, 1.0, v101
	v_mul_f32_e32 v101, 0x3fb8aa3b, v108
	v_mul_f32_e32 v88, 0x3fb8aa3b, v112
	v_exp_f32_e32 v101, v101
	v_mul_f32_e32 v106, 0x3fb8aa3b, v109
	v_exp_f32_e32 v88, v88
	v_exp_f32_e32 v107, v106
	v_add_f32_e32 v101, 1.0, v101
	v_rcp_f32_e32 v106, v101
	v_add_f32_e32 v88, 1.0, v88
	v_add_f32_e32 v101, 1.0, v107
	v_mul_f32_e32 v107, 0x3fb8aa3b, v110
	v_rcp_f32_e32 v88, v88
	v_rcp_f32_e32 v89, v89
	v_exp_f32_e32 v107, v107
	v_mul_f32_e32 v108, 0x3fb8aa3b, v111
	v_rcp_f32_e32 v91, v91
	v_exp_f32_e32 v109, v108
	v_add_f32_e64 v110, -v178, 1.0
	v_add_f32_e64 v111, -v179, 1.0
	v_rcp_f32_e32 v108, v101
	v_add_f32_e32 v101, 1.0, v107
	v_mul_f32_e32 v88, v110, v88
	v_mul_f32_e32 v89, v111, v89
	v_add_f32_e64 v110, -v174, 1.0
	v_add_f32_e64 v111, -v175, 1.0
	v_rcp_f32_e32 v107, v101
	v_add_f32_e32 v101, 1.0, v109
	v_mul_f32_e32 v90, v110, v90
	v_mul_f32_e32 v91, v111, v91
	v_rcp_f32_e32 v109, v101
	v_cvt_pk_f16_f32 v88, v88, v89
	v_cvt_pk_f16_f32 v89, v90, v91
	v_and_b32_e32 v90, 0xffff0000, v89
	v_lshlrev_b32_e32 v91, 16, v89
	v_or_b32_sdwa v89, v90, v88 dst_sel:DWORD dst_unused:UNUSED_PAD src0_sel:DWORD src1_sel:WORD_1
	v_or_b32_sdwa v88, v91, v88 dst_sel:DWORD dst_unused:UNUSED_PAD src0_sel:DWORD src1_sel:WORD_0
	v_add_f32_e64 v90, -v176, 1.0
	v_add_f32_e64 v91, -v177, 1.0
	s_nop 0
	v_mul_f32_e32 v90, v90, v106
	v_mul_f32_e32 v91, v91, v107
	v_add_f32_e64 v106, -v172, 1.0
	v_add_f32_e64 v107, -v173, 1.0
	v_cvt_pk_f16_f32 v90, v90, v91
	v_mul_f32_e32 v106, v106, v108
	v_mul_f32_e32 v107, v107, v109
	s_nop 0
	v_cvt_pk_f16_f32 v91, v106, v107
	v_and_b32_e32 v101, 0xffff0000, v91
	v_lshlrev_b32_e32 v106, 16, v91
	v_or_b32_sdwa v91, v101, v90 dst_sel:DWORD dst_unused:UNUSED_PAD src0_sel:DWORD src1_sel:WORD_1
	v_or_b32_sdwa v90, v106, v90 dst_sel:DWORD dst_unused:UNUSED_PAD src0_sel:DWORD src1_sel:WORD_0

;     __device__ __forceinline__ void operator()(const f32x4 (&acc)[2][2][4][2], const Unit& u, int wr, int wc, int fr, int fq) const {
;     ...
;                 for (int bj = 0; bj < 2; ++bj) { const f32x4 a0 = acc[ai][bj][m][0] * sc, a1 = acc[ai][bj][m][1] * sc;
;                     float v[8] = {a0[0], a0[1], a0[2], a0[3], a1[0], a1[1], a1[2], a1[3]};
.LBB0_339:
	v_mov_b32_e32 v101, v100
	v_mov_b32_e32 v92, v100
	v_mov_b32_e32 v93, v100
	v_mul_f32_e32 v88, v86, v92
	v_mul_f32_e32 v89, v87, v93
	v_mul_f32_e32 v90, v84, v100
	v_mul_f32_e32 v91, v85, v101
	v_mul_f32_e32 v84, v82, v92
	v_mul_f32_e32 v85, v83, v93
	v_mul_f32_e32 v86, v80, v100
	v_mul_f32_e32 v87, v81, v101
	s_and_b64 vcc, exec, s[14:15]
	s_mov_b64 s[0:1], -1
	s_cbranch_vccnz .LBB0_346
	s_and_b64 vcc, exec, s[12:13]
	s_cbranch_vccz .LBB0_816
	s_and_b64 vcc, exec, s[0:1]
	s_cbranch_vccnz .LBB0_821

; __device__ __forceinline__ float sigm(float x) { return __builtin_amdgcn_rcpf(1.f + fexp(-x)); }
; __device__ __forceinline__ unsigned pkh(float lo, float hi) { const _Float16 a = (_Float16)lo, b = (_Float16)hi; return (unsigned)__builtin_bit_cast(unsigned short, a) | ((unsigned)__builtin_bit_cast(unsigned short, b) << 16); }
;     __device__ __forceinline__ void operator()(const f32x4 (&acc)[2][2][4][2], const Unit& u, int wr, int wc, int fr, int fq) const {
;     ...
;                     if (reg == PB_LF) {
; #pragma unroll
;                         for (int j = 0; j < 8; ++j) v[j] = (1.f - lb[bj][j]) * sigm(-v[j]);
;                         w.x = pkh(v[0], v[1]); w.y = pkh(v[2], v[3]); w.z = pkh(v[4], v[5]); w.w = pkh(v[6], v[7]);
.LBB0_344:
	v_mul_f32_e32 v81, 0x3fb8aa3b, v103
	v_mul_f32_e32 v82, 0x3fb8aa3b, v92
	v_exp_f32_e32 v81, v81
	v_exp_f32_e32 v83, v82
	v_mul_f32_e32 v82, 0x3fb8aa3b, v93
	v_exp_f32_e32 v92, v82
	v_mul_f32_e32 v80, 0x3fb8aa3b, v102
	v_exp_f32_e32 v80, v80
	v_add_f32_e32 v81, 1.0, v81
	v_rcp_f32_e32 v82, v81
	v_add_f32_e32 v81, 1.0, v83
	v_add_f32_e32 v83, 1.0, v92
	v_mul_f32_e32 v92, 0x3fb8aa3b, v94
	v_mul_f32_e32 v93, 0x3fb8aa3b, v95
	v_mul_f32_e32 v94, 0x3fb8aa3b, v100
	v_exp_f32_e32 v93, v93
	v_exp_f32_e32 v95, v94
	v_mul_f32_e32 v94, 0x3fb8aa3b, v101
	v_add_f32_e32 v80, 1.0, v80
	v_exp_f32_e32 v100, v94
	v_rcp_f32_e32 v80, v80
	v_rcp_f32_e32 v81, v81
	v_exp_f32_e32 v92, v92
	v_rcp_f32_e32 v83, v83
	v_add_f32_e32 v93, 1.0, v93
	v_rcp_f32_e32 v94, v93
	v_add_f32_e32 v93, 1.0, v95
	v_add_f32_e32 v95, 1.0, v100
	v_add_f32_e64 v100, -v164, 1.0
	v_add_f32_e64 v101, -v165, 1.0
	v_add_f32_e32 v92, 1.0, v92
	v_mul_f32_e32 v80, v100, v80
	v_mul_f32_e32 v81, v101, v81
	v_add_f32_e64 v100, -v166, 1.0
	v_add_f32_e64 v101, -v167, 1.0
	v_rcp_f32_e32 v92, v92
	v_rcp_f32_e32 v93, v93
	v_mul_f32_e32 v82, v100, v82
	v_mul_f32_e32 v83, v101, v83
	v_rcp_f32_e32 v95, v95
	v_cvt_pk_f16_f32 v80, v80, v81
	v_cvt_pk_f16_f32 v81, v82, v83
	v_and_b32_e32 v82, 0xffff0000, v81
	v_lshlrev_b32_e32 v83, 16, v81
	v_or_b32_sdwa v81, v82, v80 dst_sel:DWORD dst_unused:UNUSED_PAD src0_sel:DWORD src1_sel:WORD_1
	v_or_b32_sdwa v80, v83, v80 dst_sel:DWORD dst_unused:UNUSED_PAD src0_sel:DWORD src1_sel:WORD_0
	v_add_f32_e64 v82, -v168, 1.0
	v_add_f32_e64 v83, -v169, 1.0
	s_nop 0
	v_mul_f32_e32 v82, v82, v92
	v_mul_f32_e32 v83, v83, v93
	v_add_f32_e64 v92, -v170, 1.0
	v_add_f32_e64 v93, -v171, 1.0
	v_cvt_pk_f16_f32 v82, v82, v83
	v_mul_f32_e32 v92, v92, v94
	v_mul_f32_e32 v93, v93, v95
	s_nop 0
	v_cvt_pk_f16_f32 v83, v92, v93
	v_and_b32_e32 v92, 0xffff0000, v83
	v_lshlrev_b32_e32 v93, 16, v83
	v_or_b32_sdwa v83, v92, v82 dst_sel:DWORD dst_unused:UNUSED_PAD src0_sel:DWORD src1_sel:WORD_1
	v_or_b32_sdwa v82, v93, v82 dst_sel:DWORD dst_unused:UNUSED_PAD src0_sel:DWORD src1_sel:WORD_0

; template <int RSM> __device__ __forceinline__ float row_scale(const float* p, int row) { const float v = __hip_atomic_load(p + row, __ATOMIC_RELAXED, __HIP_MEMORY_SCOPE_AGENT); return RSM == 0 ? v : 1.0f / sqrtf(v * (1.f / DM) + EPS); }
;     __device__ __forceinline__ void operator()(const f32x4 (&acc)[2][2][4][2], const Unit& u, int wr, int wc, int fr, int fq) const {
;     ...
;             for (int m = 0; m < 4; ++m) { const int row = row0 + ai * HALF + m * 16; const float sc = row_scale<1>(rs, row);
;                 f32x4 c0, c1, s0, s1;
;                 if (rope) { const int pos = row & (SEQ - 1); c0 = *(const f32x4*)(ropeC + pos * 8); c1 = *(const f32x4*)(ropeC + pos * 8 + 4); s0 = *(const f32x4*)(ropeS + pos * 8); s1 = *(const f32x4*)(ropeS + pos * 8 + 4); }
; #pragma unroll
;                 for (int bj = 0; bj < 2; ++bj) { const f32x4 a0 = acc[ai][bj][m][0] * sc, a1 = acc[ai][bj][m][1] * sc;
;                     float v[8] = {a0[0], a0[1], a0[2], a0[3], a1[0], a1[1], a1[2], a1[3]};
.LBB0_350:
	s_waitcnt vmcnt(0)
	v_lshlrev_b64 v[80:81], 11, v[80:81]
	s_nop 0
	s_mov_b64 s[0:1], -1
	v_mov_b32_e32 v84, v252
	v_lshl_add_u64 v[82:83], v[184:185], 0, v[80:81]
	v_mul_f32_e32 v86, v78, v84
	v_mul_f32_e32 v87, v79, v84
	v_mul_f32_e32 v88, v76, v84
	v_mul_f32_e32 v89, v77, v84
	v_mul_f32_e32 v76, v74, v84
	v_mul_f32_e32 v77, v75, v84
	v_mul_f32_e32 v78, v72, v84
	v_mul_f32_e32 v79, v73, v84
	s_and_b64 vcc, exec, s[14:15]
	s_cbranch_vccnz .LBB0_357
	s_and_b64 vcc, exec, s[12:13]
	s_cbranch_vccz .LBB0_871
	s_and_b64 vcc, exec, s[0:1]
	s_cbranch_vccnz .LBB0_876

; __device__ __forceinline__ float sigm(float x) { return __builtin_amdgcn_rcpf(1.f + fexp(-x)); }
; __device__ __forceinline__ unsigned pkh(float lo, float hi) { const _Float16 a = (_Float16)lo, b = (_Float16)hi; return (unsigned)__builtin_bit_cast(unsigned short, a) | ((unsigned)__builtin_bit_cast(unsigned short, b) << 16); }
;     __device__ __forceinline__ void operator()(const f32x4 (&acc)[2][2][4][2], const Unit& u, int wr, int wc, int fr, int fq) const {
;     ...
;                     if (reg == PB_LF) {
; #pragma unroll
;                         for (int j = 0; j < 8; ++j) v[j] = (1.f - lb[bj][j]) * sigm(-v[j]);
;                         w.x = pkh(v[0], v[1]); w.y = pkh(v[2], v[3]); w.z = pkh(v[4], v[5]); w.w = pkh(v[6], v[7]);
.LBB0_355:
	v_mul_f32_e32 v73, 0x3fb8aa3b, v97
	v_mul_f32_e32 v74, 0x3fb8aa3b, v90
	v_exp_f32_e32 v73, v73
	v_exp_f32_e32 v75, v74
	v_mul_f32_e32 v74, 0x3fb8aa3b, v91
	v_exp_f32_e32 v85, v74
	v_add_f32_e32 v73, 1.0, v73
	v_rcp_f32_e32 v74, v73
	v_add_f32_e32 v73, 1.0, v75
	v_add_f32_e32 v75, 1.0, v85
	v_mul_f32_e32 v85, 0x3fb8aa3b, v92
	v_mul_f32_e32 v72, 0x3fb8aa3b, v96
	v_exp_f32_e32 v85, v85
	v_mul_f32_e32 v90, 0x3fb8aa3b, v93
	v_exp_f32_e32 v72, v72
	v_exp_f32_e32 v91, v90
	v_add_f32_e32 v85, 1.0, v85
	v_rcp_f32_e32 v90, v85
	v_add_f32_e32 v72, 1.0, v72
	v_add_f32_e32 v85, 1.0, v91
	v_mul_f32_e32 v91, 0x3fb8aa3b, v94
	v_rcp_f32_e32 v72, v72
	v_rcp_f32_e32 v73, v73
	v_exp_f32_e32 v91, v91
	v_mul_f32_e32 v92, 0x3fb8aa3b, v95
	v_rcp_f32_e32 v75, v75
	v_exp_f32_e32 v93, v92
	v_add_f32_e64 v94, -v178, 1.0
	v_add_f32_e64 v95, -v179, 1.0
	v_rcp_f32_e32 v92, v85
	v_add_f32_e32 v85, 1.0, v91
	v_mul_f32_e32 v72, v94, v72
	v_mul_f32_e32 v73, v95, v73
	v_add_f32_e64 v94, -v174, 1.0
	v_add_f32_e64 v95, -v175, 1.0
	v_rcp_f32_e32 v91, v85
	v_add_f32_e32 v85, 1.0, v93
	v_mul_f32_e32 v74, v94, v74
	v_mul_f32_e32 v75, v95, v75
	v_rcp_f32_e32 v93, v85
	v_cvt_pk_f16_f32 v72, v72, v73
	v_cvt_pk_f16_f32 v73, v74, v75
	v_and_b32_e32 v74, 0xffff0000, v73
	v_lshlrev_b32_e32 v75, 16, v73
	v_or_b32_sdwa v73, v74, v72 dst_sel:DWORD dst_unused:UNUSED_PAD src0_sel:DWORD src1_sel:WORD_1
	v_or_b32_sdwa v72, v75, v72 dst_sel:DWORD dst_unused:UNUSED_PAD src0_sel:DWORD src1_sel:WORD_0
	v_add_f32_e64 v74, -v176, 1.0
	v_add_f32_e64 v75, -v177, 1.0
	s_nop 0
	v_mul_f32_e32 v74, v74, v90
	v_mul_f32_e32 v75, v75, v91
	v_add_f32_e64 v90, -v172, 1.0
	v_add_f32_e64 v91, -v173, 1.0
	v_cvt_pk_f16_f32 v74, v74, v75
	v_mul_f32_e32 v90, v90, v92
	v_mul_f32_e32 v91, v91, v93
	s_nop 0
	v_cvt_pk_f16_f32 v75, v90, v91
	v_and_b32_e32 v85, 0xffff0000, v75
	v_lshlrev_b32_e32 v90, 16, v75
	v_or_b32_sdwa v75, v85, v74 dst_sel:DWORD dst_unused:UNUSED_PAD src0_sel:DWORD src1_sel:WORD_1
	v_or_b32_sdwa v74, v90, v74 dst_sel:DWORD dst_unused:UNUSED_PAD src0_sel:DWORD src1_sel:WORD_0

;     __device__ __forceinline__ void operator()(const f32x4 (&acc)[2][2][4][2], const Unit& u, int wr, int wc, int fr, int fq) const {
;     ...
;                 for (int bj = 0; bj < 2; ++bj) { const f32x4 a0 = acc[ai][bj][m][0] * sc, a1 = acc[ai][bj][m][1] * sc;
;                     float v[8] = {a0[0], a0[1], a0[2], a0[3], a1[0], a1[1], a1[2], a1[3]};
.LBB0_359:
	v_mov_b32_e32 v85, v84
	v_mov_b32_e32 v76, v84
	v_mov_b32_e32 v77, v84
	v_mul_f32_e32 v72, v70, v76
	v_mul_f32_e32 v73, v71, v77
	v_mul_f32_e32 v74, v68, v84
	v_mul_f32_e32 v75, v69, v85
	v_mul_f32_e32 v68, v66, v76
	v_mul_f32_e32 v69, v67, v77
	v_mul_f32_e32 v70, v64, v84
	v_mul_f32_e32 v71, v65, v85
	s_and_b64 vcc, exec, s[14:15]
	s_mov_b64 s[0:1], -1
	s_cbranch_vccnz .LBB0_366
	s_and_b64 vcc, exec, s[12:13]
	s_cbranch_vccz .LBB0_926
	s_and_b64 vcc, exec, s[0:1]
	s_cbranch_vccnz .LBB0_931

; __device__ __forceinline__ float sigm(float x) { return __builtin_amdgcn_rcpf(1.f + fexp(-x)); }
; __device__ __forceinline__ unsigned pkh(float lo, float hi) { const _Float16 a = (_Float16)lo, b = (_Float16)hi; return (unsigned)__builtin_bit_cast(unsigned short, a) | ((unsigned)__builtin_bit_cast(unsigned short, b) << 16); }
;     __device__ __forceinline__ void operator()(const f32x4 (&acc)[2][2][4][2], const Unit& u, int wr, int wc, int fr, int fq) const {
;     ...
;                     if (reg == PB_LF) {
; #pragma unroll
;                         for (int j = 0; j < 8; ++j) v[j] = (1.f - lb[bj][j]) * sigm(-v[j]);
;                         w.x = pkh(v[0], v[1]); w.y = pkh(v[2], v[3]); w.z = pkh(v[4], v[5]); w.w = pkh(v[6], v[7]);
.LBB0_364:
	v_mul_f32_e32 v65, 0x3fb8aa3b, v87
	v_mul_f32_e32 v66, 0x3fb8aa3b, v76
	v_exp_f32_e32 v65, v65
	v_exp_f32_e32 v67, v66
	v_mul_f32_e32 v66, 0x3fb8aa3b, v77
	v_exp_f32_e32 v76, v66
	v_mul_f32_e32 v64, 0x3fb8aa3b, v86
	v_exp_f32_e32 v64, v64
	v_add_f32_e32 v65, 1.0, v65
	v_rcp_f32_e32 v66, v65
	v_add_f32_e32 v65, 1.0, v67
	v_add_f32_e32 v67, 1.0, v76
	v_mul_f32_e32 v76, 0x3fb8aa3b, v78
	v_mul_f32_e32 v77, 0x3fb8aa3b, v79
	v_mul_f32_e32 v78, 0x3fb8aa3b, v84
	v_exp_f32_e32 v77, v77
	v_exp_f32_e32 v79, v78
	v_mul_f32_e32 v78, 0x3fb8aa3b, v85
	v_add_f32_e32 v64, 1.0, v64
	v_exp_f32_e32 v84, v78
	v_rcp_f32_e32 v64, v64
	v_rcp_f32_e32 v65, v65
	v_exp_f32_e32 v76, v76
	v_rcp_f32_e32 v67, v67
	v_add_f32_e32 v77, 1.0, v77
	v_rcp_f32_e32 v78, v77
	v_add_f32_e32 v77, 1.0, v79
	v_add_f32_e32 v79, 1.0, v84
	v_add_f32_e64 v84, -v164, 1.0
	v_add_f32_e64 v85, -v165, 1.0
	v_add_f32_e32 v76, 1.0, v76
	v_mul_f32_e32 v64, v84, v64
	v_mul_f32_e32 v65, v85, v65
	v_add_f32_e64 v84, -v166, 1.0
	v_add_f32_e64 v85, -v167, 1.0
	v_rcp_f32_e32 v76, v76
	v_rcp_f32_e32 v77, v77
	v_mul_f32_e32 v66, v84, v66
	v_mul_f32_e32 v67, v85, v67
	v_rcp_f32_e32 v79, v79
	v_cvt_pk_f16_f32 v64, v64, v65
	v_cvt_pk_f16_f32 v65, v66, v67
	v_and_b32_e32 v66, 0xffff0000, v65
	v_lshlrev_b32_e32 v67, 16, v65
	v_or_b32_sdwa v65, v66, v64 dst_sel:DWORD dst_unused:UNUSED_PAD src0_sel:DWORD src1_sel:WORD_1
	v_or_b32_sdwa v64, v67, v64 dst_sel:DWORD dst_unused:UNUSED_PAD src0_sel:DWORD src1_sel:WORD_0
	v_add_f32_e64 v66, -v168, 1.0
	v_add_f32_e64 v67, -v169, 1.0
	s_nop 0
	v_mul_f32_e32 v66, v66, v76
	v_mul_f32_e32 v67, v67, v77
	v_add_f32_e64 v76, -v170, 1.0
	v_add_f32_e64 v77, -v171, 1.0
	v_cvt_pk_f16_f32 v66, v66, v67
	v_mul_f32_e32 v76, v76, v78
	v_mul_f32_e32 v77, v77, v79
	s_nop 0
	v_cvt_pk_f16_f32 v67, v76, v77
	v_and_b32_e32 v76, 0xffff0000, v67
	v_lshlrev_b32_e32 v77, 16, v67
	v_or_b32_sdwa v67, v76, v66 dst_sel:DWORD dst_unused:UNUSED_PAD src0_sel:DWORD src1_sel:WORD_1
	v_or_b32_sdwa v66, v77, v66 dst_sel:DWORD dst_unused:UNUSED_PAD src0_sel:DWORD src1_sel:WORD_0

; template <int RSM> __device__ __forceinline__ float row_scale(const float* p, int row) { const float v = __hip_atomic_load(p + row, __ATOMIC_RELAXED, __HIP_MEMORY_SCOPE_AGENT); return RSM == 0 ? v : 1.0f / sqrtf(v * (1.f / DM) + EPS); }
;     __device__ __forceinline__ void operator()(const f32x4 (&acc)[2][2][4][2], const Unit& u, int wr, int wc, int fr, int fq) const {
;     ...
;             for (int m = 0; m < 4; ++m) { const int row = row0 + ai * HALF + m * 16; const float sc = row_scale<1>(rs, row);
;                 f32x4 c0, c1, s0, s1;
;                 if (rope) { const int pos = row & (SEQ - 1); c0 = *(const f32x4*)(ropeC + pos * 8); c1 = *(const f32x4*)(ropeC + pos * 8 + 4); s0 = *(const f32x4*)(ropeS + pos * 8); s1 = *(const f32x4*)(ropeS + pos * 8 + 4); }
; #pragma unroll
;                 for (int bj = 0; bj < 2; ++bj) { const f32x4 a0 = acc[ai][bj][m][0] * sc, a1 = acc[ai][bj][m][1] * sc;
;                     float v[8] = {a0[0], a0[1], a0[2], a0[3], a1[0], a1[1], a1[2], a1[3]};
.LBB0_370:
	s_waitcnt vmcnt(0)
	v_lshlrev_b64 v[64:65], 11, v[64:65]
	s_nop 0
	s_mov_b64 s[0:1], -1
	v_mov_b32_e32 v68, v253
	v_lshl_add_u64 v[66:67], v[184:185], 0, v[64:65]
	v_mul_f32_e32 v70, v62, v68
	v_mul_f32_e32 v71, v63, v68
	v_mul_f32_e32 v72, v60, v68
	v_mul_f32_e32 v73, v61, v68
	v_mul_f32_e32 v60, v58, v68
	v_mul_f32_e32 v61, v59, v68
	v_mul_f32_e32 v62, v56, v68
	v_mul_f32_e32 v63, v57, v68
	s_and_b64 vcc, exec, s[14:15]
	s_cbranch_vccnz .LBB0_377
	s_and_b64 vcc, exec, s[12:13]
	s_cbranch_vccz .LBB0_981
	s_and_b64 vcc, exec, s[0:1]
	s_cbranch_vccnz .LBB0_986

; __device__ __forceinline__ float sigm(float x) { return __builtin_amdgcn_rcpf(1.f + fexp(-x)); }
; __device__ __forceinline__ unsigned pkh(float lo, float hi) { const _Float16 a = (_Float16)lo, b = (_Float16)hi; return (unsigned)__builtin_bit_cast(unsigned short, a) | ((unsigned)__builtin_bit_cast(unsigned short, b) << 16); }
;     __device__ __forceinline__ void operator()(const f32x4 (&acc)[2][2][4][2], const Unit& u, int wr, int wc, int fr, int fq) const {
;     ...
;                     if (reg == PB_LF) {
; #pragma unroll
;                         for (int j = 0; j < 8; ++j) v[j] = (1.f - lb[bj][j]) * sigm(-v[j]);
;                         w.x = pkh(v[0], v[1]); w.y = pkh(v[2], v[3]); w.z = pkh(v[4], v[5]); w.w = pkh(v[6], v[7]);
.LBB0_375:
	v_mul_f32_e32 v57, 0x3fb8aa3b, v81
	v_mul_f32_e32 v58, 0x3fb8aa3b, v74
	v_exp_f32_e32 v57, v57
	v_exp_f32_e32 v59, v58
	v_mul_f32_e32 v58, 0x3fb8aa3b, v75
	v_exp_f32_e32 v69, v58
	v_add_f32_e32 v57, 1.0, v57
	v_rcp_f32_e32 v58, v57
	v_add_f32_e32 v57, 1.0, v59
	v_add_f32_e32 v59, 1.0, v69
	v_mul_f32_e32 v69, 0x3fb8aa3b, v76
	v_mul_f32_e32 v56, 0x3fb8aa3b, v80
	v_exp_f32_e32 v69, v69
	v_mul_f32_e32 v74, 0x3fb8aa3b, v77
	v_exp_f32_e32 v56, v56
	v_exp_f32_e32 v75, v74
	v_add_f32_e32 v69, 1.0, v69
	v_rcp_f32_e32 v74, v69
	v_add_f32_e32 v56, 1.0, v56
	v_add_f32_e32 v69, 1.0, v75
	v_mul_f32_e32 v75, 0x3fb8aa3b, v78
	v_rcp_f32_e32 v56, v56
	v_rcp_f32_e32 v57, v57
	v_exp_f32_e32 v75, v75
	v_mul_f32_e32 v76, 0x3fb8aa3b, v79
	v_rcp_f32_e32 v59, v59
	v_exp_f32_e32 v77, v76
	v_add_f32_e64 v78, -v178, 1.0
	v_add_f32_e64 v79, -v179, 1.0
	v_rcp_f32_e32 v76, v69
	v_add_f32_e32 v69, 1.0, v75
	v_mul_f32_e32 v56, v78, v56
	v_mul_f32_e32 v57, v79, v57
	v_add_f32_e64 v78, -v174, 1.0
	v_add_f32_e64 v79, -v175, 1.0
	v_rcp_f32_e32 v75, v69
	v_add_f32_e32 v69, 1.0, v77
	v_mul_f32_e32 v58, v78, v58
	v_mul_f32_e32 v59, v79, v59
	v_rcp_f32_e32 v77, v69
	v_cvt_pk_f16_f32 v56, v56, v57
	v_cvt_pk_f16_f32 v57, v58, v59
	v_and_b32_e32 v58, 0xffff0000, v57
	v_lshlrev_b32_e32 v59, 16, v57
	v_or_b32_sdwa v57, v58, v56 dst_sel:DWORD dst_unused:UNUSED_PAD src0_sel:DWORD src1_sel:WORD_1
	v_or_b32_sdwa v56, v59, v56 dst_sel:DWORD dst_unused:UNUSED_PAD src0_sel:DWORD src1_sel:WORD_0
	v_add_f32_e64 v58, -v176, 1.0
	v_add_f32_e64 v59, -v177, 1.0
	s_nop 0
	v_mul_f32_e32 v58, v58, v74
	v_mul_f32_e32 v59, v59, v75
	v_add_f32_e64 v74, -v172, 1.0
	v_add_f32_e64 v75, -v173, 1.0
	v_cvt_pk_f16_f32 v58, v58, v59
	v_mul_f32_e32 v74, v74, v76
	v_mul_f32_e32 v75, v75, v77
	s_nop 0
	v_cvt_pk_f16_f32 v59, v74, v75
	v_and_b32_e32 v69, 0xffff0000, v59
	v_lshlrev_b32_e32 v74, 16, v59
	v_or_b32_sdwa v59, v69, v58 dst_sel:DWORD dst_unused:UNUSED_PAD src0_sel:DWORD src1_sel:WORD_1
	v_or_b32_sdwa v58, v74, v58 dst_sel:DWORD dst_unused:UNUSED_PAD src0_sel:DWORD src1_sel:WORD_0

;     __device__ __forceinline__ void operator()(const f32x4 (&acc)[2][2][4][2], const Unit& u, int wr, int wc, int fr, int fq) const {
;     ...
;                 for (int bj = 0; bj < 2; ++bj) { const f32x4 a0 = acc[ai][bj][m][0] * sc, a1 = acc[ai][bj][m][1] * sc;
;                     float v[8] = {a0[0], a0[1], a0[2], a0[3], a1[0], a1[1], a1[2], a1[3]};
.LBB0_379:
	v_mov_b32_e32 v69, v68
	v_mov_b32_e32 v60, v68
	v_mov_b32_e32 v61, v68
	v_mul_f32_e32 v56, v54, v60
	v_mul_f32_e32 v57, v55, v61
	v_mul_f32_e32 v58, v52, v68
	v_mul_f32_e32 v59, v53, v69
	v_mul_f32_e32 v52, v50, v60
	v_mul_f32_e32 v53, v51, v61
	v_mul_f32_e32 v54, v48, v68
	v_mul_f32_e32 v55, v49, v69
	s_and_b64 vcc, exec, s[14:15]
	s_mov_b64 s[0:1], -1
	s_cbranch_vccnz .LBB0_386
	s_and_b64 vcc, exec, s[12:13]
	s_cbranch_vccz .LBB0_1036
	s_and_b64 vcc, exec, s[0:1]
	s_cbranch_vccnz .LBB0_1041

; __device__ __forceinline__ float sigm(float x) { return __builtin_amdgcn_rcpf(1.f + fexp(-x)); }
; __device__ __forceinline__ unsigned pkh(float lo, float hi) { const _Float16 a = (_Float16)lo, b = (_Float16)hi; return (unsigned)__builtin_bit_cast(unsigned short, a) | ((unsigned)__builtin_bit_cast(unsigned short, b) << 16); }
;     __device__ __forceinline__ void operator()(const f32x4 (&acc)[2][2][4][2], const Unit& u, int wr, int wc, int fr, int fq) const {
;     ...
;                     if (reg == PB_LF) {
; #pragma unroll
;                         for (int j = 0; j < 8; ++j) v[j] = (1.f - lb[bj][j]) * sigm(-v[j]);
;                         w.x = pkh(v[0], v[1]); w.y = pkh(v[2], v[3]); w.z = pkh(v[4], v[5]); w.w = pkh(v[6], v[7]);
.LBB0_384:
	v_mul_f32_e32 v49, 0x3fb8aa3b, v71
	v_mul_f32_e32 v50, 0x3fb8aa3b, v60
	v_exp_f32_e32 v49, v49
	v_exp_f32_e32 v51, v50
	v_mul_f32_e32 v50, 0x3fb8aa3b, v61
	v_exp_f32_e32 v60, v50
	v_mul_f32_e32 v48, 0x3fb8aa3b, v70
	v_exp_f32_e32 v48, v48
	v_add_f32_e32 v49, 1.0, v49
	v_rcp_f32_e32 v50, v49
	v_add_f32_e32 v49, 1.0, v51
	v_add_f32_e32 v51, 1.0, v60
	v_mul_f32_e32 v60, 0x3fb8aa3b, v62
	v_mul_f32_e32 v61, 0x3fb8aa3b, v63
	v_mul_f32_e32 v62, 0x3fb8aa3b, v68
	v_exp_f32_e32 v61, v61
	v_exp_f32_e32 v63, v62
	v_mul_f32_e32 v62, 0x3fb8aa3b, v69
	v_add_f32_e32 v48, 1.0, v48
	v_exp_f32_e32 v68, v62
	v_rcp_f32_e32 v48, v48
	v_rcp_f32_e32 v49, v49
	v_exp_f32_e32 v60, v60
	v_rcp_f32_e32 v51, v51
	v_add_f32_e32 v61, 1.0, v61
	v_rcp_f32_e32 v62, v61
	v_add_f32_e32 v61, 1.0, v63
	v_add_f32_e32 v63, 1.0, v68
	v_add_f32_e64 v68, -v164, 1.0
	v_add_f32_e64 v69, -v165, 1.0
	v_add_f32_e32 v60, 1.0, v60
	v_mul_f32_e32 v48, v68, v48
	v_mul_f32_e32 v49, v69, v49
	v_add_f32_e64 v68, -v166, 1.0
	v_add_f32_e64 v69, -v167, 1.0
	v_rcp_f32_e32 v60, v60
	v_rcp_f32_e32 v61, v61
	v_mul_f32_e32 v50, v68, v50
	v_mul_f32_e32 v51, v69, v51
	v_rcp_f32_e32 v63, v63
	v_cvt_pk_f16_f32 v48, v48, v49
	v_cvt_pk_f16_f32 v49, v50, v51
	v_and_b32_e32 v50, 0xffff0000, v49
	v_lshlrev_b32_e32 v51, 16, v49
	v_or_b32_sdwa v49, v50, v48 dst_sel:DWORD dst_unused:UNUSED_PAD src0_sel:DWORD src1_sel:WORD_1
	v_or_b32_sdwa v48, v51, v48 dst_sel:DWORD dst_unused:UNUSED_PAD src0_sel:DWORD src1_sel:WORD_0
	v_add_f32_e64 v50, -v168, 1.0
	v_add_f32_e64 v51, -v169, 1.0
	s_nop 0
	v_mul_f32_e32 v50, v50, v60
	v_mul_f32_e32 v51, v51, v61
	v_add_f32_e64 v60, -v170, 1.0
	v_add_f32_e64 v61, -v171, 1.0
	v_cvt_pk_f16_f32 v50, v50, v51
	v_mul_f32_e32 v60, v60, v62
	v_mul_f32_e32 v61, v61, v63
	s_nop 0
	v_cvt_pk_f16_f32 v51, v60, v61
	v_and_b32_e32 v60, 0xffff0000, v51
	v_lshlrev_b32_e32 v61, 16, v51
	v_or_b32_sdwa v51, v60, v50 dst_sel:DWORD dst_unused:UNUSED_PAD src0_sel:DWORD src1_sel:WORD_1
	v_or_b32_sdwa v50, v61, v50 dst_sel:DWORD dst_unused:UNUSED_PAD src0_sel:DWORD src1_sel:WORD_0

; template <int RSM> __device__ __forceinline__ float row_scale(const float* p, int row) { const float v = __hip_atomic_load(p + row, __ATOMIC_RELAXED, __HIP_MEMORY_SCOPE_AGENT); return RSM == 0 ? v : 1.0f / sqrtf(v * (1.f / DM) + EPS); }
;     __device__ __forceinline__ void operator()(const f32x4 (&acc)[2][2][4][2], const Unit& u, int wr, int wc, int fr, int fq) const {
;     ...
;             for (int m = 0; m < 4; ++m) { const int row = row0 + ai * HALF + m * 16; const float sc = row_scale<1>(rs, row);
;                 f32x4 c0, c1, s0, s1;
;                 if (rope) { const int pos = row & (SEQ - 1); c0 = *(const f32x4*)(ropeC + pos * 8); c1 = *(const f32x4*)(ropeC + pos * 8 + 4); s0 = *(const f32x4*)(ropeS + pos * 8); s1 = *(const f32x4*)(ropeS + pos * 8 + 4); }
; #pragma unroll
;                 for (int bj = 0; bj < 2; ++bj) { const f32x4 a0 = acc[ai][bj][m][0] * sc, a1 = acc[ai][bj][m][1] * sc;
;                     float v[8] = {a0[0], a0[1], a0[2], a0[3], a1[0], a1[1], a1[2], a1[3]};
.LBB0_390:
	s_waitcnt vmcnt(0)
	v_lshlrev_b64 v[48:49], 11, v[48:49]
	s_nop 0
	s_mov_b64 s[0:1], -1
	v_mov_b32_e32 v52, v254
	v_lshl_add_u64 v[50:51], v[184:185], 0, v[48:49]
	v_mul_f32_e32 v54, v46, v52
	v_mul_f32_e32 v55, v47, v52
	v_mul_f32_e32 v56, v44, v52
	v_mul_f32_e32 v57, v45, v52
	v_mul_f32_e32 v44, v42, v52
	v_mul_f32_e32 v45, v43, v52
	v_mul_f32_e32 v46, v40, v52
	v_mul_f32_e32 v47, v41, v52
	s_and_b64 vcc, exec, s[14:15]
	s_cbranch_vccnz .LBB0_397
	s_and_b64 vcc, exec, s[12:13]
	s_cbranch_vccz .LBB0_1091
	s_and_b64 vcc, exec, s[0:1]
	s_cbranch_vccnz .LBB0_1096

; __device__ __forceinline__ float sigm(float x) { return __builtin_amdgcn_rcpf(1.f + fexp(-x)); }
; __device__ __forceinline__ unsigned pkh(float lo, float hi) { const _Float16 a = (_Float16)lo, b = (_Float16)hi; return (unsigned)__builtin_bit_cast(unsigned short, a) | ((unsigned)__builtin_bit_cast(unsigned short, b) << 16); }
;     __device__ __forceinline__ void operator()(const f32x4 (&acc)[2][2][4][2], const Unit& u, int wr, int wc, int fr, int fq) const {
;     ...
;                     if (reg == PB_LF) {
; #pragma unroll
;                         for (int j = 0; j < 8; ++j) v[j] = (1.f - lb[bj][j]) * sigm(-v[j]);
;                         w.x = pkh(v[0], v[1]); w.y = pkh(v[2], v[3]); w.z = pkh(v[4], v[5]); w.w = pkh(v[6], v[7]);
.LBB0_395:
	v_mul_f32_e32 v41, 0x3fb8aa3b, v65
	v_mul_f32_e32 v42, 0x3fb8aa3b, v58
	v_exp_f32_e32 v41, v41
	v_exp_f32_e32 v43, v42
	v_mul_f32_e32 v42, 0x3fb8aa3b, v59
	v_exp_f32_e32 v53, v42
	v_add_f32_e32 v41, 1.0, v41
	v_rcp_f32_e32 v42, v41
	v_add_f32_e32 v41, 1.0, v43
	v_add_f32_e32 v43, 1.0, v53
	v_mul_f32_e32 v53, 0x3fb8aa3b, v60
	v_mul_f32_e32 v40, 0x3fb8aa3b, v64
	v_exp_f32_e32 v53, v53
	v_mul_f32_e32 v58, 0x3fb8aa3b, v61
	v_exp_f32_e32 v40, v40
	v_exp_f32_e32 v59, v58
	v_add_f32_e32 v53, 1.0, v53
	v_rcp_f32_e32 v58, v53
	v_add_f32_e32 v40, 1.0, v40
	v_add_f32_e32 v53, 1.0, v59
	v_mul_f32_e32 v59, 0x3fb8aa3b, v62
	v_rcp_f32_e32 v40, v40
	v_rcp_f32_e32 v41, v41
	v_exp_f32_e32 v59, v59
	v_mul_f32_e32 v60, 0x3fb8aa3b, v63
	v_rcp_f32_e32 v43, v43
	v_exp_f32_e32 v61, v60
	v_add_f32_e64 v62, -v178, 1.0
	v_add_f32_e64 v63, -v179, 1.0
	v_rcp_f32_e32 v60, v53
	v_add_f32_e32 v53, 1.0, v59
	v_mul_f32_e32 v40, v62, v40
	v_mul_f32_e32 v41, v63, v41
	v_add_f32_e64 v62, -v174, 1.0
	v_add_f32_e64 v63, -v175, 1.0
	v_rcp_f32_e32 v59, v53
	v_add_f32_e32 v53, 1.0, v61
	v_mul_f32_e32 v42, v62, v42
	v_mul_f32_e32 v43, v63, v43
	v_rcp_f32_e32 v61, v53
	v_cvt_pk_f16_f32 v40, v40, v41
	v_cvt_pk_f16_f32 v41, v42, v43
	v_and_b32_e32 v42, 0xffff0000, v41
	v_lshlrev_b32_e32 v43, 16, v41
	v_or_b32_sdwa v41, v42, v40 dst_sel:DWORD dst_unused:UNUSED_PAD src0_sel:DWORD src1_sel:WORD_1
	v_or_b32_sdwa v40, v43, v40 dst_sel:DWORD dst_unused:UNUSED_PAD src0_sel:DWORD src1_sel:WORD_0
	v_add_f32_e64 v42, -v176, 1.0
	v_add_f32_e64 v43, -v177, 1.0
	s_nop 0
	v_mul_f32_e32 v42, v42, v58
	v_mul_f32_e32 v43, v43, v59
	v_add_f32_e64 v58, -v172, 1.0
	v_add_f32_e64 v59, -v173, 1.0
	v_cvt_pk_f16_f32 v42, v42, v43
	v_mul_f32_e32 v58, v58, v60
	v_mul_f32_e32 v59, v59, v61
	s_nop 0
	v_cvt_pk_f16_f32 v43, v58, v59
	v_and_b32_e32 v53, 0xffff0000, v43
	v_lshlrev_b32_e32 v58, 16, v43
	v_or_b32_sdwa v43, v53, v42 dst_sel:DWORD dst_unused:UNUSED_PAD src0_sel:DWORD src1_sel:WORD_1
	v_or_b32_sdwa v42, v58, v42 dst_sel:DWORD dst_unused:UNUSED_PAD src0_sel:DWORD src1_sel:WORD_0

;     __device__ __forceinline__ void operator()(const f32x4 (&acc)[2][2][4][2], const Unit& u, int wr, int wc, int fr, int fq) const {
;     ...
;                 for (int bj = 0; bj < 2; ++bj) { const f32x4 a0 = acc[ai][bj][m][0] * sc, a1 = acc[ai][bj][m][1] * sc;
;                     float v[8] = {a0[0], a0[1], a0[2], a0[3], a1[0], a1[1], a1[2], a1[3]};
.LBB0_399:
	v_mov_b32_e32 v53, v52
	v_mov_b32_e32 v44, v52
	v_mov_b32_e32 v45, v52
	v_mul_f32_e32 v40, v38, v44
	v_mul_f32_e32 v41, v39, v45
	v_mul_f32_e32 v42, v36, v52
	v_mul_f32_e32 v43, v37, v53
	v_mul_f32_e32 v36, v34, v44
	v_mul_f32_e32 v37, v35, v45
	v_mul_f32_e32 v38, v32, v52
	v_mul_f32_e32 v39, v33, v53
	s_and_b64 vcc, exec, s[14:15]
	s_mov_b64 s[0:1], -1
	s_cbranch_vccnz .LBB0_406
	s_and_b64 vcc, exec, s[12:13]
	s_cbranch_vccz .LBB0_1146
	s_and_b64 vcc, exec, s[0:1]
	s_cbranch_vccnz .LBB0_1151

; __device__ __forceinline__ float sigm(float x) { return __builtin_amdgcn_rcpf(1.f + fexp(-x)); }
; __device__ __forceinline__ unsigned pkh(float lo, float hi) { const _Float16 a = (_Float16)lo, b = (_Float16)hi; return (unsigned)__builtin_bit_cast(unsigned short, a) | ((unsigned)__builtin_bit_cast(unsigned short, b) << 16); }
;     __device__ __forceinline__ void operator()(const f32x4 (&acc)[2][2][4][2], const Unit& u, int wr, int wc, int fr, int fq) const {
;     ...
;                     if (reg == PB_LF) {
; #pragma unroll
;                         for (int j = 0; j < 8; ++j) v[j] = (1.f - lb[bj][j]) * sigm(-v[j]);
;                         w.x = pkh(v[0], v[1]); w.y = pkh(v[2], v[3]); w.z = pkh(v[4], v[5]); w.w = pkh(v[6], v[7]);
.LBB0_404:
	v_mul_f32_e32 v33, 0x3fb8aa3b, v55
	v_mul_f32_e32 v34, 0x3fb8aa3b, v44
	v_exp_f32_e32 v33, v33
	v_exp_f32_e32 v35, v34
	v_mul_f32_e32 v34, 0x3fb8aa3b, v45
	v_exp_f32_e32 v44, v34
	v_mul_f32_e32 v32, 0x3fb8aa3b, v54
	v_exp_f32_e32 v32, v32
	v_add_f32_e32 v33, 1.0, v33
	v_rcp_f32_e32 v34, v33
	v_add_f32_e32 v33, 1.0, v35
	v_add_f32_e32 v35, 1.0, v44
	v_mul_f32_e32 v44, 0x3fb8aa3b, v46
	v_mul_f32_e32 v45, 0x3fb8aa3b, v47
	v_mul_f32_e32 v46, 0x3fb8aa3b, v52
	v_exp_f32_e32 v45, v45
	v_exp_f32_e32 v47, v46
	v_mul_f32_e32 v46, 0x3fb8aa3b, v53
	v_add_f32_e32 v32, 1.0, v32
	v_exp_f32_e32 v52, v46
	v_rcp_f32_e32 v32, v32
	v_rcp_f32_e32 v33, v33
	v_exp_f32_e32 v44, v44
	v_rcp_f32_e32 v35, v35
	v_add_f32_e32 v45, 1.0, v45
	v_rcp_f32_e32 v46, v45
	v_add_f32_e32 v45, 1.0, v47
	v_add_f32_e32 v47, 1.0, v52
	v_add_f32_e64 v52, -v164, 1.0
	v_add_f32_e64 v53, -v165, 1.0
	v_add_f32_e32 v44, 1.0, v44
	v_mul_f32_e32 v32, v52, v32
	v_mul_f32_e32 v33, v53, v33
	v_add_f32_e64 v52, -v166, 1.0
	v_add_f32_e64 v53, -v167, 1.0
	v_rcp_f32_e32 v44, v44
	v_rcp_f32_e32 v45, v45
	v_mul_f32_e32 v34, v52, v34
	v_mul_f32_e32 v35, v53, v35
	v_rcp_f32_e32 v47, v47
	v_cvt_pk_f16_f32 v32, v32, v33
	v_cvt_pk_f16_f32 v33, v34, v35
	v_and_b32_e32 v34, 0xffff0000, v33
	v_lshlrev_b32_e32 v35, 16, v33
	v_or_b32_sdwa v33, v34, v32 dst_sel:DWORD dst_unused:UNUSED_PAD src0_sel:DWORD src1_sel:WORD_1
	v_or_b32_sdwa v32, v35, v32 dst_sel:DWORD dst_unused:UNUSED_PAD src0_sel:DWORD src1_sel:WORD_0
	v_add_f32_e64 v34, -v168, 1.0
	v_add_f32_e64 v35, -v169, 1.0
	s_nop 0
	v_mul_f32_e32 v34, v34, v44
	v_mul_f32_e32 v35, v35, v45
	v_add_f32_e64 v44, -v170, 1.0
	v_add_f32_e64 v45, -v171, 1.0
	v_cvt_pk_f16_f32 v34, v34, v35
	v_mul_f32_e32 v44, v44, v46
	v_mul_f32_e32 v45, v45, v47
	s_nop 0
	v_cvt_pk_f16_f32 v35, v44, v45
	v_and_b32_e32 v44, 0xffff0000, v35
	v_lshlrev_b32_e32 v45, 16, v35
	v_or_b32_sdwa v35, v44, v34 dst_sel:DWORD dst_unused:UNUSED_PAD src0_sel:DWORD src1_sel:WORD_1
	v_or_b32_sdwa v34, v45, v34 dst_sel:DWORD dst_unused:UNUSED_PAD src0_sel:DWORD src1_sel:WORD_0

; template <int RSM> __device__ __forceinline__ float row_scale(const float* p, int row) { const float v = __hip_atomic_load(p + row, __ATOMIC_RELAXED, __HIP_MEMORY_SCOPE_AGENT); return RSM == 0 ? v : 1.0f / sqrtf(v * (1.f / DM) + EPS); }
;     __device__ __forceinline__ void operator()(const f32x4 (&acc)[2][2][4][2], const Unit& u, int wr, int wc, int fr, int fq) const {
;     ...
;             for (int m = 0; m < 4; ++m) { const int row = row0 + ai * HALF + m * 16; const float sc = row_scale<1>(rs, row);
;                 f32x4 c0, c1, s0, s1;
;                 if (rope) { const int pos = row & (SEQ - 1); c0 = *(const f32x4*)(ropeC + pos * 8); c1 = *(const f32x4*)(ropeC + pos * 8 + 4); s0 = *(const f32x4*)(ropeS + pos * 8); s1 = *(const f32x4*)(ropeS + pos * 8 + 4); }
; #pragma unroll
;                 for (int bj = 0; bj < 2; ++bj) { const f32x4 a0 = acc[ai][bj][m][0] * sc, a1 = acc[ai][bj][m][1] * sc;
;                     float v[8] = {a0[0], a0[1], a0[2], a0[3], a1[0], a1[1], a1[2], a1[3]};
.LBB0_410:
	s_waitcnt vmcnt(0)
	v_lshlrev_b64 v[32:33], 11, v[32:33]
	s_nop 0
	s_mov_b64 s[0:1], -1
	v_mov_b32_e32 v36, v255
	v_lshl_add_u64 v[34:35], v[184:185], 0, v[32:33]
	v_mul_f32_e32 v38, v30, v36
	v_mul_f32_e32 v39, v31, v36
	v_mul_f32_e32 v40, v28, v36
	v_mul_f32_e32 v41, v29, v36
	v_mul_f32_e32 v28, v26, v36
	v_mul_f32_e32 v29, v27, v36
	v_mul_f32_e32 v30, v24, v36
	v_mul_f32_e32 v31, v25, v36
	s_and_b64 vcc, exec, s[14:15]
	s_cbranch_vccnz .LBB0_417
	s_and_b64 vcc, exec, s[12:13]
	s_cbranch_vccz .LBB0_1201
	s_and_b64 vcc, exec, s[0:1]
	s_cbranch_vccnz .LBB0_1206

; __device__ __forceinline__ float sigm(float x) { return __builtin_amdgcn_rcpf(1.f + fexp(-x)); }
; __device__ __forceinline__ unsigned pkh(float lo, float hi) { const _Float16 a = (_Float16)lo, b = (_Float16)hi; return (unsigned)__builtin_bit_cast(unsigned short, a) | ((unsigned)__builtin_bit_cast(unsigned short, b) << 16); }
;     __device__ __forceinline__ void operator()(const f32x4 (&acc)[2][2][4][2], const Unit& u, int wr, int wc, int fr, int fq) const {
;     ...
;                     if (reg == PB_LF) {
; #pragma unroll
;                         for (int j = 0; j < 8; ++j) v[j] = (1.f - lb[bj][j]) * sigm(-v[j]);
;                         w.x = pkh(v[0], v[1]); w.y = pkh(v[2], v[3]); w.z = pkh(v[4], v[5]); w.w = pkh(v[6], v[7]);
.LBB0_415:
	v_mul_f32_e32 v27, 0x3fb8aa3b, v49
	v_exp_f32_e32 v27, v27
	v_mul_f32_e32 v37, 0x3fb8aa3b, v42
	v_mul_f32_e32 v42, 0x3fb8aa3b, v43
	v_exp_f32_e32 v37, v37
	v_exp_f32_e32 v43, v42
	v_add_f32_e32 v27, 1.0, v27
	v_rcp_f32_e32 v42, v27
	v_add_f32_e32 v27, 1.0, v37
	v_add_f32_e32 v37, 1.0, v43
	v_rcp_f32_e32 v43, v37
	v_mul_f32_e32 v37, 0x3fb8aa3b, v44
	v_exp_f32_e32 v37, v37
	v_mul_f32_e32 v44, 0x3fb8aa3b, v45
	v_exp_f32_e32 v45, v44
	v_mul_f32_e32 v24, 0x3fb8aa3b, v48
	v_exp_f32_e32 v26, v24
	v_add_f32_e32 v37, 1.0, v37
	v_rcp_f32_e32 v44, v37
	v_add_f32_e32 v37, 1.0, v45
	v_mul_f32_e32 v45, 0x3fb8aa3b, v46
	v_exp_f32_e32 v45, v45
	v_mul_f32_e32 v46, 0x3fb8aa3b, v47
	v_exp_f32_e32 v47, v46
	v_add_f32_e32 v26, 1.0, v26
	v_rcp_f32_e32 v26, v26
	v_rcp_f32_e32 v27, v27
	v_rcp_f32_e32 v46, v37
	v_add_f32_e32 v37, 1.0, v45
	v_rcp_f32_e32 v45, v37
	v_add_f32_e32 v37, 1.0, v47
	v_add_f32_e64 v24, -v178, 1.0
	v_add_f32_e64 v25, -v179, 1.0
	v_add_f32_e64 v48, -v174, 1.0
	v_add_f32_e64 v49, -v175, 1.0
	v_rcp_f32_e32 v47, v37
	v_mul_f32_e32 v24, v24, v26
	v_mul_f32_e32 v25, v25, v27
	v_mul_f32_e32 v26, v48, v42
	v_mul_f32_e32 v27, v49, v43
	v_cvt_pk_f16_f32 v24, v24, v25
	v_cvt_pk_f16_f32 v25, v26, v27
	v_add_f32_e64 v50, -v176, 1.0
	v_add_f32_e64 v51, -v177, 1.0
	v_add_f32_e64 v52, -v172, 1.0
	v_add_f32_e64 v53, -v173, 1.0
	v_and_b32_e32 v26, 0xffff0000, v25
	v_lshlrev_b32_e32 v27, 16, v25
	v_or_b32_sdwa v25, v26, v24 dst_sel:DWORD dst_unused:UNUSED_PAD src0_sel:DWORD src1_sel:WORD_1
	v_or_b32_sdwa v24, v27, v24 dst_sel:DWORD dst_unused:UNUSED_PAD src0_sel:DWORD src1_sel:WORD_0
	v_mul_f32_e32 v26, v50, v44
	v_mul_f32_e32 v27, v51, v45
	v_mul_f32_e32 v42, v52, v46
	v_mul_f32_e32 v43, v53, v47
	v_cvt_pk_f16_f32 v26, v26, v27
	v_cvt_pk_f16_f32 v27, v42, v43
	v_and_b32_e32 v37, 0xffff0000, v27
	v_lshlrev_b32_e32 v42, 16, v27
	v_or_b32_sdwa v27, v37, v26 dst_sel:DWORD dst_unused:UNUSED_PAD src0_sel:DWORD src1_sel:WORD_1
	v_or_b32_sdwa v26, v42, v26 dst_sel:DWORD dst_unused:UNUSED_PAD src0_sel:DWORD src1_sel:WORD_0

;     __device__ __forceinline__ void operator()(const f32x4 (&acc)[2][2][4][2], const Unit& u, int wr, int wc, int fr, int fq) const {
;     ...
;                 for (int bj = 0; bj < 2; ++bj) { const f32x4 a0 = acc[ai][bj][m][0] * sc, a1 = acc[ai][bj][m][1] * sc;
;                     float v[8] = {a0[0], a0[1], a0[2], a0[3], a1[0], a1[1], a1[2], a1[3]};
.LBB0_419:
	v_mov_b32_e32 v37, v36
	v_mov_b32_e32 v24, v36
	v_mov_b32_e32 v25, v36
	v_mul_f32_e32 v28, v10, v24
	v_mul_f32_e32 v29, v11, v25
	v_mul_f32_e32 v30, v8, v36
	v_mul_f32_e32 v31, v9, v37
	v_mul_f32_e32 v24, v2, v24
	v_mul_f32_e32 v25, v3, v25
	v_mul_f32_e32 v26, v0, v36
	v_mul_f32_e32 v27, v1, v37
	s_and_b64 vcc, exec, s[14:15]
	s_mov_b64 s[0:1], -1
	s_cbranch_vccz .LBB0_422
	s_and_b64 vcc, exec, s[0:1]
	s_cbranch_vccnz .LBB0_428

; __device__ __forceinline__ float sigm(float x) { return __builtin_amdgcn_rcpf(1.f + fexp(-x)); }
; __device__ __forceinline__ unsigned pkh(float lo, float hi) { const _Float16 a = (_Float16)lo, b = (_Float16)hi; return (unsigned)__builtin_bit_cast(unsigned short, a) | ((unsigned)__builtin_bit_cast(unsigned short, b) << 16); }
;     __device__ __forceinline__ void operator()(const f32x4 (&acc)[2][2][4][2], const Unit& u, int wr, int wc, int fr, int fq) const {
;     ...
;                     if (reg == PB_LF) {
; #pragma unroll
;                         for (int j = 0; j < 8; ++j) v[j] = (1.f - lb[bj][j]) * sigm(-v[j]);
;                         w.x = pkh(v[0], v[1]); w.y = pkh(v[2], v[3]); w.z = pkh(v[4], v[5]); w.w = pkh(v[6], v[7]);
.LBB0_426:
	v_mul_f32_e32 v3, 0x3fb8aa3b, v37
	v_mul_f32_e32 v6, 0x3fb8aa3b, v38
	v_mul_f32_e32 v0, 0x3fb8aa3b, v36
	v_exp_f32_e32 v3, v3
	v_exp_f32_e32 v7, v6
	v_mul_f32_e32 v6, 0x3fb8aa3b, v39
	v_exp_f32_e32 v2, v0
	v_exp_f32_e32 v12, v6
	v_mul_f32_e32 v11, 0x3fb8aa3b, v11
	v_mul_f32_e32 v8, 0x3fb8aa3b, v8
	v_mul_f32_e32 v10, 0x3fb8aa3b, v10
	v_exp_f32_e32 v11, v11
	v_exp_f32_e32 v16, v8
	v_mul_f32_e32 v8, 0x3fb8aa3b, v9
	v_add_f32_e32 v3, 1.0, v3
	v_exp_f32_e32 v10, v10
	v_exp_f32_e32 v9, v8
	v_add_f32_e32 v2, 1.0, v2
	v_rcp_f32_e32 v6, v3
	v_add_f32_e32 v3, 1.0, v7
	v_add_f32_e32 v7, 1.0, v12
	v_rcp_f32_e32 v2, v2
	v_rcp_f32_e32 v3, v3
	v_rcp_f32_e32 v7, v7
	v_add_f32_e32 v11, 1.0, v11
	v_add_f32_e32 v10, 1.0, v10
	v_rcp_f32_e32 v8, v11
	v_add_f32_e32 v11, 1.0, v16
	v_add_f32_e32 v9, 1.0, v9
	s_waitcnt lgkmcnt(0)
	v_add_f32_e64 v0, -v164, 1.0
	v_add_f32_e64 v1, -v165, 1.0
	v_add_f32_e64 v4, -v166, 1.0
	v_add_f32_e64 v5, -v167, 1.0
	v_rcp_f32_e32 v10, v10
	v_rcp_f32_e32 v11, v11
	v_rcp_f32_e32 v9, v9
	v_mul_f32_e32 v0, v0, v2
	v_mul_f32_e32 v1, v1, v3
	v_mul_f32_e32 v2, v4, v6
	v_mul_f32_e32 v3, v5, v7
	v_cvt_pk_f16_f32 v0, v0, v1
	v_cvt_pk_f16_f32 v1, v2, v3
	v_add_f32_e64 v12, -v168, 1.0
	v_add_f32_e64 v13, -v169, 1.0
	v_add_f32_e64 v14, -v170, 1.0
	v_add_f32_e64 v15, -v171, 1.0
	v_and_b32_e32 v2, 0xffff0000, v1
	v_lshlrev_b32_e32 v3, 16, v1
	v_or_b32_sdwa v1, v2, v0 dst_sel:DWORD dst_unused:UNUSED_PAD src0_sel:DWORD src1_sel:WORD_1
	v_or_b32_sdwa v0, v3, v0 dst_sel:DWORD dst_unused:UNUSED_PAD src0_sel:DWORD src1_sel:WORD_0
	v_mul_f32_e32 v2, v12, v10
	v_mul_f32_e32 v3, v13, v11
	v_mul_f32_e32 v4, v14, v8
	v_mul_f32_e32 v5, v15, v9
	v_cvt_pk_f16_f32 v2, v2, v3
	v_cvt_pk_f16_f32 v3, v4, v5
	v_and_b32_e32 v4, 0xffff0000, v3
	v_lshlrev_b32_e32 v5, 16, v3
	v_or_b32_sdwa v3, v4, v2 dst_sel:DWORD dst_unused:UNUSED_PAD src0_sel:DWORD src1_sel:WORD_1
	v_or_b32_sdwa v2, v5, v2 dst_sel:DWORD dst_unused:UNUSED_PAD src0_sel:DWORD src1_sel:WORD_0

; __device__ __forceinline__ float silu(float x) { return x * sigm(x); }
;     __device__ __forceinline__ void operator()(const f32x4 (&acc)[2][2][4][2], const Unit& u, int wr, int wc, int fr, int fq) const {
;     ...
;                     } else if (reg == PB_QR || reg == PB_G) {
; #pragma unroll
;                         for (int j = 0; j < 8; ++j) v[j] = silu(v[j]);
;                     }
.LBB0_433:
	s_andn2_b64 vcc, exec, s[0:1]
	s_cbranch_vccnz .LBB0_435
	v_mul_f32_e32 v181, 0xbfb8aa3b, v142
	v_exp_f32_e32 v181, v181
	v_mul_f32_e32 v191, 0xbfb8aa3b, v140
	v_mul_f32_e32 v136, 0xbfb8aa3b, v194
	v_mul_f32_e32 v137, 0xbfb8aa3b, v195
	v_add_f32_e32 v181, 1.0, v181
	v_mul_f32_e32 v138, 0xbfb8aa3b, v192
	v_mul_f32_e32 v139, 0xbfb8aa3b, v193
	v_rcp_f32_e32 v198, v181
	v_mul_f32_e32 v181, 0xbfb8aa3b, v143
	v_exp_f32_e32 v191, v191
	v_mul_f32_e32 v196, 0xbfb8aa3b, v141
	v_exp_f32_e32 v136, v136
	v_exp_f32_e32 v137, v137
	v_exp_f32_e32 v138, v138
	v_exp_f32_e32 v139, v139
	v_exp_f32_e32 v181, v181
	v_exp_f32_e32 v196, v196
	v_add_f32_e32 v191, 1.0, v191
	v_add_f32_e32 v136, 1.0, v136
	v_add_f32_e32 v137, 1.0, v137
	v_add_f32_e32 v138, 1.0, v138
	v_add_f32_e32 v139, 1.0, v139
	v_add_f32_e32 v181, 1.0, v181
	v_rcp_f32_e32 v200, v191
	v_add_f32_e32 v191, 1.0, v196
	v_rcp_f32_e32 v136, v136
	v_rcp_f32_e32 v137, v137
	v_rcp_f32_e32 v138, v138
	v_rcp_f32_e32 v139, v139
	v_rcp_f32_e32 v201, v191
	v_rcp_f32_e32 v199, v181
	v_mul_f32_e32 v202, v194, v136
	v_mul_f32_e32 v203, v195, v137
	v_mul_f32_e32 v196, v192, v138
	v_mul_f32_e32 v197, v193, v139
	v_mul_f32_e32 v200, v140, v200
	v_mul_f32_e32 v201, v141, v201
	v_mul_f32_e32 v198, v142, v198
	v_mul_f32_e32 v199, v143, v199

;     __device__ __forceinline__ void operator()(const f32x4 (&acc)[2][2][4][2], const Unit& u, int wr, int wc, int fr, int fq) const {
;     ...
;                     if (reg <= 1) {
;                         if (rope) { const float cs[8] = {c0[0], c0[1], c0[2], c0[3], c1[0], c1[1], c1[2], c1[3]}; const float sn[8] = {s0[0], s0[1], s0[2], s0[3], s1[0], s1[1], s1[2], s1[3]};
; #pragma unroll
;                             for (int j = 0; j < 8; ++j) { const float o = __shfl_xor(v[j], 16); if (fq == 0) v[j] = v[j] * cs[j] - o * sn[j]; else if (fq == 1) v[j] = v[j] * cs[j] + o * sn[j]; } }
.LBB0_436:
	s_and_b64 vcc, exec, s[10:11]
	s_cbranch_vccnz .LBB0_1311
	v_and_b32_e32 v137, 64, v214
	v_xor_b32_e32 v136, 16, v214
	v_add_u32_e32 v137, 64, v137
	v_cmp_lt_i32_e32 vcc, v136, v137
	s_nop 1
	v_cndmask_b32_e32 v136, v214, v136, vcc
	v_lshlrev_b32_e32 v181, 2, v136
	ds_bpermute_b32 v201, v181, v194
	v_cmp_lt_i32_e32 vcc, 0, v204
	s_and_saveexec_b64 s[0:1], vcc
	s_xor_b64 s[0:1], exec, s[0:1]
	s_cbranch_execz .LBB0_441
	v_cmp_eq_u32_e32 vcc, 1, v204
	v_mov_b32_e32 v139, v141
	v_mov_b32_e32 v138, v140
	v_mov_b32_e32 v199, v143
	v_mov_b32_e32 v198, v142
	v_mov_b32_e32 v197, v193
	v_mov_b32_e32 v196, v192
	v_mov_b32_e32 v137, v195
	v_mov_b32_e32 v136, v194
	s_and_saveexec_b64 s[12:13], vcc
	s_cbranch_execz .LBB0_440
	v_mov_b32_e32 v136, v194
	v_mov_b32_e32 v137, v20
	v_mov_b32_e32 v200, v16
	s_waitcnt lgkmcnt(0)
	v_mul_f32_e32 v136, v136, v200
	v_mul_f32_e32 v137, v137, v201
	v_mov_b32_e32 v139, v141
	v_add_f32_e32 v136, v136, v137
	v_mov_b32_e32 v138, v140
	v_mov_b32_e32 v199, v143
	v_mov_b32_e32 v198, v142
	v_mov_b32_e32 v197, v193
	v_mov_b32_e32 v196, v192
	v_mov_b32_e32 v137, v195

;     __device__ __forceinline__ void operator()(const f32x4 (&acc)[2][2][4][2], const Unit& u, int wr, int wc, int fr, int fq) const {
;     ...
;                         if (rope) { const float cs[8] = {c0[0], c0[1], c0[2], c0[3], c1[0], c1[1], c1[2], c1[3]}; const float sn[8] = {s0[0], s0[1], s0[2], s0[3], s1[0], s1[1], s1[2], s1[3]};
; #pragma unroll
;                             for (int j = 0; j < 8; ++j) { const float o = __shfl_xor(v[j], 16); if (fq == 0) v[j] = v[j] * cs[j] - o * sn[j]; else if (fq == 1) v[j] = v[j] * cs[j] + o * sn[j]; } }
.LBB0_441:
	s_andn2_saveexec_b64 s[0:1], s[0:1]
	s_cbranch_execz .LBB0_443
	v_mov_b32_e32 v136, v194
	v_mov_b32_e32 v137, v20
	v_mov_b32_e32 v200, v16
	s_waitcnt lgkmcnt(0)
	v_mul_f32_e32 v136, v136, v200
	v_mul_f32_e32 v137, v137, v201
	v_mov_b32_e32 v196, v192
	v_sub_f32_e32 v136, v136, v137
	v_mov_b32_e32 v137, v195
	v_mov_b32_e32 v197, v193
	v_mov_b32_e32 v198, v142
	v_mov_b32_e32 v199, v143
	v_mov_b32_e32 v138, v140
	v_mov_b32_e32 v139, v141
.LBB0_443:
	s_or_b64 exec, exec, s[0:1]
	s_waitcnt lgkmcnt(0)
	ds_bpermute_b32 v201, v181, v137
	v_cmp_lt_i32_e32 vcc, 0, v204
	s_and_saveexec_b64 s[0:1], vcc
	s_xor_b64 s[0:1], exec, s[0:1]
	s_cbranch_execz .LBB0_447
	v_cmp_eq_u32_e32 vcc, 1, v204
	s_and_saveexec_b64 s[12:13], vcc
	s_cbranch_execz .LBB0_446
	v_mov_b32_e32 v202, v17
	v_mov_b32_e32 v203, v21
	v_mov_b32_e32 v200, v137
	v_mul_f32_e32 v216, v17, v137
	s_waitcnt lgkmcnt(0)
	v_fma_f32 v200, v202, v200, v216
	v_fma_f32 v201, v203, v201, v216
	s_nop 0
	v_mov_b32_e32 v137, v201

;     __device__ __forceinline__ void operator()(const f32x4 (&acc)[2][2][4][2], const Unit& u, int wr, int wc, int fr, int fq) const {
;     ...
;                         if (rope) { const float cs[8] = {c0[0], c0[1], c0[2], c0[3], c1[0], c1[1], c1[2], c1[3]}; const float sn[8] = {s0[0], s0[1], s0[2], s0[3], s1[0], s1[1], s1[2], s1[3]};
; #pragma unroll
;                             for (int j = 0; j < 8; ++j) { const float o = __shfl_xor(v[j], 16); if (fq == 0) v[j] = v[j] * cs[j] - o * sn[j]; else if (fq == 1) v[j] = v[j] * cs[j] + o * sn[j]; } }
.LBB0_447:
	s_andn2_saveexec_b64 s[0:1], s[0:1]
	s_cbranch_execz .LBB0_449
	v_mov_b32_e32 v202, v17
	v_mov_b32_e32 v203, v21
	v_mov_b32_e32 v200, v137
	v_mul_f32_e32 v216, v17, v137
	s_waitcnt lgkmcnt(0)
	v_fma_f32 v200, -v202, v200, v216
	v_fma_f32 v201, -v203, v201, v216
	s_nop 0
	v_mov_b32_e32 v137, v201
.LBB0_449:
	s_or_b64 exec, exec, s[0:1]
	s_waitcnt lgkmcnt(0)
	ds_bpermute_b32 v201, v181, v196
	v_cmp_lt_i32_e32 vcc, 0, v204
	s_and_saveexec_b64 s[0:1], vcc
	s_xor_b64 s[0:1], exec, s[0:1]
	s_cbranch_execz .LBB0_453
	v_cmp_eq_u32_e32 vcc, 1, v204
	s_and_saveexec_b64 s[12:13], vcc
	s_cbranch_execz .LBB0_452
	v_mov_b32_e32 v202, v18
	v_mov_b32_e32 v203, v22
	v_mov_b32_e32 v200, v196
	s_waitcnt lgkmcnt(0)
	v_mul_f32_e32 v196, v22, v201
	v_fma_f32 v200, v202, v200, v196
	v_fma_f32 v201, v203, v201, v196
	s_nop 0
	v_mov_b32_e32 v196, v200

;     __device__ __forceinline__ void operator()(const f32x4 (&acc)[2][2][4][2], const Unit& u, int wr, int wc, int fr, int fq) const {
;     ...
;                         if (rope) { const float cs[8] = {c0[0], c0[1], c0[2], c0[3], c1[0], c1[1], c1[2], c1[3]}; const float sn[8] = {s0[0], s0[1], s0[2], s0[3], s1[0], s1[1], s1[2], s1[3]};
; #pragma unroll
;                             for (int j = 0; j < 8; ++j) { const float o = __shfl_xor(v[j], 16); if (fq == 0) v[j] = v[j] * cs[j] - o * sn[j]; else if (fq == 1) v[j] = v[j] * cs[j] + o * sn[j]; } }
.LBB0_453:
	s_andn2_saveexec_b64 s[0:1], s[0:1]
	s_cbranch_execz .LBB0_455
	v_mov_b32_e32 v202, v18
	v_mov_b32_e32 v203, v22
	v_mov_b32_e32 v200, v196
	s_waitcnt lgkmcnt(0)
	v_mul_f32_e32 v196, v22, v201
	v_fma_f32 v200, v202, v200, -v196
	v_fma_f32 v201, v203, v201, -v196
	s_nop 0
	v_mov_b32_e32 v196, v200
.LBB0_455:
	s_or_b64 exec, exec, s[0:1]
	s_waitcnt lgkmcnt(0)
	ds_bpermute_b32 v201, v181, v197
	v_cmp_lt_i32_e32 vcc, 0, v204
	s_and_saveexec_b64 s[0:1], vcc
	s_xor_b64 s[0:1], exec, s[0:1]
	s_cbranch_execz .LBB0_459
	v_cmp_eq_u32_e32 vcc, 1, v204
	s_and_saveexec_b64 s[12:13], vcc
	s_cbranch_execz .LBB0_458
	v_mov_b32_e32 v202, v19
	v_mov_b32_e32 v203, v23
	v_mov_b32_e32 v200, v197
	s_waitcnt lgkmcnt(0)
	v_mul_f32_e32 v216, v23, v201
	v_fma_f32 v200, v202, v200, v216
	v_fma_f32 v201, v203, v201, v216
	s_nop 0
	v_mov_b32_e32 v197, v200

;     __device__ __forceinline__ void operator()(const f32x4 (&acc)[2][2][4][2], const Unit& u, int wr, int wc, int fr, int fq) const {
;     ...
;                         if (rope) { const float cs[8] = {c0[0], c0[1], c0[2], c0[3], c1[0], c1[1], c1[2], c1[3]}; const float sn[8] = {s0[0], s0[1], s0[2], s0[3], s1[0], s1[1], s1[2], s1[3]};
; #pragma unroll
;                             for (int j = 0; j < 8; ++j) { const float o = __shfl_xor(v[j], 16); if (fq == 0) v[j] = v[j] * cs[j] - o * sn[j]; else if (fq == 1) v[j] = v[j] * cs[j] + o * sn[j]; } }
.LBB0_459:
	s_andn2_saveexec_b64 s[0:1], s[0:1]
	s_cbranch_execz .LBB0_461
	v_mov_b32_e32 v202, v19
	v_mov_b32_e32 v203, v23
	v_mov_b32_e32 v200, v197
	s_waitcnt lgkmcnt(0)
	v_mul_f32_e32 v216, v23, v201
	v_fma_f32 v200, v202, v200, -v216
	v_fma_f32 v201, v203, v201, -v216
	s_nop 0
	v_mov_b32_e32 v197, v200
.LBB0_461:
	s_or_b64 exec, exec, s[0:1]
	s_waitcnt lgkmcnt(0)
	ds_bpermute_b32 v201, v181, v198
	v_cmp_lt_i32_e32 vcc, 0, v204
	s_and_saveexec_b64 s[0:1], vcc
	s_xor_b64 s[0:1], exec, s[0:1]
	s_cbranch_execz .LBB0_465
	v_cmp_eq_u32_e32 vcc, 1, v204
	s_and_saveexec_b64 s[12:13], vcc
	s_cbranch_execz .LBB0_464
	v_mov_b32_e32 v202, v4
	v_mov_b32_e32 v203, v12
	v_mov_b32_e32 v200, v198
	s_waitcnt lgkmcnt(0)
	v_mul_f32_e32 v198, v12, v201
	v_fma_f32 v200, v202, v200, v198
	v_fma_f32 v201, v203, v201, v198
	s_nop 0
	v_mov_b32_e32 v198, v200

;     __device__ __forceinline__ void operator()(const f32x4 (&acc)[2][2][4][2], const Unit& u, int wr, int wc, int fr, int fq) const {
;     ...
;                         if (rope) { const float cs[8] = {c0[0], c0[1], c0[2], c0[3], c1[0], c1[1], c1[2], c1[3]}; const float sn[8] = {s0[0], s0[1], s0[2], s0[3], s1[0], s1[1], s1[2], s1[3]};
; #pragma unroll
;                             for (int j = 0; j < 8; ++j) { const float o = __shfl_xor(v[j], 16); if (fq == 0) v[j] = v[j] * cs[j] - o * sn[j]; else if (fq == 1) v[j] = v[j] * cs[j] + o * sn[j]; } }
.LBB0_465:
	s_andn2_saveexec_b64 s[0:1], s[0:1]
	s_cbranch_execz .LBB0_467
	v_mov_b32_e32 v202, v4
	v_mov_b32_e32 v203, v12
	v_mov_b32_e32 v200, v198
	s_waitcnt lgkmcnt(0)
	v_mul_f32_e32 v198, v12, v201
	v_fma_f32 v200, v202, v200, -v198
	v_fma_f32 v201, v203, v201, -v198
	s_nop 0
	v_mov_b32_e32 v198, v200
.LBB0_467:
	s_or_b64 exec, exec, s[0:1]
	s_waitcnt lgkmcnt(0)
	ds_bpermute_b32 v201, v181, v199
	v_cmp_lt_i32_e32 vcc, 0, v204
	s_and_saveexec_b64 s[0:1], vcc
	s_xor_b64 s[0:1], exec, s[0:1]
	s_cbranch_execz .LBB0_471
	v_cmp_eq_u32_e32 vcc, 1, v204
	s_and_saveexec_b64 s[12:13], vcc
	s_cbranch_execz .LBB0_470
	v_mov_b32_e32 v202, v5
	v_mov_b32_e32 v203, v13
	v_mov_b32_e32 v200, v199
	s_waitcnt lgkmcnt(0)
	v_mul_f32_e32 v216, v13, v201
	v_fma_f32 v200, v202, v200, v216
	v_fma_f32 v201, v203, v201, v216
	s_nop 0
	v_mov_b32_e32 v199, v200

;     __device__ __forceinline__ void operator()(const f32x4 (&acc)[2][2][4][2], const Unit& u, int wr, int wc, int fr, int fq) const {
;     ...
;                         if (rope) { const float cs[8] = {c0[0], c0[1], c0[2], c0[3], c1[0], c1[1], c1[2], c1[3]}; const float sn[8] = {s0[0], s0[1], s0[2], s0[3], s1[0], s1[1], s1[2], s1[3]};
; #pragma unroll
;                             for (int j = 0; j < 8; ++j) { const float o = __shfl_xor(v[j], 16); if (fq == 0) v[j] = v[j] * cs[j] - o * sn[j]; else if (fq == 1) v[j] = v[j] * cs[j] + o * sn[j]; } }
.LBB0_471:
	s_andn2_saveexec_b64 s[0:1], s[0:1]
	s_cbranch_execz .LBB0_473
	v_mov_b32_e32 v202, v5
	v_mov_b32_e32 v203, v13
	v_mov_b32_e32 v200, v199
	s_waitcnt lgkmcnt(0)
	v_mul_f32_e32 v216, v13, v201
	v_fma_f32 v200, v202, v200, -v216
	v_fma_f32 v201, v203, v201, -v216
	s_nop 0
	v_mov_b32_e32 v199, v200
.LBB0_473:
	s_or_b64 exec, exec, s[0:1]
	s_waitcnt lgkmcnt(0)
	ds_bpermute_b32 v201, v181, v138
	v_cmp_lt_i32_e32 vcc, 0, v204
	s_and_saveexec_b64 s[0:1], vcc
	s_xor_b64 s[0:1], exec, s[0:1]
	s_cbranch_execz .LBB0_477
	v_cmp_eq_u32_e32 vcc, 1, v204
	s_and_saveexec_b64 s[12:13], vcc
	s_cbranch_execz .LBB0_476
	v_mov_b32_e32 v202, v6
	v_mov_b32_e32 v203, v14
	v_mov_b32_e32 v200, v138
	s_waitcnt lgkmcnt(0)
	v_mul_f32_e32 v138, v14, v201
	v_fma_f32 v200, v202, v200, v138
	v_fma_f32 v201, v203, v201, v138
	s_nop 0
	v_mov_b32_e32 v138, v200

;     __device__ __forceinline__ void operator()(const f32x4 (&acc)[2][2][4][2], const Unit& u, int wr, int wc, int fr, int fq) const {
;     ...
;                         if (rope) { const float cs[8] = {c0[0], c0[1], c0[2], c0[3], c1[0], c1[1], c1[2], c1[3]}; const float sn[8] = {s0[0], s0[1], s0[2], s0[3], s1[0], s1[1], s1[2], s1[3]};
; #pragma unroll
;                             for (int j = 0; j < 8; ++j) { const float o = __shfl_xor(v[j], 16); if (fq == 0) v[j] = v[j] * cs[j] - o * sn[j]; else if (fq == 1) v[j] = v[j] * cs[j] + o * sn[j]; } }
.LBB0_477:
	s_andn2_saveexec_b64 s[0:1], s[0:1]
	s_cbranch_execz .LBB0_479
	v_mov_b32_e32 v202, v6
	v_mov_b32_e32 v203, v14
	v_mov_b32_e32 v200, v138
	s_waitcnt lgkmcnt(0)
	v_mul_f32_e32 v138, v14, v201
	v_fma_f32 v200, v202, v200, -v138
	v_fma_f32 v201, v203, v201, -v138
	s_nop 0
	v_mov_b32_e32 v138, v200
.LBB0_479:
	s_or_b64 exec, exec, s[0:1]
	s_waitcnt lgkmcnt(0)
	ds_bpermute_b32 v201, v181, v139
	v_cmp_lt_i32_e32 vcc, 0, v204
	s_and_saveexec_b64 s[0:1], vcc
	s_xor_b64 s[0:1], exec, s[0:1]
	s_cbranch_execz .LBB0_483
	v_cmp_eq_u32_e32 vcc, 1, v204
	s_and_saveexec_b64 s[12:13], vcc
	s_cbranch_execz .LBB0_482
	v_mov_b32_e32 v202, v7
	v_mov_b32_e32 v203, v15
	v_mov_b32_e32 v200, v139
	s_waitcnt lgkmcnt(0)
	v_mul_f32_e32 v216, v15, v201
	v_fma_f32 v200, v202, v200, v216
	v_fma_f32 v201, v203, v201, v216
	s_nop 0
	v_mov_b32_e32 v139, v200

;     __device__ __forceinline__ void operator()(const f32x4 (&acc)[2][2][4][2], const Unit& u, int wr, int wc, int fr, int fq) const {
;     ...
;                         if (rope) { const float cs[8] = {c0[0], c0[1], c0[2], c0[3], c1[0], c1[1], c1[2], c1[3]}; const float sn[8] = {s0[0], s0[1], s0[2], s0[3], s1[0], s1[1], s1[2], s1[3]};
; #pragma unroll
;                             for (int j = 0; j < 8; ++j) { const float o = __shfl_xor(v[j], 16); if (fq == 0) v[j] = v[j] * cs[j] - o * sn[j]; else if (fq == 1) v[j] = v[j] * cs[j] + o * sn[j]; } }
.LBB0_483:
	s_andn2_saveexec_b64 s[0:1], s[0:1]
	s_cbranch_execz .LBB0_485
	v_mov_b32_e32 v202, v7
	v_mov_b32_e32 v203, v15
	v_mov_b32_e32 v200, v139
	s_waitcnt lgkmcnt(0)
	v_mul_f32_e32 v216, v15, v201
	v_fma_f32 v200, v202, v200, -v216
	v_fma_f32 v201, v203, v201, -v216
	s_nop 0
	v_mov_b32_e32 v139, v200

; __device__ __forceinline__ float silu(float x) { return x * sigm(x); }
;     __device__ __forceinline__ void operator()(const f32x4 (&acc)[2][2][4][2], const Unit& u, int wr, int wc, int fr, int fq) const {
;     ...
;                     } else if (reg == PB_QR || reg == PB_G) {
; #pragma unroll
;                         for (int j = 0; j < 8; ++j) v[j] = silu(v[j]);
;                     }
.LBB0_488:
	s_andn2_b64 vcc, exec, s[0:1]
	s_cbranch_vccnz .LBB0_490
	v_mul_f32_e32 v140, 0xbfb8aa3b, v134
	v_exp_f32_e32 v140, v140
	v_mul_f32_e32 v141, 0xbfb8aa3b, v132
	v_mul_f32_e32 v128, 0xbfb8aa3b, v138
	v_mul_f32_e32 v129, 0xbfb8aa3b, v139
	v_add_f32_e32 v140, 1.0, v140
	v_mul_f32_e32 v130, 0xbfb8aa3b, v136
	v_mul_f32_e32 v131, 0xbfb8aa3b, v137
	v_rcp_f32_e32 v142, v140
	v_mul_f32_e32 v140, 0xbfb8aa3b, v135
	v_exp_f32_e32 v141, v141
	v_mul_f32_e32 v143, 0xbfb8aa3b, v133
	v_exp_f32_e32 v128, v128
	v_exp_f32_e32 v129, v129
	v_exp_f32_e32 v130, v130
	v_exp_f32_e32 v131, v131
	v_exp_f32_e32 v140, v140
	v_exp_f32_e32 v143, v143
	v_add_f32_e32 v141, 1.0, v141
	v_add_f32_e32 v128, 1.0, v128
	v_add_f32_e32 v129, 1.0, v129
	v_add_f32_e32 v130, 1.0, v130
	v_add_f32_e32 v131, 1.0, v131
	v_add_f32_e32 v140, 1.0, v140
	v_rcp_f32_e32 v190, v141
	v_add_f32_e32 v141, 1.0, v143
	v_rcp_f32_e32 v128, v128
	v_rcp_f32_e32 v129, v129
	v_rcp_f32_e32 v130, v130
	v_rcp_f32_e32 v131, v131
	v_rcp_f32_e32 v191, v141
	v_rcp_f32_e32 v143, v140
	v_mul_f32_e32 v192, v138, v128
	v_mul_f32_e32 v193, v139, v129
	v_mul_f32_e32 v140, v136, v130
	v_mul_f32_e32 v141, v137, v131
	v_mul_f32_e32 v190, v132, v190
	v_mul_f32_e32 v191, v133, v191
	v_mul_f32_e32 v142, v134, v142
	v_mul_f32_e32 v143, v135, v143

;     __device__ __forceinline__ void operator()(const f32x4 (&acc)[2][2][4][2], const Unit& u, int wr, int wc, int fr, int fq) const {
;     ...
;                     if (reg <= 1) {
;                         if (rope) { const float cs[8] = {c0[0], c0[1], c0[2], c0[3], c1[0], c1[1], c1[2], c1[3]}; const float sn[8] = {s0[0], s0[1], s0[2], s0[3], s1[0], s1[1], s1[2], s1[3]};
; #pragma unroll
;                             for (int j = 0; j < 8; ++j) { const float o = __shfl_xor(v[j], 16); if (fq == 0) v[j] = v[j] * cs[j] - o * sn[j]; else if (fq == 1) v[j] = v[j] * cs[j] + o * sn[j]; } }
.LBB0_491:
	s_and_b64 vcc, exec, s[10:11]
	s_cbranch_vccnz .LBB0_1314
	v_and_b32_e32 v129, 64, v214
	v_xor_b32_e32 v128, 16, v214
	v_add_u32_e32 v129, 64, v129
	v_cmp_lt_i32_e32 vcc, v128, v129
	s_nop 1
	v_cndmask_b32_e32 v128, v214, v128, vcc
	v_lshlrev_b32_e32 v181, 2, v128
	ds_bpermute_b32 v191, v181, v138
	v_cmp_lt_i32_e32 vcc, 0, v204
	s_and_saveexec_b64 s[0:1], vcc
	s_xor_b64 s[0:1], exec, s[0:1]
	s_cbranch_execz .LBB0_496
	v_cmp_eq_u32_e32 vcc, 1, v204
	v_mov_b32_e32 v131, v133
	v_mov_b32_e32 v130, v132
	v_mov_b32_e32 v143, v135
	v_mov_b32_e32 v142, v134
	v_mov_b32_e32 v141, v137
	v_mov_b32_e32 v140, v136
	v_mov_b32_e32 v129, v139
	v_mov_b32_e32 v128, v138
	s_and_saveexec_b64 s[16:17], vcc
	s_cbranch_execz .LBB0_495
	v_mov_b32_e32 v128, v138
	v_mov_b32_e32 v129, v20
	v_mov_b32_e32 v190, v16
	s_waitcnt lgkmcnt(0)
	v_mul_f32_e32 v128, v128, v190
	v_mul_f32_e32 v129, v129, v191
	v_mov_b32_e32 v131, v133
	v_add_f32_e32 v128, v128, v129
	v_mov_b32_e32 v130, v132
	v_mov_b32_e32 v143, v135
	v_mov_b32_e32 v142, v134
	v_mov_b32_e32 v141, v137
	v_mov_b32_e32 v140, v136
	v_mov_b32_e32 v129, v139

;     __device__ __forceinline__ void operator()(const f32x4 (&acc)[2][2][4][2], const Unit& u, int wr, int wc, int fr, int fq) const {
;     ...
;                         if (rope) { const float cs[8] = {c0[0], c0[1], c0[2], c0[3], c1[0], c1[1], c1[2], c1[3]}; const float sn[8] = {s0[0], s0[1], s0[2], s0[3], s1[0], s1[1], s1[2], s1[3]};
; #pragma unroll
;                             for (int j = 0; j < 8; ++j) { const float o = __shfl_xor(v[j], 16); if (fq == 0) v[j] = v[j] * cs[j] - o * sn[j]; else if (fq == 1) v[j] = v[j] * cs[j] + o * sn[j]; } }
.LBB0_496:
	s_andn2_saveexec_b64 s[0:1], s[0:1]
	s_cbranch_execz .LBB0_498
	v_mov_b32_e32 v128, v138
	v_mov_b32_e32 v129, v20
	v_mov_b32_e32 v190, v16
	s_waitcnt lgkmcnt(0)
	v_mul_f32_e32 v128, v128, v190
	v_mul_f32_e32 v129, v129, v191
	v_mov_b32_e32 v140, v136
	v_sub_f32_e32 v128, v128, v129
	v_mov_b32_e32 v129, v139
	v_mov_b32_e32 v141, v137
	v_mov_b32_e32 v142, v134
	v_mov_b32_e32 v143, v135
	v_mov_b32_e32 v130, v132
	v_mov_b32_e32 v131, v133
.LBB0_498:
	s_or_b64 exec, exec, s[0:1]
	s_waitcnt lgkmcnt(0)
	ds_bpermute_b32 v191, v181, v129
	v_cmp_lt_i32_e32 vcc, 0, v204
	s_and_saveexec_b64 s[0:1], vcc
	s_xor_b64 s[0:1], exec, s[0:1]
	s_cbranch_execz .LBB0_502
	v_cmp_eq_u32_e32 vcc, 1, v204
	s_and_saveexec_b64 s[16:17], vcc
	s_cbranch_execz .LBB0_501
	v_mov_b32_e32 v192, v17
	v_mov_b32_e32 v193, v21
	v_mov_b32_e32 v190, v129
	v_mul_f32_e32 v194, v17, v129
	s_waitcnt lgkmcnt(0)
	v_fma_f32 v190, v192, v190, v194
	v_fma_f32 v191, v193, v191, v194
	s_nop 0
	v_mov_b32_e32 v129, v191

;     __device__ __forceinline__ void operator()(const f32x4 (&acc)[2][2][4][2], const Unit& u, int wr, int wc, int fr, int fq) const {
;     ...
;                         if (rope) { const float cs[8] = {c0[0], c0[1], c0[2], c0[3], c1[0], c1[1], c1[2], c1[3]}; const float sn[8] = {s0[0], s0[1], s0[2], s0[3], s1[0], s1[1], s1[2], s1[3]};
; #pragma unroll
;                             for (int j = 0; j < 8; ++j) { const float o = __shfl_xor(v[j], 16); if (fq == 0) v[j] = v[j] * cs[j] - o * sn[j]; else if (fq == 1) v[j] = v[j] * cs[j] + o * sn[j]; } }
.LBB0_502:
	s_andn2_saveexec_b64 s[0:1], s[0:1]
	s_cbranch_execz .LBB0_504
	v_mov_b32_e32 v192, v17
	v_mov_b32_e32 v193, v21
	v_mov_b32_e32 v190, v129
	v_mul_f32_e32 v194, v17, v129
	s_waitcnt lgkmcnt(0)
	v_fma_f32 v190, -v192, v190, v194
	v_fma_f32 v191, -v193, v191, v194
	s_nop 0
	v_mov_b32_e32 v129, v191
.LBB0_504:
	s_or_b64 exec, exec, s[0:1]
	s_waitcnt lgkmcnt(0)
	ds_bpermute_b32 v191, v181, v140
	v_cmp_lt_i32_e32 vcc, 0, v204
	s_and_saveexec_b64 s[0:1], vcc
	s_xor_b64 s[0:1], exec, s[0:1]
	s_cbranch_execz .LBB0_508
	v_cmp_eq_u32_e32 vcc, 1, v204
	s_and_saveexec_b64 s[16:17], vcc
	s_cbranch_execz .LBB0_507
	v_mov_b32_e32 v192, v18
	v_mov_b32_e32 v193, v22
	v_mov_b32_e32 v190, v140
	s_waitcnt lgkmcnt(0)
	v_mul_f32_e32 v140, v22, v191
	v_fma_f32 v190, v192, v190, v140
	v_fma_f32 v191, v193, v191, v140
	s_nop 0
	v_mov_b32_e32 v140, v190

;     __device__ __forceinline__ void operator()(const f32x4 (&acc)[2][2][4][2], const Unit& u, int wr, int wc, int fr, int fq) const {
;     ...
;                         if (rope) { const float cs[8] = {c0[0], c0[1], c0[2], c0[3], c1[0], c1[1], c1[2], c1[3]}; const float sn[8] = {s0[0], s0[1], s0[2], s0[3], s1[0], s1[1], s1[2], s1[3]};
; #pragma unroll
;                             for (int j = 0; j < 8; ++j) { const float o = __shfl_xor(v[j], 16); if (fq == 0) v[j] = v[j] * cs[j] - o * sn[j]; else if (fq == 1) v[j] = v[j] * cs[j] + o * sn[j]; } }
.LBB0_508:
	s_andn2_saveexec_b64 s[0:1], s[0:1]
	s_cbranch_execz .LBB0_510
	v_mov_b32_e32 v192, v18
	v_mov_b32_e32 v193, v22
	v_mov_b32_e32 v190, v140
	s_waitcnt lgkmcnt(0)
	v_mul_f32_e32 v140, v22, v191
	v_fma_f32 v190, v192, v190, -v140
	v_fma_f32 v191, v193, v191, -v140
	s_nop 0
	v_mov_b32_e32 v140, v190
.LBB0_510:
	s_or_b64 exec, exec, s[0:1]
	s_waitcnt lgkmcnt(0)
	ds_bpermute_b32 v191, v181, v141
	v_cmp_lt_i32_e32 vcc, 0, v204
	s_and_saveexec_b64 s[0:1], vcc
	s_xor_b64 s[0:1], exec, s[0:1]
	s_cbranch_execz .LBB0_514
	v_cmp_eq_u32_e32 vcc, 1, v204
	s_and_saveexec_b64 s[16:17], vcc
	s_cbranch_execz .LBB0_513
	v_mov_b32_e32 v192, v19
	v_mov_b32_e32 v193, v23
	v_mov_b32_e32 v190, v141
	s_waitcnt lgkmcnt(0)
	v_mul_f32_e32 v194, v23, v191
	v_fma_f32 v190, v192, v190, v194
	v_fma_f32 v191, v193, v191, v194
	s_nop 0
	v_mov_b32_e32 v141, v190

;     __device__ __forceinline__ void operator()(const f32x4 (&acc)[2][2][4][2], const Unit& u, int wr, int wc, int fr, int fq) const {
;     ...
;                         if (rope) { const float cs[8] = {c0[0], c0[1], c0[2], c0[3], c1[0], c1[1], c1[2], c1[3]}; const float sn[8] = {s0[0], s0[1], s0[2], s0[3], s1[0], s1[1], s1[2], s1[3]};
; #pragma unroll
;                             for (int j = 0; j < 8; ++j) { const float o = __shfl_xor(v[j], 16); if (fq == 0) v[j] = v[j] * cs[j] - o * sn[j]; else if (fq == 1) v[j] = v[j] * cs[j] + o * sn[j]; } }
.LBB0_514:
	s_andn2_saveexec_b64 s[0:1], s[0:1]
	s_cbranch_execz .LBB0_516
	v_mov_b32_e32 v192, v19
	v_mov_b32_e32 v193, v23
	v_mov_b32_e32 v190, v141
	s_waitcnt lgkmcnt(0)
	v_mul_f32_e32 v194, v23, v191
	v_fma_f32 v190, v192, v190, -v194
	v_fma_f32 v191, v193, v191, -v194
	s_nop 0
	v_mov_b32_e32 v141, v190
.LBB0_516:
	s_or_b64 exec, exec, s[0:1]
	s_waitcnt lgkmcnt(0)
	ds_bpermute_b32 v191, v181, v142
	v_cmp_lt_i32_e32 vcc, 0, v204
	s_and_saveexec_b64 s[0:1], vcc
	s_xor_b64 s[0:1], exec, s[0:1]
	s_cbranch_execz .LBB0_520
	v_cmp_eq_u32_e32 vcc, 1, v204
	s_and_saveexec_b64 s[16:17], vcc
	s_cbranch_execz .LBB0_519
	v_mov_b32_e32 v192, v4
	v_mov_b32_e32 v193, v12
	v_mov_b32_e32 v190, v142
	s_waitcnt lgkmcnt(0)
	v_mul_f32_e32 v142, v12, v191
	v_fma_f32 v190, v192, v190, v142
	v_fma_f32 v191, v193, v191, v142
	s_nop 0
	v_mov_b32_e32 v142, v190

;     __device__ __forceinline__ void operator()(const f32x4 (&acc)[2][2][4][2], const Unit& u, int wr, int wc, int fr, int fq) const {
;     ...
;                         if (rope) { const float cs[8] = {c0[0], c0[1], c0[2], c0[3], c1[0], c1[1], c1[2], c1[3]}; const float sn[8] = {s0[0], s0[1], s0[2], s0[3], s1[0], s1[1], s1[2], s1[3]};
; #pragma unroll
;                             for (int j = 0; j < 8; ++j) { const float o = __shfl_xor(v[j], 16); if (fq == 0) v[j] = v[j] * cs[j] - o * sn[j]; else if (fq == 1) v[j] = v[j] * cs[j] + o * sn[j]; } }
.LBB0_520:
	s_andn2_saveexec_b64 s[0:1], s[0:1]
	s_cbranch_execz .LBB0_522
	v_mov_b32_e32 v192, v4
	v_mov_b32_e32 v193, v12
	v_mov_b32_e32 v190, v142
	s_waitcnt lgkmcnt(0)
	v_mul_f32_e32 v142, v12, v191
	v_fma_f32 v190, v192, v190, -v142
	v_fma_f32 v191, v193, v191, -v142
	s_nop 0
	v_mov_b32_e32 v142, v190
.LBB0_522:
	s_or_b64 exec, exec, s[0:1]
	s_waitcnt lgkmcnt(0)
	ds_bpermute_b32 v191, v181, v143
	v_cmp_lt_i32_e32 vcc, 0, v204
	s_and_saveexec_b64 s[0:1], vcc
	s_xor_b64 s[0:1], exec, s[0:1]
	s_cbranch_execz .LBB0_526
	v_cmp_eq_u32_e32 vcc, 1, v204
	s_and_saveexec_b64 s[16:17], vcc
	s_cbranch_execz .LBB0_525
	v_mov_b32_e32 v192, v5
	v_mov_b32_e32 v193, v13
	v_mov_b32_e32 v190, v143
	s_waitcnt lgkmcnt(0)
	v_mul_f32_e32 v194, v13, v191
	v_fma_f32 v190, v192, v190, v194
	v_fma_f32 v191, v193, v191, v194
	s_nop 0
	v_mov_b32_e32 v143, v190

;     __device__ __forceinline__ void operator()(const f32x4 (&acc)[2][2][4][2], const Unit& u, int wr, int wc, int fr, int fq) const {
;     ...
;                         if (rope) { const float cs[8] = {c0[0], c0[1], c0[2], c0[3], c1[0], c1[1], c1[2], c1[3]}; const float sn[8] = {s0[0], s0[1], s0[2], s0[3], s1[0], s1[1], s1[2], s1[3]};
; #pragma unroll
;                             for (int j = 0; j < 8; ++j) { const float o = __shfl_xor(v[j], 16); if (fq == 0) v[j] = v[j] * cs[j] - o * sn[j]; else if (fq == 1) v[j] = v[j] * cs[j] + o * sn[j]; } }
.LBB0_526:
	s_andn2_saveexec_b64 s[0:1], s[0:1]
	s_cbranch_execz .LBB0_528
	v_mov_b32_e32 v192, v5
	v_mov_b32_e32 v193, v13
	v_mov_b32_e32 v190, v143
	s_waitcnt lgkmcnt(0)
	v_mul_f32_e32 v194, v13, v191
	v_fma_f32 v190, v192, v190, -v194
	v_fma_f32 v191, v193, v191, -v194
	s_nop 0
	v_mov_b32_e32 v143, v190
.LBB0_528:
	s_or_b64 exec, exec, s[0:1]
	s_waitcnt lgkmcnt(0)
	ds_bpermute_b32 v191, v181, v130
	v_cmp_lt_i32_e32 vcc, 0, v204
	s_and_saveexec_b64 s[0:1], vcc
	s_xor_b64 s[0:1], exec, s[0:1]
	s_cbranch_execz .LBB0_532
	v_cmp_eq_u32_e32 vcc, 1, v204
	s_and_saveexec_b64 s[16:17], vcc
	s_cbranch_execz .LBB0_531
	v_mov_b32_e32 v192, v6
	v_mov_b32_e32 v193, v14
	v_mov_b32_e32 v190, v130
	s_waitcnt lgkmcnt(0)
	v_mul_f32_e32 v130, v14, v191
	v_fma_f32 v190, v192, v190, v130
	v_fma_f32 v191, v193, v191, v130
	s_nop 0
	v_mov_b32_e32 v130, v190

;     __device__ __forceinline__ void operator()(const f32x4 (&acc)[2][2][4][2], const Unit& u, int wr, int wc, int fr, int fq) const {
;     ...
;                         if (rope) { const float cs[8] = {c0[0], c0[1], c0[2], c0[3], c1[0], c1[1], c1[2], c1[3]}; const float sn[8] = {s0[0], s0[1], s0[2], s0[3], s1[0], s1[1], s1[2], s1[3]};
; #pragma unroll
;                             for (int j = 0; j < 8; ++j) { const float o = __shfl_xor(v[j], 16); if (fq == 0) v[j] = v[j] * cs[j] - o * sn[j]; else if (fq == 1) v[j] = v[j] * cs[j] + o * sn[j]; } }
.LBB0_532:
	s_andn2_saveexec_b64 s[0:1], s[0:1]
	s_cbranch_execz .LBB0_534
	v_mov_b32_e32 v192, v6
	v_mov_b32_e32 v193, v14
	v_mov_b32_e32 v190, v130
	s_waitcnt lgkmcnt(0)
	v_mul_f32_e32 v130, v14, v191
	v_fma_f32 v190, v192, v190, -v130
	v_fma_f32 v191, v193, v191, -v130
	s_nop 0
	v_mov_b32_e32 v130, v190
.LBB0_534:
	s_or_b64 exec, exec, s[0:1]
	s_waitcnt lgkmcnt(0)
	ds_bpermute_b32 v191, v181, v131
	v_cmp_lt_i32_e32 vcc, 0, v204
	s_and_saveexec_b64 s[0:1], vcc
	s_xor_b64 s[0:1], exec, s[0:1]
	s_cbranch_execz .LBB0_538
	v_cmp_eq_u32_e32 vcc, 1, v204
	s_and_saveexec_b64 s[16:17], vcc
	s_cbranch_execz .LBB0_537
	v_mov_b32_e32 v192, v7
	v_mov_b32_e32 v193, v15
	v_mov_b32_e32 v190, v131
	s_waitcnt lgkmcnt(0)
	v_mul_f32_e32 v194, v15, v191
	v_fma_f32 v190, v192, v190, v194
	v_fma_f32 v191, v193, v191, v194
	s_nop 0
	v_mov_b32_e32 v131, v190

;     __device__ __forceinline__ void operator()(const f32x4 (&acc)[2][2][4][2], const Unit& u, int wr, int wc, int fr, int fq) const {
;     ...
;                         if (rope) { const float cs[8] = {c0[0], c0[1], c0[2], c0[3], c1[0], c1[1], c1[2], c1[3]}; const float sn[8] = {s0[0], s0[1], s0[2], s0[3], s1[0], s1[1], s1[2], s1[3]};
; #pragma unroll
;                             for (int j = 0; j < 8; ++j) { const float o = __shfl_xor(v[j], 16); if (fq == 0) v[j] = v[j] * cs[j] - o * sn[j]; else if (fq == 1) v[j] = v[j] * cs[j] + o * sn[j]; } }
.LBB0_538:
	s_andn2_saveexec_b64 s[0:1], s[0:1]
	s_cbranch_execz .LBB0_540
	v_mov_b32_e32 v192, v7
	v_mov_b32_e32 v193, v15
	v_mov_b32_e32 v190, v131
	s_waitcnt lgkmcnt(0)
	v_mul_f32_e32 v194, v15, v191
	v_fma_f32 v190, v192, v190, -v194
	v_fma_f32 v191, v193, v191, -v194
	s_nop 0
	v_mov_b32_e32 v131, v190

; __device__ __forceinline__ float silu(float x) { return x * sigm(x); }
;     __device__ __forceinline__ void operator()(const f32x4 (&acc)[2][2][4][2], const Unit& u, int wr, int wc, int fr, int fq) const {
;     ...
;                     } else if (reg == PB_QR || reg == PB_G) {
; #pragma unroll
;                         for (int j = 0; j < 8; ++j) v[j] = silu(v[j]);
;                     }
.LBB0_543:
	s_andn2_b64 vcc, exec, s[0:1]
	s_cbranch_vccnz .LBB0_545
	v_mul_f32_e32 v133, 0xbfb8aa3b, v126
	v_exp_f32_e32 v133, v133
	v_mul_f32_e32 v138, 0xbfb8aa3b, v124
	v_mul_f32_e32 v120, 0xbfb8aa3b, v136
	v_mul_f32_e32 v121, 0xbfb8aa3b, v137
	v_add_f32_e32 v133, 1.0, v133
	v_mul_f32_e32 v122, 0xbfb8aa3b, v134
	v_mul_f32_e32 v123, 0xbfb8aa3b, v135
	v_rcp_f32_e32 v140, v133
	v_mul_f32_e32 v133, 0xbfb8aa3b, v127
	v_exp_f32_e32 v138, v138
	v_mul_f32_e32 v139, 0xbfb8aa3b, v125
	v_exp_f32_e32 v120, v120
	v_exp_f32_e32 v121, v121
	v_exp_f32_e32 v122, v122
	v_exp_f32_e32 v123, v123
	v_exp_f32_e32 v133, v133
	v_exp_f32_e32 v139, v139
	v_add_f32_e32 v138, 1.0, v138
	v_add_f32_e32 v120, 1.0, v120
	v_add_f32_e32 v121, 1.0, v121
	v_add_f32_e32 v122, 1.0, v122
	v_add_f32_e32 v123, 1.0, v123
	v_add_f32_e32 v133, 1.0, v133
	v_rcp_f32_e32 v142, v138
	v_add_f32_e32 v138, 1.0, v139
	v_rcp_f32_e32 v120, v120
	v_rcp_f32_e32 v121, v121
	v_rcp_f32_e32 v122, v122
	v_rcp_f32_e32 v123, v123
	v_rcp_f32_e32 v143, v138
	v_rcp_f32_e32 v141, v133
	v_mul_f32_e32 v186, v136, v120
	v_mul_f32_e32 v187, v137, v121
	v_mul_f32_e32 v138, v134, v122
	v_mul_f32_e32 v139, v135, v123
	v_mul_f32_e32 v142, v124, v142
	v_mul_f32_e32 v143, v125, v143
	v_mul_f32_e32 v140, v126, v140
	v_mul_f32_e32 v141, v127, v141

;     __device__ __forceinline__ void operator()(const f32x4 (&acc)[2][2][4][2], const Unit& u, int wr, int wc, int fr, int fq) const {
;     ...
;                     if (reg <= 1) {
;                         if (rope) { const float cs[8] = {c0[0], c0[1], c0[2], c0[3], c1[0], c1[1], c1[2], c1[3]}; const float sn[8] = {s0[0], s0[1], s0[2], s0[3], s1[0], s1[1], s1[2], s1[3]};
; #pragma unroll
;                             for (int j = 0; j < 8; ++j) { const float o = __shfl_xor(v[j], 16); if (fq == 0) v[j] = v[j] * cs[j] - o * sn[j]; else if (fq == 1) v[j] = v[j] * cs[j] + o * sn[j]; } }
.LBB0_546:
	s_and_b64 vcc, exec, s[10:11]
	s_cbranch_vccnz .LBB0_1317
	v_and_b32_e32 v121, 64, v214
	v_xor_b32_e32 v120, 16, v214
	v_add_u32_e32 v121, 64, v121
	v_cmp_lt_i32_e32 vcc, v120, v121
	s_nop 1
	v_cndmask_b32_e32 v120, v214, v120, vcc
	v_lshlrev_b32_e32 v133, 2, v120
	ds_bpermute_b32 v143, v133, v136
	v_cmp_lt_i32_e32 vcc, 0, v204
	s_and_saveexec_b64 s[0:1], vcc
	s_xor_b64 s[0:1], exec, s[0:1]
	s_cbranch_execz .LBB0_551
	v_cmp_eq_u32_e32 vcc, 1, v204
	v_mov_b32_e32 v123, v125
	v_mov_b32_e32 v122, v124
	v_mov_b32_e32 v141, v127
	v_mov_b32_e32 v140, v126
	v_mov_b32_e32 v139, v135
	v_mov_b32_e32 v138, v134
	v_mov_b32_e32 v121, v137
	v_mov_b32_e32 v120, v136
	s_and_saveexec_b64 s[16:17], vcc
	s_cbranch_execz .LBB0_550
	v_mov_b32_e32 v120, v136
	v_mov_b32_e32 v121, v20
	v_mov_b32_e32 v142, v16
	s_waitcnt lgkmcnt(0)
	v_mul_f32_e32 v120, v120, v142
	v_mul_f32_e32 v121, v121, v143
	v_mov_b32_e32 v123, v125
	v_add_f32_e32 v120, v120, v121
	v_mov_b32_e32 v122, v124
	v_mov_b32_e32 v141, v127
	v_mov_b32_e32 v140, v126
	v_mov_b32_e32 v139, v135
	v_mov_b32_e32 v138, v134
	v_mov_b32_e32 v121, v137

;     __device__ __forceinline__ void operator()(const f32x4 (&acc)[2][2][4][2], const Unit& u, int wr, int wc, int fr, int fq) const {
;     ...
;                         if (rope) { const float cs[8] = {c0[0], c0[1], c0[2], c0[3], c1[0], c1[1], c1[2], c1[3]}; const float sn[8] = {s0[0], s0[1], s0[2], s0[3], s1[0], s1[1], s1[2], s1[3]};
; #pragma unroll
;                             for (int j = 0; j < 8; ++j) { const float o = __shfl_xor(v[j], 16); if (fq == 0) v[j] = v[j] * cs[j] - o * sn[j]; else if (fq == 1) v[j] = v[j] * cs[j] + o * sn[j]; } }
.LBB0_551:
	s_andn2_saveexec_b64 s[0:1], s[0:1]
	s_cbranch_execz .LBB0_553
	v_mov_b32_e32 v120, v136
	v_mov_b32_e32 v121, v20
	v_mov_b32_e32 v142, v16
	s_waitcnt lgkmcnt(0)
	v_mul_f32_e32 v120, v120, v142
	v_mul_f32_e32 v121, v121, v143
	v_mov_b32_e32 v138, v134
	v_sub_f32_e32 v120, v120, v121
	v_mov_b32_e32 v121, v137
	v_mov_b32_e32 v139, v135
	v_mov_b32_e32 v140, v126
	v_mov_b32_e32 v141, v127
	v_mov_b32_e32 v122, v124
	v_mov_b32_e32 v123, v125
.LBB0_553:
	s_or_b64 exec, exec, s[0:1]
	s_waitcnt lgkmcnt(0)
	ds_bpermute_b32 v143, v133, v121
	v_cmp_lt_i32_e32 vcc, 0, v204
	s_and_saveexec_b64 s[0:1], vcc
	s_xor_b64 s[0:1], exec, s[0:1]
	s_cbranch_execz .LBB0_557
	v_cmp_eq_u32_e32 vcc, 1, v204
	s_and_saveexec_b64 s[16:17], vcc
	s_cbranch_execz .LBB0_556
	v_mov_b32_e32 v186, v17
	v_mov_b32_e32 v187, v21
	v_mov_b32_e32 v142, v121
	v_mul_f32_e32 v188, v17, v121
	s_waitcnt lgkmcnt(0)
	v_fma_f32 v142, v186, v142, v188
	v_fma_f32 v143, v187, v143, v188
	s_nop 0
	v_mov_b32_e32 v121, v143

;     __device__ __forceinline__ void operator()(const f32x4 (&acc)[2][2][4][2], const Unit& u, int wr, int wc, int fr, int fq) const {
;     ...
;                         if (rope) { const float cs[8] = {c0[0], c0[1], c0[2], c0[3], c1[0], c1[1], c1[2], c1[3]}; const float sn[8] = {s0[0], s0[1], s0[2], s0[3], s1[0], s1[1], s1[2], s1[3]};
; #pragma unroll
;                             for (int j = 0; j < 8; ++j) { const float o = __shfl_xor(v[j], 16); if (fq == 0) v[j] = v[j] * cs[j] - o * sn[j]; else if (fq == 1) v[j] = v[j] * cs[j] + o * sn[j]; } }
.LBB0_557:
	s_andn2_saveexec_b64 s[0:1], s[0:1]
	s_cbranch_execz .LBB0_559
	v_mov_b32_e32 v186, v17
	v_mov_b32_e32 v187, v21
	v_mov_b32_e32 v142, v121
	v_mul_f32_e32 v188, v17, v121
	s_waitcnt lgkmcnt(0)
	v_fma_f32 v142, -v186, v142, v188
	v_fma_f32 v143, -v187, v143, v188
	s_nop 0
	v_mov_b32_e32 v121, v143
.LBB0_559:
	s_or_b64 exec, exec, s[0:1]
	s_waitcnt lgkmcnt(0)
	ds_bpermute_b32 v143, v133, v138
	v_cmp_lt_i32_e32 vcc, 0, v204
	s_and_saveexec_b64 s[0:1], vcc
	s_xor_b64 s[0:1], exec, s[0:1]
	s_cbranch_execz .LBB0_563
	v_cmp_eq_u32_e32 vcc, 1, v204
	s_and_saveexec_b64 s[16:17], vcc
	s_cbranch_execz .LBB0_562
	v_mov_b32_e32 v186, v18
	v_mov_b32_e32 v187, v22
	v_mov_b32_e32 v142, v138
	s_waitcnt lgkmcnt(0)
	v_mul_f32_e32 v138, v22, v143
	v_fma_f32 v142, v186, v142, v138
	v_fma_f32 v143, v187, v143, v138
	s_nop 0
	v_mov_b32_e32 v138, v142

;     __device__ __forceinline__ void operator()(const f32x4 (&acc)[2][2][4][2], const Unit& u, int wr, int wc, int fr, int fq) const {
;     ...
;                         if (rope) { const float cs[8] = {c0[0], c0[1], c0[2], c0[3], c1[0], c1[1], c1[2], c1[3]}; const float sn[8] = {s0[0], s0[1], s0[2], s0[3], s1[0], s1[1], s1[2], s1[3]};
; #pragma unroll
;                             for (int j = 0; j < 8; ++j) { const float o = __shfl_xor(v[j], 16); if (fq == 0) v[j] = v[j] * cs[j] - o * sn[j]; else if (fq == 1) v[j] = v[j] * cs[j] + o * sn[j]; } }
.LBB0_563:
	s_andn2_saveexec_b64 s[0:1], s[0:1]
	s_cbranch_execz .LBB0_565
	v_mov_b32_e32 v186, v18
	v_mov_b32_e32 v187, v22
	v_mov_b32_e32 v142, v138
	s_waitcnt lgkmcnt(0)
	v_mul_f32_e32 v138, v22, v143
	v_fma_f32 v142, v186, v142, -v138
	v_fma_f32 v143, v187, v143, -v138
	s_nop 0
	v_mov_b32_e32 v138, v142
.LBB0_565:
	s_or_b64 exec, exec, s[0:1]
	s_waitcnt lgkmcnt(0)
	ds_bpermute_b32 v143, v133, v139
	v_cmp_lt_i32_e32 vcc, 0, v204
	s_and_saveexec_b64 s[0:1], vcc
	s_xor_b64 s[0:1], exec, s[0:1]
	s_cbranch_execz .LBB0_569
	v_cmp_eq_u32_e32 vcc, 1, v204
	s_and_saveexec_b64 s[16:17], vcc
	s_cbranch_execz .LBB0_568
	v_mov_b32_e32 v186, v19
	v_mov_b32_e32 v187, v23
	v_mov_b32_e32 v142, v139
	s_waitcnt lgkmcnt(0)
	v_mul_f32_e32 v188, v23, v143
	v_fma_f32 v142, v186, v142, v188
	v_fma_f32 v143, v187, v143, v188
	s_nop 0
	v_mov_b32_e32 v139, v142

;     __device__ __forceinline__ void operator()(const f32x4 (&acc)[2][2][4][2], const Unit& u, int wr, int wc, int fr, int fq) const {
;     ...
;                         if (rope) { const float cs[8] = {c0[0], c0[1], c0[2], c0[3], c1[0], c1[1], c1[2], c1[3]}; const float sn[8] = {s0[0], s0[1], s0[2], s0[3], s1[0], s1[1], s1[2], s1[3]};
; #pragma unroll
;                             for (int j = 0; j < 8; ++j) { const float o = __shfl_xor(v[j], 16); if (fq == 0) v[j] = v[j] * cs[j] - o * sn[j]; else if (fq == 1) v[j] = v[j] * cs[j] + o * sn[j]; } }
.LBB0_569:
	s_andn2_saveexec_b64 s[0:1], s[0:1]
	s_cbranch_execz .LBB0_571
	v_mov_b32_e32 v186, v19
	v_mov_b32_e32 v187, v23
	v_mov_b32_e32 v142, v139
	s_waitcnt lgkmcnt(0)
	v_mul_f32_e32 v188, v23, v143
	v_fma_f32 v142, v186, v142, -v188
	v_fma_f32 v143, v187, v143, -v188
	s_nop 0
	v_mov_b32_e32 v139, v142
.LBB0_571:
	s_or_b64 exec, exec, s[0:1]
	s_waitcnt lgkmcnt(0)
	ds_bpermute_b32 v143, v133, v140
	v_cmp_lt_i32_e32 vcc, 0, v204
	s_and_saveexec_b64 s[0:1], vcc
	s_xor_b64 s[0:1], exec, s[0:1]
	s_cbranch_execz .LBB0_575
	v_cmp_eq_u32_e32 vcc, 1, v204
	s_and_saveexec_b64 s[16:17], vcc
	s_cbranch_execz .LBB0_574
	v_mov_b32_e32 v186, v4
	v_mov_b32_e32 v187, v12
	v_mov_b32_e32 v142, v140
	s_waitcnt lgkmcnt(0)
	v_mul_f32_e32 v140, v12, v143
	v_fma_f32 v142, v186, v142, v140
	v_fma_f32 v143, v187, v143, v140
	s_nop 0
	v_mov_b32_e32 v140, v142

;     __device__ __forceinline__ void operator()(const f32x4 (&acc)[2][2][4][2], const Unit& u, int wr, int wc, int fr, int fq) const {
;     ...
;                         if (rope) { const float cs[8] = {c0[0], c0[1], c0[2], c0[3], c1[0], c1[1], c1[2], c1[3]}; const float sn[8] = {s0[0], s0[1], s0[2], s0[3], s1[0], s1[1], s1[2], s1[3]};
; #pragma unroll
;                             for (int j = 0; j < 8; ++j) { const float o = __shfl_xor(v[j], 16); if (fq == 0) v[j] = v[j] * cs[j] - o * sn[j]; else if (fq == 1) v[j] = v[j] * cs[j] + o * sn[j]; } }
.LBB0_575:
	s_andn2_saveexec_b64 s[0:1], s[0:1]
	s_cbranch_execz .LBB0_577
	v_mov_b32_e32 v186, v4
	v_mov_b32_e32 v187, v12
	v_mov_b32_e32 v142, v140
	s_waitcnt lgkmcnt(0)
	v_mul_f32_e32 v140, v12, v143
	v_fma_f32 v142, v186, v142, -v140
	v_fma_f32 v143, v187, v143, -v140
	s_nop 0
	v_mov_b32_e32 v140, v142
.LBB0_577:
	s_or_b64 exec, exec, s[0:1]
	s_waitcnt lgkmcnt(0)
	ds_bpermute_b32 v143, v133, v141
	v_cmp_lt_i32_e32 vcc, 0, v204
	s_and_saveexec_b64 s[0:1], vcc
	s_xor_b64 s[0:1], exec, s[0:1]
	s_cbranch_execz .LBB0_581
	v_cmp_eq_u32_e32 vcc, 1, v204
	s_and_saveexec_b64 s[16:17], vcc
	s_cbranch_execz .LBB0_580
	v_mov_b32_e32 v186, v5
	v_mov_b32_e32 v187, v13
	v_mov_b32_e32 v142, v141
	s_waitcnt lgkmcnt(0)
	v_mul_f32_e32 v188, v13, v143
	v_fma_f32 v142, v186, v142, v188
	v_fma_f32 v143, v187, v143, v188
	s_nop 0
	v_mov_b32_e32 v141, v142

;     __device__ __forceinline__ void operator()(const f32x4 (&acc)[2][2][4][2], const Unit& u, int wr, int wc, int fr, int fq) const {
;     ...
;                         if (rope) { const float cs[8] = {c0[0], c0[1], c0[2], c0[3], c1[0], c1[1], c1[2], c1[3]}; const float sn[8] = {s0[0], s0[1], s0[2], s0[3], s1[0], s1[1], s1[2], s1[3]};
; #pragma unroll
;                             for (int j = 0; j < 8; ++j) { const float o = __shfl_xor(v[j], 16); if (fq == 0) v[j] = v[j] * cs[j] - o * sn[j]; else if (fq == 1) v[j] = v[j] * cs[j] + o * sn[j]; } }
.LBB0_581:
	s_andn2_saveexec_b64 s[0:1], s[0:1]
	s_cbranch_execz .LBB0_583
	v_mov_b32_e32 v186, v5
	v_mov_b32_e32 v187, v13
	v_mov_b32_e32 v142, v141
	s_waitcnt lgkmcnt(0)
	v_mul_f32_e32 v188, v13, v143
	v_fma_f32 v142, v186, v142, -v188
	v_fma_f32 v143, v187, v143, -v188
	s_nop 0
	v_mov_b32_e32 v141, v142
.LBB0_583:
	s_or_b64 exec, exec, s[0:1]
	s_waitcnt lgkmcnt(0)
	ds_bpermute_b32 v143, v133, v122
	v_cmp_lt_i32_e32 vcc, 0, v204
	s_and_saveexec_b64 s[0:1], vcc
	s_xor_b64 s[0:1], exec, s[0:1]
	s_cbranch_execz .LBB0_587
	v_cmp_eq_u32_e32 vcc, 1, v204
	s_and_saveexec_b64 s[16:17], vcc
	s_cbranch_execz .LBB0_586
	v_mov_b32_e32 v186, v6
	v_mov_b32_e32 v187, v14
	v_mov_b32_e32 v142, v122
	s_waitcnt lgkmcnt(0)
	v_mul_f32_e32 v122, v14, v143
	v_fma_f32 v142, v186, v142, v122
	v_fma_f32 v143, v187, v143, v122
	s_nop 0
	v_mov_b32_e32 v122, v142

;     __device__ __forceinline__ void operator()(const f32x4 (&acc)[2][2][4][2], const Unit& u, int wr, int wc, int fr, int fq) const {
;     ...
;                         if (rope) { const float cs[8] = {c0[0], c0[1], c0[2], c0[3], c1[0], c1[1], c1[2], c1[3]}; const float sn[8] = {s0[0], s0[1], s0[2], s0[3], s1[0], s1[1], s1[2], s1[3]};
; #pragma unroll
;                             for (int j = 0; j < 8; ++j) { const float o = __shfl_xor(v[j], 16); if (fq == 0) v[j] = v[j] * cs[j] - o * sn[j]; else if (fq == 1) v[j] = v[j] * cs[j] + o * sn[j]; } }
.LBB0_587:
	s_andn2_saveexec_b64 s[0:1], s[0:1]
	s_cbranch_execz .LBB0_589
	v_mov_b32_e32 v186, v6
	v_mov_b32_e32 v187, v14
	v_mov_b32_e32 v142, v122
	s_waitcnt lgkmcnt(0)
	v_mul_f32_e32 v122, v14, v143
	v_fma_f32 v142, v186, v142, -v122
	v_fma_f32 v143, v187, v143, -v122
	s_nop 0
	v_mov_b32_e32 v122, v142
.LBB0_589:
	s_or_b64 exec, exec, s[0:1]
	s_waitcnt lgkmcnt(0)
	ds_bpermute_b32 v143, v133, v123
	v_cmp_lt_i32_e32 vcc, 0, v204
	s_and_saveexec_b64 s[0:1], vcc
	s_xor_b64 s[0:1], exec, s[0:1]
	s_cbranch_execz .LBB0_593
	v_cmp_eq_u32_e32 vcc, 1, v204
	s_and_saveexec_b64 s[16:17], vcc
	s_cbranch_execz .LBB0_592
	v_mov_b32_e32 v186, v7
	v_mov_b32_e32 v187, v15
	v_mov_b32_e32 v142, v123
	s_waitcnt lgkmcnt(0)
	v_mul_f32_e32 v188, v15, v143
	v_fma_f32 v142, v186, v142, v188
	v_fma_f32 v143, v187, v143, v188
	s_nop 0
	v_mov_b32_e32 v123, v142

;     __device__ __forceinline__ void operator()(const f32x4 (&acc)[2][2][4][2], const Unit& u, int wr, int wc, int fr, int fq) const {
;     ...
;                         if (rope) { const float cs[8] = {c0[0], c0[1], c0[2], c0[3], c1[0], c1[1], c1[2], c1[3]}; const float sn[8] = {s0[0], s0[1], s0[2], s0[3], s1[0], s1[1], s1[2], s1[3]};
; #pragma unroll
;                             for (int j = 0; j < 8; ++j) { const float o = __shfl_xor(v[j], 16); if (fq == 0) v[j] = v[j] * cs[j] - o * sn[j]; else if (fq == 1) v[j] = v[j] * cs[j] + o * sn[j]; } }
.LBB0_593:
	s_andn2_saveexec_b64 s[0:1], s[0:1]
	s_cbranch_execz .LBB0_595
	v_mov_b32_e32 v186, v7
	v_mov_b32_e32 v187, v15
	v_mov_b32_e32 v142, v123
	s_waitcnt lgkmcnt(0)
	v_mul_f32_e32 v188, v15, v143
	v_fma_f32 v142, v186, v142, -v188
	v_fma_f32 v143, v187, v143, -v188
	s_nop 0
	v_mov_b32_e32 v123, v142

; __device__ __forceinline__ float fexp(float x) { return __builtin_amdgcn_exp2f(x * LOG2E); }
; __device__ __forceinline__ float sigm(float x) { return __builtin_amdgcn_rcpf(1.f + fexp(-x)); }
; __device__ __forceinline__ float silu(float x) { return x * sigm(x); }
;     __device__ __forceinline__ void operator()(const f32x4 (&acc)[2][2][4][2], const Unit& u, int wr, int wc, int fr, int fq) const {
;     ...
;                     } else if (reg == PB_QR || reg == PB_G) {
; #pragma unroll
;                         for (int j = 0; j < 8; ++j) v[j] = silu(v[j]);
.LBB0_598:
	s_andn2_b64 vcc, exec, s[0:1]
	s_cbranch_vccnz .LBB0_600
	v_mul_f32_e32 v124, 0xbfb8aa3b, v118
	v_exp_f32_e32 v124, v124
	v_mul_f32_e32 v125, 0xbfb8aa3b, v116
	v_mul_f32_e32 v112, 0xbfb8aa3b, v122
	v_mul_f32_e32 v113, 0xbfb8aa3b, v123
	v_add_f32_e32 v124, 1.0, v124
	v_mul_f32_e32 v114, 0xbfb8aa3b, v120
	v_mul_f32_e32 v115, 0xbfb8aa3b, v121
	v_rcp_f32_e32 v126, v124
	v_mul_f32_e32 v124, 0xbfb8aa3b, v119
	v_exp_f32_e32 v125, v125
	v_mul_f32_e32 v127, 0xbfb8aa3b, v117
	v_exp_f32_e32 v112, v112
	v_exp_f32_e32 v113, v113
	v_exp_f32_e32 v114, v114
	v_exp_f32_e32 v115, v115
	v_exp_f32_e32 v124, v124
	v_exp_f32_e32 v127, v127
	v_add_f32_e32 v125, 1.0, v125
	v_add_f32_e32 v112, 1.0, v112
	v_add_f32_e32 v113, 1.0, v113
	v_add_f32_e32 v114, 1.0, v114
	v_add_f32_e32 v115, 1.0, v115
	v_add_f32_e32 v124, 1.0, v124
	v_rcp_f32_e32 v132, v125
	v_add_f32_e32 v125, 1.0, v127
	v_rcp_f32_e32 v112, v112
	v_rcp_f32_e32 v113, v113
	v_rcp_f32_e32 v114, v114
	v_rcp_f32_e32 v115, v115
	v_rcp_f32_e32 v133, v125
	v_rcp_f32_e32 v127, v124
	v_mul_f32_e32 v134, v122, v112
	v_mul_f32_e32 v135, v123, v113
	v_mul_f32_e32 v124, v120, v114
	v_mul_f32_e32 v125, v121, v115
	v_mul_f32_e32 v132, v116, v132
	v_mul_f32_e32 v133, v117, v133
	v_mul_f32_e32 v126, v118, v126
	v_mul_f32_e32 v127, v119, v127

;     __device__ __forceinline__ void operator()(const f32x4 (&acc)[2][2][4][2], const Unit& u, int wr, int wc, int fr, int fq) const {
;     ...
;                     if (reg <= 1) {
;                         if (rope) { const float cs[8] = {c0[0], c0[1], c0[2], c0[3], c1[0], c1[1], c1[2], c1[3]}; const float sn[8] = {s0[0], s0[1], s0[2], s0[3], s1[0], s1[1], s1[2], s1[3]};
; #pragma unroll
;                             for (int j = 0; j < 8; ++j) { const float o = __shfl_xor(v[j], 16); if (fq == 0) v[j] = v[j] * cs[j] - o * sn[j]; else if (fq == 1) v[j] = v[j] * cs[j] + o * sn[j]; } }
.LBB0_601:
	s_and_b64 vcc, exec, s[10:11]
	s_cbranch_vccnz .LBB0_1320
	v_and_b32_e32 v113, 64, v214
	v_xor_b32_e32 v112, 16, v214
	v_add_u32_e32 v113, 64, v113
	v_cmp_lt_i32_e32 vcc, v112, v113
	s_nop 1
	v_cndmask_b32_e32 v112, v214, v112, vcc
	v_lshlrev_b32_e32 v134, 2, v112
	ds_bpermute_b32 v133, v134, v122
	v_cmp_lt_i32_e32 vcc, 0, v204
	s_and_saveexec_b64 s[0:1], vcc
	s_xor_b64 s[0:1], exec, s[0:1]
	s_cbranch_execz .LBB0_606
	v_cmp_eq_u32_e32 vcc, 1, v204
	v_mov_b32_e32 v115, v117
	v_mov_b32_e32 v114, v116
	v_mov_b32_e32 v127, v119
	v_mov_b32_e32 v126, v118
	v_mov_b32_e32 v125, v121
	v_mov_b32_e32 v124, v120
	v_mov_b32_e32 v113, v123
	v_mov_b32_e32 v112, v122
	s_and_saveexec_b64 s[16:17], vcc
	s_cbranch_execz .LBB0_605
	v_mov_b32_e32 v112, v122
	v_mov_b32_e32 v113, v20
	v_mov_b32_e32 v132, v16
	s_waitcnt lgkmcnt(0)
	v_mul_f32_e32 v112, v112, v132
	v_mul_f32_e32 v113, v113, v133
	v_mov_b32_e32 v115, v117
	v_add_f32_e32 v112, v112, v113
	v_mov_b32_e32 v114, v116
	v_mov_b32_e32 v127, v119
	v_mov_b32_e32 v126, v118
	v_mov_b32_e32 v125, v121
	v_mov_b32_e32 v124, v120
	v_mov_b32_e32 v113, v123

;     __device__ __forceinline__ void operator()(const f32x4 (&acc)[2][2][4][2], const Unit& u, int wr, int wc, int fr, int fq) const {
;     ...
;                         if (rope) { const float cs[8] = {c0[0], c0[1], c0[2], c0[3], c1[0], c1[1], c1[2], c1[3]}; const float sn[8] = {s0[0], s0[1], s0[2], s0[3], s1[0], s1[1], s1[2], s1[3]};
; #pragma unroll
;                             for (int j = 0; j < 8; ++j) { const float o = __shfl_xor(v[j], 16); if (fq == 0) v[j] = v[j] * cs[j] - o * sn[j]; else if (fq == 1) v[j] = v[j] * cs[j] + o * sn[j]; } }
.LBB0_606:
	s_andn2_saveexec_b64 s[0:1], s[0:1]
	s_cbranch_execz .LBB0_608
	v_mov_b32_e32 v112, v122
	v_mov_b32_e32 v113, v20
	v_mov_b32_e32 v132, v16
	s_waitcnt lgkmcnt(0)
	v_mul_f32_e32 v112, v112, v132
	v_mul_f32_e32 v113, v113, v133
	v_mov_b32_e32 v124, v120
	v_sub_f32_e32 v112, v112, v113
	v_mov_b32_e32 v113, v123
	v_mov_b32_e32 v125, v121
	v_mov_b32_e32 v126, v118
	v_mov_b32_e32 v127, v119
	v_mov_b32_e32 v114, v116
	v_mov_b32_e32 v115, v117
.LBB0_608:
	s_or_b64 exec, exec, s[0:1]
	s_waitcnt lgkmcnt(0)
	ds_bpermute_b32 v133, v134, v113
	v_cmp_lt_i32_e32 vcc, 0, v204
	s_and_saveexec_b64 s[0:1], vcc
	s_xor_b64 s[0:1], exec, s[0:1]
	s_cbranch_execz .LBB0_612
	v_cmp_eq_u32_e32 vcc, 1, v204
	s_and_saveexec_b64 s[16:17], vcc
	s_cbranch_execz .LBB0_611
	v_mov_b32_e32 v136, v17
	v_mov_b32_e32 v137, v21
	v_mov_b32_e32 v132, v113
	v_mul_f32_e32 v138, v17, v113
	s_waitcnt lgkmcnt(0)
	v_fma_f32 v132, v136, v132, v138
	v_fma_f32 v133, v137, v133, v138
	s_nop 0
	v_mov_b32_e32 v113, v133

;     __device__ __forceinline__ void operator()(const f32x4 (&acc)[2][2][4][2], const Unit& u, int wr, int wc, int fr, int fq) const {
;     ...
;                         if (rope) { const float cs[8] = {c0[0], c0[1], c0[2], c0[3], c1[0], c1[1], c1[2], c1[3]}; const float sn[8] = {s0[0], s0[1], s0[2], s0[3], s1[0], s1[1], s1[2], s1[3]};
; #pragma unroll
;                             for (int j = 0; j < 8; ++j) { const float o = __shfl_xor(v[j], 16); if (fq == 0) v[j] = v[j] * cs[j] - o * sn[j]; else if (fq == 1) v[j] = v[j] * cs[j] + o * sn[j]; } }
.LBB0_612:
	s_andn2_saveexec_b64 s[0:1], s[0:1]
	s_cbranch_execz .LBB0_614
	v_mov_b32_e32 v136, v17
	v_mov_b32_e32 v137, v21
	v_mov_b32_e32 v132, v113
	v_mul_f32_e32 v138, v17, v113
	s_waitcnt lgkmcnt(0)
	v_fma_f32 v132, -v136, v132, v138
	v_fma_f32 v133, -v137, v133, v138
	s_nop 0
	v_mov_b32_e32 v113, v133
.LBB0_614:
	s_or_b64 exec, exec, s[0:1]
	s_waitcnt lgkmcnt(0)
	ds_bpermute_b32 v133, v134, v124
	v_cmp_lt_i32_e32 vcc, 0, v204
	s_and_saveexec_b64 s[0:1], vcc
	s_xor_b64 s[0:1], exec, s[0:1]
	s_cbranch_execz .LBB0_618
	v_cmp_eq_u32_e32 vcc, 1, v204
	s_and_saveexec_b64 s[16:17], vcc
	s_cbranch_execz .LBB0_617
	v_mov_b32_e32 v136, v18
	v_mov_b32_e32 v137, v22
	v_mov_b32_e32 v132, v124
	s_waitcnt lgkmcnt(0)
	v_mul_f32_e32 v124, v22, v133
	v_fma_f32 v132, v136, v132, v124
	v_fma_f32 v133, v137, v133, v124
	s_nop 0
	v_mov_b32_e32 v124, v132

;     __device__ __forceinline__ void operator()(const f32x4 (&acc)[2][2][4][2], const Unit& u, int wr, int wc, int fr, int fq) const {
;     ...
;                         if (rope) { const float cs[8] = {c0[0], c0[1], c0[2], c0[3], c1[0], c1[1], c1[2], c1[3]}; const float sn[8] = {s0[0], s0[1], s0[2], s0[3], s1[0], s1[1], s1[2], s1[3]};
; #pragma unroll
;                             for (int j = 0; j < 8; ++j) { const float o = __shfl_xor(v[j], 16); if (fq == 0) v[j] = v[j] * cs[j] - o * sn[j]; else if (fq == 1) v[j] = v[j] * cs[j] + o * sn[j]; } }
.LBB0_618:
	s_andn2_saveexec_b64 s[0:1], s[0:1]
	s_cbranch_execz .LBB0_620
	v_mov_b32_e32 v136, v18
	v_mov_b32_e32 v137, v22
	v_mov_b32_e32 v132, v124
	s_waitcnt lgkmcnt(0)
	v_mul_f32_e32 v124, v22, v133
	v_fma_f32 v132, v136, v132, -v124
	v_fma_f32 v133, v137, v133, -v124
	s_nop 0
	v_mov_b32_e32 v124, v132
.LBB0_620:
	s_or_b64 exec, exec, s[0:1]
	s_waitcnt lgkmcnt(0)
	ds_bpermute_b32 v133, v134, v125
	v_cmp_lt_i32_e32 vcc, 0, v204
	s_and_saveexec_b64 s[0:1], vcc
	s_xor_b64 s[0:1], exec, s[0:1]
	s_cbranch_execz .LBB0_624
	v_cmp_eq_u32_e32 vcc, 1, v204
	s_and_saveexec_b64 s[16:17], vcc
	s_cbranch_execz .LBB0_623
	v_mov_b32_e32 v136, v19
	v_mov_b32_e32 v137, v23
	v_mov_b32_e32 v132, v125
	s_waitcnt lgkmcnt(0)
	v_mul_f32_e32 v138, v23, v133
	v_fma_f32 v132, v136, v132, v138
	v_fma_f32 v133, v137, v133, v138
	s_nop 0
	v_mov_b32_e32 v125, v132

;     __device__ __forceinline__ void operator()(const f32x4 (&acc)[2][2][4][2], const Unit& u, int wr, int wc, int fr, int fq) const {
;     ...
;                         if (rope) { const float cs[8] = {c0[0], c0[1], c0[2], c0[3], c1[0], c1[1], c1[2], c1[3]}; const float sn[8] = {s0[0], s0[1], s0[2], s0[3], s1[0], s1[1], s1[2], s1[3]};
; #pragma unroll
;                             for (int j = 0; j < 8; ++j) { const float o = __shfl_xor(v[j], 16); if (fq == 0) v[j] = v[j] * cs[j] - o * sn[j]; else if (fq == 1) v[j] = v[j] * cs[j] + o * sn[j]; } }
.LBB0_624:
	s_andn2_saveexec_b64 s[0:1], s[0:1]
	s_cbranch_execz .LBB0_626
	v_mov_b32_e32 v136, v19
	v_mov_b32_e32 v137, v23
	v_mov_b32_e32 v132, v125
	s_waitcnt lgkmcnt(0)
	v_mul_f32_e32 v138, v23, v133
	v_fma_f32 v132, v136, v132, -v138
	v_fma_f32 v133, v137, v133, -v138
	s_nop 0
	v_mov_b32_e32 v125, v132
.LBB0_626:
	s_or_b64 exec, exec, s[0:1]
	s_waitcnt lgkmcnt(0)
	ds_bpermute_b32 v133, v134, v126
	v_cmp_lt_i32_e32 vcc, 0, v204
	s_and_saveexec_b64 s[0:1], vcc
	s_xor_b64 s[0:1], exec, s[0:1]
	s_cbranch_execz .LBB0_630
	v_cmp_eq_u32_e32 vcc, 1, v204
	s_and_saveexec_b64 s[16:17], vcc
	s_cbranch_execz .LBB0_629
	v_mov_b32_e32 v136, v4
	v_mov_b32_e32 v137, v12
	v_mov_b32_e32 v132, v126
	s_waitcnt lgkmcnt(0)
	v_mul_f32_e32 v126, v12, v133
	v_fma_f32 v132, v136, v132, v126
	v_fma_f32 v133, v137, v133, v126
	s_nop 0
	v_mov_b32_e32 v126, v132

;     __device__ __forceinline__ void operator()(const f32x4 (&acc)[2][2][4][2], const Unit& u, int wr, int wc, int fr, int fq) const {
;     ...
;                         if (rope) { const float cs[8] = {c0[0], c0[1], c0[2], c0[3], c1[0], c1[1], c1[2], c1[3]}; const float sn[8] = {s0[0], s0[1], s0[2], s0[3], s1[0], s1[1], s1[2], s1[3]};
; #pragma unroll
;                             for (int j = 0; j < 8; ++j) { const float o = __shfl_xor(v[j], 16); if (fq == 0) v[j] = v[j] * cs[j] - o * sn[j]; else if (fq == 1) v[j] = v[j] * cs[j] + o * sn[j]; } }
.LBB0_630:
	s_andn2_saveexec_b64 s[0:1], s[0:1]
	s_cbranch_execz .LBB0_632
	v_mov_b32_e32 v136, v4
	v_mov_b32_e32 v137, v12
	v_mov_b32_e32 v132, v126
	s_waitcnt lgkmcnt(0)
	v_mul_f32_e32 v126, v12, v133
	v_fma_f32 v132, v136, v132, -v126
	v_fma_f32 v133, v137, v133, -v126
	s_nop 0
	v_mov_b32_e32 v126, v132
.LBB0_632:
	s_or_b64 exec, exec, s[0:1]
	s_waitcnt lgkmcnt(0)
	ds_bpermute_b32 v133, v134, v127
	v_cmp_lt_i32_e32 vcc, 0, v204
	s_and_saveexec_b64 s[0:1], vcc
	s_xor_b64 s[0:1], exec, s[0:1]
	s_cbranch_execz .LBB0_636
	v_cmp_eq_u32_e32 vcc, 1, v204
	s_and_saveexec_b64 s[16:17], vcc
	s_cbranch_execz .LBB0_635
	v_mov_b32_e32 v136, v5
	v_mov_b32_e32 v137, v13
	v_mov_b32_e32 v132, v127
	s_waitcnt lgkmcnt(0)
	v_mul_f32_e32 v138, v13, v133
	v_fma_f32 v132, v136, v132, v138
	v_fma_f32 v133, v137, v133, v138
	s_nop 0
	v_mov_b32_e32 v127, v132

;     __device__ __forceinline__ void operator()(const f32x4 (&acc)[2][2][4][2], const Unit& u, int wr, int wc, int fr, int fq) const {
;     ...
;                         if (rope) { const float cs[8] = {c0[0], c0[1], c0[2], c0[3], c1[0], c1[1], c1[2], c1[3]}; const float sn[8] = {s0[0], s0[1], s0[2], s0[3], s1[0], s1[1], s1[2], s1[3]};
; #pragma unroll
;                             for (int j = 0; j < 8; ++j) { const float o = __shfl_xor(v[j], 16); if (fq == 0) v[j] = v[j] * cs[j] - o * sn[j]; else if (fq == 1) v[j] = v[j] * cs[j] + o * sn[j]; } }
.LBB0_636:
	s_andn2_saveexec_b64 s[0:1], s[0:1]
	s_cbranch_execz .LBB0_638
	v_mov_b32_e32 v136, v5
	v_mov_b32_e32 v137, v13
	v_mov_b32_e32 v132, v127
	s_waitcnt lgkmcnt(0)
	v_mul_f32_e32 v138, v13, v133
	v_fma_f32 v132, v136, v132, -v138
	v_fma_f32 v133, v137, v133, -v138
	s_nop 0
	v_mov_b32_e32 v127, v132
.LBB0_638:
	s_or_b64 exec, exec, s[0:1]
	s_waitcnt lgkmcnt(0)
	ds_bpermute_b32 v133, v134, v114
	v_cmp_lt_i32_e32 vcc, 0, v204
	s_and_saveexec_b64 s[0:1], vcc
	s_xor_b64 s[0:1], exec, s[0:1]
	s_cbranch_execz .LBB0_642
	v_cmp_eq_u32_e32 vcc, 1, v204
	s_and_saveexec_b64 s[16:17], vcc
	s_cbranch_execz .LBB0_641
	v_mov_b32_e32 v136, v6
	v_mov_b32_e32 v137, v14
	v_mov_b32_e32 v132, v114
	s_waitcnt lgkmcnt(0)
	v_mul_f32_e32 v114, v14, v133
	v_fma_f32 v132, v136, v132, v114
	v_fma_f32 v133, v137, v133, v114
	s_nop 0
	v_mov_b32_e32 v114, v132

;     __device__ __forceinline__ void operator()(const f32x4 (&acc)[2][2][4][2], const Unit& u, int wr, int wc, int fr, int fq) const {
;     ...
;                         if (rope) { const float cs[8] = {c0[0], c0[1], c0[2], c0[3], c1[0], c1[1], c1[2], c1[3]}; const float sn[8] = {s0[0], s0[1], s0[2], s0[3], s1[0], s1[1], s1[2], s1[3]};
; #pragma unroll
;                             for (int j = 0; j < 8; ++j) { const float o = __shfl_xor(v[j], 16); if (fq == 0) v[j] = v[j] * cs[j] - o * sn[j]; else if (fq == 1) v[j] = v[j] * cs[j] + o * sn[j]; } }
.LBB0_642:
	s_andn2_saveexec_b64 s[0:1], s[0:1]
	s_cbranch_execz .LBB0_644
	v_mov_b32_e32 v136, v6
	v_mov_b32_e32 v137, v14
	v_mov_b32_e32 v132, v114
	s_waitcnt lgkmcnt(0)
	v_mul_f32_e32 v114, v14, v133
	v_fma_f32 v132, v136, v132, -v114
	v_fma_f32 v133, v137, v133, -v114
	s_nop 0
	v_mov_b32_e32 v114, v132
.LBB0_644:
	s_or_b64 exec, exec, s[0:1]
	s_waitcnt lgkmcnt(0)
	ds_bpermute_b32 v133, v134, v115
	v_cmp_lt_i32_e32 vcc, 0, v204
	s_and_saveexec_b64 s[0:1], vcc
	s_xor_b64 s[0:1], exec, s[0:1]
	s_cbranch_execz .LBB0_648
	v_cmp_eq_u32_e32 vcc, 1, v204
	s_and_saveexec_b64 s[16:17], vcc
	s_cbranch_execz .LBB0_647
	v_mov_b32_e32 v134, v7
	v_mov_b32_e32 v135, v15
	v_mov_b32_e32 v132, v115
	s_waitcnt lgkmcnt(0)
	v_mul_f32_e32 v136, v15, v133
	v_fma_f32 v132, v134, v132, v136
	v_fma_f32 v133, v135, v133, v136
	s_nop 0
	v_mov_b32_e32 v115, v132

;     __device__ __forceinline__ void operator()(const f32x4 (&acc)[2][2][4][2], const Unit& u, int wr, int wc, int fr, int fq) const {
;     ...
;                         if (rope) { const float cs[8] = {c0[0], c0[1], c0[2], c0[3], c1[0], c1[1], c1[2], c1[3]}; const float sn[8] = {s0[0], s0[1], s0[2], s0[3], s1[0], s1[1], s1[2], s1[3]};
; #pragma unroll
;                             for (int j = 0; j < 8; ++j) { const float o = __shfl_xor(v[j], 16); if (fq == 0) v[j] = v[j] * cs[j] - o * sn[j]; else if (fq == 1) v[j] = v[j] * cs[j] + o * sn[j]; } }
.LBB0_648:
	s_andn2_saveexec_b64 s[0:1], s[0:1]
	s_cbranch_execz .LBB0_650
	v_mov_b32_e32 v134, v7
	v_mov_b32_e32 v135, v15
	v_mov_b32_e32 v132, v115
	s_waitcnt lgkmcnt(0)
	v_mul_f32_e32 v136, v15, v133
	v_fma_f32 v132, v134, v132, -v136
	v_fma_f32 v133, v135, v133, -v136
	s_nop 0
	v_mov_b32_e32 v115, v132

; __device__ __forceinline__ float fexp(float x) { return __builtin_amdgcn_exp2f(x * LOG2E); }
; __device__ __forceinline__ float sigm(float x) { return __builtin_amdgcn_rcpf(1.f + fexp(-x)); }
; __device__ __forceinline__ float silu(float x) { return x * sigm(x); }
;     __device__ __forceinline__ void operator()(const f32x4 (&acc)[2][2][4][2], const Unit& u, int wr, int wc, int fr, int fq) const {
;     ...
;                     } else if (reg == PB_QR || reg == PB_G) {
; #pragma unroll
;                         for (int j = 0; j < 8; ++j) v[j] = silu(v[j]);
.LBB0_653:
	s_andn2_b64 vcc, exec, s[0:1]
	s_cbranch_vccnz .LBB0_655
	v_mul_f32_e32 v117, 0xbfb8aa3b, v110
	v_exp_f32_e32 v117, v117
	v_mul_f32_e32 v122, 0xbfb8aa3b, v108
	v_mul_f32_e32 v104, 0xbfb8aa3b, v120
	v_mul_f32_e32 v105, 0xbfb8aa3b, v121
	v_add_f32_e32 v117, 1.0, v117
	v_mul_f32_e32 v106, 0xbfb8aa3b, v118
	v_mul_f32_e32 v107, 0xbfb8aa3b, v119
	v_rcp_f32_e32 v124, v117
	v_mul_f32_e32 v117, 0xbfb8aa3b, v111
	v_exp_f32_e32 v122, v122
	v_mul_f32_e32 v123, 0xbfb8aa3b, v109
	v_exp_f32_e32 v104, v104
	v_exp_f32_e32 v105, v105
	v_exp_f32_e32 v106, v106
	v_exp_f32_e32 v107, v107
	v_exp_f32_e32 v117, v117
	v_exp_f32_e32 v123, v123
	v_add_f32_e32 v122, 1.0, v122
	v_add_f32_e32 v104, 1.0, v104
	v_add_f32_e32 v105, 1.0, v105
	v_add_f32_e32 v106, 1.0, v106
	v_add_f32_e32 v107, 1.0, v107
	v_add_f32_e32 v117, 1.0, v117
	v_rcp_f32_e32 v126, v122
	v_add_f32_e32 v122, 1.0, v123
	v_rcp_f32_e32 v104, v104
	v_rcp_f32_e32 v105, v105
	v_rcp_f32_e32 v106, v106
	v_rcp_f32_e32 v107, v107
	v_rcp_f32_e32 v127, v122
	v_rcp_f32_e32 v125, v117
	v_mul_f32_e32 v128, v120, v104
	v_mul_f32_e32 v129, v121, v105
	v_mul_f32_e32 v122, v118, v106
	v_mul_f32_e32 v123, v119, v107
	v_mul_f32_e32 v126, v108, v126
	v_mul_f32_e32 v127, v109, v127
	v_mul_f32_e32 v124, v110, v124
	v_mul_f32_e32 v125, v111, v125

;     __device__ __forceinline__ void operator()(const f32x4 (&acc)[2][2][4][2], const Unit& u, int wr, int wc, int fr, int fq) const {
;     ...
;                     if (reg <= 1) {
;                         if (rope) { const float cs[8] = {c0[0], c0[1], c0[2], c0[3], c1[0], c1[1], c1[2], c1[3]}; const float sn[8] = {s0[0], s0[1], s0[2], s0[3], s1[0], s1[1], s1[2], s1[3]};
; #pragma unroll
;                             for (int j = 0; j < 8; ++j) { const float o = __shfl_xor(v[j], 16); if (fq == 0) v[j] = v[j] * cs[j] - o * sn[j]; else if (fq == 1) v[j] = v[j] * cs[j] + o * sn[j]; } }
.LBB0_656:
	s_and_b64 vcc, exec, s[10:11]
	s_cbranch_vccnz .LBB0_1323
	v_and_b32_e32 v105, 64, v214
	v_xor_b32_e32 v104, 16, v214
	v_add_u32_e32 v105, 64, v105
	v_cmp_lt_i32_e32 vcc, v104, v105
	s_nop 1
	v_cndmask_b32_e32 v104, v214, v104, vcc
	v_lshlrev_b32_e32 v117, 2, v104
	ds_bpermute_b32 v127, v117, v120
	v_cmp_lt_i32_e32 vcc, 0, v204
	s_and_saveexec_b64 s[0:1], vcc
	s_xor_b64 s[0:1], exec, s[0:1]
	s_cbranch_execz .LBB0_661
	v_cmp_eq_u32_e32 vcc, 1, v204
	v_mov_b32_e32 v107, v109
	v_mov_b32_e32 v106, v108
	v_mov_b32_e32 v125, v111
	v_mov_b32_e32 v124, v110
	v_mov_b32_e32 v123, v119
	v_mov_b32_e32 v122, v118
	v_mov_b32_e32 v105, v121
	v_mov_b32_e32 v104, v120
	s_and_saveexec_b64 s[16:17], vcc
	s_cbranch_execz .LBB0_660
	v_mov_b32_e32 v104, v120
	v_mov_b32_e32 v105, v20
	v_mov_b32_e32 v126, v16
	s_waitcnt lgkmcnt(0)
	v_mul_f32_e32 v104, v104, v126
	v_mul_f32_e32 v105, v105, v127
	v_mov_b32_e32 v107, v109
	v_add_f32_e32 v104, v104, v105
	v_mov_b32_e32 v106, v108
	v_mov_b32_e32 v125, v111
	v_mov_b32_e32 v124, v110
	v_mov_b32_e32 v123, v119
	v_mov_b32_e32 v122, v118
	v_mov_b32_e32 v105, v121

;     __device__ __forceinline__ void operator()(const f32x4 (&acc)[2][2][4][2], const Unit& u, int wr, int wc, int fr, int fq) const {
;     ...
;                         if (rope) { const float cs[8] = {c0[0], c0[1], c0[2], c0[3], c1[0], c1[1], c1[2], c1[3]}; const float sn[8] = {s0[0], s0[1], s0[2], s0[3], s1[0], s1[1], s1[2], s1[3]};
; #pragma unroll
;                             for (int j = 0; j < 8; ++j) { const float o = __shfl_xor(v[j], 16); if (fq == 0) v[j] = v[j] * cs[j] - o * sn[j]; else if (fq == 1) v[j] = v[j] * cs[j] + o * sn[j]; } }
.LBB0_661:
	s_andn2_saveexec_b64 s[0:1], s[0:1]
	s_cbranch_execz .LBB0_663
	v_mov_b32_e32 v104, v120
	v_mov_b32_e32 v105, v20
	v_mov_b32_e32 v126, v16
	s_waitcnt lgkmcnt(0)
	v_mul_f32_e32 v104, v104, v126
	v_mul_f32_e32 v105, v105, v127
	v_mov_b32_e32 v122, v118
	v_sub_f32_e32 v104, v104, v105
	v_mov_b32_e32 v105, v121
	v_mov_b32_e32 v123, v119
	v_mov_b32_e32 v124, v110
	v_mov_b32_e32 v125, v111
	v_mov_b32_e32 v106, v108
	v_mov_b32_e32 v107, v109
.LBB0_663:
	s_or_b64 exec, exec, s[0:1]
	s_waitcnt lgkmcnt(0)
	ds_bpermute_b32 v127, v117, v105
	v_cmp_lt_i32_e32 vcc, 0, v204
	s_and_saveexec_b64 s[0:1], vcc
	s_xor_b64 s[0:1], exec, s[0:1]
	s_cbranch_execz .LBB0_667
	v_cmp_eq_u32_e32 vcc, 1, v204
	s_and_saveexec_b64 s[16:17], vcc
	s_cbranch_execz .LBB0_666
	v_mov_b32_e32 v128, v17
	v_mov_b32_e32 v129, v21
	v_mov_b32_e32 v126, v105
	v_mul_f32_e32 v130, v17, v105
	s_waitcnt lgkmcnt(0)
	v_fma_f32 v126, v128, v126, v130
	v_fma_f32 v127, v129, v127, v130
	s_nop 0
	v_mov_b32_e32 v105, v127

;     __device__ __forceinline__ void operator()(const f32x4 (&acc)[2][2][4][2], const Unit& u, int wr, int wc, int fr, int fq) const {
;     ...
;                         if (rope) { const float cs[8] = {c0[0], c0[1], c0[2], c0[3], c1[0], c1[1], c1[2], c1[3]}; const float sn[8] = {s0[0], s0[1], s0[2], s0[3], s1[0], s1[1], s1[2], s1[3]};
; #pragma unroll
;                             for (int j = 0; j < 8; ++j) { const float o = __shfl_xor(v[j], 16); if (fq == 0) v[j] = v[j] * cs[j] - o * sn[j]; else if (fq == 1) v[j] = v[j] * cs[j] + o * sn[j]; } }
.LBB0_667:
	s_andn2_saveexec_b64 s[0:1], s[0:1]
	s_cbranch_execz .LBB0_669
	v_mov_b32_e32 v128, v17
	v_mov_b32_e32 v129, v21
	v_mov_b32_e32 v126, v105
	v_mul_f32_e32 v130, v17, v105
	s_waitcnt lgkmcnt(0)
	v_fma_f32 v126, -v128, v126, v130
	v_fma_f32 v127, -v129, v127, v130
	s_nop 0
	v_mov_b32_e32 v105, v127
.LBB0_669:
	s_or_b64 exec, exec, s[0:1]
	s_waitcnt lgkmcnt(0)
	ds_bpermute_b32 v127, v117, v122
	v_cmp_lt_i32_e32 vcc, 0, v204
	s_and_saveexec_b64 s[0:1], vcc
	s_xor_b64 s[0:1], exec, s[0:1]
	s_cbranch_execz .LBB0_673
	v_cmp_eq_u32_e32 vcc, 1, v204
	s_and_saveexec_b64 s[16:17], vcc
	s_cbranch_execz .LBB0_672
	v_mov_b32_e32 v128, v18
	v_mov_b32_e32 v129, v22
	v_mov_b32_e32 v126, v122
	s_waitcnt lgkmcnt(0)
	v_mul_f32_e32 v122, v22, v127
	v_fma_f32 v126, v128, v126, v122
	v_fma_f32 v127, v129, v127, v122
	s_nop 0
	v_mov_b32_e32 v122, v126

;     __device__ __forceinline__ void operator()(const f32x4 (&acc)[2][2][4][2], const Unit& u, int wr, int wc, int fr, int fq) const {
;     ...
;                         if (rope) { const float cs[8] = {c0[0], c0[1], c0[2], c0[3], c1[0], c1[1], c1[2], c1[3]}; const float sn[8] = {s0[0], s0[1], s0[2], s0[3], s1[0], s1[1], s1[2], s1[3]};
; #pragma unroll
;                             for (int j = 0; j < 8; ++j) { const float o = __shfl_xor(v[j], 16); if (fq == 0) v[j] = v[j] * cs[j] - o * sn[j]; else if (fq == 1) v[j] = v[j] * cs[j] + o * sn[j]; } }
.LBB0_673:
	s_andn2_saveexec_b64 s[0:1], s[0:1]
	s_cbranch_execz .LBB0_675
	v_mov_b32_e32 v128, v18
	v_mov_b32_e32 v129, v22
	v_mov_b32_e32 v126, v122
	s_waitcnt lgkmcnt(0)
	v_mul_f32_e32 v122, v22, v127
	v_fma_f32 v126, v128, v126, -v122
	v_fma_f32 v127, v129, v127, -v122
	s_nop 0
	v_mov_b32_e32 v122, v126
.LBB0_675:
	s_or_b64 exec, exec, s[0:1]
	s_waitcnt lgkmcnt(0)
	ds_bpermute_b32 v127, v117, v123
	v_cmp_lt_i32_e32 vcc, 0, v204
	s_and_saveexec_b64 s[0:1], vcc
	s_xor_b64 s[0:1], exec, s[0:1]
	s_cbranch_execz .LBB0_679
	v_cmp_eq_u32_e32 vcc, 1, v204
	s_and_saveexec_b64 s[16:17], vcc
	s_cbranch_execz .LBB0_678
	v_mov_b32_e32 v128, v19
	v_mov_b32_e32 v129, v23
	v_mov_b32_e32 v126, v123
	s_waitcnt lgkmcnt(0)
	v_mul_f32_e32 v130, v23, v127
	v_fma_f32 v126, v128, v126, v130
	v_fma_f32 v127, v129, v127, v130
	s_nop 0
	v_mov_b32_e32 v123, v126

;     __device__ __forceinline__ void operator()(const f32x4 (&acc)[2][2][4][2], const Unit& u, int wr, int wc, int fr, int fq) const {
;     ...
;                         if (rope) { const float cs[8] = {c0[0], c0[1], c0[2], c0[3], c1[0], c1[1], c1[2], c1[3]}; const float sn[8] = {s0[0], s0[1], s0[2], s0[3], s1[0], s1[1], s1[2], s1[3]};
; #pragma unroll
;                             for (int j = 0; j < 8; ++j) { const float o = __shfl_xor(v[j], 16); if (fq == 0) v[j] = v[j] * cs[j] - o * sn[j]; else if (fq == 1) v[j] = v[j] * cs[j] + o * sn[j]; } }
.LBB0_679:
	s_andn2_saveexec_b64 s[0:1], s[0:1]
	s_cbranch_execz .LBB0_681
	v_mov_b32_e32 v128, v19
	v_mov_b32_e32 v129, v23
	v_mov_b32_e32 v126, v123
	s_waitcnt lgkmcnt(0)
	v_mul_f32_e32 v130, v23, v127
	v_fma_f32 v126, v128, v126, -v130
	v_fma_f32 v127, v129, v127, -v130
	s_nop 0
	v_mov_b32_e32 v123, v126
.LBB0_681:
	s_or_b64 exec, exec, s[0:1]
	s_waitcnt lgkmcnt(0)
	ds_bpermute_b32 v127, v117, v124
	v_cmp_lt_i32_e32 vcc, 0, v204
	s_and_saveexec_b64 s[0:1], vcc
	s_xor_b64 s[0:1], exec, s[0:1]
	s_cbranch_execz .LBB0_685
	v_cmp_eq_u32_e32 vcc, 1, v204
	s_and_saveexec_b64 s[16:17], vcc
	s_cbranch_execz .LBB0_684
	v_mov_b32_e32 v128, v4
	v_mov_b32_e32 v129, v12
	v_mov_b32_e32 v126, v124
	s_waitcnt lgkmcnt(0)
	v_mul_f32_e32 v124, v12, v127
	v_fma_f32 v126, v128, v126, v124
	v_fma_f32 v127, v129, v127, v124
	s_nop 0
	v_mov_b32_e32 v124, v126

;     __device__ __forceinline__ void operator()(const f32x4 (&acc)[2][2][4][2], const Unit& u, int wr, int wc, int fr, int fq) const {
;     ...
;                         if (rope) { const float cs[8] = {c0[0], c0[1], c0[2], c0[3], c1[0], c1[1], c1[2], c1[3]}; const float sn[8] = {s0[0], s0[1], s0[2], s0[3], s1[0], s1[1], s1[2], s1[3]};
; #pragma unroll
;                             for (int j = 0; j < 8; ++j) { const float o = __shfl_xor(v[j], 16); if (fq == 0) v[j] = v[j] * cs[j] - o * sn[j]; else if (fq == 1) v[j] = v[j] * cs[j] + o * sn[j]; } }
.LBB0_685:
	s_andn2_saveexec_b64 s[0:1], s[0:1]
	s_cbranch_execz .LBB0_687
	v_mov_b32_e32 v128, v4
	v_mov_b32_e32 v129, v12
	v_mov_b32_e32 v126, v124
	s_waitcnt lgkmcnt(0)
	v_mul_f32_e32 v124, v12, v127
	v_fma_f32 v126, v128, v126, -v124
	v_fma_f32 v127, v129, v127, -v124
	s_nop 0
	v_mov_b32_e32 v124, v126
.LBB0_687:
	s_or_b64 exec, exec, s[0:1]
	s_waitcnt lgkmcnt(0)
	ds_bpermute_b32 v127, v117, v125
	v_cmp_lt_i32_e32 vcc, 0, v204
	s_and_saveexec_b64 s[0:1], vcc
	s_xor_b64 s[0:1], exec, s[0:1]
	s_cbranch_execz .LBB0_691
	v_cmp_eq_u32_e32 vcc, 1, v204
	s_and_saveexec_b64 s[16:17], vcc
	s_cbranch_execz .LBB0_690
	v_mov_b32_e32 v128, v5
	v_mov_b32_e32 v129, v13
	v_mov_b32_e32 v126, v125
	s_waitcnt lgkmcnt(0)
	v_mul_f32_e32 v130, v13, v127
	v_fma_f32 v126, v128, v126, v130
	v_fma_f32 v127, v129, v127, v130
	s_nop 0
	v_mov_b32_e32 v125, v126

;     __device__ __forceinline__ void operator()(const f32x4 (&acc)[2][2][4][2], const Unit& u, int wr, int wc, int fr, int fq) const {
;     ...
;                         if (rope) { const float cs[8] = {c0[0], c0[1], c0[2], c0[3], c1[0], c1[1], c1[2], c1[3]}; const float sn[8] = {s0[0], s0[1], s0[2], s0[3], s1[0], s1[1], s1[2], s1[3]};
; #pragma unroll
;                             for (int j = 0; j < 8; ++j) { const float o = __shfl_xor(v[j], 16); if (fq == 0) v[j] = v[j] * cs[j] - o * sn[j]; else if (fq == 1) v[j] = v[j] * cs[j] + o * sn[j]; } }
.LBB0_691:
	s_andn2_saveexec_b64 s[0:1], s[0:1]
	s_cbranch_execz .LBB0_693
	v_mov_b32_e32 v128, v5
	v_mov_b32_e32 v129, v13
	v_mov_b32_e32 v126, v125
	s_waitcnt lgkmcnt(0)
	v_mul_f32_e32 v130, v13, v127
	v_fma_f32 v126, v128, v126, -v130
	v_fma_f32 v127, v129, v127, -v130
	s_nop 0
	v_mov_b32_e32 v125, v126
.LBB0_693:
	s_or_b64 exec, exec, s[0:1]
	s_waitcnt lgkmcnt(0)
	ds_bpermute_b32 v127, v117, v106
	v_cmp_lt_i32_e32 vcc, 0, v204
	s_and_saveexec_b64 s[0:1], vcc
	s_xor_b64 s[0:1], exec, s[0:1]
	s_cbranch_execz .LBB0_697
	v_cmp_eq_u32_e32 vcc, 1, v204
	s_and_saveexec_b64 s[16:17], vcc
	s_cbranch_execz .LBB0_696
	v_mov_b32_e32 v128, v6
	v_mov_b32_e32 v129, v14
	v_mov_b32_e32 v126, v106
	s_waitcnt lgkmcnt(0)
	v_mul_f32_e32 v106, v14, v127
	v_fma_f32 v126, v128, v126, v106
	v_fma_f32 v127, v129, v127, v106
	s_nop 0
	v_mov_b32_e32 v106, v126

;     __device__ __forceinline__ void operator()(const f32x4 (&acc)[2][2][4][2], const Unit& u, int wr, int wc, int fr, int fq) const {
;     ...
;                         if (rope) { const float cs[8] = {c0[0], c0[1], c0[2], c0[3], c1[0], c1[1], c1[2], c1[3]}; const float sn[8] = {s0[0], s0[1], s0[2], s0[3], s1[0], s1[1], s1[2], s1[3]};
; #pragma unroll
;                             for (int j = 0; j < 8; ++j) { const float o = __shfl_xor(v[j], 16); if (fq == 0) v[j] = v[j] * cs[j] - o * sn[j]; else if (fq == 1) v[j] = v[j] * cs[j] + o * sn[j]; } }
.LBB0_697:
	s_andn2_saveexec_b64 s[0:1], s[0:1]
	s_cbranch_execz .LBB0_699
	v_mov_b32_e32 v128, v6
	v_mov_b32_e32 v129, v14
	v_mov_b32_e32 v126, v106
	s_waitcnt lgkmcnt(0)
	v_mul_f32_e32 v106, v14, v127
	v_fma_f32 v126, v128, v126, -v106
	v_fma_f32 v127, v129, v127, -v106
	s_nop 0
	v_mov_b32_e32 v106, v126
.LBB0_699:
	s_or_b64 exec, exec, s[0:1]
	s_waitcnt lgkmcnt(0)
	ds_bpermute_b32 v127, v117, v107
	v_cmp_lt_i32_e32 vcc, 0, v204
	s_and_saveexec_b64 s[0:1], vcc
	s_xor_b64 s[0:1], exec, s[0:1]
	s_cbranch_execz .LBB0_703
	v_cmp_eq_u32_e32 vcc, 1, v204
	s_and_saveexec_b64 s[16:17], vcc
	s_cbranch_execz .LBB0_702
	v_mov_b32_e32 v128, v7
	v_mov_b32_e32 v129, v15
	v_mov_b32_e32 v126, v107
	s_waitcnt lgkmcnt(0)
	v_mul_f32_e32 v130, v15, v127
	v_fma_f32 v126, v128, v126, v130
	v_fma_f32 v127, v129, v127, v130
	s_nop 0
	v_mov_b32_e32 v107, v126

;     __device__ __forceinline__ void operator()(const f32x4 (&acc)[2][2][4][2], const Unit& u, int wr, int wc, int fr, int fq) const {
;     ...
;                         if (rope) { const float cs[8] = {c0[0], c0[1], c0[2], c0[3], c1[0], c1[1], c1[2], c1[3]}; const float sn[8] = {s0[0], s0[1], s0[2], s0[3], s1[0], s1[1], s1[2], s1[3]};
; #pragma unroll
;                             for (int j = 0; j < 8; ++j) { const float o = __shfl_xor(v[j], 16); if (fq == 0) v[j] = v[j] * cs[j] - o * sn[j]; else if (fq == 1) v[j] = v[j] * cs[j] + o * sn[j]; } }
.LBB0_703:
	s_andn2_saveexec_b64 s[0:1], s[0:1]
	s_cbranch_execz .LBB0_705
	v_mov_b32_e32 v128, v7
	v_mov_b32_e32 v129, v15
	v_mov_b32_e32 v126, v107
	s_waitcnt lgkmcnt(0)
	v_mul_f32_e32 v130, v15, v127
	v_fma_f32 v126, v128, v126, -v130
	v_fma_f32 v127, v129, v127, -v130
	s_nop 0
	v_mov_b32_e32 v107, v126

; __device__ __forceinline__ float fexp(float x) { return __builtin_amdgcn_exp2f(x * LOG2E); }
; __device__ __forceinline__ float sigm(float x) { return __builtin_amdgcn_rcpf(1.f + fexp(-x)); }
; __device__ __forceinline__ float silu(float x) { return x * sigm(x); }
;     __device__ __forceinline__ void operator()(const f32x4 (&acc)[2][2][4][2], const Unit& u, int wr, int wc, int fr, int fq) const {
;     ...
;                     } else if (reg == PB_QR || reg == PB_G) {
; #pragma unroll
;                         for (int j = 0; j < 8; ++j) v[j] = silu(v[j]);
.LBB0_708:
	s_andn2_b64 vcc, exec, s[0:1]
	s_cbranch_vccnz .LBB0_710
	v_mul_f32_e32 v108, 0xbfb8aa3b, v102
	v_exp_f32_e32 v108, v108
	v_mul_f32_e32 v109, 0xbfb8aa3b, v100
	v_mul_f32_e32 v96, 0xbfb8aa3b, v106
	v_mul_f32_e32 v97, 0xbfb8aa3b, v107
	v_add_f32_e32 v108, 1.0, v108
	v_mul_f32_e32 v98, 0xbfb8aa3b, v104
	v_mul_f32_e32 v99, 0xbfb8aa3b, v105
	v_rcp_f32_e32 v110, v108
	v_mul_f32_e32 v108, 0xbfb8aa3b, v103
	v_exp_f32_e32 v109, v109
	v_mul_f32_e32 v111, 0xbfb8aa3b, v101
	v_exp_f32_e32 v96, v96
	v_exp_f32_e32 v97, v97
	v_exp_f32_e32 v98, v98
	v_exp_f32_e32 v99, v99
	v_exp_f32_e32 v108, v108
	v_exp_f32_e32 v111, v111
	v_add_f32_e32 v109, 1.0, v109
	v_add_f32_e32 v96, 1.0, v96
	v_add_f32_e32 v97, 1.0, v97
	v_add_f32_e32 v98, 1.0, v98
	v_add_f32_e32 v99, 1.0, v99
	v_add_f32_e32 v108, 1.0, v108
	v_rcp_f32_e32 v116, v109
	v_add_f32_e32 v109, 1.0, v111
	v_rcp_f32_e32 v96, v96
	v_rcp_f32_e32 v97, v97
	v_rcp_f32_e32 v98, v98
	v_rcp_f32_e32 v99, v99
	v_rcp_f32_e32 v117, v109
	v_rcp_f32_e32 v111, v108
	v_mul_f32_e32 v118, v106, v96
	v_mul_f32_e32 v119, v107, v97
	v_mul_f32_e32 v108, v104, v98
	v_mul_f32_e32 v109, v105, v99
	v_mul_f32_e32 v116, v100, v116
	v_mul_f32_e32 v117, v101, v117
	v_mul_f32_e32 v110, v102, v110
	v_mul_f32_e32 v111, v103, v111

;     __device__ __forceinline__ void operator()(const f32x4 (&acc)[2][2][4][2], const Unit& u, int wr, int wc, int fr, int fq) const {
;     ...
;                     if (reg <= 1) {
;                         if (rope) { const float cs[8] = {c0[0], c0[1], c0[2], c0[3], c1[0], c1[1], c1[2], c1[3]}; const float sn[8] = {s0[0], s0[1], s0[2], s0[3], s1[0], s1[1], s1[2], s1[3]};
; #pragma unroll
;                             for (int j = 0; j < 8; ++j) { const float o = __shfl_xor(v[j], 16); if (fq == 0) v[j] = v[j] * cs[j] - o * sn[j]; else if (fq == 1) v[j] = v[j] * cs[j] + o * sn[j]; } }
.LBB0_711:
	s_and_b64 vcc, exec, s[10:11]
	s_cbranch_vccnz .LBB0_1326
	v_and_b32_e32 v97, 64, v214
	v_xor_b32_e32 v96, 16, v214
	v_add_u32_e32 v97, 64, v97
	v_cmp_lt_i32_e32 vcc, v96, v97
	s_nop 1
	v_cndmask_b32_e32 v96, v214, v96, vcc
	v_lshlrev_b32_e32 v118, 2, v96
	ds_bpermute_b32 v117, v118, v106
	v_cmp_lt_i32_e32 vcc, 0, v204
	s_and_saveexec_b64 s[0:1], vcc
	s_xor_b64 s[0:1], exec, s[0:1]
	s_cbranch_execz .LBB0_716
	v_cmp_eq_u32_e32 vcc, 1, v204
	v_mov_b32_e32 v99, v101
	v_mov_b32_e32 v98, v100
	v_mov_b32_e32 v111, v103
	v_mov_b32_e32 v110, v102
	v_mov_b32_e32 v109, v105
	v_mov_b32_e32 v108, v104
	v_mov_b32_e32 v97, v107
	v_mov_b32_e32 v96, v106
	s_and_saveexec_b64 s[16:17], vcc
	s_cbranch_execz .LBB0_715
	v_mov_b32_e32 v96, v106
	v_mov_b32_e32 v97, v20
	v_mov_b32_e32 v116, v16
	s_waitcnt lgkmcnt(0)
	v_mul_f32_e32 v96, v96, v116
	v_mul_f32_e32 v97, v97, v117
	v_mov_b32_e32 v99, v101
	v_add_f32_e32 v96, v96, v97
	v_mov_b32_e32 v98, v100
	v_mov_b32_e32 v111, v103
	v_mov_b32_e32 v110, v102
	v_mov_b32_e32 v109, v105
	v_mov_b32_e32 v108, v104
	v_mov_b32_e32 v97, v107

;     __device__ __forceinline__ void operator()(const f32x4 (&acc)[2][2][4][2], const Unit& u, int wr, int wc, int fr, int fq) const {
;     ...
;                         if (rope) { const float cs[8] = {c0[0], c0[1], c0[2], c0[3], c1[0], c1[1], c1[2], c1[3]}; const float sn[8] = {s0[0], s0[1], s0[2], s0[3], s1[0], s1[1], s1[2], s1[3]};
; #pragma unroll
;                             for (int j = 0; j < 8; ++j) { const float o = __shfl_xor(v[j], 16); if (fq == 0) v[j] = v[j] * cs[j] - o * sn[j]; else if (fq == 1) v[j] = v[j] * cs[j] + o * sn[j]; } }
.LBB0_716:
	s_andn2_saveexec_b64 s[0:1], s[0:1]
	s_cbranch_execz .LBB0_718
	v_mov_b32_e32 v96, v106
	v_mov_b32_e32 v97, v20
	v_mov_b32_e32 v116, v16
	s_waitcnt lgkmcnt(0)
	v_mul_f32_e32 v96, v96, v116
	v_mul_f32_e32 v97, v97, v117
	v_mov_b32_e32 v108, v104
	v_sub_f32_e32 v96, v96, v97
	v_mov_b32_e32 v97, v107
	v_mov_b32_e32 v109, v105
	v_mov_b32_e32 v110, v102
	v_mov_b32_e32 v111, v103
	v_mov_b32_e32 v98, v100
	v_mov_b32_e32 v99, v101
.LBB0_718:
	s_or_b64 exec, exec, s[0:1]
	s_waitcnt lgkmcnt(0)
	ds_bpermute_b32 v117, v118, v97
	v_cmp_lt_i32_e32 vcc, 0, v204
	s_and_saveexec_b64 s[0:1], vcc
	s_xor_b64 s[0:1], exec, s[0:1]
	s_cbranch_execz .LBB0_722
	v_cmp_eq_u32_e32 vcc, 1, v204
	s_and_saveexec_b64 s[16:17], vcc
	s_cbranch_execz .LBB0_721
	v_mov_b32_e32 v120, v17
	v_mov_b32_e32 v121, v21
	v_mov_b32_e32 v116, v97
	v_mul_f32_e32 v122, v17, v97
	s_waitcnt lgkmcnt(0)
	v_fma_f32 v116, v120, v116, v122
	v_fma_f32 v117, v121, v117, v122
	s_nop 0
	v_mov_b32_e32 v97, v117

;     __device__ __forceinline__ void operator()(const f32x4 (&acc)[2][2][4][2], const Unit& u, int wr, int wc, int fr, int fq) const {
;     ...
;                         if (rope) { const float cs[8] = {c0[0], c0[1], c0[2], c0[3], c1[0], c1[1], c1[2], c1[3]}; const float sn[8] = {s0[0], s0[1], s0[2], s0[3], s1[0], s1[1], s1[2], s1[3]};
; #pragma unroll
;                             for (int j = 0; j < 8; ++j) { const float o = __shfl_xor(v[j], 16); if (fq == 0) v[j] = v[j] * cs[j] - o * sn[j]; else if (fq == 1) v[j] = v[j] * cs[j] + o * sn[j]; } }
.LBB0_722:
	s_andn2_saveexec_b64 s[0:1], s[0:1]
	s_cbranch_execz .LBB0_724
	v_mov_b32_e32 v120, v17
	v_mov_b32_e32 v121, v21
	v_mov_b32_e32 v116, v97
	v_mul_f32_e32 v122, v17, v97
	s_waitcnt lgkmcnt(0)
	v_fma_f32 v116, -v120, v116, v122
	v_fma_f32 v117, -v121, v117, v122
	s_nop 0
	v_mov_b32_e32 v97, v117
.LBB0_724:
	s_or_b64 exec, exec, s[0:1]
	s_waitcnt lgkmcnt(0)
	ds_bpermute_b32 v117, v118, v108
	v_cmp_lt_i32_e32 vcc, 0, v204
	s_and_saveexec_b64 s[0:1], vcc
	s_xor_b64 s[0:1], exec, s[0:1]
	s_cbranch_execz .LBB0_728
	v_cmp_eq_u32_e32 vcc, 1, v204
	s_and_saveexec_b64 s[16:17], vcc
	s_cbranch_execz .LBB0_727
	v_mov_b32_e32 v120, v18
	v_mov_b32_e32 v121, v22
	v_mov_b32_e32 v116, v108
	s_waitcnt lgkmcnt(0)
	v_mul_f32_e32 v108, v22, v117
	v_fma_f32 v116, v120, v116, v108
	v_fma_f32 v117, v121, v117, v108
	s_nop 0
	v_mov_b32_e32 v108, v116

;     __device__ __forceinline__ void operator()(const f32x4 (&acc)[2][2][4][2], const Unit& u, int wr, int wc, int fr, int fq) const {
;     ...
;                         if (rope) { const float cs[8] = {c0[0], c0[1], c0[2], c0[3], c1[0], c1[1], c1[2], c1[3]}; const float sn[8] = {s0[0], s0[1], s0[2], s0[3], s1[0], s1[1], s1[2], s1[3]};
; #pragma unroll
;                             for (int j = 0; j < 8; ++j) { const float o = __shfl_xor(v[j], 16); if (fq == 0) v[j] = v[j] * cs[j] - o * sn[j]; else if (fq == 1) v[j] = v[j] * cs[j] + o * sn[j]; } }
.LBB0_728:
	s_andn2_saveexec_b64 s[0:1], s[0:1]
	s_cbranch_execz .LBB0_730
	v_mov_b32_e32 v120, v18
	v_mov_b32_e32 v121, v22
	v_mov_b32_e32 v116, v108
	s_waitcnt lgkmcnt(0)
	v_mul_f32_e32 v108, v22, v117
	v_fma_f32 v116, v120, v116, -v108
	v_fma_f32 v117, v121, v117, -v108
	s_nop 0
	v_mov_b32_e32 v108, v116
.LBB0_730:
	s_or_b64 exec, exec, s[0:1]
	s_waitcnt lgkmcnt(0)
	ds_bpermute_b32 v117, v118, v109
	v_cmp_lt_i32_e32 vcc, 0, v204
	s_and_saveexec_b64 s[0:1], vcc
	s_xor_b64 s[0:1], exec, s[0:1]
	s_cbranch_execz .LBB0_734
	v_cmp_eq_u32_e32 vcc, 1, v204
	s_and_saveexec_b64 s[16:17], vcc
	s_cbranch_execz .LBB0_733
	v_mov_b32_e32 v120, v19
	v_mov_b32_e32 v121, v23
	v_mov_b32_e32 v116, v109
	s_waitcnt lgkmcnt(0)
	v_mul_f32_e32 v122, v23, v117
	v_fma_f32 v116, v120, v116, v122
	v_fma_f32 v117, v121, v117, v122
	s_nop 0
	v_mov_b32_e32 v109, v116

;     __device__ __forceinline__ void operator()(const f32x4 (&acc)[2][2][4][2], const Unit& u, int wr, int wc, int fr, int fq) const {
;     ...
;                         if (rope) { const float cs[8] = {c0[0], c0[1], c0[2], c0[3], c1[0], c1[1], c1[2], c1[3]}; const float sn[8] = {s0[0], s0[1], s0[2], s0[3], s1[0], s1[1], s1[2], s1[3]};
; #pragma unroll
;                             for (int j = 0; j < 8; ++j) { const float o = __shfl_xor(v[j], 16); if (fq == 0) v[j] = v[j] * cs[j] - o * sn[j]; else if (fq == 1) v[j] = v[j] * cs[j] + o * sn[j]; } }
.LBB0_734:
	s_andn2_saveexec_b64 s[0:1], s[0:1]
	s_cbranch_execz .LBB0_736
	v_mov_b32_e32 v120, v19
	v_mov_b32_e32 v121, v23
	v_mov_b32_e32 v116, v109
	s_waitcnt lgkmcnt(0)
	v_mul_f32_e32 v122, v23, v117
	v_fma_f32 v116, v120, v116, -v122
	v_fma_f32 v117, v121, v117, -v122
	s_nop 0
	v_mov_b32_e32 v109, v116
.LBB0_736:
	s_or_b64 exec, exec, s[0:1]
	s_waitcnt lgkmcnt(0)
	ds_bpermute_b32 v117, v118, v110
	v_cmp_lt_i32_e32 vcc, 0, v204
	s_and_saveexec_b64 s[0:1], vcc
	s_xor_b64 s[0:1], exec, s[0:1]
	s_cbranch_execz .LBB0_740
	v_cmp_eq_u32_e32 vcc, 1, v204
	s_and_saveexec_b64 s[16:17], vcc
	s_cbranch_execz .LBB0_739
	v_mov_b32_e32 v120, v4
	v_mov_b32_e32 v121, v12
	v_mov_b32_e32 v116, v110
	s_waitcnt lgkmcnt(0)
	v_mul_f32_e32 v110, v12, v117
	v_fma_f32 v116, v120, v116, v110
	v_fma_f32 v117, v121, v117, v110
	s_nop 0
	v_mov_b32_e32 v110, v116

;     __device__ __forceinline__ void operator()(const f32x4 (&acc)[2][2][4][2], const Unit& u, int wr, int wc, int fr, int fq) const {
;     ...
;                         if (rope) { const float cs[8] = {c0[0], c0[1], c0[2], c0[3], c1[0], c1[1], c1[2], c1[3]}; const float sn[8] = {s0[0], s0[1], s0[2], s0[3], s1[0], s1[1], s1[2], s1[3]};
; #pragma unroll
;                             for (int j = 0; j < 8; ++j) { const float o = __shfl_xor(v[j], 16); if (fq == 0) v[j] = v[j] * cs[j] - o * sn[j]; else if (fq == 1) v[j] = v[j] * cs[j] + o * sn[j]; } }
.LBB0_740:
	s_andn2_saveexec_b64 s[0:1], s[0:1]
	s_cbranch_execz .LBB0_742
	v_mov_b32_e32 v120, v4
	v_mov_b32_e32 v121, v12
	v_mov_b32_e32 v116, v110
	s_waitcnt lgkmcnt(0)
	v_mul_f32_e32 v110, v12, v117
	v_fma_f32 v116, v120, v116, -v110
	v_fma_f32 v117, v121, v117, -v110
	s_nop 0
	v_mov_b32_e32 v110, v116
.LBB0_742:
	s_or_b64 exec, exec, s[0:1]
	s_waitcnt lgkmcnt(0)
	ds_bpermute_b32 v117, v118, v111
	v_cmp_lt_i32_e32 vcc, 0, v204
	s_and_saveexec_b64 s[0:1], vcc
	s_xor_b64 s[0:1], exec, s[0:1]
	s_cbranch_execz .LBB0_746
	v_cmp_eq_u32_e32 vcc, 1, v204
	s_and_saveexec_b64 s[16:17], vcc
	s_cbranch_execz .LBB0_745
	v_mov_b32_e32 v120, v5
	v_mov_b32_e32 v121, v13
	v_mov_b32_e32 v116, v111
	s_waitcnt lgkmcnt(0)
	v_mul_f32_e32 v122, v13, v117
	v_fma_f32 v116, v120, v116, v122
	v_fma_f32 v117, v121, v117, v122
	s_nop 0
	v_mov_b32_e32 v111, v116

;     __device__ __forceinline__ void operator()(const f32x4 (&acc)[2][2][4][2], const Unit& u, int wr, int wc, int fr, int fq) const {
;     ...
;                         if (rope) { const float cs[8] = {c0[0], c0[1], c0[2], c0[3], c1[0], c1[1], c1[2], c1[3]}; const float sn[8] = {s0[0], s0[1], s0[2], s0[3], s1[0], s1[1], s1[2], s1[3]};
; #pragma unroll
;                             for (int j = 0; j < 8; ++j) { const float o = __shfl_xor(v[j], 16); if (fq == 0) v[j] = v[j] * cs[j] - o * sn[j]; else if (fq == 1) v[j] = v[j] * cs[j] + o * sn[j]; } }
.LBB0_746:
	s_andn2_saveexec_b64 s[0:1], s[0:1]
	s_cbranch_execz .LBB0_748
	v_mov_b32_e32 v120, v5
	v_mov_b32_e32 v121, v13
	v_mov_b32_e32 v116, v111
	s_waitcnt lgkmcnt(0)
	v_mul_f32_e32 v122, v13, v117
	v_fma_f32 v116, v120, v116, -v122
	v_fma_f32 v117, v121, v117, -v122
	s_nop 0
	v_mov_b32_e32 v111, v116
.LBB0_748:
	s_or_b64 exec, exec, s[0:1]
	s_waitcnt lgkmcnt(0)
	ds_bpermute_b32 v117, v118, v98
	v_cmp_lt_i32_e32 vcc, 0, v204
	s_and_saveexec_b64 s[0:1], vcc
	s_xor_b64 s[0:1], exec, s[0:1]
	s_cbranch_execz .LBB0_752
	v_cmp_eq_u32_e32 vcc, 1, v204
	s_and_saveexec_b64 s[16:17], vcc
	s_cbranch_execz .LBB0_751
	v_mov_b32_e32 v120, v6
	v_mov_b32_e32 v121, v14
	v_mov_b32_e32 v116, v98
	s_waitcnt lgkmcnt(0)
	v_mul_f32_e32 v98, v14, v117
	v_fma_f32 v116, v120, v116, v98
	v_fma_f32 v117, v121, v117, v98
	s_nop 0
	v_mov_b32_e32 v98, v116

;     __device__ __forceinline__ void operator()(const f32x4 (&acc)[2][2][4][2], const Unit& u, int wr, int wc, int fr, int fq) const {
;     ...
;                         if (rope) { const float cs[8] = {c0[0], c0[1], c0[2], c0[3], c1[0], c1[1], c1[2], c1[3]}; const float sn[8] = {s0[0], s0[1], s0[2], s0[3], s1[0], s1[1], s1[2], s1[3]};
; #pragma unroll
;                             for (int j = 0; j < 8; ++j) { const float o = __shfl_xor(v[j], 16); if (fq == 0) v[j] = v[j] * cs[j] - o * sn[j]; else if (fq == 1) v[j] = v[j] * cs[j] + o * sn[j]; } }
.LBB0_752:
	s_andn2_saveexec_b64 s[0:1], s[0:1]
	s_cbranch_execz .LBB0_754
	v_mov_b32_e32 v120, v6
	v_mov_b32_e32 v121, v14
	v_mov_b32_e32 v116, v98
	s_waitcnt lgkmcnt(0)
	v_mul_f32_e32 v98, v14, v117
	v_fma_f32 v116, v120, v116, -v98
	v_fma_f32 v117, v121, v117, -v98
	s_nop 0
	v_mov_b32_e32 v98, v116
.LBB0_754:
	s_or_b64 exec, exec, s[0:1]
	s_waitcnt lgkmcnt(0)
	ds_bpermute_b32 v117, v118, v99
	v_cmp_lt_i32_e32 vcc, 0, v204
	s_and_saveexec_b64 s[0:1], vcc
	s_xor_b64 s[0:1], exec, s[0:1]
	s_cbranch_execz .LBB0_758
	v_cmp_eq_u32_e32 vcc, 1, v204
	s_and_saveexec_b64 s[16:17], vcc
	s_cbranch_execz .LBB0_757
	v_mov_b32_e32 v118, v7
	v_mov_b32_e32 v119, v15
	v_mov_b32_e32 v116, v99
	s_waitcnt lgkmcnt(0)
	v_mul_f32_e32 v120, v15, v117
	v_fma_f32 v116, v118, v116, v120
	v_fma_f32 v117, v119, v117, v120
	s_nop 0
	v_mov_b32_e32 v99, v116

;     __device__ __forceinline__ void operator()(const f32x4 (&acc)[2][2][4][2], const Unit& u, int wr, int wc, int fr, int fq) const {
;     ...
;                         if (rope) { const float cs[8] = {c0[0], c0[1], c0[2], c0[3], c1[0], c1[1], c1[2], c1[3]}; const float sn[8] = {s0[0], s0[1], s0[2], s0[3], s1[0], s1[1], s1[2], s1[3]};
; #pragma unroll
;                             for (int j = 0; j < 8; ++j) { const float o = __shfl_xor(v[j], 16); if (fq == 0) v[j] = v[j] * cs[j] - o * sn[j]; else if (fq == 1) v[j] = v[j] * cs[j] + o * sn[j]; } }
.LBB0_758:
	s_andn2_saveexec_b64 s[0:1], s[0:1]
	s_cbranch_execz .LBB0_760
	v_mov_b32_e32 v118, v7
	v_mov_b32_e32 v119, v15
	v_mov_b32_e32 v116, v99
	s_waitcnt lgkmcnt(0)
	v_mul_f32_e32 v120, v15, v117
	v_fma_f32 v116, v118, v116, -v120
	v_fma_f32 v117, v119, v117, -v120
	s_nop 0
	v_mov_b32_e32 v99, v116

; __device__ __forceinline__ float fexp(float x) { return __builtin_amdgcn_exp2f(x * LOG2E); }
; __device__ __forceinline__ float sigm(float x) { return __builtin_amdgcn_rcpf(1.f + fexp(-x)); }
; __device__ __forceinline__ float silu(float x) { return x * sigm(x); }
;     __device__ __forceinline__ void operator()(const f32x4 (&acc)[2][2][4][2], const Unit& u, int wr, int wc, int fr, int fq) const {
;     ...
;                     } else if (reg == PB_QR || reg == PB_G) {
; #pragma unroll
;                         for (int j = 0; j < 8; ++j) v[j] = silu(v[j]);
.LBB0_763:
	s_andn2_b64 vcc, exec, s[0:1]
	s_cbranch_vccnz .LBB0_765
	v_mul_f32_e32 v101, 0xbfb8aa3b, v94
	v_exp_f32_e32 v101, v101
	v_mul_f32_e32 v106, 0xbfb8aa3b, v92
	v_mul_f32_e32 v88, 0xbfb8aa3b, v104
	v_mul_f32_e32 v89, 0xbfb8aa3b, v105
	v_add_f32_e32 v101, 1.0, v101
	v_mul_f32_e32 v90, 0xbfb8aa3b, v102
	v_mul_f32_e32 v91, 0xbfb8aa3b, v103
	v_rcp_f32_e32 v108, v101
	v_mul_f32_e32 v101, 0xbfb8aa3b, v95
	v_exp_f32_e32 v106, v106
	v_mul_f32_e32 v107, 0xbfb8aa3b, v93
	v_exp_f32_e32 v88, v88
	v_exp_f32_e32 v89, v89
	v_exp_f32_e32 v90, v90
	v_exp_f32_e32 v91, v91
	v_exp_f32_e32 v101, v101
	v_exp_f32_e32 v107, v107
	v_add_f32_e32 v106, 1.0, v106
	v_add_f32_e32 v88, 1.0, v88
	v_add_f32_e32 v89, 1.0, v89
	v_add_f32_e32 v90, 1.0, v90
	v_add_f32_e32 v91, 1.0, v91
	v_add_f32_e32 v101, 1.0, v101
	v_rcp_f32_e32 v110, v106
	v_add_f32_e32 v106, 1.0, v107
	v_rcp_f32_e32 v88, v88
	v_rcp_f32_e32 v89, v89
	v_rcp_f32_e32 v90, v90
	v_rcp_f32_e32 v91, v91
	v_rcp_f32_e32 v111, v106
	v_rcp_f32_e32 v109, v101
	v_mul_f32_e32 v112, v104, v88
	v_mul_f32_e32 v113, v105, v89
	v_mul_f32_e32 v106, v102, v90
	v_mul_f32_e32 v107, v103, v91
	v_mul_f32_e32 v110, v92, v110
	v_mul_f32_e32 v111, v93, v111
	v_mul_f32_e32 v108, v94, v108
	v_mul_f32_e32 v109, v95, v109

;     __device__ __forceinline__ void operator()(const f32x4 (&acc)[2][2][4][2], const Unit& u, int wr, int wc, int fr, int fq) const {
;     ...
;                     if (reg <= 1) {
;                         if (rope) { const float cs[8] = {c0[0], c0[1], c0[2], c0[3], c1[0], c1[1], c1[2], c1[3]}; const float sn[8] = {s0[0], s0[1], s0[2], s0[3], s1[0], s1[1], s1[2], s1[3]};
; #pragma unroll
;                             for (int j = 0; j < 8; ++j) { const float o = __shfl_xor(v[j], 16); if (fq == 0) v[j] = v[j] * cs[j] - o * sn[j]; else if (fq == 1) v[j] = v[j] * cs[j] + o * sn[j]; } }
.LBB0_766:
	s_and_b64 vcc, exec, s[10:11]
	s_cbranch_vccnz .LBB0_1329
	v_and_b32_e32 v89, 64, v214
	v_xor_b32_e32 v88, 16, v214
	v_add_u32_e32 v89, 64, v89
	v_cmp_lt_i32_e32 vcc, v88, v89
	s_nop 1
	v_cndmask_b32_e32 v88, v214, v88, vcc
	v_lshlrev_b32_e32 v101, 2, v88
	ds_bpermute_b32 v111, v101, v104
	v_cmp_lt_i32_e32 vcc, 0, v204
	s_and_saveexec_b64 s[0:1], vcc
	s_xor_b64 s[0:1], exec, s[0:1]
	s_cbranch_execz .LBB0_771
	v_cmp_eq_u32_e32 vcc, 1, v204
	v_mov_b32_e32 v91, v93
	v_mov_b32_e32 v90, v92
	v_mov_b32_e32 v109, v95
	v_mov_b32_e32 v108, v94
	v_mov_b32_e32 v107, v103
	v_mov_b32_e32 v106, v102
	v_mov_b32_e32 v89, v105
	v_mov_b32_e32 v88, v104
	s_and_saveexec_b64 s[16:17], vcc
	s_cbranch_execz .LBB0_770
	v_mov_b32_e32 v88, v104
	v_mov_b32_e32 v89, v20
	v_mov_b32_e32 v110, v16
	s_waitcnt lgkmcnt(0)
	v_mul_f32_e32 v88, v88, v110
	v_mul_f32_e32 v89, v89, v111
	v_mov_b32_e32 v91, v93
	v_add_f32_e32 v88, v88, v89
	v_mov_b32_e32 v90, v92
	v_mov_b32_e32 v109, v95
	v_mov_b32_e32 v108, v94
	v_mov_b32_e32 v107, v103
	v_mov_b32_e32 v106, v102
	v_mov_b32_e32 v89, v105

;     __device__ __forceinline__ void operator()(const f32x4 (&acc)[2][2][4][2], const Unit& u, int wr, int wc, int fr, int fq) const {
;     ...
;                         if (rope) { const float cs[8] = {c0[0], c0[1], c0[2], c0[3], c1[0], c1[1], c1[2], c1[3]}; const float sn[8] = {s0[0], s0[1], s0[2], s0[3], s1[0], s1[1], s1[2], s1[3]};
; #pragma unroll
;                             for (int j = 0; j < 8; ++j) { const float o = __shfl_xor(v[j], 16); if (fq == 0) v[j] = v[j] * cs[j] - o * sn[j]; else if (fq == 1) v[j] = v[j] * cs[j] + o * sn[j]; } }
.LBB0_771:
	s_andn2_saveexec_b64 s[0:1], s[0:1]
	s_cbranch_execz .LBB0_773
	v_mov_b32_e32 v88, v104
	v_mov_b32_e32 v89, v20
	v_mov_b32_e32 v110, v16
	s_waitcnt lgkmcnt(0)
	v_mul_f32_e32 v88, v88, v110
	v_mul_f32_e32 v89, v89, v111
	v_mov_b32_e32 v106, v102
	v_sub_f32_e32 v88, v88, v89
	v_mov_b32_e32 v89, v105
	v_mov_b32_e32 v107, v103
	v_mov_b32_e32 v108, v94
	v_mov_b32_e32 v109, v95
	v_mov_b32_e32 v90, v92
	v_mov_b32_e32 v91, v93
.LBB0_773:
	s_or_b64 exec, exec, s[0:1]
	s_waitcnt lgkmcnt(0)
	ds_bpermute_b32 v111, v101, v89
	v_cmp_lt_i32_e32 vcc, 0, v204
	s_and_saveexec_b64 s[0:1], vcc
	s_xor_b64 s[0:1], exec, s[0:1]
	s_cbranch_execz .LBB0_777
	v_cmp_eq_u32_e32 vcc, 1, v204
	s_and_saveexec_b64 s[16:17], vcc
	s_cbranch_execz .LBB0_776
	v_mov_b32_e32 v112, v17
	v_mov_b32_e32 v113, v21
	v_mov_b32_e32 v110, v89
	v_mul_f32_e32 v114, v17, v89
	s_waitcnt lgkmcnt(0)
	v_fma_f32 v110, v112, v110, v114
	v_fma_f32 v111, v113, v111, v114
	s_nop 0
	v_mov_b32_e32 v89, v111

;     __device__ __forceinline__ void operator()(const f32x4 (&acc)[2][2][4][2], const Unit& u, int wr, int wc, int fr, int fq) const {
;     ...
;                         if (rope) { const float cs[8] = {c0[0], c0[1], c0[2], c0[3], c1[0], c1[1], c1[2], c1[3]}; const float sn[8] = {s0[0], s0[1], s0[2], s0[3], s1[0], s1[1], s1[2], s1[3]};
; #pragma unroll
;                             for (int j = 0; j < 8; ++j) { const float o = __shfl_xor(v[j], 16); if (fq == 0) v[j] = v[j] * cs[j] - o * sn[j]; else if (fq == 1) v[j] = v[j] * cs[j] + o * sn[j]; } }
.LBB0_777:
	s_andn2_saveexec_b64 s[0:1], s[0:1]
	s_cbranch_execz .LBB0_779
	v_mov_b32_e32 v112, v17
	v_mov_b32_e32 v113, v21
	v_mov_b32_e32 v110, v89
	v_mul_f32_e32 v114, v17, v89
	s_waitcnt lgkmcnt(0)
	v_fma_f32 v110, -v112, v110, v114
	v_fma_f32 v111, -v113, v111, v114
	s_nop 0
	v_mov_b32_e32 v89, v111
.LBB0_779:
	s_or_b64 exec, exec, s[0:1]
	s_waitcnt lgkmcnt(0)
	ds_bpermute_b32 v111, v101, v106
	v_cmp_lt_i32_e32 vcc, 0, v204
	s_and_saveexec_b64 s[0:1], vcc
	s_xor_b64 s[0:1], exec, s[0:1]
	s_cbranch_execz .LBB0_783
	v_cmp_eq_u32_e32 vcc, 1, v204
	s_and_saveexec_b64 s[16:17], vcc
	s_cbranch_execz .LBB0_782
	v_mov_b32_e32 v112, v18
	v_mov_b32_e32 v113, v22
	v_mov_b32_e32 v110, v106
	s_waitcnt lgkmcnt(0)
	v_mul_f32_e32 v106, v22, v111
	v_fma_f32 v110, v112, v110, v106
	v_fma_f32 v111, v113, v111, v106
	s_nop 0
	v_mov_b32_e32 v106, v110

;     __device__ __forceinline__ void operator()(const f32x4 (&acc)[2][2][4][2], const Unit& u, int wr, int wc, int fr, int fq) const {
;     ...
;                         if (rope) { const float cs[8] = {c0[0], c0[1], c0[2], c0[3], c1[0], c1[1], c1[2], c1[3]}; const float sn[8] = {s0[0], s0[1], s0[2], s0[3], s1[0], s1[1], s1[2], s1[3]};
; #pragma unroll
;                             for (int j = 0; j < 8; ++j) { const float o = __shfl_xor(v[j], 16); if (fq == 0) v[j] = v[j] * cs[j] - o * sn[j]; else if (fq == 1) v[j] = v[j] * cs[j] + o * sn[j]; } }
.LBB0_783:
	s_andn2_saveexec_b64 s[0:1], s[0:1]
	s_cbranch_execz .LBB0_785
	v_mov_b32_e32 v112, v18
	v_mov_b32_e32 v113, v22
	v_mov_b32_e32 v110, v106
	s_waitcnt lgkmcnt(0)
	v_mul_f32_e32 v106, v22, v111
	v_fma_f32 v110, v112, v110, -v106
	v_fma_f32 v111, v113, v111, -v106
	s_nop 0
	v_mov_b32_e32 v106, v110
.LBB0_785:
	s_or_b64 exec, exec, s[0:1]
	s_waitcnt lgkmcnt(0)
	ds_bpermute_b32 v111, v101, v107
	v_cmp_lt_i32_e32 vcc, 0, v204
	s_and_saveexec_b64 s[0:1], vcc
	s_xor_b64 s[0:1], exec, s[0:1]
	s_cbranch_execz .LBB0_789
	v_cmp_eq_u32_e32 vcc, 1, v204
	s_and_saveexec_b64 s[16:17], vcc
	s_cbranch_execz .LBB0_788
	v_mov_b32_e32 v112, v19
	v_mov_b32_e32 v113, v23
	v_mov_b32_e32 v110, v107
	s_waitcnt lgkmcnt(0)
	v_mul_f32_e32 v114, v23, v111
	v_fma_f32 v110, v112, v110, v114
	v_fma_f32 v111, v113, v111, v114
	s_nop 0
	v_mov_b32_e32 v107, v110

;     __device__ __forceinline__ void operator()(const f32x4 (&acc)[2][2][4][2], const Unit& u, int wr, int wc, int fr, int fq) const {
;     ...
;                         if (rope) { const float cs[8] = {c0[0], c0[1], c0[2], c0[3], c1[0], c1[1], c1[2], c1[3]}; const float sn[8] = {s0[0], s0[1], s0[2], s0[3], s1[0], s1[1], s1[2], s1[3]};
; #pragma unroll
;                             for (int j = 0; j < 8; ++j) { const float o = __shfl_xor(v[j], 16); if (fq == 0) v[j] = v[j] * cs[j] - o * sn[j]; else if (fq == 1) v[j] = v[j] * cs[j] + o * sn[j]; } }
.LBB0_789:
	s_andn2_saveexec_b64 s[0:1], s[0:1]
	s_cbranch_execz .LBB0_791
	v_mov_b32_e32 v112, v19
	v_mov_b32_e32 v113, v23
	v_mov_b32_e32 v110, v107
	s_waitcnt lgkmcnt(0)
	v_mul_f32_e32 v114, v23, v111
	v_fma_f32 v110, v112, v110, -v114
	v_fma_f32 v111, v113, v111, -v114
	s_nop 0
	v_mov_b32_e32 v107, v110
.LBB0_791:
	s_or_b64 exec, exec, s[0:1]
	s_waitcnt lgkmcnt(0)
	ds_bpermute_b32 v111, v101, v108
	v_cmp_lt_i32_e32 vcc, 0, v204
	s_and_saveexec_b64 s[0:1], vcc
	s_xor_b64 s[0:1], exec, s[0:1]
	s_cbranch_execz .LBB0_795
	v_cmp_eq_u32_e32 vcc, 1, v204
	s_and_saveexec_b64 s[16:17], vcc
	s_cbranch_execz .LBB0_794
	v_mov_b32_e32 v112, v4
	v_mov_b32_e32 v113, v12
	v_mov_b32_e32 v110, v108
	s_waitcnt lgkmcnt(0)
	v_mul_f32_e32 v108, v12, v111
	v_fma_f32 v110, v112, v110, v108
	v_fma_f32 v111, v113, v111, v108
	s_nop 0
	v_mov_b32_e32 v108, v110

;     __device__ __forceinline__ void operator()(const f32x4 (&acc)[2][2][4][2], const Unit& u, int wr, int wc, int fr, int fq) const {
;     ...
;                         if (rope) { const float cs[8] = {c0[0], c0[1], c0[2], c0[3], c1[0], c1[1], c1[2], c1[3]}; const float sn[8] = {s0[0], s0[1], s0[2], s0[3], s1[0], s1[1], s1[2], s1[3]};
; #pragma unroll
;                             for (int j = 0; j < 8; ++j) { const float o = __shfl_xor(v[j], 16); if (fq == 0) v[j] = v[j] * cs[j] - o * sn[j]; else if (fq == 1) v[j] = v[j] * cs[j] + o * sn[j]; } }
.LBB0_795:
	s_andn2_saveexec_b64 s[0:1], s[0:1]
	s_cbranch_execz .LBB0_797
	v_mov_b32_e32 v112, v4
	v_mov_b32_e32 v113, v12
	v_mov_b32_e32 v110, v108
	s_waitcnt lgkmcnt(0)
	v_mul_f32_e32 v108, v12, v111
	v_fma_f32 v110, v112, v110, -v108
	v_fma_f32 v111, v113, v111, -v108
	s_nop 0
	v_mov_b32_e32 v108, v110
.LBB0_797:
	s_or_b64 exec, exec, s[0:1]
	s_waitcnt lgkmcnt(0)
	ds_bpermute_b32 v111, v101, v109
	v_cmp_lt_i32_e32 vcc, 0, v204
	s_and_saveexec_b64 s[0:1], vcc
	s_xor_b64 s[0:1], exec, s[0:1]
	s_cbranch_execz .LBB0_801
	v_cmp_eq_u32_e32 vcc, 1, v204
	s_and_saveexec_b64 s[16:17], vcc
	s_cbranch_execz .LBB0_800
	v_mov_b32_e32 v112, v5
	v_mov_b32_e32 v113, v13
	v_mov_b32_e32 v110, v109
	s_waitcnt lgkmcnt(0)
	v_mul_f32_e32 v114, v13, v111
	v_fma_f32 v110, v112, v110, v114
	v_fma_f32 v111, v113, v111, v114
	s_nop 0
	v_mov_b32_e32 v109, v110

;     __device__ __forceinline__ void operator()(const f32x4 (&acc)[2][2][4][2], const Unit& u, int wr, int wc, int fr, int fq) const {
;     ...
;                         if (rope) { const float cs[8] = {c0[0], c0[1], c0[2], c0[3], c1[0], c1[1], c1[2], c1[3]}; const float sn[8] = {s0[0], s0[1], s0[2], s0[3], s1[0], s1[1], s1[2], s1[3]};
; #pragma unroll
;                             for (int j = 0; j < 8; ++j) { const float o = __shfl_xor(v[j], 16); if (fq == 0) v[j] = v[j] * cs[j] - o * sn[j]; else if (fq == 1) v[j] = v[j] * cs[j] + o * sn[j]; } }
.LBB0_801:
	s_andn2_saveexec_b64 s[0:1], s[0:1]
	s_cbranch_execz .LBB0_803
	v_mov_b32_e32 v112, v5
	v_mov_b32_e32 v113, v13
	v_mov_b32_e32 v110, v109
	s_waitcnt lgkmcnt(0)
	v_mul_f32_e32 v114, v13, v111
	v_fma_f32 v110, v112, v110, -v114
	v_fma_f32 v111, v113, v111, -v114
	s_nop 0
	v_mov_b32_e32 v109, v110
.LBB0_803:
	s_or_b64 exec, exec, s[0:1]
	s_waitcnt lgkmcnt(0)
	ds_bpermute_b32 v111, v101, v90
	v_cmp_lt_i32_e32 vcc, 0, v204
	s_and_saveexec_b64 s[0:1], vcc
	s_xor_b64 s[0:1], exec, s[0:1]
	s_cbranch_execz .LBB0_807
	v_cmp_eq_u32_e32 vcc, 1, v204
	s_and_saveexec_b64 s[16:17], vcc
	s_cbranch_execz .LBB0_806
	v_mov_b32_e32 v112, v6
	v_mov_b32_e32 v113, v14
	v_mov_b32_e32 v110, v90
	s_waitcnt lgkmcnt(0)
	v_mul_f32_e32 v90, v14, v111
	v_fma_f32 v110, v112, v110, v90
	v_fma_f32 v111, v113, v111, v90
	s_nop 0
	v_mov_b32_e32 v90, v110

;     __device__ __forceinline__ void operator()(const f32x4 (&acc)[2][2][4][2], const Unit& u, int wr, int wc, int fr, int fq) const {
;     ...
;                         if (rope) { const float cs[8] = {c0[0], c0[1], c0[2], c0[3], c1[0], c1[1], c1[2], c1[3]}; const float sn[8] = {s0[0], s0[1], s0[2], s0[3], s1[0], s1[1], s1[2], s1[3]};
; #pragma unroll
;                             for (int j = 0; j < 8; ++j) { const float o = __shfl_xor(v[j], 16); if (fq == 0) v[j] = v[j] * cs[j] - o * sn[j]; else if (fq == 1) v[j] = v[j] * cs[j] + o * sn[j]; } }
.LBB0_807:
	s_andn2_saveexec_b64 s[0:1], s[0:1]
	s_cbranch_execz .LBB0_809
	v_mov_b32_e32 v112, v6
	v_mov_b32_e32 v113, v14
	v_mov_b32_e32 v110, v90
	s_waitcnt lgkmcnt(0)
	v_mul_f32_e32 v90, v14, v111
	v_fma_f32 v110, v112, v110, -v90
	v_fma_f32 v111, v113, v111, -v90
	s_nop 0
	v_mov_b32_e32 v90, v110
.LBB0_809:
	s_or_b64 exec, exec, s[0:1]
	s_waitcnt lgkmcnt(0)
	ds_bpermute_b32 v111, v101, v91
	v_cmp_lt_i32_e32 vcc, 0, v204
	s_and_saveexec_b64 s[0:1], vcc
	s_xor_b64 s[0:1], exec, s[0:1]
	s_cbranch_execz .LBB0_813
	v_cmp_eq_u32_e32 vcc, 1, v204
	s_and_saveexec_b64 s[16:17], vcc
	s_cbranch_execz .LBB0_812
	v_mov_b32_e32 v112, v7
	v_mov_b32_e32 v113, v15
	v_mov_b32_e32 v110, v91
	s_waitcnt lgkmcnt(0)
	v_mul_f32_e32 v114, v15, v111
	v_fma_f32 v110, v112, v110, v114
	v_fma_f32 v111, v113, v111, v114
	s_nop 0
	v_mov_b32_e32 v91, v110

;     __device__ __forceinline__ void operator()(const f32x4 (&acc)[2][2][4][2], const Unit& u, int wr, int wc, int fr, int fq) const {
;     ...
;                         if (rope) { const float cs[8] = {c0[0], c0[1], c0[2], c0[3], c1[0], c1[1], c1[2], c1[3]}; const float sn[8] = {s0[0], s0[1], s0[2], s0[3], s1[0], s1[1], s1[2], s1[3]};
; #pragma unroll
;                             for (int j = 0; j < 8; ++j) { const float o = __shfl_xor(v[j], 16); if (fq == 0) v[j] = v[j] * cs[j] - o * sn[j]; else if (fq == 1) v[j] = v[j] * cs[j] + o * sn[j]; } }
.LBB0_813:
	s_andn2_saveexec_b64 s[0:1], s[0:1]
	s_cbranch_execz .LBB0_815
	v_mov_b32_e32 v112, v7
	v_mov_b32_e32 v113, v15
	v_mov_b32_e32 v110, v91
	s_waitcnt lgkmcnt(0)
	v_mul_f32_e32 v114, v15, v111
	v_fma_f32 v110, v112, v110, -v114
	v_fma_f32 v111, v113, v111, -v114
	s_nop 0
	v_mov_b32_e32 v91, v110

; __device__ __forceinline__ float fexp(float x) { return __builtin_amdgcn_exp2f(x * LOG2E); }
; __device__ __forceinline__ float sigm(float x) { return __builtin_amdgcn_rcpf(1.f + fexp(-x)); }
; __device__ __forceinline__ float silu(float x) { return x * sigm(x); }
;     __device__ __forceinline__ void operator()(const f32x4 (&acc)[2][2][4][2], const Unit& u, int wr, int wc, int fr, int fq) const {
;     ...
;                     } else if (reg == PB_QR || reg == PB_G) {
; #pragma unroll
;                         for (int j = 0; j < 8; ++j) v[j] = silu(v[j]);
.LBB0_818:
	s_andn2_b64 vcc, exec, s[0:1]
	s_cbranch_vccnz .LBB0_820
	v_mul_f32_e32 v92, 0xbfb8aa3b, v86
	v_exp_f32_e32 v92, v92
	v_mul_f32_e32 v93, 0xbfb8aa3b, v84
	v_mul_f32_e32 v80, 0xbfb8aa3b, v90
	v_mul_f32_e32 v81, 0xbfb8aa3b, v91
	v_add_f32_e32 v92, 1.0, v92
	v_mul_f32_e32 v82, 0xbfb8aa3b, v88
	v_mul_f32_e32 v83, 0xbfb8aa3b, v89
	v_rcp_f32_e32 v94, v92
	v_mul_f32_e32 v92, 0xbfb8aa3b, v87
	v_exp_f32_e32 v93, v93
	v_mul_f32_e32 v95, 0xbfb8aa3b, v85
	v_exp_f32_e32 v80, v80
	v_exp_f32_e32 v81, v81
	v_exp_f32_e32 v82, v82
	v_exp_f32_e32 v83, v83
	v_exp_f32_e32 v92, v92
	v_exp_f32_e32 v95, v95
	v_add_f32_e32 v93, 1.0, v93
	v_add_f32_e32 v80, 1.0, v80
	v_add_f32_e32 v81, 1.0, v81
	v_add_f32_e32 v82, 1.0, v82
	v_add_f32_e32 v83, 1.0, v83
	v_add_f32_e32 v92, 1.0, v92
	v_rcp_f32_e32 v100, v93
	v_add_f32_e32 v93, 1.0, v95
	v_rcp_f32_e32 v80, v80
	v_rcp_f32_e32 v81, v81
	v_rcp_f32_e32 v82, v82
	v_rcp_f32_e32 v83, v83
	v_rcp_f32_e32 v101, v93
	v_rcp_f32_e32 v95, v92
	v_mul_f32_e32 v102, v90, v80
	v_mul_f32_e32 v103, v91, v81
	v_mul_f32_e32 v92, v88, v82
	v_mul_f32_e32 v93, v89, v83
	v_mul_f32_e32 v100, v84, v100
	v_mul_f32_e32 v101, v85, v101
	v_mul_f32_e32 v94, v86, v94
	v_mul_f32_e32 v95, v87, v95

;     __device__ __forceinline__ void operator()(const f32x4 (&acc)[2][2][4][2], const Unit& u, int wr, int wc, int fr, int fq) const {
;     ...
;                     if (reg <= 1) {
;                         if (rope) { const float cs[8] = {c0[0], c0[1], c0[2], c0[3], c1[0], c1[1], c1[2], c1[3]}; const float sn[8] = {s0[0], s0[1], s0[2], s0[3], s1[0], s1[1], s1[2], s1[3]};
; #pragma unroll
;                             for (int j = 0; j < 8; ++j) { const float o = __shfl_xor(v[j], 16); if (fq == 0) v[j] = v[j] * cs[j] - o * sn[j]; else if (fq == 1) v[j] = v[j] * cs[j] + o * sn[j]; } }
.LBB0_821:
	s_and_b64 vcc, exec, s[10:11]
	s_cbranch_vccnz .LBB0_1332
	v_and_b32_e32 v81, 64, v214
	v_xor_b32_e32 v80, 16, v214
	v_add_u32_e32 v81, 64, v81
	v_cmp_lt_i32_e32 vcc, v80, v81
	s_nop 1
	v_cndmask_b32_e32 v80, v214, v80, vcc
	v_lshlrev_b32_e32 v102, 2, v80
	ds_bpermute_b32 v101, v102, v90
	v_cmp_lt_i32_e32 vcc, 0, v204
	s_and_saveexec_b64 s[0:1], vcc
	s_xor_b64 s[0:1], exec, s[0:1]
	s_cbranch_execz .LBB0_826
	v_cmp_eq_u32_e32 vcc, 1, v204
	v_mov_b32_e32 v83, v85
	v_mov_b32_e32 v82, v84
	v_mov_b32_e32 v95, v87
	v_mov_b32_e32 v94, v86
	v_mov_b32_e32 v93, v89
	v_mov_b32_e32 v92, v88
	v_mov_b32_e32 v81, v91
	v_mov_b32_e32 v80, v90
	s_and_saveexec_b64 s[16:17], vcc
	s_cbranch_execz .LBB0_825
	v_mov_b32_e32 v80, v90
	v_mov_b32_e32 v81, v20
	v_mov_b32_e32 v100, v16
	s_waitcnt lgkmcnt(0)
	v_mul_f32_e32 v80, v80, v100
	v_mul_f32_e32 v81, v81, v101
	v_mov_b32_e32 v83, v85
	v_add_f32_e32 v80, v80, v81
	v_mov_b32_e32 v82, v84
	v_mov_b32_e32 v95, v87
	v_mov_b32_e32 v94, v86
	v_mov_b32_e32 v93, v89
	v_mov_b32_e32 v92, v88
	v_mov_b32_e32 v81, v91

;     __device__ __forceinline__ void operator()(const f32x4 (&acc)[2][2][4][2], const Unit& u, int wr, int wc, int fr, int fq) const {
;     ...
;                         if (rope) { const float cs[8] = {c0[0], c0[1], c0[2], c0[3], c1[0], c1[1], c1[2], c1[3]}; const float sn[8] = {s0[0], s0[1], s0[2], s0[3], s1[0], s1[1], s1[2], s1[3]};
; #pragma unroll
;                             for (int j = 0; j < 8; ++j) { const float o = __shfl_xor(v[j], 16); if (fq == 0) v[j] = v[j] * cs[j] - o * sn[j]; else if (fq == 1) v[j] = v[j] * cs[j] + o * sn[j]; } }
.LBB0_826:
	s_andn2_saveexec_b64 s[0:1], s[0:1]
	s_cbranch_execz .LBB0_828
	v_mov_b32_e32 v80, v90
	v_mov_b32_e32 v81, v20
	v_mov_b32_e32 v100, v16
	s_waitcnt lgkmcnt(0)
	v_mul_f32_e32 v80, v80, v100
	v_mul_f32_e32 v81, v81, v101
	v_mov_b32_e32 v92, v88
	v_sub_f32_e32 v80, v80, v81
	v_mov_b32_e32 v81, v91
	v_mov_b32_e32 v93, v89
	v_mov_b32_e32 v94, v86
	v_mov_b32_e32 v95, v87
	v_mov_b32_e32 v82, v84
	v_mov_b32_e32 v83, v85
.LBB0_828:
	s_or_b64 exec, exec, s[0:1]
	s_waitcnt lgkmcnt(0)
	ds_bpermute_b32 v101, v102, v81
	v_cmp_lt_i32_e32 vcc, 0, v204
	s_and_saveexec_b64 s[0:1], vcc
	s_xor_b64 s[0:1], exec, s[0:1]
	s_cbranch_execz .LBB0_832
	v_cmp_eq_u32_e32 vcc, 1, v204
	s_and_saveexec_b64 s[16:17], vcc
	s_cbranch_execz .LBB0_831
	v_mov_b32_e32 v104, v17
	v_mov_b32_e32 v105, v21
	v_mov_b32_e32 v100, v81
	v_mul_f32_e32 v106, v17, v81
	s_waitcnt lgkmcnt(0)
	v_fma_f32 v100, v104, v100, v106
	v_fma_f32 v101, v105, v101, v106
	s_nop 0
	v_mov_b32_e32 v81, v101

;     __device__ __forceinline__ void operator()(const f32x4 (&acc)[2][2][4][2], const Unit& u, int wr, int wc, int fr, int fq) const {
;     ...
;                         if (rope) { const float cs[8] = {c0[0], c0[1], c0[2], c0[3], c1[0], c1[1], c1[2], c1[3]}; const float sn[8] = {s0[0], s0[1], s0[2], s0[3], s1[0], s1[1], s1[2], s1[3]};
; #pragma unroll
;                             for (int j = 0; j < 8; ++j) { const float o = __shfl_xor(v[j], 16); if (fq == 0) v[j] = v[j] * cs[j] - o * sn[j]; else if (fq == 1) v[j] = v[j] * cs[j] + o * sn[j]; } }
.LBB0_832:
	s_andn2_saveexec_b64 s[0:1], s[0:1]
	s_cbranch_execz .LBB0_834
	v_mov_b32_e32 v104, v17
	v_mov_b32_e32 v105, v21
	v_mov_b32_e32 v100, v81
	v_mul_f32_e32 v106, v17, v81
	s_waitcnt lgkmcnt(0)
	v_fma_f32 v100, -v104, v100, v106
	v_fma_f32 v101, -v105, v101, v106
	s_nop 0
	v_mov_b32_e32 v81, v101
.LBB0_834:
	s_or_b64 exec, exec, s[0:1]
	s_waitcnt lgkmcnt(0)
	ds_bpermute_b32 v101, v102, v92
	v_cmp_lt_i32_e32 vcc, 0, v204
	s_and_saveexec_b64 s[0:1], vcc
	s_xor_b64 s[0:1], exec, s[0:1]
	s_cbranch_execz .LBB0_838
	v_cmp_eq_u32_e32 vcc, 1, v204
	s_and_saveexec_b64 s[16:17], vcc
	s_cbranch_execz .LBB0_837
	v_mov_b32_e32 v104, v18
	v_mov_b32_e32 v105, v22
	v_mov_b32_e32 v100, v92
	s_waitcnt lgkmcnt(0)
	v_mul_f32_e32 v92, v22, v101
	v_fma_f32 v100, v104, v100, v92
	v_fma_f32 v101, v105, v101, v92
	s_nop 0
	v_mov_b32_e32 v92, v100

;     __device__ __forceinline__ void operator()(const f32x4 (&acc)[2][2][4][2], const Unit& u, int wr, int wc, int fr, int fq) const {
;     ...
;                         if (rope) { const float cs[8] = {c0[0], c0[1], c0[2], c0[3], c1[0], c1[1], c1[2], c1[3]}; const float sn[8] = {s0[0], s0[1], s0[2], s0[3], s1[0], s1[1], s1[2], s1[3]};
; #pragma unroll
;                             for (int j = 0; j < 8; ++j) { const float o = __shfl_xor(v[j], 16); if (fq == 0) v[j] = v[j] * cs[j] - o * sn[j]; else if (fq == 1) v[j] = v[j] * cs[j] + o * sn[j]; } }
.LBB0_838:
	s_andn2_saveexec_b64 s[0:1], s[0:1]
	s_cbranch_execz .LBB0_840
	v_mov_b32_e32 v104, v18
	v_mov_b32_e32 v105, v22
	v_mov_b32_e32 v100, v92
	s_waitcnt lgkmcnt(0)
	v_mul_f32_e32 v92, v22, v101
	v_fma_f32 v100, v104, v100, -v92
	v_fma_f32 v101, v105, v101, -v92
	s_nop 0
	v_mov_b32_e32 v92, v100
.LBB0_840:
	s_or_b64 exec, exec, s[0:1]
	s_waitcnt lgkmcnt(0)
	ds_bpermute_b32 v101, v102, v93
	v_cmp_lt_i32_e32 vcc, 0, v204
	s_and_saveexec_b64 s[0:1], vcc
	s_xor_b64 s[0:1], exec, s[0:1]
	s_cbranch_execz .LBB0_844
	v_cmp_eq_u32_e32 vcc, 1, v204
	s_and_saveexec_b64 s[16:17], vcc
	s_cbranch_execz .LBB0_843
	v_mov_b32_e32 v104, v19
	v_mov_b32_e32 v105, v23
	v_mov_b32_e32 v100, v93
	s_waitcnt lgkmcnt(0)
	v_mul_f32_e32 v106, v23, v101
	v_fma_f32 v100, v104, v100, v106
	v_fma_f32 v101, v105, v101, v106
	s_nop 0
	v_mov_b32_e32 v93, v100

;     __device__ __forceinline__ void operator()(const f32x4 (&acc)[2][2][4][2], const Unit& u, int wr, int wc, int fr, int fq) const {
;     ...
;                         if (rope) { const float cs[8] = {c0[0], c0[1], c0[2], c0[3], c1[0], c1[1], c1[2], c1[3]}; const float sn[8] = {s0[0], s0[1], s0[2], s0[3], s1[0], s1[1], s1[2], s1[3]};
; #pragma unroll
;                             for (int j = 0; j < 8; ++j) { const float o = __shfl_xor(v[j], 16); if (fq == 0) v[j] = v[j] * cs[j] - o * sn[j]; else if (fq == 1) v[j] = v[j] * cs[j] + o * sn[j]; } }
.LBB0_844:
	s_andn2_saveexec_b64 s[0:1], s[0:1]
	s_cbranch_execz .LBB0_846
	v_mov_b32_e32 v104, v19
	v_mov_b32_e32 v105, v23
	v_mov_b32_e32 v100, v93
	s_waitcnt lgkmcnt(0)
	v_mul_f32_e32 v106, v23, v101
	v_fma_f32 v100, v104, v100, -v106
	v_fma_f32 v101, v105, v101, -v106
	s_nop 0
	v_mov_b32_e32 v93, v100
.LBB0_846:
	s_or_b64 exec, exec, s[0:1]
	s_waitcnt lgkmcnt(0)
	ds_bpermute_b32 v101, v102, v94
	v_cmp_lt_i32_e32 vcc, 0, v204
	s_and_saveexec_b64 s[0:1], vcc
	s_xor_b64 s[0:1], exec, s[0:1]
	s_cbranch_execz .LBB0_850
	v_cmp_eq_u32_e32 vcc, 1, v204
	s_and_saveexec_b64 s[16:17], vcc
	s_cbranch_execz .LBB0_849
	v_mov_b32_e32 v104, v4
	v_mov_b32_e32 v105, v12
	v_mov_b32_e32 v100, v94
	s_waitcnt lgkmcnt(0)
	v_mul_f32_e32 v94, v12, v101
	v_fma_f32 v100, v104, v100, v94
	v_fma_f32 v101, v105, v101, v94
	s_nop 0
	v_mov_b32_e32 v94, v100

;     __device__ __forceinline__ void operator()(const f32x4 (&acc)[2][2][4][2], const Unit& u, int wr, int wc, int fr, int fq) const {
;     ...
;                         if (rope) { const float cs[8] = {c0[0], c0[1], c0[2], c0[3], c1[0], c1[1], c1[2], c1[3]}; const float sn[8] = {s0[0], s0[1], s0[2], s0[3], s1[0], s1[1], s1[2], s1[3]};
; #pragma unroll
;                             for (int j = 0; j < 8; ++j) { const float o = __shfl_xor(v[j], 16); if (fq == 0) v[j] = v[j] * cs[j] - o * sn[j]; else if (fq == 1) v[j] = v[j] * cs[j] + o * sn[j]; } }
.LBB0_850:
	s_andn2_saveexec_b64 s[0:1], s[0:1]
	s_cbranch_execz .LBB0_852
	v_mov_b32_e32 v104, v4
	v_mov_b32_e32 v105, v12
	v_mov_b32_e32 v100, v94
	s_waitcnt lgkmcnt(0)
	v_mul_f32_e32 v94, v12, v101
	v_fma_f32 v100, v104, v100, -v94
	v_fma_f32 v101, v105, v101, -v94
	s_nop 0
	v_mov_b32_e32 v94, v100
.LBB0_852:
	s_or_b64 exec, exec, s[0:1]
	s_waitcnt lgkmcnt(0)
	ds_bpermute_b32 v101, v102, v95
	v_cmp_lt_i32_e32 vcc, 0, v204
	s_and_saveexec_b64 s[0:1], vcc
	s_xor_b64 s[0:1], exec, s[0:1]
	s_cbranch_execz .LBB0_856
	v_cmp_eq_u32_e32 vcc, 1, v204
	s_and_saveexec_b64 s[16:17], vcc
	s_cbranch_execz .LBB0_855
	v_mov_b32_e32 v104, v5
	v_mov_b32_e32 v105, v13
	v_mov_b32_e32 v100, v95
	s_waitcnt lgkmcnt(0)
	v_mul_f32_e32 v106, v13, v101
	v_fma_f32 v100, v104, v100, v106
	v_fma_f32 v101, v105, v101, v106
	s_nop 0
	v_mov_b32_e32 v95, v100

;     __device__ __forceinline__ void operator()(const f32x4 (&acc)[2][2][4][2], const Unit& u, int wr, int wc, int fr, int fq) const {
;     ...
;                         if (rope) { const float cs[8] = {c0[0], c0[1], c0[2], c0[3], c1[0], c1[1], c1[2], c1[3]}; const float sn[8] = {s0[0], s0[1], s0[2], s0[3], s1[0], s1[1], s1[2], s1[3]};
; #pragma unroll
;                             for (int j = 0; j < 8; ++j) { const float o = __shfl_xor(v[j], 16); if (fq == 0) v[j] = v[j] * cs[j] - o * sn[j]; else if (fq == 1) v[j] = v[j] * cs[j] + o * sn[j]; } }
.LBB0_856:
	s_andn2_saveexec_b64 s[0:1], s[0:1]
	s_cbranch_execz .LBB0_858
	v_mov_b32_e32 v104, v5
	v_mov_b32_e32 v105, v13
	v_mov_b32_e32 v100, v95
	s_waitcnt lgkmcnt(0)
	v_mul_f32_e32 v106, v13, v101
	v_fma_f32 v100, v104, v100, -v106
	v_fma_f32 v101, v105, v101, -v106
	s_nop 0
	v_mov_b32_e32 v95, v100
.LBB0_858:
	s_or_b64 exec, exec, s[0:1]
	s_waitcnt lgkmcnt(0)
	ds_bpermute_b32 v101, v102, v82
	v_cmp_lt_i32_e32 vcc, 0, v204
	s_and_saveexec_b64 s[0:1], vcc
	s_xor_b64 s[0:1], exec, s[0:1]
	s_cbranch_execz .LBB0_862
	v_cmp_eq_u32_e32 vcc, 1, v204
	s_and_saveexec_b64 s[16:17], vcc
	s_cbranch_execz .LBB0_861
	v_mov_b32_e32 v104, v6
	v_mov_b32_e32 v105, v14
	v_mov_b32_e32 v100, v82
	s_waitcnt lgkmcnt(0)
	v_mul_f32_e32 v82, v14, v101
	v_fma_f32 v100, v104, v100, v82
	v_fma_f32 v101, v105, v101, v82
	s_nop 0
	v_mov_b32_e32 v82, v100

;     __device__ __forceinline__ void operator()(const f32x4 (&acc)[2][2][4][2], const Unit& u, int wr, int wc, int fr, int fq) const {
;     ...
;                         if (rope) { const float cs[8] = {c0[0], c0[1], c0[2], c0[3], c1[0], c1[1], c1[2], c1[3]}; const float sn[8] = {s0[0], s0[1], s0[2], s0[3], s1[0], s1[1], s1[2], s1[3]};
; #pragma unroll
;                             for (int j = 0; j < 8; ++j) { const float o = __shfl_xor(v[j], 16); if (fq == 0) v[j] = v[j] * cs[j] - o * sn[j]; else if (fq == 1) v[j] = v[j] * cs[j] + o * sn[j]; } }
.LBB0_862:
	s_andn2_saveexec_b64 s[0:1], s[0:1]
	s_cbranch_execz .LBB0_864
	v_mov_b32_e32 v104, v6
	v_mov_b32_e32 v105, v14
	v_mov_b32_e32 v100, v82
	s_waitcnt lgkmcnt(0)
	v_mul_f32_e32 v82, v14, v101
	v_fma_f32 v100, v104, v100, -v82
	v_fma_f32 v101, v105, v101, -v82
	s_nop 0
	v_mov_b32_e32 v82, v100
.LBB0_864:
	s_or_b64 exec, exec, s[0:1]
	s_waitcnt lgkmcnt(0)
	ds_bpermute_b32 v101, v102, v83
	v_cmp_lt_i32_e32 vcc, 0, v204
	s_and_saveexec_b64 s[0:1], vcc
	s_xor_b64 s[0:1], exec, s[0:1]
	s_cbranch_execz .LBB0_868
	v_cmp_eq_u32_e32 vcc, 1, v204
	s_and_saveexec_b64 s[16:17], vcc
	s_cbranch_execz .LBB0_867
	v_mov_b32_e32 v102, v7
	v_mov_b32_e32 v103, v15
	v_mov_b32_e32 v100, v83
	s_waitcnt lgkmcnt(0)
	v_mul_f32_e32 v104, v15, v101
	v_fma_f32 v100, v102, v100, v104
	v_fma_f32 v101, v103, v101, v104
	s_nop 0
	v_mov_b32_e32 v83, v100

;     __device__ __forceinline__ void operator()(const f32x4 (&acc)[2][2][4][2], const Unit& u, int wr, int wc, int fr, int fq) const {
;     ...
;                         if (rope) { const float cs[8] = {c0[0], c0[1], c0[2], c0[3], c1[0], c1[1], c1[2], c1[3]}; const float sn[8] = {s0[0], s0[1], s0[2], s0[3], s1[0], s1[1], s1[2], s1[3]};
; #pragma unroll
;                             for (int j = 0; j < 8; ++j) { const float o = __shfl_xor(v[j], 16); if (fq == 0) v[j] = v[j] * cs[j] - o * sn[j]; else if (fq == 1) v[j] = v[j] * cs[j] + o * sn[j]; } }
.LBB0_868:
	s_andn2_saveexec_b64 s[0:1], s[0:1]
	s_cbranch_execz .LBB0_870
	v_mov_b32_e32 v102, v7
	v_mov_b32_e32 v103, v15
	v_mov_b32_e32 v100, v83
	s_waitcnt lgkmcnt(0)
	v_mul_f32_e32 v104, v15, v101
	v_fma_f32 v100, v102, v100, -v104
	v_fma_f32 v101, v103, v101, -v104
	s_nop 0
	v_mov_b32_e32 v83, v100

; __device__ __forceinline__ float fexp(float x) { return __builtin_amdgcn_exp2f(x * LOG2E); }
; __device__ __forceinline__ float sigm(float x) { return __builtin_amdgcn_rcpf(1.f + fexp(-x)); }
; __device__ __forceinline__ float silu(float x) { return x * sigm(x); }
;     __device__ __forceinline__ void operator()(const f32x4 (&acc)[2][2][4][2], const Unit& u, int wr, int wc, int fr, int fq) const {
;     ...
;                     } else if (reg == PB_QR || reg == PB_G) {
; #pragma unroll
;                         for (int j = 0; j < 8; ++j) v[j] = silu(v[j]);
.LBB0_873:
	s_andn2_b64 vcc, exec, s[0:1]
	s_cbranch_vccnz .LBB0_875
	v_mul_f32_e32 v85, 0xbfb8aa3b, v78
	v_exp_f32_e32 v85, v85
	v_mul_f32_e32 v90, 0xbfb8aa3b, v76
	v_mul_f32_e32 v72, 0xbfb8aa3b, v88
	v_mul_f32_e32 v73, 0xbfb8aa3b, v89
	v_add_f32_e32 v85, 1.0, v85
	v_mul_f32_e32 v74, 0xbfb8aa3b, v86
	v_mul_f32_e32 v75, 0xbfb8aa3b, v87
	v_rcp_f32_e32 v92, v85
	v_mul_f32_e32 v85, 0xbfb8aa3b, v79
	v_exp_f32_e32 v90, v90
	v_mul_f32_e32 v91, 0xbfb8aa3b, v77
	v_exp_f32_e32 v72, v72
	v_exp_f32_e32 v73, v73
	v_exp_f32_e32 v74, v74
	v_exp_f32_e32 v75, v75
	v_exp_f32_e32 v85, v85
	v_exp_f32_e32 v91, v91
	v_add_f32_e32 v90, 1.0, v90
	v_add_f32_e32 v72, 1.0, v72
	v_add_f32_e32 v73, 1.0, v73
	v_add_f32_e32 v74, 1.0, v74
	v_add_f32_e32 v75, 1.0, v75
	v_add_f32_e32 v85, 1.0, v85
	v_rcp_f32_e32 v94, v90
	v_add_f32_e32 v90, 1.0, v91
	v_rcp_f32_e32 v72, v72
	v_rcp_f32_e32 v73, v73
	v_rcp_f32_e32 v74, v74
	v_rcp_f32_e32 v75, v75
	v_rcp_f32_e32 v95, v90
	v_rcp_f32_e32 v93, v85
	v_mul_f32_e32 v96, v88, v72
	v_mul_f32_e32 v97, v89, v73
	v_mul_f32_e32 v90, v86, v74
	v_mul_f32_e32 v91, v87, v75
	v_mul_f32_e32 v94, v76, v94
	v_mul_f32_e32 v95, v77, v95
	v_mul_f32_e32 v92, v78, v92
	v_mul_f32_e32 v93, v79, v93

;     __device__ __forceinline__ void operator()(const f32x4 (&acc)[2][2][4][2], const Unit& u, int wr, int wc, int fr, int fq) const {
;     ...
;                     if (reg <= 1) {
;                         if (rope) { const float cs[8] = {c0[0], c0[1], c0[2], c0[3], c1[0], c1[1], c1[2], c1[3]}; const float sn[8] = {s0[0], s0[1], s0[2], s0[3], s1[0], s1[1], s1[2], s1[3]};
; #pragma unroll
;                             for (int j = 0; j < 8; ++j) { const float o = __shfl_xor(v[j], 16); if (fq == 0) v[j] = v[j] * cs[j] - o * sn[j]; else if (fq == 1) v[j] = v[j] * cs[j] + o * sn[j]; } }
.LBB0_876:
	s_and_b64 vcc, exec, s[10:11]
	s_cbranch_vccnz .LBB0_1335
	v_and_b32_e32 v73, 64, v214
	v_xor_b32_e32 v72, 16, v214
	v_add_u32_e32 v73, 64, v73
	v_cmp_lt_i32_e32 vcc, v72, v73
	s_nop 1
	v_cndmask_b32_e32 v72, v214, v72, vcc
	v_lshlrev_b32_e32 v85, 2, v72
	ds_bpermute_b32 v95, v85, v88
	v_cmp_lt_i32_e32 vcc, 0, v204
	s_and_saveexec_b64 s[0:1], vcc
	s_xor_b64 s[0:1], exec, s[0:1]
	s_cbranch_execz .LBB0_881
	v_cmp_eq_u32_e32 vcc, 1, v204
	v_mov_b32_e32 v75, v77
	v_mov_b32_e32 v74, v76
	v_mov_b32_e32 v93, v79
	v_mov_b32_e32 v92, v78
	v_mov_b32_e32 v91, v87
	v_mov_b32_e32 v90, v86
	v_mov_b32_e32 v73, v89
	v_mov_b32_e32 v72, v88
	s_and_saveexec_b64 s[16:17], vcc
	s_cbranch_execz .LBB0_880
	v_mov_b32_e32 v72, v88
	v_mov_b32_e32 v73, v20
	v_mov_b32_e32 v94, v16
	s_waitcnt lgkmcnt(0)
	v_mul_f32_e32 v72, v72, v94
	v_mul_f32_e32 v73, v73, v95
	v_mov_b32_e32 v75, v77
	v_add_f32_e32 v72, v72, v73
	v_mov_b32_e32 v74, v76
	v_mov_b32_e32 v93, v79
	v_mov_b32_e32 v92, v78
	v_mov_b32_e32 v91, v87
	v_mov_b32_e32 v90, v86
	v_mov_b32_e32 v73, v89

;     __device__ __forceinline__ void operator()(const f32x4 (&acc)[2][2][4][2], const Unit& u, int wr, int wc, int fr, int fq) const {
;     ...
;                         if (rope) { const float cs[8] = {c0[0], c0[1], c0[2], c0[3], c1[0], c1[1], c1[2], c1[3]}; const float sn[8] = {s0[0], s0[1], s0[2], s0[3], s1[0], s1[1], s1[2], s1[3]};
; #pragma unroll
;                             for (int j = 0; j < 8; ++j) { const float o = __shfl_xor(v[j], 16); if (fq == 0) v[j] = v[j] * cs[j] - o * sn[j]; else if (fq == 1) v[j] = v[j] * cs[j] + o * sn[j]; } }
.LBB0_881:
	s_andn2_saveexec_b64 s[0:1], s[0:1]
	s_cbranch_execz .LBB0_883
	v_mov_b32_e32 v72, v88
	v_mov_b32_e32 v73, v20
	v_mov_b32_e32 v94, v16
	s_waitcnt lgkmcnt(0)
	v_mul_f32_e32 v72, v72, v94
	v_mul_f32_e32 v73, v73, v95
	v_mov_b32_e32 v90, v86
	v_sub_f32_e32 v72, v72, v73
	v_mov_b32_e32 v73, v89
	v_mov_b32_e32 v91, v87
	v_mov_b32_e32 v92, v78
	v_mov_b32_e32 v93, v79
	v_mov_b32_e32 v74, v76
	v_mov_b32_e32 v75, v77
.LBB0_883:
	s_or_b64 exec, exec, s[0:1]
	s_waitcnt lgkmcnt(0)
	ds_bpermute_b32 v95, v85, v73
	v_cmp_lt_i32_e32 vcc, 0, v204
	s_and_saveexec_b64 s[0:1], vcc
	s_xor_b64 s[0:1], exec, s[0:1]
	s_cbranch_execz .LBB0_887
	v_cmp_eq_u32_e32 vcc, 1, v204
	s_and_saveexec_b64 s[16:17], vcc
	s_cbranch_execz .LBB0_886
	v_mov_b32_e32 v96, v17
	v_mov_b32_e32 v97, v21
	v_mov_b32_e32 v94, v73
	v_mul_f32_e32 v98, v17, v73
	s_waitcnt lgkmcnt(0)
	v_fma_f32 v94, v96, v94, v98
	v_fma_f32 v95, v97, v95, v98
	s_nop 0
	v_mov_b32_e32 v73, v95

;     __device__ __forceinline__ void operator()(const f32x4 (&acc)[2][2][4][2], const Unit& u, int wr, int wc, int fr, int fq) const {
;     ...
;                         if (rope) { const float cs[8] = {c0[0], c0[1], c0[2], c0[3], c1[0], c1[1], c1[2], c1[3]}; const float sn[8] = {s0[0], s0[1], s0[2], s0[3], s1[0], s1[1], s1[2], s1[3]};
; #pragma unroll
;                             for (int j = 0; j < 8; ++j) { const float o = __shfl_xor(v[j], 16); if (fq == 0) v[j] = v[j] * cs[j] - o * sn[j]; else if (fq == 1) v[j] = v[j] * cs[j] + o * sn[j]; } }
.LBB0_887:
	s_andn2_saveexec_b64 s[0:1], s[0:1]
	s_cbranch_execz .LBB0_889
	v_mov_b32_e32 v96, v17
	v_mov_b32_e32 v97, v21
	v_mov_b32_e32 v94, v73
	v_mul_f32_e32 v98, v17, v73
	s_waitcnt lgkmcnt(0)
	v_fma_f32 v94, -v96, v94, v98
	v_fma_f32 v95, -v97, v95, v98
	s_nop 0
	v_mov_b32_e32 v73, v95
.LBB0_889:
	s_or_b64 exec, exec, s[0:1]
	s_waitcnt lgkmcnt(0)
	ds_bpermute_b32 v95, v85, v90
	v_cmp_lt_i32_e32 vcc, 0, v204
	s_and_saveexec_b64 s[0:1], vcc
	s_xor_b64 s[0:1], exec, s[0:1]
	s_cbranch_execz .LBB0_893
	v_cmp_eq_u32_e32 vcc, 1, v204
	s_and_saveexec_b64 s[16:17], vcc
	s_cbranch_execz .LBB0_892
	v_mov_b32_e32 v96, v18
	v_mov_b32_e32 v97, v22
	v_mov_b32_e32 v94, v90
	s_waitcnt lgkmcnt(0)
	v_mul_f32_e32 v90, v22, v95
	v_fma_f32 v94, v96, v94, v90
	v_fma_f32 v95, v97, v95, v90
	s_nop 0
	v_mov_b32_e32 v90, v94

;     __device__ __forceinline__ void operator()(const f32x4 (&acc)[2][2][4][2], const Unit& u, int wr, int wc, int fr, int fq) const {
;     ...
;                     if (reg <= 1) {
;                         if (rope) { const float cs[8] = {c0[0], c0[1], c0[2], c0[3], c1[0], c1[1], c1[2], c1[3]}; const float sn[8] = {s0[0], s0[1], s0[2], s0[3], s1[0], s1[1], s1[2], s1[3]};
; #pragma unroll
;                             for (int j = 0; j < 8; ++j) { const float o = __shfl_xor(v[j], 16); if (fq == 0) v[j] = v[j] * cs[j] - o * sn[j]; else if (fq == 1) v[j] = v[j] * cs[j] + o * sn[j]; } }
.LBB0_893:
	s_andn2_saveexec_b64 s[0:1], s[0:1]
	s_cbranch_execz .LBB0_895
	v_mov_b32_e32 v96, v18
	v_mov_b32_e32 v97, v22
	v_mov_b32_e32 v94, v90
	s_waitcnt lgkmcnt(0)
	v_mul_f32_e32 v90, v22, v95
	v_fma_f32 v94, v96, v94, -v90
	v_fma_f32 v95, v97, v95, -v90
	s_nop 0
	v_mov_b32_e32 v90, v94
.LBB0_895:
	s_or_b64 exec, exec, s[0:1]
	s_waitcnt lgkmcnt(0)
	ds_bpermute_b32 v95, v85, v91
	v_cmp_lt_i32_e32 vcc, 0, v204
	s_and_saveexec_b64 s[0:1], vcc
	s_xor_b64 s[0:1], exec, s[0:1]
	s_cbranch_execz .LBB0_899
	v_cmp_eq_u32_e32 vcc, 1, v204
	s_and_saveexec_b64 s[16:17], vcc
	s_cbranch_execz .LBB0_898
	v_mov_b32_e32 v96, v19
	v_mov_b32_e32 v97, v23
	v_mov_b32_e32 v94, v91
	s_waitcnt lgkmcnt(0)
	v_mul_f32_e32 v98, v23, v95
	v_fma_f32 v94, v96, v94, v98
	v_fma_f32 v95, v97, v95, v98
	s_nop 0
	v_mov_b32_e32 v91, v94

;     __device__ __forceinline__ void operator()(const f32x4 (&acc)[2][2][4][2], const Unit& u, int wr, int wc, int fr, int fq) const {
;     ...
;                     if (reg <= 1) {
;                         if (rope) { const float cs[8] = {c0[0], c0[1], c0[2], c0[3], c1[0], c1[1], c1[2], c1[3]}; const float sn[8] = {s0[0], s0[1], s0[2], s0[3], s1[0], s1[1], s1[2], s1[3]};
; #pragma unroll
;                             for (int j = 0; j < 8; ++j) { const float o = __shfl_xor(v[j], 16); if (fq == 0) v[j] = v[j] * cs[j] - o * sn[j]; else if (fq == 1) v[j] = v[j] * cs[j] + o * sn[j]; } }
.LBB0_899:
	s_andn2_saveexec_b64 s[0:1], s[0:1]
	s_cbranch_execz .LBB0_901
	v_mov_b32_e32 v96, v19
	v_mov_b32_e32 v97, v23
	v_mov_b32_e32 v94, v91
	s_waitcnt lgkmcnt(0)
	v_mul_f32_e32 v98, v23, v95
	v_fma_f32 v94, v96, v94, -v98
	v_fma_f32 v95, v97, v95, -v98
	s_nop 0
	v_mov_b32_e32 v91, v94
.LBB0_901:
	s_or_b64 exec, exec, s[0:1]
	s_waitcnt lgkmcnt(0)
	ds_bpermute_b32 v95, v85, v92
	v_cmp_lt_i32_e32 vcc, 0, v204
	s_and_saveexec_b64 s[0:1], vcc
	s_xor_b64 s[0:1], exec, s[0:1]
	s_cbranch_execz .LBB0_905
	v_cmp_eq_u32_e32 vcc, 1, v204
	s_and_saveexec_b64 s[16:17], vcc
	s_cbranch_execz .LBB0_904
	v_mov_b32_e32 v96, v4
	v_mov_b32_e32 v97, v12
	v_mov_b32_e32 v94, v92
	s_waitcnt lgkmcnt(0)
	v_mul_f32_e32 v92, v12, v95
	v_fma_f32 v94, v96, v94, v92
	v_fma_f32 v95, v97, v95, v92
	s_nop 0
	v_mov_b32_e32 v92, v94

;     __device__ __forceinline__ void operator()(const f32x4 (&acc)[2][2][4][2], const Unit& u, int wr, int wc, int fr, int fq) const {
;     ...
;                     if (reg <= 1) {
;                         if (rope) { const float cs[8] = {c0[0], c0[1], c0[2], c0[3], c1[0], c1[1], c1[2], c1[3]}; const float sn[8] = {s0[0], s0[1], s0[2], s0[3], s1[0], s1[1], s1[2], s1[3]};
; #pragma unroll
;                             for (int j = 0; j < 8; ++j) { const float o = __shfl_xor(v[j], 16); if (fq == 0) v[j] = v[j] * cs[j] - o * sn[j]; else if (fq == 1) v[j] = v[j] * cs[j] + o * sn[j]; } }
.LBB0_905:
	s_andn2_saveexec_b64 s[0:1], s[0:1]
	s_cbranch_execz .LBB0_907
	v_mov_b32_e32 v96, v4
	v_mov_b32_e32 v97, v12
	v_mov_b32_e32 v94, v92
	s_waitcnt lgkmcnt(0)
	v_mul_f32_e32 v92, v12, v95
	v_fma_f32 v94, v96, v94, -v92
	v_fma_f32 v95, v97, v95, -v92
	s_nop 0
	v_mov_b32_e32 v92, v94
.LBB0_907:
	s_or_b64 exec, exec, s[0:1]
	s_waitcnt lgkmcnt(0)
	ds_bpermute_b32 v95, v85, v93
	v_cmp_lt_i32_e32 vcc, 0, v204
	s_and_saveexec_b64 s[0:1], vcc
	s_xor_b64 s[0:1], exec, s[0:1]
	s_cbranch_execz .LBB0_911
	v_cmp_eq_u32_e32 vcc, 1, v204
	s_and_saveexec_b64 s[16:17], vcc
	s_cbranch_execz .LBB0_910
	v_mov_b32_e32 v96, v5
	v_mov_b32_e32 v97, v13
	v_mov_b32_e32 v94, v93
	s_waitcnt lgkmcnt(0)
	v_mul_f32_e32 v98, v13, v95
	v_fma_f32 v94, v96, v94, v98
	v_fma_f32 v95, v97, v95, v98
	s_nop 0
	v_mov_b32_e32 v93, v94

;     __device__ __forceinline__ void operator()(const f32x4 (&acc)[2][2][4][2], const Unit& u, int wr, int wc, int fr, int fq) const {
;     ...
;                     if (reg <= 1) {
;                         if (rope) { const float cs[8] = {c0[0], c0[1], c0[2], c0[3], c1[0], c1[1], c1[2], c1[3]}; const float sn[8] = {s0[0], s0[1], s0[2], s0[3], s1[0], s1[1], s1[2], s1[3]};
; #pragma unroll
;                             for (int j = 0; j < 8; ++j) { const float o = __shfl_xor(v[j], 16); if (fq == 0) v[j] = v[j] * cs[j] - o * sn[j]; else if (fq == 1) v[j] = v[j] * cs[j] + o * sn[j]; } }
.LBB0_911:
	s_andn2_saveexec_b64 s[0:1], s[0:1]
	s_cbranch_execz .LBB0_913
	v_mov_b32_e32 v96, v5
	v_mov_b32_e32 v97, v13
	v_mov_b32_e32 v94, v93
	s_waitcnt lgkmcnt(0)
	v_mul_f32_e32 v98, v13, v95
	v_fma_f32 v94, v96, v94, -v98
	v_fma_f32 v95, v97, v95, -v98
	s_nop 0
	v_mov_b32_e32 v93, v94
.LBB0_913:
	s_or_b64 exec, exec, s[0:1]
	s_waitcnt lgkmcnt(0)
	ds_bpermute_b32 v95, v85, v74
	v_cmp_lt_i32_e32 vcc, 0, v204
	s_and_saveexec_b64 s[0:1], vcc
	s_xor_b64 s[0:1], exec, s[0:1]
	s_cbranch_execz .LBB0_917
	v_cmp_eq_u32_e32 vcc, 1, v204
	s_and_saveexec_b64 s[16:17], vcc
	s_cbranch_execz .LBB0_916
	v_mov_b32_e32 v96, v6
	v_mov_b32_e32 v97, v14
	v_mov_b32_e32 v94, v74
	s_waitcnt lgkmcnt(0)
	v_mul_f32_e32 v74, v14, v95
	v_fma_f32 v94, v96, v94, v74
	v_fma_f32 v95, v97, v95, v74
	s_nop 0
	v_mov_b32_e32 v74, v94

;     __device__ __forceinline__ void operator()(const f32x4 (&acc)[2][2][4][2], const Unit& u, int wr, int wc, int fr, int fq) const {
;     ...
;                     if (reg <= 1) {
;                         if (rope) { const float cs[8] = {c0[0], c0[1], c0[2], c0[3], c1[0], c1[1], c1[2], c1[3]}; const float sn[8] = {s0[0], s0[1], s0[2], s0[3], s1[0], s1[1], s1[2], s1[3]};
; #pragma unroll
;                             for (int j = 0; j < 8; ++j) { const float o = __shfl_xor(v[j], 16); if (fq == 0) v[j] = v[j] * cs[j] - o * sn[j]; else if (fq == 1) v[j] = v[j] * cs[j] + o * sn[j]; } }
.LBB0_917:
	s_andn2_saveexec_b64 s[0:1], s[0:1]
	s_cbranch_execz .LBB0_919
	v_mov_b32_e32 v96, v6
	v_mov_b32_e32 v97, v14
	v_mov_b32_e32 v94, v74
	s_waitcnt lgkmcnt(0)
	v_mul_f32_e32 v74, v14, v95
	v_fma_f32 v94, v96, v94, -v74
	v_fma_f32 v95, v97, v95, -v74
	s_nop 0
	v_mov_b32_e32 v74, v94
.LBB0_919:
	s_or_b64 exec, exec, s[0:1]
	s_waitcnt lgkmcnt(0)
	ds_bpermute_b32 v95, v85, v75
	v_cmp_lt_i32_e32 vcc, 0, v204
	s_and_saveexec_b64 s[0:1], vcc
	s_xor_b64 s[0:1], exec, s[0:1]
	s_cbranch_execz .LBB0_923
	v_cmp_eq_u32_e32 vcc, 1, v204
	s_and_saveexec_b64 s[16:17], vcc
	s_cbranch_execz .LBB0_922
	v_mov_b32_e32 v96, v7
	v_mov_b32_e32 v97, v15
	v_mov_b32_e32 v94, v75
	s_waitcnt lgkmcnt(0)
	v_mul_f32_e32 v98, v15, v95
	v_fma_f32 v94, v96, v94, v98
	v_fma_f32 v95, v97, v95, v98
	s_nop 0
	v_mov_b32_e32 v75, v94

;     __device__ __forceinline__ void operator()(const f32x4 (&acc)[2][2][4][2], const Unit& u, int wr, int wc, int fr, int fq) const {
;     ...
;                     if (reg <= 1) {
;                         if (rope) { const float cs[8] = {c0[0], c0[1], c0[2], c0[3], c1[0], c1[1], c1[2], c1[3]}; const float sn[8] = {s0[0], s0[1], s0[2], s0[3], s1[0], s1[1], s1[2], s1[3]};
; #pragma unroll
;                             for (int j = 0; j < 8; ++j) { const float o = __shfl_xor(v[j], 16); if (fq == 0) v[j] = v[j] * cs[j] - o * sn[j]; else if (fq == 1) v[j] = v[j] * cs[j] + o * sn[j]; } }
.LBB0_923:
	s_andn2_saveexec_b64 s[0:1], s[0:1]
	s_cbranch_execz .LBB0_925
	v_mov_b32_e32 v96, v7
	v_mov_b32_e32 v97, v15
	v_mov_b32_e32 v94, v75
	s_waitcnt lgkmcnt(0)
	v_mul_f32_e32 v98, v15, v95
	v_fma_f32 v94, v96, v94, -v98
	v_fma_f32 v95, v97, v95, -v98
	s_nop 0
	v_mov_b32_e32 v75, v94

; __device__ __forceinline__ float fexp(float x) { return __builtin_amdgcn_exp2f(x * LOG2E); }
; __device__ __forceinline__ float sigm(float x) { return __builtin_amdgcn_rcpf(1.f + fexp(-x)); }
; __device__ __forceinline__ float silu(float x) { return x * sigm(x); }
;     __device__ __forceinline__ void operator()(const f32x4 (&acc)[2][2][4][2], const Unit& u, int wr, int wc, int fr, int fq) const {
;     ...
;                     } else if (reg == PB_QR || reg == PB_G) {
; #pragma unroll
;                         for (int j = 0; j < 8; ++j) v[j] = silu(v[j]);
.LBB0_928:
	s_andn2_b64 vcc, exec, s[0:1]
	s_cbranch_vccnz .LBB0_930
	v_mul_f32_e32 v76, 0xbfb8aa3b, v70
	v_exp_f32_e32 v76, v76
	v_mul_f32_e32 v77, 0xbfb8aa3b, v68
	v_mul_f32_e32 v64, 0xbfb8aa3b, v74
	v_mul_f32_e32 v65, 0xbfb8aa3b, v75
	v_add_f32_e32 v76, 1.0, v76
	v_mul_f32_e32 v66, 0xbfb8aa3b, v72
	v_mul_f32_e32 v67, 0xbfb8aa3b, v73
	v_rcp_f32_e32 v78, v76
	v_mul_f32_e32 v76, 0xbfb8aa3b, v71
	v_exp_f32_e32 v77, v77
	v_mul_f32_e32 v79, 0xbfb8aa3b, v69
	v_exp_f32_e32 v64, v64
	v_exp_f32_e32 v65, v65
	v_exp_f32_e32 v66, v66
	v_exp_f32_e32 v67, v67
	v_exp_f32_e32 v76, v76
	v_exp_f32_e32 v79, v79
	v_add_f32_e32 v77, 1.0, v77
	v_add_f32_e32 v64, 1.0, v64
	v_add_f32_e32 v65, 1.0, v65
	v_add_f32_e32 v66, 1.0, v66
	v_add_f32_e32 v67, 1.0, v67
	v_add_f32_e32 v76, 1.0, v76
	v_rcp_f32_e32 v84, v77
	v_add_f32_e32 v77, 1.0, v79
	v_rcp_f32_e32 v64, v64
	v_rcp_f32_e32 v65, v65
	v_rcp_f32_e32 v66, v66
	v_rcp_f32_e32 v67, v67
	v_rcp_f32_e32 v85, v77
	v_rcp_f32_e32 v79, v76
	v_mul_f32_e32 v86, v74, v64
	v_mul_f32_e32 v87, v75, v65
	v_mul_f32_e32 v76, v72, v66
	v_mul_f32_e32 v77, v73, v67
	v_mul_f32_e32 v84, v68, v84
	v_mul_f32_e32 v85, v69, v85
	v_mul_f32_e32 v78, v70, v78
	v_mul_f32_e32 v79, v71, v79

;     __device__ __forceinline__ void operator()(const f32x4 (&acc)[2][2][4][2], const Unit& u, int wr, int wc, int fr, int fq) const {
;     ...
;                     if (reg <= 1) {
;                         if (rope) { const float cs[8] = {c0[0], c0[1], c0[2], c0[3], c1[0], c1[1], c1[2], c1[3]}; const float sn[8] = {s0[0], s0[1], s0[2], s0[3], s1[0], s1[1], s1[2], s1[3]};
; #pragma unroll
;                             for (int j = 0; j < 8; ++j) { const float o = __shfl_xor(v[j], 16); if (fq == 0) v[j] = v[j] * cs[j] - o * sn[j]; else if (fq == 1) v[j] = v[j] * cs[j] + o * sn[j]; } }
.LBB0_931:
	s_and_b64 vcc, exec, s[10:11]
	s_cbranch_vccnz .LBB0_1338
	v_and_b32_e32 v65, 64, v214
	v_xor_b32_e32 v64, 16, v214
	v_add_u32_e32 v65, 64, v65
	v_cmp_lt_i32_e32 vcc, v64, v65
	s_nop 1
	v_cndmask_b32_e32 v64, v214, v64, vcc
	v_lshlrev_b32_e32 v86, 2, v64
	ds_bpermute_b32 v85, v86, v74
	v_cmp_lt_i32_e32 vcc, 0, v204
	s_and_saveexec_b64 s[0:1], vcc
	s_xor_b64 s[0:1], exec, s[0:1]
	s_cbranch_execz .LBB0_936
	v_cmp_eq_u32_e32 vcc, 1, v204
	v_mov_b32_e32 v67, v69
	v_mov_b32_e32 v66, v68
	v_mov_b32_e32 v79, v71
	v_mov_b32_e32 v78, v70
	v_mov_b32_e32 v77, v73
	v_mov_b32_e32 v76, v72
	v_mov_b32_e32 v65, v75
	v_mov_b32_e32 v64, v74
	s_and_saveexec_b64 s[16:17], vcc
	s_cbranch_execz .LBB0_935
	v_mov_b32_e32 v64, v74
	v_mov_b32_e32 v65, v20
	v_mov_b32_e32 v84, v16
	s_waitcnt lgkmcnt(0)
	v_mul_f32_e32 v64, v64, v84
	v_mul_f32_e32 v65, v65, v85
	v_mov_b32_e32 v67, v69
	v_add_f32_e32 v64, v64, v65
	v_mov_b32_e32 v66, v68
	v_mov_b32_e32 v79, v71
	v_mov_b32_e32 v78, v70
	v_mov_b32_e32 v77, v73
	v_mov_b32_e32 v76, v72
	v_mov_b32_e32 v65, v75

;     __device__ __forceinline__ void operator()(const f32x4 (&acc)[2][2][4][2], const Unit& u, int wr, int wc, int fr, int fq) const {
;     ...
;                     if (reg <= 1) {
;                         if (rope) { const float cs[8] = {c0[0], c0[1], c0[2], c0[3], c1[0], c1[1], c1[2], c1[3]}; const float sn[8] = {s0[0], s0[1], s0[2], s0[3], s1[0], s1[1], s1[2], s1[3]};
; #pragma unroll
;                             for (int j = 0; j < 8; ++j) { const float o = __shfl_xor(v[j], 16); if (fq == 0) v[j] = v[j] * cs[j] - o * sn[j]; else if (fq == 1) v[j] = v[j] * cs[j] + o * sn[j]; } }
.LBB0_936:
	s_andn2_saveexec_b64 s[0:1], s[0:1]
	s_cbranch_execz .LBB0_938
	v_mov_b32_e32 v64, v74
	v_mov_b32_e32 v65, v20
	v_mov_b32_e32 v84, v16
	s_waitcnt lgkmcnt(0)
	v_mul_f32_e32 v64, v64, v84
	v_mul_f32_e32 v65, v65, v85
	v_mov_b32_e32 v76, v72
	v_sub_f32_e32 v64, v64, v65
	v_mov_b32_e32 v65, v75
	v_mov_b32_e32 v77, v73
	v_mov_b32_e32 v78, v70
	v_mov_b32_e32 v79, v71
	v_mov_b32_e32 v66, v68
	v_mov_b32_e32 v67, v69
.LBB0_938:
	s_or_b64 exec, exec, s[0:1]
	s_waitcnt lgkmcnt(0)
	ds_bpermute_b32 v85, v86, v65
	v_cmp_lt_i32_e32 vcc, 0, v204
	s_and_saveexec_b64 s[0:1], vcc
	s_xor_b64 s[0:1], exec, s[0:1]
	s_cbranch_execz .LBB0_942
	v_cmp_eq_u32_e32 vcc, 1, v204
	s_and_saveexec_b64 s[16:17], vcc
	s_cbranch_execz .LBB0_941
	v_mov_b32_e32 v88, v17
	v_mov_b32_e32 v89, v21
	v_mov_b32_e32 v84, v65
	v_mul_f32_e32 v90, v17, v65
	s_waitcnt lgkmcnt(0)
	v_fma_f32 v84, v88, v84, v90
	v_fma_f32 v85, v89, v85, v90
	s_nop 0
	v_mov_b32_e32 v65, v85

;     __device__ __forceinline__ void operator()(const f32x4 (&acc)[2][2][4][2], const Unit& u, int wr, int wc, int fr, int fq) const {
;     ...
;                     if (reg <= 1) {
;                         if (rope) { const float cs[8] = {c0[0], c0[1], c0[2], c0[3], c1[0], c1[1], c1[2], c1[3]}; const float sn[8] = {s0[0], s0[1], s0[2], s0[3], s1[0], s1[1], s1[2], s1[3]};
; #pragma unroll
;                             for (int j = 0; j < 8; ++j) { const float o = __shfl_xor(v[j], 16); if (fq == 0) v[j] = v[j] * cs[j] - o * sn[j]; else if (fq == 1) v[j] = v[j] * cs[j] + o * sn[j]; } }
.LBB0_942:
	s_andn2_saveexec_b64 s[0:1], s[0:1]
	s_cbranch_execz .LBB0_944
	v_mov_b32_e32 v88, v17
	v_mov_b32_e32 v89, v21
	v_mov_b32_e32 v84, v65
	v_mul_f32_e32 v90, v17, v65
	s_waitcnt lgkmcnt(0)
	v_fma_f32 v84, -v88, v84, v90
	v_fma_f32 v85, -v89, v85, v90
	s_nop 0
	v_mov_b32_e32 v65, v85
.LBB0_944:
	s_or_b64 exec, exec, s[0:1]
	s_waitcnt lgkmcnt(0)
	ds_bpermute_b32 v85, v86, v76
	v_cmp_lt_i32_e32 vcc, 0, v204
	s_and_saveexec_b64 s[0:1], vcc
	s_xor_b64 s[0:1], exec, s[0:1]
	s_cbranch_execz .LBB0_948
	v_cmp_eq_u32_e32 vcc, 1, v204
	s_and_saveexec_b64 s[16:17], vcc
	s_cbranch_execz .LBB0_947
	v_mov_b32_e32 v88, v18
	v_mov_b32_e32 v89, v22
	v_mov_b32_e32 v84, v76
	s_waitcnt lgkmcnt(0)
	v_mul_f32_e32 v76, v22, v85
	v_fma_f32 v84, v88, v84, v76
	v_fma_f32 v85, v89, v85, v76
	s_nop 0
	v_mov_b32_e32 v76, v84

;     __device__ __forceinline__ void operator()(const f32x4 (&acc)[2][2][4][2], const Unit& u, int wr, int wc, int fr, int fq) const {
;     ...
;                     if (reg <= 1) {
;                         if (rope) { const float cs[8] = {c0[0], c0[1], c0[2], c0[3], c1[0], c1[1], c1[2], c1[3]}; const float sn[8] = {s0[0], s0[1], s0[2], s0[3], s1[0], s1[1], s1[2], s1[3]};
; #pragma unroll
;                             for (int j = 0; j < 8; ++j) { const float o = __shfl_xor(v[j], 16); if (fq == 0) v[j] = v[j] * cs[j] - o * sn[j]; else if (fq == 1) v[j] = v[j] * cs[j] + o * sn[j]; } }
.LBB0_948:
	s_andn2_saveexec_b64 s[0:1], s[0:1]
	s_cbranch_execz .LBB0_950
	v_mov_b32_e32 v88, v18
	v_mov_b32_e32 v89, v22
	v_mov_b32_e32 v84, v76
	s_waitcnt lgkmcnt(0)
	v_mul_f32_e32 v76, v22, v85
	v_fma_f32 v84, v88, v84, -v76
	v_fma_f32 v85, v89, v85, -v76
	s_nop 0
	v_mov_b32_e32 v76, v84
.LBB0_950:
	s_or_b64 exec, exec, s[0:1]
	s_waitcnt lgkmcnt(0)
	ds_bpermute_b32 v85, v86, v77
	v_cmp_lt_i32_e32 vcc, 0, v204
	s_and_saveexec_b64 s[0:1], vcc
	s_xor_b64 s[0:1], exec, s[0:1]
	s_cbranch_execz .LBB0_954
	v_cmp_eq_u32_e32 vcc, 1, v204
	s_and_saveexec_b64 s[16:17], vcc
	s_cbranch_execz .LBB0_953
	v_mov_b32_e32 v88, v19
	v_mov_b32_e32 v89, v23
	v_mov_b32_e32 v84, v77
	s_waitcnt lgkmcnt(0)
	v_mul_f32_e32 v90, v23, v85
	v_fma_f32 v84, v88, v84, v90
	v_fma_f32 v85, v89, v85, v90
	s_nop 0
	v_mov_b32_e32 v77, v84

;     __device__ __forceinline__ void operator()(const f32x4 (&acc)[2][2][4][2], const Unit& u, int wr, int wc, int fr, int fq) const {
;     ...
;                     if (reg <= 1) {
;                         if (rope) { const float cs[8] = {c0[0], c0[1], c0[2], c0[3], c1[0], c1[1], c1[2], c1[3]}; const float sn[8] = {s0[0], s0[1], s0[2], s0[3], s1[0], s1[1], s1[2], s1[3]};
; #pragma unroll
;                             for (int j = 0; j < 8; ++j) { const float o = __shfl_xor(v[j], 16); if (fq == 0) v[j] = v[j] * cs[j] - o * sn[j]; else if (fq == 1) v[j] = v[j] * cs[j] + o * sn[j]; } }
.LBB0_954:
	s_andn2_saveexec_b64 s[0:1], s[0:1]
	s_cbranch_execz .LBB0_956
	v_mov_b32_e32 v88, v19
	v_mov_b32_e32 v89, v23
	v_mov_b32_e32 v84, v77
	s_waitcnt lgkmcnt(0)
	v_mul_f32_e32 v90, v23, v85
	v_fma_f32 v84, v88, v84, -v90
	v_fma_f32 v85, v89, v85, -v90
	s_nop 0
	v_mov_b32_e32 v77, v84
.LBB0_956:
	s_or_b64 exec, exec, s[0:1]
	s_waitcnt lgkmcnt(0)
	ds_bpermute_b32 v85, v86, v78
	v_cmp_lt_i32_e32 vcc, 0, v204
	s_and_saveexec_b64 s[0:1], vcc
	s_xor_b64 s[0:1], exec, s[0:1]
	s_cbranch_execz .LBB0_960
	v_cmp_eq_u32_e32 vcc, 1, v204
	s_and_saveexec_b64 s[16:17], vcc
	s_cbranch_execz .LBB0_959
	v_mov_b32_e32 v88, v4
	v_mov_b32_e32 v89, v12
	v_mov_b32_e32 v84, v78
	s_waitcnt lgkmcnt(0)
	v_mul_f32_e32 v78, v12, v85
	v_fma_f32 v84, v88, v84, v78
	v_fma_f32 v85, v89, v85, v78
	s_nop 0
	v_mov_b32_e32 v78, v84

;     __device__ __forceinline__ void operator()(const f32x4 (&acc)[2][2][4][2], const Unit& u, int wr, int wc, int fr, int fq) const {
;     ...
;                     if (reg <= 1) {
;                         if (rope) { const float cs[8] = {c0[0], c0[1], c0[2], c0[3], c1[0], c1[1], c1[2], c1[3]}; const float sn[8] = {s0[0], s0[1], s0[2], s0[3], s1[0], s1[1], s1[2], s1[3]};
; #pragma unroll
;                             for (int j = 0; j < 8; ++j) { const float o = __shfl_xor(v[j], 16); if (fq == 0) v[j] = v[j] * cs[j] - o * sn[j]; else if (fq == 1) v[j] = v[j] * cs[j] + o * sn[j]; } }
.LBB0_960:
	s_andn2_saveexec_b64 s[0:1], s[0:1]
	s_cbranch_execz .LBB0_962
	v_mov_b32_e32 v88, v4
	v_mov_b32_e32 v89, v12
	v_mov_b32_e32 v84, v78
	s_waitcnt lgkmcnt(0)
	v_mul_f32_e32 v78, v12, v85
	v_fma_f32 v84, v88, v84, -v78
	v_fma_f32 v85, v89, v85, -v78
	s_nop 0
	v_mov_b32_e32 v78, v84
.LBB0_962:
	s_or_b64 exec, exec, s[0:1]
	s_waitcnt lgkmcnt(0)
	ds_bpermute_b32 v85, v86, v79
	v_cmp_lt_i32_e32 vcc, 0, v204
	s_and_saveexec_b64 s[0:1], vcc
	s_xor_b64 s[0:1], exec, s[0:1]
	s_cbranch_execz .LBB0_966
	v_cmp_eq_u32_e32 vcc, 1, v204
	s_and_saveexec_b64 s[16:17], vcc
	s_cbranch_execz .LBB0_965
	v_mov_b32_e32 v88, v5
	v_mov_b32_e32 v89, v13
	v_mov_b32_e32 v84, v79
	s_waitcnt lgkmcnt(0)
	v_mul_f32_e32 v90, v13, v85
	v_fma_f32 v84, v88, v84, v90
	v_fma_f32 v85, v89, v85, v90
	s_nop 0
	v_mov_b32_e32 v79, v84

;     __device__ __forceinline__ void operator()(const f32x4 (&acc)[2][2][4][2], const Unit& u, int wr, int wc, int fr, int fq) const {
;     ...
;                     if (reg <= 1) {
;                         if (rope) { const float cs[8] = {c0[0], c0[1], c0[2], c0[3], c1[0], c1[1], c1[2], c1[3]}; const float sn[8] = {s0[0], s0[1], s0[2], s0[3], s1[0], s1[1], s1[2], s1[3]};
; #pragma unroll
;                             for (int j = 0; j < 8; ++j) { const float o = __shfl_xor(v[j], 16); if (fq == 0) v[j] = v[j] * cs[j] - o * sn[j]; else if (fq == 1) v[j] = v[j] * cs[j] + o * sn[j]; } }
.LBB0_966:
	s_andn2_saveexec_b64 s[0:1], s[0:1]
	s_cbranch_execz .LBB0_968
	v_mov_b32_e32 v88, v5
	v_mov_b32_e32 v89, v13
	v_mov_b32_e32 v84, v79
	s_waitcnt lgkmcnt(0)
	v_mul_f32_e32 v90, v13, v85
	v_fma_f32 v84, v88, v84, -v90
	v_fma_f32 v85, v89, v85, -v90
	s_nop 0
	v_mov_b32_e32 v79, v84
.LBB0_968:
	s_or_b64 exec, exec, s[0:1]
	s_waitcnt lgkmcnt(0)
	ds_bpermute_b32 v85, v86, v66
	v_cmp_lt_i32_e32 vcc, 0, v204
	s_and_saveexec_b64 s[0:1], vcc
	s_xor_b64 s[0:1], exec, s[0:1]
	s_cbranch_execz .LBB0_972
	v_cmp_eq_u32_e32 vcc, 1, v204
	s_and_saveexec_b64 s[16:17], vcc
	s_cbranch_execz .LBB0_971
	v_mov_b32_e32 v88, v6
	v_mov_b32_e32 v89, v14
	v_mov_b32_e32 v84, v66
	s_waitcnt lgkmcnt(0)
	v_mul_f32_e32 v66, v14, v85
	v_fma_f32 v84, v88, v84, v66
	v_fma_f32 v85, v89, v85, v66
	s_nop 0
	v_mov_b32_e32 v66, v84

;     __device__ __forceinline__ void operator()(const f32x4 (&acc)[2][2][4][2], const Unit& u, int wr, int wc, int fr, int fq) const {
;     ...
;                     if (reg <= 1) {
;                         if (rope) { const float cs[8] = {c0[0], c0[1], c0[2], c0[3], c1[0], c1[1], c1[2], c1[3]}; const float sn[8] = {s0[0], s0[1], s0[2], s0[3], s1[0], s1[1], s1[2], s1[3]};
; #pragma unroll
;                             for (int j = 0; j < 8; ++j) { const float o = __shfl_xor(v[j], 16); if (fq == 0) v[j] = v[j] * cs[j] - o * sn[j]; else if (fq == 1) v[j] = v[j] * cs[j] + o * sn[j]; } }
.LBB0_972:
	s_andn2_saveexec_b64 s[0:1], s[0:1]
	s_cbranch_execz .LBB0_974
	v_mov_b32_e32 v88, v6
	v_mov_b32_e32 v89, v14
	v_mov_b32_e32 v84, v66
	s_waitcnt lgkmcnt(0)
	v_mul_f32_e32 v66, v14, v85
	v_fma_f32 v84, v88, v84, -v66
	v_fma_f32 v85, v89, v85, -v66
	s_nop 0
	v_mov_b32_e32 v66, v84
.LBB0_974:
	s_or_b64 exec, exec, s[0:1]
	s_waitcnt lgkmcnt(0)
	ds_bpermute_b32 v85, v86, v67
	v_cmp_lt_i32_e32 vcc, 0, v204
	s_and_saveexec_b64 s[0:1], vcc
	s_xor_b64 s[0:1], exec, s[0:1]
	s_cbranch_execz .LBB0_978
	v_cmp_eq_u32_e32 vcc, 1, v204
	s_and_saveexec_b64 s[16:17], vcc
	s_cbranch_execz .LBB0_977
	v_mov_b32_e32 v86, v7
	v_mov_b32_e32 v87, v15
	v_mov_b32_e32 v84, v67
	s_waitcnt lgkmcnt(0)
	v_mul_f32_e32 v88, v15, v85
	v_fma_f32 v84, v86, v84, v88
	v_fma_f32 v85, v87, v85, v88
	s_nop 0
	v_mov_b32_e32 v67, v84

;     __device__ __forceinline__ void operator()(const f32x4 (&acc)[2][2][4][2], const Unit& u, int wr, int wc, int fr, int fq) const {
;     ...
;                     if (reg <= 1) {
;                         if (rope) { const float cs[8] = {c0[0], c0[1], c0[2], c0[3], c1[0], c1[1], c1[2], c1[3]}; const float sn[8] = {s0[0], s0[1], s0[2], s0[3], s1[0], s1[1], s1[2], s1[3]};
; #pragma unroll
;                             for (int j = 0; j < 8; ++j) { const float o = __shfl_xor(v[j], 16); if (fq == 0) v[j] = v[j] * cs[j] - o * sn[j]; else if (fq == 1) v[j] = v[j] * cs[j] + o * sn[j]; } }
.LBB0_978:
	s_andn2_saveexec_b64 s[0:1], s[0:1]
	s_cbranch_execz .LBB0_980
	v_mov_b32_e32 v86, v7
	v_mov_b32_e32 v87, v15
	v_mov_b32_e32 v84, v67
	s_waitcnt lgkmcnt(0)
	v_mul_f32_e32 v88, v15, v85
	v_fma_f32 v84, v86, v84, -v88
	v_fma_f32 v85, v87, v85, -v88
	s_nop 0
	v_mov_b32_e32 v67, v84

; __device__ __forceinline__ float fexp(float x) { return __builtin_amdgcn_exp2f(x * LOG2E); }
; __device__ __forceinline__ float sigm(float x) { return __builtin_amdgcn_rcpf(1.f + fexp(-x)); }
; __device__ __forceinline__ float silu(float x) { return x * sigm(x); }
;     __device__ __forceinline__ void operator()(const f32x4 (&acc)[2][2][4][2], const Unit& u, int wr, int wc, int fr, int fq) const {
;     ...
;                     } else if (reg == PB_QR || reg == PB_G) {
; #pragma unroll
;                         for (int j = 0; j < 8; ++j) v[j] = silu(v[j]);
.LBB0_983:
	s_andn2_b64 vcc, exec, s[0:1]
	s_cbranch_vccnz .LBB0_985
	v_mul_f32_e32 v69, 0xbfb8aa3b, v62
	v_exp_f32_e32 v69, v69
	v_mul_f32_e32 v74, 0xbfb8aa3b, v60
	v_mul_f32_e32 v56, 0xbfb8aa3b, v72
	v_mul_f32_e32 v57, 0xbfb8aa3b, v73
	v_add_f32_e32 v69, 1.0, v69
	v_mul_f32_e32 v58, 0xbfb8aa3b, v70
	v_mul_f32_e32 v59, 0xbfb8aa3b, v71
	v_rcp_f32_e32 v76, v69
	v_mul_f32_e32 v69, 0xbfb8aa3b, v63
	v_exp_f32_e32 v74, v74
	v_mul_f32_e32 v75, 0xbfb8aa3b, v61
	v_exp_f32_e32 v56, v56
	v_exp_f32_e32 v57, v57
	v_exp_f32_e32 v58, v58
	v_exp_f32_e32 v59, v59
	v_exp_f32_e32 v69, v69
	v_exp_f32_e32 v75, v75
	v_add_f32_e32 v74, 1.0, v74
	v_add_f32_e32 v56, 1.0, v56
	v_add_f32_e32 v57, 1.0, v57
	v_add_f32_e32 v58, 1.0, v58
	v_add_f32_e32 v59, 1.0, v59
	v_add_f32_e32 v69, 1.0, v69
	v_rcp_f32_e32 v78, v74
	v_add_f32_e32 v74, 1.0, v75
	v_rcp_f32_e32 v56, v56
	v_rcp_f32_e32 v57, v57
	v_rcp_f32_e32 v58, v58
	v_rcp_f32_e32 v59, v59
	v_rcp_f32_e32 v79, v74
	v_rcp_f32_e32 v77, v69
	v_mul_f32_e32 v80, v72, v56
	v_mul_f32_e32 v81, v73, v57
	v_mul_f32_e32 v74, v70, v58
	v_mul_f32_e32 v75, v71, v59
	v_mul_f32_e32 v78, v60, v78
	v_mul_f32_e32 v79, v61, v79
	v_mul_f32_e32 v76, v62, v76
	v_mul_f32_e32 v77, v63, v77

;     __device__ __forceinline__ void operator()(const f32x4 (&acc)[2][2][4][2], const Unit& u, int wr, int wc, int fr, int fq) const {
;     ...
;                     if (reg <= 1) {
;                         if (rope) { const float cs[8] = {c0[0], c0[1], c0[2], c0[3], c1[0], c1[1], c1[2], c1[3]}; const float sn[8] = {s0[0], s0[1], s0[2], s0[3], s1[0], s1[1], s1[2], s1[3]};
; #pragma unroll
;                             for (int j = 0; j < 8; ++j) { const float o = __shfl_xor(v[j], 16); if (fq == 0) v[j] = v[j] * cs[j] - o * sn[j]; else if (fq == 1) v[j] = v[j] * cs[j] + o * sn[j]; } }
.LBB0_986:
	s_and_b64 vcc, exec, s[10:11]
	s_cbranch_vccnz .LBB0_1341
	v_and_b32_e32 v57, 64, v214
	v_xor_b32_e32 v56, 16, v214
	v_add_u32_e32 v57, 64, v57
	v_cmp_lt_i32_e32 vcc, v56, v57
	s_nop 1
	v_cndmask_b32_e32 v56, v214, v56, vcc
	v_lshlrev_b32_e32 v69, 2, v56
	ds_bpermute_b32 v79, v69, v72
	v_cmp_lt_i32_e32 vcc, 0, v204
	s_and_saveexec_b64 s[0:1], vcc
	s_xor_b64 s[0:1], exec, s[0:1]
	s_cbranch_execz .LBB0_991
	v_cmp_eq_u32_e32 vcc, 1, v204
	v_mov_b32_e32 v59, v61
	v_mov_b32_e32 v58, v60
	v_mov_b32_e32 v77, v63
	v_mov_b32_e32 v76, v62
	v_mov_b32_e32 v75, v71
	v_mov_b32_e32 v74, v70
	v_mov_b32_e32 v57, v73
	v_mov_b32_e32 v56, v72
	s_and_saveexec_b64 s[16:17], vcc
	s_cbranch_execz .LBB0_990
	v_mov_b32_e32 v56, v72
	v_mov_b32_e32 v57, v20
	v_mov_b32_e32 v78, v16
	s_waitcnt lgkmcnt(0)
	v_mul_f32_e32 v56, v56, v78
	v_mul_f32_e32 v57, v57, v79
	v_mov_b32_e32 v59, v61
	v_add_f32_e32 v56, v56, v57
	v_mov_b32_e32 v58, v60
	v_mov_b32_e32 v77, v63
	v_mov_b32_e32 v76, v62
	v_mov_b32_e32 v75, v71
	v_mov_b32_e32 v74, v70
	v_mov_b32_e32 v57, v73

;     __device__ __forceinline__ void operator()(const f32x4 (&acc)[2][2][4][2], const Unit& u, int wr, int wc, int fr, int fq) const {
;     ...
;                     if (reg <= 1) {
;                         if (rope) { const float cs[8] = {c0[0], c0[1], c0[2], c0[3], c1[0], c1[1], c1[2], c1[3]}; const float sn[8] = {s0[0], s0[1], s0[2], s0[3], s1[0], s1[1], s1[2], s1[3]};
; #pragma unroll
;                             for (int j = 0; j < 8; ++j) { const float o = __shfl_xor(v[j], 16); if (fq == 0) v[j] = v[j] * cs[j] - o * sn[j]; else if (fq == 1) v[j] = v[j] * cs[j] + o * sn[j]; } }
.LBB0_991:
	s_andn2_saveexec_b64 s[0:1], s[0:1]
	s_cbranch_execz .LBB0_993
	v_mov_b32_e32 v56, v72
	v_mov_b32_e32 v57, v20
	v_mov_b32_e32 v78, v16
	s_waitcnt lgkmcnt(0)
	v_mul_f32_e32 v56, v56, v78
	v_mul_f32_e32 v57, v57, v79
	v_mov_b32_e32 v74, v70
	v_sub_f32_e32 v56, v56, v57
	v_mov_b32_e32 v57, v73
	v_mov_b32_e32 v75, v71
	v_mov_b32_e32 v76, v62
	v_mov_b32_e32 v77, v63
	v_mov_b32_e32 v58, v60
	v_mov_b32_e32 v59, v61
.LBB0_993:
	s_or_b64 exec, exec, s[0:1]
	s_waitcnt lgkmcnt(0)
	ds_bpermute_b32 v79, v69, v57
	v_cmp_lt_i32_e32 vcc, 0, v204
	s_and_saveexec_b64 s[0:1], vcc
	s_xor_b64 s[0:1], exec, s[0:1]
	s_cbranch_execz .LBB0_997
	v_cmp_eq_u32_e32 vcc, 1, v204
	s_and_saveexec_b64 s[16:17], vcc
	s_cbranch_execz .LBB0_996
	v_mov_b32_e32 v80, v17
	v_mov_b32_e32 v81, v21
	v_mov_b32_e32 v78, v57
	v_mul_f32_e32 v82, v17, v57
	s_waitcnt lgkmcnt(0)
	v_fma_f32 v78, v80, v78, v82
	v_fma_f32 v79, v81, v79, v82
	s_nop 0
	v_mov_b32_e32 v57, v79

;     __device__ __forceinline__ void operator()(const f32x4 (&acc)[2][2][4][2], const Unit& u, int wr, int wc, int fr, int fq) const {
;     ...
;                     if (reg <= 1) {
;                         if (rope) { const float cs[8] = {c0[0], c0[1], c0[2], c0[3], c1[0], c1[1], c1[2], c1[3]}; const float sn[8] = {s0[0], s0[1], s0[2], s0[3], s1[0], s1[1], s1[2], s1[3]};
; #pragma unroll
;                             for (int j = 0; j < 8; ++j) { const float o = __shfl_xor(v[j], 16); if (fq == 0) v[j] = v[j] * cs[j] - o * sn[j]; else if (fq == 1) v[j] = v[j] * cs[j] + o * sn[j]; } }
.LBB0_997:
	s_andn2_saveexec_b64 s[0:1], s[0:1]
	s_cbranch_execz .LBB0_999
	v_mov_b32_e32 v80, v17
	v_mov_b32_e32 v81, v21
	v_mov_b32_e32 v78, v57
	v_mul_f32_e32 v82, v17, v57
	s_waitcnt lgkmcnt(0)
	v_fma_f32 v78, -v80, v78, v82
	v_fma_f32 v79, -v81, v79, v82
	s_nop 0
	v_mov_b32_e32 v57, v79
.LBB0_999:
	s_or_b64 exec, exec, s[0:1]
	s_waitcnt lgkmcnt(0)
	ds_bpermute_b32 v79, v69, v74
	v_cmp_lt_i32_e32 vcc, 0, v204
	s_and_saveexec_b64 s[0:1], vcc
	s_xor_b64 s[0:1], exec, s[0:1]
	s_cbranch_execz .LBB0_1003
	v_cmp_eq_u32_e32 vcc, 1, v204
	s_and_saveexec_b64 s[16:17], vcc
	s_cbranch_execz .LBB0_1002
	v_mov_b32_e32 v80, v18
	v_mov_b32_e32 v81, v22
	v_mov_b32_e32 v78, v74
	s_waitcnt lgkmcnt(0)
	v_mul_f32_e32 v74, v22, v79
	v_fma_f32 v78, v80, v78, v74
	v_fma_f32 v79, v81, v79, v74
	s_nop 0
	v_mov_b32_e32 v74, v78

;     __device__ __forceinline__ void operator()(const f32x4 (&acc)[2][2][4][2], const Unit& u, int wr, int wc, int fr, int fq) const {
;     ...
;                     if (reg <= 1) {
;                         if (rope) { const float cs[8] = {c0[0], c0[1], c0[2], c0[3], c1[0], c1[1], c1[2], c1[3]}; const float sn[8] = {s0[0], s0[1], s0[2], s0[3], s1[0], s1[1], s1[2], s1[3]};
; #pragma unroll
;                             for (int j = 0; j < 8; ++j) { const float o = __shfl_xor(v[j], 16); if (fq == 0) v[j] = v[j] * cs[j] - o * sn[j]; else if (fq == 1) v[j] = v[j] * cs[j] + o * sn[j]; } }
.LBB0_1003:
	s_andn2_saveexec_b64 s[0:1], s[0:1]
	s_cbranch_execz .LBB0_1005
	v_mov_b32_e32 v80, v18
	v_mov_b32_e32 v81, v22
	v_mov_b32_e32 v78, v74
	s_waitcnt lgkmcnt(0)
	v_mul_f32_e32 v74, v22, v79
	v_fma_f32 v78, v80, v78, -v74
	v_fma_f32 v79, v81, v79, -v74
	s_nop 0
	v_mov_b32_e32 v74, v78
.LBB0_1005:
	s_or_b64 exec, exec, s[0:1]
	s_waitcnt lgkmcnt(0)
	ds_bpermute_b32 v79, v69, v75
	v_cmp_lt_i32_e32 vcc, 0, v204
	s_and_saveexec_b64 s[0:1], vcc
	s_xor_b64 s[0:1], exec, s[0:1]
	s_cbranch_execz .LBB0_1009
	v_cmp_eq_u32_e32 vcc, 1, v204
	s_and_saveexec_b64 s[16:17], vcc
	s_cbranch_execz .LBB0_1008
	v_mov_b32_e32 v80, v19
	v_mov_b32_e32 v81, v23
	v_mov_b32_e32 v78, v75
	s_waitcnt lgkmcnt(0)
	v_mul_f32_e32 v82, v23, v79
	v_fma_f32 v78, v80, v78, v82
	v_fma_f32 v79, v81, v79, v82
	s_nop 0
	v_mov_b32_e32 v75, v78

;     __device__ __forceinline__ void operator()(const f32x4 (&acc)[2][2][4][2], const Unit& u, int wr, int wc, int fr, int fq) const {
;     ...
;                     if (reg <= 1) {
;                         if (rope) { const float cs[8] = {c0[0], c0[1], c0[2], c0[3], c1[0], c1[1], c1[2], c1[3]}; const float sn[8] = {s0[0], s0[1], s0[2], s0[3], s1[0], s1[1], s1[2], s1[3]};
; #pragma unroll
;                             for (int j = 0; j < 8; ++j) { const float o = __shfl_xor(v[j], 16); if (fq == 0) v[j] = v[j] * cs[j] - o * sn[j]; else if (fq == 1) v[j] = v[j] * cs[j] + o * sn[j]; } }
.LBB0_1009:
	s_andn2_saveexec_b64 s[0:1], s[0:1]
	s_cbranch_execz .LBB0_1011
	v_mov_b32_e32 v80, v19
	v_mov_b32_e32 v81, v23
	v_mov_b32_e32 v78, v75
	s_waitcnt lgkmcnt(0)
	v_mul_f32_e32 v82, v23, v79
	v_fma_f32 v78, v80, v78, -v82
	v_fma_f32 v79, v81, v79, -v82
	s_nop 0
	v_mov_b32_e32 v75, v78
.LBB0_1011:
	s_or_b64 exec, exec, s[0:1]
	s_waitcnt lgkmcnt(0)
	ds_bpermute_b32 v79, v69, v76
	v_cmp_lt_i32_e32 vcc, 0, v204
	s_and_saveexec_b64 s[0:1], vcc
	s_xor_b64 s[0:1], exec, s[0:1]
	s_cbranch_execz .LBB0_1015
	v_cmp_eq_u32_e32 vcc, 1, v204
	s_and_saveexec_b64 s[16:17], vcc
	s_cbranch_execz .LBB0_1014
	v_mov_b32_e32 v80, v4
	v_mov_b32_e32 v81, v12
	v_mov_b32_e32 v78, v76
	s_waitcnt lgkmcnt(0)
	v_mul_f32_e32 v76, v12, v79
	v_fma_f32 v78, v80, v78, v76
	v_fma_f32 v79, v81, v79, v76
	s_nop 0
	v_mov_b32_e32 v76, v78

;     __device__ __forceinline__ void operator()(const f32x4 (&acc)[2][2][4][2], const Unit& u, int wr, int wc, int fr, int fq) const {
;     ...
;                     if (reg <= 1) {
;                         if (rope) { const float cs[8] = {c0[0], c0[1], c0[2], c0[3], c1[0], c1[1], c1[2], c1[3]}; const float sn[8] = {s0[0], s0[1], s0[2], s0[3], s1[0], s1[1], s1[2], s1[3]};
; #pragma unroll
;                             for (int j = 0; j < 8; ++j) { const float o = __shfl_xor(v[j], 16); if (fq == 0) v[j] = v[j] * cs[j] - o * sn[j]; else if (fq == 1) v[j] = v[j] * cs[j] + o * sn[j]; } }
.LBB0_1015:
	s_andn2_saveexec_b64 s[0:1], s[0:1]
	s_cbranch_execz .LBB0_1017
	v_mov_b32_e32 v80, v4
	v_mov_b32_e32 v81, v12
	v_mov_b32_e32 v78, v76
	s_waitcnt lgkmcnt(0)
	v_mul_f32_e32 v76, v12, v79
	v_fma_f32 v78, v80, v78, -v76
	v_fma_f32 v79, v81, v79, -v76
	s_nop 0
	v_mov_b32_e32 v76, v78
.LBB0_1017:
	s_or_b64 exec, exec, s[0:1]
	s_waitcnt lgkmcnt(0)
	ds_bpermute_b32 v79, v69, v77
	v_cmp_lt_i32_e32 vcc, 0, v204
	s_and_saveexec_b64 s[0:1], vcc
	s_xor_b64 s[0:1], exec, s[0:1]
	s_cbranch_execz .LBB0_1021
	v_cmp_eq_u32_e32 vcc, 1, v204
	s_and_saveexec_b64 s[16:17], vcc
	s_cbranch_execz .LBB0_1020
	v_mov_b32_e32 v80, v5
	v_mov_b32_e32 v81, v13
	v_mov_b32_e32 v78, v77
	s_waitcnt lgkmcnt(0)
	v_mul_f32_e32 v82, v13, v79
	v_fma_f32 v78, v80, v78, v82
	v_fma_f32 v79, v81, v79, v82
	s_nop 0
	v_mov_b32_e32 v77, v78

;     __device__ __forceinline__ void operator()(const f32x4 (&acc)[2][2][4][2], const Unit& u, int wr, int wc, int fr, int fq) const {
;     ...
;                     if (reg <= 1) {
;                         if (rope) { const float cs[8] = {c0[0], c0[1], c0[2], c0[3], c1[0], c1[1], c1[2], c1[3]}; const float sn[8] = {s0[0], s0[1], s0[2], s0[3], s1[0], s1[1], s1[2], s1[3]};
; #pragma unroll
;                             for (int j = 0; j < 8; ++j) { const float o = __shfl_xor(v[j], 16); if (fq == 0) v[j] = v[j] * cs[j] - o * sn[j]; else if (fq == 1) v[j] = v[j] * cs[j] + o * sn[j]; } }
.LBB0_1021:
	s_andn2_saveexec_b64 s[0:1], s[0:1]
	s_cbranch_execz .LBB0_1023
	v_mov_b32_e32 v80, v5
	v_mov_b32_e32 v81, v13
	v_mov_b32_e32 v78, v77
	s_waitcnt lgkmcnt(0)
	v_mul_f32_e32 v82, v13, v79
	v_fma_f32 v78, v80, v78, -v82
	v_fma_f32 v79, v81, v79, -v82
	s_nop 0
	v_mov_b32_e32 v77, v78
.LBB0_1023:
	s_or_b64 exec, exec, s[0:1]
	s_waitcnt lgkmcnt(0)
	ds_bpermute_b32 v79, v69, v58
	v_cmp_lt_i32_e32 vcc, 0, v204
	s_and_saveexec_b64 s[0:1], vcc
	s_xor_b64 s[0:1], exec, s[0:1]
	s_cbranch_execz .LBB0_1027
	v_cmp_eq_u32_e32 vcc, 1, v204
	s_and_saveexec_b64 s[16:17], vcc
	s_cbranch_execz .LBB0_1026
	v_mov_b32_e32 v80, v6
	v_mov_b32_e32 v81, v14
	v_mov_b32_e32 v78, v58
	s_waitcnt lgkmcnt(0)
	v_mul_f32_e32 v58, v14, v79
	v_fma_f32 v78, v80, v78, v58
	v_fma_f32 v79, v81, v79, v58
	s_nop 0
	v_mov_b32_e32 v58, v78

;     __device__ __forceinline__ void operator()(const f32x4 (&acc)[2][2][4][2], const Unit& u, int wr, int wc, int fr, int fq) const {
;     ...
;                     if (reg <= 1) {
;                         if (rope) { const float cs[8] = {c0[0], c0[1], c0[2], c0[3], c1[0], c1[1], c1[2], c1[3]}; const float sn[8] = {s0[0], s0[1], s0[2], s0[3], s1[0], s1[1], s1[2], s1[3]};
; #pragma unroll
;                             for (int j = 0; j < 8; ++j) { const float o = __shfl_xor(v[j], 16); if (fq == 0) v[j] = v[j] * cs[j] - o * sn[j]; else if (fq == 1) v[j] = v[j] * cs[j] + o * sn[j]; } }
.LBB0_1027:
	s_andn2_saveexec_b64 s[0:1], s[0:1]
	s_cbranch_execz .LBB0_1029
	v_mov_b32_e32 v80, v6
	v_mov_b32_e32 v81, v14
	v_mov_b32_e32 v78, v58
	s_waitcnt lgkmcnt(0)
	v_mul_f32_e32 v58, v14, v79
	v_fma_f32 v78, v80, v78, -v58
	v_fma_f32 v79, v81, v79, -v58
	s_nop 0
	v_mov_b32_e32 v58, v78
.LBB0_1029:
	s_or_b64 exec, exec, s[0:1]
	s_waitcnt lgkmcnt(0)
	ds_bpermute_b32 v79, v69, v59
	v_cmp_lt_i32_e32 vcc, 0, v204
	s_and_saveexec_b64 s[0:1], vcc
	s_xor_b64 s[0:1], exec, s[0:1]
	s_cbranch_execz .LBB0_1033
	v_cmp_eq_u32_e32 vcc, 1, v204
	s_and_saveexec_b64 s[16:17], vcc
	s_cbranch_execz .LBB0_1032
	v_mov_b32_e32 v80, v7
	v_mov_b32_e32 v81, v15
	v_mov_b32_e32 v78, v59
	s_waitcnt lgkmcnt(0)
	v_mul_f32_e32 v82, v15, v79
	v_fma_f32 v78, v80, v78, v82
	v_fma_f32 v79, v81, v79, v82
	s_nop 0
	v_mov_b32_e32 v59, v78

;     __device__ __forceinline__ void operator()(const f32x4 (&acc)[2][2][4][2], const Unit& u, int wr, int wc, int fr, int fq) const {
;     ...
;                     if (reg <= 1) {
;                         if (rope) { const float cs[8] = {c0[0], c0[1], c0[2], c0[3], c1[0], c1[1], c1[2], c1[3]}; const float sn[8] = {s0[0], s0[1], s0[2], s0[3], s1[0], s1[1], s1[2], s1[3]};
; #pragma unroll
;                             for (int j = 0; j < 8; ++j) { const float o = __shfl_xor(v[j], 16); if (fq == 0) v[j] = v[j] * cs[j] - o * sn[j]; else if (fq == 1) v[j] = v[j] * cs[j] + o * sn[j]; } }
.LBB0_1033:
	s_andn2_saveexec_b64 s[0:1], s[0:1]
	s_cbranch_execz .LBB0_1035
	v_mov_b32_e32 v80, v7
	v_mov_b32_e32 v81, v15
	v_mov_b32_e32 v78, v59
	s_waitcnt lgkmcnt(0)
	v_mul_f32_e32 v82, v15, v79
	v_fma_f32 v78, v80, v78, -v82
	v_fma_f32 v79, v81, v79, -v82
	s_nop 0
	v_mov_b32_e32 v59, v78

; __device__ __forceinline__ float fexp(float x) { return __builtin_amdgcn_exp2f(x * LOG2E); }
; __device__ __forceinline__ float sigm(float x) { return __builtin_amdgcn_rcpf(1.f + fexp(-x)); }
; __device__ __forceinline__ float silu(float x) { return x * sigm(x); }
;     __device__ __forceinline__ void operator()(const f32x4 (&acc)[2][2][4][2], const Unit& u, int wr, int wc, int fr, int fq) const {
;     ...
;                     } else if (reg == PB_QR || reg == PB_G) {
; #pragma unroll
;                         for (int j = 0; j < 8; ++j) v[j] = silu(v[j]);
.LBB0_1038:
	s_andn2_b64 vcc, exec, s[0:1]
	s_cbranch_vccnz .LBB0_1040
	v_mul_f32_e32 v60, 0xbfb8aa3b, v54
	v_exp_f32_e32 v60, v60
	v_mul_f32_e32 v61, 0xbfb8aa3b, v52
	v_mul_f32_e32 v48, 0xbfb8aa3b, v58
	v_mul_f32_e32 v49, 0xbfb8aa3b, v59
	v_add_f32_e32 v60, 1.0, v60
	v_mul_f32_e32 v50, 0xbfb8aa3b, v56
	v_mul_f32_e32 v51, 0xbfb8aa3b, v57
	v_rcp_f32_e32 v62, v60
	v_mul_f32_e32 v60, 0xbfb8aa3b, v55
	v_exp_f32_e32 v61, v61
	v_mul_f32_e32 v63, 0xbfb8aa3b, v53
	v_exp_f32_e32 v48, v48
	v_exp_f32_e32 v49, v49
	v_exp_f32_e32 v50, v50
	v_exp_f32_e32 v51, v51
	v_exp_f32_e32 v60, v60
	v_exp_f32_e32 v63, v63
	v_add_f32_e32 v61, 1.0, v61
	v_add_f32_e32 v48, 1.0, v48
	v_add_f32_e32 v49, 1.0, v49
	v_add_f32_e32 v50, 1.0, v50
	v_add_f32_e32 v51, 1.0, v51
	v_add_f32_e32 v60, 1.0, v60
	v_rcp_f32_e32 v68, v61
	v_add_f32_e32 v61, 1.0, v63
	v_rcp_f32_e32 v48, v48
	v_rcp_f32_e32 v49, v49
	v_rcp_f32_e32 v50, v50
	v_rcp_f32_e32 v51, v51
	v_rcp_f32_e32 v69, v61
	v_rcp_f32_e32 v63, v60
	v_mul_f32_e32 v70, v58, v48
	v_mul_f32_e32 v71, v59, v49
	v_mul_f32_e32 v60, v56, v50
	v_mul_f32_e32 v61, v57, v51
	v_mul_f32_e32 v68, v52, v68
	v_mul_f32_e32 v69, v53, v69
	v_mul_f32_e32 v62, v54, v62
	v_mul_f32_e32 v63, v55, v63

;     __device__ __forceinline__ void operator()(const f32x4 (&acc)[2][2][4][2], const Unit& u, int wr, int wc, int fr, int fq) const {
;     ...
;                     if (reg <= 1) {
;                         if (rope) { const float cs[8] = {c0[0], c0[1], c0[2], c0[3], c1[0], c1[1], c1[2], c1[3]}; const float sn[8] = {s0[0], s0[1], s0[2], s0[3], s1[0], s1[1], s1[2], s1[3]};
; #pragma unroll
;                             for (int j = 0; j < 8; ++j) { const float o = __shfl_xor(v[j], 16); if (fq == 0) v[j] = v[j] * cs[j] - o * sn[j]; else if (fq == 1) v[j] = v[j] * cs[j] + o * sn[j]; } }
.LBB0_1041:
	s_and_b64 vcc, exec, s[10:11]
	s_cbranch_vccnz .LBB0_1344
	v_and_b32_e32 v49, 64, v214
	v_xor_b32_e32 v48, 16, v214
	v_add_u32_e32 v49, 64, v49
	v_cmp_lt_i32_e32 vcc, v48, v49
	s_nop 1
	v_cndmask_b32_e32 v48, v214, v48, vcc
	v_lshlrev_b32_e32 v70, 2, v48
	ds_bpermute_b32 v69, v70, v58
	v_cmp_lt_i32_e32 vcc, 0, v204
	s_and_saveexec_b64 s[0:1], vcc
	s_xor_b64 s[0:1], exec, s[0:1]
	s_cbranch_execz .LBB0_1046
	v_cmp_eq_u32_e32 vcc, 1, v204
	v_mov_b32_e32 v51, v53
	v_mov_b32_e32 v50, v52
	v_mov_b32_e32 v63, v55
	v_mov_b32_e32 v62, v54
	v_mov_b32_e32 v61, v57
	v_mov_b32_e32 v60, v56
	v_mov_b32_e32 v49, v59
	v_mov_b32_e32 v48, v58
	s_and_saveexec_b64 s[16:17], vcc
	s_cbranch_execz .LBB0_1045
	v_mov_b32_e32 v48, v58
	v_mov_b32_e32 v49, v20
	v_mov_b32_e32 v68, v16
	s_waitcnt lgkmcnt(0)
	v_mul_f32_e32 v48, v48, v68
	v_mul_f32_e32 v49, v49, v69
	v_mov_b32_e32 v51, v53
	v_add_f32_e32 v48, v48, v49
	v_mov_b32_e32 v50, v52
	v_mov_b32_e32 v63, v55
	v_mov_b32_e32 v62, v54
	v_mov_b32_e32 v61, v57
	v_mov_b32_e32 v60, v56
	v_mov_b32_e32 v49, v59

;     __device__ __forceinline__ void operator()(const f32x4 (&acc)[2][2][4][2], const Unit& u, int wr, int wc, int fr, int fq) const {
;     ...
;                     if (reg <= 1) {
;                         if (rope) { const float cs[8] = {c0[0], c0[1], c0[2], c0[3], c1[0], c1[1], c1[2], c1[3]}; const float sn[8] = {s0[0], s0[1], s0[2], s0[3], s1[0], s1[1], s1[2], s1[3]};
; #pragma unroll
;                             for (int j = 0; j < 8; ++j) { const float o = __shfl_xor(v[j], 16); if (fq == 0) v[j] = v[j] * cs[j] - o * sn[j]; else if (fq == 1) v[j] = v[j] * cs[j] + o * sn[j]; } }
.LBB0_1046:
	s_andn2_saveexec_b64 s[0:1], s[0:1]
	s_cbranch_execz .LBB0_1048
	v_mov_b32_e32 v48, v58
	v_mov_b32_e32 v49, v20
	v_mov_b32_e32 v68, v16
	s_waitcnt lgkmcnt(0)
	v_mul_f32_e32 v48, v48, v68
	v_mul_f32_e32 v49, v49, v69
	v_mov_b32_e32 v60, v56
	v_sub_f32_e32 v48, v48, v49
	v_mov_b32_e32 v49, v59
	v_mov_b32_e32 v61, v57
	v_mov_b32_e32 v62, v54
	v_mov_b32_e32 v63, v55
	v_mov_b32_e32 v50, v52
	v_mov_b32_e32 v51, v53
.LBB0_1048:
	s_or_b64 exec, exec, s[0:1]
	s_waitcnt lgkmcnt(0)
	ds_bpermute_b32 v69, v70, v49
	v_cmp_lt_i32_e32 vcc, 0, v204
	s_and_saveexec_b64 s[0:1], vcc
	s_xor_b64 s[0:1], exec, s[0:1]
	s_cbranch_execz .LBB0_1052
	v_cmp_eq_u32_e32 vcc, 1, v204
	s_and_saveexec_b64 s[16:17], vcc
	s_cbranch_execz .LBB0_1051
	v_mov_b32_e32 v72, v17
	v_mov_b32_e32 v73, v21
	v_mov_b32_e32 v68, v49
	v_mul_f32_e32 v74, v17, v49
	s_waitcnt lgkmcnt(0)
	v_fma_f32 v68, v72, v68, v74
	v_fma_f32 v69, v73, v69, v74
	s_nop 0
	v_mov_b32_e32 v49, v69

;     __device__ __forceinline__ void operator()(const f32x4 (&acc)[2][2][4][2], const Unit& u, int wr, int wc, int fr, int fq) const {
;     ...
;                     if (reg <= 1) {
;                         if (rope) { const float cs[8] = {c0[0], c0[1], c0[2], c0[3], c1[0], c1[1], c1[2], c1[3]}; const float sn[8] = {s0[0], s0[1], s0[2], s0[3], s1[0], s1[1], s1[2], s1[3]};
; #pragma unroll
;                             for (int j = 0; j < 8; ++j) { const float o = __shfl_xor(v[j], 16); if (fq == 0) v[j] = v[j] * cs[j] - o * sn[j]; else if (fq == 1) v[j] = v[j] * cs[j] + o * sn[j]; } }
.LBB0_1052:
	s_andn2_saveexec_b64 s[0:1], s[0:1]
	s_cbranch_execz .LBB0_1054
	v_mov_b32_e32 v72, v17
	v_mov_b32_e32 v73, v21
	v_mov_b32_e32 v68, v49
	v_mul_f32_e32 v74, v17, v49
	s_waitcnt lgkmcnt(0)
	v_fma_f32 v68, -v72, v68, v74
	v_fma_f32 v69, -v73, v69, v74
	s_nop 0
	v_mov_b32_e32 v49, v69
.LBB0_1054:
	s_or_b64 exec, exec, s[0:1]
	s_waitcnt lgkmcnt(0)
	ds_bpermute_b32 v69, v70, v60
	v_cmp_lt_i32_e32 vcc, 0, v204
	s_and_saveexec_b64 s[0:1], vcc
	s_xor_b64 s[0:1], exec, s[0:1]
	s_cbranch_execz .LBB0_1058
	v_cmp_eq_u32_e32 vcc, 1, v204
	s_and_saveexec_b64 s[16:17], vcc
	s_cbranch_execz .LBB0_1057
	v_mov_b32_e32 v72, v18
	v_mov_b32_e32 v73, v22
	v_mov_b32_e32 v68, v60
	s_waitcnt lgkmcnt(0)
	v_mul_f32_e32 v60, v22, v69
	v_fma_f32 v68, v72, v68, v60
	v_fma_f32 v69, v73, v69, v60
	s_nop 0
	v_mov_b32_e32 v60, v68

;     __device__ __forceinline__ void operator()(const f32x4 (&acc)[2][2][4][2], const Unit& u, int wr, int wc, int fr, int fq) const {
;     ...
;                     if (reg <= 1) {
;                         if (rope) { const float cs[8] = {c0[0], c0[1], c0[2], c0[3], c1[0], c1[1], c1[2], c1[3]}; const float sn[8] = {s0[0], s0[1], s0[2], s0[3], s1[0], s1[1], s1[2], s1[3]};
; #pragma unroll
;                             for (int j = 0; j < 8; ++j) { const float o = __shfl_xor(v[j], 16); if (fq == 0) v[j] = v[j] * cs[j] - o * sn[j]; else if (fq == 1) v[j] = v[j] * cs[j] + o * sn[j]; } }
.LBB0_1058:
	s_andn2_saveexec_b64 s[0:1], s[0:1]
	s_cbranch_execz .LBB0_1060
	v_mov_b32_e32 v72, v18
	v_mov_b32_e32 v73, v22
	v_mov_b32_e32 v68, v60
	s_waitcnt lgkmcnt(0)
	v_mul_f32_e32 v60, v22, v69
	v_fma_f32 v68, v72, v68, -v60
	v_fma_f32 v69, v73, v69, -v60
	s_nop 0
	v_mov_b32_e32 v60, v68
.LBB0_1060:
	s_or_b64 exec, exec, s[0:1]
	s_waitcnt lgkmcnt(0)
	ds_bpermute_b32 v69, v70, v61
	v_cmp_lt_i32_e32 vcc, 0, v204
	s_and_saveexec_b64 s[0:1], vcc
	s_xor_b64 s[0:1], exec, s[0:1]
	s_cbranch_execz .LBB0_1064
	v_cmp_eq_u32_e32 vcc, 1, v204
	s_and_saveexec_b64 s[16:17], vcc
	s_cbranch_execz .LBB0_1063
	v_mov_b32_e32 v72, v19
	v_mov_b32_e32 v73, v23
	v_mov_b32_e32 v68, v61
	s_waitcnt lgkmcnt(0)
	v_mul_f32_e32 v74, v23, v69
	v_fma_f32 v68, v72, v68, v74
	v_fma_f32 v69, v73, v69, v74
	s_nop 0
	v_mov_b32_e32 v61, v68

;     __device__ __forceinline__ void operator()(const f32x4 (&acc)[2][2][4][2], const Unit& u, int wr, int wc, int fr, int fq) const {
;     ...
;                     if (reg <= 1) {
;                         if (rope) { const float cs[8] = {c0[0], c0[1], c0[2], c0[3], c1[0], c1[1], c1[2], c1[3]}; const float sn[8] = {s0[0], s0[1], s0[2], s0[3], s1[0], s1[1], s1[2], s1[3]};
; #pragma unroll
;                             for (int j = 0; j < 8; ++j) { const float o = __shfl_xor(v[j], 16); if (fq == 0) v[j] = v[j] * cs[j] - o * sn[j]; else if (fq == 1) v[j] = v[j] * cs[j] + o * sn[j]; } }
.LBB0_1064:
	s_andn2_saveexec_b64 s[0:1], s[0:1]
	s_cbranch_execz .LBB0_1066
	v_mov_b32_e32 v72, v19
	v_mov_b32_e32 v73, v23
	v_mov_b32_e32 v68, v61
	s_waitcnt lgkmcnt(0)
	v_mul_f32_e32 v74, v23, v69
	v_fma_f32 v68, v72, v68, -v74
	v_fma_f32 v69, v73, v69, -v74
	s_nop 0
	v_mov_b32_e32 v61, v68
.LBB0_1066:
	s_or_b64 exec, exec, s[0:1]
	s_waitcnt lgkmcnt(0)
	ds_bpermute_b32 v69, v70, v62
	v_cmp_lt_i32_e32 vcc, 0, v204
	s_and_saveexec_b64 s[0:1], vcc
	s_xor_b64 s[0:1], exec, s[0:1]
	s_cbranch_execz .LBB0_1070
	v_cmp_eq_u32_e32 vcc, 1, v204
	s_and_saveexec_b64 s[16:17], vcc
	s_cbranch_execz .LBB0_1069
	v_mov_b32_e32 v72, v4
	v_mov_b32_e32 v73, v12
	v_mov_b32_e32 v68, v62
	s_waitcnt lgkmcnt(0)
	v_mul_f32_e32 v62, v12, v69
	v_fma_f32 v68, v72, v68, v62
	v_fma_f32 v69, v73, v69, v62
	s_nop 0
	v_mov_b32_e32 v62, v68

;     __device__ __forceinline__ void operator()(const f32x4 (&acc)[2][2][4][2], const Unit& u, int wr, int wc, int fr, int fq) const {
;     ...
;                     if (reg <= 1) {
;                         if (rope) { const float cs[8] = {c0[0], c0[1], c0[2], c0[3], c1[0], c1[1], c1[2], c1[3]}; const float sn[8] = {s0[0], s0[1], s0[2], s0[3], s1[0], s1[1], s1[2], s1[3]};
; #pragma unroll
;                             for (int j = 0; j < 8; ++j) { const float o = __shfl_xor(v[j], 16); if (fq == 0) v[j] = v[j] * cs[j] - o * sn[j]; else if (fq == 1) v[j] = v[j] * cs[j] + o * sn[j]; } }
.LBB0_1070:
	s_andn2_saveexec_b64 s[0:1], s[0:1]
	s_cbranch_execz .LBB0_1072
	v_mov_b32_e32 v72, v4
	v_mov_b32_e32 v73, v12
	v_mov_b32_e32 v68, v62
	s_waitcnt lgkmcnt(0)
	v_mul_f32_e32 v62, v12, v69
	v_fma_f32 v68, v72, v68, -v62
	v_fma_f32 v69, v73, v69, -v62
	s_nop 0
	v_mov_b32_e32 v62, v68
.LBB0_1072:
	s_or_b64 exec, exec, s[0:1]
	s_waitcnt lgkmcnt(0)
	ds_bpermute_b32 v69, v70, v63
	v_cmp_lt_i32_e32 vcc, 0, v204
	s_and_saveexec_b64 s[0:1], vcc
	s_xor_b64 s[0:1], exec, s[0:1]
	s_cbranch_execz .LBB0_1076
	v_cmp_eq_u32_e32 vcc, 1, v204
	s_and_saveexec_b64 s[16:17], vcc
	s_cbranch_execz .LBB0_1075
	v_mov_b32_e32 v72, v5
	v_mov_b32_e32 v73, v13
	v_mov_b32_e32 v68, v63
	s_waitcnt lgkmcnt(0)
	v_mul_f32_e32 v74, v13, v69
	v_fma_f32 v68, v72, v68, v74
	v_fma_f32 v69, v73, v69, v74
	s_nop 0
	v_mov_b32_e32 v63, v68

;     __device__ __forceinline__ void operator()(const f32x4 (&acc)[2][2][4][2], const Unit& u, int wr, int wc, int fr, int fq) const {
;     ...
;                     if (reg <= 1) {
;                         if (rope) { const float cs[8] = {c0[0], c0[1], c0[2], c0[3], c1[0], c1[1], c1[2], c1[3]}; const float sn[8] = {s0[0], s0[1], s0[2], s0[3], s1[0], s1[1], s1[2], s1[3]};
; #pragma unroll
;                             for (int j = 0; j < 8; ++j) { const float o = __shfl_xor(v[j], 16); if (fq == 0) v[j] = v[j] * cs[j] - o * sn[j]; else if (fq == 1) v[j] = v[j] * cs[j] + o * sn[j]; } }
.LBB0_1076:
	s_andn2_saveexec_b64 s[0:1], s[0:1]
	s_cbranch_execz .LBB0_1078
	v_mov_b32_e32 v72, v5
	v_mov_b32_e32 v73, v13
	v_mov_b32_e32 v68, v63
	s_waitcnt lgkmcnt(0)
	v_mul_f32_e32 v74, v13, v69
	v_fma_f32 v68, v72, v68, -v74
	v_fma_f32 v69, v73, v69, -v74
	s_nop 0
	v_mov_b32_e32 v63, v68
.LBB0_1078:
	s_or_b64 exec, exec, s[0:1]
	s_waitcnt lgkmcnt(0)
	ds_bpermute_b32 v69, v70, v50
	v_cmp_lt_i32_e32 vcc, 0, v204
	s_and_saveexec_b64 s[0:1], vcc
	s_xor_b64 s[0:1], exec, s[0:1]
	s_cbranch_execz .LBB0_1082
	v_cmp_eq_u32_e32 vcc, 1, v204
	s_and_saveexec_b64 s[16:17], vcc
	s_cbranch_execz .LBB0_1081
	v_mov_b32_e32 v72, v6
	v_mov_b32_e32 v73, v14
	v_mov_b32_e32 v68, v50
	s_waitcnt lgkmcnt(0)
	v_mul_f32_e32 v50, v14, v69
	v_fma_f32 v68, v72, v68, v50
	v_fma_f32 v69, v73, v69, v50
	s_nop 0
	v_mov_b32_e32 v50, v68

;     __device__ __forceinline__ void operator()(const f32x4 (&acc)[2][2][4][2], const Unit& u, int wr, int wc, int fr, int fq) const {
;     ...
;                     if (reg <= 1) {
;                         if (rope) { const float cs[8] = {c0[0], c0[1], c0[2], c0[3], c1[0], c1[1], c1[2], c1[3]}; const float sn[8] = {s0[0], s0[1], s0[2], s0[3], s1[0], s1[1], s1[2], s1[3]};
; #pragma unroll
;                             for (int j = 0; j < 8; ++j) { const float o = __shfl_xor(v[j], 16); if (fq == 0) v[j] = v[j] * cs[j] - o * sn[j]; else if (fq == 1) v[j] = v[j] * cs[j] + o * sn[j]; } }
.LBB0_1082:
	s_andn2_saveexec_b64 s[0:1], s[0:1]
	s_cbranch_execz .LBB0_1084
	v_mov_b32_e32 v72, v6
	v_mov_b32_e32 v73, v14
	v_mov_b32_e32 v68, v50
	s_waitcnt lgkmcnt(0)
	v_mul_f32_e32 v50, v14, v69
	v_fma_f32 v68, v72, v68, -v50
	v_fma_f32 v69, v73, v69, -v50
	s_nop 0
	v_mov_b32_e32 v50, v68
.LBB0_1084:
	s_or_b64 exec, exec, s[0:1]
	s_waitcnt lgkmcnt(0)
	ds_bpermute_b32 v69, v70, v51
	v_cmp_lt_i32_e32 vcc, 0, v204
	s_and_saveexec_b64 s[0:1], vcc
	s_xor_b64 s[0:1], exec, s[0:1]
	s_cbranch_execz .LBB0_1088
	v_cmp_eq_u32_e32 vcc, 1, v204
	s_and_saveexec_b64 s[16:17], vcc
	s_cbranch_execz .LBB0_1087
	v_mov_b32_e32 v70, v7
	v_mov_b32_e32 v71, v15
	v_mov_b32_e32 v68, v51
	s_waitcnt lgkmcnt(0)
	v_mul_f32_e32 v72, v15, v69
	v_fma_f32 v68, v70, v68, v72
	v_fma_f32 v69, v71, v69, v72
	s_nop 0
	v_mov_b32_e32 v51, v68

;     __device__ __forceinline__ void operator()(const f32x4 (&acc)[2][2][4][2], const Unit& u, int wr, int wc, int fr, int fq) const {
;     ...
;                     if (reg <= 1) {
;                         if (rope) { const float cs[8] = {c0[0], c0[1], c0[2], c0[3], c1[0], c1[1], c1[2], c1[3]}; const float sn[8] = {s0[0], s0[1], s0[2], s0[3], s1[0], s1[1], s1[2], s1[3]};
; #pragma unroll
;                             for (int j = 0; j < 8; ++j) { const float o = __shfl_xor(v[j], 16); if (fq == 0) v[j] = v[j] * cs[j] - o * sn[j]; else if (fq == 1) v[j] = v[j] * cs[j] + o * sn[j]; } }
.LBB0_1088:
	s_andn2_saveexec_b64 s[0:1], s[0:1]
	s_cbranch_execz .LBB0_1090
	v_mov_b32_e32 v70, v7
	v_mov_b32_e32 v71, v15
	v_mov_b32_e32 v68, v51
	s_waitcnt lgkmcnt(0)
	v_mul_f32_e32 v72, v15, v69
	v_fma_f32 v68, v70, v68, -v72
	v_fma_f32 v69, v71, v69, -v72
	s_nop 0
	v_mov_b32_e32 v51, v68

; __device__ __forceinline__ float fexp(float x) { return __builtin_amdgcn_exp2f(x * LOG2E); }
; __device__ __forceinline__ float sigm(float x) { return __builtin_amdgcn_rcpf(1.f + fexp(-x)); }
; __device__ __forceinline__ float silu(float x) { return x * sigm(x); }
;     __device__ __forceinline__ void operator()(const f32x4 (&acc)[2][2][4][2], const Unit& u, int wr, int wc, int fr, int fq) const {
;     ...
;                     } else if (reg == PB_QR || reg == PB_G) {
; #pragma unroll
;                         for (int j = 0; j < 8; ++j) v[j] = silu(v[j]);
.LBB0_1093:
	s_andn2_b64 vcc, exec, s[0:1]
	s_cbranch_vccnz .LBB0_1095
	v_mul_f32_e32 v53, 0xbfb8aa3b, v46
	v_exp_f32_e32 v53, v53
	v_mul_f32_e32 v58, 0xbfb8aa3b, v44
	v_mul_f32_e32 v40, 0xbfb8aa3b, v56
	v_mul_f32_e32 v41, 0xbfb8aa3b, v57
	v_add_f32_e32 v53, 1.0, v53
	v_mul_f32_e32 v42, 0xbfb8aa3b, v54
	v_mul_f32_e32 v43, 0xbfb8aa3b, v55
	v_rcp_f32_e32 v60, v53
	v_mul_f32_e32 v53, 0xbfb8aa3b, v47
	v_exp_f32_e32 v58, v58
	v_mul_f32_e32 v59, 0xbfb8aa3b, v45
	v_exp_f32_e32 v40, v40
	v_exp_f32_e32 v41, v41
	v_exp_f32_e32 v42, v42
	v_exp_f32_e32 v43, v43
	v_exp_f32_e32 v53, v53
	v_exp_f32_e32 v59, v59
	v_add_f32_e32 v58, 1.0, v58
	v_add_f32_e32 v40, 1.0, v40
	v_add_f32_e32 v41, 1.0, v41
	v_add_f32_e32 v42, 1.0, v42
	v_add_f32_e32 v43, 1.0, v43
	v_add_f32_e32 v53, 1.0, v53
	v_rcp_f32_e32 v62, v58
	v_add_f32_e32 v58, 1.0, v59
	v_rcp_f32_e32 v40, v40
	v_rcp_f32_e32 v41, v41
	v_rcp_f32_e32 v42, v42
	v_rcp_f32_e32 v43, v43
	v_rcp_f32_e32 v63, v58
	v_rcp_f32_e32 v61, v53
	v_mul_f32_e32 v64, v56, v40
	v_mul_f32_e32 v65, v57, v41
	v_mul_f32_e32 v58, v54, v42
	v_mul_f32_e32 v59, v55, v43
	v_mul_f32_e32 v62, v44, v62
	v_mul_f32_e32 v63, v45, v63
	v_mul_f32_e32 v60, v46, v60
	v_mul_f32_e32 v61, v47, v61

;     __device__ __forceinline__ void operator()(const f32x4 (&acc)[2][2][4][2], const Unit& u, int wr, int wc, int fr, int fq) const {
;     ...
;                     if (reg <= 1) {
;                         if (rope) { const float cs[8] = {c0[0], c0[1], c0[2], c0[3], c1[0], c1[1], c1[2], c1[3]}; const float sn[8] = {s0[0], s0[1], s0[2], s0[3], s1[0], s1[1], s1[2], s1[3]};
; #pragma unroll
;                             for (int j = 0; j < 8; ++j) { const float o = __shfl_xor(v[j], 16); if (fq == 0) v[j] = v[j] * cs[j] - o * sn[j]; else if (fq == 1) v[j] = v[j] * cs[j] + o * sn[j]; } }
.LBB0_1096:
	s_and_b64 vcc, exec, s[10:11]
	s_cbranch_vccnz .LBB0_1347
	v_and_b32_e32 v41, 64, v214
	v_xor_b32_e32 v40, 16, v214
	v_add_u32_e32 v41, 64, v41
	v_cmp_lt_i32_e32 vcc, v40, v41
	s_nop 1
	v_cndmask_b32_e32 v40, v214, v40, vcc
	v_lshlrev_b32_e32 v53, 2, v40
	ds_bpermute_b32 v63, v53, v56
	v_cmp_lt_i32_e32 vcc, 0, v204
	s_and_saveexec_b64 s[0:1], vcc
	s_xor_b64 s[0:1], exec, s[0:1]
	s_cbranch_execz .LBB0_1101
	v_cmp_eq_u32_e32 vcc, 1, v204
	v_mov_b32_e32 v43, v45
	v_mov_b32_e32 v42, v44
	v_mov_b32_e32 v61, v47
	v_mov_b32_e32 v60, v46
	v_mov_b32_e32 v59, v55
	v_mov_b32_e32 v58, v54
	v_mov_b32_e32 v41, v57
	v_mov_b32_e32 v40, v56
	s_and_saveexec_b64 s[16:17], vcc
	s_cbranch_execz .LBB0_1100
	v_mov_b32_e32 v40, v56
	v_mov_b32_e32 v41, v20
	v_mov_b32_e32 v62, v16
	s_waitcnt lgkmcnt(0)
	v_mul_f32_e32 v40, v40, v62
	v_mul_f32_e32 v41, v41, v63
	v_mov_b32_e32 v43, v45
	v_add_f32_e32 v40, v40, v41
	v_mov_b32_e32 v42, v44
	v_mov_b32_e32 v61, v47
	v_mov_b32_e32 v60, v46
	v_mov_b32_e32 v59, v55
	v_mov_b32_e32 v58, v54
	v_mov_b32_e32 v41, v57

;     __device__ __forceinline__ void operator()(const f32x4 (&acc)[2][2][4][2], const Unit& u, int wr, int wc, int fr, int fq) const {
;     ...
;                     if (reg <= 1) {
;                         if (rope) { const float cs[8] = {c0[0], c0[1], c0[2], c0[3], c1[0], c1[1], c1[2], c1[3]}; const float sn[8] = {s0[0], s0[1], s0[2], s0[3], s1[0], s1[1], s1[2], s1[3]};
; #pragma unroll
;                             for (int j = 0; j < 8; ++j) { const float o = __shfl_xor(v[j], 16); if (fq == 0) v[j] = v[j] * cs[j] - o * sn[j]; else if (fq == 1) v[j] = v[j] * cs[j] + o * sn[j]; } }
.LBB0_1101:
	s_andn2_saveexec_b64 s[0:1], s[0:1]
	s_cbranch_execz .LBB0_1103
	v_mov_b32_e32 v40, v56
	v_mov_b32_e32 v41, v20
	v_mov_b32_e32 v62, v16
	s_waitcnt lgkmcnt(0)
	v_mul_f32_e32 v40, v40, v62
	v_mul_f32_e32 v41, v41, v63
	v_mov_b32_e32 v58, v54
	v_sub_f32_e32 v40, v40, v41
	v_mov_b32_e32 v41, v57
	v_mov_b32_e32 v59, v55
	v_mov_b32_e32 v60, v46
	v_mov_b32_e32 v61, v47
	v_mov_b32_e32 v42, v44
	v_mov_b32_e32 v43, v45
.LBB0_1103:
	s_or_b64 exec, exec, s[0:1]
	s_waitcnt lgkmcnt(0)
	ds_bpermute_b32 v63, v53, v41
	v_cmp_lt_i32_e32 vcc, 0, v204
	s_and_saveexec_b64 s[0:1], vcc
	s_xor_b64 s[0:1], exec, s[0:1]
	s_cbranch_execz .LBB0_1107
	v_cmp_eq_u32_e32 vcc, 1, v204
	s_and_saveexec_b64 s[16:17], vcc
	s_cbranch_execz .LBB0_1106
	v_mov_b32_e32 v64, v17
	v_mov_b32_e32 v65, v21
	v_mov_b32_e32 v62, v41
	v_mul_f32_e32 v66, v17, v41
	s_waitcnt lgkmcnt(0)
	v_fma_f32 v62, v64, v62, v66
	v_fma_f32 v63, v65, v63, v66
	s_nop 0
	v_mov_b32_e32 v41, v63

;     __device__ __forceinline__ void operator()(const f32x4 (&acc)[2][2][4][2], const Unit& u, int wr, int wc, int fr, int fq) const {
;     ...
;                     if (reg <= 1) {
;                         if (rope) { const float cs[8] = {c0[0], c0[1], c0[2], c0[3], c1[0], c1[1], c1[2], c1[3]}; const float sn[8] = {s0[0], s0[1], s0[2], s0[3], s1[0], s1[1], s1[2], s1[3]};
; #pragma unroll
;                             for (int j = 0; j < 8; ++j) { const float o = __shfl_xor(v[j], 16); if (fq == 0) v[j] = v[j] * cs[j] - o * sn[j]; else if (fq == 1) v[j] = v[j] * cs[j] + o * sn[j]; } }
.LBB0_1107:
	s_andn2_saveexec_b64 s[0:1], s[0:1]
	s_cbranch_execz .LBB0_1109
	v_mov_b32_e32 v64, v17
	v_mov_b32_e32 v65, v21
	v_mov_b32_e32 v62, v41
	v_mul_f32_e32 v66, v17, v41
	s_waitcnt lgkmcnt(0)
	v_fma_f32 v62, -v64, v62, v66
	v_fma_f32 v63, -v65, v63, v66
	s_nop 0
	v_mov_b32_e32 v41, v63
.LBB0_1109:
	s_or_b64 exec, exec, s[0:1]
	s_waitcnt lgkmcnt(0)
	ds_bpermute_b32 v63, v53, v58
	v_cmp_lt_i32_e32 vcc, 0, v204
	s_and_saveexec_b64 s[0:1], vcc
	s_xor_b64 s[0:1], exec, s[0:1]
	s_cbranch_execz .LBB0_1113
	v_cmp_eq_u32_e32 vcc, 1, v204
	s_and_saveexec_b64 s[16:17], vcc
	s_cbranch_execz .LBB0_1112
	v_mov_b32_e32 v64, v18
	v_mov_b32_e32 v65, v22
	v_mov_b32_e32 v62, v58
	s_waitcnt lgkmcnt(0)
	v_mul_f32_e32 v58, v22, v63
	v_fma_f32 v62, v64, v62, v58
	v_fma_f32 v63, v65, v63, v58
	s_nop 0
	v_mov_b32_e32 v58, v62

;     __device__ __forceinline__ void operator()(const f32x4 (&acc)[2][2][4][2], const Unit& u, int wr, int wc, int fr, int fq) const {
;     ...
;                     if (reg <= 1) {
;                         if (rope) { const float cs[8] = {c0[0], c0[1], c0[2], c0[3], c1[0], c1[1], c1[2], c1[3]}; const float sn[8] = {s0[0], s0[1], s0[2], s0[3], s1[0], s1[1], s1[2], s1[3]};
; #pragma unroll
;                             for (int j = 0; j < 8; ++j) { const float o = __shfl_xor(v[j], 16); if (fq == 0) v[j] = v[j] * cs[j] - o * sn[j]; else if (fq == 1) v[j] = v[j] * cs[j] + o * sn[j]; } }
.LBB0_1113:
	s_andn2_saveexec_b64 s[0:1], s[0:1]
	s_cbranch_execz .LBB0_1115
	v_mov_b32_e32 v64, v18
	v_mov_b32_e32 v65, v22
	v_mov_b32_e32 v62, v58
	s_waitcnt lgkmcnt(0)
	v_mul_f32_e32 v58, v22, v63
	v_fma_f32 v62, v64, v62, -v58
	v_fma_f32 v63, v65, v63, -v58
	s_nop 0
	v_mov_b32_e32 v58, v62
.LBB0_1115:
	s_or_b64 exec, exec, s[0:1]
	s_waitcnt lgkmcnt(0)
	ds_bpermute_b32 v63, v53, v59
	v_cmp_lt_i32_e32 vcc, 0, v204
	s_and_saveexec_b64 s[0:1], vcc
	s_xor_b64 s[0:1], exec, s[0:1]
	s_cbranch_execz .LBB0_1119
	v_cmp_eq_u32_e32 vcc, 1, v204
	s_and_saveexec_b64 s[16:17], vcc
	s_cbranch_execz .LBB0_1118
	v_mov_b32_e32 v64, v19
	v_mov_b32_e32 v65, v23
	v_mov_b32_e32 v62, v59
	s_waitcnt lgkmcnt(0)
	v_mul_f32_e32 v66, v23, v63
	v_fma_f32 v62, v64, v62, v66
	v_fma_f32 v63, v65, v63, v66
	s_nop 0
	v_mov_b32_e32 v59, v62

;     __device__ __forceinline__ void operator()(const f32x4 (&acc)[2][2][4][2], const Unit& u, int wr, int wc, int fr, int fq) const {
;     ...
;                     if (reg <= 1) {
;                         if (rope) { const float cs[8] = {c0[0], c0[1], c0[2], c0[3], c1[0], c1[1], c1[2], c1[3]}; const float sn[8] = {s0[0], s0[1], s0[2], s0[3], s1[0], s1[1], s1[2], s1[3]};
; #pragma unroll
;                             for (int j = 0; j < 8; ++j) { const float o = __shfl_xor(v[j], 16); if (fq == 0) v[j] = v[j] * cs[j] - o * sn[j]; else if (fq == 1) v[j] = v[j] * cs[j] + o * sn[j]; } }
.LBB0_1119:
	s_andn2_saveexec_b64 s[0:1], s[0:1]
	s_cbranch_execz .LBB0_1121
	v_mov_b32_e32 v64, v19
	v_mov_b32_e32 v65, v23
	v_mov_b32_e32 v62, v59
	s_waitcnt lgkmcnt(0)
	v_mul_f32_e32 v66, v23, v63
	v_fma_f32 v62, v64, v62, -v66
	v_fma_f32 v63, v65, v63, -v66
	s_nop 0
	v_mov_b32_e32 v59, v62
.LBB0_1121:
	s_or_b64 exec, exec, s[0:1]
	s_waitcnt lgkmcnt(0)
	ds_bpermute_b32 v63, v53, v60
	v_cmp_lt_i32_e32 vcc, 0, v204
	s_and_saveexec_b64 s[0:1], vcc
	s_xor_b64 s[0:1], exec, s[0:1]
	s_cbranch_execz .LBB0_1125
	v_cmp_eq_u32_e32 vcc, 1, v204
	s_and_saveexec_b64 s[16:17], vcc
	s_cbranch_execz .LBB0_1124
	v_mov_b32_e32 v64, v4
	v_mov_b32_e32 v65, v12
	v_mov_b32_e32 v62, v60
	s_waitcnt lgkmcnt(0)
	v_mul_f32_e32 v60, v12, v63
	v_fma_f32 v62, v64, v62, v60
	v_fma_f32 v63, v65, v63, v60
	s_nop 0
	v_mov_b32_e32 v60, v62

;     __device__ __forceinline__ void operator()(const f32x4 (&acc)[2][2][4][2], const Unit& u, int wr, int wc, int fr, int fq) const {
;     ...
;                     if (reg <= 1) {
;                         if (rope) { const float cs[8] = {c0[0], c0[1], c0[2], c0[3], c1[0], c1[1], c1[2], c1[3]}; const float sn[8] = {s0[0], s0[1], s0[2], s0[3], s1[0], s1[1], s1[2], s1[3]};
; #pragma unroll
;                             for (int j = 0; j < 8; ++j) { const float o = __shfl_xor(v[j], 16); if (fq == 0) v[j] = v[j] * cs[j] - o * sn[j]; else if (fq == 1) v[j] = v[j] * cs[j] + o * sn[j]; } }
.LBB0_1125:
	s_andn2_saveexec_b64 s[0:1], s[0:1]
	s_cbranch_execz .LBB0_1127
	v_mov_b32_e32 v64, v4
	v_mov_b32_e32 v65, v12
	v_mov_b32_e32 v62, v60
	s_waitcnt lgkmcnt(0)
	v_mul_f32_e32 v60, v12, v63
	v_fma_f32 v62, v64, v62, -v60
	v_fma_f32 v63, v65, v63, -v60
	s_nop 0
	v_mov_b32_e32 v60, v62
.LBB0_1127:
	s_or_b64 exec, exec, s[0:1]
	s_waitcnt lgkmcnt(0)
	ds_bpermute_b32 v63, v53, v61
	v_cmp_lt_i32_e32 vcc, 0, v204
	s_and_saveexec_b64 s[0:1], vcc
	s_xor_b64 s[0:1], exec, s[0:1]
	s_cbranch_execz .LBB0_1131
	v_cmp_eq_u32_e32 vcc, 1, v204
	s_and_saveexec_b64 s[16:17], vcc
	s_cbranch_execz .LBB0_1130
	v_mov_b32_e32 v64, v5
	v_mov_b32_e32 v65, v13
	v_mov_b32_e32 v62, v61
	s_waitcnt lgkmcnt(0)
	v_mul_f32_e32 v66, v13, v63
	v_fma_f32 v62, v64, v62, v66
	v_fma_f32 v63, v65, v63, v66
	s_nop 0
	v_mov_b32_e32 v61, v62

;     __device__ __forceinline__ void operator()(const f32x4 (&acc)[2][2][4][2], const Unit& u, int wr, int wc, int fr, int fq) const {
;     ...
;                     if (reg <= 1) {
;                         if (rope) { const float cs[8] = {c0[0], c0[1], c0[2], c0[3], c1[0], c1[1], c1[2], c1[3]}; const float sn[8] = {s0[0], s0[1], s0[2], s0[3], s1[0], s1[1], s1[2], s1[3]};
; #pragma unroll
;                             for (int j = 0; j < 8; ++j) { const float o = __shfl_xor(v[j], 16); if (fq == 0) v[j] = v[j] * cs[j] - o * sn[j]; else if (fq == 1) v[j] = v[j] * cs[j] + o * sn[j]; } }
.LBB0_1131:
	s_andn2_saveexec_b64 s[0:1], s[0:1]
	s_cbranch_execz .LBB0_1133
	v_mov_b32_e32 v64, v5
	v_mov_b32_e32 v65, v13
	v_mov_b32_e32 v62, v61
	s_waitcnt lgkmcnt(0)
	v_mul_f32_e32 v66, v13, v63
	v_fma_f32 v62, v64, v62, -v66
	v_fma_f32 v63, v65, v63, -v66
	s_nop 0
	v_mov_b32_e32 v61, v62
.LBB0_1133:
	s_or_b64 exec, exec, s[0:1]
	s_waitcnt lgkmcnt(0)
	ds_bpermute_b32 v63, v53, v42
	v_cmp_lt_i32_e32 vcc, 0, v204
	s_and_saveexec_b64 s[0:1], vcc
	s_xor_b64 s[0:1], exec, s[0:1]
	s_cbranch_execz .LBB0_1137
	v_cmp_eq_u32_e32 vcc, 1, v204
	s_and_saveexec_b64 s[16:17], vcc
	s_cbranch_execz .LBB0_1136
	v_mov_b32_e32 v64, v6
	v_mov_b32_e32 v65, v14
	v_mov_b32_e32 v62, v42
	s_waitcnt lgkmcnt(0)
	v_mul_f32_e32 v42, v14, v63
	v_fma_f32 v62, v64, v62, v42
	v_fma_f32 v63, v65, v63, v42
	s_nop 0
	v_mov_b32_e32 v42, v62

;     __device__ __forceinline__ void operator()(const f32x4 (&acc)[2][2][4][2], const Unit& u, int wr, int wc, int fr, int fq) const {
;     ...
;                     if (reg <= 1) {
;                         if (rope) { const float cs[8] = {c0[0], c0[1], c0[2], c0[3], c1[0], c1[1], c1[2], c1[3]}; const float sn[8] = {s0[0], s0[1], s0[2], s0[3], s1[0], s1[1], s1[2], s1[3]};
; #pragma unroll
;                             for (int j = 0; j < 8; ++j) { const float o = __shfl_xor(v[j], 16); if (fq == 0) v[j] = v[j] * cs[j] - o * sn[j]; else if (fq == 1) v[j] = v[j] * cs[j] + o * sn[j]; } }
.LBB0_1137:
	s_andn2_saveexec_b64 s[0:1], s[0:1]
	s_cbranch_execz .LBB0_1139
	v_mov_b32_e32 v64, v6
	v_mov_b32_e32 v65, v14
	v_mov_b32_e32 v62, v42
	s_waitcnt lgkmcnt(0)
	v_mul_f32_e32 v42, v14, v63
	v_fma_f32 v62, v64, v62, -v42
	v_fma_f32 v63, v65, v63, -v42
	s_nop 0
	v_mov_b32_e32 v42, v62
.LBB0_1139:
	s_or_b64 exec, exec, s[0:1]
	s_waitcnt lgkmcnt(0)
	ds_bpermute_b32 v63, v53, v43
	v_cmp_lt_i32_e32 vcc, 0, v204
	s_and_saveexec_b64 s[0:1], vcc
	s_xor_b64 s[0:1], exec, s[0:1]
	s_cbranch_execz .LBB0_1143
	v_cmp_eq_u32_e32 vcc, 1, v204
	s_and_saveexec_b64 s[16:17], vcc
	s_cbranch_execz .LBB0_1142
	v_mov_b32_e32 v64, v7
	v_mov_b32_e32 v65, v15
	v_mov_b32_e32 v62, v43
	s_waitcnt lgkmcnt(0)
	v_mul_f32_e32 v66, v15, v63
	v_fma_f32 v62, v64, v62, v66
	v_fma_f32 v63, v65, v63, v66
	s_nop 0
	v_mov_b32_e32 v43, v62

;     __device__ __forceinline__ void operator()(const f32x4 (&acc)[2][2][4][2], const Unit& u, int wr, int wc, int fr, int fq) const {
;     ...
;                     if (reg <= 1) {
;                         if (rope) { const float cs[8] = {c0[0], c0[1], c0[2], c0[3], c1[0], c1[1], c1[2], c1[3]}; const float sn[8] = {s0[0], s0[1], s0[2], s0[3], s1[0], s1[1], s1[2], s1[3]};
; #pragma unroll
;                             for (int j = 0; j < 8; ++j) { const float o = __shfl_xor(v[j], 16); if (fq == 0) v[j] = v[j] * cs[j] - o * sn[j]; else if (fq == 1) v[j] = v[j] * cs[j] + o * sn[j]; } }
.LBB0_1143:
	s_andn2_saveexec_b64 s[0:1], s[0:1]
	s_cbranch_execz .LBB0_1145
	v_mov_b32_e32 v64, v7
	v_mov_b32_e32 v65, v15
	v_mov_b32_e32 v62, v43
	s_waitcnt lgkmcnt(0)
	v_mul_f32_e32 v66, v15, v63
	v_fma_f32 v62, v64, v62, -v66
	v_fma_f32 v63, v65, v63, -v66
	s_nop 0
	v_mov_b32_e32 v43, v62

; __device__ __forceinline__ float fexp(float x) { return __builtin_amdgcn_exp2f(x * LOG2E); }
; __device__ __forceinline__ float sigm(float x) { return __builtin_amdgcn_rcpf(1.f + fexp(-x)); }
; __device__ __forceinline__ float silu(float x) { return x * sigm(x); }
;     __device__ __forceinline__ void operator()(const f32x4 (&acc)[2][2][4][2], const Unit& u, int wr, int wc, int fr, int fq) const {
;     ...
;                     } else if (reg == PB_QR || reg == PB_G) {
; #pragma unroll
;                         for (int j = 0; j < 8; ++j) v[j] = silu(v[j]);
.LBB0_1148:
	s_andn2_b64 vcc, exec, s[0:1]
	s_cbranch_vccnz .LBB0_1150
	v_mul_f32_e32 v44, 0xbfb8aa3b, v38
	v_exp_f32_e32 v44, v44
	v_mul_f32_e32 v45, 0xbfb8aa3b, v36
	v_mul_f32_e32 v32, 0xbfb8aa3b, v42
	v_mul_f32_e32 v33, 0xbfb8aa3b, v43
	v_add_f32_e32 v44, 1.0, v44
	v_mul_f32_e32 v34, 0xbfb8aa3b, v40
	v_mul_f32_e32 v35, 0xbfb8aa3b, v41
	v_rcp_f32_e32 v46, v44
	v_mul_f32_e32 v44, 0xbfb8aa3b, v39
	v_exp_f32_e32 v45, v45
	v_mul_f32_e32 v47, 0xbfb8aa3b, v37
	v_exp_f32_e32 v32, v32
	v_exp_f32_e32 v33, v33
	v_exp_f32_e32 v34, v34
	v_exp_f32_e32 v35, v35
	v_exp_f32_e32 v44, v44
	v_exp_f32_e32 v47, v47
	v_add_f32_e32 v45, 1.0, v45
	v_add_f32_e32 v32, 1.0, v32
	v_add_f32_e32 v33, 1.0, v33
	v_add_f32_e32 v34, 1.0, v34
	v_add_f32_e32 v35, 1.0, v35
	v_add_f32_e32 v44, 1.0, v44
	v_rcp_f32_e32 v52, v45
	v_add_f32_e32 v45, 1.0, v47
	v_rcp_f32_e32 v32, v32
	v_rcp_f32_e32 v33, v33
	v_rcp_f32_e32 v34, v34
	v_rcp_f32_e32 v35, v35
	v_rcp_f32_e32 v53, v45
	v_rcp_f32_e32 v47, v44
	v_mul_f32_e32 v54, v42, v32
	v_mul_f32_e32 v55, v43, v33
	v_mul_f32_e32 v44, v40, v34
	v_mul_f32_e32 v45, v41, v35
	v_mul_f32_e32 v52, v36, v52
	v_mul_f32_e32 v53, v37, v53
	v_mul_f32_e32 v46, v38, v46
	v_mul_f32_e32 v47, v39, v47

;     __device__ __forceinline__ void operator()(const f32x4 (&acc)[2][2][4][2], const Unit& u, int wr, int wc, int fr, int fq) const {
;     ...
;                     if (reg <= 1) {
;                         if (rope) { const float cs[8] = {c0[0], c0[1], c0[2], c0[3], c1[0], c1[1], c1[2], c1[3]}; const float sn[8] = {s0[0], s0[1], s0[2], s0[3], s1[0], s1[1], s1[2], s1[3]};
; #pragma unroll
;                             for (int j = 0; j < 8; ++j) { const float o = __shfl_xor(v[j], 16); if (fq == 0) v[j] = v[j] * cs[j] - o * sn[j]; else if (fq == 1) v[j] = v[j] * cs[j] + o * sn[j]; } }
.LBB0_1151:
	s_and_b64 vcc, exec, s[10:11]
	s_cbranch_vccnz .LBB0_1350
	v_and_b32_e32 v33, 64, v214
	v_xor_b32_e32 v32, 16, v214
	v_add_u32_e32 v33, 64, v33
	v_cmp_lt_i32_e32 vcc, v32, v33
	s_nop 1
	v_cndmask_b32_e32 v32, v214, v32, vcc
	v_lshlrev_b32_e32 v54, 2, v32
	ds_bpermute_b32 v53, v54, v42
	v_cmp_lt_i32_e32 vcc, 0, v204
	s_and_saveexec_b64 s[0:1], vcc
	s_xor_b64 s[0:1], exec, s[0:1]
	s_cbranch_execz .LBB0_1156
	v_cmp_eq_u32_e32 vcc, 1, v204
	v_mov_b32_e32 v35, v37
	v_mov_b32_e32 v34, v36
	v_mov_b32_e32 v47, v39
	v_mov_b32_e32 v46, v38
	v_mov_b32_e32 v45, v41
	v_mov_b32_e32 v44, v40
	v_mov_b32_e32 v33, v43
	v_mov_b32_e32 v32, v42
	s_and_saveexec_b64 s[16:17], vcc
	s_cbranch_execz .LBB0_1155
	v_mov_b32_e32 v32, v42
	v_mov_b32_e32 v33, v20
	v_mov_b32_e32 v52, v16
	s_waitcnt lgkmcnt(0)
	v_mul_f32_e32 v32, v32, v52
	v_mul_f32_e32 v33, v33, v53
	v_mov_b32_e32 v35, v37
	v_add_f32_e32 v32, v32, v33
	v_mov_b32_e32 v34, v36
	v_mov_b32_e32 v47, v39
	v_mov_b32_e32 v46, v38
	v_mov_b32_e32 v45, v41
	v_mov_b32_e32 v44, v40
	v_mov_b32_e32 v33, v43

;     __device__ __forceinline__ void operator()(const f32x4 (&acc)[2][2][4][2], const Unit& u, int wr, int wc, int fr, int fq) const {
;     ...
;                     if (reg <= 1) {
;                         if (rope) { const float cs[8] = {c0[0], c0[1], c0[2], c0[3], c1[0], c1[1], c1[2], c1[3]}; const float sn[8] = {s0[0], s0[1], s0[2], s0[3], s1[0], s1[1], s1[2], s1[3]};
; #pragma unroll
;                             for (int j = 0; j < 8; ++j) { const float o = __shfl_xor(v[j], 16); if (fq == 0) v[j] = v[j] * cs[j] - o * sn[j]; else if (fq == 1) v[j] = v[j] * cs[j] + o * sn[j]; } }
.LBB0_1156:
	s_andn2_saveexec_b64 s[0:1], s[0:1]
	s_cbranch_execz .LBB0_1158
	v_mov_b32_e32 v32, v42
	v_mov_b32_e32 v33, v20
	v_mov_b32_e32 v52, v16
	s_waitcnt lgkmcnt(0)
	v_mul_f32_e32 v32, v32, v52
	v_mul_f32_e32 v33, v33, v53
	v_mov_b32_e32 v44, v40
	v_sub_f32_e32 v32, v32, v33
	v_mov_b32_e32 v33, v43
	v_mov_b32_e32 v45, v41
	v_mov_b32_e32 v46, v38
	v_mov_b32_e32 v47, v39
	v_mov_b32_e32 v34, v36
	v_mov_b32_e32 v35, v37
.LBB0_1158:
	s_or_b64 exec, exec, s[0:1]
	s_waitcnt lgkmcnt(0)
	ds_bpermute_b32 v53, v54, v33
	v_cmp_lt_i32_e32 vcc, 0, v204
	s_and_saveexec_b64 s[0:1], vcc
	s_xor_b64 s[0:1], exec, s[0:1]
	s_cbranch_execz .LBB0_1162
	v_cmp_eq_u32_e32 vcc, 1, v204
	s_and_saveexec_b64 s[16:17], vcc
	s_cbranch_execz .LBB0_1161
	v_mov_b32_e32 v56, v17
	v_mov_b32_e32 v57, v21
	v_mov_b32_e32 v52, v33
	v_mul_f32_e32 v58, v17, v33
	s_waitcnt lgkmcnt(0)
	v_fma_f32 v52, v56, v52, v58
	v_fma_f32 v53, v57, v53, v58
	s_nop 0
	v_mov_b32_e32 v33, v53

;     __device__ __forceinline__ void operator()(const f32x4 (&acc)[2][2][4][2], const Unit& u, int wr, int wc, int fr, int fq) const {
;     ...
;                     if (reg <= 1) {
;                         if (rope) { const float cs[8] = {c0[0], c0[1], c0[2], c0[3], c1[0], c1[1], c1[2], c1[3]}; const float sn[8] = {s0[0], s0[1], s0[2], s0[3], s1[0], s1[1], s1[2], s1[3]};
; #pragma unroll
;                             for (int j = 0; j < 8; ++j) { const float o = __shfl_xor(v[j], 16); if (fq == 0) v[j] = v[j] * cs[j] - o * sn[j]; else if (fq == 1) v[j] = v[j] * cs[j] + o * sn[j]; } }
.LBB0_1162:
	s_andn2_saveexec_b64 s[0:1], s[0:1]
	s_cbranch_execz .LBB0_1164
	v_mov_b32_e32 v56, v17
	v_mov_b32_e32 v57, v21
	v_mov_b32_e32 v52, v33
	v_mul_f32_e32 v58, v17, v33
	s_waitcnt lgkmcnt(0)
	v_fma_f32 v52, -v56, v52, v58
	v_fma_f32 v53, -v57, v53, v58
	s_nop 0
	v_mov_b32_e32 v33, v53
.LBB0_1164:
	s_or_b64 exec, exec, s[0:1]
	s_waitcnt lgkmcnt(0)
	ds_bpermute_b32 v53, v54, v44
	v_cmp_lt_i32_e32 vcc, 0, v204
	s_and_saveexec_b64 s[0:1], vcc
	s_xor_b64 s[0:1], exec, s[0:1]
	s_cbranch_execz .LBB0_1168
	v_cmp_eq_u32_e32 vcc, 1, v204
	s_and_saveexec_b64 s[16:17], vcc
	s_cbranch_execz .LBB0_1167
	v_mov_b32_e32 v56, v18
	v_mov_b32_e32 v57, v22
	v_mov_b32_e32 v52, v44
	s_waitcnt lgkmcnt(0)
	v_mul_f32_e32 v44, v22, v53
	v_fma_f32 v52, v56, v52, v44
	v_fma_f32 v53, v57, v53, v44
	s_nop 0
	v_mov_b32_e32 v44, v52

;     __device__ __forceinline__ void operator()(const f32x4 (&acc)[2][2][4][2], const Unit& u, int wr, int wc, int fr, int fq) const {
;     ...
;                     if (reg <= 1) {
;                         if (rope) { const float cs[8] = {c0[0], c0[1], c0[2], c0[3], c1[0], c1[1], c1[2], c1[3]}; const float sn[8] = {s0[0], s0[1], s0[2], s0[3], s1[0], s1[1], s1[2], s1[3]};
; #pragma unroll
;                             for (int j = 0; j < 8; ++j) { const float o = __shfl_xor(v[j], 16); if (fq == 0) v[j] = v[j] * cs[j] - o * sn[j]; else if (fq == 1) v[j] = v[j] * cs[j] + o * sn[j]; } }
.LBB0_1168:
	s_andn2_saveexec_b64 s[0:1], s[0:1]
	s_cbranch_execz .LBB0_1170
	v_mov_b32_e32 v56, v18
	v_mov_b32_e32 v57, v22
	v_mov_b32_e32 v52, v44
	s_waitcnt lgkmcnt(0)
	v_mul_f32_e32 v44, v22, v53
	v_fma_f32 v52, v56, v52, -v44
	v_fma_f32 v53, v57, v53, -v44
	s_nop 0
	v_mov_b32_e32 v44, v52
.LBB0_1170:
	s_or_b64 exec, exec, s[0:1]
	s_waitcnt lgkmcnt(0)
	ds_bpermute_b32 v53, v54, v45
	v_cmp_lt_i32_e32 vcc, 0, v204
	s_and_saveexec_b64 s[0:1], vcc
	s_xor_b64 s[0:1], exec, s[0:1]
	s_cbranch_execz .LBB0_1174
	v_cmp_eq_u32_e32 vcc, 1, v204
	s_and_saveexec_b64 s[16:17], vcc
	s_cbranch_execz .LBB0_1173
	v_mov_b32_e32 v56, v19
	v_mov_b32_e32 v57, v23
	v_mov_b32_e32 v52, v45
	s_waitcnt lgkmcnt(0)
	v_mul_f32_e32 v58, v23, v53
	v_fma_f32 v52, v56, v52, v58
	v_fma_f32 v53, v57, v53, v58
	s_nop 0
	v_mov_b32_e32 v45, v52

;     __device__ __forceinline__ void operator()(const f32x4 (&acc)[2][2][4][2], const Unit& u, int wr, int wc, int fr, int fq) const {
;     ...
;                     if (reg <= 1) {
;                         if (rope) { const float cs[8] = {c0[0], c0[1], c0[2], c0[3], c1[0], c1[1], c1[2], c1[3]}; const float sn[8] = {s0[0], s0[1], s0[2], s0[3], s1[0], s1[1], s1[2], s1[3]};
; #pragma unroll
;                             for (int j = 0; j < 8; ++j) { const float o = __shfl_xor(v[j], 16); if (fq == 0) v[j] = v[j] * cs[j] - o * sn[j]; else if (fq == 1) v[j] = v[j] * cs[j] + o * sn[j]; } }
.LBB0_1174:
	s_andn2_saveexec_b64 s[0:1], s[0:1]
	s_cbranch_execz .LBB0_1176
	v_mov_b32_e32 v56, v19
	v_mov_b32_e32 v57, v23
	v_mov_b32_e32 v52, v45
	s_waitcnt lgkmcnt(0)
	v_mul_f32_e32 v58, v23, v53
	v_fma_f32 v52, v56, v52, -v58
	v_fma_f32 v53, v57, v53, -v58
	s_nop 0
	v_mov_b32_e32 v45, v52
.LBB0_1176:
	s_or_b64 exec, exec, s[0:1]
	s_waitcnt lgkmcnt(0)
	ds_bpermute_b32 v53, v54, v46
	v_cmp_lt_i32_e32 vcc, 0, v204
	s_and_saveexec_b64 s[0:1], vcc
	s_xor_b64 s[0:1], exec, s[0:1]
	s_cbranch_execz .LBB0_1180
	v_cmp_eq_u32_e32 vcc, 1, v204
	s_and_saveexec_b64 s[16:17], vcc
	s_cbranch_execz .LBB0_1179
	v_mov_b32_e32 v56, v4
	v_mov_b32_e32 v57, v12
	v_mov_b32_e32 v52, v46
	s_waitcnt lgkmcnt(0)
	v_mul_f32_e32 v46, v12, v53
	v_fma_f32 v52, v56, v52, v46
	v_fma_f32 v53, v57, v53, v46
	s_nop 0
	v_mov_b32_e32 v46, v52

;     __device__ __forceinline__ void operator()(const f32x4 (&acc)[2][2][4][2], const Unit& u, int wr, int wc, int fr, int fq) const {
;     ...
;                     if (reg <= 1) {
;                         if (rope) { const float cs[8] = {c0[0], c0[1], c0[2], c0[3], c1[0], c1[1], c1[2], c1[3]}; const float sn[8] = {s0[0], s0[1], s0[2], s0[3], s1[0], s1[1], s1[2], s1[3]};
; #pragma unroll
;                             for (int j = 0; j < 8; ++j) { const float o = __shfl_xor(v[j], 16); if (fq == 0) v[j] = v[j] * cs[j] - o * sn[j]; else if (fq == 1) v[j] = v[j] * cs[j] + o * sn[j]; } }
.LBB0_1180:
	s_andn2_saveexec_b64 s[0:1], s[0:1]
	s_cbranch_execz .LBB0_1182
	v_mov_b32_e32 v56, v4
	v_mov_b32_e32 v57, v12
	v_mov_b32_e32 v52, v46
	s_waitcnt lgkmcnt(0)
	v_mul_f32_e32 v46, v12, v53
	v_fma_f32 v52, v56, v52, -v46
	v_fma_f32 v53, v57, v53, -v46
	s_nop 0
	v_mov_b32_e32 v46, v52
.LBB0_1182:
	s_or_b64 exec, exec, s[0:1]
	s_waitcnt lgkmcnt(0)
	ds_bpermute_b32 v53, v54, v47
	v_cmp_lt_i32_e32 vcc, 0, v204
	s_and_saveexec_b64 s[0:1], vcc
	s_xor_b64 s[0:1], exec, s[0:1]
	s_cbranch_execz .LBB0_1186
	v_cmp_eq_u32_e32 vcc, 1, v204
	s_and_saveexec_b64 s[16:17], vcc
	s_cbranch_execz .LBB0_1185
	v_mov_b32_e32 v56, v5
	v_mov_b32_e32 v57, v13
	v_mov_b32_e32 v52, v47
	s_waitcnt lgkmcnt(0)
	v_mul_f32_e32 v58, v13, v53
	v_fma_f32 v52, v56, v52, v58
	v_fma_f32 v53, v57, v53, v58
	s_nop 0
	v_mov_b32_e32 v47, v52

;     __device__ __forceinline__ void operator()(const f32x4 (&acc)[2][2][4][2], const Unit& u, int wr, int wc, int fr, int fq) const {
;     ...
;                     if (reg <= 1) {
;                         if (rope) { const float cs[8] = {c0[0], c0[1], c0[2], c0[3], c1[0], c1[1], c1[2], c1[3]}; const float sn[8] = {s0[0], s0[1], s0[2], s0[3], s1[0], s1[1], s1[2], s1[3]};
; #pragma unroll
;                             for (int j = 0; j < 8; ++j) { const float o = __shfl_xor(v[j], 16); if (fq == 0) v[j] = v[j] * cs[j] - o * sn[j]; else if (fq == 1) v[j] = v[j] * cs[j] + o * sn[j]; } }
.LBB0_1186:
	s_andn2_saveexec_b64 s[0:1], s[0:1]
	s_cbranch_execz .LBB0_1188
	v_mov_b32_e32 v56, v5
	v_mov_b32_e32 v57, v13
	v_mov_b32_e32 v52, v47
	s_waitcnt lgkmcnt(0)
	v_mul_f32_e32 v58, v13, v53
	v_fma_f32 v52, v56, v52, -v58
	v_fma_f32 v53, v57, v53, -v58
	s_nop 0
	v_mov_b32_e32 v47, v52
.LBB0_1188:
	s_or_b64 exec, exec, s[0:1]
	s_waitcnt lgkmcnt(0)
	ds_bpermute_b32 v53, v54, v34
	v_cmp_lt_i32_e32 vcc, 0, v204
	s_and_saveexec_b64 s[0:1], vcc
	s_xor_b64 s[0:1], exec, s[0:1]
	s_cbranch_execz .LBB0_1192
	v_cmp_eq_u32_e32 vcc, 1, v204
	s_and_saveexec_b64 s[16:17], vcc
	s_cbranch_execz .LBB0_1191
	v_mov_b32_e32 v56, v6
	v_mov_b32_e32 v57, v14
	v_mov_b32_e32 v52, v34
	s_waitcnt lgkmcnt(0)
	v_mul_f32_e32 v34, v14, v53
	v_fma_f32 v52, v56, v52, v34
	v_fma_f32 v53, v57, v53, v34
	s_nop 0
	v_mov_b32_e32 v34, v52

;     __device__ __forceinline__ void operator()(const f32x4 (&acc)[2][2][4][2], const Unit& u, int wr, int wc, int fr, int fq) const {
;     ...
;                     if (reg <= 1) {
;                         if (rope) { const float cs[8] = {c0[0], c0[1], c0[2], c0[3], c1[0], c1[1], c1[2], c1[3]}; const float sn[8] = {s0[0], s0[1], s0[2], s0[3], s1[0], s1[1], s1[2], s1[3]};
; #pragma unroll
;                             for (int j = 0; j < 8; ++j) { const float o = __shfl_xor(v[j], 16); if (fq == 0) v[j] = v[j] * cs[j] - o * sn[j]; else if (fq == 1) v[j] = v[j] * cs[j] + o * sn[j]; } }
.LBB0_1192:
	s_andn2_saveexec_b64 s[0:1], s[0:1]
	s_cbranch_execz .LBB0_1194
	v_mov_b32_e32 v56, v6
	v_mov_b32_e32 v57, v14
	v_mov_b32_e32 v52, v34
	s_waitcnt lgkmcnt(0)
	v_mul_f32_e32 v34, v14, v53
	v_fma_f32 v52, v56, v52, -v34
	v_fma_f32 v53, v57, v53, -v34
	s_nop 0
	v_mov_b32_e32 v34, v52
.LBB0_1194:
	s_or_b64 exec, exec, s[0:1]
	s_waitcnt lgkmcnt(0)
	ds_bpermute_b32 v53, v54, v35
	v_cmp_lt_i32_e32 vcc, 0, v204
	s_and_saveexec_b64 s[0:1], vcc
	s_xor_b64 s[0:1], exec, s[0:1]
	s_cbranch_execz .LBB0_1198
	v_cmp_eq_u32_e32 vcc, 1, v204
	s_and_saveexec_b64 s[16:17], vcc
	s_cbranch_execz .LBB0_1197
	v_mov_b32_e32 v54, v7
	v_mov_b32_e32 v55, v15
	v_mov_b32_e32 v52, v35
	s_waitcnt lgkmcnt(0)
	v_mul_f32_e32 v56, v15, v53
	v_fma_f32 v52, v54, v52, v56
	v_fma_f32 v53, v55, v53, v56
	s_nop 0
	v_mov_b32_e32 v35, v52

;     __device__ __forceinline__ void operator()(const f32x4 (&acc)[2][2][4][2], const Unit& u, int wr, int wc, int fr, int fq) const {
;     ...
;                     if (reg <= 1) {
;                         if (rope) { const float cs[8] = {c0[0], c0[1], c0[2], c0[3], c1[0], c1[1], c1[2], c1[3]}; const float sn[8] = {s0[0], s0[1], s0[2], s0[3], s1[0], s1[1], s1[2], s1[3]};
; #pragma unroll
;                             for (int j = 0; j < 8; ++j) { const float o = __shfl_xor(v[j], 16); if (fq == 0) v[j] = v[j] * cs[j] - o * sn[j]; else if (fq == 1) v[j] = v[j] * cs[j] + o * sn[j]; } }
.LBB0_1198:
	s_andn2_saveexec_b64 s[0:1], s[0:1]
	s_cbranch_execz .LBB0_1200
	v_mov_b32_e32 v54, v7
	v_mov_b32_e32 v55, v15
	v_mov_b32_e32 v52, v35
	s_waitcnt lgkmcnt(0)
	v_mul_f32_e32 v56, v15, v53
	v_fma_f32 v52, v54, v52, -v56
	v_fma_f32 v53, v55, v53, -v56
	s_nop 0
	v_mov_b32_e32 v35, v52

; __device__ __forceinline__ float fexp(float x) { return __builtin_amdgcn_exp2f(x * LOG2E); }
; __device__ __forceinline__ float sigm(float x) { return __builtin_amdgcn_rcpf(1.f + fexp(-x)); }
; __device__ __forceinline__ float silu(float x) { return x * sigm(x); }
;     __device__ __forceinline__ void operator()(const f32x4 (&acc)[2][2][4][2], const Unit& u, int wr, int wc, int fr, int fq) const {
;     ...
;                     } else if (reg == PB_QR || reg == PB_G) {
; #pragma unroll
;                         for (int j = 0; j < 8; ++j) v[j] = silu(v[j]);
.LBB0_1203:
	s_andn2_b64 vcc, exec, s[0:1]
	s_cbranch_vccnz .LBB0_1205
	v_mul_f32_e32 v37, 0xbfb8aa3b, v30
	v_exp_f32_e32 v37, v37
	v_mul_f32_e32 v42, 0xbfb8aa3b, v28
	v_mul_f32_e32 v24, 0xbfb8aa3b, v40
	v_mul_f32_e32 v25, 0xbfb8aa3b, v41
	v_add_f32_e32 v37, 1.0, v37
	v_mul_f32_e32 v26, 0xbfb8aa3b, v38
	v_mul_f32_e32 v27, 0xbfb8aa3b, v39
	v_rcp_f32_e32 v44, v37
	v_mul_f32_e32 v37, 0xbfb8aa3b, v31
	v_exp_f32_e32 v42, v42
	v_mul_f32_e32 v43, 0xbfb8aa3b, v29
	v_exp_f32_e32 v24, v24
	v_exp_f32_e32 v25, v25
	v_exp_f32_e32 v26, v26
	v_exp_f32_e32 v27, v27
	v_exp_f32_e32 v37, v37
	v_exp_f32_e32 v43, v43
	v_add_f32_e32 v42, 1.0, v42
	v_add_f32_e32 v24, 1.0, v24
	v_add_f32_e32 v25, 1.0, v25
	v_add_f32_e32 v26, 1.0, v26
	v_add_f32_e32 v27, 1.0, v27
	v_add_f32_e32 v37, 1.0, v37
	v_rcp_f32_e32 v46, v42
	v_add_f32_e32 v42, 1.0, v43
	v_rcp_f32_e32 v24, v24
	v_rcp_f32_e32 v25, v25
	v_rcp_f32_e32 v26, v26
	v_rcp_f32_e32 v27, v27
	v_rcp_f32_e32 v47, v42
	v_rcp_f32_e32 v45, v37
	v_mul_f32_e32 v48, v40, v24
	v_mul_f32_e32 v49, v41, v25
	v_mul_f32_e32 v42, v38, v26
	v_mul_f32_e32 v43, v39, v27
	v_mul_f32_e32 v46, v28, v46
	v_mul_f32_e32 v47, v29, v47
	v_mul_f32_e32 v44, v30, v44
	v_mul_f32_e32 v45, v31, v45

;     __device__ __forceinline__ void operator()(const f32x4 (&acc)[2][2][4][2], const Unit& u, int wr, int wc, int fr, int fq) const {
;     ...
;                     if (reg <= 1) {
;                         if (rope) { const float cs[8] = {c0[0], c0[1], c0[2], c0[3], c1[0], c1[1], c1[2], c1[3]}; const float sn[8] = {s0[0], s0[1], s0[2], s0[3], s1[0], s1[1], s1[2], s1[3]};
; #pragma unroll
;                             for (int j = 0; j < 8; ++j) { const float o = __shfl_xor(v[j], 16); if (fq == 0) v[j] = v[j] * cs[j] - o * sn[j]; else if (fq == 1) v[j] = v[j] * cs[j] + o * sn[j]; } }
.LBB0_1206:
	s_and_b64 vcc, exec, s[10:11]
	s_cbranch_vccnz .LBB0_1353
	v_and_b32_e32 v25, 64, v214
	v_xor_b32_e32 v24, 16, v214
	v_add_u32_e32 v25, 64, v25
	v_cmp_lt_i32_e32 vcc, v24, v25
	s_nop 1
	v_cndmask_b32_e32 v24, v214, v24, vcc
	v_lshlrev_b32_e32 v37, 2, v24
	ds_bpermute_b32 v47, v37, v40
	v_cmp_lt_i32_e32 vcc, 0, v204
	s_and_saveexec_b64 s[0:1], vcc
	s_xor_b64 s[0:1], exec, s[0:1]
	s_cbranch_execz .LBB0_1211
	v_cmp_eq_u32_e32 vcc, 1, v204
	v_mov_b32_e32 v27, v29
	v_mov_b32_e32 v26, v28
	v_mov_b32_e32 v45, v31
	v_mov_b32_e32 v44, v30
	v_mov_b32_e32 v43, v39
	v_mov_b32_e32 v42, v38
	v_mov_b32_e32 v25, v41
	v_mov_b32_e32 v24, v40
	s_and_saveexec_b64 s[16:17], vcc
	s_cbranch_execz .LBB0_1210
	v_mov_b32_e32 v24, v40
	v_mov_b32_e32 v25, v20
	v_mov_b32_e32 v46, v16
	s_waitcnt lgkmcnt(0)
	v_mul_f32_e32 v24, v24, v46
	v_mul_f32_e32 v25, v25, v47
	v_mov_b32_e32 v27, v29
	v_add_f32_e32 v24, v24, v25
	v_mov_b32_e32 v26, v28
	v_mov_b32_e32 v45, v31
	v_mov_b32_e32 v44, v30
	v_mov_b32_e32 v43, v39
	v_mov_b32_e32 v42, v38
	v_mov_b32_e32 v25, v41

;     __device__ __forceinline__ void operator()(const f32x4 (&acc)[2][2][4][2], const Unit& u, int wr, int wc, int fr, int fq) const {
;     ...
;                     if (reg <= 1) {
;                         if (rope) { const float cs[8] = {c0[0], c0[1], c0[2], c0[3], c1[0], c1[1], c1[2], c1[3]}; const float sn[8] = {s0[0], s0[1], s0[2], s0[3], s1[0], s1[1], s1[2], s1[3]};
; #pragma unroll
;                             for (int j = 0; j < 8; ++j) { const float o = __shfl_xor(v[j], 16); if (fq == 0) v[j] = v[j] * cs[j] - o * sn[j]; else if (fq == 1) v[j] = v[j] * cs[j] + o * sn[j]; } }
.LBB0_1211:
	s_andn2_saveexec_b64 s[0:1], s[0:1]
	s_cbranch_execz .LBB0_1213
	v_mov_b32_e32 v24, v40
	v_mov_b32_e32 v25, v20
	v_mov_b32_e32 v46, v16
	s_waitcnt lgkmcnt(0)
	v_mul_f32_e32 v24, v24, v46
	v_mul_f32_e32 v25, v25, v47
	v_mov_b32_e32 v42, v38
	v_sub_f32_e32 v24, v24, v25
	v_mov_b32_e32 v25, v41
	v_mov_b32_e32 v43, v39
	v_mov_b32_e32 v44, v30
	v_mov_b32_e32 v45, v31
	v_mov_b32_e32 v26, v28
	v_mov_b32_e32 v27, v29
.LBB0_1213:
	s_or_b64 exec, exec, s[0:1]
	s_waitcnt lgkmcnt(0)
	ds_bpermute_b32 v47, v37, v25
	v_cmp_lt_i32_e32 vcc, 0, v204
	s_and_saveexec_b64 s[0:1], vcc
	s_xor_b64 s[0:1], exec, s[0:1]
	s_cbranch_execz .LBB0_1217
	v_cmp_eq_u32_e32 vcc, 1, v204
	s_and_saveexec_b64 s[16:17], vcc
	s_cbranch_execz .LBB0_1216
	v_mov_b32_e32 v48, v17
	v_mov_b32_e32 v49, v21
	v_mov_b32_e32 v46, v25
	v_mul_f32_e32 v50, v17, v25
	s_waitcnt lgkmcnt(0)
	v_fma_f32 v46, v48, v46, v50
	v_fma_f32 v47, v49, v47, v50
	s_nop 0
	v_mov_b32_e32 v25, v47

;     __device__ __forceinline__ void operator()(const f32x4 (&acc)[2][2][4][2], const Unit& u, int wr, int wc, int fr, int fq) const {
;     ...
;                     if (reg <= 1) {
;                         if (rope) { const float cs[8] = {c0[0], c0[1], c0[2], c0[3], c1[0], c1[1], c1[2], c1[3]}; const float sn[8] = {s0[0], s0[1], s0[2], s0[3], s1[0], s1[1], s1[2], s1[3]};
; #pragma unroll
;                             for (int j = 0; j < 8; ++j) { const float o = __shfl_xor(v[j], 16); if (fq == 0) v[j] = v[j] * cs[j] - o * sn[j]; else if (fq == 1) v[j] = v[j] * cs[j] + o * sn[j]; } }
.LBB0_1217:
	s_andn2_saveexec_b64 s[0:1], s[0:1]
	s_cbranch_execz .LBB0_1219
	v_mov_b32_e32 v48, v17
	v_mov_b32_e32 v49, v21
	v_mov_b32_e32 v46, v25
	v_mul_f32_e32 v50, v17, v25
	s_waitcnt lgkmcnt(0)
	v_fma_f32 v46, -v48, v46, v50
	v_fma_f32 v47, -v49, v47, v50
	s_nop 0
	v_mov_b32_e32 v25, v47
.LBB0_1219:
	s_or_b64 exec, exec, s[0:1]
	s_waitcnt lgkmcnt(0)
	ds_bpermute_b32 v47, v37, v42
	v_cmp_lt_i32_e32 vcc, 0, v204
	s_and_saveexec_b64 s[0:1], vcc
	s_xor_b64 s[0:1], exec, s[0:1]
	s_cbranch_execz .LBB0_1223
	v_cmp_eq_u32_e32 vcc, 1, v204
	s_and_saveexec_b64 s[16:17], vcc
	s_cbranch_execz .LBB0_1222
	v_mov_b32_e32 v48, v18
	v_mov_b32_e32 v49, v22
	v_mov_b32_e32 v46, v42
	s_waitcnt lgkmcnt(0)
	v_mul_f32_e32 v42, v22, v47
	v_fma_f32 v46, v48, v46, v42
	v_fma_f32 v47, v49, v47, v42
	s_nop 0
	v_mov_b32_e32 v42, v46

;     __device__ __forceinline__ void operator()(const f32x4 (&acc)[2][2][4][2], const Unit& u, int wr, int wc, int fr, int fq) const {
;     ...
;                     if (reg <= 1) {
;                         if (rope) { const float cs[8] = {c0[0], c0[1], c0[2], c0[3], c1[0], c1[1], c1[2], c1[3]}; const float sn[8] = {s0[0], s0[1], s0[2], s0[3], s1[0], s1[1], s1[2], s1[3]};
; #pragma unroll
;                             for (int j = 0; j < 8; ++j) { const float o = __shfl_xor(v[j], 16); if (fq == 0) v[j] = v[j] * cs[j] - o * sn[j]; else if (fq == 1) v[j] = v[j] * cs[j] + o * sn[j]; } }
.LBB0_1223:
	s_andn2_saveexec_b64 s[0:1], s[0:1]
	s_cbranch_execz .LBB0_1225
	v_mov_b32_e32 v48, v18
	v_mov_b32_e32 v49, v22
	v_mov_b32_e32 v46, v42
	s_waitcnt lgkmcnt(0)
	v_mul_f32_e32 v42, v22, v47
	v_fma_f32 v46, v48, v46, -v42
	v_fma_f32 v47, v49, v47, -v42
	s_nop 0
	v_mov_b32_e32 v42, v46
.LBB0_1225:
	s_or_b64 exec, exec, s[0:1]
	s_waitcnt lgkmcnt(0)
	ds_bpermute_b32 v47, v37, v43
	v_cmp_lt_i32_e32 vcc, 0, v204
	s_and_saveexec_b64 s[0:1], vcc
	s_xor_b64 s[0:1], exec, s[0:1]
	s_cbranch_execz .LBB0_1229
	v_cmp_eq_u32_e32 vcc, 1, v204
	s_and_saveexec_b64 s[16:17], vcc
	s_cbranch_execz .LBB0_1228
	v_mov_b32_e32 v48, v19
	v_mov_b32_e32 v49, v23
	v_mov_b32_e32 v46, v43
	s_waitcnt lgkmcnt(0)
	v_mul_f32_e32 v50, v23, v47
	v_fma_f32 v46, v48, v46, v50
	v_fma_f32 v47, v49, v47, v50
	s_nop 0
	v_mov_b32_e32 v43, v46

;     __device__ __forceinline__ void operator()(const f32x4 (&acc)[2][2][4][2], const Unit& u, int wr, int wc, int fr, int fq) const {
;     ...
;                     if (reg <= 1) {
;                         if (rope) { const float cs[8] = {c0[0], c0[1], c0[2], c0[3], c1[0], c1[1], c1[2], c1[3]}; const float sn[8] = {s0[0], s0[1], s0[2], s0[3], s1[0], s1[1], s1[2], s1[3]};
; #pragma unroll
;                             for (int j = 0; j < 8; ++j) { const float o = __shfl_xor(v[j], 16); if (fq == 0) v[j] = v[j] * cs[j] - o * sn[j]; else if (fq == 1) v[j] = v[j] * cs[j] + o * sn[j]; } }
.LBB0_1229:
	s_andn2_saveexec_b64 s[0:1], s[0:1]
	s_cbranch_execz .LBB0_1231
	v_mov_b32_e32 v48, v19
	v_mov_b32_e32 v49, v23
	v_mov_b32_e32 v46, v43
	s_waitcnt lgkmcnt(0)
	v_mul_f32_e32 v50, v23, v47
	v_fma_f32 v46, v48, v46, -v50
	v_fma_f32 v47, v49, v47, -v50
	s_nop 0
	v_mov_b32_e32 v43, v46
.LBB0_1231:
	s_or_b64 exec, exec, s[0:1]
	s_waitcnt lgkmcnt(0)
	ds_bpermute_b32 v47, v37, v44
	v_cmp_lt_i32_e32 vcc, 0, v204
	s_and_saveexec_b64 s[0:1], vcc
	s_xor_b64 s[0:1], exec, s[0:1]
	s_cbranch_execz .LBB0_1235
	v_cmp_eq_u32_e32 vcc, 1, v204
	s_and_saveexec_b64 s[16:17], vcc
	s_cbranch_execz .LBB0_1234
	v_mov_b32_e32 v48, v4
	v_mov_b32_e32 v49, v12
	v_mov_b32_e32 v46, v44
	s_waitcnt lgkmcnt(0)
	v_mul_f32_e32 v44, v12, v47
	v_fma_f32 v46, v48, v46, v44
	v_fma_f32 v47, v49, v47, v44
	s_nop 0
	v_mov_b32_e32 v44, v46

;     __device__ __forceinline__ void operator()(const f32x4 (&acc)[2][2][4][2], const Unit& u, int wr, int wc, int fr, int fq) const {
;     ...
;                     if (reg <= 1) {
;                         if (rope) { const float cs[8] = {c0[0], c0[1], c0[2], c0[3], c1[0], c1[1], c1[2], c1[3]}; const float sn[8] = {s0[0], s0[1], s0[2], s0[3], s1[0], s1[1], s1[2], s1[3]};
; #pragma unroll
;                             for (int j = 0; j < 8; ++j) { const float o = __shfl_xor(v[j], 16); if (fq == 0) v[j] = v[j] * cs[j] - o * sn[j]; else if (fq == 1) v[j] = v[j] * cs[j] + o * sn[j]; } }
.LBB0_1235:
	s_andn2_saveexec_b64 s[0:1], s[0:1]
	s_cbranch_execz .LBB0_1237
	v_mov_b32_e32 v48, v4
	v_mov_b32_e32 v49, v12
	v_mov_b32_e32 v46, v44
	s_waitcnt lgkmcnt(0)
	v_mul_f32_e32 v44, v12, v47
	v_fma_f32 v46, v48, v46, -v44
	v_fma_f32 v47, v49, v47, -v44
	s_nop 0
	v_mov_b32_e32 v44, v46
.LBB0_1237:
	s_or_b64 exec, exec, s[0:1]
	s_waitcnt lgkmcnt(0)
	ds_bpermute_b32 v47, v37, v45
	v_cmp_lt_i32_e32 vcc, 0, v204
	s_and_saveexec_b64 s[0:1], vcc
	s_xor_b64 s[0:1], exec, s[0:1]
	s_cbranch_execz .LBB0_1241
	v_cmp_eq_u32_e32 vcc, 1, v204
	s_and_saveexec_b64 s[16:17], vcc
	s_cbranch_execz .LBB0_1240
	v_mov_b32_e32 v48, v5
	v_mov_b32_e32 v49, v13
	v_mov_b32_e32 v46, v45
	s_waitcnt lgkmcnt(0)
	v_mul_f32_e32 v50, v13, v47
	v_fma_f32 v46, v48, v46, v50
	v_fma_f32 v47, v49, v47, v50
	s_nop 0
	v_mov_b32_e32 v45, v46

;     __device__ __forceinline__ void operator()(const f32x4 (&acc)[2][2][4][2], const Unit& u, int wr, int wc, int fr, int fq) const {
;     ...
;                     if (reg <= 1) {
;                         if (rope) { const float cs[8] = {c0[0], c0[1], c0[2], c0[3], c1[0], c1[1], c1[2], c1[3]}; const float sn[8] = {s0[0], s0[1], s0[2], s0[3], s1[0], s1[1], s1[2], s1[3]};
; #pragma unroll
;                             for (int j = 0; j < 8; ++j) { const float o = __shfl_xor(v[j], 16); if (fq == 0) v[j] = v[j] * cs[j] - o * sn[j]; else if (fq == 1) v[j] = v[j] * cs[j] + o * sn[j]; } }
.LBB0_1241:
	s_andn2_saveexec_b64 s[0:1], s[0:1]
	s_cbranch_execz .LBB0_1243
	v_mov_b32_e32 v48, v5
	v_mov_b32_e32 v49, v13
	v_mov_b32_e32 v46, v45
	s_waitcnt lgkmcnt(0)
	v_mul_f32_e32 v50, v13, v47
	v_fma_f32 v46, v48, v46, -v50
	v_fma_f32 v47, v49, v47, -v50
	s_nop 0
	v_mov_b32_e32 v45, v46
.LBB0_1243:
	s_or_b64 exec, exec, s[0:1]
	s_waitcnt lgkmcnt(0)
	ds_bpermute_b32 v47, v37, v26
	v_cmp_lt_i32_e32 vcc, 0, v204
	s_and_saveexec_b64 s[0:1], vcc
	s_xor_b64 s[0:1], exec, s[0:1]
	s_cbranch_execz .LBB0_1247
	v_cmp_eq_u32_e32 vcc, 1, v204
	s_and_saveexec_b64 s[16:17], vcc
	s_cbranch_execz .LBB0_1246
	v_mov_b32_e32 v48, v6
	v_mov_b32_e32 v49, v14
	v_mov_b32_e32 v46, v26
	s_waitcnt lgkmcnt(0)
	v_mul_f32_e32 v26, v14, v47
	v_fma_f32 v46, v48, v46, v26
	v_fma_f32 v47, v49, v47, v26
	s_nop 0
	v_mov_b32_e32 v26, v46

;     __device__ __forceinline__ void operator()(const f32x4 (&acc)[2][2][4][2], const Unit& u, int wr, int wc, int fr, int fq) const {
;     ...
;                     if (reg <= 1) {
;                         if (rope) { const float cs[8] = {c0[0], c0[1], c0[2], c0[3], c1[0], c1[1], c1[2], c1[3]}; const float sn[8] = {s0[0], s0[1], s0[2], s0[3], s1[0], s1[1], s1[2], s1[3]};
; #pragma unroll
;                             for (int j = 0; j < 8; ++j) { const float o = __shfl_xor(v[j], 16); if (fq == 0) v[j] = v[j] * cs[j] - o * sn[j]; else if (fq == 1) v[j] = v[j] * cs[j] + o * sn[j]; } }
.LBB0_1247:
	s_andn2_saveexec_b64 s[0:1], s[0:1]
	s_cbranch_execz .LBB0_1249
	v_mov_b32_e32 v48, v6
	v_mov_b32_e32 v49, v14
	v_mov_b32_e32 v46, v26
	s_waitcnt lgkmcnt(0)
	v_mul_f32_e32 v26, v14, v47
	v_fma_f32 v46, v48, v46, -v26
	v_fma_f32 v47, v49, v47, -v26
	s_nop 0
	v_mov_b32_e32 v26, v46
.LBB0_1249:
	s_or_b64 exec, exec, s[0:1]
	s_waitcnt lgkmcnt(0)
	ds_bpermute_b32 v47, v37, v27
	v_cmp_lt_i32_e32 vcc, 0, v204
	s_and_saveexec_b64 s[0:1], vcc
	s_xor_b64 s[0:1], exec, s[0:1]
	s_cbranch_execz .LBB0_1253
	v_cmp_eq_u32_e32 vcc, 1, v204
	s_and_saveexec_b64 s[16:17], vcc
	s_cbranch_execz .LBB0_1252
	v_mov_b32_e32 v48, v7
	v_mov_b32_e32 v49, v15
	v_mov_b32_e32 v46, v27
	s_waitcnt lgkmcnt(0)
	v_mul_f32_e32 v50, v15, v47
	v_fma_f32 v46, v48, v46, v50
	v_fma_f32 v47, v49, v47, v50
	s_nop 0
	v_mov_b32_e32 v27, v46

;     __device__ __forceinline__ void operator()(const f32x4 (&acc)[2][2][4][2], const Unit& u, int wr, int wc, int fr, int fq) const {
;     ...
;                     if (reg <= 1) {
;                         if (rope) { const float cs[8] = {c0[0], c0[1], c0[2], c0[3], c1[0], c1[1], c1[2], c1[3]}; const float sn[8] = {s0[0], s0[1], s0[2], s0[3], s1[0], s1[1], s1[2], s1[3]};
; #pragma unroll
;                             for (int j = 0; j < 8; ++j) { const float o = __shfl_xor(v[j], 16); if (fq == 0) v[j] = v[j] * cs[j] - o * sn[j]; else if (fq == 1) v[j] = v[j] * cs[j] + o * sn[j]; } }
.LBB0_1253:
	s_andn2_saveexec_b64 s[0:1], s[0:1]
	s_cbranch_execz .LBB0_1255
	v_mov_b32_e32 v48, v7
	v_mov_b32_e32 v49, v15
	v_mov_b32_e32 v46, v27
	s_waitcnt lgkmcnt(0)
	v_mul_f32_e32 v50, v15, v47
	v_fma_f32 v46, v48, v46, -v50
	v_fma_f32 v47, v49, v47, -v50
	s_nop 0
	v_mov_b32_e32 v27, v46

; __device__ __forceinline__ float fexp(float x) { return __builtin_amdgcn_exp2f(x * LOG2E); }
; __device__ __forceinline__ float sigm(float x) { return __builtin_amdgcn_rcpf(1.f + fexp(-x)); }
; __device__ __forceinline__ float silu(float x) { return x * sigm(x); }
;     __device__ __forceinline__ void operator()(const f32x4 (&acc)[2][2][4][2], const Unit& u, int wr, int wc, int fr, int fq) const {
;     ...
;                     } else if (reg == PB_QR || reg == PB_G) {
; #pragma unroll
;                         for (int j = 0; j < 8; ++j) v[j] = silu(v[j]);
.LBB0_1258:
	s_andn2_b64 vcc, exec, s[0:1]
	s_cbranch_vccnz .LBB0_1260
	v_mul_f32_e32 v8, 0xbfb8aa3b, v26
	v_exp_f32_e32 v8, v8
	v_mul_f32_e32 v0, 0xbfb8aa3b, v30
	v_mul_f32_e32 v1, 0xbfb8aa3b, v31
	v_mul_f32_e32 v2, 0xbfb8aa3b, v28
	v_add_f32_e32 v8, 1.0, v8
	v_mul_f32_e32 v3, 0xbfb8aa3b, v29
	v_rcp_f32_e32 v10, v8
	v_mul_f32_e32 v8, 0xbfb8aa3b, v27
	v_mul_f32_e32 v9, 0xbfb8aa3b, v24
	v_mul_f32_e32 v11, 0xbfb8aa3b, v25
	v_exp_f32_e32 v0, v0
	v_exp_f32_e32 v1, v1
	v_exp_f32_e32 v2, v2
	v_exp_f32_e32 v3, v3
	v_exp_f32_e32 v8, v8
	v_exp_f32_e32 v9, v9
	v_exp_f32_e32 v11, v11
	v_add_f32_e32 v0, 1.0, v0
	v_add_f32_e32 v1, 1.0, v1
	v_add_f32_e32 v2, 1.0, v2
	v_add_f32_e32 v3, 1.0, v3
	v_add_f32_e32 v36, 1.0, v8
	v_add_f32_e32 v8, 1.0, v9
	v_add_f32_e32 v9, 1.0, v11
	v_rcp_f32_e32 v0, v0
	v_rcp_f32_e32 v1, v1
	v_rcp_f32_e32 v2, v2
	v_rcp_f32_e32 v3, v3
	v_rcp_f32_e32 v8, v8
	v_rcp_f32_e32 v9, v9
	v_rcp_f32_e32 v11, v36
	v_mul_f32_e32 v38, v28, v2
	v_mul_f32_e32 v39, v29, v3
	v_mul_f32_e32 v36, v30, v0
	v_mul_f32_e32 v37, v31, v1
	v_mul_f32_e32 v8, v24, v8
	v_mul_f32_e32 v9, v25, v9
	v_mul_f32_e32 v10, v26, v10
	v_mul_f32_e32 v11, v27, v11

;     __device__ __forceinline__ void operator()(const f32x4 (&acc)[2][2][4][2], const Unit& u, int wr, int wc, int fr, int fq) const {
;     ...
;                     if (reg <= 1) {
;                         if (rope) { const float cs[8] = {c0[0], c0[1], c0[2], c0[3], c1[0], c1[1], c1[2], c1[3]}; const float sn[8] = {s0[0], s0[1], s0[2], s0[3], s1[0], s1[1], s1[2], s1[3]};
; #pragma unroll
;                             for (int j = 0; j < 8; ++j) { const float o = __shfl_xor(v[j], 16); if (fq == 0) v[j] = v[j] * cs[j] - o * sn[j]; else if (fq == 1) v[j] = v[j] * cs[j] + o * sn[j]; } }
.LBB0_1261:
	s_and_b64 vcc, exec, s[10:11]
	s_cbranch_vccnz .LBB0_1356
	v_and_b32_e32 v1, 64, v214
	v_xor_b32_e32 v0, 16, v214
	v_add_u32_e32 v1, 64, v1
	v_cmp_lt_i32_e32 vcc, v0, v1
	s_nop 1
	v_cndmask_b32_e32 v0, v214, v0, vcc
	v_lshlrev_b32_e32 v2, 2, v0
	ds_bpermute_b32 v1, v2, v30
	v_cmp_lt_i32_e32 vcc, 0, v204
	s_and_saveexec_b64 s[0:1], vcc
	s_xor_b64 s[0:1], exec, s[0:1]
	s_cbranch_execz .LBB0_1266
	v_cmp_eq_u32_e32 vcc, 1, v204
	v_mov_b32_e32 v39, v25
	v_mov_b32_e32 v38, v24
	v_mov_b32_e32 v43, v27
	v_mov_b32_e32 v42, v26
	v_mov_b32_e32 v41, v29
	v_mov_b32_e32 v40, v28
	v_mov_b32_e32 v37, v31
	v_mov_b32_e32 v36, v30
	s_and_saveexec_b64 s[6:7], vcc
	s_cbranch_execz .LBB0_1265
	v_mov_b32_e32 v8, v30
	v_mov_b32_e32 v9, v20
	v_mov_b32_e32 v0, v16
	s_waitcnt lgkmcnt(0)
	v_mul_f32_e32 v0, v8, v0
	v_mul_f32_e32 v1, v9, v1
	v_mov_b32_e32 v39, v25
	v_add_f32_e32 v36, v0, v1
	v_mov_b32_e32 v38, v24
	v_mov_b32_e32 v43, v27
	v_mov_b32_e32 v42, v26
	v_mov_b32_e32 v41, v29
	v_mov_b32_e32 v40, v28
	v_mov_b32_e32 v37, v31

;     __device__ __forceinline__ void operator()(const f32x4 (&acc)[2][2][4][2], const Unit& u, int wr, int wc, int fr, int fq) const {
;     ...
;                     if (reg <= 1) {
;                         if (rope) { const float cs[8] = {c0[0], c0[1], c0[2], c0[3], c1[0], c1[1], c1[2], c1[3]}; const float sn[8] = {s0[0], s0[1], s0[2], s0[3], s1[0], s1[1], s1[2], s1[3]};
; #pragma unroll
;                             for (int j = 0; j < 8; ++j) { const float o = __shfl_xor(v[j], 16); if (fq == 0) v[j] = v[j] * cs[j] - o * sn[j]; else if (fq == 1) v[j] = v[j] * cs[j] + o * sn[j]; } }
.LBB0_1266:
	s_andn2_saveexec_b64 s[0:1], s[0:1]
	s_cbranch_execz .LBB0_1268
	v_mov_b32_e32 v8, v30
	v_mov_b32_e32 v9, v20
	v_mov_b32_e32 v0, v16
	s_waitcnt lgkmcnt(0)
	v_mul_f32_e32 v0, v8, v0
	v_mul_f32_e32 v1, v9, v1
	v_mov_b32_e32 v37, v31
	v_sub_f32_e32 v36, v0, v1
	v_mov_b32_e32 v40, v28
	v_mov_b32_e32 v41, v29
	v_mov_b32_e32 v42, v26
	v_mov_b32_e32 v43, v27
	v_mov_b32_e32 v38, v24
	v_mov_b32_e32 v39, v25
.LBB0_1268:
	s_or_b64 exec, exec, s[0:1]
	s_waitcnt lgkmcnt(0)
	ds_bpermute_b32 v1, v2, v37
	v_cmp_lt_i32_e32 vcc, 0, v204
	s_and_saveexec_b64 s[0:1], vcc
	s_xor_b64 s[0:1], exec, s[0:1]
	s_cbranch_execz .LBB0_1272
	v_cmp_eq_u32_e32 vcc, 1, v204
	s_and_saveexec_b64 s[6:7], vcc
	s_cbranch_execz .LBB0_1271
	v_mov_b32_e32 v20, v17
	v_mov_b32_e32 v0, v37
	v_mul_f32_e32 v8, v17, v37
	s_waitcnt lgkmcnt(0)
	v_fma_f32 v0, v20, v0, v8
	v_fma_f32 v1, v21, v1, v8
	s_nop 0
	v_mov_b32_e32 v37, v1

;     __device__ __forceinline__ void operator()(const f32x4 (&acc)[2][2][4][2], const Unit& u, int wr, int wc, int fr, int fq) const {
;     ...
;                     if (reg <= 1) {
;                         if (rope) { const float cs[8] = {c0[0], c0[1], c0[2], c0[3], c1[0], c1[1], c1[2], c1[3]}; const float sn[8] = {s0[0], s0[1], s0[2], s0[3], s1[0], s1[1], s1[2], s1[3]};
; #pragma unroll
;                             for (int j = 0; j < 8; ++j) { const float o = __shfl_xor(v[j], 16); if (fq == 0) v[j] = v[j] * cs[j] - o * sn[j]; else if (fq == 1) v[j] = v[j] * cs[j] + o * sn[j]; } }
.LBB0_1272:
	s_andn2_saveexec_b64 s[0:1], s[0:1]
	s_cbranch_execz .LBB0_1274
	v_mov_b32_e32 v20, v17
	v_mov_b32_e32 v0, v37
	v_mul_f32_e32 v8, v17, v37
	s_waitcnt lgkmcnt(0)
	v_fma_f32 v0, -v20, v0, v8
	v_fma_f32 v1, -v21, v1, v8
	s_nop 0
	v_mov_b32_e32 v37, v1
.LBB0_1274:
	s_or_b64 exec, exec, s[0:1]
	s_waitcnt lgkmcnt(0)
	ds_bpermute_b32 v1, v2, v40
	v_cmp_lt_i32_e32 vcc, 0, v204
	s_and_saveexec_b64 s[0:1], vcc
	s_xor_b64 s[0:1], exec, s[0:1]
	s_cbranch_execz .LBB0_1278
	v_cmp_eq_u32_e32 vcc, 1, v204
	s_and_saveexec_b64 s[6:7], vcc
	s_cbranch_execz .LBB0_1277
	v_mov_b32_e32 v8, v18
	v_mov_b32_e32 v9, v22
	v_mov_b32_e32 v0, v40
	s_waitcnt lgkmcnt(0)
	v_mul_f32_e32 v10, v22, v1
	v_fma_f32 v0, v8, v0, v10
	v_fma_f32 v1, v9, v1, v10
	s_nop 0
	v_mov_b32_e32 v40, v0

;     __device__ __forceinline__ void operator()(const f32x4 (&acc)[2][2][4][2], const Unit& u, int wr, int wc, int fr, int fq) const {
;     ...
;                     if (reg <= 1) {
;                         if (rope) { const float cs[8] = {c0[0], c0[1], c0[2], c0[3], c1[0], c1[1], c1[2], c1[3]}; const float sn[8] = {s0[0], s0[1], s0[2], s0[3], s1[0], s1[1], s1[2], s1[3]};
; #pragma unroll
;                             for (int j = 0; j < 8; ++j) { const float o = __shfl_xor(v[j], 16); if (fq == 0) v[j] = v[j] * cs[j] - o * sn[j]; else if (fq == 1) v[j] = v[j] * cs[j] + o * sn[j]; } }
.LBB0_1278:
	s_andn2_saveexec_b64 s[0:1], s[0:1]
	s_cbranch_execz .LBB0_1280
	v_mov_b32_e32 v8, v18
	v_mov_b32_e32 v9, v22
	v_mov_b32_e32 v0, v40
	s_waitcnt lgkmcnt(0)
	v_mul_f32_e32 v10, v22, v1
	v_fma_f32 v0, v8, v0, -v10
	v_fma_f32 v1, v9, v1, -v10
	s_nop 0
	v_mov_b32_e32 v40, v0
.LBB0_1280:
	s_or_b64 exec, exec, s[0:1]
	s_waitcnt lgkmcnt(0)
	ds_bpermute_b32 v1, v2, v41
	v_cmp_lt_i32_e32 vcc, 0, v204
	s_and_saveexec_b64 s[0:1], vcc
	s_xor_b64 s[0:1], exec, s[0:1]
	s_cbranch_execz .LBB0_1284
	v_cmp_eq_u32_e32 vcc, 1, v204
	s_and_saveexec_b64 s[6:7], vcc
	s_cbranch_execz .LBB0_1283
	v_mov_b32_e32 v22, v19
	v_mov_b32_e32 v0, v41
	s_waitcnt lgkmcnt(0)
	v_mul_f32_e32 v8, v23, v1
	v_fma_f32 v0, v22, v0, v8
	v_fma_f32 v1, v23, v1, v8
	s_nop 0
	v_mov_b32_e32 v41, v0

;     __device__ __forceinline__ void operator()(const f32x4 (&acc)[2][2][4][2], const Unit& u, int wr, int wc, int fr, int fq) const {
;     ...
;                     if (reg <= 1) {
;                         if (rope) { const float cs[8] = {c0[0], c0[1], c0[2], c0[3], c1[0], c1[1], c1[2], c1[3]}; const float sn[8] = {s0[0], s0[1], s0[2], s0[3], s1[0], s1[1], s1[2], s1[3]};
; #pragma unroll
;                             for (int j = 0; j < 8; ++j) { const float o = __shfl_xor(v[j], 16); if (fq == 0) v[j] = v[j] * cs[j] - o * sn[j]; else if (fq == 1) v[j] = v[j] * cs[j] + o * sn[j]; } }
.LBB0_1284:
	s_andn2_saveexec_b64 s[0:1], s[0:1]
	s_cbranch_execz .LBB0_1286
	v_mov_b32_e32 v22, v19
	v_mov_b32_e32 v0, v41
	s_waitcnt lgkmcnt(0)
	v_mul_f32_e32 v8, v23, v1
	v_fma_f32 v0, v22, v0, -v8
	v_fma_f32 v1, v23, v1, -v8
	s_nop 0
	v_mov_b32_e32 v41, v0
.LBB0_1286:
	s_or_b64 exec, exec, s[0:1]
	s_waitcnt lgkmcnt(0)
	ds_bpermute_b32 v1, v2, v42
	v_cmp_lt_i32_e32 vcc, 0, v204
	s_and_saveexec_b64 s[0:1], vcc
	s_xor_b64 s[0:1], exec, s[0:1]
	s_cbranch_execz .LBB0_1290
	v_cmp_eq_u32_e32 vcc, 1, v204
	s_and_saveexec_b64 s[6:7], vcc
	s_cbranch_execz .LBB0_1289
	v_mov_b32_e32 v8, v4
	v_mov_b32_e32 v9, v12
	v_mov_b32_e32 v0, v42
	s_waitcnt lgkmcnt(0)
	v_mul_f32_e32 v10, v12, v1
	v_fma_f32 v0, v8, v0, v10
	v_fma_f32 v1, v9, v1, v10
	s_nop 0
	v_mov_b32_e32 v42, v0

;     __device__ __forceinline__ void operator()(const f32x4 (&acc)[2][2][4][2], const Unit& u, int wr, int wc, int fr, int fq) const {
;     ...
;                     if (reg <= 1) {
;                         if (rope) { const float cs[8] = {c0[0], c0[1], c0[2], c0[3], c1[0], c1[1], c1[2], c1[3]}; const float sn[8] = {s0[0], s0[1], s0[2], s0[3], s1[0], s1[1], s1[2], s1[3]};
; #pragma unroll
;                             for (int j = 0; j < 8; ++j) { const float o = __shfl_xor(v[j], 16); if (fq == 0) v[j] = v[j] * cs[j] - o * sn[j]; else if (fq == 1) v[j] = v[j] * cs[j] + o * sn[j]; } }
.LBB0_1290:
	s_andn2_saveexec_b64 s[0:1], s[0:1]
	s_cbranch_execz .LBB0_1292
	v_mov_b32_e32 v8, v4
	v_mov_b32_e32 v9, v12
	v_mov_b32_e32 v0, v42
	s_waitcnt lgkmcnt(0)
	v_mul_f32_e32 v4, v12, v1
	v_fma_f32 v0, v8, v0, -v4
	v_fma_f32 v1, v9, v1, -v4
	s_nop 0
	v_mov_b32_e32 v42, v0
.LBB0_1292:
	s_or_b64 exec, exec, s[0:1]
	s_waitcnt lgkmcnt(0)
	ds_bpermute_b32 v1, v2, v43
	v_cmp_lt_i32_e32 vcc, 0, v204
	s_and_saveexec_b64 s[0:1], vcc
	s_xor_b64 s[0:1], exec, s[0:1]
	s_cbranch_execz .LBB0_1296
	v_cmp_eq_u32_e32 vcc, 1, v204
	s_and_saveexec_b64 s[6:7], vcc
	s_cbranch_execz .LBB0_1295
	v_mov_b32_e32 v12, v5
	v_mov_b32_e32 v0, v43
	s_waitcnt lgkmcnt(0)
	v_mul_f32_e32 v4, v13, v1
	v_fma_f32 v0, v12, v0, v4
	v_fma_f32 v1, v13, v1, v4
	s_nop 0
	v_mov_b32_e32 v43, v0

;     __device__ __forceinline__ void operator()(const f32x4 (&acc)[2][2][4][2], const Unit& u, int wr, int wc, int fr, int fq) const {
;     ...
;                     if (reg <= 1) {
;                         if (rope) { const float cs[8] = {c0[0], c0[1], c0[2], c0[3], c1[0], c1[1], c1[2], c1[3]}; const float sn[8] = {s0[0], s0[1], s0[2], s0[3], s1[0], s1[1], s1[2], s1[3]};
; #pragma unroll
;                             for (int j = 0; j < 8; ++j) { const float o = __shfl_xor(v[j], 16); if (fq == 0) v[j] = v[j] * cs[j] - o * sn[j]; else if (fq == 1) v[j] = v[j] * cs[j] + o * sn[j]; } }
.LBB0_1296:
	s_andn2_saveexec_b64 s[0:1], s[0:1]
	s_cbranch_execz .LBB0_1298
	v_mov_b32_e32 v12, v5
	v_mov_b32_e32 v0, v43
	s_waitcnt lgkmcnt(0)
	v_mul_f32_e32 v4, v13, v1
	v_fma_f32 v0, v12, v0, -v4
	v_fma_f32 v1, v13, v1, -v4
	s_nop 0
	v_mov_b32_e32 v43, v0
.LBB0_1298:
	s_or_b64 exec, exec, s[0:1]
	s_waitcnt lgkmcnt(0)
	ds_bpermute_b32 v1, v2, v38
	v_cmp_lt_i32_e32 vcc, 0, v204
	s_and_saveexec_b64 s[0:1], vcc
	s_xor_b64 s[0:1], exec, s[0:1]
	s_cbranch_execz .LBB0_1302
	v_cmp_eq_u32_e32 vcc, 1, v204
	s_and_saveexec_b64 s[6:7], vcc
	s_cbranch_execz .LBB0_1301
	v_mov_b32_e32 v4, v6
	v_mov_b32_e32 v5, v14
	v_mov_b32_e32 v0, v38
	s_waitcnt lgkmcnt(0)
	v_mul_f32_e32 v8, v14, v1
	v_fma_f32 v0, v4, v0, v8
	v_fma_f32 v1, v5, v1, v8
	s_nop 0
	v_mov_b32_e32 v38, v0

;     __device__ __forceinline__ void operator()(const f32x4 (&acc)[2][2][4][2], const Unit& u, int wr, int wc, int fr, int fq) const {
;     ...
;                     if (reg <= 1) {
;                         if (rope) { const float cs[8] = {c0[0], c0[1], c0[2], c0[3], c1[0], c1[1], c1[2], c1[3]}; const float sn[8] = {s0[0], s0[1], s0[2], s0[3], s1[0], s1[1], s1[2], s1[3]};
; #pragma unroll
;                             for (int j = 0; j < 8; ++j) { const float o = __shfl_xor(v[j], 16); if (fq == 0) v[j] = v[j] * cs[j] - o * sn[j]; else if (fq == 1) v[j] = v[j] * cs[j] + o * sn[j]; } }
.LBB0_1302:
	s_andn2_saveexec_b64 s[0:1], s[0:1]
	s_cbranch_execz .LBB0_1304
	v_mov_b32_e32 v4, v6
	v_mov_b32_e32 v5, v14
	v_mov_b32_e32 v0, v38
	s_waitcnt lgkmcnt(0)
	v_mul_f32_e32 v6, v14, v1
	v_fma_f32 v0, v4, v0, -v6
	v_fma_f32 v1, v5, v1, -v6
	s_nop 0
	v_mov_b32_e32 v38, v0
.LBB0_1304:
	s_or_b64 exec, exec, s[0:1]
	s_waitcnt lgkmcnt(0)
	ds_bpermute_b32 v1, v2, v39
	v_cmp_lt_i32_e32 vcc, 0, v204
	s_and_saveexec_b64 s[0:1], vcc
	s_xor_b64 s[0:1], exec, s[0:1]
	s_cbranch_execz .LBB0_1308
	v_cmp_eq_u32_e32 vcc, 1, v204
	s_and_saveexec_b64 s[6:7], vcc
	s_cbranch_execz .LBB0_1307
	v_mov_b32_e32 v14, v7
	v_mov_b32_e32 v0, v39
	s_waitcnt lgkmcnt(0)
	v_mul_f32_e32 v2, v15, v1
	v_fma_f32 v0, v14, v0, v2
	v_fma_f32 v1, v15, v1, v2
	s_nop 0
	v_mov_b32_e32 v39, v0

;     __device__ __forceinline__ void operator()(const f32x4 (&acc)[2][2][4][2], const Unit& u, int wr, int wc, int fr, int fq) const {
;     ...
;                     if (reg <= 1) {
;                         if (rope) { const float cs[8] = {c0[0], c0[1], c0[2], c0[3], c1[0], c1[1], c1[2], c1[3]}; const float sn[8] = {s0[0], s0[1], s0[2], s0[3], s1[0], s1[1], s1[2], s1[3]};
; #pragma unroll
;                             for (int j = 0; j < 8; ++j) { const float o = __shfl_xor(v[j], 16); if (fq == 0) v[j] = v[j] * cs[j] - o * sn[j]; else if (fq == 1) v[j] = v[j] * cs[j] + o * sn[j]; } }
.LBB0_1308:
	s_andn2_saveexec_b64 s[0:1], s[0:1]
	s_cbranch_execz .LBB0_1310
	v_mov_b32_e32 v14, v7
	v_mov_b32_e32 v0, v39
	s_waitcnt lgkmcnt(0)
	v_mul_f32_e32 v2, v15, v1
	v_fma_f32 v0, v14, v0, -v2
	v_fma_f32 v1, v15, v1, -v2
	s_nop 0
	v_mov_b32_e32 v39, v0

; template <int RSM> __device__ __forceinline__ float row_scale(const float* p, int row) { const float v = __hip_atomic_load(p + row, __ATOMIC_RELAXED, __HIP_MEMORY_SCOPE_AGENT); return RSM == 0 ? v : 1.0f / sqrtf(v * (1.f / DM) + EPS); }
;     __device__ __forceinline__ void operator()(const f32x4 (&acc)[2][2][4][2], const Unit& u, int wr, int wc, int fr, int fq) const {
;     ...
;             for (int m = 0; m < 4; ++m) { const int row = row0 + ai * HALF + m * 16; const float sc = row_scale<1>(rs, row);
;                 f32x4 c0, c1, s0, s1;
;                 if (rope) { const int pos = row & (SEQ - 1); c0 = *(const f32x4*)(ropeC + pos * 8); c1 = *(const f32x4*)(ropeC + pos * 8 + 4); s0 = *(const f32x4*)(ropeS + pos * 8); s1 = *(const f32x4*)(ropeS + pos * 8 + 4); }
; #pragma unroll
;                 for (int bj = 0; bj < 2; ++bj) { const f32x4 a0 = acc[ai][bj][m][0] * sc, a1 = acc[ai][bj][m][1] * sc;
;                     float v[8] = {a0[0], a0[1], a0[2], a0[3], a1[0], a1[1], a1[2], a1[3]};
.LBB0_1312:
	s_waitcnt lgkmcnt(0)
	v_mul_f32_e32 v200, v152, v138
	v_mul_f32_e32 v201, v152, v139
	v_mul_f32_e32 v198, v152, v198
	v_mul_f32_e32 v199, v152, v199
	v_mul_f32_e32 v196, v152, v196
	v_mul_f32_e32 v197, v152, v197
	v_mul_f32_e32 v202, v152, v136
	v_mul_f32_e32 v203, v152, v137
	s_mov_b64 s[0:1], -1
	s_and_b64 vcc, exec, s[4:5]
	s_cbranch_vccz .LBB0_274

; template <int RSM> __device__ __forceinline__ float row_scale(const float* p, int row) { const float v = __hip_atomic_load(p + row, __ATOMIC_RELAXED, __HIP_MEMORY_SCOPE_AGENT); return RSM == 0 ? v : 1.0f / sqrtf(v * (1.f / DM) + EPS); }
;     __device__ __forceinline__ void operator()(const f32x4 (&acc)[2][2][4][2], const Unit& u, int wr, int wc, int fr, int fq) const {
;     ...
;             for (int m = 0; m < 4; ++m) { const int row = row0 + ai * HALF + m * 16; const float sc = row_scale<1>(rs, row);
;                 f32x4 c0, c1, s0, s1;
;                 if (rope) { const int pos = row & (SEQ - 1); c0 = *(const f32x4*)(ropeC + pos * 8); c1 = *(const f32x4*)(ropeC + pos * 8 + 4); s0 = *(const f32x4*)(ropeS + pos * 8); s1 = *(const f32x4*)(ropeS + pos * 8 + 4); }
; #pragma unroll
;                 for (int bj = 0; bj < 2; ++bj) { const f32x4 a0 = acc[ai][bj][m][0] * sc, a1 = acc[ai][bj][m][1] * sc;
;                     float v[8] = {a0[0], a0[1], a0[2], a0[3], a1[0], a1[1], a1[2], a1[3]};
.LBB0_1315:
	s_waitcnt lgkmcnt(0)
	v_mul_f32_e32 v190, v152, v130
	v_mul_f32_e32 v191, v152, v131
	v_mul_f32_e32 v142, v152, v142
	v_mul_f32_e32 v143, v152, v143
	v_mul_f32_e32 v140, v152, v140
	v_mul_f32_e32 v141, v152, v141
	v_mul_f32_e32 v192, v152, v128
	v_mul_f32_e32 v193, v152, v129
	s_andn2_b64 vcc, exec, s[4:5]
	s_mov_b64 s[0:1], -1
	s_cbranch_vccnz .LBB0_283

; template <int RSM> __device__ __forceinline__ float row_scale(const float* p, int row) { const float v = __hip_atomic_load(p + row, __ATOMIC_RELAXED, __HIP_MEMORY_SCOPE_AGENT); return RSM == 0 ? v : 1.0f / sqrtf(v * (1.f / DM) + EPS); }
;     __device__ __forceinline__ void operator()(const f32x4 (&acc)[2][2][4][2], const Unit& u, int wr, int wc, int fr, int fq) const {
;     ...
;             for (int m = 0; m < 4; ++m) { const int row = row0 + ai * HALF + m * 16; const float sc = row_scale<1>(rs, row);
;                 f32x4 c0, c1, s0, s1;
;                 if (rope) { const int pos = row & (SEQ - 1); c0 = *(const f32x4*)(ropeC + pos * 8); c1 = *(const f32x4*)(ropeC + pos * 8 + 4); s0 = *(const f32x4*)(ropeS + pos * 8); s1 = *(const f32x4*)(ropeS + pos * 8 + 4); }
; #pragma unroll
;                 for (int bj = 0; bj < 2; ++bj) { const f32x4 a0 = acc[ai][bj][m][0] * sc, a1 = acc[ai][bj][m][1] * sc;
;                     float v[8] = {a0[0], a0[1], a0[2], a0[3], a1[0], a1[1], a1[2], a1[3]};
.LBB0_1318:
	s_waitcnt lgkmcnt(0)
	v_mul_f32_e32 v142, v152, v122
	v_mul_f32_e32 v143, v152, v123
	v_mul_f32_e32 v140, v152, v140
	v_mul_f32_e32 v141, v152, v141
	v_mul_f32_e32 v138, v152, v138
	v_mul_f32_e32 v139, v152, v139
	v_mul_f32_e32 v186, v152, v120
	v_mul_f32_e32 v187, v152, v121
	s_andn2_b64 vcc, exec, s[4:5]
	s_mov_b64 s[0:1], -1
	s_cbranch_vccnz .LBB0_294

; template <int RSM> __device__ __forceinline__ float row_scale(const float* p, int row) { const float v = __hip_atomic_load(p + row, __ATOMIC_RELAXED, __HIP_MEMORY_SCOPE_AGENT); return RSM == 0 ? v : 1.0f / sqrtf(v * (1.f / DM) + EPS); }
;     __device__ __forceinline__ void operator()(const f32x4 (&acc)[2][2][4][2], const Unit& u, int wr, int wc, int fr, int fq) const {
;     ...
;             for (int m = 0; m < 4; ++m) { const int row = row0 + ai * HALF + m * 16; const float sc = row_scale<1>(rs, row);
;                 f32x4 c0, c1, s0, s1;
;                 if (rope) { const int pos = row & (SEQ - 1); c0 = *(const f32x4*)(ropeC + pos * 8); c1 = *(const f32x4*)(ropeC + pos * 8 + 4); s0 = *(const f32x4*)(ropeS + pos * 8); s1 = *(const f32x4*)(ropeS + pos * 8 + 4); }
; #pragma unroll
;                 for (int bj = 0; bj < 2; ++bj) { const f32x4 a0 = acc[ai][bj][m][0] * sc, a1 = acc[ai][bj][m][1] * sc;
;                     float v[8] = {a0[0], a0[1], a0[2], a0[3], a1[0], a1[1], a1[2], a1[3]};
.LBB0_1321:
	s_waitcnt lgkmcnt(0)
	v_mul_f32_e32 v132, v152, v114
	v_mul_f32_e32 v133, v152, v115
	v_mul_f32_e32 v126, v152, v126
	v_mul_f32_e32 v127, v152, v127
	v_mul_f32_e32 v124, v152, v124
	v_mul_f32_e32 v125, v152, v125
	v_mul_f32_e32 v134, v152, v112
	v_mul_f32_e32 v135, v152, v113
	s_andn2_b64 vcc, exec, s[4:5]
	s_mov_b64 s[0:1], -1
	s_cbranch_vccnz .LBB0_303

; template <int RSM> __device__ __forceinline__ float row_scale(const float* p, int row) { const float v = __hip_atomic_load(p + row, __ATOMIC_RELAXED, __HIP_MEMORY_SCOPE_AGENT); return RSM == 0 ? v : 1.0f / sqrtf(v * (1.f / DM) + EPS); }
;     __device__ __forceinline__ void operator()(const f32x4 (&acc)[2][2][4][2], const Unit& u, int wr, int wc, int fr, int fq) const {
;     ...
;             for (int m = 0; m < 4; ++m) { const int row = row0 + ai * HALF + m * 16; const float sc = row_scale<1>(rs, row);
;                 f32x4 c0, c1, s0, s1;
;                 if (rope) { const int pos = row & (SEQ - 1); c0 = *(const f32x4*)(ropeC + pos * 8); c1 = *(const f32x4*)(ropeC + pos * 8 + 4); s0 = *(const f32x4*)(ropeS + pos * 8); s1 = *(const f32x4*)(ropeS + pos * 8 + 4); }
; #pragma unroll
;                 for (int bj = 0; bj < 2; ++bj) { const f32x4 a0 = acc[ai][bj][m][0] * sc, a1 = acc[ai][bj][m][1] * sc;
;                     float v[8] = {a0[0], a0[1], a0[2], a0[3], a1[0], a1[1], a1[2], a1[3]};
.LBB0_1324:
	s_waitcnt lgkmcnt(0)
	v_mul_f32_e32 v126, v152, v106
	v_mul_f32_e32 v127, v152, v107
	v_mul_f32_e32 v124, v152, v124
	v_mul_f32_e32 v125, v152, v125
	v_mul_f32_e32 v122, v152, v122
	v_mul_f32_e32 v123, v152, v123
	v_mul_f32_e32 v128, v152, v104
	v_mul_f32_e32 v129, v152, v105
	s_andn2_b64 vcc, exec, s[4:5]
	s_mov_b64 s[0:1], -1
	s_cbranch_vccnz .LBB0_314

; template <int RSM> __device__ __forceinline__ float row_scale(const float* p, int row) { const float v = __hip_atomic_load(p + row, __ATOMIC_RELAXED, __HIP_MEMORY_SCOPE_AGENT); return RSM == 0 ? v : 1.0f / sqrtf(v * (1.f / DM) + EPS); }
;     __device__ __forceinline__ void operator()(const f32x4 (&acc)[2][2][4][2], const Unit& u, int wr, int wc, int fr, int fq) const {
;     ...
;             for (int m = 0; m < 4; ++m) { const int row = row0 + ai * HALF + m * 16; const float sc = row_scale<1>(rs, row);
;                 f32x4 c0, c1, s0, s1;
;                 if (rope) { const int pos = row & (SEQ - 1); c0 = *(const f32x4*)(ropeC + pos * 8); c1 = *(const f32x4*)(ropeC + pos * 8 + 4); s0 = *(const f32x4*)(ropeS + pos * 8); s1 = *(const f32x4*)(ropeS + pos * 8 + 4); }
; #pragma unroll
;                 for (int bj = 0; bj < 2; ++bj) { const f32x4 a0 = acc[ai][bj][m][0] * sc, a1 = acc[ai][bj][m][1] * sc;
;                     float v[8] = {a0[0], a0[1], a0[2], a0[3], a1[0], a1[1], a1[2], a1[3]};
.LBB0_1327:
	s_waitcnt lgkmcnt(0)
	v_mul_f32_e32 v116, v152, v98
	v_mul_f32_e32 v117, v152, v99
	v_mul_f32_e32 v110, v152, v110
	v_mul_f32_e32 v111, v152, v111
	v_mul_f32_e32 v108, v152, v108
	v_mul_f32_e32 v109, v152, v109
	v_mul_f32_e32 v118, v152, v96
	v_mul_f32_e32 v119, v152, v97
	s_andn2_b64 vcc, exec, s[4:5]
	s_mov_b64 s[0:1], -1
	s_cbranch_vccnz .LBB0_323

; template <int RSM> __device__ __forceinline__ float row_scale(const float* p, int row) { const float v = __hip_atomic_load(p + row, __ATOMIC_RELAXED, __HIP_MEMORY_SCOPE_AGENT); return RSM == 0 ? v : 1.0f / sqrtf(v * (1.f / DM) + EPS); }
;     __device__ __forceinline__ void operator()(const f32x4 (&acc)[2][2][4][2], const Unit& u, int wr, int wc, int fr, int fq) const {
;     ...
;             for (int m = 0; m < 4; ++m) { const int row = row0 + ai * HALF + m * 16; const float sc = row_scale<1>(rs, row);
;                 f32x4 c0, c1, s0, s1;
;                 if (rope) { const int pos = row & (SEQ - 1); c0 = *(const f32x4*)(ropeC + pos * 8); c1 = *(const f32x4*)(ropeC + pos * 8 + 4); s0 = *(const f32x4*)(ropeS + pos * 8); s1 = *(const f32x4*)(ropeS + pos * 8 + 4); }
; #pragma unroll
;                 for (int bj = 0; bj < 2; ++bj) { const f32x4 a0 = acc[ai][bj][m][0] * sc, a1 = acc[ai][bj][m][1] * sc;
;                     float v[8] = {a0[0], a0[1], a0[2], a0[3], a1[0], a1[1], a1[2], a1[3]};
.LBB0_1330:
	s_waitcnt lgkmcnt(0)
	v_mul_f32_e32 v110, v152, v90
	v_mul_f32_e32 v111, v152, v91
	v_mul_f32_e32 v108, v152, v108
	v_mul_f32_e32 v109, v152, v109
	v_mul_f32_e32 v106, v152, v106
	v_mul_f32_e32 v107, v152, v107
	v_mul_f32_e32 v112, v152, v88
	v_mul_f32_e32 v113, v152, v89
	s_andn2_b64 vcc, exec, s[4:5]
	s_mov_b64 s[0:1], -1
	s_cbranch_vccnz .LBB0_334

; template <int RSM> __device__ __forceinline__ float row_scale(const float* p, int row) { const float v = __hip_atomic_load(p + row, __ATOMIC_RELAXED, __HIP_MEMORY_SCOPE_AGENT); return RSM == 0 ? v : 1.0f / sqrtf(v * (1.f / DM) + EPS); }
;     __device__ __forceinline__ void operator()(const f32x4 (&acc)[2][2][4][2], const Unit& u, int wr, int wc, int fr, int fq) const {
;     ...
;             for (int m = 0; m < 4; ++m) { const int row = row0 + ai * HALF + m * 16; const float sc = row_scale<1>(rs, row);
;                 f32x4 c0, c1, s0, s1;
;                 if (rope) { const int pos = row & (SEQ - 1); c0 = *(const f32x4*)(ropeC + pos * 8); c1 = *(const f32x4*)(ropeC + pos * 8 + 4); s0 = *(const f32x4*)(ropeS + pos * 8); s1 = *(const f32x4*)(ropeS + pos * 8 + 4); }
; #pragma unroll
;                 for (int bj = 0; bj < 2; ++bj) { const f32x4 a0 = acc[ai][bj][m][0] * sc, a1 = acc[ai][bj][m][1] * sc;
;                     float v[8] = {a0[0], a0[1], a0[2], a0[3], a1[0], a1[1], a1[2], a1[3]};
.LBB0_1333:
	s_waitcnt lgkmcnt(0)
	v_mul_f32_e32 v100, v152, v82
	v_mul_f32_e32 v101, v152, v83
	v_mul_f32_e32 v94, v152, v94
	v_mul_f32_e32 v95, v152, v95
	v_mul_f32_e32 v92, v152, v92
	v_mul_f32_e32 v93, v152, v93
	v_mul_f32_e32 v102, v152, v80
	v_mul_f32_e32 v103, v152, v81
	s_andn2_b64 vcc, exec, s[4:5]
	s_mov_b64 s[0:1], -1
	s_cbranch_vccnz .LBB0_343

; template <int RSM> __device__ __forceinline__ float row_scale(const float* p, int row) { const float v = __hip_atomic_load(p + row, __ATOMIC_RELAXED, __HIP_MEMORY_SCOPE_AGENT); return RSM == 0 ? v : 1.0f / sqrtf(v * (1.f / DM) + EPS); }
;     __device__ __forceinline__ void operator()(const f32x4 (&acc)[2][2][4][2], const Unit& u, int wr, int wc, int fr, int fq) const {
;     ...
;             for (int m = 0; m < 4; ++m) { const int row = row0 + ai * HALF + m * 16; const float sc = row_scale<1>(rs, row);
;                 f32x4 c0, c1, s0, s1;
;                 if (rope) { const int pos = row & (SEQ - 1); c0 = *(const f32x4*)(ropeC + pos * 8); c1 = *(const f32x4*)(ropeC + pos * 8 + 4); s0 = *(const f32x4*)(ropeS + pos * 8); s1 = *(const f32x4*)(ropeS + pos * 8 + 4); }
; #pragma unroll
;                 for (int bj = 0; bj < 2; ++bj) { const f32x4 a0 = acc[ai][bj][m][0] * sc, a1 = acc[ai][bj][m][1] * sc;
;                     float v[8] = {a0[0], a0[1], a0[2], a0[3], a1[0], a1[1], a1[2], a1[3]};
.LBB0_1336:
	s_waitcnt lgkmcnt(0)
	v_mul_f32_e32 v94, v152, v74
	v_mul_f32_e32 v95, v152, v75
	v_mul_f32_e32 v92, v152, v92
	v_mul_f32_e32 v93, v152, v93
	v_mul_f32_e32 v90, v152, v90
	v_mul_f32_e32 v91, v152, v91
	v_mul_f32_e32 v96, v152, v72
	v_mul_f32_e32 v97, v152, v73
	s_andn2_b64 vcc, exec, s[4:5]
	s_mov_b64 s[0:1], -1
	s_cbranch_vccnz .LBB0_354

; template <int RSM> __device__ __forceinline__ float row_scale(const float* p, int row) { const float v = __hip_atomic_load(p + row, __ATOMIC_RELAXED, __HIP_MEMORY_SCOPE_AGENT); return RSM == 0 ? v : 1.0f / sqrtf(v * (1.f / DM) + EPS); }
;     __device__ __forceinline__ void operator()(const f32x4 (&acc)[2][2][4][2], const Unit& u, int wr, int wc, int fr, int fq) const {
;     ...
;             for (int m = 0; m < 4; ++m) { const int row = row0 + ai * HALF + m * 16; const float sc = row_scale<1>(rs, row);
;                 f32x4 c0, c1, s0, s1;
;                 if (rope) { const int pos = row & (SEQ - 1); c0 = *(const f32x4*)(ropeC + pos * 8); c1 = *(const f32x4*)(ropeC + pos * 8 + 4); s0 = *(const f32x4*)(ropeS + pos * 8); s1 = *(const f32x4*)(ropeS + pos * 8 + 4); }
; #pragma unroll
;                 for (int bj = 0; bj < 2; ++bj) { const f32x4 a0 = acc[ai][bj][m][0] * sc, a1 = acc[ai][bj][m][1] * sc;
;                     float v[8] = {a0[0], a0[1], a0[2], a0[3], a1[0], a1[1], a1[2], a1[3]};
.LBB0_1339:
	s_waitcnt lgkmcnt(0)
	v_mul_f32_e32 v84, v152, v66
	v_mul_f32_e32 v85, v152, v67
	v_mul_f32_e32 v78, v152, v78
	v_mul_f32_e32 v79, v152, v79
	v_mul_f32_e32 v76, v152, v76
	v_mul_f32_e32 v77, v152, v77
	v_mul_f32_e32 v86, v152, v64
	v_mul_f32_e32 v87, v152, v65
	s_andn2_b64 vcc, exec, s[4:5]
	s_mov_b64 s[0:1], -1
	s_cbranch_vccnz .LBB0_363

; template <int RSM> __device__ __forceinline__ float row_scale(const float* p, int row) { const float v = __hip_atomic_load(p + row, __ATOMIC_RELAXED, __HIP_MEMORY_SCOPE_AGENT); return RSM == 0 ? v : 1.0f / sqrtf(v * (1.f / DM) + EPS); }
;     __device__ __forceinline__ void operator()(const f32x4 (&acc)[2][2][4][2], const Unit& u, int wr, int wc, int fr, int fq) const {
;     ...
;             for (int m = 0; m < 4; ++m) { const int row = row0 + ai * HALF + m * 16; const float sc = row_scale<1>(rs, row);
;                 f32x4 c0, c1, s0, s1;
;                 if (rope) { const int pos = row & (SEQ - 1); c0 = *(const f32x4*)(ropeC + pos * 8); c1 = *(const f32x4*)(ropeC + pos * 8 + 4); s0 = *(const f32x4*)(ropeS + pos * 8); s1 = *(const f32x4*)(ropeS + pos * 8 + 4); }
; #pragma unroll
;                 for (int bj = 0; bj < 2; ++bj) { const f32x4 a0 = acc[ai][bj][m][0] * sc, a1 = acc[ai][bj][m][1] * sc;
;                     float v[8] = {a0[0], a0[1], a0[2], a0[3], a1[0], a1[1], a1[2], a1[3]};
.LBB0_1342:
	s_waitcnt lgkmcnt(0)
	v_mul_f32_e32 v78, v152, v58
	v_mul_f32_e32 v79, v152, v59
	v_mul_f32_e32 v76, v152, v76
	v_mul_f32_e32 v77, v152, v77
	v_mul_f32_e32 v74, v152, v74
	v_mul_f32_e32 v75, v152, v75
	v_mul_f32_e32 v80, v152, v56
	v_mul_f32_e32 v81, v152, v57
	s_andn2_b64 vcc, exec, s[4:5]
	s_mov_b64 s[0:1], -1
	s_cbranch_vccnz .LBB0_374

; template <int RSM> __device__ __forceinline__ float row_scale(const float* p, int row) { const float v = __hip_atomic_load(p + row, __ATOMIC_RELAXED, __HIP_MEMORY_SCOPE_AGENT); return RSM == 0 ? v : 1.0f / sqrtf(v * (1.f / DM) + EPS); }
;     __device__ __forceinline__ void operator()(const f32x4 (&acc)[2][2][4][2], const Unit& u, int wr, int wc, int fr, int fq) const {
;     ...
;             for (int m = 0; m < 4; ++m) { const int row = row0 + ai * HALF + m * 16; const float sc = row_scale<1>(rs, row);
;                 f32x4 c0, c1, s0, s1;
;                 if (rope) { const int pos = row & (SEQ - 1); c0 = *(const f32x4*)(ropeC + pos * 8); c1 = *(const f32x4*)(ropeC + pos * 8 + 4); s0 = *(const f32x4*)(ropeS + pos * 8); s1 = *(const f32x4*)(ropeS + pos * 8 + 4); }
; #pragma unroll
;                 for (int bj = 0; bj < 2; ++bj) { const f32x4 a0 = acc[ai][bj][m][0] * sc, a1 = acc[ai][bj][m][1] * sc;
;                     float v[8] = {a0[0], a0[1], a0[2], a0[3], a1[0], a1[1], a1[2], a1[3]};
.LBB0_1345:
	s_waitcnt lgkmcnt(0)
	v_mul_f32_e32 v68, v152, v50
	v_mul_f32_e32 v69, v152, v51
	v_mul_f32_e32 v62, v152, v62
	v_mul_f32_e32 v63, v152, v63
	v_mul_f32_e32 v60, v152, v60
	v_mul_f32_e32 v61, v152, v61
	v_mul_f32_e32 v70, v152, v48
	v_mul_f32_e32 v71, v152, v49
	s_andn2_b64 vcc, exec, s[4:5]
	s_mov_b64 s[0:1], -1
	s_cbranch_vccnz .LBB0_383

; template <int RSM> __device__ __forceinline__ float row_scale(const float* p, int row) { const float v = __hip_atomic_load(p + row, __ATOMIC_RELAXED, __HIP_MEMORY_SCOPE_AGENT); return RSM == 0 ? v : 1.0f / sqrtf(v * (1.f / DM) + EPS); }
;     __device__ __forceinline__ void operator()(const f32x4 (&acc)[2][2][4][2], const Unit& u, int wr, int wc, int fr, int fq) const {
;     ...
;             for (int m = 0; m < 4; ++m) { const int row = row0 + ai * HALF + m * 16; const float sc = row_scale<1>(rs, row);
;                 f32x4 c0, c1, s0, s1;
;                 if (rope) { const int pos = row & (SEQ - 1); c0 = *(const f32x4*)(ropeC + pos * 8); c1 = *(const f32x4*)(ropeC + pos * 8 + 4); s0 = *(const f32x4*)(ropeS + pos * 8); s1 = *(const f32x4*)(ropeS + pos * 8 + 4); }
; #pragma unroll
;                 for (int bj = 0; bj < 2; ++bj) { const f32x4 a0 = acc[ai][bj][m][0] * sc, a1 = acc[ai][bj][m][1] * sc;
;                     float v[8] = {a0[0], a0[1], a0[2], a0[3], a1[0], a1[1], a1[2], a1[3]};
.LBB0_1348:
	s_waitcnt lgkmcnt(0)
	v_mul_f32_e32 v62, v152, v42
	v_mul_f32_e32 v63, v152, v43
	v_mul_f32_e32 v60, v152, v60
	v_mul_f32_e32 v61, v152, v61
	v_mul_f32_e32 v58, v152, v58
	v_mul_f32_e32 v59, v152, v59
	v_mul_f32_e32 v64, v152, v40
	v_mul_f32_e32 v65, v152, v41
	s_andn2_b64 vcc, exec, s[4:5]
	s_mov_b64 s[0:1], -1
	s_cbranch_vccnz .LBB0_394

; template <int RSM> __device__ __forceinline__ float row_scale(const float* p, int row) { const float v = __hip_atomic_load(p + row, __ATOMIC_RELAXED, __HIP_MEMORY_SCOPE_AGENT); return RSM == 0 ? v : 1.0f / sqrtf(v * (1.f / DM) + EPS); }
;     __device__ __forceinline__ void operator()(const f32x4 (&acc)[2][2][4][2], const Unit& u, int wr, int wc, int fr, int fq) const {
;     ...
;             for (int m = 0; m < 4; ++m) { const int row = row0 + ai * HALF + m * 16; const float sc = row_scale<1>(rs, row);
;                 f32x4 c0, c1, s0, s1;
;                 if (rope) { const int pos = row & (SEQ - 1); c0 = *(const f32x4*)(ropeC + pos * 8); c1 = *(const f32x4*)(ropeC + pos * 8 + 4); s0 = *(const f32x4*)(ropeS + pos * 8); s1 = *(const f32x4*)(ropeS + pos * 8 + 4); }
; #pragma unroll
;                 for (int bj = 0; bj < 2; ++bj) { const f32x4 a0 = acc[ai][bj][m][0] * sc, a1 = acc[ai][bj][m][1] * sc;
;                     float v[8] = {a0[0], a0[1], a0[2], a0[3], a1[0], a1[1], a1[2], a1[3]};
.LBB0_1351:
	s_waitcnt lgkmcnt(0)
	v_mul_f32_e32 v52, v152, v34
	v_mul_f32_e32 v53, v152, v35
	v_mul_f32_e32 v46, v152, v46
	v_mul_f32_e32 v47, v152, v47
	v_mul_f32_e32 v44, v152, v44
	v_mul_f32_e32 v45, v152, v45
	v_mul_f32_e32 v54, v152, v32
	v_mul_f32_e32 v55, v152, v33
	s_andn2_b64 vcc, exec, s[4:5]
	s_mov_b64 s[0:1], -1
	s_cbranch_vccnz .LBB0_403

; template <int RSM> __device__ __forceinline__ float row_scale(const float* p, int row) { const float v = __hip_atomic_load(p + row, __ATOMIC_RELAXED, __HIP_MEMORY_SCOPE_AGENT); return RSM == 0 ? v : 1.0f / sqrtf(v * (1.f / DM) + EPS); }
;     __device__ __forceinline__ void operator()(const f32x4 (&acc)[2][2][4][2], const Unit& u, int wr, int wc, int fr, int fq) const {
;     ...
;             for (int m = 0; m < 4; ++m) { const int row = row0 + ai * HALF + m * 16; const float sc = row_scale<1>(rs, row);
;                 f32x4 c0, c1, s0, s1;
;                 if (rope) { const int pos = row & (SEQ - 1); c0 = *(const f32x4*)(ropeC + pos * 8); c1 = *(const f32x4*)(ropeC + pos * 8 + 4); s0 = *(const f32x4*)(ropeS + pos * 8); s1 = *(const f32x4*)(ropeS + pos * 8 + 4); }
; #pragma unroll
;                 for (int bj = 0; bj < 2; ++bj) { const f32x4 a0 = acc[ai][bj][m][0] * sc, a1 = acc[ai][bj][m][1] * sc;
;                     float v[8] = {a0[0], a0[1], a0[2], a0[3], a1[0], a1[1], a1[2], a1[3]};
.LBB0_1354:
	s_waitcnt lgkmcnt(0)
	v_mul_f32_e32 v46, v152, v26
	v_mul_f32_e32 v47, v152, v27
	v_mul_f32_e32 v44, v152, v44
	v_mul_f32_e32 v45, v152, v45
	v_mul_f32_e32 v42, v152, v42
	v_mul_f32_e32 v43, v152, v43
	v_mul_f32_e32 v48, v152, v24
	v_mul_f32_e32 v49, v152, v25
	s_andn2_b64 vcc, exec, s[4:5]
	s_mov_b64 s[0:1], -1
	s_cbranch_vccnz .LBB0_414

; template <int RSM> __device__ __forceinline__ float row_scale(const float* p, int row) { const float v = __hip_atomic_load(p + row, __ATOMIC_RELAXED, __HIP_MEMORY_SCOPE_AGENT); return RSM == 0 ? v : 1.0f / sqrtf(v * (1.f / DM) + EPS); }
;     __device__ __forceinline__ void operator()(const f32x4 (&acc)[2][2][4][2], const Unit& u, int wr, int wc, int fr, int fq) const {
;     ...
;             for (int m = 0; m < 4; ++m) { const int row = row0 + ai * HALF + m * 16; const float sc = row_scale<1>(rs, row);
;                 f32x4 c0, c1, s0, s1;
;                 if (rope) { const int pos = row & (SEQ - 1); c0 = *(const f32x4*)(ropeC + pos * 8); c1 = *(const f32x4*)(ropeC + pos * 8 + 4); s0 = *(const f32x4*)(ropeS + pos * 8); s1 = *(const f32x4*)(ropeS + pos * 8 + 4); }
; #pragma unroll
;                 for (int bj = 0; bj < 2; ++bj) { const f32x4 a0 = acc[ai][bj][m][0] * sc, a1 = acc[ai][bj][m][1] * sc;
;                     float v[8] = {a0[0], a0[1], a0[2], a0[3], a1[0], a1[1], a1[2], a1[3]};
.LBB0_1357:
	v_mul_f32_e32 v8, v152, v38
	v_mul_f32_e32 v9, v152, v39
	v_mul_f32_e32 v10, v152, v42
	v_mul_f32_e32 v11, v152, v43
	v_mul_f32_e32 v38, v152, v40
	v_mul_f32_e32 v39, v152, v41
	v_mul_f32_e32 v36, v152, v36
	v_mul_f32_e32 v37, v152, v37
	s_andn2_b64 vcc, exec, s[4:5]
	s_mov_b64 s[0:1], -1
	s_cbranch_vccnz .LBB0_425

; #define WAIT_BAR(N) asm volatile("s_waitcnt vmcnt(" #N ") lgkmcnt(0)\n\ts_barrier":::"memory")
;   #define RESC() do{ if(resc){ asm volatile("s_waitcnt lgkmcnt(0)":::"memory"); \
;       _Pragma("unroll") for(int d_=0;d_<2;++d_) _Pragma("unroll") for(int r=0;r<16;++r)o[d_][r]*=wsf[crow(r,hi)]; } }while(0)
;   #define ROT() do{sl_prev=sl_cur;sl_cur=sl_next;sl_next=(sl_next==(NSLOT-1)*SLOTB)?0:sl_next+SLOTB;}while(0)
; template<int THRL> __device__ __forceinline__ void attn_unit(int b,int h,int hv,int qb,const bf16*Q,const bf16*__restrict__ K,const bf16*__restrict__ V,bf16*O,char*shm){
;     ...
;   int t=1;
;     ...
;   for(;t+5<NT;t+=2){
;     STEP(pB0,pB1,pA0,pA1,t,true,true,true);     WAIT_BAR(2); RESC(); ROT();
.LBB0_1427:
	s_waitcnt lgkmcnt(14)
	v_mfma_f32_32x32x16_bf16 v[48:63], v[172:175], v[208:211], v[48:63]
	v_exp_f32_e32 v128, v128
	v_exp_f32_e32 v129, v129
	v_exp_f32_e32 v130, v130
	v_exp_f32_e32 v131, v131
	s_waitcnt lgkmcnt(12)
	v_mfma_f32_32x32x16_bf16 v[32:47], v[172:175], v[96:99], v[32:47]
	v_exp_f32_e32 v132, v132
	v_exp_f32_e32 v133, v133
	v_exp_f32_e32 v134, v134
	v_exp_f32_e32 v135, v135
	v_add_u32_e32 v0, s50, v240
	ds_read_b128 v[92:95], v0
	ds_read_b128 v[200:203], v0 offset:512
	s_waitcnt lgkmcnt(12)
	v_mfma_f32_32x32x16_bf16 v[48:63], v[164:167], v[2:5], v[48:63]
	v_exp_f32_e32 v136, v136
	v_exp_f32_e32 v137, v137
	v_exp_f32_e32 v138, v138
	v_exp_f32_e32 v139, v139
	ds_read_b128 v[204:207], v0 offset:2048
	ds_read_b128 v[196:199], v0 offset:2560
	s_waitcnt lgkmcnt(12)
	v_mfma_f32_32x32x16_bf16 v[32:47], v[164:167], v[6:9], v[32:47]
	v_exp_f32_e32 v140, v140
	v_exp_f32_e32 v141, v141
	v_exp_f32_e32 v142, v142
	v_exp_f32_e32 v143, v143
	ds_read_b128 v[192:195], v0 offset:4096
	ds_read_b128 v[188:191], v0 offset:4608
	s_waitcnt lgkmcnt(12)
	v_mfma_f32_32x32x16_bf16 v[48:63], v[156:159], v[10:13], v[48:63]
	v_exp_f32_e32 v112, v112
	v_exp_f32_e32 v113, v113
	v_exp_f32_e32 v114, v114
	v_exp_f32_e32 v115, v115
	ds_read_b128 v[184:187], v0 offset:6144
	ds_read_b128 v[180:183], v0 offset:6656
	s_waitcnt lgkmcnt(12)
	v_mfma_f32_32x32x16_bf16 v[32:47], v[156:159], v[80:83], v[32:47]
	v_exp_f32_e32 v116, v116
	v_exp_f32_e32 v117, v117
	v_exp_f32_e32 v118, v118
	v_exp_f32_e32 v119, v119
	s_waitcnt lgkmcnt(10)
	v_mfma_f32_32x32x16_bf16 v[48:63], v[148:151], v[84:87], v[48:63]
	v_exp_f32_e32 v120, v120
	v_exp_f32_e32 v121, v121
	v_exp_f32_e32 v122, v122
	v_exp_f32_e32 v123, v123
	s_waitcnt lgkmcnt(8)
	v_mfma_f32_32x32x16_bf16 v[32:47], v[148:151], v[88:91], v[32:47]
	v_exp_f32_e32 v124, v124
	v_exp_f32_e32 v125, v125
	v_exp_f32_e32 v126, v126
	v_exp_f32_e32 v127, v127
	s_waitcnt vmcnt(2) lgkmcnt(0)
	s_barrier
	s_andn2_b64 vcc, exec, s[0:1]
	v_add_u32_e32 v0, s59, v242
	s_cbranch_vccnz .LBB0_1429
	s_waitcnt lgkmcnt(0)
	ds_read_b128 v[2:5], v0 offset:49248
	ds_read_b128 v[6:9], v0 offset:49216
	ds_read_b128 v[10:13], v0 offset:49184
	ds_read_b128 v[80:83], v0 offset:49152
	s_waitcnt lgkmcnt(3)
	v_mul_f32_e32 v60, v60, v2
	v_mul_f32_e32 v61, v61, v3
	s_waitcnt lgkmcnt(2)
	v_mul_f32_e32 v56, v56, v6
	v_mul_f32_e32 v57, v57, v7
	s_waitcnt lgkmcnt(1)
	v_mul_f32_e32 v52, v52, v10
	v_mul_f32_e32 v53, v53, v11
	v_mul_f32_e32 v62, v62, v4
	v_mul_f32_e32 v63, v63, v5
	v_mul_f32_e32 v58, v58, v8
	v_mul_f32_e32 v59, v59, v9
	v_mul_f32_e32 v54, v54, v12
	v_mul_f32_e32 v55, v55, v13
	s_waitcnt lgkmcnt(0)
	v_mul_f32_e32 v50, v50, v82
	v_mul_f32_e32 v51, v51, v83
	v_mul_f32_e32 v48, v48, v80
	v_mul_f32_e32 v49, v49, v81
	v_mul_f32_e32 v44, v44, v2
	v_mul_f32_e32 v45, v45, v3
	v_mul_f32_e32 v40, v40, v6
	v_mul_f32_e32 v41, v41, v7
	v_mul_f32_e32 v36, v36, v10
	v_mul_f32_e32 v37, v37, v11
	v_mul_f32_e32 v46, v46, v4
	v_mul_f32_e32 v47, v47, v5
	v_mul_f32_e32 v42, v42, v8
	v_mul_f32_e32 v43, v43, v9
	v_mul_f32_e32 v38, v38, v12
	v_mul_f32_e32 v39, v39, v13
	v_mul_f32_e32 v34, v34, v82
	v_mul_f32_e32 v35, v35, v83
	v_mul_f32_e32 v32, v32, v80
	v_mul_f32_e32 v33, v33, v81

; #define WAIT_BAR(N) asm volatile("s_waitcnt vmcnt(" #N ") lgkmcnt(0)\n\ts_barrier":::"memory")
;   #define RESC() do{ if(resc){ asm volatile("s_waitcnt lgkmcnt(0)":::"memory"); \
;       _Pragma("unroll") for(int d_=0;d_<2;++d_) _Pragma("unroll") for(int r=0;r<16;++r)o[d_][r]*=wsf[crow(r,hi)]; } }while(0)
;   #define ROT() do{sl_prev=sl_cur;sl_cur=sl_next;sl_next=(sl_next==(NSLOT-1)*SLOTB)?0:sl_next+SLOTB;}while(0)
; template<int THRL> __device__ __forceinline__ void attn_unit(int b,int h,int hv,int qb,const bf16*Q,const bf16*__restrict__ K,const bf16*__restrict__ V,bf16*O,char*shm){
;     ...
;   int t=1;
;     ...
;   for(;t+5<NT;t+=2){
;     STEP(pB0,pB1,pA0,pA1,t,true,true,true);     WAIT_BAR(2); RESC(); ROT();
;     STEP(pA0,pA1,pB0,pB1,t+1,true,true,true);   WAIT_BAR(2); RESC(); ROT();
.LBB0_1430:
	s_waitcnt lgkmcnt(14)
	v_mfma_f32_32x32x16_bf16 v[48:63], v[172:175], v[176:179], v[48:63]
	v_exp_f32_e32 v96, v96
	v_exp_f32_e32 v97, v97
	v_exp_f32_e32 v98, v98
	v_exp_f32_e32 v99, v99
	s_waitcnt lgkmcnt(12)
	v_mfma_f32_32x32x16_bf16 v[32:47], v[172:175], v[128:131], v[32:47]
	v_exp_f32_e32 v100, v100
	v_exp_f32_e32 v101, v101
	v_exp_f32_e32 v102, v102
	v_exp_f32_e32 v103, v103
	v_add_u32_e32 v14, s73, v240
	ds_read_b128 v[204:207], v14
	ds_read_b128 v[200:203], v14 offset:512
	s_waitcnt lgkmcnt(12)
	v_mfma_f32_32x32x16_bf16 v[48:63], v[164:167], v[2:5], v[48:63]
	v_exp_f32_e32 v104, v104
	v_exp_f32_e32 v105, v105
	v_exp_f32_e32 v106, v106
	v_exp_f32_e32 v107, v107
	ds_read_b128 v[196:199], v14 offset:2048
	ds_read_b128 v[192:195], v14 offset:2560
	s_waitcnt lgkmcnt(12)
	v_mfma_f32_32x32x16_bf16 v[32:47], v[164:167], v[6:9], v[32:47]
	v_exp_f32_e32 v108, v108
	v_exp_f32_e32 v109, v109
	v_exp_f32_e32 v110, v110
	v_exp_f32_e32 v111, v111
	ds_read_b128 v[188:191], v14 offset:4096
	ds_read_b128 v[184:187], v14 offset:4608
	s_waitcnt lgkmcnt(12)
	v_mfma_f32_32x32x16_bf16 v[48:63], v[156:159], v[10:13], v[48:63]
	v_exp_f32_e32 v80, v80
	v_exp_f32_e32 v81, v81
	v_exp_f32_e32 v82, v82
	v_exp_f32_e32 v83, v83
	ds_read_b128 v[180:183], v14 offset:6144
	ds_read_b128 v[176:179], v14 offset:6656
	s_waitcnt lgkmcnt(12)
	v_mfma_f32_32x32x16_bf16 v[32:47], v[156:159], v[112:115], v[32:47]
	v_exp_f32_e32 v84, v84
	v_exp_f32_e32 v85, v85
	v_exp_f32_e32 v86, v86
	v_exp_f32_e32 v87, v87
	s_waitcnt lgkmcnt(10)
	v_mfma_f32_32x32x16_bf16 v[48:63], v[148:151], v[116:119], v[48:63]
	v_exp_f32_e32 v88, v88
	v_exp_f32_e32 v89, v89
	v_exp_f32_e32 v90, v90
	v_exp_f32_e32 v91, v91
	s_waitcnt lgkmcnt(8)
	v_mfma_f32_32x32x16_bf16 v[32:47], v[148:151], v[120:123], v[32:47]
	v_exp_f32_e32 v92, v92
	v_exp_f32_e32 v93, v93
	v_exp_f32_e32 v94, v94
	v_exp_f32_e32 v95, v95
	s_waitcnt vmcnt(2) lgkmcnt(0)
	s_barrier
	s_andn2_b64 vcc, exec, s[0:1]
	s_cbranch_vccnz .LBB0_1432
	s_waitcnt lgkmcnt(0)
	ds_read_b128 v[2:5], v0 offset:49248
	ds_read_b128 v[6:9], v0 offset:49216
	ds_read_b128 v[10:13], v0 offset:49184
	ds_read_b128 v[112:115], v0 offset:49152
	s_waitcnt lgkmcnt(3)
	v_mul_f32_e32 v60, v60, v2
	v_mul_f32_e32 v61, v61, v3
	s_waitcnt lgkmcnt(2)
	v_mul_f32_e32 v56, v56, v6
	v_mul_f32_e32 v57, v57, v7
	s_waitcnt lgkmcnt(1)
	v_mul_f32_e32 v52, v52, v10
	v_mul_f32_e32 v53, v53, v11
	v_mul_f32_e32 v62, v62, v4
	v_mul_f32_e32 v63, v63, v5
	v_mul_f32_e32 v58, v58, v8
	v_mul_f32_e32 v59, v59, v9
	v_mul_f32_e32 v54, v54, v12
	v_mul_f32_e32 v55, v55, v13
	s_waitcnt lgkmcnt(0)
	v_mul_f32_e32 v50, v50, v114
	v_mul_f32_e32 v51, v51, v115
	v_mul_f32_e32 v48, v48, v112
	v_mul_f32_e32 v49, v49, v113
	v_mul_f32_e32 v44, v44, v2
	v_mul_f32_e32 v45, v45, v3
	v_mul_f32_e32 v40, v40, v6
	v_mul_f32_e32 v41, v41, v7
	v_mul_f32_e32 v36, v36, v10
	v_mul_f32_e32 v37, v37, v11
	v_mul_f32_e32 v46, v46, v4
	v_mul_f32_e32 v47, v47, v5
	v_mul_f32_e32 v42, v42, v8
	v_mul_f32_e32 v43, v43, v9
	v_mul_f32_e32 v38, v38, v12
	v_mul_f32_e32 v39, v39, v13
	v_mul_f32_e32 v34, v34, v114
	v_mul_f32_e32 v35, v35, v115
	v_mul_f32_e32 v32, v32, v112
	v_mul_f32_e32 v33, v33, v113

.LBB0_1453:
	s_waitcnt lgkmcnt(0)
	ds_read_b128 v[2:5], v244 offset:49248
	ds_read_b128 v[6:9], v244 offset:49216
	ds_read_b128 v[10:13], v244 offset:49184
	ds_read_b128 v[80:83], v244 offset:49152
	s_waitcnt lgkmcnt(3)
	v_mul_f32_e32 v60, v60, v2
	v_mul_f32_e32 v61, v61, v3
	s_waitcnt lgkmcnt(2)
	v_mul_f32_e32 v56, v56, v6
	v_mul_f32_e32 v57, v57, v7
	s_waitcnt lgkmcnt(1)
	v_mul_f32_e32 v52, v52, v10
	v_mul_f32_e32 v53, v53, v11
	v_mul_f32_e32 v62, v62, v4
	v_mul_f32_e32 v63, v63, v5
	v_mul_f32_e32 v58, v58, v8
	v_mul_f32_e32 v59, v59, v9
	v_mul_f32_e32 v54, v54, v12
	v_mul_f32_e32 v55, v55, v13
	s_waitcnt lgkmcnt(0)
	v_mul_f32_e32 v50, v50, v82
	v_mul_f32_e32 v51, v51, v83
	v_mul_f32_e32 v48, v48, v80
	v_mul_f32_e32 v49, v49, v81
	v_mul_f32_e32 v44, v44, v2
	v_mul_f32_e32 v45, v45, v3
	v_mul_f32_e32 v40, v40, v6
	v_mul_f32_e32 v41, v41, v7
	v_mul_f32_e32 v36, v36, v10
	v_mul_f32_e32 v37, v37, v11
	v_mul_f32_e32 v46, v46, v4
	v_mul_f32_e32 v47, v47, v5
	v_mul_f32_e32 v42, v42, v8
	v_mul_f32_e32 v43, v43, v9
	v_mul_f32_e32 v38, v38, v12
	v_mul_f32_e32 v39, v39, v13
	v_mul_f32_e32 v34, v34, v82
	v_mul_f32_e32 v35, v35, v83
	v_mul_f32_e32 v32, v32, v80
	v_mul_f32_e32 v33, v33, v81

.LBB0_1472:
	s_waitcnt lgkmcnt(0)
	ds_read_b128 v[2:5], v244 offset:49248
	ds_read_b128 v[6:9], v244 offset:49216
	ds_read_b128 v[10:13], v244 offset:49184
	ds_read_b128 v[112:115], v244 offset:49152
	s_waitcnt lgkmcnt(3)
	v_mul_f32_e32 v60, v60, v2
	v_mul_f32_e32 v61, v61, v3
	s_waitcnt lgkmcnt(2)
	v_mul_f32_e32 v56, v56, v6
	v_mul_f32_e32 v57, v57, v7
	s_waitcnt lgkmcnt(1)
	v_mul_f32_e32 v52, v52, v10
	v_mul_f32_e32 v53, v53, v11
	v_mul_f32_e32 v62, v62, v4
	v_mul_f32_e32 v63, v63, v5
	v_mul_f32_e32 v58, v58, v8
	v_mul_f32_e32 v59, v59, v9
	v_mul_f32_e32 v54, v54, v12
	v_mul_f32_e32 v55, v55, v13
	s_waitcnt lgkmcnt(0)
	v_mul_f32_e32 v50, v50, v114
	v_mul_f32_e32 v51, v51, v115
	v_mul_f32_e32 v48, v48, v112
	v_mul_f32_e32 v49, v49, v113
	v_mul_f32_e32 v44, v44, v2
	v_mul_f32_e32 v45, v45, v3
	v_mul_f32_e32 v40, v40, v6
	v_mul_f32_e32 v41, v41, v7
	v_mul_f32_e32 v36, v36, v10
	v_mul_f32_e32 v37, v37, v11
	v_mul_f32_e32 v46, v46, v4
	v_mul_f32_e32 v47, v47, v5
	v_mul_f32_e32 v42, v42, v8
	v_mul_f32_e32 v43, v43, v9
	v_mul_f32_e32 v38, v38, v12
	v_mul_f32_e32 v39, v39, v13
	v_mul_f32_e32 v34, v34, v114
	v_mul_f32_e32 v35, v35, v115
	v_mul_f32_e32 v32, v32, v112
	v_mul_f32_e32 v33, v33, v113

; #define WAIT_BAR(N) asm volatile("s_waitcnt vmcnt(" #N ") lgkmcnt(0)\n\ts_barrier":::"memory")
;   #define RESC() do{ if(resc){ asm volatile("s_waitcnt lgkmcnt(0)":::"memory"); \
;       _Pragma("unroll") for(int d_=0;d_<2;++d_) _Pragma("unroll") for(int r=0;r<16;++r)o[d_][r]*=wsf[crow(r,hi)]; } }while(0)
;   #define ROT() do{sl_prev=sl_cur;sl_cur=sl_next;sl_next=(sl_next==(NSLOT-1)*SLOTB)?0:sl_next+SLOTB;}while(0)
;   #define ENDW(tt) do{ if((tt)+3<NT){WAIT_BAR(2);} else if((tt)+2<NT){WAIT_BAR(1);} else {WAIT_BAR(0);} }while(0)
; template<int THRL> __device__ __forceinline__ void attn_unit(int b,int h,int hv,int qb,const bf16*Q,const bf16*__restrict__ K,const bf16*__restrict__ V,bf16*O,char*shm){
;     ...
;   int t=1;
;     ...
;   for(;t+5<NT;t+=2){
;     STEP(pB0,pB1,pA0,pA1,t,true,true,true);     WAIT_BAR(2); RESC(); ROT();
;     STEP(pA0,pA1,pB0,pB1,t+1,true,true,true);   WAIT_BAR(2); RESC(); ROT();
;   }
;     ...
;   for(;t+1<NT;t+=2){
;     STEP(pB0,pB1,pA0,pA1,t,(t+3<NT),(t+1<NT),(t+1<NT));       ENDW(t);   RESC(); ROT();
;     STEP(pA0,pA1,pB0,pB1,t+1,(t+4<NT),(t+2<NT),(t+2<NT));     ENDW(t+1); RESC(); ROT();
;   }
;   STEP(pB0,pB1,pA0,pA1,NT-1,false,false,false); RESC();
.LBB0_1495:
	s_waitcnt lgkmcnt(14)
	v_mfma_f32_32x32x16_bf16 v[48:63], v[172:175], v[6:9], v[48:63]
	v_exp_f32_e32 v80, v80
	v_exp_f32_e32 v81, v81
	v_exp_f32_e32 v82, v82
	v_exp_f32_e32 v83, v83
	s_waitcnt lgkmcnt(12)
	v_mfma_f32_32x32x16_bf16 v[32:47], v[172:175], v[2:5], v[32:47]
	v_exp_f32_e32 v84, v84
	v_exp_f32_e32 v85, v85
	v_exp_f32_e32 v86, v86
	v_exp_f32_e32 v87, v87
	s_waitcnt lgkmcnt(10)
	v_mfma_f32_32x32x16_bf16 v[48:63], v[164:167], v[10:13], v[48:63]
	v_exp_f32_e32 v88, v88
	v_exp_f32_e32 v89, v89
	v_exp_f32_e32 v90, v90
	v_exp_f32_e32 v91, v91
	s_waitcnt lgkmcnt(8)
	v_mfma_f32_32x32x16_bf16 v[32:47], v[164:167], v[128:131], v[32:47]
	v_exp_f32_e32 v92, v92
	v_exp_f32_e32 v93, v93
	v_exp_f32_e32 v94, v94
	v_exp_f32_e32 v95, v95
	s_waitcnt lgkmcnt(6)
	v_mfma_f32_32x32x16_bf16 v[48:63], v[156:159], v[132:135], v[48:63]
	v_exp_f32_e32 v64, v64
	v_exp_f32_e32 v65, v65
	v_exp_f32_e32 v66, v66
	v_exp_f32_e32 v67, v67
	s_waitcnt lgkmcnt(4)
	v_mfma_f32_32x32x16_bf16 v[32:47], v[156:159], v[136:139], v[32:47]
	v_exp_f32_e32 v68, v68
	v_exp_f32_e32 v69, v69
	v_exp_f32_e32 v70, v70
	v_exp_f32_e32 v71, v71
	s_waitcnt lgkmcnt(2)
	v_mfma_f32_32x32x16_bf16 v[48:63], v[148:151], v[140:143], v[48:63]
	v_exp_f32_e32 v72, v72
	v_exp_f32_e32 v73, v73
	v_exp_f32_e32 v74, v74
	v_exp_f32_e32 v75, v75
	s_waitcnt lgkmcnt(0)
	v_mfma_f32_32x32x16_bf16 v[32:47], v[148:151], v[152:155], v[32:47]
	v_exp_f32_e32 v76, v76
	v_exp_f32_e32 v77, v77
	v_exp_f32_e32 v78, v78
	v_exp_f32_e32 v79, v79
	s_andn2_b64 vcc, exec, s[0:1]
	v_lshl_add_u32 v2, v235, 2, s59
	s_cbranch_vccnz .LBB0_1497
	s_waitcnt lgkmcnt(0)
	ds_read_b128 v[4:7], v2 offset:49248
	ds_read_b128 v[8:11], v2 offset:49216
	ds_read_b128 v[12:15], v2 offset:49184
	ds_read_b128 v[96:99], v2 offset:49152
	s_waitcnt lgkmcnt(3)
	v_mul_f32_e32 v62, v62, v6
	v_mul_f32_e32 v63, v63, v7
	s_waitcnt lgkmcnt(2)
	v_mul_f32_e32 v58, v58, v10
	v_mul_f32_e32 v59, v59, v11
	s_waitcnt lgkmcnt(1)
	v_mul_f32_e32 v54, v54, v14
	v_mul_f32_e32 v55, v55, v15
	s_waitcnt lgkmcnt(0)
	v_mul_f32_e32 v50, v50, v98
	v_mul_f32_e32 v51, v51, v99
	v_mul_f32_e32 v60, v60, v4
	v_mul_f32_e32 v61, v61, v5
	v_mul_f32_e32 v56, v56, v8
	v_mul_f32_e32 v57, v57, v9
	v_mul_f32_e32 v52, v52, v12
	v_mul_f32_e32 v53, v53, v13
	v_mul_f32_e32 v48, v48, v96
	v_mul_f32_e32 v49, v49, v97
	v_mul_f32_e32 v46, v46, v6
	v_mul_f32_e32 v47, v47, v7
	v_mul_f32_e32 v42, v42, v10
	v_mul_f32_e32 v43, v43, v11
	v_mul_f32_e32 v38, v38, v14
	v_mul_f32_e32 v39, v39, v15
	v_mul_f32_e32 v34, v34, v98
	v_mul_f32_e32 v35, v35, v99
	v_mul_f32_e32 v44, v44, v4
	v_mul_f32_e32 v45, v45, v5
	v_mul_f32_e32 v40, v40, v8
	v_mul_f32_e32 v41, v41, v9
	v_mul_f32_e32 v36, v36, v12
	v_mul_f32_e32 v37, v37, v13
	v_mul_f32_e32 v32, v32, v96
	v_mul_f32_e32 v33, v33, v97

; #define LAS __attribute__((address_space(3)))
; __device__ __forceinline__ unsigned pkbf(float lo, float hi) { const f32x2_m v = {lo, hi}; const bf16x2_m b = __builtin_convertvector(v, bf16x2_m); return __builtin_bit_cast(unsigned, b); }
; #define HG_MFMA(x, y, c) __builtin_amdgcn_mfma_f32_16x16x32_bf16((x), (y), (c), 0, 0, 0)
; #define HG_BAR() asm volatile("s_waitcnt lgkmcnt(0)\n\ts_barrier" ::: "memory")
; __device__ __forceinline__ void hgrn_unit(LAS unsigned char* lds, int b, int h, int vs, const bf16* QR, const _Float16* LF, const bf16* IO, bf16* OR_) {
;     ...
;             for (int ki = 0; ki < 2; ++ki)
; #pragma unroll
;                 for (int vj = 0; vj < 2; ++vj) { sacc[ki][vj] = sacc[ki][vj] * glv[ki]; sacc[ki][vj] = HG_MFMA(klf[ki][0], vtf[vj][0], sacc[ki][vj]); sacc[ki][vj] = HG_MFMA(klf[ki][1], vtf[vj][1], sacc[ki][vj]); }
; #pragma unroll
;             for (int sj = 0; sj < 4; ++sj) *(LAS v2u*)(lds + OFF_AM + ((16 * mw + fr) * TS + 16 * sj + 4 * fq) * 2) = (v2u){pkbf(a[sj][0], a[sj][1]), pkbf(a[sj][2], a[sj][3])};
;             HG_BAR();
;             bf16x8 amf[2];
; #pragma unroll
;             for (int ss = 0; ss < 2; ++ss) amf[ss] = HG_LD8(OFF_AM + ((16 * mw + fr) * TS + 32 * ss + 8 * fq) * 2);
; #pragma unroll
;             for (int ki = 0; ki < 2; ++ki)
; #pragma unroll
;                 for (int vj = 0; vj < 2; ++vj) *(LAS v2u*)(lds + OFF_ST + ((16 * vj + fr) * QS + 16 * (2 * mw + ki) + 4 * fq) * 2) = (v2u){pkbf(sacc[ki][vj][0], sacc[ki][vj][1]), pkbf(sacc[ki][vj][2], sacc[ki][vj][3])};
; #pragma unroll
;             for (int vj = 0; vj < 2; ++vj) {
; #pragma unroll
;                 for (int ss = 0; ss < 2; ++ss) if (32 * ss <= 16 * mw + 15) o[vj] = HG_MFMA(vtf[vj][ss], amf[ss], o[vj]);
;                 *(v2u*)(op + (size_t)c * 64 * 1024 + 16 * vj) = (v2u){pkbf(o[vj][0], o[vj][1]), pkbf(o[vj][2], o[vj][3])}; }
;             HG_BAR();
.LBB0_1532:
	s_waitcnt lgkmcnt(14)
	v_mfma_f32_16x16x32_bf16 v[132:135], v[132:135], v[52:55], 0
	v_mov_b32_e32 v136, s43
	v_cndmask_b32_e64 v136, v148, v136, s[10:11]
	s_waitcnt lgkmcnt(5)
	v_mul_f32_e32 v34, v34, v94
	v_mul_f32_e32 v35, v35, v95
	v_mfma_f32_16x16x32_bf16 v[52:55], v[116:119], v[52:55], 0
	v_mul_f32_e64 v32, v32, v92
	v_mul_f32_e64 v33, v33, v93
	v_cndmask_b32_e64 v137, 0, v149, s[12:13]
	v_cndmask_b32_e64 v136, v136, v148, s[12:13]
	v_mfma_f32_16x16x32_bf16 v[112:115], v[112:115], v[56:59], v[132:135]
	v_cndmask_b32_e64 v138, v150, 0, s[14:15]
	v_cndmask_b32_e64 v139, v151, 0, s[16:17]
	v_mul_f32_e32 v12, v12, v94
	v_mul_f32_e32 v13, v13, v95
	v_mfma_f32_16x16x32_bf16 v[52:55], v[120:123], v[56:59], v[52:55]
	v_mul_f32_e64 v10, v10, v92
	v_mul_f32_e64 v11, v11, v93
	v_cndmask_b32_e64 v137, v149, v137, s[8:9]
	v_cndmask_b32_e64 v139, v151, v139, s[8:9]
	s_waitcnt lgkmcnt(4)
	v_mfma_f32_16x16x32_bf16 v[32:35], v[96:99], v[48:51], v[32:35]
	v_cndmask_b32_e64 v138, v150, v138, s[8:9]
	v_cndmask_b32_e64 v136, v148, v136, s[8:9]
	s_waitcnt lgkmcnt(2)
	v_mul_f32_e32 v8, v8, v78
	v_mul_f32_e32 v9, v9, v79
	v_mfma_f32_16x16x32_bf16 v[10:13], v[96:99], v[40:43], v[10:13]
	v_mul_f32_e64 v6, v6, v76
	v_mul_f32_e64 v7, v7, v77
	v_mul_f32_e32 v4, v4, v78
	v_mul_f32_e32 v5, v5, v79
	v_mul_f32_e32 v2, v2, v76
	v_mul_f32_e32 v3, v3, v77
	v_mfma_f32_16x16x32_bf16 v[104:107], v[104:107], v[60:63], v[112:115]
	v_cvt_pk_bf16_f32 v56, v136, v137
	v_cvt_pk_bf16_f32 v57, v138, v139
	v_cvt_pk_bf16_f32 v58, v72, v73
	v_mfma_f32_16x16x32_bf16 v[52:55], v[124:127], v[60:63], v[52:55]
	v_cvt_pk_bf16_f32 v59, v74, v75
	v_add_u32_e32 v60, 0xe000, v204
	ds_write2_b64 v60, v[56:57], v[58:59] offset0:64 offset1:68
	s_waitcnt lgkmcnt(2)
	v_mfma_f32_16x16x32_bf16 v[6:9], v[80:83], v[48:51], v[6:9]
	v_cvt_pk_bf16_f32 v56, v88, v89
	v_cvt_pk_bf16_f32 v57, v90, v91
	v_cvt_pk_bf16_f32 v58, v68, v69
	v_mfma_f32_16x16x32_bf16 v[2:5], v[80:83], v[40:43], v[2:5]
	v_cvt_pk_bf16_f32 v59, v70, v71
	ds_write2_b64 v60, v[56:57], v[58:59] offset0:72 offset1:76
	s_waitcnt lgkmcnt(0)
	s_barrier
	v_mfma_f32_16x16x32_bf16 v[32:35], v[100:103], v[44:47], v[32:35]
	ds_read_b128 v[60:63], v205 offset:57856
	ds_read_b128 v[56:59], v205 offset:57920
	s_add_i32 s18, 0, 0x10600
	s_andn2_b64 vcc, exec, s[24:25]
	v_mfma_f32_16x16x32_bf16 v[10:13], v[100:103], v[36:39], v[10:13]
	v_mfma_f32_16x16x32_bf16 v[104:107], v[108:111], v[64:67], v[104:107]
	s_waitcnt lgkmcnt(4)
	v_mfma_f32_16x16x32_bf16 v[6:9], v[84:87], v[44:47], v[6:9]
	v_mfma_f32_16x16x32_bf16 v[2:5], v[84:87], v[36:39], v[2:5]
	v_mfma_f32_16x16x32_bf16 v[52:55], v[128:131], v[64:67], v[52:55]
	v_cvt_pk_bf16_f32 v64, v32, v33
	v_cvt_pk_bf16_f32 v65, v34, v35
	v_add_u32_e32 v66, s18, v195
	ds_write_b64 v66, v[64:65]
	v_cvt_pk_bf16_f32 v64, v10, v11
	v_cvt_pk_bf16_f32 v65, v12, v13
	v_add_u32_e32 v66, s18, v196
	ds_write_b64 v66, v[64:65]
	v_cvt_pk_bf16_f32 v64, v6, v7
	v_cvt_pk_bf16_f32 v65, v8, v9
	v_add_u32_e32 v66, s18, v197
	s_waitcnt lgkmcnt(3)
	v_mfma_f32_16x16x32_bf16 v[48:51], v[48:51], v[60:63], v[104:107]
	ds_write_b64 v66, v[64:65]
	v_cvt_pk_bf16_f32 v64, v2, v3
	v_cvt_pk_bf16_f32 v65, v4, v5
	v_add_u32_e32 v66, s18, v198
	ds_write_b64 v66, v[64:65]
	v_cndmask_b32_e64 v64, 0, 1, s[24:25]
	v_cmp_ne_u32_e64 s[18:19], 1, v64
	s_cbranch_vccnz .LBB0_1534
	s_waitcnt lgkmcnt(4)
	v_mfma_f32_16x16x32_bf16 v[48:51], v[44:47], v[56:59], v[48:51]

; #define LAS __attribute__((address_space(3)))
; #define HG_BAR() asm volatile("s_waitcnt lgkmcnt(0)\n\ts_barrier" ::: "memory")
; __device__ __forceinline__ void hgrn_unit(LAS unsigned char* lds, int b, int h, int vs, const bf16* QR, const _Float16* LF, const bf16* IO, bf16* OR_) {
;     ...
;             float qa[2][16], kb[2][16], tot[2];
; #pragma unroll
;             for (int e = 0; e < 2; ++e) { float run = 1.f;
; #pragma unroll
;                 for (int i = 0; i < 16; ++i) { const unsigned short hb = (unsigned short)(e ? (clf[i] >> 16) : (clf[i] & 0xffffu)); const float kk = (float)__builtin_bit_cast(_Float16, hb);
;                     run *= (1.f - kk); const float q = e ? bfhi(cq[i]) : bflo(cq[i]);
;                     qa[e][i] = q * run; kb[e][i] = kk * __builtin_amdgcn_rcpf(run); }
;                 tot[e] = run; }
;             ((LAS f32x2_m*)(lds + OFF_TOT))[ew * 64 + lane] = (f32x2_m){tot[0], tot[1]};
;             HG_BAR();
.LBB0_1552:
	s_waitcnt vmcnt(62)
	v_cvt_f32_f16_sdwa v159, v43 dst_sel:DWORD dst_unused:UNUSED_PAD src0_sel:WORD_1
	v_cvt_f32_f16_e32 v158, v41
	v_cvt_f32_f16_sdwa v163, v41 dst_sel:DWORD dst_unused:UNUSED_PAD src0_sel:WORD_1
	v_cvt_f32_f16_e32 v162, v43
	s_waitcnt vmcnt(61)
	v_cvt_f32_f16_sdwa v167, v47 dst_sel:DWORD dst_unused:UNUSED_PAD src0_sel:WORD_1
	v_cvt_f32_f16_e32 v166, v47
	s_waitcnt vmcnt(59)
	v_cvt_f32_f16_sdwa v177, v51 dst_sel:DWORD dst_unused:UNUSED_PAD src0_sel:WORD_1
	v_cvt_f32_f16_e32 v176, v51
	s_waitcnt vmcnt(57)
	v_cvt_f32_f16_sdwa v181, v49 dst_sel:DWORD dst_unused:UNUSED_PAD src0_sel:WORD_1
	v_cvt_f32_f16_e32 v180, v49
	v_add_f32_e64 v160, -v158, 1.0
	v_add_f32_e64 v161, -v159, 1.0
	v_add_f32_e64 v168, -v162, 1.0
	v_add_f32_e64 v169, -v163, 1.0
	s_waitcnt vmcnt(55)
	v_cvt_f32_f16_sdwa v191, v45 dst_sel:DWORD dst_unused:UNUSED_PAD src0_sel:WORD_1
	v_cvt_f32_f16_e32 v190, v45
	v_mul_f32_e32 v170, v168, v160
	v_mul_f32_e32 v171, v169, v161
	v_add_f32_e64 v76, -v166, 1.0
	v_add_f32_e64 v77, -v167, 1.0
	s_waitcnt vmcnt(53)
	v_cvt_f32_f16_sdwa v109, v55 dst_sel:DWORD dst_unused:UNUSED_PAD src0_sel:WORD_1
	v_cvt_f32_f16_e32 v108, v55
	v_mul_f32_e32 v174, v170, v76
	v_mul_f32_e32 v175, v171, v77
	v_add_f32_e64 v76, -v176, 1.0
	v_add_f32_e64 v77, -v177, 1.0
	s_waitcnt vmcnt(51)
	v_cvt_f32_f16_sdwa v197, v58 dst_sel:DWORD dst_unused:UNUSED_PAD src0_sel:WORD_1
	v_cvt_f32_f16_e32 v196, v58
	v_mul_f32_e32 v182, v174, v76
	v_mul_f32_e32 v183, v175, v77
	v_add_f32_e64 v76, -v180, 1.0
	v_add_f32_e64 v77, -v181, 1.0
	s_waitcnt vmcnt(49)
	v_cvt_f32_f16_sdwa v105, v63 dst_sel:DWORD dst_unused:UNUSED_PAD src0_sel:WORD_1
	v_cvt_f32_f16_e32 v104, v63
	v_mul_f32_e32 v186, v182, v76
	v_mul_f32_e32 v187, v183, v77
	v_add_f32_e64 v76, -v190, 1.0
	v_add_f32_e64 v77, -v191, 1.0
	s_waitcnt vmcnt(47)
	v_cvt_f32_f16_sdwa v103, v59 dst_sel:DWORD dst_unused:UNUSED_PAD src0_sel:WORD_1
	v_cvt_f32_f16_e32 v102, v59
	v_lshlrev_b32_e32 v78, 16, v54
	v_and_b32_e32 v79, 0xffff0000, v54
	v_mul_f32_e32 v192, v186, v76
	v_mul_f32_e32 v193, v187, v77
	v_add_f32_e64 v54, -v108, 1.0
	v_add_f32_e64 v55, -v109, 1.0
	s_waitcnt vmcnt(45)
	v_cvt_f32_f16_sdwa v87, v64 dst_sel:DWORD dst_unused:UNUSED_PAD src0_sel:WORD_1
	v_cvt_f32_f16_e32 v86, v64
	v_mul_f32_e32 v198, v192, v54
	v_mul_f32_e32 v199, v193, v55
	v_add_f32_e64 v54, -v196, 1.0
	v_add_f32_e64 v55, -v197, 1.0
	s_waitcnt vmcnt(43)
	v_cvt_f32_f16_sdwa v83, v70 dst_sel:DWORD dst_unused:UNUSED_PAD src0_sel:WORD_1
	v_cvt_f32_f16_e32 v82, v70
	v_lshlrev_b32_e32 v94, 16, v39
	s_waitcnt vmcnt(42)
	v_lshlrev_b32_e32 v40, 16, v72
	s_waitcnt vmcnt(40)
	v_lshlrev_b32_e32 v38, 16, v73
	v_and_b32_e32 v100, 0xffff0000, v39
	v_and_b32_e32 v41, 0xffff0000, v72
	v_and_b32_e32 v39, 0xffff0000, v73
	v_mul_f32_e32 v202, v198, v54
	v_mul_f32_e32 v203, v199, v55
	v_add_f32_e64 v54, -v104, 1.0
	v_add_f32_e64 v55, -v105, 1.0
	v_cvt_f32_f16_sdwa v73, v69 dst_sel:DWORD dst_unused:UNUSED_PAD src0_sel:WORD_1
	v_cvt_f32_f16_e32 v72, v69
	v_lshlrev_b32_e32 v42, 16, v71
	v_and_b32_e32 v43, 0xffff0000, v71
	v_mul_f32_e32 v206, v202, v54
	v_mul_f32_e32 v207, v203, v55
	v_add_f32_e64 v54, -v102, 1.0
	v_add_f32_e64 v55, -v103, 1.0
	s_waitcnt vmcnt(39)
	v_cvt_f32_f16_sdwa v71, v67 dst_sel:DWORD dst_unused:UNUSED_PAD src0_sel:WORD_1
	v_cvt_f32_f16_e32 v70, v67
	v_mul_f32_e32 v106, v206, v54
	v_mul_f32_e32 v107, v207, v55
	v_add_f32_e64 v54, -v86, 1.0
	v_add_f32_e64 v55, -v87, 1.0
	v_lshlrev_b32_e32 v50, 16, v56
	v_mul_f32_e32 v92, v106, v54
	v_mul_f32_e32 v93, v107, v55
	v_add_f32_e64 v54, -v82, 1.0
	v_add_f32_e64 v55, -v83, 1.0
	v_lshlrev_b32_e32 v48, 16, v57
	v_mul_f32_e32 v88, v92, v54
	v_mul_f32_e32 v89, v93, v55
	v_add_f32_e64 v54, -v72, 1.0
	v_add_f32_e64 v55, -v73, 1.0
	v_and_b32_e32 v51, 0xffff0000, v56
	v_and_b32_e32 v49, 0xffff0000, v57
	v_mul_f32_e32 v76, v88, v54
	v_mul_f32_e32 v77, v89, v55
	v_add_f32_e64 v54, -v70, 1.0
	v_add_f32_e64 v55, -v71, 1.0
	s_waitcnt vmcnt(37)
	v_cvt_f32_f16_sdwa v57, v68 dst_sel:DWORD dst_unused:UNUSED_PAD src0_sel:WORD_1
	v_cvt_f32_f16_e32 v56, v68
	v_lshlrev_b32_e32 v156, 16, v37
	v_lshlrev_b32_e32 v60, 16, v35
	v_lshlrev_b32_e32 v36, 16, v74
	s_waitcnt vmcnt(36)
	v_lshlrev_b32_e32 v34, 16, v75
	v_and_b32_e32 v157, 0xffff0000, v37
	v_and_b32_e32 v61, 0xffff0000, v35
	v_and_b32_e32 v37, 0xffff0000, v74
	v_and_b32_e32 v35, 0xffff0000, v75
	v_mul_f32_e32 v74, v76, v54
	v_mul_f32_e32 v75, v77, v55
	s_waitcnt vmcnt(35)
	v_cvt_f32_f16_sdwa v55, v81 dst_sel:DWORD dst_unused:UNUSED_PAD src0_sel:WORD_1
	v_cvt_f32_f16_e32 v54, v81
	v_add_f32_e64 v58, -v56, 1.0
	v_add_f32_e64 v59, -v57, 1.0
	v_lshlrev_b32_e32 v44, 16, v66
	v_and_b32_e32 v45, 0xffff0000, v66
	v_mul_f32_e32 v66, v74, v58
	v_mul_f32_e32 v67, v75, v59
	v_add_f32_e64 v58, -v54, 1.0
	v_add_f32_e64 v59, -v55, 1.0
	v_lshlrev_b32_e32 v90, 16, v53
	v_mul_f32_e32 v58, v66, v58
	v_mul_f32_e32 v59, v67, v59
	ds_write_b64 v0, v[58:59]
	s_waitcnt lgkmcnt(0)
	s_barrier
; #define LAS __attribute__((address_space(3)))
; __device__ __forceinline__ unsigned pkbf(float lo, float hi) { const f32x2_m v = {lo, hi}; const bf16x2_m b = __builtin_convertvector(v, bf16x2_m); return __builtin_bit_cast(unsigned, b); }
; __device__ __forceinline__ void hgrn_unit(LAS unsigned char* lds, int b, int h, int vs, const bf16* QR, const _Float16* LF, const bf16* IO, bf16* OR_) {
;     ...
;             float eoff[2], ieoff[2], eGl[2];
;             { const f32x2_m t0v = ((LAS f32x2_m*)(lds + OFF_TOT))[lane], t1v = ((LAS f32x2_m*)(lds + OFF_TOT))[64 + lane], t2v = ((LAS f32x2_m*)(lds + OFF_TOT))[128 + lane], t3v = ((LAS f32x2_m*)(lds + OFF_TOT))[192 + lane];
; #pragma unroll
;               for (int e = 0; e < 2; ++e) { const float off = (ew > 0 ? t0v[e] : 1.f) * (ew > 1 ? t1v[e] : 1.f) * (ew > 2 ? t2v[e] : 1.f);
;                   eoff[e] = off; ieoff[e] = __builtin_amdgcn_rcpf(off); eGl[e] = (t0v[e] * t1v[e]) * (t2v[e] * t3v[e]); } }
;             unsigned klp[2][8];
; #pragma unroll
;             for (int i = 0; i < 16; i += 2) { float kl[2][2];
; #pragma unroll
;                 for (int d = 0; d < 2; ++d) { const float kn0 = kb[0][i + d] * ieoff[0], kn1 = kb[1][i + d] * ieoff[1];
;                     ((LAS unsigned*)(lds + OFF_QG))[(t0 + i + d) * (QS / 2) + lane] = pkbf(qa[0][i + d] * eoff[0], qa[1][i + d] * eoff[1]);
;                     ((LAS unsigned*)(lds + OFF_KN))[(t0 + i + d) * (QS / 2) + lane] = pkbf(kn0, kn1);
;                     kl[0][d] = kn0 * eGl[0]; kl[1][d] = kn1 * eGl[1]; }
;                 klp[0][i >> 1] = pkbf(kl[0][0], kl[0][1]); klp[1][i >> 1] = pkbf(kl[1][0], kl[1][1]); }
; #pragma unroll
;             for (int e = 0; e < 2; ++e) { const int k = 2 * lane + e;
;                 *(LAS v4u*)(lds + OFF_KLT + (k * TS + t0) * 2) = (v4u){klp[e][0], klp[e][1], klp[e][2], klp[e][3]};
;                 *(LAS v4u*)(lds + OFF_KLT + (k * TS + t0 + 8) * 2) = (v4u){klp[e][4], klp[e][5], klp[e][6], klp[e][7]}; }
;             if (ew == 0) ((LAS f32x2_m*)(lds + OFF_GL))[lane] = (f32x2_m){eGl[0], eGl[1]};
	ds_read2st64_b64 v[148:151], v110 offset1:1
	ds_read2st64_b64 v[152:155], v110 offset0:2 offset1:3
	v_lshlrev_b32_e32 v52, 16, v33
	s_waitcnt vmcnt(34)
	v_lshlrev_b32_e32 v32, 16, v62
	v_and_b32_e32 v91, 0xffff0000, v53
	v_and_b32_e32 v53, 0xffff0000, v33
	v_and_b32_e32 v33, 0xffff0000, v62
	s_waitcnt lgkmcnt(1)
	v_cndmask_b32_e64 v62, 1.0, v148, s[8:9]
	v_cndmask_b32_e64 v63, 1.0, v150, s[10:11]
	v_mul_f32_e32 v95, v62, v63
	v_cndmask_b32_e64 v62, 1.0, v149, s[8:9]
	v_cndmask_b32_e64 v63, 1.0, v151, s[10:11]
	s_waitcnt lgkmcnt(0)
	v_cndmask_b32_e64 v161, 1.0, v152, s[12:13]
	v_mul_f32_e32 v101, v62, v63
	v_cndmask_b32_e64 v63, 1.0, v153, s[12:13]
	v_mov_b32_e32 v62, v169
	v_rcp_f32_e32 v164, v160
	v_rcp_f32_e32 v172, v170
	v_rcp_f32_e32 v165, v169
	v_rcp_f32_e32 v173, v171
	v_mul_f32_e32 v160, v160, v94
	v_mul_f32_e32 v161, v161, v95
	v_mul_f32_e32 v100, v62, v100
	v_mul_f32_e32 v101, v63, v101
	v_rcp_f32_e32 v94, v161
	v_rcp_f32_e32 v95, v101
	v_mul_f32_e32 v62, v148, v150
	v_mul_f32_e32 v63, v149, v151
	v_mul_f32_e32 v148, v152, v154
	v_mul_f32_e32 v149, v153, v155
	v_mov_b32_e32 v150, v160
	v_mov_b32_e32 v151, v100
	v_mov_b32_e32 v100, v161
	v_mul_f32_e32 v62, v62, v148
	v_mul_f32_e32 v63, v63, v149
	v_mov_b32_e32 v148, v158
	v_mov_b32_e32 v149, v163
	v_mul_f32_e32 v150, v150, v100
	v_mul_f32_e32 v151, v151, v101
	v_mov_b32_e32 v163, v159
	v_mul_f32_e32 v152, v170, v156
	v_mul_f32_e32 v153, v171, v157
	v_rcp_f32_e32 v178, v174
	v_rcp_f32_e32 v184, v182
	v_rcp_f32_e32 v179, v175
	v_rcp_f32_e32 v185, v183
	v_mul_f32_e32 v148, v164, v148
	v_mul_f32_e32 v149, v165, v149
	v_cvt_pk_bf16_f32 v147, v150, v151
	v_mul_f32_e32 v150, v172, v162
	v_mul_f32_e32 v151, v173, v163
	v_mul_f32_e32 v152, v152, v100
	v_mul_f32_e32 v153, v153, v101
	v_mul_f32_e32 v148, v148, v94
	v_mul_f32_e32 v149, v149, v95
	v_mul_f32_e32 v150, v150, v94
	v_mul_f32_e32 v151, v151, v95
	v_cvt_pk_bf16_f32 v152, v152, v153
	ds_write2_b32 v112, v147, v152 offset1:68
	v_cvt_pk_bf16_f32 v147, v150, v151
	v_mov_b32_e32 v152, v148
	v_mov_b32_e32 v153, v150
	v_mov_b32_e32 v150, v149
	v_mul_f32_e32 v90, v174, v90
	v_mul_f32_e32 v91, v175, v91
	v_cvt_pk_bf16_f32 v154, v148, v149
	v_add_u32_e32 v155, 0x4400, v112
	v_mul_f32_e32 v152, v62, v152
	v_mul_f32_e32 v153, v62, v153
	v_mul_f32_e32 v150, v63, v150
	v_mul_f32_e32 v151, v63, v151
	v_mul_f32_e32 v90, v90, v100
	v_mul_f32_e32 v91, v91, v101
	v_mul_f32_e32 v78, v182, v78
	v_mul_f32_e32 v79, v183, v79
	ds_write2_b32 v155, v154, v147 offset1:68
	v_cvt_pk_bf16_f32 v148, v152, v153
	v_cvt_pk_bf16_f32 v152, v150, v151
	v_mul_f32_e32 v150, v178, v166
	v_mul_f32_e32 v151, v179, v167
	v_cvt_pk_bf16_f32 v147, v90, v91
	v_mul_f32_e32 v90, v184, v176
	v_mul_f32_e32 v91, v185, v177
	v_mul_f32_e32 v78, v78, v100
	v_mul_f32_e32 v79, v79, v101
	v_rcp_f32_e32 v188, v186
	v_rcp_f32_e32 v189, v187
	v_rcp_f32_e32 v194, v192
	v_rcp_f32_e32 v195, v193
	v_mul_f32_e32 v150, v150, v94
	v_mul_f32_e32 v151, v151, v95
	v_mul_f32_e32 v90, v90, v94
	v_mul_f32_e32 v91, v91, v95
	v_cvt_pk_bf16_f32 v78, v78, v79
	v_cvt_pk_bf16_f32 v149, v150, v151
	ds_write2_b32 v112, v147, v78 offset0:136 offset1:204
	v_cvt_pk_bf16_f32 v78, v90, v91
	ds_write2_b32 v155, v149, v78 offset0:136 offset1:204
	v_mov_b32_e32 v78, v150
	v_mov_b32_e32 v79, v90
	v_mov_b32_e32 v90, v151
	v_mul_f32_e32 v60, v186, v60
	v_mul_f32_e32 v61, v187, v61
	v_mul_f32_e32 v78, v62, v78
	v_mul_f32_e32 v79, v62, v79
	v_mul_f32_e32 v90, v63, v90
	v_mul_f32_e32 v91, v63, v91
	v_mul_f32_e32 v60, v60, v100
	v_mul_f32_e32 v61, v61, v101
	v_mul_f32_e32 v52, v192, v52
	v_mul_f32_e32 v53, v193, v53
	v_cvt_pk_bf16_f32 v149, v78, v79
	v_cvt_pk_bf16_f32 v153, v90, v91
	v_mul_f32_e32 v78, v188, v180
	v_mul_f32_e32 v79, v189, v181
	v_cvt_pk_bf16_f32 v90, v60, v61
	v_mul_f32_e32 v60, v194, v190
	v_mul_f32_e32 v61, v195, v191
	v_mul_f32_e32 v52, v52, v100
	v_mul_f32_e32 v53, v53, v101
	v_rcp_f32_e32 v200, v198
	v_rcp_f32_e32 v204, v202
	v_rcp_f32_e32 v201, v199
	v_rcp_f32_e32 v205, v203
	v_mul_f32_e32 v78, v78, v94
	v_mul_f32_e32 v79, v79, v95
	v_mul_f32_e32 v60, v60, v94
	v_mul_f32_e32 v61, v61, v95
	v_cvt_pk_bf16_f32 v52, v52, v53
	v_add_u32_e32 v147, 0x400, v112
	v_cvt_pk_bf16_f32 v91, v78, v79
	ds_write2_b32 v147, v90, v52 offset0:16 offset1:84
	v_cvt_pk_bf16_f32 v52, v60, v61
	v_add_u32_e32 v90, 0x4800, v112
	ds_write2_b32 v90, v91, v52 offset0:16 offset1:84
	v_mov_b32_e32 v52, v78
	v_mov_b32_e32 v53, v60
	v_mov_b32_e32 v60, v79
	v_mul_f32_e32 v50, v198, v50
	v_mul_f32_e32 v51, v199, v51
	v_mul_f32_e32 v52, v62, v52
	v_mul_f32_e32 v53, v62, v53
	v_mul_f32_e32 v60, v63, v60
	v_mul_f32_e32 v61, v63, v61
	v_mul_f32_e32 v50, v50, v100
	v_mul_f32_e32 v51, v51, v101
	v_mul_f32_e32 v48, v202, v48
	v_mul_f32_e32 v49, v203, v49
	v_cvt_pk_bf16_f32 v150, v52, v53
	v_cvt_pk_bf16_f32 v154, v60, v61
	v_mul_f32_e32 v52, v200, v108
	v_mul_f32_e32 v53, v201, v109
	v_cvt_pk_bf16_f32 v60, v50, v51
	v_mul_f32_e32 v50, v204, v196
	v_mul_f32_e32 v51, v205, v197
	v_mul_f32_e32 v48, v48, v100
	v_mul_f32_e32 v49, v49, v101
	v_rcp_f32_e32 v208, v206
	v_rcp_f32_e32 v210, v106
	v_rcp_f32_e32 v209, v207
	v_rcp_f32_e32 v211, v107
	v_mul_f32_e32 v52, v52, v94
; #define LAS __attribute__((address_space(3)))
; __device__ __forceinline__ unsigned pkbf(float lo, float hi) { const f32x2_m v = {lo, hi}; const bf16x2_m b = __builtin_convertvector(v, bf16x2_m); return __builtin_bit_cast(unsigned, b); }
; __device__ __forceinline__ void hgrn_unit(LAS unsigned char* lds, int b, int h, int vs, const bf16* QR, const _Float16* LF, const bf16* IO, bf16* OR_) {
;     ...
;             float eoff[2], ieoff[2], eGl[2];
;             { const f32x2_m t0v = ((LAS f32x2_m*)(lds + OFF_TOT))[lane], t1v = ((LAS f32x2_m*)(lds + OFF_TOT))[64 + lane], t2v = ((LAS f32x2_m*)(lds + OFF_TOT))[128 + lane], t3v = ((LAS f32x2_m*)(lds + OFF_TOT))[192 + lane];
; #pragma unroll
;               for (int e = 0; e < 2; ++e) { const float off = (ew > 0 ? t0v[e] : 1.f) * (ew > 1 ? t1v[e] : 1.f) * (ew > 2 ? t2v[e] : 1.f);
;                   eoff[e] = off; ieoff[e] = __builtin_amdgcn_rcpf(off); eGl[e] = (t0v[e] * t1v[e]) * (t2v[e] * t3v[e]); } }
;             unsigned klp[2][8];
; #pragma unroll
;             for (int i = 0; i < 16; i += 2) { float kl[2][2];
; #pragma unroll
;                 for (int d = 0; d < 2; ++d) { const float kn0 = kb[0][i + d] * ieoff[0], kn1 = kb[1][i + d] * ieoff[1];
;                     ((LAS unsigned*)(lds + OFF_QG))[(t0 + i + d) * (QS / 2) + lane] = pkbf(qa[0][i + d] * eoff[0], qa[1][i + d] * eoff[1]);
;                     ((LAS unsigned*)(lds + OFF_KN))[(t0 + i + d) * (QS / 2) + lane] = pkbf(kn0, kn1);
;                     kl[0][d] = kn0 * eGl[0]; kl[1][d] = kn1 * eGl[1]; }
;                 klp[0][i >> 1] = pkbf(kl[0][0], kl[0][1]); klp[1][i >> 1] = pkbf(kl[1][0], kl[1][1]); }
; #pragma unroll
;             for (int e = 0; e < 2; ++e) { const int k = 2 * lane + e;
;                 *(LAS v4u*)(lds + OFF_KLT + (k * TS + t0) * 2) = (v4u){klp[e][0], klp[e][1], klp[e][2], klp[e][3]};
;                 *(LAS v4u*)(lds + OFF_KLT + (k * TS + t0 + 8) * 2) = (v4u){klp[e][4], klp[e][5], klp[e][6], klp[e][7]}; }
;             if (ew == 0) ((LAS f32x2_m*)(lds + OFF_GL))[lane] = (f32x2_m){eGl[0], eGl[1]};
	v_mul_f32_e32 v53, v53, v95
	v_mul_f32_e32 v50, v50, v94
	v_mul_f32_e32 v51, v51, v95
	v_cvt_pk_bf16_f32 v48, v48, v49
	v_lshlrev_b32_e32 v46, 16, v65
	v_and_b32_e32 v47, 0xffff0000, v65
	v_cvt_pk_bf16_f32 v61, v52, v53
	ds_write2_b32 v147, v60, v48 offset0:152 offset1:220
	v_cvt_pk_bf16_f32 v48, v50, v51
	ds_write2_b32 v90, v61, v48 offset0:152 offset1:220
	v_mov_b32_e32 v48, v52
	v_mov_b32_e32 v49, v50
	v_mov_b32_e32 v50, v53
	v_mul_f32_e32 v46, v206, v46
	v_mul_f32_e32 v47, v207, v47
	v_mul_f32_e32 v48, v62, v48
	v_mul_f32_e32 v49, v62, v49
	v_mul_f32_e32 v50, v63, v50
	v_mul_f32_e32 v51, v63, v51
	v_mul_f32_e32 v46, v46, v100
	v_mul_f32_e32 v47, v47, v101
	v_mul_f32_e32 v44, v106, v44
	v_mul_f32_e32 v45, v107, v45
	v_cvt_pk_bf16_f32 v151, v48, v49
	v_cvt_pk_bf16_f32 v155, v50, v51
	v_mul_f32_e32 v48, v208, v104
	v_mul_f32_e32 v49, v209, v105
	v_cvt_pk_bf16_f32 v50, v46, v47
	v_mul_f32_e32 v46, v210, v102
	v_mul_f32_e32 v47, v211, v103
	v_mul_f32_e32 v44, v44, v100
	v_mul_f32_e32 v45, v45, v101
	v_rcp_f32_e32 v98, v92
	v_rcp_f32_e32 v96, v88
	v_rcp_f32_e32 v99, v93
	v_rcp_f32_e32 v97, v89
	v_mul_f32_e32 v48, v48, v94
	v_mul_f32_e32 v49, v49, v95
	v_mul_f32_e32 v46, v46, v94
	v_mul_f32_e32 v47, v47, v95
	v_cvt_pk_bf16_f32 v44, v44, v45
	v_add_u32_e32 v52, 0x800, v112
	v_cvt_pk_bf16_f32 v51, v48, v49
	ds_write2_b32 v52, v50, v44 offset0:32 offset1:100
	v_cvt_pk_bf16_f32 v44, v46, v47
	v_add_u32_e32 v50, 0x4c00, v112
	ds_write2_b32 v50, v51, v44 offset0:32 offset1:100
	v_mov_b32_e32 v44, v48
	v_mov_b32_e32 v45, v46
	v_mov_b32_e32 v46, v49
	v_mul_f32_e32 v42, v92, v42
	v_mul_f32_e32 v43, v93, v43
	v_mul_f32_e32 v44, v62, v44
	v_mul_f32_e32 v45, v62, v45
	v_mul_f32_e32 v46, v63, v46
	v_mul_f32_e32 v47, v63, v47
	v_mul_f32_e32 v42, v42, v100
	v_mul_f32_e32 v43, v43, v101
	v_mul_f32_e32 v40, v88, v40
	v_mul_f32_e32 v41, v89, v41
	v_cvt_pk_bf16_f32 v44, v44, v45
	v_cvt_pk_bf16_f32 v48, v46, v47
	v_mul_f32_e32 v46, v98, v86
	v_mul_f32_e32 v47, v99, v87
	v_cvt_pk_bf16_f32 v45, v42, v43
	v_mul_f32_e32 v42, v96, v82
	v_mul_f32_e32 v43, v97, v83
	v_mul_f32_e32 v40, v40, v100
	v_mul_f32_e32 v41, v41, v101
	v_rcp_f32_e32 v84, v76
	v_rcp_f32_e32 v80, v74
	v_rcp_f32_e32 v85, v77
	v_rcp_f32_e32 v81, v75
	v_mul_f32_e32 v46, v46, v94
	v_mul_f32_e32 v47, v47, v95
	v_mul_f32_e32 v42, v42, v94
	v_mul_f32_e32 v43, v43, v95
	v_cvt_pk_bf16_f32 v40, v40, v41
	v_cvt_pk_bf16_f32 v49, v46, v47
	ds_write2_b32 v52, v45, v40 offset0:168 offset1:236
	v_cvt_pk_bf16_f32 v40, v42, v43
	ds_write2_b32 v50, v49, v40 offset0:168 offset1:236
	v_mov_b32_e32 v40, v46
	v_mov_b32_e32 v41, v42
	v_mov_b32_e32 v42, v47
	v_mul_f32_e32 v38, v76, v38
	v_mul_f32_e32 v39, v77, v39
	v_mul_f32_e32 v40, v62, v40
	v_mul_f32_e32 v41, v62, v41
	v_mul_f32_e32 v42, v63, v42
	v_mul_f32_e32 v43, v63, v43
	v_mul_f32_e32 v38, v38, v100
	v_mul_f32_e32 v39, v39, v101
	v_mul_f32_e32 v36, v74, v36
	v_mul_f32_e32 v37, v75, v37
	v_cvt_pk_bf16_f32 v45, v40, v41
	v_cvt_pk_bf16_f32 v49, v42, v43
	v_mul_f32_e32 v40, v84, v72
	v_mul_f32_e32 v41, v85, v73
	v_cvt_pk_bf16_f32 v42, v38, v39
	v_mul_f32_e32 v38, v80, v70
	v_mul_f32_e32 v39, v81, v71
	v_mul_f32_e32 v36, v36, v100
	v_mul_f32_e32 v37, v37, v101
	v_rcp_f32_e32 v68, v66
	v_rcp_f32_e32 v64, v58
	v_rcp_f32_e32 v69, v67
	v_rcp_f32_e32 v65, v59
	v_mul_f32_e32 v40, v40, v94
	v_mul_f32_e32 v41, v41, v95
	v_mul_f32_e32 v38, v38, v94
	v_mul_f32_e32 v39, v39, v95
	v_cvt_pk_bf16_f32 v36, v36, v37
	v_add_u32_e32 v47, 0xc00, v112
	v_cvt_pk_bf16_f32 v43, v40, v41
	ds_write2_b32 v47, v42, v36 offset0:48 offset1:116
	v_cvt_pk_bf16_f32 v36, v38, v39
	v_add_u32_e32 v42, 0x5000, v112
	ds_write2_b32 v42, v43, v36 offset0:48 offset1:116
	v_mov_b32_e32 v36, v40
	v_mov_b32_e32 v37, v38
	v_mov_b32_e32 v38, v41
	v_mul_f32_e32 v34, v66, v34
	v_mul_f32_e32 v35, v67, v35
	v_mul_f32_e32 v36, v62, v36
	v_mul_f32_e32 v37, v62, v37
	v_mul_f32_e32 v38, v63, v38
	v_mul_f32_e32 v39, v63, v39
	v_mul_f32_e32 v34, v34, v100
	v_mul_f32_e32 v35, v35, v101
	v_mul_f32_e32 v32, v58, v32
	v_mul_f32_e32 v33, v59, v33
	v_cvt_pk_bf16_f32 v46, v36, v37
	v_cvt_pk_bf16_f32 v50, v38, v39
	v_mul_f32_e32 v36, v68, v56
	v_mul_f32_e32 v37, v69, v57
	v_cvt_pk_bf16_f32 v38, v34, v35
	v_mul_f32_e32 v34, v64, v54
	v_mul_f32_e32 v35, v65, v55
	v_mul_f32_e32 v32, v32, v100
	v_mul_f32_e32 v33, v33, v101
	v_mul_f32_e32 v36, v36, v94
	v_mul_f32_e32 v37, v37, v95
	v_mul_f32_e32 v34, v34, v94
	v_mul_f32_e32 v35, v35, v95
	v_cvt_pk_bf16_f32 v32, v32, v33
	v_cvt_pk_bf16_f32 v39, v36, v37
	ds_write2_b32 v47, v38, v32 offset0:184 offset1:252
	v_cvt_pk_bf16_f32 v32, v34, v35
	v_mov_b32_e32 v33, v34
	v_mov_b32_e32 v34, v37
	ds_write2_b32 v42, v39, v32 offset0:184 offset1:252
	v_mov_b32_e32 v32, v36
	v_mul_f32_e32 v34, v63, v34
	v_mul_f32_e32 v35, v63, v35
	v_mul_f32_e32 v32, v62, v32
	v_mul_f32_e32 v33, v62, v33
	v_cvt_pk_bf16_f32 v51, v34, v35
	s_andn2_b64 vcc, exec, s[14:15]
	v_cvt_pk_bf16_f32 v47, v32, v33
	ds_write_b128 v113, v[148:151] offset:34816
	ds_write_b128 v113, v[44:47] offset:34832
	ds_write_b128 v113, v[152:155] offset:34960
	ds_write_b128 v113, v[48:51] offset:34976
	s_cbranch_vccnz .LBB0_1548
	ds_write_b64 v111, v[62:63]
	s_branch .LBB0_1548

; __device__ __forceinline__ float fexp(float x) { return __builtin_amdgcn_exp2f(x * LOG2E); }
; __device__ __forceinline__ void combine_rows(const bf16* O1, const bf16* O2, const bf16* OR_, const bf16* Gs, bf16* YA, bf16* YR, float lam, const float* subln, const float* gnorm, int gw, int NGW, int lane) {
;     float wa[16], wg[16];
; #pragma unroll
;     for (int i = 0; i < 16; ++i) { wa[i] = subln[16 * (lane & 7) + i] * 0.8f; wg[i] = gnorm[16 * (lane & 7) + i]; }
; __global__ void __launch_bounds__(512, 2) fwd_megakernel(Args a) {
;     ...
;     { const float d1 = wave_sum(a.in[I_LQ1][lane] * a.in[I_LK1][lane]), d2 = wave_sum(a.in[I_LQ2][lane] * a.in[I_LK2][lane]);
;       const float lam = fexp(d1) - fexp(d2) + 0.2f;
;       combine_rows(O1, O2, (const bf16*)(ws + WS_OR), P + PB_G * PBUF, YA, YR, lam, a.in[I_SUBLN], a.in[I_GNORM], gw, NGW, lane); }
.LBB0_1606:
	s_or_b64 exec, exec, s[4:5]
	v_readlane_b32 s8, v250, 12
	s_waitcnt lgkmcnt(0)
	v_lshlrev_b32_e32 v0, 2, v223
	v_readlane_b32 s9, v250, 13
	s_barrier
	global_load_dword v1, v0, s[28:29]
	global_load_dword v2, v0, s[30:31]
	v_readlane_b32 s10, v250, 14
	v_readlane_b32 s11, v250, 15
	global_load_dword v3, v0, s[8:9]
	s_nop 3
	global_load_dword v0, v0, s[10:11]
	v_mbcnt_hi_u32_b32 v4, -1, v226
	v_and_b32_e32 v5, 64, v4
	v_xor_b32_e32 v6, 1, v4
	v_add_u32_e32 v5, 64, v5
	v_cmp_lt_i32_e32 vcc, v6, v5
	v_xor_b32_e32 v7, 2, v4
	v_xor_b32_e32 v8, 4, v4
	v_cndmask_b32_e32 v6, v4, v6, vcc
	v_lshlrev_b32_e32 v54, 2, v6
	v_cmp_lt_i32_e32 vcc, v7, v5
	v_xor_b32_e32 v9, 8, v4
	v_xor_b32_e32 v10, 16, v4
	v_cndmask_b32_e32 v7, v4, v7, vcc
	v_lshlrev_b32_e32 v55, 2, v7
	v_cmp_lt_i32_e32 vcc, v8, v5
	v_xor_b32_e32 v11, 32, v4
	v_readlane_b32 s0, v250, 34
	v_readlane_b32 s1, v250, 35
	v_readlane_b32 s68, v250, 53
	v_readlane_b32 s12, v250, 16
	v_readlane_b32 s13, v250, 17
	v_readlane_b32 s16, v250, 20
	v_readlane_b32 s17, v250, 21
	v_mov_b32_e32 v17, 0
	v_readlane_b32 s69, v250, 54
	v_readlane_b32 s14, v250, 18
	v_readlane_b32 s15, v250, 19
	v_readlane_b32 s18, v250, 22
	v_readlane_b32 s19, v250, 23
	v_readlane_b32 s20, v250, 24
	v_readlane_b32 s21, v250, 25
	v_readlane_b32 s22, v250, 26
	v_readlane_b32 s23, v250, 27
	s_waitcnt vmcnt(2)
	v_mul_f32_e32 v6, v1, v2
	ds_bpermute_b32 v6, v54, v6
	s_waitcnt vmcnt(0)
	v_mul_f32_e32 v12, v3, v0
	ds_bpermute_b32 v12, v54, v12
	s_waitcnt lgkmcnt(1)
	v_fmac_f32_e32 v6, v1, v2
	v_cndmask_b32_e32 v2, v4, v8, vcc
	v_lshlrev_b32_e32 v56, 2, v2
	s_waitcnt lgkmcnt(0)
	v_fmac_f32_e32 v12, v3, v0
	ds_bpermute_b32 v0, v55, v6
	ds_bpermute_b32 v1, v55, v12
	v_cmp_lt_i32_e32 vcc, v9, v5
	s_waitcnt lgkmcnt(1)
	v_add_f32_e32 v0, v6, v0
	s_waitcnt lgkmcnt(0)
	v_add_f32_e32 v1, v12, v1
	ds_bpermute_b32 v2, v56, v0
	ds_bpermute_b32 v3, v56, v1
	v_cndmask_b32_e32 v6, v4, v9, vcc
	v_lshlrev_b32_e32 v6, 2, v6
	v_cmp_lt_i32_e32 vcc, v10, v5
	s_waitcnt lgkmcnt(1)
	v_add_f32_e32 v0, v0, v2
	s_waitcnt lgkmcnt(0)
	v_add_f32_e32 v1, v1, v3
	ds_bpermute_b32 v2, v6, v0
	ds_bpermute_b32 v3, v6, v1
	v_cndmask_b32_e32 v6, v4, v10, vcc
	v_lshlrev_b32_e32 v226, 2, v6
	v_cmp_lt_i32_e32 vcc, v11, v5
	s_waitcnt lgkmcnt(1)
	v_add_f32_e32 v0, v0, v2
	s_waitcnt lgkmcnt(0)
	v_add_f32_e32 v1, v1, v3
	ds_bpermute_b32 v2, v226, v0
	ds_bpermute_b32 v3, v226, v1
	v_cndmask_b32_e32 v4, v4, v11, vcc
	v_lshlrev_b32_e32 v227, 2, v4
	s_andn2_b64 vcc, exec, s[0:1]
	s_waitcnt lgkmcnt(1)
	v_add_f32_e32 v18, v0, v2
	s_waitcnt lgkmcnt(0)
	v_add_f32_e32 v16, v1, v3
	ds_bpermute_b32 v20, v227, v18
	ds_bpermute_b32 v19, v227, v16
	v_cndmask_b32_e64 v0, 0, 1, s[0:1]
	v_cmp_ne_u32_e64 s[8:9], 1, v0
	s_cbranch_vccnz .LBB0_1609
	v_lshlrev_b32_e32 v0, 6, v223
	v_and_b32_e32 v12, 0x1c0, v0
	global_load_dwordx4 v[28:31], v12, s[12:13]
	global_load_dwordx4 v[32:35], v12, s[12:13] offset:16
	global_load_dwordx4 v[36:39], v12, s[12:13] offset:32
	global_load_dwordx4 v[40:43], v12, s[12:13] offset:48
	global_load_dwordx4 v[0:3], v12, s[16:17] offset:48
	global_load_dwordx4 v[4:7], v12, s[16:17] offset:32
	global_load_dwordx4 v[8:11], v12, s[16:17] offset:16
	s_nop 0
	global_load_dwordx4 v[12:15], v12, s[16:17]
	s_waitcnt lgkmcnt(1)
	v_add_f32_e32 v18, v18, v20
	s_waitcnt lgkmcnt(0)
	v_add_f32_e32 v19, v16, v19
	s_ashr_i32 s35, s34, 31
	v_mul_f32_e32 v18, 0x3fb8aa3b, v18
	v_mul_f32_e32 v19, 0x3fb8aa3b, v19
	s_lshl_b64 s[16:17], s[34:35], 11
	v_exp_f32_e32 v18, v18
	v_exp_f32_e32 v19, v19
	s_add_u32 s16, s62, s16
	v_lshlrev_b32_e32 v16, 5, v223
	s_addc_u32 s17, s63, s17
	s_mov_b64 s[12:13], 0x1df00010
	v_lshl_add_u64 v[16:17], s[16:17], 0, v[16:17]
	v_lshl_add_u64 v[24:25], v[16:17], 0, s[12:13]
	v_sub_f32_e32 v16, v18, v19
	s_mov_b32 s10, 0x3f4ccccd
	s_mov_b32 s0, 0xfbfffff0
	s_mov_b32 s4, 0xfdfffff0
	s_mov_b32 s14, 0xf9fffff0
	s_ashr_i32 s65, s64, 31
	v_add_f32_e32 v26, 0x3e4ccccd, v16
	s_mov_b32 s1, -1
	s_mov_b32 s5, -1
	s_mov_b32 s3, 0xfe000000
	s_mov_b32 s15, -1
	s_mov_b32 s18, 0xfa000000
	v_mov_b32_e32 v57, 0x358637bd
	s_mov_b32 s19, 0xf800000
	v_mov_b32_e32 v58, 0x260
	s_mov_b32 s20, 0xee000000
	s_brev_b32 s21, 15
	s_lshl_b64 s[16:17], s[64:65], 11
	v_mov_b32_e32 v27, v26
	s_mov_b32 s22, s34
	s_waitcnt vmcnt(7)
	v_mul_f32_e32 v28, s10, v28
	v_mul_f32_e32 v29, s10, v29
	v_mul_f32_e32 v30, s10, v30
	v_mul_f32_e32 v31, s10, v31
	s_waitcnt vmcnt(6)
	v_mul_f32_e32 v32, s10, v32
	v_mul_f32_e32 v33, s10, v33
	v_mul_f32_e32 v34, s10, v34
	v_mul_f32_e32 v35, s10, v35
	s_waitcnt vmcnt(5)
	v_mul_f32_e32 v36, s10, v36
	v_mul_f32_e32 v37, s10, v37
	v_mul_f32_e32 v38, s10, v38
	v_mul_f32_e32 v39, s10, v39
	s_waitcnt vmcnt(4)
	v_mul_f32_e32 v40, s10, v40
	v_mul_f32_e32 v41, s10, v41
	v_mul_f32_e32 v42, s10, v42
	v_mul_f32_e32 v43, s10, v43
; __device__ __forceinline__ void combine_rows(const bf16* O1, const bf16* O2, const bf16* OR_, const bf16* Gs, bf16* YA, bf16* YR, float lam, const float* subln, const float* gnorm, int gw, int NGW, int lane) {
;     ...
;     for (int m = gw; m < M; m += NGW) { const size_t p = (size_t)m * 1024 + 16 * lane;
;         float a[16], b2[16], r[16], g[16]; unpack16(O1 + p, a); unpack16(O2 + p, b2); unpack16(OR_ + p, r); unpack16(Gs + p, g);
;         float sa = 0.f, sr = 0.f;
; #pragma unroll
;         for (int i = 0; i < 16; ++i) { a[i] = a[i] - lam * b2[i]; sa += a[i] * a[i]; sr += r[i] * r[i]; }
;         sa += __shfl_xor(sa, 1); sa += __shfl_xor(sa, 2); sa += __shfl_xor(sa, 4); sr += __shfl_xor(sr, 1); sr += __shfl_xor(sr, 2); sr += __shfl_xor(sr, 4);
.LBB0_1608:
	v_add_co_u32_e32 v50, vcc, 0xfc000000, v24
	global_load_dwordx4 v[20:23], v[24:25], off
	global_load_dwordx4 v[16:19], v[24:25], off offset:-16
	v_addc_co_u32_e32 v51, vcc, -1, v25, vcc
	v_add_co_u32_e32 v68, vcc, s3, v24
	v_lshl_add_u64 v[48:49], v[24:25], 0, s[0:1]
	v_lshl_add_u64 v[46:47], v[24:25], 0, s[4:5]
	v_addc_co_u32_e32 v69, vcc, -1, v25, vcc
	global_load_dwordx4 v[60:63], v[48:49], off offset:16
	s_nop 0
	global_load_dwordx4 v[48:51], v[50:51], off offset:-16
	s_nop 0
	global_load_dwordx4 v[64:67], v[46:47], off offset:16
	s_nop 0
	global_load_dwordx4 v[68:71], v[68:69], off offset:-16
	v_add_co_u32_e32 v72, vcc, s18, v24
	v_lshl_add_u64 v[44:45], v[24:25], 0, s[14:15]
	s_nop 0
	v_addc_co_u32_e32 v73, vcc, -1, v25, vcc
	global_load_dwordx4 v[44:47], v[44:45], off offset:16
	s_nop 0
	global_load_dwordx4 v[72:75], v[72:73], off offset:-16
	v_add_co_u32_e64 v52, s[10:11], s20, v24
	s_add_i32 s22, s22, s64
	s_nop 0
	v_addc_co_u32_e64 v53, s[10:11], -1, v25, s[10:11]
	s_cmpk_lt_i32 s22, 0x4000
	s_waitcnt vmcnt(7)
	v_and_b32_e32 v76, 0xffff0000, v23
	s_waitcnt vmcnt(6)
	v_lshlrev_b32_e32 v84, 16, v16
	v_and_b32_e32 v85, 0xffff0000, v16
	v_lshlrev_b32_e32 v77, 16, v23
	v_lshlrev_b32_e32 v78, 16, v22
	v_and_b32_e32 v79, 0xffff0000, v22
	v_lshlrev_b32_e32 v22, 16, v21
	v_and_b32_e32 v23, 0xffff0000, v21
	v_lshlrev_b32_e32 v80, 16, v20
	v_and_b32_e32 v81, 0xffff0000, v20
	v_lshlrev_b32_e32 v20, 16, v19
	v_and_b32_e32 v21, 0xffff0000, v19
	v_lshlrev_b32_e32 v82, 16, v18
	v_and_b32_e32 v83, 0xffff0000, v18
	v_lshlrev_b32_e32 v18, 16, v17
	v_and_b32_e32 v19, 0xffff0000, v17
	v_mul_f32_e32 v98, v84, v84
	v_mul_f32_e32 v99, v85, v85
	v_mul_f32_e32 v96, v18, v18
	v_mul_f32_e32 v97, v19, v19
	v_add_f32_e32 v59, v98, v99
	s_waitcnt vmcnt(5)
	v_and_b32_e32 v100, 0xffff0000, v63
	v_lshlrev_b32_e32 v101, 16, v63
	v_lshlrev_b32_e32 v102, 16, v62
	v_and_b32_e32 v103, 0xffff0000, v62
	v_lshlrev_b32_e32 v62, 16, v61
	v_and_b32_e32 v63, 0xffff0000, v61
	v_lshlrev_b32_e32 v104, 16, v60
	v_and_b32_e32 v105, 0xffff0000, v60
	s_waitcnt vmcnt(4)
	v_lshlrev_b32_e32 v60, 16, v51
	v_and_b32_e32 v61, 0xffff0000, v51
	v_lshlrev_b32_e32 v106, 16, v50
	v_and_b32_e32 v107, 0xffff0000, v50
	v_lshlrev_b32_e32 v50, 16, v49
	v_and_b32_e32 v51, 0xffff0000, v49
	v_lshlrev_b32_e32 v108, 16, v48
	v_and_b32_e32 v109, 0xffff0000, v48
	s_waitcnt vmcnt(3)
	v_and_b32_e32 v48, 0xffff0000, v67
	v_lshlrev_b32_e32 v49, 16, v67
	v_lshlrev_b32_e32 v98, 16, v66
	v_and_b32_e32 v99, 0xffff0000, v66
	v_lshlrev_b32_e32 v66, 16, v65
	v_and_b32_e32 v67, 0xffff0000, v65
	v_lshlrev_b32_e32 v110, 16, v64
	v_and_b32_e32 v111, 0xffff0000, v64
	s_waitcnt vmcnt(2)
	v_lshlrev_b32_e32 v64, 16, v71
	v_and_b32_e32 v65, 0xffff0000, v71
	v_lshlrev_b32_e32 v112, 16, v70
	v_and_b32_e32 v113, 0xffff0000, v70
	v_lshlrev_b32_e32 v70, 16, v69
	v_and_b32_e32 v71, 0xffff0000, v69
	v_lshlrev_b32_e32 v114, 16, v68
	v_and_b32_e32 v115, 0xffff0000, v68
	v_add_f32_e32 v59, v96, v59
	v_mul_f32_e32 v94, v82, v82
	v_mul_f32_e32 v95, v83, v83
	v_fma_f32 v50, -v26, v70, v50
	v_fma_f32 v51, -v27, v71, v51
	v_fma_f32 v70, -v26, v114, v108
	v_fma_f32 v71, -v27, v115, v109
	v_add_f32_e32 v59, v97, v59
	v_mul_f32_e32 v118, v70, v70
	v_mul_f32_e32 v119, v71, v71
	v_add_f32_e32 v59, v94, v59
	v_mul_f32_e32 v92, v20, v20
	v_mul_f32_e32 v93, v21, v21
	v_mul_f32_e32 v116, v50, v50
	v_mul_f32_e32 v117, v51, v51
	v_add_f32_e32 v94, v118, v119
	v_add_f32_e32 v59, v95, v59
	v_fma_f32 v60, -v26, v64, v60
	v_fma_f32 v61, -v27, v65, v61
	v_fma_f32 v64, -v26, v112, v106
	v_fma_f32 v65, -v27, v113, v107
	v_add_f32_e32 v94, v116, v94
	v_add_f32_e32 v59, v92, v59
	v_mul_f32_e32 v90, v80, v80
	v_mul_f32_e32 v91, v81, v81
	v_mul_f32_e32 v114, v64, v64
	v_mul_f32_e32 v115, v65, v65
	v_add_f32_e32 v92, v117, v94
	v_add_f32_e32 v59, v93, v59
	v_add_f32_e32 v92, v114, v92
	v_add_f32_e32 v59, v90, v59
	v_mul_f32_e32 v88, v22, v22
	v_mul_f32_e32 v89, v23, v23
	v_mul_f32_e32 v112, v60, v60
	v_mul_f32_e32 v113, v61, v61
	v_add_f32_e32 v90, v115, v92
	v_add_f32_e32 v59, v91, v59
	v_fma_f32 v62, -v26, v66, v62
	v_fma_f32 v63, -v27, v67, v63
	v_fma_f32 v66, -v26, v110, v104
	v_fma_f32 v67, -v27, v111, v105
	v_add_f32_e32 v90, v112, v90
	v_add_f32_e32 v59, v88, v59
	v_mul_f32_e32 v86, v78, v78
	v_mul_f32_e32 v87, v79, v79
	v_mul_f32_e32 v110, v66, v66
	v_mul_f32_e32 v111, v67, v67
	v_add_f32_e32 v88, v113, v90
	v_add_f32_e32 v59, v89, v59
	v_add_f32_e32 v88, v110, v88
	v_add_f32_e32 v59, v86, v59
	v_mul_f32_e32 v16, v76, v76
	v_mul_f32_e32 v17, v77, v77
	v_mul_f32_e32 v108, v62, v62
	v_mul_f32_e32 v109, v63, v63
	v_add_f32_e32 v86, v111, v88
	v_add_f32_e32 v59, v87, v59
	v_fma_f32 v68, -v26, v98, v102
	v_fma_f32 v69, -v27, v99, v103
	v_add_f32_e32 v86, v108, v86
	v_add_f32_e32 v17, v17, v59
	v_mul_f32_e32 v96, v68, v68
	v_mul_f32_e32 v97, v69, v69
	v_add_f32_e32 v59, v109, v86
	v_add_f32_e32 v16, v16, v17
	v_fma_f32 v48, -v26, v48, v100
	v_fma_f32 v49, -v27, v49, v101
	v_add_f32_e32 v17, v96, v59
	ds_bpermute_b32 v59, v54, v16
	s_waitcnt vmcnt(1)
	v_lshlrev_b32_e32 v100, 16, v45
	v_and_b32_e32 v101, 0xffff0000, v45
	v_lshlrev_b32_e32 v102, 16, v44
	v_and_b32_e32 v103, 0xffff0000, v44
	s_waitcnt vmcnt(0)
	v_lshlrev_b32_e32 v44, 16, v75
	v_and_b32_e32 v45, 0xffff0000, v75
	v_lshlrev_b32_e32 v104, 16, v74
	v_and_b32_e32 v105, 0xffff0000, v74
	v_lshlrev_b32_e32 v74, 16, v73
	v_and_b32_e32 v75, 0xffff0000, v73
	v_lshlrev_b32_e32 v106, 16, v72
	v_and_b32_e32 v107, 0xffff0000, v72
	v_mul_f32_e32 v72, v48, v48
	v_mul_f32_e32 v73, v49, v49
	v_add_f32_e32 v17, v97, v17
	v_add_f32_e32 v17, v73, v17
	v_add_f32_e32 v17, v72, v17
	ds_bpermute_b32 v72, v54, v17
	s_waitcnt lgkmcnt(1)
; __device__ __forceinline__ void combine_rows(const bf16* O1, const bf16* O2, const bf16* OR_, const bf16* Gs, bf16* YA, bf16* YR, float lam, const float* subln, const float* gnorm, int gw, int NGW, int lane) {
;     ...
;         sa += __shfl_xor(sa, 1); sa += __shfl_xor(sa, 2); sa += __shfl_xor(sa, 4); sr += __shfl_xor(sr, 1); sr += __shfl_xor(sr, 2); sr += __shfl_xor(sr, 4);
;         const float ra = 1.0f / sqrtf(sa * (1.f / 128.f) + EPS), rr = 1.0f / sqrtf(sr * (1.f / 128.f) + EPS);
; #pragma unroll
;         for (int i = 0; i < 16; ++i) { a[i] = a[i] * ra * wa[i]; r[i] = r[i] * rr * wg[i] * g[i]; }
;         pack16(YA + p, a); pack16(YR + p, r); }
	v_add_f32_e32 v16, v16, v59
	ds_bpermute_b32 v59, v55, v16
	v_lshlrev_b32_e32 v98, 16, v46
	v_and_b32_e32 v99, 0xffff0000, v46
	s_waitcnt lgkmcnt(1)
	v_add_f32_e32 v17, v17, v72
	ds_bpermute_b32 v72, v55, v17
	s_waitcnt lgkmcnt(1)
	v_add_f32_e32 v16, v16, v59
	ds_bpermute_b32 v59, v56, v16
	v_lshlrev_b32_e32 v46, 16, v47
	v_and_b32_e32 v47, 0xffff0000, v47
	s_waitcnt lgkmcnt(1)
	v_add_f32_e32 v17, v17, v72
	ds_bpermute_b32 v72, v56, v17
	s_waitcnt lgkmcnt(1)
	v_add_f32_e32 v16, v16, v59
	v_fmamk_f32 v16, v16, 0x3c000000, v57
	v_mul_f32_e32 v59, 0x4f800000, v16
	v_cmp_gt_f32_e32 vcc, s19, v16
	s_waitcnt lgkmcnt(0)
	v_add_f32_e32 v17, v17, v72
	v_fmamk_f32 v17, v17, 0x3c000000, v57
	v_cndmask_b32_e32 v16, v16, v59, vcc
	v_sqrt_f32_e32 v59, v16
	v_mul_f32_e32 v72, 0x4f800000, v17
	v_cmp_gt_f32_e64 s[10:11], s19, v17
	v_add_u32_e32 v73, -1, v59
	s_nop 0
	v_cndmask_b32_e64 v17, v17, v72, s[10:11]
	v_sqrt_f32_e32 v72, v17
	v_add_u32_e32 v86, 1, v59
	v_fma_f32 v87, -v73, v59, v16
	v_fma_f32 v88, -v86, v59, v16
	v_cmp_ge_f32_e64 s[12:13], 0, v87
	s_nop 1
	v_cndmask_b32_e64 v59, v59, v73, s[12:13]
	v_cmp_lt_f32_e64 s[12:13], 0, v88
	v_add_u32_e32 v73, -1, v72
	v_fma_f32 v88, -v73, v72, v17
	v_cndmask_b32_e64 v59, v59, v86, s[12:13]
	v_add_u32_e32 v86, 1, v72
	v_mul_f32_e32 v87, 0x37800000, v59
	v_fma_f32 v89, -v86, v72, v17
	v_cndmask_b32_e32 v59, v59, v87, vcc
	v_cmp_class_f32_e32 vcc, v16, v58
	v_cmp_ge_f32_e64 s[12:13], 0, v88
	s_nop 0
	v_cndmask_b32_e32 v59, v59, v16, vcc
	v_cndmask_b32_e64 v72, v72, v73, s[12:13]
	v_cmp_lt_f32_e32 vcc, 0, v89
	s_nop 1
	v_cndmask_b32_e32 v16, v72, v86, vcc
	v_div_scale_f32 v72, s[12:13], v59, v59, 1.0
	v_mul_f32_e32 v86, 0x37800000, v16
	v_rcp_f32_e32 v87, v72
	v_cndmask_b32_e64 v16, v16, v86, s[10:11]
	v_cmp_class_f32_e32 vcc, v17, v58
	v_div_scale_f32 v73, s[12:13], 1.0, v59, 1.0
	s_nop 0
	v_cndmask_b32_e32 v16, v16, v17, vcc
	v_div_scale_f32 v17, s[10:11], v16, v16, 1.0
	v_rcp_f32_e32 v88, v17
	v_fma_f32 v89, -v72, v87, 1.0
	v_fmac_f32_e32 v87, v89, v87
	v_mul_f32_e32 v89, v73, v87
	v_fma_f32 v90, -v72, v89, v73
	v_fma_f32 v91, -v17, v88, 1.0
	v_div_scale_f32 v86, vcc, 1.0, v16, 1.0
	v_fmac_f32_e32 v89, v90, v87
	v_fmac_f32_e32 v88, v91, v88
	v_fma_f32 v72, -v72, v89, v73
	v_mul_f32_e32 v73, v86, v88
	v_fma_f32 v90, -v17, v73, v86
	v_fmac_f32_e32 v73, v90, v88
	v_fma_f32 v17, -v17, v73, v86
	v_div_fmas_f32 v17, v17, v88, v73
	s_mov_b64 vcc, s[12:13]
	v_div_fixup_f32 v16, v17, v16, 1.0
	v_div_fmas_f32 v17, v72, v87, v89
	v_mul_f32_e32 v70, v70, v16
	v_mul_f32_e32 v71, v71, v16
	v_div_fixup_f32 v86, v17, v59, 1.0
	v_mul_f32_e32 v50, v50, v16
	v_mul_f32_e32 v51, v51, v16
	v_mul_f32_e32 v64, v64, v16
	v_mul_f32_e32 v65, v65, v16
	v_mul_f32_e32 v60, v60, v16
	v_mul_f32_e32 v61, v61, v16
	v_mul_f32_e32 v66, v66, v16
	v_mul_f32_e32 v67, v67, v16
	v_mul_f32_e32 v62, v62, v16
	v_mul_f32_e32 v63, v63, v16
	v_mul_f32_e32 v68, v68, v16
	v_mul_f32_e32 v69, v69, v16
	v_mul_f32_e32 v17, v49, v16
	v_mul_f32_e32 v16, v48, v16
	v_mul_f32_e32 v48, v28, v70
	v_mul_f32_e32 v49, v29, v71
	v_mul_f32_e32 v70, v86, v84
	v_mul_f32_e32 v71, v86, v85
	v_mul_f32_e32 v18, v86, v18
	v_mul_f32_e32 v19, v86, v19
	v_mul_f32_e32 v82, v86, v82
	v_mul_f32_e32 v83, v86, v83
	v_mul_f32_e32 v20, v86, v20
	v_mul_f32_e32 v21, v86, v21
	v_mul_f32_e32 v50, v30, v50
	v_mul_f32_e32 v51, v31, v51
	v_mul_f32_e32 v64, v32, v64
	v_mul_f32_e32 v65, v33, v65
	v_mul_f32_e32 v60, v34, v60
	v_mul_f32_e32 v61, v35, v61
	v_mul_f32_e32 v80, v86, v80
	v_mul_f32_e32 v81, v86, v81
	v_mul_f32_e32 v22, v86, v22
	v_mul_f32_e32 v23, v86, v23
	v_mul_f32_e32 v78, v86, v78
	v_mul_f32_e32 v79, v86, v79
	v_mul_f32_e32 v84, v42, v17
	v_mul_f32_e32 v85, v43, v16
	v_mul_f32_e32 v16, v86, v76
	v_mul_f32_e32 v17, v86, v77
	v_mul_f32_e32 v70, v12, v70
	v_mul_f32_e32 v71, v13, v71
	v_mul_f32_e32 v76, v14, v18
	v_mul_f32_e32 v77, v15, v19
	v_mul_f32_e32 v82, v8, v82
	v_mul_f32_e32 v83, v9, v83
	v_mul_f32_e32 v86, v10, v20
	v_mul_f32_e32 v87, v11, v21
	v_add_co_u32_e32 v72, vcc, s21, v24
	v_mul_f32_e32 v66, v36, v66
	v_mul_f32_e32 v67, v37, v67
	v_mul_f32_e32 v62, v38, v62
	v_mul_f32_e32 v63, v39, v63
	v_mul_f32_e32 v68, v40, v68
	v_mul_f32_e32 v69, v41, v69
	v_mul_f32_e32 v80, v4, v80
	v_mul_f32_e32 v81, v5, v81
	v_mul_f32_e32 v88, v6, v22
	v_mul_f32_e32 v89, v7, v23
	v_mul_f32_e32 v78, v0, v78
	v_mul_f32_e32 v79, v1, v79
	v_mul_f32_e32 v90, v2, v17
	v_mul_f32_e32 v91, v3, v16
	v_cvt_pk_bf16_f32 v16, v48, v49
	v_cvt_pk_bf16_f32 v17, v50, v51
	v_cvt_pk_bf16_f32 v18, v64, v65
	v_cvt_pk_bf16_f32 v19, v60, v61
	v_mul_f32_e32 v48, v70, v106
	v_mul_f32_e32 v49, v71, v107
	v_mul_f32_e32 v50, v76, v74
	v_mul_f32_e32 v51, v77, v75
	v_mul_f32_e32 v60, v82, v104
	v_mul_f32_e32 v61, v83, v105
	v_mul_f32_e32 v44, v86, v44
	v_mul_f32_e32 v45, v87, v45
	v_addc_co_u32_e32 v73, vcc, -1, v25, vcc
	v_lshl_add_u64 v[24:25], v[24:25], 0, s[16:17]
	v_cvt_pk_bf16_f32 v20, v66, v67
	v_cvt_pk_bf16_f32 v21, v62, v63
	v_cvt_pk_bf16_f32 v22, v68, v69
	v_cvt_pk_bf16_f32 v23, v84, v85
	v_mul_f32_e32 v62, v80, v102
	v_mul_f32_e32 v63, v81, v103
	v_mul_f32_e32 v64, v88, v100
	v_mul_f32_e32 v65, v89, v101
	v_mul_f32_e32 v66, v78, v98
	v_mul_f32_e32 v67, v79, v99
	v_mul_f32_e32 v46, v90, v46
	v_mul_f32_e32 v47, v91, v47
	global_store_dwordx4 v[52:53], v[16:19], off offset:-16
	global_store_dwordx4 v[52:53], v[20:23], off
	s_nop 0
	v_cvt_pk_bf16_f32 v16, v48, v49
	v_cvt_pk_bf16_f32 v17, v50, v51
	v_cvt_pk_bf16_f32 v18, v60, v61
	v_cvt_pk_bf16_f32 v19, v44, v45
	v_cvt_pk_bf16_f32 v20, v62, v63
	v_cvt_pk_bf16_f32 v21, v64, v65
	v_cvt_pk_bf16_f32 v22, v66, v67
	v_cvt_pk_bf16_f32 v23, v46, v47
	global_store_dwordx4 v[72:73], v[16:19], off offset:-16
	global_store_dwordx4 v[72:73], v[20:23], off
	s_cbranch_scc1 .LBB0_1608

; __device__ __forceinline__ unsigned pkbf(float lo, float hi) { const f32x2_m v = {lo, hi}; const bf16x2_m b = __builtin_convertvector(v, bf16x2_m); return __builtin_bit_cast(unsigned, b); }
;     __device__ __forceinline__ void operator()(const f32x4 (&acc)[2][2][4][2], const Unit& u, int wr, int wc, int fr, int fq) const {
;     ...
;         for (int ai = 0; ai < 2; ++ai) { v2u gq[4][2]; v4u tq[4][2];
; #pragma unroll
;             for (int m = 0; m < 4; ++m)
; #pragma unroll
;                 for (int bj = 0; bj < 2; ++bj) { const size_t p = (size_t)(row0 + ai * HALF + m * 16) * DM + col0 + bj * HALF; gq[m][bj] = *(const v2u*)(gt + p); if (MODE == 1) tq[m][bj] = *(const v4u*)(T1 + p); }
;             asm volatile("" ::: "memory");
; #pragma unroll
;             for (int m = 0; m < 4; ++m)
; #pragma unroll
;                 for (int bj = 0; bj < 2; ++bj) { const size_t p = (size_t)(row0 + ai * HALF + m * 16) * DM + col0 + bj * HALF;
;                     const f32x4 a0 = acc[ai][bj][m][0], a1 = acc[ai][bj][m][1]; const v2u g = gq[m][bj]; const float s = 1.f / 255.f;
;                     float v[8] = {a0[0] * ((float)((g.x >> 0) & 0xffu) * s), a0[1] * ((float)((g.x >> 8) & 0xffu) * s), a0[2] * ((float)((g.x >> 16) & 0xffu) * s), a0[3] * ((float)((g.x >> 24) & 0xffu) * s),
;                                   a1[0] * ((float)((g.y >> 0) & 0xffu) * s), a1[1] * ((float)((g.y >> 8) & 0xffu) * s), a1[2] * ((float)((g.y >> 16) & 0xffu) * s), a1[3] * ((float)((g.y >> 24) & 0xffu) * s)};
;                     if (MODE == 1) { const v4u t = tq[m][bj];
;                         v[0] += bflo(t.x); v[1] += bfhi(t.x); v[2] += bflo(t.y); v[3] += bfhi(t.y); v[4] += bflo(t.z); v[5] += bfhi(t.z); v[6] += bflo(t.w); v[7] += bfhi(t.w); }
;                     v4u w; w.x = pkbf(v[0], v[1]); w.y = pkbf(v[2], v[3]); w.z = pkbf(v[4], v[5]); w.w = pkbf(v[6], v[7]);
;                     *(v4u*)(T1 + p) = w; } }
.LBB0_1681:
	v_lshl_add_u32 v146, s30, 8, v154
	v_lshl_or_b32 v144, s50, 8, v156
	v_readlane_b32 s0, v250, 4
	v_ashrrev_i32_e32 v145, 31, v144
	v_readlane_b32 s1, v250, 5
	v_ashrrev_i32_e32 v147, 31, v146
	v_lshlrev_b64 v[150:151], 11, v[146:147]
	v_lshl_add_u64 v[148:149], s[0:1], 0, v[144:145]
	v_or_b32_e32 v152, 16, v146
	v_lshl_add_u64 v[150:151], v[148:149], 0, v[150:151]
	v_ashrrev_i32_e32 v153, 31, v152
	global_load_dwordx2 v[160:161], v[150:151], off
	global_load_dwordx2 v[162:163], v[150:151], off offset:128
	v_lshlrev_b64 v[150:151], 11, v[152:153]
	v_lshl_add_u64 v[164:165], v[148:149], 0, v[150:151]
	global_load_dwordx2 v[166:167], v[164:165], off
	v_or_b32_e32 v168, 32, v146
	global_load_dwordx2 v[164:165], v[164:165], off offset:128
	v_or_b32_e32 v150, 48, v146
	v_ashrrev_i32_e32 v169, 31, v168
	v_ashrrev_i32_e32 v151, 31, v150
	v_lshlrev_b64 v[172:173], 11, v[168:169]
	v_lshlrev_b64 v[174:175], 11, v[150:151]
	v_lshlrev_b64 v[176:177], 12, v[152:153]
	v_lshl_add_u64 v[152:153], v[148:149], 0, v[172:173]
	v_lshl_add_u64 v[172:173], v[148:149], 0, v[174:175]
	global_load_dwordx2 v[174:175], v[152:153], off
	global_load_dwordx2 v[178:179], v[152:153], off offset:128
	global_load_dwordx2 v[180:181], v[172:173], off
	s_nop 0
	global_load_dwordx2 v[152:153], v[172:173], off offset:128
	v_lshlrev_b64 v[170:171], 12, v[146:147]
	v_lshlrev_b64 v[144:145], 1, v[144:145]
	v_lshl_add_u64 v[170:171], s[6:7], 0, v[170:171]
	v_lshl_add_u64 v[170:171], v[170:171], 0, v[144:145]
	s_andn2_b64 vcc, exec, s[10:11]
	s_mov_b64 s[0:1], -1
	s_waitcnt vmcnt(0)
	v_cvt_f32_ubyte1_e32 v173, v160
	v_cvt_f32_ubyte0_e32 v172, v160
	v_cvt_f32_ubyte3_e32 v183, v160
	v_cvt_f32_ubyte2_e32 v182, v160
	v_cvt_f32_ubyte1_e32 v185, v161
	v_cvt_f32_ubyte0_e32 v184, v161
	v_cvt_f32_ubyte3_e32 v187, v161
	v_cvt_f32_ubyte2_e32 v186, v161
	v_cvt_f32_ubyte1_e32 v161, v162
	v_cvt_f32_ubyte0_e32 v160, v162
	v_cvt_f32_ubyte3_e32 v189, v162
	v_cvt_f32_ubyte2_e32 v188, v162
	v_cvt_f32_ubyte1_e32 v191, v163
	v_cvt_f32_ubyte0_e32 v190, v163
	v_cvt_f32_ubyte3_e32 v193, v163
	v_cvt_f32_ubyte2_e32 v192, v163
	v_mul_f32_e32 v162, s16, v172
	v_mul_f32_e32 v163, s16, v173
	v_mul_f32_e32 v172, s16, v182
	v_mul_f32_e32 v173, s16, v183
	v_mul_f32_e32 v182, s16, v184
	v_mul_f32_e32 v183, s16, v185
	v_mul_f32_e32 v184, s16, v186
	v_mul_f32_e32 v185, s16, v187
	v_mul_f32_e32 v160, s16, v160
	v_mul_f32_e32 v161, s16, v161
	v_mul_f32_e32 v186, s16, v188
	v_mul_f32_e32 v187, s16, v189
	v_mul_f32_e32 v188, s16, v190
	v_mul_f32_e32 v189, s16, v191
	v_mul_f32_e32 v190, s16, v192
	v_mul_f32_e32 v191, s16, v193
	v_cvt_f32_ubyte1_e32 v197, v167
	v_cvt_f32_ubyte0_e32 v196, v167
	v_mul_f32_e32 v124, v124, v162
	v_mul_f32_e32 v125, v125, v163
	v_mul_f32_e32 v126, v126, v172
	v_mul_f32_e32 v127, v127, v173
	v_mul_f32_e32 v120, v120, v182
	v_mul_f32_e32 v121, v121, v183
	v_mul_f32_e32 v122, v122, v184
	v_mul_f32_e32 v123, v123, v185
	v_cvt_f32_ubyte1_e32 v193, v166
	v_cvt_f32_ubyte0_e32 v192, v166
	v_cvt_f32_ubyte3_e32 v195, v166
	v_cvt_f32_ubyte2_e32 v194, v166
	v_cvt_f32_ubyte3_e32 v199, v167
	v_cvt_f32_ubyte2_e32 v198, v167
	v_mul_f32_e32 v112, v112, v160
	v_mul_f32_e32 v113, v113, v161
	v_mul_f32_e32 v114, v114, v186
	v_mul_f32_e32 v115, v115, v187
	v_mul_f32_e32 v160, v104, v188
	v_mul_f32_e32 v161, v105, v189
	v_mul_f32_e32 v162, v106, v190
	v_mul_f32_e32 v163, v107, v191
	v_mul_f32_e32 v182, s16, v196
	v_mul_f32_e32 v183, s16, v197
	v_cvt_pk_bf16_f32 v104, v124, v125
	v_cvt_pk_bf16_f32 v105, v126, v127
	v_cvt_pk_bf16_f32 v106, v120, v121
	v_cvt_pk_bf16_f32 v107, v122, v123
	v_mul_f32_e32 v166, s16, v192
	v_mul_f32_e32 v167, s16, v193
	v_mul_f32_e32 v172, s16, v194
	v_mul_f32_e32 v173, s16, v195
	v_cvt_pk_bf16_f32 v112, v112, v113
	v_cvt_pk_bf16_f32 v113, v114, v115
	v_cvt_pk_bf16_f32 v114, v160, v161
	v_cvt_pk_bf16_f32 v115, v162, v163
	v_mul_f32_e32 v108, v108, v182
	v_mul_f32_e32 v109, v109, v183
	global_store_dwordx4 v[170:171], v[104:107], off
	global_store_dwordx4 v[170:171], v[112:115], off offset:256
	v_mul_f32_e32 v116, v116, v166
	v_mul_f32_e32 v117, v117, v167
	v_mul_f32_e32 v104, s16, v198
	v_mul_f32_e32 v105, s16, v199
	v_mul_f32_e32 v118, v118, v172
	v_mul_f32_e32 v119, v119, v173
	v_mul_f32_e32 v110, v110, v104
	v_mul_f32_e32 v111, v111, v105
	v_cvt_pk_bf16_f32 v106, v108, v109
	v_lshl_add_u64 v[108:109], s[6:7], 0, v[176:177]
	v_cvt_pk_bf16_f32 v104, v116, v117
	v_cvt_pk_bf16_f32 v105, v118, v119
	v_cvt_pk_bf16_f32 v107, v110, v111
	v_lshl_add_u64 v[108:109], v[108:109], 0, v[144:145]
	global_store_dwordx4 v[108:109], v[104:107], off
	s_nop 1
	v_cvt_f32_ubyte1_e32 v105, v164
	v_cvt_f32_ubyte0_e32 v104, v164
	v_mul_f32_e32 v104, s16, v104
	v_mul_f32_e32 v105, s16, v105
	s_nop 0
	v_mul_f32_e32 v100, v100, v104
	v_mul_f32_e32 v101, v101, v105
	v_cvt_f32_ubyte3_e32 v105, v164
	v_cvt_f32_ubyte2_e32 v104, v164
	v_mul_f32_e32 v104, s16, v104
	v_mul_f32_e32 v105, s16, v105
	s_nop 0
	v_mul_f32_e32 v102, v102, v104
	v_mul_f32_e32 v103, v103, v105
	v_cvt_f32_ubyte1_e32 v105, v165
	v_cvt_f32_ubyte0_e32 v104, v165
	v_mul_f32_e32 v104, s16, v104
	v_mul_f32_e32 v105, s16, v105
	s_nop 0
	v_mul_f32_e32 v104, v92, v104
	v_mul_f32_e32 v105, v93, v105
	v_cvt_f32_ubyte3_e32 v93, v165
	v_cvt_f32_ubyte2_e32 v92, v165
	v_mul_f32_e32 v92, s16, v92
	v_mul_f32_e32 v93, s16, v93
	s_nop 0
	v_mul_f32_e32 v106, v94, v92
	v_mul_f32_e32 v107, v95, v93
	v_cvt_pk_bf16_f32 v92, v100, v101
	v_cvt_pk_bf16_f32 v93, v102, v103
	v_cvt_pk_bf16_f32 v94, v104, v105
	v_cvt_pk_bf16_f32 v95, v106, v107
	global_store_dwordx4 v[108:109], v[92:95], off offset:256
	s_nop 1
	v_cvt_f32_ubyte1_e32 v95, v174
	v_cvt_f32_ubyte0_e32 v94, v174
; __device__ __forceinline__ unsigned pkbf(float lo, float hi) { const f32x2_m v = {lo, hi}; const bf16x2_m b = __builtin_convertvector(v, bf16x2_m); return __builtin_bit_cast(unsigned, b); }
;     __device__ __forceinline__ void operator()(const f32x4 (&acc)[2][2][4][2], const Unit& u, int wr, int wc, int fr, int fq) const {
;     ...
;         for (int ai = 0; ai < 2; ++ai) { v2u gq[4][2]; v4u tq[4][2];
; #pragma unroll
;             for (int m = 0; m < 4; ++m)
; #pragma unroll
;                 for (int bj = 0; bj < 2; ++bj) { const size_t p = (size_t)(row0 + ai * HALF + m * 16) * DM + col0 + bj * HALF; gq[m][bj] = *(const v2u*)(gt + p); if (MODE == 1) tq[m][bj] = *(const v4u*)(T1 + p); }
;             asm volatile("" ::: "memory");
; #pragma unroll
;             for (int m = 0; m < 4; ++m)
; #pragma unroll
;                 for (int bj = 0; bj < 2; ++bj) { const size_t p = (size_t)(row0 + ai * HALF + m * 16) * DM + col0 + bj * HALF;
;                     const f32x4 a0 = acc[ai][bj][m][0], a1 = acc[ai][bj][m][1]; const v2u g = gq[m][bj]; const float s = 1.f / 255.f;
;                     float v[8] = {a0[0] * ((float)((g.x >> 0) & 0xffu) * s), a0[1] * ((float)((g.x >> 8) & 0xffu) * s), a0[2] * ((float)((g.x >> 16) & 0xffu) * s), a0[3] * ((float)((g.x >> 24) & 0xffu) * s),
;                                   a1[0] * ((float)((g.y >> 0) & 0xffu) * s), a1[1] * ((float)((g.y >> 8) & 0xffu) * s), a1[2] * ((float)((g.y >> 16) & 0xffu) * s), a1[3] * ((float)((g.y >> 24) & 0xffu) * s)};
;                     if (MODE == 1) { const v4u t = tq[m][bj];
;                         v[0] += bflo(t.x); v[1] += bfhi(t.x); v[2] += bflo(t.y); v[3] += bfhi(t.y); v[4] += bflo(t.z); v[5] += bfhi(t.z); v[6] += bflo(t.w); v[7] += bfhi(t.w); }
;                     v4u w; w.x = pkbf(v[0], v[1]); w.y = pkbf(v[2], v[3]); w.z = pkbf(v[4], v[5]); w.w = pkbf(v[6], v[7]);
;                     *(v4u*)(T1 + p) = w; } }
	v_mul_f32_e32 v94, s16, v94
	v_mul_f32_e32 v95, s16, v95
	v_lshlrev_b64 v[92:93], 12, v[168:169]
	v_mul_f32_e32 v94, v96, v94
	v_mul_f32_e32 v95, v97, v95
	v_cvt_f32_ubyte3_e32 v97, v174
	v_cvt_f32_ubyte2_e32 v96, v174
	v_mul_f32_e32 v96, s16, v96
	v_mul_f32_e32 v97, s16, v97
	v_lshl_add_u64 v[92:93], s[6:7], 0, v[92:93]
	v_mul_f32_e32 v96, v98, v96
	v_mul_f32_e32 v97, v99, v97
	v_cvt_f32_ubyte1_e32 v99, v175
	v_cvt_f32_ubyte0_e32 v98, v175
	v_mul_f32_e32 v98, s16, v98
	v_mul_f32_e32 v99, s16, v99
	v_lshl_add_u64 v[92:93], v[92:93], 0, v[144:145]
	v_mul_f32_e32 v98, v88, v98
	v_mul_f32_e32 v99, v89, v99
	v_cvt_f32_ubyte3_e32 v89, v175
	v_cvt_f32_ubyte2_e32 v88, v175
	v_mul_f32_e32 v88, s16, v88
	v_mul_f32_e32 v89, s16, v89
	s_nop 0
	v_mul_f32_e32 v100, v90, v88
	v_mul_f32_e32 v101, v91, v89
	v_cvt_pk_bf16_f32 v88, v94, v95
	v_cvt_pk_bf16_f32 v89, v96, v97
	v_cvt_pk_bf16_f32 v90, v98, v99
	v_cvt_pk_bf16_f32 v91, v100, v101
	global_store_dwordx4 v[92:93], v[88:91], off
	s_nop 1
	v_cvt_f32_ubyte1_e32 v89, v178
	v_cvt_f32_ubyte0_e32 v88, v178
	v_mul_f32_e32 v88, s16, v88
	v_mul_f32_e32 v89, s16, v89
	s_nop 0
	v_mul_f32_e32 v84, v84, v88
	v_mul_f32_e32 v85, v85, v89
	v_cvt_f32_ubyte3_e32 v89, v178
	v_cvt_f32_ubyte2_e32 v88, v178
	v_mul_f32_e32 v88, s16, v88
	v_mul_f32_e32 v89, s16, v89
	s_nop 0
	v_mul_f32_e32 v86, v86, v88
	v_mul_f32_e32 v87, v87, v89
	v_cvt_f32_ubyte1_e32 v89, v179
	v_cvt_f32_ubyte0_e32 v88, v179
	v_mul_f32_e32 v88, s16, v88
	v_mul_f32_e32 v89, s16, v89
	s_nop 0
	v_mul_f32_e32 v88, v76, v88
	v_mul_f32_e32 v89, v77, v89
	v_cvt_f32_ubyte3_e32 v77, v179
	v_cvt_f32_ubyte2_e32 v76, v179
	v_mul_f32_e32 v76, s16, v76
	v_mul_f32_e32 v77, s16, v77
	s_nop 0
	v_mul_f32_e32 v90, v78, v76
	v_mul_f32_e32 v91, v79, v77
	v_cvt_pk_bf16_f32 v76, v84, v85
	v_cvt_pk_bf16_f32 v77, v86, v87
	v_cvt_pk_bf16_f32 v78, v88, v89
	v_cvt_pk_bf16_f32 v79, v90, v91
	global_store_dwordx4 v[92:93], v[76:79], off offset:256
	s_nop 1
	v_cvt_f32_ubyte1_e32 v79, v180
	v_cvt_f32_ubyte0_e32 v78, v180
	v_mul_f32_e32 v78, s16, v78
	v_mul_f32_e32 v79, s16, v79
	v_lshlrev_b64 v[76:77], 12, v[150:151]
	v_mul_f32_e32 v78, v80, v78
	v_mul_f32_e32 v79, v81, v79
	v_cvt_f32_ubyte3_e32 v81, v180
	v_cvt_f32_ubyte2_e32 v80, v180
	v_mul_f32_e32 v80, s16, v80
	v_mul_f32_e32 v81, s16, v81
	v_lshl_add_u64 v[76:77], s[6:7], 0, v[76:77]
	v_mul_f32_e32 v80, v82, v80
	v_mul_f32_e32 v81, v83, v81
	v_cvt_f32_ubyte1_e32 v83, v181
	v_cvt_f32_ubyte0_e32 v82, v181
	v_mul_f32_e32 v82, s16, v82
	v_mul_f32_e32 v83, s16, v83
	v_lshl_add_u64 v[76:77], v[76:77], 0, v[144:145]
	v_mul_f32_e32 v82, v72, v82
	v_mul_f32_e32 v83, v73, v83
	v_cvt_f32_ubyte3_e32 v73, v181
	v_cvt_f32_ubyte2_e32 v72, v181
	v_mul_f32_e32 v72, s16, v72
	v_mul_f32_e32 v73, s16, v73
	s_nop 0
	v_mul_f32_e32 v84, v74, v72
	v_mul_f32_e32 v85, v75, v73
	v_cvt_pk_bf16_f32 v72, v78, v79
	v_cvt_pk_bf16_f32 v73, v80, v81
	v_cvt_pk_bf16_f32 v74, v82, v83
	v_cvt_pk_bf16_f32 v75, v84, v85
	global_store_dwordx4 v[76:77], v[72:75], off
	v_add_u32_e32 v80, 0xa0, v146
	v_ashrrev_i32_e32 v81, 31, v80
	v_cvt_f32_ubyte1_e32 v73, v152
	v_cvt_f32_ubyte0_e32 v72, v152
	v_mul_f32_e32 v72, s16, v72
	v_mul_f32_e32 v73, s16, v73
	v_add_u32_e32 v82, 0xb0, v146
	v_mul_f32_e32 v68, v68, v72
	v_mul_f32_e32 v69, v69, v73
	v_cvt_f32_ubyte3_e32 v73, v152
	v_cvt_f32_ubyte2_e32 v72, v152
	v_mul_f32_e32 v72, s16, v72
	v_mul_f32_e32 v73, s16, v73
	v_ashrrev_i32_e32 v83, 31, v82
	v_mul_f32_e32 v70, v70, v72
	v_mul_f32_e32 v71, v71, v73
	v_cvt_f32_ubyte1_e32 v73, v153
	v_cvt_f32_ubyte0_e32 v72, v153
	v_mul_f32_e32 v72, s16, v72
	v_mul_f32_e32 v73, s16, v73
	s_nop 0
	v_mul_f32_e32 v72, v64, v72
	v_mul_f32_e32 v73, v65, v73
	v_cvt_f32_ubyte3_e32 v65, v153
	v_cvt_f32_ubyte2_e32 v64, v153
	v_mul_f32_e32 v64, s16, v64
	v_mul_f32_e32 v65, s16, v65
	s_nop 0
	v_mul_f32_e32 v74, v66, v64
	v_mul_f32_e32 v75, v67, v65
	v_cvt_pk_bf16_f32 v64, v68, v69
	v_add_u32_e32 v68, 0x80, v146
	v_cvt_pk_bf16_f32 v65, v70, v71
	v_cvt_pk_bf16_f32 v66, v72, v73
	v_cvt_pk_bf16_f32 v67, v74, v75
	v_ashrrev_i32_e32 v69, 31, v68
	global_store_dwordx4 v[76:77], v[64:67], off offset:256
	v_add_u32_e32 v74, 0x90, v146
	v_ashrrev_i32_e32 v75, 31, v74
	v_lshlrev_b64 v[64:65], 11, v[68:69]
	v_lshl_add_u64 v[64:65], v[148:149], 0, v[64:65]
	global_load_dwordx2 v[70:71], v[64:65], off
	global_load_dwordx2 v[72:73], v[64:65], off offset:128
	v_lshlrev_b64 v[64:65], 11, v[74:75]
	v_lshl_add_u64 v[64:65], v[148:149], 0, v[64:65]
	global_load_dwordx2 v[76:77], v[64:65], off
	global_load_dwordx2 v[78:79], v[64:65], off offset:128
	v_lshlrev_b64 v[64:65], 11, v[80:81]
	v_lshl_add_u64 v[64:65], v[148:149], 0, v[64:65]
	v_lshlrev_b64 v[66:67], 11, v[82:83]
	v_lshl_add_u64 v[84:85], v[148:149], 0, v[66:67]
	global_load_dwordx2 v[86:87], v[64:65], off
	global_load_dwordx2 v[88:89], v[64:65], off offset:128
	global_load_dwordx2 v[66:67], v[84:85], off
	s_nop 0
	global_load_dwordx2 v[64:65], v[84:85], off offset:128
	v_lshlrev_b64 v[68:69], 12, v[68:69]
	s_waitcnt vmcnt(7)
	v_cvt_f32_ubyte1_e32 v85, v70
	v_cvt_f32_ubyte0_e32 v84, v70
	v_mul_f32_e32 v84, s16, v84
	v_mul_f32_e32 v85, s16, v85
	s_nop 0
	v_mul_f32_e32 v60, v60, v84
	v_mul_f32_e32 v61, v61, v85
	v_cvt_f32_ubyte3_e32 v85, v70
	v_cvt_f32_ubyte2_e32 v84, v70
	v_mul_f32_e32 v84, s16, v84
	v_mul_f32_e32 v85, s16, v85
	s_nop 0
	v_mul_f32_e32 v62, v62, v84
	v_mul_f32_e32 v63, v63, v85
	v_cvt_f32_ubyte1_e32 v85, v71
	v_cvt_f32_ubyte0_e32 v84, v71
	v_mul_f32_e32 v84, s16, v84
	v_mul_f32_e32 v85, s16, v85
	s_nop 0
	v_mul_f32_e32 v84, v56, v84
	v_mul_f32_e32 v85, v57, v85
	v_cvt_f32_ubyte3_e32 v57, v71
	v_cvt_f32_ubyte2_e32 v56, v71
	v_mul_f32_e32 v56, s16, v56
	v_mul_f32_e32 v57, s16, v57
	s_nop 0
	v_mul_f32_e32 v70, v58, v56
	v_mul_f32_e32 v71, v59, v57
	v_cvt_pk_bf16_f32 v56, v60, v61
	v_lshl_add_u64 v[60:61], s[6:7], 0, v[68:69]
	v_cvt_pk_bf16_f32 v57, v62, v63
	v_cvt_pk_bf16_f32 v58, v84, v85
	v_cvt_pk_bf16_f32 v59, v70, v71
	v_lshl_add_u64 v[60:61], v[60:61], 0, v[144:145]
	global_store_dwordx4 v[60:61], v[56:59], off
	s_waitcnt vmcnt(7)
; __device__ __forceinline__ unsigned pkbf(float lo, float hi) { const f32x2_m v = {lo, hi}; const bf16x2_m b = __builtin_convertvector(v, bf16x2_m); return __builtin_bit_cast(unsigned, b); }
;     __device__ __forceinline__ void operator()(const f32x4 (&acc)[2][2][4][2], const Unit& u, int wr, int wc, int fr, int fq) const {
;     ...
;         for (int ai = 0; ai < 2; ++ai) { v2u gq[4][2]; v4u tq[4][2];
; #pragma unroll
;             for (int m = 0; m < 4; ++m)
; #pragma unroll
;                 for (int bj = 0; bj < 2; ++bj) { const size_t p = (size_t)(row0 + ai * HALF + m * 16) * DM + col0 + bj * HALF; gq[m][bj] = *(const v2u*)(gt + p); if (MODE == 1) tq[m][bj] = *(const v4u*)(T1 + p); }
;             asm volatile("" ::: "memory");
; #pragma unroll
;             for (int m = 0; m < 4; ++m)
; #pragma unroll
;                 for (int bj = 0; bj < 2; ++bj) { const size_t p = (size_t)(row0 + ai * HALF + m * 16) * DM + col0 + bj * HALF;
;                     const f32x4 a0 = acc[ai][bj][m][0], a1 = acc[ai][bj][m][1]; const v2u g = gq[m][bj]; const float s = 1.f / 255.f;
;                     float v[8] = {a0[0] * ((float)((g.x >> 0) & 0xffu) * s), a0[1] * ((float)((g.x >> 8) & 0xffu) * s), a0[2] * ((float)((g.x >> 16) & 0xffu) * s), a0[3] * ((float)((g.x >> 24) & 0xffu) * s),
;                                   a1[0] * ((float)((g.y >> 0) & 0xffu) * s), a1[1] * ((float)((g.y >> 8) & 0xffu) * s), a1[2] * ((float)((g.y >> 16) & 0xffu) * s), a1[3] * ((float)((g.y >> 24) & 0xffu) * s)};
;                     if (MODE == 1) { const v4u t = tq[m][bj];
;                         v[0] += bflo(t.x); v[1] += bfhi(t.x); v[2] += bflo(t.y); v[3] += bfhi(t.y); v[4] += bflo(t.z); v[5] += bfhi(t.z); v[6] += bflo(t.w); v[7] += bfhi(t.w); }
;                     v4u w; w.x = pkbf(v[0], v[1]); w.y = pkbf(v[2], v[3]); w.z = pkbf(v[4], v[5]); w.w = pkbf(v[6], v[7]);
;                     *(v4u*)(T1 + p) = w; } }
	s_nop 0
	v_cvt_f32_ubyte1_e32 v57, v72
	v_cvt_f32_ubyte0_e32 v56, v72
	v_mul_f32_e32 v56, s16, v56
	v_mul_f32_e32 v57, s16, v57
	s_nop 0
	v_mul_f32_e32 v52, v52, v56
	v_mul_f32_e32 v53, v53, v57
	v_cvt_f32_ubyte3_e32 v57, v72
	v_cvt_f32_ubyte2_e32 v56, v72
	v_mul_f32_e32 v56, s16, v56
	v_mul_f32_e32 v57, s16, v57
	s_nop 0
	v_mul_f32_e32 v54, v54, v56
	v_mul_f32_e32 v55, v55, v57
	v_cvt_f32_ubyte1_e32 v57, v73
	v_cvt_f32_ubyte0_e32 v56, v73
	v_mul_f32_e32 v56, s16, v56
	v_mul_f32_e32 v57, s16, v57
	s_nop 0
	v_mul_f32_e32 v56, v44, v56
	v_mul_f32_e32 v57, v45, v57
	v_cvt_f32_ubyte3_e32 v45, v73
	v_cvt_f32_ubyte2_e32 v44, v73
	v_mul_f32_e32 v44, s16, v44
	v_mul_f32_e32 v45, s16, v45
	s_nop 0
	v_mul_f32_e32 v58, v46, v44
	v_mul_f32_e32 v59, v47, v45
	v_cvt_pk_bf16_f32 v44, v52, v53
	v_cvt_pk_bf16_f32 v45, v54, v55
	v_cvt_pk_bf16_f32 v46, v56, v57
	v_cvt_pk_bf16_f32 v47, v58, v59
	global_store_dwordx4 v[60:61], v[44:47], off offset:256
	s_waitcnt vmcnt(7)
	s_nop 0
	v_cvt_f32_ubyte1_e32 v47, v76
	v_cvt_f32_ubyte0_e32 v46, v76
	v_mul_f32_e32 v46, s16, v46
	v_mul_f32_e32 v47, s16, v47
	v_lshlrev_b64 v[44:45], 12, v[74:75]
	v_mul_f32_e32 v46, v48, v46
	v_mul_f32_e32 v47, v49, v47
	v_cvt_f32_ubyte3_e32 v49, v76
	v_cvt_f32_ubyte2_e32 v48, v76
	v_mul_f32_e32 v48, s16, v48
	v_mul_f32_e32 v49, s16, v49
	v_lshl_add_u64 v[44:45], s[6:7], 0, v[44:45]
	v_mul_f32_e32 v48, v50, v48
	v_mul_f32_e32 v49, v51, v49
	v_cvt_f32_ubyte1_e32 v51, v77
	v_cvt_f32_ubyte0_e32 v50, v77
	v_mul_f32_e32 v50, s16, v50
	v_mul_f32_e32 v51, s16, v51
	v_lshl_add_u64 v[44:45], v[44:45], 0, v[144:145]
	v_mul_f32_e32 v50, v40, v50
	v_mul_f32_e32 v51, v41, v51
	v_cvt_f32_ubyte3_e32 v41, v77
	v_cvt_f32_ubyte2_e32 v40, v77
	v_mul_f32_e32 v40, s16, v40
	v_mul_f32_e32 v41, s16, v41
	s_nop 0
	v_mul_f32_e32 v52, v42, v40
	v_mul_f32_e32 v53, v43, v41
	v_cvt_pk_bf16_f32 v40, v46, v47
	v_cvt_pk_bf16_f32 v41, v48, v49
	v_cvt_pk_bf16_f32 v42, v50, v51
	v_cvt_pk_bf16_f32 v43, v52, v53
	global_store_dwordx4 v[44:45], v[40:43], off
	s_waitcnt vmcnt(7)
	s_nop 0
	v_cvt_f32_ubyte1_e32 v41, v78
	v_cvt_f32_ubyte0_e32 v40, v78
	v_mul_f32_e32 v40, s16, v40
	v_mul_f32_e32 v41, s16, v41
	s_nop 0
	v_mul_f32_e32 v36, v36, v40
	v_mul_f32_e32 v37, v37, v41
	v_cvt_f32_ubyte3_e32 v41, v78
	v_cvt_f32_ubyte2_e32 v40, v78
	v_mul_f32_e32 v40, s16, v40
	v_mul_f32_e32 v41, s16, v41
	s_nop 0
	v_mul_f32_e32 v38, v38, v40
	v_mul_f32_e32 v39, v39, v41
	v_cvt_f32_ubyte1_e32 v41, v79
	v_cvt_f32_ubyte0_e32 v40, v79
	v_mul_f32_e32 v40, s16, v40
	v_mul_f32_e32 v41, s16, v41
	s_nop 0
	v_mul_f32_e32 v40, v28, v40
	v_mul_f32_e32 v41, v29, v41
	v_cvt_f32_ubyte3_e32 v29, v79
	v_cvt_f32_ubyte2_e32 v28, v79
	v_mul_f32_e32 v28, s16, v28
	v_mul_f32_e32 v29, s16, v29
	s_nop 0
	v_mul_f32_e32 v42, v30, v28
	v_mul_f32_e32 v43, v31, v29
	v_cvt_pk_bf16_f32 v28, v36, v37
	v_cvt_pk_bf16_f32 v29, v38, v39
	v_cvt_pk_bf16_f32 v30, v40, v41
	v_cvt_pk_bf16_f32 v31, v42, v43
	global_store_dwordx4 v[44:45], v[28:31], off offset:256
	s_waitcnt vmcnt(7)
	s_nop 0
	v_cvt_f32_ubyte1_e32 v31, v86
	v_cvt_f32_ubyte0_e32 v30, v86
	v_mul_f32_e32 v30, s16, v30
	v_mul_f32_e32 v31, s16, v31
	v_lshlrev_b64 v[28:29], 12, v[80:81]
	v_mul_f32_e32 v30, v32, v30
	v_mul_f32_e32 v31, v33, v31
	v_cvt_f32_ubyte3_e32 v33, v86
	v_cvt_f32_ubyte2_e32 v32, v86
	v_mul_f32_e32 v32, s16, v32
	v_mul_f32_e32 v33, s16, v33
	v_lshl_add_u64 v[28:29], s[6:7], 0, v[28:29]
	v_mul_f32_e32 v32, v34, v32
	v_mul_f32_e32 v33, v35, v33
	v_cvt_f32_ubyte1_e32 v35, v87
	v_cvt_f32_ubyte0_e32 v34, v87
	v_mul_f32_e32 v34, s16, v34
	v_mul_f32_e32 v35, s16, v35
	v_lshl_add_u64 v[28:29], v[28:29], 0, v[144:145]
	v_mul_f32_e32 v34, v24, v34
	v_mul_f32_e32 v35, v25, v35
	v_cvt_f32_ubyte3_e32 v25, v87
	v_cvt_f32_ubyte2_e32 v24, v87
	v_mul_f32_e32 v24, s16, v24
	v_mul_f32_e32 v25, s16, v25
	s_nop 0
	v_mul_f32_e32 v36, v26, v24
	v_mul_f32_e32 v37, v27, v25
	v_cvt_pk_bf16_f32 v24, v30, v31
	v_cvt_pk_bf16_f32 v25, v32, v33
	v_cvt_pk_bf16_f32 v26, v34, v35
	v_cvt_pk_bf16_f32 v27, v36, v37
	global_store_dwordx4 v[28:29], v[24:27], off
	s_waitcnt vmcnt(7)
	s_nop 0
	v_cvt_f32_ubyte1_e32 v25, v88
	v_cvt_f32_ubyte0_e32 v24, v88
	v_mul_f32_e32 v24, s16, v24
	v_mul_f32_e32 v25, s16, v25
	s_nop 0
	v_mul_f32_e32 v20, v20, v24
	v_mul_f32_e32 v21, v21, v25
	v_cvt_f32_ubyte3_e32 v25, v88
	v_cvt_f32_ubyte2_e32 v24, v88
	v_mul_f32_e32 v24, s16, v24
	v_mul_f32_e32 v25, s16, v25
	s_nop 0
	v_mul_f32_e32 v22, v22, v24
	v_mul_f32_e32 v23, v23, v25
	v_cvt_f32_ubyte1_e32 v25, v89
	v_cvt_f32_ubyte0_e32 v24, v89
	v_mul_f32_e32 v24, s16, v24
	v_mul_f32_e32 v25, s16, v25
	s_nop 0
	v_mul_f32_e32 v24, v12, v24
	v_mul_f32_e32 v25, v13, v25
	v_cvt_f32_ubyte3_e32 v13, v89
	v_cvt_f32_ubyte2_e32 v12, v89
	v_mul_f32_e32 v12, s16, v12
	v_mul_f32_e32 v13, s16, v13
	s_nop 0
	v_mul_f32_e32 v26, v14, v12
	v_mul_f32_e32 v27, v15, v13
	v_cvt_pk_bf16_f32 v12, v20, v21
	v_cvt_pk_bf16_f32 v13, v22, v23
	v_cvt_pk_bf16_f32 v14, v24, v25
	v_cvt_pk_bf16_f32 v15, v26, v27
	global_store_dwordx4 v[28:29], v[12:15], off offset:256
	s_waitcnt vmcnt(7)
	s_nop 0
	v_cvt_f32_ubyte1_e32 v15, v66
	v_cvt_f32_ubyte0_e32 v14, v66
	v_mul_f32_e32 v14, s16, v14
	v_mul_f32_e32 v15, s16, v15
	v_lshlrev_b64 v[12:13], 12, v[82:83]
	v_mul_f32_e32 v14, v16, v14
	v_mul_f32_e32 v15, v17, v15
	v_cvt_f32_ubyte3_e32 v17, v66
	v_cvt_f32_ubyte2_e32 v16, v66
	v_mul_f32_e32 v16, s16, v16
	v_mul_f32_e32 v17, s16, v17
	v_lshl_add_u64 v[12:13], s[6:7], 0, v[12:13]
	v_mul_f32_e32 v16, v18, v16
	v_mul_f32_e32 v17, v19, v17
	v_cvt_f32_ubyte1_e32 v19, v67
	v_cvt_f32_ubyte0_e32 v18, v67
	v_mul_f32_e32 v18, s16, v18
	v_mul_f32_e32 v19, s16, v19
	v_lshl_add_u64 v[12:13], v[12:13], 0, v[144:145]
	v_mul_f32_e32 v18, v8, v18
	v_mul_f32_e32 v19, v9, v19
	v_cvt_f32_ubyte3_e32 v9, v67
	v_cvt_f32_ubyte2_e32 v8, v67
	v_mul_f32_e32 v8, s16, v8
	v_mul_f32_e32 v9, s16, v9
	s_nop 0
	v_mul_f32_e32 v20, v10, v8
	v_mul_f32_e32 v21, v11, v9
	v_cvt_pk_bf16_f32 v8, v14, v15
	v_cvt_pk_bf16_f32 v9, v16, v17
	v_cvt_pk_bf16_f32 v10, v18, v19
	v_cvt_pk_bf16_f32 v11, v20, v21
	global_store_dwordx4 v[12:13], v[8:11], off
	s_waitcnt vmcnt(7)
	s_nop 0
	v_cvt_f32_ubyte1_e32 v9, v64
	v_cvt_f32_ubyte0_e32 v8, v64
	v_mul_f32_e32 v8, s16, v8
	v_mul_f32_e32 v9, s16, v9
	s_nop 0
	v_mul_f32_e32 v4, v4, v8
	v_mul_f32_e32 v5, v5, v9
	v_cvt_f32_ubyte3_e32 v9, v64
	v_cvt_f32_ubyte2_e32 v8, v64
	v_mul_f32_e32 v8, s16, v8
	v_mul_f32_e32 v9, s16, v9
	s_nop 0
	v_mul_f32_e32 v6, v6, v8
	v_mul_f32_e32 v7, v7, v9
	v_cvt_f32_ubyte1_e32 v9, v65
	v_cvt_f32_ubyte0_e32 v8, v65
	v_mul_f32_e32 v8, s16, v8
	v_mul_f32_e32 v9, s16, v9
	s_nop 0
	v_mul_f32_e32 v8, v0, v8
	v_mul_f32_e32 v9, v1, v9
	v_cvt_f32_ubyte3_e32 v1, v65
	v_cvt_f32_ubyte2_e32 v0, v65
	v_mul_f32_e32 v0, s16, v0
	v_mul_f32_e32 v1, s16, v1
	s_nop 0
	v_mul_f32_e32 v10, v2, v0
	v_mul_f32_e32 v11, v3, v1
	v_cvt_pk_bf16_f32 v0, v4, v5
	v_cvt_pk_bf16_f32 v1, v6, v7
	v_cvt_pk_bf16_f32 v2, v8, v9
	v_cvt_pk_bf16_f32 v3, v10, v11
	global_store_dwordx4 v[12:13], v[0:3], off offset:256
	s_cbranch_vccnz .LBB0_1670
; #define PG8_BAR __builtin_amdgcn_s_barrier()
; template <class Epi, class Sched, bool ALIGN_EPI = false, bool SP2 = false>
; __device__ __forceinline__ void gemm_phase(PG8_LAS unsigned char* lds, const Gemm g, const Sched& S, const Epi& E) {
;     ...
;         if (!has_next) break;
; #pragma unroll
;         for (int a = 0; a < 2; ++a)
; #pragma unroll
;             for (int b = 0; b < 2; ++b)
; #pragma unroll
;                 for (int m = 0; m < 4; ++m)
; #pragma unroll
;                     for (int n = 0; n < 2; ++n) acc[a][b][m][n] = (f32x4){0.f, 0.f, 0.f, 0.f};
;         cur = nxt; cA = nA; cB = nB; ++ui;
;         if constexpr (ALIGN_EPI) { if (wr == 1) PG8_BAR; }
;     }
	s_andn2_b64 vcc, exec, s[4:5]
	s_cbranch_vccnz .LBB0_1669
	s_barrier
	s_branch .LBB0_1669

; __device__ __forceinline__ unsigned pkbf(float lo, float hi) { const f32x2_m v = {lo, hi}; const bf16x2_m b = __builtin_convertvector(v, bf16x2_m); return __builtin_bit_cast(unsigned, b); }
;     __device__ __forceinline__ void operator()(const f32x4 (&acc)[2][2][4][2], const Unit& u, int wr, int wc, int fr, int fq) const {
;     ...
;         for (int ai = 0; ai < 2; ++ai) { v2u gq[4][2]; v4u tq[4][2];
; #pragma unroll
;             for (int m = 0; m < 4; ++m)
; #pragma unroll
;                 for (int bj = 0; bj < 2; ++bj) { const size_t p = (size_t)(row0 + ai * HALF + m * 16) * DM + col0 + bj * HALF; gq[m][bj] = *(const v2u*)(gt + p); if (MODE == 1) tq[m][bj] = *(const v4u*)(T1 + p); }
;             asm volatile("" ::: "memory");
; #pragma unroll
;             for (int m = 0; m < 4; ++m)
; #pragma unroll
;                 for (int bj = 0; bj < 2; ++bj) { const size_t p = (size_t)(row0 + ai * HALF + m * 16) * DM + col0 + bj * HALF;
;                     const f32x4 a0 = acc[ai][bj][m][0], a1 = acc[ai][bj][m][1]; const v2u g = gq[m][bj]; const float s = 1.f / 255.f;
;                     float v[8] = {a0[0] * ((float)((g.x >> 0) & 0xffu) * s), a0[1] * ((float)((g.x >> 8) & 0xffu) * s), a0[2] * ((float)((g.x >> 16) & 0xffu) * s), a0[3] * ((float)((g.x >> 24) & 0xffu) * s),
;                                   a1[0] * ((float)((g.y >> 0) & 0xffu) * s), a1[1] * ((float)((g.y >> 8) & 0xffu) * s), a1[2] * ((float)((g.y >> 16) & 0xffu) * s), a1[3] * ((float)((g.y >> 24) & 0xffu) * s)};
;                     if (MODE == 1) { const v4u t = tq[m][bj];
;                         v[0] += bflo(t.x); v[1] += bfhi(t.x); v[2] += bflo(t.y); v[3] += bfhi(t.y); v[4] += bflo(t.z); v[5] += bfhi(t.z); v[6] += bflo(t.w); v[7] += bfhi(t.w); }
;                     v4u w; w.x = pkbf(v[0], v[1]); w.y = pkbf(v[2], v[3]); w.z = pkbf(v[4], v[5]); w.w = pkbf(v[6], v[7]);
;                     *(v4u*)(T1 + p) = w; } }
.LBB0_1705:
	v_lshl_add_u32 v160, s36, 8, v172
	v_lshl_or_b32 v158, s52, 8, v174
	v_ashrrev_i32_e32 v161, 31, v160
	v_ashrrev_i32_e32 v159, 31, v158
	v_lshlrev_b64 v[128:129], 11, v[160:161]
	v_lshl_add_u64 v[128:129], v[128:129], 0, v[158:159]
	v_lshl_add_u64 v[130:131], s[12:13], 0, v[128:129]
	global_load_dwordx2 v[198:199], v[130:131], off
	v_lshl_add_u64 v[130:131], v[128:129], 1, s[6:7]
	global_load_dwordx4 v[178:181], v[130:131], off
	v_or_b32_e32 v128, 0x80, v128
	v_lshl_add_u64 v[130:131], s[12:13], 0, v[128:129]
	global_load_dwordx2 v[200:201], v[130:131], off
	v_lshl_add_u64 v[128:129], v[128:129], 1, s[6:7]
	global_load_dwordx4 v[182:185], v[128:129], off
	v_or_b32_e32 v202, 16, v160
	v_ashrrev_i32_e32 v203, 31, v202
	v_or_b32_e32 v162, 48, v160
	v_lshlrev_b64 v[128:129], 12, v[160:161]
	v_lshlrev_b64 v[130:131], 11, v[202:203]
	v_ashrrev_i32_e32 v163, 31, v162
	v_lshlrev_b64 v[156:157], 1, v[158:159]
	v_lshl_add_u64 v[128:129], s[6:7], 0, v[128:129]
	v_lshl_add_u64 v[130:131], v[130:131], 0, v[158:159]
	v_lshlrev_b64 v[134:135], 11, v[162:163]
	v_lshl_add_u64 v[204:205], v[128:129], 0, v[156:157]
	v_lshl_add_u64 v[128:129], s[12:13], 0, v[130:131]
	v_lshl_add_u64 v[136:137], v[134:135], 0, v[158:159]
	v_lshl_add_u64 v[134:135], v[130:131], 1, s[6:7]
	global_load_dwordx2 v[206:207], v[128:129], off
	global_load_dwordx4 v[186:189], v[134:135], off
	v_or_b32_e32 v168, 32, v160
	v_ashrrev_i32_e32 v169, 31, v168
	v_lshlrev_b64 v[132:133], 11, v[168:169]
	v_lshl_add_u64 v[132:133], v[132:133], 0, v[158:159]
	v_or_b32_e32 v130, 0x80, v130
	v_lshl_add_u64 v[138:139], s[12:13], 0, v[132:133]
	v_lshl_add_u64 v[164:165], v[132:133], 1, s[6:7]
	v_or_b32_e32 v132, 0x80, v132
	v_lshl_add_u64 v[166:167], s[12:13], 0, v[136:137]
	v_lshl_add_u64 v[128:129], v[136:137], 1, s[6:7]
	v_or_b32_e32 v136, 0x80, v136
	v_lshl_add_u64 v[170:171], s[12:13], 0, v[130:131]
	v_lshl_add_u64 v[130:131], v[130:131], 1, s[6:7]
	global_load_dwordx2 v[208:209], v[138:139], off
	global_load_dwordx4 v[190:193], v[164:165], off
	v_lshl_add_u64 v[138:139], s[12:13], 0, v[132:133]
	v_lshl_add_u64 v[164:165], v[132:133], 1, s[6:7]
	global_load_dwordx2 v[166:167], v[166:167], off
	s_nop 0
	global_load_dwordx4 v[132:135], v[128:129], off
	v_lshl_add_u64 v[128:129], s[12:13], 0, v[136:137]
	v_lshl_add_u64 v[210:211], v[136:137], 1, s[6:7]
	global_load_dwordx2 v[212:213], v[170:171], off
	global_load_dwordx4 v[194:197], v[130:131], off
	s_nop 0
	global_load_dwordx2 v[170:171], v[138:139], off
	s_nop 0
	global_load_dwordx4 v[136:139], v[164:165], off
	s_nop 0
	global_load_dwordx2 v[164:165], v[128:129], off
	s_nop 0
	global_load_dwordx4 v[128:131], v[210:211], off
	s_andn2_b64 vcc, exec, s[10:11]
	s_mov_b64 s[0:1], -1
	s_waitcnt vmcnt(0)
	v_cvt_f32_ubyte1_e32 v211, v198
	v_cvt_f32_ubyte0_e32 v210, v198
	v_cvt_f32_ubyte3_e32 v217, v198
	v_cvt_f32_ubyte2_e32 v216, v198
	v_cvt_f32_ubyte1_e32 v219, v199
	v_cvt_f32_ubyte0_e32 v218, v199
	v_cvt_f32_ubyte3_e32 v229, v199
	v_cvt_f32_ubyte2_e32 v228, v199
	v_lshlrev_b32_e32 v214, 16, v178
	v_and_b32_e32 v215, 0xffff0000, v178
	v_lshlrev_b32_e32 v178, 16, v179
	v_and_b32_e32 v179, 0xffff0000, v179
	v_lshlrev_b32_e32 v220, 16, v180
	v_and_b32_e32 v221, 0xffff0000, v180
	v_lshlrev_b32_e32 v180, 16, v181
	v_and_b32_e32 v181, 0xffff0000, v181
	v_mul_f32_e32 v198, s18, v210
	v_mul_f32_e32 v199, s18, v211
	v_mul_f32_e32 v210, s18, v216
	v_mul_f32_e32 v211, s18, v217
	v_mul_f32_e32 v216, s18, v218
	v_mul_f32_e32 v217, s18, v219
	v_mul_f32_e32 v218, s18, v228
	v_mul_f32_e32 v219, s18, v229
	v_fma_f32 v124, v124, v198, v214
	v_fma_f32 v125, v125, v199, v215
	v_fma_f32 v126, v126, v210, v178
	v_fma_f32 v127, v127, v211, v179
	v_fma_f32 v178, v120, v216, v220
	v_fma_f32 v179, v121, v217, v221
	v_fma_f32 v180, v122, v218, v180
	v_fma_f32 v181, v123, v219, v181
	v_cvt_f32_ubyte1_e32 v229, v200
	v_cvt_f32_ubyte0_e32 v228, v200
	v_cvt_pk_bf16_f32 v120, v124, v125
	v_cvt_pk_bf16_f32 v121, v126, v127
	v_cvt_pk_bf16_f32 v122, v178, v179
	v_cvt_pk_bf16_f32 v123, v180, v181
	global_store_dwordx4 v[204:205], v[120:123], off
	s_nop 1
	v_mul_f32_e32 v120, s18, v228
	v_mul_f32_e32 v121, s18, v229
	v_lshlrev_b32_e32 v122, 16, v182
	v_and_b32_e32 v123, 0xffff0000, v182
	v_fma_f32 v116, v116, v120, v122
	v_fma_f32 v117, v117, v121, v123
	v_cvt_f32_ubyte3_e32 v121, v200
	v_cvt_f32_ubyte2_e32 v120, v200
	v_mul_f32_e32 v120, s18, v120
	v_mul_f32_e32 v121, s18, v121
	v_lshlrev_b32_e32 v122, 16, v183
	v_and_b32_e32 v123, 0xffff0000, v183
	v_fma_f32 v118, v118, v120, v122
	v_fma_f32 v119, v119, v121, v123
	v_cvt_f32_ubyte1_e32 v121, v201
	v_cvt_f32_ubyte0_e32 v120, v201
	v_mul_f32_e32 v120, s18, v120
	v_mul_f32_e32 v121, s18, v121
	v_lshlrev_b32_e32 v122, 16, v184
	v_and_b32_e32 v123, 0xffff0000, v184
	v_fma_f32 v120, v112, v120, v122
	v_fma_f32 v121, v113, v121, v123
	v_cvt_f32_ubyte3_e32 v113, v201
	v_cvt_f32_ubyte2_e32 v112, v201
	v_mul_f32_e32 v112, s18, v112
	v_mul_f32_e32 v113, s18, v113
	v_lshlrev_b32_e32 v122, 16, v185
	v_and_b32_e32 v123, 0xffff0000, v185
	v_fma_f32 v122, v114, v112, v122
	v_fma_f32 v123, v115, v113, v123
	v_cvt_pk_bf16_f32 v112, v116, v117
	v_cvt_pk_bf16_f32 v113, v118, v119
	v_cvt_pk_bf16_f32 v114, v120, v121
	v_cvt_pk_bf16_f32 v115, v122, v123
	global_store_dwordx4 v[204:205], v[112:115], off offset:256
	v_lshlrev_b32_e32 v116, 16, v186
	v_and_b32_e32 v117, 0xffff0000, v186
	v_cvt_f32_ubyte1_e32 v115, v206
	v_cvt_f32_ubyte0_e32 v114, v206
	v_mul_f32_e32 v114, s18, v114
	v_mul_f32_e32 v115, s18, v115
	v_lshlrev_b64 v[112:113], 12, v[202:203]
	v_fma_f32 v108, v108, v114, v116
	v_fma_f32 v109, v109, v115, v117
	v_cvt_f32_ubyte3_e32 v115, v206
; __device__ __forceinline__ unsigned pkbf(float lo, float hi) { const f32x2_m v = {lo, hi}; const bf16x2_m b = __builtin_convertvector(v, bf16x2_m); return __builtin_bit_cast(unsigned, b); }
;     __device__ __forceinline__ void operator()(const f32x4 (&acc)[2][2][4][2], const Unit& u, int wr, int wc, int fr, int fq) const {
;     ...
;                 for (int bj = 0; bj < 2; ++bj) { const size_t p = (size_t)(row0 + ai * HALF + m * 16) * DM + col0 + bj * HALF;
;                     const f32x4 a0 = acc[ai][bj][m][0], a1 = acc[ai][bj][m][1]; const v2u g = gq[m][bj]; const float s = 1.f / 255.f;
;                     float v[8] = {a0[0] * ((float)((g.x >> 0) & 0xffu) * s), a0[1] * ((float)((g.x >> 8) & 0xffu) * s), a0[2] * ((float)((g.x >> 16) & 0xffu) * s), a0[3] * ((float)((g.x >> 24) & 0xffu) * s),
;                                   a1[0] * ((float)((g.y >> 0) & 0xffu) * s), a1[1] * ((float)((g.y >> 8) & 0xffu) * s), a1[2] * ((float)((g.y >> 16) & 0xffu) * s), a1[3] * ((float)((g.y >> 24) & 0xffu) * s)};
;                     if (MODE == 1) { const v4u t = tq[m][bj];
;                         v[0] += bflo(t.x); v[1] += bfhi(t.x); v[2] += bflo(t.y); v[3] += bfhi(t.y); v[4] += bflo(t.z); v[5] += bfhi(t.z); v[6] += bflo(t.w); v[7] += bfhi(t.w); }
;                     v4u w; w.x = pkbf(v[0], v[1]); w.y = pkbf(v[2], v[3]); w.z = pkbf(v[4], v[5]); w.w = pkbf(v[6], v[7]);
;                     *(v4u*)(T1 + p) = w; } }
	v_cvt_f32_ubyte2_e32 v114, v206
	v_mul_f32_e32 v114, s18, v114
	v_mul_f32_e32 v115, s18, v115
	v_lshlrev_b32_e32 v116, 16, v187
	v_and_b32_e32 v117, 0xffff0000, v187
	v_fma_f32 v110, v110, v114, v116
	v_fma_f32 v111, v111, v115, v117
	v_cvt_f32_ubyte1_e32 v115, v207
	v_cvt_f32_ubyte0_e32 v114, v207
	v_mul_f32_e32 v114, s18, v114
	v_mul_f32_e32 v115, s18, v115
	v_lshlrev_b32_e32 v116, 16, v188
	v_and_b32_e32 v117, 0xffff0000, v188
	v_fma_f32 v114, v104, v114, v116
	v_fma_f32 v115, v105, v115, v117
	v_cvt_f32_ubyte3_e32 v105, v207
	v_cvt_f32_ubyte2_e32 v104, v207
	v_mul_f32_e32 v104, s18, v104
	v_mul_f32_e32 v105, s18, v105
	v_lshlrev_b32_e32 v116, 16, v189
	v_and_b32_e32 v117, 0xffff0000, v189
	v_fma_f32 v116, v106, v104, v116
	v_fma_f32 v117, v107, v105, v117
	v_cvt_pk_bf16_f32 v104, v108, v109
	v_lshl_add_u64 v[108:109], s[6:7], 0, v[112:113]
	v_cvt_pk_bf16_f32 v105, v110, v111
	v_cvt_pk_bf16_f32 v106, v114, v115
	v_cvt_pk_bf16_f32 v107, v116, v117
	v_lshl_add_u64 v[108:109], v[108:109], 0, v[156:157]
	global_store_dwordx4 v[108:109], v[104:107], off
	v_add_u32_e32 v114, 0x90, v160
	v_ashrrev_i32_e32 v115, 31, v114
	v_cvt_f32_ubyte1_e32 v105, v212
	v_cvt_f32_ubyte0_e32 v104, v212
	v_mul_f32_e32 v104, s18, v104
	v_mul_f32_e32 v105, s18, v105
	v_lshlrev_b32_e32 v106, 16, v194
	v_and_b32_e32 v107, 0xffff0000, v194
	v_fma_f32 v100, v100, v104, v106
	v_fma_f32 v101, v101, v105, v107
	v_cvt_f32_ubyte3_e32 v105, v212
	v_cvt_f32_ubyte2_e32 v104, v212
	v_mul_f32_e32 v104, s18, v104
	v_mul_f32_e32 v105, s18, v105
	v_lshlrev_b32_e32 v106, 16, v195
	v_and_b32_e32 v107, 0xffff0000, v195
	v_fma_f32 v102, v102, v104, v106
	v_fma_f32 v103, v103, v105, v107
	v_cvt_f32_ubyte1_e32 v105, v213
	v_cvt_f32_ubyte0_e32 v104, v213
	v_mul_f32_e32 v104, s18, v104
	v_mul_f32_e32 v105, s18, v105
	v_lshlrev_b32_e32 v106, 16, v196
	v_and_b32_e32 v107, 0xffff0000, v196
	v_fma_f32 v104, v96, v104, v106
	v_fma_f32 v105, v97, v105, v107
	v_cvt_f32_ubyte3_e32 v97, v213
	v_cvt_f32_ubyte2_e32 v96, v213
	v_mul_f32_e32 v96, s18, v96
	v_mul_f32_e32 v97, s18, v97
	v_lshlrev_b32_e32 v106, 16, v197
	v_and_b32_e32 v107, 0xffff0000, v197
	v_fma_f32 v106, v98, v96, v106
	v_fma_f32 v107, v99, v97, v107
	v_cvt_pk_bf16_f32 v96, v100, v101
	v_cvt_pk_bf16_f32 v97, v102, v103
	v_cvt_pk_bf16_f32 v98, v104, v105
	v_cvt_pk_bf16_f32 v99, v106, v107
	global_store_dwordx4 v[108:109], v[96:99], off offset:256
	v_lshlrev_b32_e32 v100, 16, v190
	v_and_b32_e32 v101, 0xffff0000, v190
	v_cvt_f32_ubyte1_e32 v99, v208
	v_cvt_f32_ubyte0_e32 v98, v208
	v_mul_f32_e32 v98, s18, v98
	v_mul_f32_e32 v99, s18, v99
	v_lshlrev_b64 v[96:97], 12, v[168:169]
	v_fma_f32 v92, v92, v98, v100
	v_fma_f32 v93, v93, v99, v101
	v_cvt_f32_ubyte3_e32 v99, v208
	v_cvt_f32_ubyte2_e32 v98, v208
	v_mul_f32_e32 v98, s18, v98
	v_mul_f32_e32 v99, s18, v99
	v_lshlrev_b32_e32 v100, 16, v191
	v_and_b32_e32 v101, 0xffff0000, v191
	v_fma_f32 v94, v94, v98, v100
	v_fma_f32 v95, v95, v99, v101
	v_cvt_f32_ubyte1_e32 v99, v209
	v_cvt_f32_ubyte0_e32 v98, v209
	v_mul_f32_e32 v98, s18, v98
	v_mul_f32_e32 v99, s18, v99
	v_lshlrev_b32_e32 v100, 16, v192
	v_and_b32_e32 v101, 0xffff0000, v192
	v_fma_f32 v98, v88, v98, v100
	v_fma_f32 v99, v89, v99, v101
	v_cvt_f32_ubyte3_e32 v89, v209
	v_cvt_f32_ubyte2_e32 v88, v209
	v_mul_f32_e32 v88, s18, v88
	v_mul_f32_e32 v89, s18, v89
	v_lshlrev_b32_e32 v100, 16, v193
	v_and_b32_e32 v101, 0xffff0000, v193
	v_fma_f32 v100, v90, v88, v100
	v_fma_f32 v101, v91, v89, v101
	v_cvt_pk_bf16_f32 v88, v92, v93
	v_lshl_add_u64 v[92:93], s[6:7], 0, v[96:97]
	v_cvt_pk_bf16_f32 v89, v94, v95
	v_cvt_pk_bf16_f32 v90, v98, v99
	v_cvt_pk_bf16_f32 v91, v100, v101
	v_lshl_add_u64 v[92:93], v[92:93], 0, v[156:157]
	global_store_dwordx4 v[92:93], v[88:91], off
	v_add_u32_e32 v108, 0x80, v160
	v_ashrrev_i32_e32 v109, 31, v108
	v_cvt_f32_ubyte1_e32 v89, v170
	v_cvt_f32_ubyte0_e32 v88, v170
	v_mul_f32_e32 v88, s18, v88
	v_mul_f32_e32 v89, s18, v89
	v_lshlrev_b32_e32 v90, 16, v136
	v_and_b32_e32 v91, 0xffff0000, v136
	v_fma_f32 v84, v84, v88, v90
	v_fma_f32 v85, v85, v89, v91
	v_cvt_f32_ubyte3_e32 v89, v170
	v_cvt_f32_ubyte2_e32 v88, v170
	v_mul_f32_e32 v88, s18, v88
	v_mul_f32_e32 v89, s18, v89
	v_lshlrev_b32_e32 v90, 16, v137
	v_and_b32_e32 v91, 0xffff0000, v137
	v_fma_f32 v86, v86, v88, v90
	v_fma_f32 v87, v87, v89, v91
	v_cvt_f32_ubyte1_e32 v89, v171
	v_cvt_f32_ubyte0_e32 v88, v171
	v_mul_f32_e32 v88, s18, v88
	v_mul_f32_e32 v89, s18, v89
	v_lshlrev_b32_e32 v90, 16, v138
	v_and_b32_e32 v91, 0xffff0000, v138
	v_fma_f32 v88, v80, v88, v90
	v_fma_f32 v89, v81, v89, v91
	v_cvt_f32_ubyte3_e32 v81, v171
	v_cvt_f32_ubyte2_e32 v80, v171
	v_mul_f32_e32 v80, s18, v80
	v_mul_f32_e32 v81, s18, v81
	v_lshlrev_b32_e32 v90, 16, v139
	v_and_b32_e32 v91, 0xffff0000, v139
	v_fma_f32 v90, v82, v80, v90
	v_fma_f32 v91, v83, v81, v91
	v_cvt_pk_bf16_f32 v80, v84, v85
	v_cvt_pk_bf16_f32 v81, v86, v87
	v_cvt_pk_bf16_f32 v82, v88, v89
	v_cvt_pk_bf16_f32 v83, v90, v91
	global_store_dwordx4 v[92:93], v[80:83], off offset:256
	v_lshlrev_b32_e32 v84, 16, v132
	v_and_b32_e32 v85, 0xffff0000, v132
	v_cvt_f32_ubyte1_e32 v83, v166
	v_cvt_f32_ubyte0_e32 v82, v166
	v_mul_f32_e32 v82, s18, v82
	v_mul_f32_e32 v83, s18, v83
	v_lshlrev_b64 v[80:81], 12, v[162:163]
	v_fma_f32 v76, v76, v82, v84
	v_fma_f32 v77, v77, v83, v85
	v_cvt_f32_ubyte3_e32 v83, v166
	v_cvt_f32_ubyte2_e32 v82, v166
	v_mul_f32_e32 v82, s18, v82
	v_mul_f32_e32 v83, s18, v83
	v_lshlrev_b32_e32 v84, 16, v133
	v_and_b32_e32 v85, 0xffff0000, v133
	v_fma_f32 v78, v78, v82, v84
	v_fma_f32 v79, v79, v83, v85
	v_cvt_f32_ubyte1_e32 v83, v167
	v_cvt_f32_ubyte0_e32 v82, v167
	v_mul_f32_e32 v82, s18, v82
; __device__ __forceinline__ unsigned pkbf(float lo, float hi) { const f32x2_m v = {lo, hi}; const bf16x2_m b = __builtin_convertvector(v, bf16x2_m); return __builtin_bit_cast(unsigned, b); }
;     __device__ __forceinline__ void operator()(const f32x4 (&acc)[2][2][4][2], const Unit& u, int wr, int wc, int fr, int fq) const {
;     ...
;         for (int ai = 0; ai < 2; ++ai) { v2u gq[4][2]; v4u tq[4][2];
; #pragma unroll
;             for (int m = 0; m < 4; ++m)
; #pragma unroll
;                 for (int bj = 0; bj < 2; ++bj) { const size_t p = (size_t)(row0 + ai * HALF + m * 16) * DM + col0 + bj * HALF; gq[m][bj] = *(const v2u*)(gt + p); if (MODE == 1) tq[m][bj] = *(const v4u*)(T1 + p); }
;             asm volatile("" ::: "memory");
; #pragma unroll
;             for (int m = 0; m < 4; ++m)
; #pragma unroll
;                 for (int bj = 0; bj < 2; ++bj) { const size_t p = (size_t)(row0 + ai * HALF + m * 16) * DM + col0 + bj * HALF;
;                     const f32x4 a0 = acc[ai][bj][m][0], a1 = acc[ai][bj][m][1]; const v2u g = gq[m][bj]; const float s = 1.f / 255.f;
;                     float v[8] = {a0[0] * ((float)((g.x >> 0) & 0xffu) * s), a0[1] * ((float)((g.x >> 8) & 0xffu) * s), a0[2] * ((float)((g.x >> 16) & 0xffu) * s), a0[3] * ((float)((g.x >> 24) & 0xffu) * s),
;                                   a1[0] * ((float)((g.y >> 0) & 0xffu) * s), a1[1] * ((float)((g.y >> 8) & 0xffu) * s), a1[2] * ((float)((g.y >> 16) & 0xffu) * s), a1[3] * ((float)((g.y >> 24) & 0xffu) * s)};
;                     if (MODE == 1) { const v4u t = tq[m][bj];
;                         v[0] += bflo(t.x); v[1] += bfhi(t.x); v[2] += bflo(t.y); v[3] += bfhi(t.y); v[4] += bflo(t.z); v[5] += bfhi(t.z); v[6] += bflo(t.w); v[7] += bfhi(t.w); }
;                     v4u w; w.x = pkbf(v[0], v[1]); w.y = pkbf(v[2], v[3]); w.z = pkbf(v[4], v[5]); w.w = pkbf(v[6], v[7]);
;                     *(v4u*)(T1 + p) = w; } }
	v_mul_f32_e32 v83, s18, v83
	v_lshlrev_b32_e32 v84, 16, v134
	v_and_b32_e32 v85, 0xffff0000, v134
	v_fma_f32 v82, v72, v82, v84
	v_fma_f32 v83, v73, v83, v85
	v_cvt_f32_ubyte3_e32 v73, v167
	v_cvt_f32_ubyte2_e32 v72, v167
	v_mul_f32_e32 v72, s18, v72
	v_mul_f32_e32 v73, s18, v73
	v_lshlrev_b32_e32 v84, 16, v135
	v_and_b32_e32 v85, 0xffff0000, v135
	v_fma_f32 v84, v74, v72, v84
	v_fma_f32 v85, v75, v73, v85
	v_cvt_pk_bf16_f32 v72, v76, v77
	v_lshl_add_u64 v[76:77], s[6:7], 0, v[80:81]
	v_cvt_pk_bf16_f32 v73, v78, v79
	v_cvt_pk_bf16_f32 v74, v82, v83
	v_cvt_pk_bf16_f32 v75, v84, v85
	v_lshl_add_u64 v[76:77], v[76:77], 0, v[156:157]
	global_store_dwordx4 v[76:77], v[72:75], off
	v_add_u32_e32 v90, 0xa0, v160
	v_ashrrev_i32_e32 v91, 31, v90
	v_cvt_f32_ubyte1_e32 v73, v164
	v_cvt_f32_ubyte0_e32 v72, v164
	v_mul_f32_e32 v72, s18, v72
	v_mul_f32_e32 v73, s18, v73
	v_lshlrev_b32_e32 v74, 16, v128
	v_and_b32_e32 v75, 0xffff0000, v128
	v_fma_f32 v68, v68, v72, v74
	v_fma_f32 v69, v69, v73, v75
	v_cvt_f32_ubyte3_e32 v73, v164
	v_cvt_f32_ubyte2_e32 v72, v164
	v_mul_f32_e32 v72, s18, v72
	v_mul_f32_e32 v73, s18, v73
	v_lshlrev_b32_e32 v74, 16, v129
	v_and_b32_e32 v75, 0xffff0000, v129
	v_fma_f32 v70, v70, v72, v74
	v_fma_f32 v71, v71, v73, v75
	v_cvt_f32_ubyte1_e32 v73, v165
	v_cvt_f32_ubyte0_e32 v72, v165
	v_mul_f32_e32 v72, s18, v72
	v_mul_f32_e32 v73, s18, v73
	v_lshlrev_b32_e32 v74, 16, v130
	v_and_b32_e32 v75, 0xffff0000, v130
	v_fma_f32 v72, v64, v72, v74
	v_fma_f32 v73, v65, v73, v75
	v_cvt_f32_ubyte3_e32 v65, v165
	v_cvt_f32_ubyte2_e32 v64, v165
	v_mul_f32_e32 v64, s18, v64
	v_mul_f32_e32 v65, s18, v65
	v_lshlrev_b32_e32 v74, 16, v131
	v_and_b32_e32 v75, 0xffff0000, v131
	v_fma_f32 v74, v66, v64, v74
	v_fma_f32 v75, v67, v65, v75
	v_cvt_pk_bf16_f32 v64, v68, v69
	v_cvt_pk_bf16_f32 v65, v70, v71
	v_cvt_pk_bf16_f32 v66, v72, v73
	v_cvt_pk_bf16_f32 v67, v74, v75
	global_store_dwordx4 v[76:77], v[64:67], off offset:256
	v_add_u32_e32 v84, 0xb0, v160
	v_ashrrev_i32_e32 v85, 31, v84
	v_lshlrev_b64 v[64:65], 11, v[108:109]
	v_lshl_add_u64 v[64:65], v[64:65], 0, v[158:159]
	v_lshl_add_u64 v[66:67], s[12:13], 0, v[64:65]
	global_load_dwordx2 v[110:111], v[66:67], off
	v_lshl_add_u64 v[66:67], v[64:65], 1, s[6:7]
	global_load_dwordx4 v[92:95], v[66:67], off
	v_or_b32_e32 v64, 0x80, v64
	v_lshl_add_u64 v[66:67], s[12:13], 0, v[64:65]
	global_load_dwordx2 v[112:113], v[66:67], off
	v_lshl_add_u64 v[64:65], v[64:65], 1, s[6:7]
	global_load_dwordx4 v[96:99], v[64:65], off
	v_lshlrev_b64 v[64:65], 11, v[114:115]
	v_lshl_add_u64 v[64:65], v[64:65], 0, v[158:159]
	v_lshl_add_u64 v[66:67], s[12:13], 0, v[64:65]
	v_lshl_add_u64 v[68:69], v[64:65], 1, s[6:7]
	global_load_dwordx2 v[116:117], v[66:67], off
	global_load_dwordx4 v[100:103], v[68:69], off
	v_or_b32_e32 v64, 0x80, v64
	v_lshl_add_u64 v[66:67], s[12:13], 0, v[64:65]
	v_lshl_add_u64 v[64:65], v[64:65], 1, s[6:7]
	global_load_dwordx2 v[118:119], v[66:67], off
	global_load_dwordx4 v[104:107], v[64:65], off
	v_lshlrev_b64 v[64:65], 11, v[90:91]
	v_lshl_add_u64 v[64:65], v[64:65], 0, v[158:159]
	v_lshl_add_u64 v[66:67], s[12:13], 0, v[64:65]
	v_lshl_add_u64 v[68:69], v[64:65], 1, s[6:7]
	global_load_dwordx2 v[88:89], v[66:67], off
	global_load_dwordx4 v[76:79], v[68:69], off
	v_or_b32_e32 v64, 0x80, v64
	v_lshl_add_u64 v[66:67], s[12:13], 0, v[64:65]
	v_lshl_add_u64 v[64:65], v[64:65], 1, s[6:7]
	global_load_dwordx2 v[86:87], v[66:67], off
	global_load_dwordx4 v[72:75], v[64:65], off
	v_lshlrev_b64 v[64:65], 11, v[84:85]
	v_lshl_add_u64 v[64:65], v[64:65], 0, v[158:159]
	v_lshl_add_u64 v[66:67], s[12:13], 0, v[64:65]
	v_lshl_add_u64 v[68:69], v[64:65], 1, s[6:7]
	global_load_dwordx2 v[82:83], v[66:67], off
	s_nop 0
	global_load_dwordx4 v[68:71], v[68:69], off
	v_or_b32_e32 v64, 0x80, v64
	v_lshl_add_u64 v[66:67], s[12:13], 0, v[64:65]
	v_lshl_add_u64 v[64:65], v[64:65], 1, s[6:7]
	global_load_dwordx2 v[80:81], v[66:67], off
	s_nop 0
	global_load_dwordx4 v[64:67], v[64:65], off
	v_lshlrev_b64 v[108:109], 12, v[108:109]
	s_waitcnt vmcnt(15)
	v_cvt_f32_ubyte1_e32 v121, v110
	v_cvt_f32_ubyte0_e32 v120, v110
	v_mul_f32_e32 v120, s18, v120
	v_mul_f32_e32 v121, s18, v121
	s_waitcnt vmcnt(14)
	v_lshlrev_b32_e32 v122, 16, v92
	v_and_b32_e32 v123, 0xffff0000, v92
	v_fma_f32 v60, v60, v120, v122
	v_fma_f32 v61, v61, v121, v123
	v_cvt_f32_ubyte3_e32 v121, v110
	v_cvt_f32_ubyte2_e32 v120, v110
	v_mul_f32_e32 v120, s18, v120
	v_mul_f32_e32 v121, s18, v121
	v_lshlrev_b32_e32 v92, 16, v93
	v_and_b32_e32 v93, 0xffff0000, v93
	v_fma_f32 v62, v62, v120, v92
	v_fma_f32 v63, v63, v121, v93
	v_cvt_f32_ubyte1_e32 v93, v111
	v_cvt_f32_ubyte0_e32 v92, v111
	v_mul_f32_e32 v92, s18, v92
	v_mul_f32_e32 v93, s18, v93
	v_lshlrev_b32_e32 v120, 16, v94
	v_and_b32_e32 v121, 0xffff0000, v94
	v_fma_f32 v92, v56, v92, v120
	v_fma_f32 v93, v57, v93, v121
	v_cvt_f32_ubyte3_e32 v57, v111
	v_cvt_f32_ubyte2_e32 v56, v111
	v_mul_f32_e32 v56, s18, v56
	v_mul_f32_e32 v57, s18, v57
	v_lshlrev_b32_e32 v94, 16, v95
	v_and_b32_e32 v95, 0xffff0000, v95
	v_fma_f32 v94, v58, v56, v94
	v_fma_f32 v95, v59, v57, v95
	v_cvt_pk_bf16_f32 v56, v60, v61
	v_lshl_add_u64 v[60:61], s[6:7], 0, v[108:109]
	v_cvt_pk_bf16_f32 v57, v62, v63
	v_cvt_pk_bf16_f32 v58, v92, v93
	v_cvt_pk_bf16_f32 v59, v94, v95
	v_lshl_add_u64 v[60:61], v[60:61], 0, v[156:157]
	global_store_dwordx4 v[60:61], v[56:59], off
	s_waitcnt vmcnt(14)
	s_nop 0
	v_cvt_f32_ubyte1_e32 v57, v112
	v_cvt_f32_ubyte0_e32 v56, v112
	v_mul_f32_e32 v56, s18, v56
	v_mul_f32_e32 v57, s18, v57
	s_waitcnt vmcnt(13)
; __device__ __forceinline__ unsigned pkbf(float lo, float hi) { const f32x2_m v = {lo, hi}; const bf16x2_m b = __builtin_convertvector(v, bf16x2_m); return __builtin_bit_cast(unsigned, b); }
;     __device__ __forceinline__ void operator()(const f32x4 (&acc)[2][2][4][2], const Unit& u, int wr, int wc, int fr, int fq) const {
;     ...
;                 for (int bj = 0; bj < 2; ++bj) { const size_t p = (size_t)(row0 + ai * HALF + m * 16) * DM + col0 + bj * HALF;
;                     const f32x4 a0 = acc[ai][bj][m][0], a1 = acc[ai][bj][m][1]; const v2u g = gq[m][bj]; const float s = 1.f / 255.f;
;                     float v[8] = {a0[0] * ((float)((g.x >> 0) & 0xffu) * s), a0[1] * ((float)((g.x >> 8) & 0xffu) * s), a0[2] * ((float)((g.x >> 16) & 0xffu) * s), a0[3] * ((float)((g.x >> 24) & 0xffu) * s),
;                                   a1[0] * ((float)((g.y >> 0) & 0xffu) * s), a1[1] * ((float)((g.y >> 8) & 0xffu) * s), a1[2] * ((float)((g.y >> 16) & 0xffu) * s), a1[3] * ((float)((g.y >> 24) & 0xffu) * s)};
;                     if (MODE == 1) { const v4u t = tq[m][bj];
;                         v[0] += bflo(t.x); v[1] += bfhi(t.x); v[2] += bflo(t.y); v[3] += bfhi(t.y); v[4] += bflo(t.z); v[5] += bfhi(t.z); v[6] += bflo(t.w); v[7] += bfhi(t.w); }
;                     v4u w; w.x = pkbf(v[0], v[1]); w.y = pkbf(v[2], v[3]); w.z = pkbf(v[4], v[5]); w.w = pkbf(v[6], v[7]);
;                     *(v4u*)(T1 + p) = w; } }
	v_lshlrev_b32_e32 v58, 16, v96
	v_and_b32_e32 v59, 0xffff0000, v96
	v_fma_f32 v52, v52, v56, v58
	v_fma_f32 v53, v53, v57, v59
	v_cvt_f32_ubyte3_e32 v57, v112
	v_cvt_f32_ubyte2_e32 v56, v112
	v_mul_f32_e32 v56, s18, v56
	v_mul_f32_e32 v57, s18, v57
	v_lshlrev_b32_e32 v58, 16, v97
	v_and_b32_e32 v59, 0xffff0000, v97
	v_fma_f32 v54, v54, v56, v58
	v_fma_f32 v55, v55, v57, v59
	v_cvt_f32_ubyte1_e32 v57, v113
	v_cvt_f32_ubyte0_e32 v56, v113
	v_mul_f32_e32 v56, s18, v56
	v_mul_f32_e32 v57, s18, v57
	v_lshlrev_b32_e32 v58, 16, v98
	v_and_b32_e32 v59, 0xffff0000, v98
	v_fma_f32 v56, v48, v56, v58
	v_fma_f32 v57, v49, v57, v59
	v_cvt_f32_ubyte3_e32 v49, v113
	v_cvt_f32_ubyte2_e32 v48, v113
	v_mul_f32_e32 v48, s18, v48
	v_mul_f32_e32 v49, s18, v49
	v_lshlrev_b32_e32 v58, 16, v99
	v_and_b32_e32 v59, 0xffff0000, v99
	v_fma_f32 v58, v50, v48, v58
	v_fma_f32 v59, v51, v49, v59
	v_cvt_pk_bf16_f32 v48, v52, v53
	v_cvt_pk_bf16_f32 v49, v54, v55
	v_cvt_pk_bf16_f32 v50, v56, v57
	v_cvt_pk_bf16_f32 v51, v58, v59
	global_store_dwordx4 v[60:61], v[48:51], off offset:256
	s_waitcnt vmcnt(12)
	v_lshlrev_b32_e32 v52, 16, v100
	v_and_b32_e32 v53, 0xffff0000, v100
	v_cvt_f32_ubyte1_e32 v51, v116
	v_cvt_f32_ubyte0_e32 v50, v116
	v_mul_f32_e32 v50, s18, v50
	v_mul_f32_e32 v51, s18, v51
	v_lshlrev_b64 v[48:49], 12, v[114:115]
	v_fma_f32 v44, v44, v50, v52
	v_fma_f32 v45, v45, v51, v53
	v_cvt_f32_ubyte3_e32 v51, v116
	v_cvt_f32_ubyte2_e32 v50, v116
	v_mul_f32_e32 v50, s18, v50
	v_mul_f32_e32 v51, s18, v51
	v_lshlrev_b32_e32 v52, 16, v101
	v_and_b32_e32 v53, 0xffff0000, v101
	v_fma_f32 v46, v46, v50, v52
	v_fma_f32 v47, v47, v51, v53
	v_cvt_f32_ubyte1_e32 v51, v117
	v_cvt_f32_ubyte0_e32 v50, v117
	v_mul_f32_e32 v50, s18, v50
	v_mul_f32_e32 v51, s18, v51
	v_lshlrev_b32_e32 v52, 16, v102
	v_and_b32_e32 v53, 0xffff0000, v102
	v_fma_f32 v50, v40, v50, v52
	v_fma_f32 v51, v41, v51, v53
	v_cvt_f32_ubyte3_e32 v41, v117
	v_cvt_f32_ubyte2_e32 v40, v117
	v_mul_f32_e32 v40, s18, v40
	v_mul_f32_e32 v41, s18, v41
	v_lshlrev_b32_e32 v52, 16, v103
	v_and_b32_e32 v53, 0xffff0000, v103
	v_fma_f32 v52, v42, v40, v52
	v_fma_f32 v53, v43, v41, v53
	v_cvt_pk_bf16_f32 v40, v44, v45
	v_lshl_add_u64 v[44:45], s[6:7], 0, v[48:49]
	v_cvt_pk_bf16_f32 v41, v46, v47
	v_cvt_pk_bf16_f32 v42, v50, v51
	v_cvt_pk_bf16_f32 v43, v52, v53
	v_lshl_add_u64 v[44:45], v[44:45], 0, v[156:157]
	global_store_dwordx4 v[44:45], v[40:43], off
	s_waitcnt vmcnt(12)
	s_nop 0
	v_cvt_f32_ubyte1_e32 v41, v118
	v_cvt_f32_ubyte0_e32 v40, v118
	v_mul_f32_e32 v40, s18, v40
	v_mul_f32_e32 v41, s18, v41
	s_waitcnt vmcnt(11)
	v_lshlrev_b32_e32 v42, 16, v104
	v_and_b32_e32 v43, 0xffff0000, v104
	v_fma_f32 v36, v36, v40, v42
	v_fma_f32 v37, v37, v41, v43
	v_cvt_f32_ubyte3_e32 v41, v118
	v_cvt_f32_ubyte2_e32 v40, v118
	v_mul_f32_e32 v40, s18, v40
	v_mul_f32_e32 v41, s18, v41
	v_lshlrev_b32_e32 v42, 16, v105
	v_and_b32_e32 v43, 0xffff0000, v105
	v_fma_f32 v38, v38, v40, v42
	v_fma_f32 v39, v39, v41, v43
	v_cvt_f32_ubyte1_e32 v41, v119
	v_cvt_f32_ubyte0_e32 v40, v119
	v_mul_f32_e32 v40, s18, v40
	v_mul_f32_e32 v41, s18, v41
	v_lshlrev_b32_e32 v42, 16, v106
	v_and_b32_e32 v43, 0xffff0000, v106
	v_fma_f32 v40, v32, v40, v42
	v_fma_f32 v41, v33, v41, v43
	v_cvt_f32_ubyte3_e32 v33, v119
	v_cvt_f32_ubyte2_e32 v32, v119
	v_mul_f32_e32 v32, s18, v32
	v_mul_f32_e32 v33, s18, v33
	v_lshlrev_b32_e32 v42, 16, v107
	v_and_b32_e32 v43, 0xffff0000, v107
	v_fma_f32 v42, v34, v32, v42
	v_fma_f32 v43, v35, v33, v43
	v_cvt_pk_bf16_f32 v32, v36, v37
	v_cvt_pk_bf16_f32 v33, v38, v39
	v_cvt_pk_bf16_f32 v34, v40, v41
	v_cvt_pk_bf16_f32 v35, v42, v43
	global_store_dwordx4 v[44:45], v[32:35], off offset:256
	s_waitcnt vmcnt(10)
	v_lshlrev_b32_e32 v36, 16, v76
	v_and_b32_e32 v37, 0xffff0000, v76
	v_cvt_f32_ubyte1_e32 v35, v88
	v_cvt_f32_ubyte0_e32 v34, v88
	v_mul_f32_e32 v34, s18, v34
	v_mul_f32_e32 v35, s18, v35
	v_lshlrev_b64 v[32:33], 12, v[90:91]
	v_fma_f32 v28, v28, v34, v36
	v_fma_f32 v29, v29, v35, v37
	v_cvt_f32_ubyte3_e32 v35, v88
	v_cvt_f32_ubyte2_e32 v34, v88
	v_mul_f32_e32 v34, s18, v34
	v_mul_f32_e32 v35, s18, v35
	v_lshlrev_b32_e32 v36, 16, v77
	v_and_b32_e32 v37, 0xffff0000, v77
	v_fma_f32 v30, v30, v34, v36
	v_fma_f32 v31, v31, v35, v37
	v_cvt_f32_ubyte1_e32 v35, v89
	v_cvt_f32_ubyte0_e32 v34, v89
	v_mul_f32_e32 v34, s18, v34
	v_mul_f32_e32 v35, s18, v35
	v_lshlrev_b32_e32 v36, 16, v78
	v_and_b32_e32 v37, 0xffff0000, v78
	v_fma_f32 v34, v24, v34, v36
	v_fma_f32 v35, v25, v35, v37
	v_cvt_f32_ubyte3_e32 v25, v89
	v_cvt_f32_ubyte2_e32 v24, v89
	v_mul_f32_e32 v24, s18, v24
	v_mul_f32_e32 v25, s18, v25
	v_lshlrev_b32_e32 v36, 16, v79
	v_and_b32_e32 v37, 0xffff0000, v79
	v_fma_f32 v36, v26, v24, v36
	v_fma_f32 v37, v27, v25, v37
	v_cvt_pk_bf16_f32 v24, v28, v29
	v_lshl_add_u64 v[28:29], s[6:7], 0, v[32:33]
	v_cvt_pk_bf16_f32 v25, v30, v31
	v_cvt_pk_bf16_f32 v26, v34, v35
	v_cvt_pk_bf16_f32 v27, v36, v37
	v_lshl_add_u64 v[28:29], v[28:29], 0, v[156:157]
	global_store_dwordx4 v[28:29], v[24:27], off
	s_waitcnt vmcnt(10)
; #define PG8_BAR __builtin_amdgcn_s_barrier()
; __device__ __forceinline__ unsigned pkbf(float lo, float hi) { const f32x2_m v = {lo, hi}; const bf16x2_m b = __builtin_convertvector(v, bf16x2_m); return __builtin_bit_cast(unsigned, b); }
; template <class Epi, class Sched, bool ALIGN_EPI = false, bool SP2 = false>
; __device__ __forceinline__ void gemm_phase(PG8_LAS unsigned char* lds, const Gemm g, const Sched& S, const Epi& E) {
;     ...
;         if constexpr (ALIGN_EPI) { if (wr == 0) PG8_BAR; }
;         if constexpr (!Epi::AFTER_DRAIN) { E(acc, cur, wr, wc, fr, fq); S.done(cur); }
;         if (!has_next) break;
; #pragma unroll
;         for (int a = 0; a < 2; ++a)
; #pragma unroll
;             for (int b = 0; b < 2; ++b)
; #pragma unroll
;                 for (int m = 0; m < 4; ++m)
; #pragma unroll
;                     for (int n = 0; n < 2; ++n) acc[a][b][m][n] = (f32x4){0.f, 0.f, 0.f, 0.f};
;         cur = nxt; cA = nA; cB = nB; ++ui;
;         if constexpr (ALIGN_EPI) { if (wr == 1) PG8_BAR; }
;     __device__ __forceinline__ void operator()(const f32x4 (&acc)[2][2][4][2], const Unit& u, int wr, int wc, int fr, int fq) const {
;     ...
;                 for (int bj = 0; bj < 2; ++bj) { const size_t p = (size_t)(row0 + ai * HALF + m * 16) * DM + col0 + bj * HALF;
;                     const f32x4 a0 = acc[ai][bj][m][0], a1 = acc[ai][bj][m][1]; const v2u g = gq[m][bj]; const float s = 1.f / 255.f;
;                     float v[8] = {a0[0] * ((float)((g.x >> 0) & 0xffu) * s), a0[1] * ((float)((g.x >> 8) & 0xffu) * s), a0[2] * ((float)((g.x >> 16) & 0xffu) * s), a0[3] * ((float)((g.x >> 24) & 0xffu) * s),
;                                   a1[0] * ((float)((g.y >> 0) & 0xffu) * s), a1[1] * ((float)((g.y >> 8) & 0xffu) * s), a1[2] * ((float)((g.y >> 16) & 0xffu) * s), a1[3] * ((float)((g.y >> 24) & 0xffu) * s)};
;                     if (MODE == 1) { const v4u t = tq[m][bj];
;                         v[0] += bflo(t.x); v[1] += bfhi(t.x); v[2] += bflo(t.y); v[3] += bfhi(t.y); v[4] += bflo(t.z); v[5] += bfhi(t.z); v[6] += bflo(t.w); v[7] += bfhi(t.w); }
;                     v4u w; w.x = pkbf(v[0], v[1]); w.y = pkbf(v[2], v[3]); w.z = pkbf(v[4], v[5]); w.w = pkbf(v[6], v[7]);
;                     *(v4u*)(T1 + p) = w; } }
	s_nop 0
	v_cvt_f32_ubyte1_e32 v25, v86
	v_cvt_f32_ubyte0_e32 v24, v86
	v_mul_f32_e32 v24, s18, v24
	v_mul_f32_e32 v25, s18, v25
	s_waitcnt vmcnt(9)
	v_lshlrev_b32_e32 v26, 16, v72
	v_and_b32_e32 v27, 0xffff0000, v72
	v_fma_f32 v20, v20, v24, v26
	v_fma_f32 v21, v21, v25, v27
	v_cvt_f32_ubyte3_e32 v25, v86
	v_cvt_f32_ubyte2_e32 v24, v86
	v_mul_f32_e32 v24, s18, v24
	v_mul_f32_e32 v25, s18, v25
	v_lshlrev_b32_e32 v26, 16, v73
	v_and_b32_e32 v27, 0xffff0000, v73
	v_fma_f32 v22, v22, v24, v26
	v_fma_f32 v23, v23, v25, v27
	v_cvt_f32_ubyte1_e32 v25, v87
	v_cvt_f32_ubyte0_e32 v24, v87
	v_mul_f32_e32 v24, s18, v24
	v_mul_f32_e32 v25, s18, v25
	v_lshlrev_b32_e32 v26, 16, v74
	v_and_b32_e32 v27, 0xffff0000, v74
	v_fma_f32 v24, v16, v24, v26
	v_fma_f32 v25, v17, v25, v27
	v_cvt_f32_ubyte3_e32 v17, v87
	v_cvt_f32_ubyte2_e32 v16, v87
	v_mul_f32_e32 v16, s18, v16
	v_mul_f32_e32 v17, s18, v17
	v_lshlrev_b32_e32 v26, 16, v75
	v_and_b32_e32 v27, 0xffff0000, v75
	v_fma_f32 v26, v18, v16, v26
	v_fma_f32 v27, v19, v17, v27
	v_cvt_pk_bf16_f32 v16, v20, v21
	v_cvt_pk_bf16_f32 v17, v22, v23
	v_cvt_pk_bf16_f32 v18, v24, v25
	v_cvt_pk_bf16_f32 v19, v26, v27
	global_store_dwordx4 v[28:29], v[16:19], off offset:256
	s_waitcnt vmcnt(8)
	v_lshlrev_b32_e32 v20, 16, v68
	v_and_b32_e32 v21, 0xffff0000, v68
	v_cvt_f32_ubyte1_e32 v19, v82
	v_cvt_f32_ubyte0_e32 v18, v82
	v_mul_f32_e32 v18, s18, v18
	v_mul_f32_e32 v19, s18, v19
	v_lshlrev_b64 v[16:17], 12, v[84:85]
	v_fma_f32 v12, v12, v18, v20
	v_fma_f32 v13, v13, v19, v21
	v_cvt_f32_ubyte3_e32 v19, v82
	v_cvt_f32_ubyte2_e32 v18, v82
	v_mul_f32_e32 v18, s18, v18
	v_mul_f32_e32 v19, s18, v19
	v_lshlrev_b32_e32 v20, 16, v69
	v_and_b32_e32 v21, 0xffff0000, v69
	v_fma_f32 v14, v14, v18, v20
	v_fma_f32 v15, v15, v19, v21
	v_cvt_f32_ubyte1_e32 v19, v83
	v_cvt_f32_ubyte0_e32 v18, v83
	v_mul_f32_e32 v18, s18, v18
	v_mul_f32_e32 v19, s18, v19
	v_lshlrev_b32_e32 v20, 16, v70
	v_and_b32_e32 v21, 0xffff0000, v70
	v_fma_f32 v18, v8, v18, v20
	v_fma_f32 v19, v9, v19, v21
	v_cvt_f32_ubyte3_e32 v9, v83
	v_cvt_f32_ubyte2_e32 v8, v83
	v_mul_f32_e32 v8, s18, v8
	v_mul_f32_e32 v9, s18, v9
	v_lshlrev_b32_e32 v20, 16, v71
	v_and_b32_e32 v21, 0xffff0000, v71
	v_fma_f32 v20, v10, v8, v20
	v_fma_f32 v21, v11, v9, v21
	v_cvt_pk_bf16_f32 v8, v12, v13
	v_lshl_add_u64 v[12:13], s[6:7], 0, v[16:17]
	v_cvt_pk_bf16_f32 v9, v14, v15
	v_cvt_pk_bf16_f32 v10, v18, v19
	v_cvt_pk_bf16_f32 v11, v20, v21
	v_lshl_add_u64 v[12:13], v[12:13], 0, v[156:157]
	global_store_dwordx4 v[12:13], v[8:11], off
	s_waitcnt vmcnt(8)
	s_nop 0
	v_cvt_f32_ubyte1_e32 v9, v80
	v_cvt_f32_ubyte0_e32 v8, v80
	v_mul_f32_e32 v8, s18, v8
	v_mul_f32_e32 v9, s18, v9
	s_waitcnt vmcnt(7)
	v_lshlrev_b32_e32 v10, 16, v64
	v_and_b32_e32 v11, 0xffff0000, v64
	v_fma_f32 v4, v4, v8, v10
	v_fma_f32 v5, v5, v9, v11
	v_cvt_f32_ubyte3_e32 v9, v80
	v_cvt_f32_ubyte2_e32 v8, v80
	v_mul_f32_e32 v8, s18, v8
	v_mul_f32_e32 v9, s18, v9
	v_lshlrev_b32_e32 v10, 16, v65
	v_and_b32_e32 v11, 0xffff0000, v65
	v_fma_f32 v6, v6, v8, v10
	v_fma_f32 v7, v7, v9, v11
	v_cvt_f32_ubyte1_e32 v9, v81
	v_cvt_f32_ubyte0_e32 v8, v81
	v_mul_f32_e32 v8, s18, v8
	v_mul_f32_e32 v9, s18, v9
	v_lshlrev_b32_e32 v10, 16, v66
	v_and_b32_e32 v11, 0xffff0000, v66
	v_fma_f32 v8, v0, v8, v10
	v_fma_f32 v9, v1, v9, v11
	v_cvt_f32_ubyte3_e32 v1, v81
	v_cvt_f32_ubyte2_e32 v0, v81
	v_mul_f32_e32 v0, s18, v0
	v_mul_f32_e32 v1, s18, v1
	v_lshlrev_b32_e32 v10, 16, v67
	v_and_b32_e32 v11, 0xffff0000, v67
	v_fma_f32 v10, v2, v0, v10
	v_fma_f32 v11, v3, v1, v11
	v_cvt_pk_bf16_f32 v0, v4, v5
	v_cvt_pk_bf16_f32 v1, v6, v7
	v_cvt_pk_bf16_f32 v2, v8, v9
	v_cvt_pk_bf16_f32 v3, v10, v11
	global_store_dwordx4 v[12:13], v[0:3], off offset:256
	s_cbranch_vccnz .LBB0_1694
	s_andn2_b64 vcc, exec, s[4:5]
	s_cbranch_vccnz .LBB0_1693
	s_barrier
	s_branch .LBB0_1693

; __device__ __forceinline__ unsigned pkbf(float lo, float hi) { const f32x2_m v = {lo, hi}; const bf16x2_m b = __builtin_convertvector(v, bf16x2_m); return __builtin_bit_cast(unsigned, b); }
;     __device__ __forceinline__ void operator()(const f32x4 (&acc)[2][2][4][2], const Unit& u, int wr, int wc, int fr, int fq) const {
;     ...
;         for (int ai = 0; ai < 2; ++ai) { f32x4 pre[4][2][2];
; #pragma unroll
;             for (int m = 0; m < 4; ++m)
; #pragma unroll
;                 for (int bj = 0; bj < 2; ++bj)
; #pragma unroll
;                     for (int n = 0; n < 2; ++n) pre[m][bj][n] = *(const f32x4*)(base + (size_t)(row0 + ai * HALF + m * 16) * ldc + col0 + bj * HALF + n * 16);
;             asm volatile("" ::: "memory");
; #pragma unroll
;             for (int m = 0; m < 4; ++m) { const int row = row0 + ai * HALF + m * 16; const size_t off = (size_t)row * ldc + col0; float sq = 0.f;
; #pragma unroll
;                 for (int bj = 0; bj < 2; ++bj)
; #pragma unroll
;                     for (int n = 0; n < 2; ++n) { const size_t p = off + bj * HALF + n * 16; const f32x4 o = pre[m][bj][n] + acc[ai][bj][m][n] * scale; *(f32x4*)(out + p) = o;
;                         if (NORM == 1) *(v2u*)(xb + p) = (v2u){pkbf(o[0], o[1]), pkbf(o[2], o[3])};
;                         if (NORM) sq += (o[0] * o[0] + o[1] * o[1]) + (o[2] * o[2] + o[3] * o[3]); }
;                 if (NORM) { sq += __shfl_xor(sq, 16); sq += __shfl_xor(sq, 32); if (fq == 0) __hip_atomic_fetch_add(ss + row, sq, __ATOMIC_RELAXED, __HIP_MEMORY_SCOPE_AGENT); } } }
.LBB0_1801:
	v_lshl_add_u32 v192, s36, 8, v206
	v_lshl_or_b32 v188, s38, 8, v208
	v_ashrrev_i32_e32 v189, 31, v188
	v_ashrrev_i32_e32 v193, 31, v192
	v_lshl_add_u64 v[190:191], v[188:189], 2, s[60:61]
	v_lshlrev_b64 v[128:129], 13, v[192:193]
	v_lshl_add_u64 v[220:221], v[190:191], 0, v[128:129]
	global_load_dwordx4 v[212:215], v[220:221], off
	global_load_dwordx4 v[216:219], v[220:221], off offset:64
	global_load_dwordx4 v[228:231], v[220:221], off offset:512
	global_load_dwordx4 v[232:235], v[220:221], off offset:576
	v_or_b32_e32 v202, 16, v192
	v_or_b32_e32 v198, 32, v192
	v_or_b32_e32 v194, 48, v192
	v_ashrrev_i32_e32 v203, 31, v202
	v_ashrrev_i32_e32 v199, 31, v198
	v_ashrrev_i32_e32 v195, 31, v194
	v_lshlrev_b64 v[128:129], 13, v[202:203]
	v_lshlrev_b64 v[130:131], 13, v[198:199]
	v_lshlrev_b64 v[132:133], 13, v[194:195]
	v_lshl_add_u64 v[204:205], v[190:191], 0, v[128:129]
	v_lshl_add_u64 v[200:201], v[190:191], 0, v[130:131]
	v_lshl_add_u64 v[196:197], v[190:191], 0, v[132:133]
	global_load_dwordx4 v[172:175], v[204:205], off
	global_load_dwordx4 v[168:171], v[204:205], off offset:64
	global_load_dwordx4 v[164:167], v[204:205], off offset:512
	global_load_dwordx4 v[160:163], v[204:205], off offset:576
	global_load_dwordx4 v[156:159], v[200:201], off
	global_load_dwordx4 v[152:155], v[200:201], off offset:64
	global_load_dwordx4 v[148:151], v[200:201], off offset:512
	global_load_dwordx4 v[144:147], v[200:201], off offset:576
	global_load_dwordx4 v[140:143], v[196:197], off
	global_load_dwordx4 v[136:139], v[196:197], off offset:64
	global_load_dwordx4 v[132:135], v[196:197], off offset:512
	global_load_dwordx4 v[128:131], v[196:197], off offset:576
	v_lshlrev_b64 v[224:225], 11, v[192:193]
	v_lshl_add_u64 v[224:225], v[224:225], 0, v[188:189]
	v_lshlrev_b64 v[224:225], 1, v[224:225]
	v_lshl_add_u64 v[236:237], s[70:71], 0, v[224:225]
	v_or_b32_e32 v238, 32, v224
	v_mov_b32_e32 v239, v225
	v_lshl_add_u64 v[238:239], s[70:71], 0, v[238:239]
	v_or_b32_e32 v240, 0x100, v224
	v_mov_b32_e32 v241, v225
	v_or_b32_e32 v224, 0x120, v224
	s_waitcnt vmcnt(0)
	v_add_f32_e32 v126, v126, v214
	v_add_f32_e32 v127, v127, v215
	v_add_f32_e32 v124, v124, v212
	v_add_f32_e32 v125, v125, v213
	v_add_f32_e32 v122, v122, v218
	v_add_f32_e32 v123, v123, v219
	v_add_f32_e32 v120, v120, v216
	v_add_f32_e32 v121, v121, v217
	v_add_f32_e32 v118, v118, v230
	v_add_f32_e32 v119, v119, v231
	v_add_f32_e32 v116, v116, v228
	v_add_f32_e32 v117, v117, v229
	global_store_dwordx4 v[220:221], v[124:127], off
	v_cvt_pk_bf16_f32 v212, v124, v125
	v_cvt_pk_bf16_f32 v213, v126, v127
	v_mul_f32_e32 v125, v125, v125
	v_mul_f32_e32 v127, v127, v127
	v_mul_f32_e32 v218, v121, v121
	v_mul_f32_e32 v219, v123, v123
	v_add_f32_e32 v114, v114, v234
	v_add_f32_e32 v115, v115, v235
	v_add_f32_e32 v112, v112, v232
	v_add_f32_e32 v113, v113, v233
	v_mul_f32_e32 v228, v117, v117
	v_mul_f32_e32 v229, v119, v119
	v_fmac_f32_e32 v125, v124, v124
	v_fmac_f32_e32 v127, v126, v126
	v_fmac_f32_e32 v218, v120, v120
	v_fmac_f32_e32 v219, v122, v122
	v_cvt_pk_bf16_f32 v214, v120, v121
	v_cvt_pk_bf16_f32 v215, v122, v123
	v_cvt_pk_bf16_f32 v216, v116, v117
	v_mul_f32_e32 v230, v113, v113
	v_mul_f32_e32 v231, v115, v115
	global_store_dwordx2 v[236:237], v[212:213], off
	global_store_dwordx4 v[220:221], v[120:123], off offset:64
	global_store_dwordx2 v[238:239], v[214:215], off
	global_store_dwordx4 v[220:221], v[116:119], off offset:512
	v_fmac_f32_e32 v228, v116, v116
	v_fmac_f32_e32 v229, v118, v118
	v_add_f32_e32 v116, v125, v127
	v_add_f32_e32 v117, v218, v219
	v_cvt_pk_bf16_f32 v217, v118, v119
	v_fmac_f32_e32 v230, v112, v112
	v_fmac_f32_e32 v231, v114, v114
	v_add_f32_e32 v118, v228, v229
	v_add_f32_e32 v116, v116, v117
	v_add_f32_e32 v116, v116, v118
	v_add_f32_e32 v117, v230, v231
	v_add_f32_e32 v118, v116, v117
	ds_bpermute_b32 v119, v226, v118
	v_lshl_add_u64 v[116:117], s[70:71], 0, v[240:241]
	global_store_dwordx2 v[116:117], v[216:217], off
	global_store_dwordx4 v[220:221], v[112:115], off offset:576
	v_cvt_pk_bf16_f32 v116, v112, v113
	v_cvt_pk_bf16_f32 v117, v114, v115
	s_waitcnt lgkmcnt(0)
	v_add_f32_e32 v112, v118, v119
	ds_bpermute_b32 v113, v227, v112
	v_lshl_add_u64 v[114:115], s[70:71], 0, v[224:225]
	global_store_dwordx2 v[114:115], v[116:117], off
	s_and_saveexec_b64 s[0:1], s[4:5]
	s_cbranch_execz .LBB0_1803
	v_lshl_add_u64 v[114:115], v[192:193], 2, s[12:13]
	s_waitcnt lgkmcnt(0)
	v_add_f32_e32 v112, v112, v113
	global_atomic_add_f32 v[114:115], v112, off
; __device__ __forceinline__ unsigned pkbf(float lo, float hi) { const f32x2_m v = {lo, hi}; const bf16x2_m b = __builtin_convertvector(v, bf16x2_m); return __builtin_bit_cast(unsigned, b); }
;     __device__ __forceinline__ void operator()(const f32x4 (&acc)[2][2][4][2], const Unit& u, int wr, int wc, int fr, int fq) const {
;     ...
;             for (int m = 0; m < 4; ++m) { const int row = row0 + ai * HALF + m * 16; const size_t off = (size_t)row * ldc + col0; float sq = 0.f;
; #pragma unroll
;                 for (int bj = 0; bj < 2; ++bj)
; #pragma unroll
;                     for (int n = 0; n < 2; ++n) { const size_t p = off + bj * HALF + n * 16; const f32x4 o = pre[m][bj][n] + acc[ai][bj][m][n] * scale; *(f32x4*)(out + p) = o;
;                         if (NORM == 1) *(v2u*)(xb + p) = (v2u){pkbf(o[0], o[1]), pkbf(o[2], o[3])};
;                         if (NORM) sq += (o[0] * o[0] + o[1] * o[1]) + (o[2] * o[2] + o[3] * o[3]); }
;                 if (NORM) { sq += __shfl_xor(sq, 16); sq += __shfl_xor(sq, 32); if (fq == 0) __hip_atomic_fetch_add(ss + row, sq, __ATOMIC_RELAXED, __HIP_MEMORY_SCOPE_AGENT); } } }
.LBB0_1803:
	s_or_b64 exec, exec, s[0:1]
	s_waitcnt lgkmcnt(0)
	v_lshlrev_b64 v[112:113], 11, v[202:203]
	v_add_f32_e32 v110, v110, v174
	v_add_f32_e32 v111, v111, v175
	v_add_f32_e32 v108, v108, v172
	v_add_f32_e32 v109, v109, v173
	v_lshl_add_u64 v[112:113], v[112:113], 0, v[188:189]
	global_store_dwordx4 v[204:205], v[108:111], off
	v_cvt_pk_bf16_f32 v114, v108, v109
	v_lshlrev_b64 v[112:113], 1, v[112:113]
	v_mul_f32_e32 v109, v109, v109
	v_fmac_f32_e32 v109, v108, v108
	v_mul_f32_e32 v108, v111, v111
	v_cvt_pk_bf16_f32 v115, v110, v111
	v_lshl_add_u64 v[116:117], s[70:71], 0, v[112:113]
	v_fmac_f32_e32 v108, v110, v110
	v_add_f32_e32 v106, v106, v170
	v_add_f32_e32 v107, v107, v171
	v_add_f32_e32 v104, v104, v168
	v_add_f32_e32 v105, v105, v169
	global_store_dwordx2 v[116:117], v[114:115], off
	v_add_f32_e32 v114, v109, v108
	global_store_dwordx4 v[204:205], v[104:107], off offset:64
	v_cvt_pk_bf16_f32 v108, v104, v105
	v_or_b32_e32 v110, 32, v112
	v_mul_f32_e32 v105, v105, v105
	v_fmac_f32_e32 v105, v104, v104
	v_mul_f32_e32 v104, v107, v107
	v_mov_b32_e32 v111, v113
	v_fmac_f32_e32 v104, v106, v106
	v_cvt_pk_bf16_f32 v109, v106, v107
	v_lshl_add_u64 v[110:111], s[70:71], 0, v[110:111]
	v_add_f32_e32 v104, v105, v104
	v_add_f32_e32 v102, v102, v166
	v_add_f32_e32 v103, v103, v167
	v_add_f32_e32 v100, v100, v164
	v_add_f32_e32 v101, v101, v165
	global_store_dwordx2 v[110:111], v[108:109], off
	v_add_f32_e32 v108, v114, v104
	global_store_dwordx4 v[204:205], v[100:103], off offset:512
	v_cvt_pk_bf16_f32 v104, v100, v101
	v_add_f32_e32 v98, v98, v162
	v_add_f32_e32 v99, v99, v163
	v_mul_f32_e32 v101, v101, v101
	v_fmac_f32_e32 v101, v100, v100
	v_mul_f32_e32 v100, v103, v103
	v_fmac_f32_e32 v100, v102, v102
	v_add_f32_e32 v96, v96, v160
	v_add_f32_e32 v97, v97, v161
	v_cvt_pk_bf16_f32 v105, v102, v103
	v_add_f32_e32 v100, v101, v100
	v_mul_f32_e32 v101, v97, v97
	v_mul_f32_e32 v102, v99, v99
	v_fmac_f32_e32 v101, v96, v96
	v_fmac_f32_e32 v102, v98, v98
	v_add_f32_e32 v100, v108, v100
	v_add_f32_e32 v101, v101, v102
	v_add_f32_e32 v102, v100, v101
	ds_bpermute_b32 v103, v226, v102
	v_or_b32_e32 v106, 0x100, v112
	v_mov_b32_e32 v107, v113
	v_lshl_add_u64 v[100:101], s[70:71], 0, v[106:107]
	global_store_dwordx2 v[100:101], v[104:105], off
	global_store_dwordx4 v[204:205], v[96:99], off offset:576
	v_cvt_pk_bf16_f32 v100, v96, v97
	v_or_b32_e32 v112, 0x120, v112
	s_waitcnt lgkmcnt(0)
	v_add_f32_e32 v96, v102, v103
	ds_bpermute_b32 v97, v227, v96
	v_cvt_pk_bf16_f32 v101, v98, v99
	v_lshl_add_u64 v[98:99], s[70:71], 0, v[112:113]
	global_store_dwordx2 v[98:99], v[100:101], off
	s_and_saveexec_b64 s[0:1], s[4:5]
	s_cbranch_execz .LBB0_1805
	v_lshl_add_u64 v[98:99], v[202:203], 2, s[12:13]
	s_waitcnt lgkmcnt(0)
	v_add_f32_e32 v96, v96, v97
	global_atomic_add_f32 v[98:99], v96, off
.LBB0_1805:
	s_or_b64 exec, exec, s[0:1]
	s_waitcnt lgkmcnt(0)
	v_lshlrev_b64 v[96:97], 11, v[198:199]
	v_add_f32_e32 v94, v94, v158
	v_add_f32_e32 v95, v95, v159
	v_add_f32_e32 v92, v92, v156
	v_add_f32_e32 v93, v93, v157
	v_lshl_add_u64 v[96:97], v[96:97], 0, v[188:189]
	global_store_dwordx4 v[200:201], v[92:95], off
	v_cvt_pk_bf16_f32 v98, v92, v93
	v_lshlrev_b64 v[96:97], 1, v[96:97]
	v_mul_f32_e32 v93, v93, v93
	v_fmac_f32_e32 v93, v92, v92
	v_mul_f32_e32 v92, v95, v95
	v_cvt_pk_bf16_f32 v99, v94, v95
	v_lshl_add_u64 v[100:101], s[70:71], 0, v[96:97]
	v_fmac_f32_e32 v92, v94, v94
	v_add_f32_e32 v90, v90, v154
	v_add_f32_e32 v91, v91, v155
	v_add_f32_e32 v88, v88, v152
	v_add_f32_e32 v89, v89, v153
	global_store_dwordx2 v[100:101], v[98:99], off
	v_add_f32_e32 v98, v93, v92
	global_store_dwordx4 v[200:201], v[88:91], off offset:64
	v_cvt_pk_bf16_f32 v92, v88, v89
	v_or_b32_e32 v94, 32, v96
	v_mul_f32_e32 v89, v89, v89
	v_fmac_f32_e32 v89, v88, v88
	v_mul_f32_e32 v88, v91, v91
	v_mov_b32_e32 v95, v97
	v_fmac_f32_e32 v88, v90, v90
	v_cvt_pk_bf16_f32 v93, v90, v91
	v_lshl_add_u64 v[94:95], s[70:71], 0, v[94:95]
	v_add_f32_e32 v88, v89, v88
	v_add_f32_e32 v86, v86, v150
	v_add_f32_e32 v87, v87, v151
	v_add_f32_e32 v84, v84, v148
	v_add_f32_e32 v85, v85, v149
	global_store_dwordx2 v[94:95], v[92:93], off
	v_add_f32_e32 v92, v98, v88
	global_store_dwordx4 v[200:201], v[84:87], off offset:512
	v_cvt_pk_bf16_f32 v88, v84, v85
	v_add_f32_e32 v82, v82, v146
	v_add_f32_e32 v83, v83, v147
	v_mul_f32_e32 v85, v85, v85
	v_fmac_f32_e32 v85, v84, v84
	v_mul_f32_e32 v84, v87, v87
	v_fmac_f32_e32 v84, v86, v86
	v_add_f32_e32 v80, v80, v144
	v_add_f32_e32 v81, v81, v145
	v_cvt_pk_bf16_f32 v89, v86, v87
	v_add_f32_e32 v84, v85, v84
	v_mul_f32_e32 v85, v81, v81
	v_mul_f32_e32 v86, v83, v83
	v_fmac_f32_e32 v85, v80, v80
	v_fmac_f32_e32 v86, v82, v82
	v_add_f32_e32 v84, v92, v84
	v_add_f32_e32 v85, v85, v86
	v_add_f32_e32 v86, v84, v85
	ds_bpermute_b32 v87, v226, v86
	v_or_b32_e32 v90, 0x100, v96
	v_mov_b32_e32 v91, v97
	v_lshl_add_u64 v[84:85], s[70:71], 0, v[90:91]
	global_store_dwordx2 v[84:85], v[88:89], off
	global_store_dwordx4 v[200:201], v[80:83], off offset:576
	v_cvt_pk_bf16_f32 v84, v80, v81
	v_or_b32_e32 v96, 0x120, v96
	s_waitcnt lgkmcnt(0)
	v_add_f32_e32 v80, v86, v87
	ds_bpermute_b32 v81, v227, v80
	v_cvt_pk_bf16_f32 v85, v82, v83
	v_lshl_add_u64 v[82:83], s[70:71], 0, v[96:97]
	global_store_dwordx2 v[82:83], v[84:85], off
	s_and_saveexec_b64 s[0:1], s[4:5]
	s_cbranch_execz .LBB0_1807
	v_lshl_add_u64 v[82:83], v[198:199], 2, s[12:13]
	s_waitcnt lgkmcnt(0)
	v_add_f32_e32 v80, v80, v81
	global_atomic_add_f32 v[82:83], v80, off
; __device__ __forceinline__ unsigned pkbf(float lo, float hi) { const f32x2_m v = {lo, hi}; const bf16x2_m b = __builtin_convertvector(v, bf16x2_m); return __builtin_bit_cast(unsigned, b); }
;     __device__ __forceinline__ void operator()(const f32x4 (&acc)[2][2][4][2], const Unit& u, int wr, int wc, int fr, int fq) const {
;     ...
;         for (int ai = 0; ai < 2; ++ai) { f32x4 pre[4][2][2];
; #pragma unroll
;             for (int m = 0; m < 4; ++m)
; #pragma unroll
;                 for (int bj = 0; bj < 2; ++bj)
; #pragma unroll
;                     for (int n = 0; n < 2; ++n) pre[m][bj][n] = *(const f32x4*)(base + (size_t)(row0 + ai * HALF + m * 16) * ldc + col0 + bj * HALF + n * 16);
;             asm volatile("" ::: "memory");
; #pragma unroll
;             for (int m = 0; m < 4; ++m) { const int row = row0 + ai * HALF + m * 16; const size_t off = (size_t)row * ldc + col0; float sq = 0.f;
; #pragma unroll
;                 for (int bj = 0; bj < 2; ++bj)
; #pragma unroll
;                     for (int n = 0; n < 2; ++n) { const size_t p = off + bj * HALF + n * 16; const f32x4 o = pre[m][bj][n] + acc[ai][bj][m][n] * scale; *(f32x4*)(out + p) = o;
;                         if (NORM == 1) *(v2u*)(xb + p) = (v2u){pkbf(o[0], o[1]), pkbf(o[2], o[3])};
;                         if (NORM) sq += (o[0] * o[0] + o[1] * o[1]) + (o[2] * o[2] + o[3] * o[3]); }
;                 if (NORM) { sq += __shfl_xor(sq, 16); sq += __shfl_xor(sq, 32); if (fq == 0) __hip_atomic_fetch_add(ss + row, sq, __ATOMIC_RELAXED, __HIP_MEMORY_SCOPE_AGENT); } } }
.LBB0_1807:
	s_or_b64 exec, exec, s[0:1]
	s_waitcnt lgkmcnt(0)
	v_lshlrev_b64 v[80:81], 11, v[194:195]
	v_add_f32_e32 v78, v78, v142
	v_add_f32_e32 v79, v79, v143
	v_add_f32_e32 v76, v76, v140
	v_add_f32_e32 v77, v77, v141
	v_lshl_add_u64 v[80:81], v[80:81], 0, v[188:189]
	global_store_dwordx4 v[196:197], v[76:79], off
	v_cvt_pk_bf16_f32 v82, v76, v77
	v_lshlrev_b64 v[80:81], 1, v[80:81]
	v_mul_f32_e32 v77, v77, v77
	v_fmac_f32_e32 v77, v76, v76
	v_mul_f32_e32 v76, v79, v79
	v_cvt_pk_bf16_f32 v83, v78, v79
	v_lshl_add_u64 v[84:85], s[70:71], 0, v[80:81]
	v_fmac_f32_e32 v76, v78, v78
	v_add_f32_e32 v74, v74, v138
	v_add_f32_e32 v75, v75, v139
	v_add_f32_e32 v72, v72, v136
	v_add_f32_e32 v73, v73, v137
	global_store_dwordx2 v[84:85], v[82:83], off
	v_add_f32_e32 v82, v77, v76
	global_store_dwordx4 v[196:197], v[72:75], off offset:64
	v_cvt_pk_bf16_f32 v76, v72, v73
	v_or_b32_e32 v78, 32, v80
	v_mul_f32_e32 v73, v73, v73
	v_fmac_f32_e32 v73, v72, v72
	v_mul_f32_e32 v72, v75, v75
	v_mov_b32_e32 v79, v81
	v_fmac_f32_e32 v72, v74, v74
	v_cvt_pk_bf16_f32 v77, v74, v75
	v_lshl_add_u64 v[78:79], s[70:71], 0, v[78:79]
	v_add_f32_e32 v72, v73, v72
	v_add_f32_e32 v70, v70, v134
	v_add_f32_e32 v71, v71, v135
	v_add_f32_e32 v68, v68, v132
	v_add_f32_e32 v69, v69, v133
	global_store_dwordx2 v[78:79], v[76:77], off
	v_add_f32_e32 v76, v82, v72
	global_store_dwordx4 v[196:197], v[68:71], off offset:512
	v_cvt_pk_bf16_f32 v72, v68, v69
	v_add_f32_e32 v66, v66, v130
	v_add_f32_e32 v67, v67, v131
	v_mul_f32_e32 v69, v69, v69
	v_fmac_f32_e32 v69, v68, v68
	v_mul_f32_e32 v68, v71, v71
	v_fmac_f32_e32 v68, v70, v70
	v_add_f32_e32 v64, v64, v128
	v_add_f32_e32 v65, v65, v129
	v_cvt_pk_bf16_f32 v73, v70, v71
	v_add_f32_e32 v68, v69, v68
	v_mul_f32_e32 v69, v65, v65
	v_mul_f32_e32 v70, v67, v67
	v_fmac_f32_e32 v69, v64, v64
	v_fmac_f32_e32 v70, v66, v66
	v_add_f32_e32 v68, v76, v68
	v_add_f32_e32 v69, v69, v70
	v_add_f32_e32 v70, v68, v69
	ds_bpermute_b32 v71, v226, v70
	v_or_b32_e32 v74, 0x100, v80
	v_mov_b32_e32 v75, v81
	v_lshl_add_u64 v[68:69], s[70:71], 0, v[74:75]
	global_store_dwordx2 v[68:69], v[72:73], off
	global_store_dwordx4 v[196:197], v[64:67], off offset:576
	v_cvt_pk_bf16_f32 v68, v64, v65
	v_or_b32_e32 v80, 0x120, v80
	s_waitcnt lgkmcnt(0)
	v_add_f32_e32 v64, v70, v71
	ds_bpermute_b32 v65, v227, v64
	v_cvt_pk_bf16_f32 v69, v66, v67
	v_lshl_add_u64 v[66:67], s[70:71], 0, v[80:81]
	global_store_dwordx2 v[66:67], v[68:69], off
	s_and_saveexec_b64 s[0:1], s[4:5]
	s_cbranch_execz .LBB0_1809
	v_lshl_add_u64 v[66:67], v[194:195], 2, s[12:13]
	s_waitcnt lgkmcnt(0)
	v_add_f32_e32 v64, v64, v65
	global_atomic_add_f32 v[66:67], v64, off
.LBB0_1809:
	s_or_b64 exec, exec, s[0:1]
	v_add_u32_e32 v124, 0x80, v192
	v_ashrrev_i32_e32 v125, 31, v124
	s_waitcnt lgkmcnt(0)
	v_lshlrev_b64 v[64:65], 13, v[124:125]
	v_lshl_add_u64 v[142:143], v[190:191], 0, v[64:65]
	global_load_dwordx4 v[126:129], v[142:143], off
	global_load_dwordx4 v[130:133], v[142:143], off offset:64
	global_load_dwordx4 v[134:137], v[142:143], off offset:512
	global_load_dwordx4 v[138:141], v[142:143], off offset:576
	v_add_u32_e32 v120, 0x90, v192
	v_add_u32_e32 v116, 0xa0, v192
	v_add_u32_e32 v112, 0xb0, v192
	v_ashrrev_i32_e32 v121, 31, v120
	v_ashrrev_i32_e32 v117, 31, v116
	v_ashrrev_i32_e32 v113, 31, v112
	v_lshlrev_b64 v[64:65], 13, v[120:121]
	v_lshlrev_b64 v[66:67], 13, v[116:117]
	v_lshlrev_b64 v[68:69], 13, v[112:113]
	v_lshl_add_u64 v[122:123], v[190:191], 0, v[64:65]
	v_lshl_add_u64 v[118:119], v[190:191], 0, v[66:67]
	v_lshl_add_u64 v[114:115], v[190:191], 0, v[68:69]
	global_load_dwordx4 v[108:111], v[122:123], off
	global_load_dwordx4 v[104:107], v[122:123], off offset:64
	global_load_dwordx4 v[100:103], v[122:123], off offset:512
	global_load_dwordx4 v[96:99], v[122:123], off offset:576
	global_load_dwordx4 v[92:95], v[118:119], off
	global_load_dwordx4 v[88:91], v[118:119], off offset:64
	global_load_dwordx4 v[84:87], v[118:119], off offset:512
	global_load_dwordx4 v[80:83], v[118:119], off offset:576
	global_load_dwordx4 v[76:79], v[114:115], off
	global_load_dwordx4 v[72:75], v[114:115], off offset:64
	global_load_dwordx4 v[68:71], v[114:115], off offset:512
	global_load_dwordx4 v[64:67], v[114:115], off offset:576
	v_lshlrev_b64 v[144:145], 11, v[124:125]
	v_lshl_add_u64 v[144:145], v[144:145], 0, v[188:189]
	v_lshlrev_b64 v[144:145], 1, v[144:145]
	v_lshl_add_u64 v[146:147], s[70:71], 0, v[144:145]
	v_or_b32_e32 v148, 32, v144
	v_mov_b32_e32 v149, v145
	v_lshl_add_u64 v[148:149], s[70:71], 0, v[148:149]
	v_or_b32_e32 v150, 0x100, v144
	v_mov_b32_e32 v151, v145
	v_or_b32_e32 v144, 0x120, v144
	s_waitcnt vmcnt(15)
	v_add_f32_e32 v62, v62, v128
	v_add_f32_e32 v63, v63, v129
	v_add_f32_e32 v60, v60, v126
	v_add_f32_e32 v61, v61, v127
	s_waitcnt vmcnt(14)
	v_add_f32_e32 v58, v58, v132
	v_add_f32_e32 v59, v59, v133
	v_add_f32_e32 v56, v56, v130
	v_add_f32_e32 v57, v57, v131
	s_waitcnt vmcnt(13)
	v_add_f32_e32 v54, v54, v136
	v_add_f32_e32 v55, v55, v137
	v_add_f32_e32 v52, v52, v134
	v_add_f32_e32 v53, v53, v135
	global_store_dwordx4 v[142:143], v[60:63], off
	v_cvt_pk_bf16_f32 v126, v60, v61
	v_cvt_pk_bf16_f32 v127, v62, v63
	v_mul_f32_e32 v61, v61, v61
	v_mul_f32_e32 v63, v63, v63
	v_mul_f32_e32 v132, v57, v57
	v_mul_f32_e32 v133, v59, v59
	s_waitcnt vmcnt(13)
	v_add_f32_e32 v50, v50, v140
	v_add_f32_e32 v51, v51, v141
	v_add_f32_e32 v48, v48, v138
	v_add_f32_e32 v49, v49, v139
	v_mul_f32_e32 v134, v53, v53
	v_mul_f32_e32 v135, v55, v55
	v_fmac_f32_e32 v61, v60, v60
	v_fmac_f32_e32 v63, v62, v62
	v_fmac_f32_e32 v132, v56, v56
	v_fmac_f32_e32 v133, v58, v58
	v_cvt_pk_bf16_f32 v128, v56, v57
	v_cvt_pk_bf16_f32 v129, v58, v59
	v_cvt_pk_bf16_f32 v130, v52, v53
	v_mul_f32_e32 v136, v49, v49
	v_mul_f32_e32 v137, v51, v51
	global_store_dwordx2 v[146:147], v[126:127], off
	global_store_dwordx4 v[142:143], v[56:59], off offset:64
	global_store_dwordx2 v[148:149], v[128:129], off
	global_store_dwordx4 v[142:143], v[52:55], off offset:512
	v_fmac_f32_e32 v134, v52, v52
	v_fmac_f32_e32 v135, v54, v54
	v_add_f32_e32 v52, v61, v63
	v_add_f32_e32 v53, v132, v133
	v_cvt_pk_bf16_f32 v131, v54, v55
	v_fmac_f32_e32 v136, v48, v48
	v_fmac_f32_e32 v137, v50, v50
	v_add_f32_e32 v54, v134, v135
	v_add_f32_e32 v52, v52, v53
	v_add_f32_e32 v52, v52, v54
	v_add_f32_e32 v53, v136, v137
	v_add_f32_e32 v54, v52, v53
	ds_bpermute_b32 v55, v226, v54
	v_lshl_add_u64 v[52:53], s[70:71], 0, v[150:151]
	global_store_dwordx2 v[52:53], v[130:131], off
	global_store_dwordx4 v[142:143], v[48:51], off offset:576
	v_cvt_pk_bf16_f32 v52, v48, v49
	v_cvt_pk_bf16_f32 v53, v50, v51
	s_waitcnt lgkmcnt(0)
	v_add_f32_e32 v48, v54, v55
	ds_bpermute_b32 v49, v227, v48
	v_lshl_add_u64 v[50:51], s[70:71], 0, v[144:145]
	global_store_dwordx2 v[50:51], v[52:53], off
	s_and_saveexec_b64 s[0:1], s[4:5]
	s_cbranch_execz .LBB0_1811
	v_lshl_add_u64 v[50:51], v[124:125], 2, s[12:13]
	s_waitcnt lgkmcnt(0)
	v_add_f32_e32 v48, v48, v49
	global_atomic_add_f32 v[50:51], v48, off
; __device__ __forceinline__ unsigned pkbf(float lo, float hi) { const f32x2_m v = {lo, hi}; const bf16x2_m b = __builtin_convertvector(v, bf16x2_m); return __builtin_bit_cast(unsigned, b); }
;     __device__ __forceinline__ void operator()(const f32x4 (&acc)[2][2][4][2], const Unit& u, int wr, int wc, int fr, int fq) const {
;     ...
;             for (int m = 0; m < 4; ++m) { const int row = row0 + ai * HALF + m * 16; const size_t off = (size_t)row * ldc + col0; float sq = 0.f;
; #pragma unroll
;                 for (int bj = 0; bj < 2; ++bj)
; #pragma unroll
;                     for (int n = 0; n < 2; ++n) { const size_t p = off + bj * HALF + n * 16; const f32x4 o = pre[m][bj][n] + acc[ai][bj][m][n] * scale; *(f32x4*)(out + p) = o;
;                         if (NORM == 1) *(v2u*)(xb + p) = (v2u){pkbf(o[0], o[1]), pkbf(o[2], o[3])};
;                         if (NORM) sq += (o[0] * o[0] + o[1] * o[1]) + (o[2] * o[2] + o[3] * o[3]); }
;                 if (NORM) { sq += __shfl_xor(sq, 16); sq += __shfl_xor(sq, 32); if (fq == 0) __hip_atomic_fetch_add(ss + row, sq, __ATOMIC_RELAXED, __HIP_MEMORY_SCOPE_AGENT); } } }
.LBB0_1811:
	s_or_b64 exec, exec, s[0:1]
	s_waitcnt lgkmcnt(0)
	v_lshlrev_b64 v[48:49], 11, v[120:121]
	s_waitcnt vmcnt(19)
	v_add_f32_e32 v46, v46, v110
	v_add_f32_e32 v47, v47, v111
	v_add_f32_e32 v44, v44, v108
	v_add_f32_e32 v45, v45, v109
	v_lshl_add_u64 v[48:49], v[48:49], 0, v[188:189]
	global_store_dwordx4 v[122:123], v[44:47], off
	v_cvt_pk_bf16_f32 v50, v44, v45
	v_lshlrev_b64 v[48:49], 1, v[48:49]
	v_mul_f32_e32 v45, v45, v45
	v_fmac_f32_e32 v45, v44, v44
	v_mul_f32_e32 v44, v47, v47
	v_cvt_pk_bf16_f32 v51, v46, v47
	v_lshl_add_u64 v[52:53], s[70:71], 0, v[48:49]
	v_fmac_f32_e32 v44, v46, v46
	s_waitcnt vmcnt(19)
	v_add_f32_e32 v42, v42, v106
	v_add_f32_e32 v43, v43, v107
	v_add_f32_e32 v40, v40, v104
	v_add_f32_e32 v41, v41, v105
	global_store_dwordx2 v[52:53], v[50:51], off
	v_add_f32_e32 v50, v45, v44
	global_store_dwordx4 v[122:123], v[40:43], off offset:64
	v_cvt_pk_bf16_f32 v44, v40, v41
	v_or_b32_e32 v46, 32, v48
	v_mul_f32_e32 v41, v41, v41
	v_fmac_f32_e32 v41, v40, v40
	v_mul_f32_e32 v40, v43, v43
	v_mov_b32_e32 v47, v49
	v_fmac_f32_e32 v40, v42, v42
	v_cvt_pk_bf16_f32 v45, v42, v43
	v_lshl_add_u64 v[46:47], s[70:71], 0, v[46:47]
	v_add_f32_e32 v40, v41, v40
	s_waitcnt vmcnt(20)
	v_add_f32_e32 v38, v38, v102
	v_add_f32_e32 v39, v39, v103
	v_add_f32_e32 v36, v36, v100
	v_add_f32_e32 v37, v37, v101
	global_store_dwordx2 v[46:47], v[44:45], off
	v_add_f32_e32 v44, v50, v40
	global_store_dwordx4 v[122:123], v[36:39], off offset:512
	v_cvt_pk_bf16_f32 v40, v36, v37
	s_waitcnt vmcnt(21)
	v_add_f32_e32 v34, v34, v98
	v_add_f32_e32 v35, v35, v99
	v_mul_f32_e32 v37, v37, v37
	v_fmac_f32_e32 v37, v36, v36
	v_mul_f32_e32 v36, v39, v39
	v_fmac_f32_e32 v36, v38, v38
	v_add_f32_e32 v32, v32, v96
	v_add_f32_e32 v33, v33, v97
	v_cvt_pk_bf16_f32 v41, v38, v39
	v_add_f32_e32 v36, v37, v36
	v_mul_f32_e32 v37, v33, v33
	v_mul_f32_e32 v38, v35, v35
	v_fmac_f32_e32 v37, v32, v32
	v_fmac_f32_e32 v38, v34, v34
	v_add_f32_e32 v36, v44, v36
	v_add_f32_e32 v37, v37, v38
	v_add_f32_e32 v38, v36, v37
	ds_bpermute_b32 v39, v226, v38
	v_or_b32_e32 v42, 0x100, v48
	v_mov_b32_e32 v43, v49
	v_lshl_add_u64 v[36:37], s[70:71], 0, v[42:43]
	global_store_dwordx2 v[36:37], v[40:41], off
	global_store_dwordx4 v[122:123], v[32:35], off offset:576
	v_cvt_pk_bf16_f32 v36, v32, v33
	v_or_b32_e32 v48, 0x120, v48
	s_waitcnt lgkmcnt(0)
	v_add_f32_e32 v32, v38, v39
	ds_bpermute_b32 v33, v227, v32
	v_cvt_pk_bf16_f32 v37, v34, v35
	v_lshl_add_u64 v[34:35], s[70:71], 0, v[48:49]
	global_store_dwordx2 v[34:35], v[36:37], off
	s_and_saveexec_b64 s[0:1], s[4:5]
	s_cbranch_execz .LBB0_1813
	v_lshl_add_u64 v[34:35], v[120:121], 2, s[12:13]
	s_waitcnt lgkmcnt(0)
	v_add_f32_e32 v32, v32, v33
	global_atomic_add_f32 v[34:35], v32, off
; __device__ __forceinline__ unsigned pkbf(float lo, float hi) { const f32x2_m v = {lo, hi}; const bf16x2_m b = __builtin_convertvector(v, bf16x2_m); return __builtin_bit_cast(unsigned, b); }
;     __device__ __forceinline__ void operator()(const f32x4 (&acc)[2][2][4][2], const Unit& u, int wr, int wc, int fr, int fq) const {
;     ...
;             for (int m = 0; m < 4; ++m) { const int row = row0 + ai * HALF + m * 16; const size_t off = (size_t)row * ldc + col0; float sq = 0.f;
; #pragma unroll
;                 for (int bj = 0; bj < 2; ++bj)
; #pragma unroll
;                     for (int n = 0; n < 2; ++n) { const size_t p = off + bj * HALF + n * 16; const f32x4 o = pre[m][bj][n] + acc[ai][bj][m][n] * scale; *(f32x4*)(out + p) = o;
;                         if (NORM == 1) *(v2u*)(xb + p) = (v2u){pkbf(o[0], o[1]), pkbf(o[2], o[3])};
;                         if (NORM) sq += (o[0] * o[0] + o[1] * o[1]) + (o[2] * o[2] + o[3] * o[3]); }
;                 if (NORM) { sq += __shfl_xor(sq, 16); sq += __shfl_xor(sq, 32); if (fq == 0) __hip_atomic_fetch_add(ss + row, sq, __ATOMIC_RELAXED, __HIP_MEMORY_SCOPE_AGENT); } } }
.LBB0_1813:
	s_or_b64 exec, exec, s[0:1]
	s_waitcnt lgkmcnt(0)
	v_lshlrev_b64 v[32:33], 11, v[116:117]
	s_waitcnt vmcnt(23)
	v_add_f32_e32 v30, v30, v94
	v_add_f32_e32 v31, v31, v95
	v_add_f32_e32 v28, v28, v92
	v_add_f32_e32 v29, v29, v93
	v_lshl_add_u64 v[32:33], v[32:33], 0, v[188:189]
	global_store_dwordx4 v[118:119], v[28:31], off
	v_cvt_pk_bf16_f32 v34, v28, v29
	v_lshlrev_b64 v[32:33], 1, v[32:33]
	v_mul_f32_e32 v29, v29, v29
	v_fmac_f32_e32 v29, v28, v28
	v_mul_f32_e32 v28, v31, v31
	v_cvt_pk_bf16_f32 v35, v30, v31
	v_lshl_add_u64 v[36:37], s[70:71], 0, v[32:33]
	v_fmac_f32_e32 v28, v30, v30
	s_waitcnt vmcnt(23)
	v_add_f32_e32 v26, v26, v90
	v_add_f32_e32 v27, v27, v91
	v_add_f32_e32 v24, v24, v88
	v_add_f32_e32 v25, v25, v89
	global_store_dwordx2 v[36:37], v[34:35], off
	v_add_f32_e32 v34, v29, v28
	global_store_dwordx4 v[118:119], v[24:27], off offset:64
	v_cvt_pk_bf16_f32 v28, v24, v25
	v_or_b32_e32 v30, 32, v32
	v_mul_f32_e32 v25, v25, v25
	v_fmac_f32_e32 v25, v24, v24
	v_mul_f32_e32 v24, v27, v27
	v_mov_b32_e32 v31, v33
	v_fmac_f32_e32 v24, v26, v26
	v_cvt_pk_bf16_f32 v29, v26, v27
	v_lshl_add_u64 v[30:31], s[70:71], 0, v[30:31]
	v_add_f32_e32 v24, v25, v24
	s_waitcnt vmcnt(24)
	v_add_f32_e32 v22, v22, v86
	v_add_f32_e32 v23, v23, v87
	v_add_f32_e32 v20, v20, v84
	v_add_f32_e32 v21, v21, v85
	global_store_dwordx2 v[30:31], v[28:29], off
	v_add_f32_e32 v28, v34, v24
	global_store_dwordx4 v[118:119], v[20:23], off offset:512
	v_cvt_pk_bf16_f32 v24, v20, v21
	s_waitcnt vmcnt(25)
	v_add_f32_e32 v18, v18, v82
	v_add_f32_e32 v19, v19, v83
	v_mul_f32_e32 v21, v21, v21
	v_fmac_f32_e32 v21, v20, v20
	v_mul_f32_e32 v20, v23, v23
	v_fmac_f32_e32 v20, v22, v22
	v_add_f32_e32 v16, v16, v80
	v_add_f32_e32 v17, v17, v81
	v_cvt_pk_bf16_f32 v25, v22, v23
	v_add_f32_e32 v20, v21, v20
	v_mul_f32_e32 v21, v17, v17
	v_mul_f32_e32 v22, v19, v19
	v_fmac_f32_e32 v21, v16, v16
	v_fmac_f32_e32 v22, v18, v18
	v_add_f32_e32 v20, v28, v20
	v_add_f32_e32 v21, v21, v22
	v_add_f32_e32 v22, v20, v21
	ds_bpermute_b32 v23, v226, v22
	v_or_b32_e32 v26, 0x100, v32
	v_mov_b32_e32 v27, v33
	v_lshl_add_u64 v[20:21], s[70:71], 0, v[26:27]
	global_store_dwordx2 v[20:21], v[24:25], off
	global_store_dwordx4 v[118:119], v[16:19], off offset:576
	v_cvt_pk_bf16_f32 v20, v16, v17
	v_or_b32_e32 v32, 0x120, v32
	s_waitcnt lgkmcnt(0)
	v_add_f32_e32 v16, v22, v23
	ds_bpermute_b32 v17, v227, v16
	v_cvt_pk_bf16_f32 v21, v18, v19
	v_lshl_add_u64 v[18:19], s[70:71], 0, v[32:33]
	global_store_dwordx2 v[18:19], v[20:21], off
	s_and_saveexec_b64 s[0:1], s[4:5]
	s_cbranch_execz .LBB0_1815
	v_lshl_add_u64 v[18:19], v[116:117], 2, s[12:13]
	s_waitcnt lgkmcnt(0)
	v_add_f32_e32 v16, v16, v17
	global_atomic_add_f32 v[18:19], v16, off
.LBB0_1815:
	s_or_b64 exec, exec, s[0:1]
	s_waitcnt lgkmcnt(0)
	v_lshlrev_b64 v[16:17], 11, v[112:113]
	s_waitcnt vmcnt(27)
	v_add_f32_e32 v14, v14, v78
	v_add_f32_e32 v15, v15, v79
	v_add_f32_e32 v12, v12, v76
	v_add_f32_e32 v13, v13, v77
	v_lshl_add_u64 v[16:17], v[16:17], 0, v[188:189]
	global_store_dwordx4 v[114:115], v[12:15], off
	v_cvt_pk_bf16_f32 v18, v12, v13
	v_lshlrev_b64 v[16:17], 1, v[16:17]
	v_mul_f32_e32 v13, v13, v13
	v_fmac_f32_e32 v13, v12, v12
	v_mul_f32_e32 v12, v15, v15
	v_cvt_pk_bf16_f32 v19, v14, v15
	v_lshl_add_u64 v[20:21], s[70:71], 0, v[16:17]
	v_fmac_f32_e32 v12, v14, v14
	s_waitcnt vmcnt(27)
	v_add_f32_e32 v10, v10, v74
	v_add_f32_e32 v11, v11, v75
	v_add_f32_e32 v8, v8, v72
	v_add_f32_e32 v9, v9, v73
	global_store_dwordx2 v[20:21], v[18:19], off
	v_add_f32_e32 v18, v13, v12
	global_store_dwordx4 v[114:115], v[8:11], off offset:64
	v_cvt_pk_bf16_f32 v12, v8, v9
	v_or_b32_e32 v14, 32, v16
	v_mul_f32_e32 v9, v9, v9
	v_fmac_f32_e32 v9, v8, v8
	v_mul_f32_e32 v8, v11, v11
	v_mov_b32_e32 v15, v17
	v_fmac_f32_e32 v8, v10, v10
	v_cvt_pk_bf16_f32 v13, v10, v11
	v_lshl_add_u64 v[14:15], s[70:71], 0, v[14:15]
	v_add_f32_e32 v8, v9, v8
	s_waitcnt vmcnt(28)
	v_add_f32_e32 v6, v6, v70
	v_add_f32_e32 v7, v7, v71
	v_add_f32_e32 v4, v4, v68
	v_add_f32_e32 v5, v5, v69
	global_store_dwordx2 v[14:15], v[12:13], off
	v_add_f32_e32 v12, v18, v8
	global_store_dwordx4 v[114:115], v[4:7], off offset:512
	v_cvt_pk_bf16_f32 v8, v4, v5
	s_waitcnt vmcnt(29)
	v_add_f32_e32 v2, v2, v66
	v_add_f32_e32 v3, v3, v67
	v_mul_f32_e32 v5, v5, v5
	v_fmac_f32_e32 v5, v4, v4
	v_mul_f32_e32 v4, v7, v7
	v_fmac_f32_e32 v4, v6, v6
	v_add_f32_e32 v0, v0, v64
	v_add_f32_e32 v1, v1, v65
	v_cvt_pk_bf16_f32 v9, v6, v7
	v_add_f32_e32 v4, v5, v4
	v_mul_f32_e32 v5, v1, v1
	v_mul_f32_e32 v6, v3, v3
	v_fmac_f32_e32 v5, v0, v0
	v_fmac_f32_e32 v6, v2, v2
	v_add_f32_e32 v4, v12, v4
	v_add_f32_e32 v5, v5, v6
	v_add_f32_e32 v6, v4, v5
	ds_bpermute_b32 v7, v226, v6
	v_or_b32_e32 v10, 0x100, v16
	v_mov_b32_e32 v11, v17
	v_lshl_add_u64 v[4:5], s[70:71], 0, v[10:11]
	global_store_dwordx2 v[4:5], v[8:9], off
	global_store_dwordx4 v[114:115], v[0:3], off offset:576
	v_cvt_pk_bf16_f32 v4, v0, v1
	v_or_b32_e32 v16, 0x120, v16
	s_waitcnt lgkmcnt(0)
	v_add_f32_e32 v0, v6, v7
	ds_bpermute_b32 v1, v227, v0
	v_cvt_pk_bf16_f32 v5, v2, v3
	v_lshl_add_u64 v[2:3], s[70:71], 0, v[16:17]
	global_store_dwordx2 v[2:3], v[4:5], off
	s_and_saveexec_b64 s[0:1], s[4:5]
	s_cbranch_execz .LBB0_1817
	v_lshl_add_u64 v[2:3], v[112:113], 2, s[12:13]
	s_waitcnt lgkmcnt(0)
	v_add_f32_e32 v0, v0, v1
	global_atomic_add_f32 v[2:3], v0, off

; __device__ __forceinline__ float silu(float x) { return x * sigm(x); }
; __device__ __forceinline__ unsigned pkbf(float lo, float hi) { const f32x2_m v = {lo, hi}; const bf16x2_m b = __builtin_convertvector(v, bf16x2_m); return __builtin_bit_cast(unsigned, b); }
; template <int RSM> __device__ __forceinline__ float row_scale(const float* p, int row) { const float v = __hip_atomic_load(p + row, __ATOMIC_RELAXED, __HIP_MEMORY_SCOPE_AGENT); return RSM == 0 ? v : 1.0f / sqrtf(v * (1.f / DM) + EPS); }
;     __device__ __forceinline__ void operator()(const f32x4 (&acc)[2][2][4][2], const Unit& u, int wr, int wc, int fr, int fq) const {
;         const int row0 = u.pm * BM + wr * 64 + fr, col0 = u.pn * HALF + wc * 32 + 8 * fq;
; #pragma unroll
;         for (int ai = 0; ai < 2; ++ai)
; #pragma unroll
;             for (int m = 0; m < 4; ++m) { const int row = row0 + ai * HALF + m * 16; bf16* rowp = O + (size_t)row * ldc + col0; const float sc = row_scale<RSM>(rs, row);
;                 const f32x4 g0 = acc[ai][0][m][0] * sc, g1 = acc[ai][0][m][1] * sc, u0 = acc[ai][1][m][0] * sc, u1 = acc[ai][1][m][1] * sc;
;                 v4u w; w.x = pkbf(silu(g0[0]) * u0[0], silu(g0[1]) * u0[1]); w.y = pkbf(silu(g0[2]) * u0[2], silu(g0[3]) * u0[3]);
;                 w.z = pkbf(silu(g1[0]) * u1[0], silu(g1[1]) * u1[1]); w.w = pkbf(silu(g1[2]) * u1[2], silu(g1[3]) * u1[3]);
;                 *(v4u*)rowp = w; }
.LBB0_1885:
	v_lshl_add_u32 v144, s6, 8, v152
	v_ashrrev_i32_e32 v145, 31, v144
	v_lshl_add_u64 v[150:151], v[144:145], 2, s[12:13]
	global_load_dword v245, v[150:151], off sc1
	global_load_dword v246, v[150:151], off offset:64 sc1
	global_load_dword v247, v[150:151], off offset:128 sc1
	global_load_dword v248, v[150:151], off offset:192 sc1
	global_load_dword v249, v[150:151], off offset:512 sc1
	global_load_dword v251, v[150:151], off offset:576 sc1
	global_load_dword v252, v[150:151], off offset:640 sc1
	global_load_dword v253, v[150:151], off offset:704 sc1
	v_bfe_u32 v163, v222, 4, 1
	v_cmp_ne_u32_e64 s[98:99], 0, v163
	v_bfe_u32 v163, v222, 5, 1
	v_cmp_ne_u32_e64 s[100:101], 0, v163
	v_and_b32_e32 v145, 15, v222
	v_lshlrev_b32_e32 v145, 2, v145
	s_waitcnt vmcnt(0)
	v_cndmask_b32_e64 v245, v245, v247, s[98:99]
	v_cndmask_b32_e64 v249, v249, v252, s[98:99]
	v_cndmask_b32_e64 v245, v245, v249, s[100:101]
	v_cndmask_b32_e64 v246, v246, v248, s[98:99]
	v_cndmask_b32_e64 v251, v251, v253, s[98:99]
	v_cndmask_b32_e64 v246, v246, v251, s[100:101]
	v_fmamk_f32 v245, v245, 0x3a000000, v158
	v_mul_f32_e32 v163, 0x4f800000, v245
	v_cmp_gt_f32_e32 vcc, s50, v245
	s_nop 1
	v_cndmask_b32_e32 v245, v245, v163, vcc
	v_sqrt_f32_e32 v164, v245
	s_nop 0
	v_add_u32_e32 v165, -1, v164
	v_add_u32_e32 v166, 1, v164
	v_fma_f32 v167, -v165, v164, v245
	v_fma_f32 v168, -v166, v164, v245
	v_cmp_ge_f32_e64 s[98:99], 0, v167
	s_nop 1
	v_cndmask_b32_e64 v164, v164, v165, s[98:99]
	v_cmp_lt_f32_e64 s[98:99], 0, v168
	s_nop 1
	v_cndmask_b32_e64 v164, v164, v166, s[98:99]
	v_mul_f32_e32 v165, 0x37800000, v164
	v_cndmask_b32_e32 v164, v164, v165, vcc
	v_cmp_class_f32_e32 vcc, v245, v159
	s_nop 1
	v_cndmask_b32_e32 v245, v164, v245, vcc
	v_div_scale_f32 v166, s[100:101], v245, v245, 1.0
	v_rcp_f32_e32 v167, v166
	v_div_scale_f32 v163, vcc, 1.0, v245, 1.0
	v_fma_f32 v168, -v166, v167, 1.0
	v_fmac_f32_e32 v167, v168, v167
	v_mul_f32_e32 v168, v163, v167
	v_fma_f32 v169, -v166, v168, v163
	v_fmac_f32_e32 v168, v169, v167
	v_fma_f32 v163, -v166, v168, v163
	v_div_fmas_f32 v163, v163, v167, v168
	v_div_fixup_f32 v245, v163, v245, 1.0
	v_fmamk_f32 v246, v246, 0x3a000000, v158
	v_mul_f32_e32 v163, 0x4f800000, v246
	v_cmp_gt_f32_e32 vcc, s50, v246
	s_nop 1
	v_cndmask_b32_e32 v246, v246, v163, vcc
	v_sqrt_f32_e32 v164, v246
	s_nop 0
	v_add_u32_e32 v165, -1, v164
	v_add_u32_e32 v166, 1, v164
	v_fma_f32 v167, -v165, v164, v246
	v_fma_f32 v168, -v166, v164, v246
	v_cmp_ge_f32_e64 s[98:99], 0, v167
	s_nop 1
	v_cndmask_b32_e64 v164, v164, v165, s[98:99]
	v_cmp_lt_f32_e64 s[98:99], 0, v168
	s_nop 1
	v_cndmask_b32_e64 v164, v164, v166, s[98:99]
	v_mul_f32_e32 v165, 0x37800000, v164
	v_cndmask_b32_e32 v164, v164, v165, vcc
	v_cmp_class_f32_e32 vcc, v246, v159
	s_nop 1
	v_cndmask_b32_e32 v246, v164, v246, vcc
	v_div_scale_f32 v166, s[100:101], v246, v246, 1.0
	v_rcp_f32_e32 v167, v166
	v_div_scale_f32 v163, vcc, 1.0, v246, 1.0
	v_fma_f32 v168, -v166, v167, 1.0
	v_fmac_f32_e32 v167, v168, v167
	v_mul_f32_e32 v168, v163, v167
	v_fma_f32 v169, -v166, v168, v163
	v_fmac_f32_e32 v168, v169, v167
	v_fma_f32 v163, -v166, v168, v163
	v_div_fmas_f32 v163, v163, v167, v168
	v_div_fixup_f32 v246, v163, v246, 1.0
	ds_bpermute_b32 v247, v145, v245
	ds_bpermute_b32 v248, v145, v246
	ds_bpermute_b32 v249, v145, v245 offset:64
	ds_bpermute_b32 v251, v145, v246 offset:64
	ds_bpermute_b32 v252, v145, v245 offset:128
	ds_bpermute_b32 v253, v145, v246 offset:128
	ds_bpermute_b32 v254, v145, v245 offset:192
	ds_bpermute_b32 v255, v145, v246 offset:192
	s_waitcnt lgkmcnt(0)
	v_lshl_or_b32 v148, s7, 7, v154
	v_or_b32_e32 v162, 16, v144
	v_mov_b64_e32 v[146:147], s[26:27]
	v_ashrrev_i32_e32 v149, 31, v148
	v_mad_i64_i32 v[160:161], s[0:1], v144, s47, v[146:147]
	v_lshlrev_b64 v[148:149], 1, v[148:149]
	v_lshl_add_u64 v[160:161], v[160:161], 0, v[148:149]
	v_ashrrev_i32_e32 v163, 31, v162
	v_lshl_add_u64 v[164:165], v[162:163], 2, s[12:13]
	v_mov_b32_e32 v166, v247
	v_mul_f32_e32 v126, v126, v166
	v_mul_f32_e32 v127, v127, v166
	v_mul_f32_e32 v124, v124, v166
	v_mul_f32_e32 v125, v125, v166
	v_mul_f32_e32 v122, v122, v166
	v_mul_f32_e32 v123, v123, v166
	v_mul_f32_e32 v120, v120, v166
	v_mul_f32_e32 v121, v121, v166
	v_mul_f32_e32 v118, v118, v166
	v_mul_f32_e32 v119, v119, v166
	v_mul_f32_e32 v116, v116, v166
	v_mul_f32_e32 v117, v117, v166
	v_mul_f32_e32 v114, v114, v166
	v_mul_f32_e32 v115, v115, v166
	v_mul_f32_e32 v112, v112, v166
	v_mul_f32_e32 v113, v113, v166
	v_mul_f32_e32 v145, 0xbfb8aa3b, v124
	v_mul_f32_e32 v163, 0xbfb8aa3b, v125
	v_mul_f32_e32 v166, 0xbfb8aa3b, v126
	v_mul_f32_e32 v167, 0xbfb8aa3b, v127
	v_mul_f32_e32 v168, 0xbfb8aa3b, v120
	v_mul_f32_e32 v169, 0xbfb8aa3b, v121
	v_mul_f32_e32 v170, 0xbfb8aa3b, v122
	v_mul_f32_e32 v171, 0xbfb8aa3b, v123
	v_exp_f32_e32 v145, v145
	v_exp_f32_e32 v163, v163
	v_exp_f32_e32 v166, v166
	v_exp_f32_e32 v167, v167
	v_exp_f32_e32 v168, v168
	v_exp_f32_e32 v169, v169
	v_exp_f32_e32 v170, v170
	v_exp_f32_e32 v171, v171
	v_add_f32_e32 v145, 1.0, v145
	v_add_f32_e32 v163, 1.0, v163
	v_add_f32_e32 v172, 1.0, v166
	v_add_f32_e32 v173, 1.0, v167
	v_add_f32_e32 v174, 1.0, v168
	v_add_f32_e32 v175, 1.0, v169
	v_add_f32_e32 v176, 1.0, v170
	v_add_f32_e32 v177, 1.0, v171
	v_rcp_f32_e32 v166, v145
	v_rcp_f32_e32 v167, v163
	v_rcp_f32_e32 v168, v172
	v_rcp_f32_e32 v169, v173
	v_rcp_f32_e32 v170, v174
	v_rcp_f32_e32 v171, v175
	v_rcp_f32_e32 v172, v176
	v_rcp_f32_e32 v173, v177
	v_mul_f32_e32 v124, v124, v166
	v_mul_f32_e32 v125, v125, v167
	v_mul_f32_e32 v126, v126, v168
	v_mul_f32_e32 v127, v127, v169
	v_mul_f32_e32 v120, v120, v170
	v_mul_f32_e32 v121, v121, v171
; __device__ __forceinline__ float silu(float x) { return x * sigm(x); }
; __device__ __forceinline__ unsigned pkbf(float lo, float hi) { const f32x2_m v = {lo, hi}; const bf16x2_m b = __builtin_convertvector(v, bf16x2_m); return __builtin_bit_cast(unsigned, b); }
; template <int RSM> __device__ __forceinline__ float row_scale(const float* p, int row) { const float v = __hip_atomic_load(p + row, __ATOMIC_RELAXED, __HIP_MEMORY_SCOPE_AGENT); return RSM == 0 ? v : 1.0f / sqrtf(v * (1.f / DM) + EPS); }
;     __device__ __forceinline__ void operator()(const f32x4 (&acc)[2][2][4][2], const Unit& u, int wr, int wc, int fr, int fq) const {
;     ...
;             for (int m = 0; m < 4; ++m) { const int row = row0 + ai * HALF + m * 16; bf16* rowp = O + (size_t)row * ldc + col0; const float sc = row_scale<RSM>(rs, row);
;                 const f32x4 g0 = acc[ai][0][m][0] * sc, g1 = acc[ai][0][m][1] * sc, u0 = acc[ai][1][m][0] * sc, u1 = acc[ai][1][m][1] * sc;
;                 v4u w; w.x = pkbf(silu(g0[0]) * u0[0], silu(g0[1]) * u0[1]); w.y = pkbf(silu(g0[2]) * u0[2], silu(g0[3]) * u0[3]);
;                 w.z = pkbf(silu(g1[0]) * u1[0], silu(g1[1]) * u1[1]); w.w = pkbf(silu(g1[2]) * u1[2], silu(g1[3]) * u1[3]);
;                 *(v4u*)rowp = w; }
	v_mul_f32_e32 v122, v122, v172
	v_mul_f32_e32 v123, v123, v173
	v_mul_f32_e32 v116, v116, v124
	v_mul_f32_e32 v117, v117, v125
	v_mul_f32_e32 v118, v118, v126
	v_mul_f32_e32 v119, v119, v127
	v_mul_f32_e32 v120, v112, v120
	v_mul_f32_e32 v121, v113, v121
	v_mul_f32_e32 v122, v114, v122
	v_mul_f32_e32 v123, v115, v123
	v_cvt_pk_bf16_f32 v112, v116, v117
	v_cvt_pk_bf16_f32 v113, v118, v119
	v_cvt_pk_bf16_f32 v114, v120, v121
	v_cvt_pk_bf16_f32 v115, v122, v123
	global_store_dwordx4 v[160:161], v[112:115], off
	s_nop 1
	v_or_b32_e32 v112, 32, v144
	v_ashrrev_i32_e32 v113, 31, v112
	v_mad_i64_i32 v[114:115], s[0:1], v162, s47, v[146:147]
	v_lshl_add_u64 v[114:115], v[114:115], 0, v[148:149]
	s_nop 0
	v_lshl_add_u64 v[116:117], v[112:113], 2, s[12:13]
	v_mov_b32_e32 v118, v248
	v_mul_f32_e32 v110, v110, v118
	v_mul_f32_e32 v111, v111, v118
	v_mul_f32_e32 v108, v108, v118
	v_mul_f32_e32 v109, v109, v118
	v_mul_f32_e32 v106, v106, v118
	v_mul_f32_e32 v107, v107, v118
	v_mul_f32_e32 v104, v104, v118
	v_mul_f32_e32 v105, v105, v118
	v_mul_f32_e32 v102, v102, v118
	v_mul_f32_e32 v103, v103, v118
	v_mul_f32_e32 v100, v100, v118
	v_mul_f32_e32 v101, v101, v118
	v_mul_f32_e32 v98, v98, v118
	v_mul_f32_e32 v99, v99, v118
	v_mul_f32_e32 v96, v96, v118
	v_mul_f32_e32 v97, v97, v118
	v_mul_f32_e32 v113, 0xbfb8aa3b, v108
	v_mul_f32_e32 v118, 0xbfb8aa3b, v109
	v_mul_f32_e32 v119, 0xbfb8aa3b, v110
	v_mul_f32_e32 v120, 0xbfb8aa3b, v111
	v_mul_f32_e32 v121, 0xbfb8aa3b, v104
	v_mul_f32_e32 v122, 0xbfb8aa3b, v105
	v_mul_f32_e32 v123, 0xbfb8aa3b, v106
	v_mul_f32_e32 v124, 0xbfb8aa3b, v107
	v_exp_f32_e32 v113, v113
	v_exp_f32_e32 v118, v118
	v_exp_f32_e32 v119, v119
	v_exp_f32_e32 v120, v120
	v_exp_f32_e32 v121, v121
	v_exp_f32_e32 v122, v122
	v_exp_f32_e32 v123, v123
	v_exp_f32_e32 v124, v124
	v_add_f32_e32 v113, 1.0, v113
	v_add_f32_e32 v125, 1.0, v118
	v_add_f32_e32 v126, 1.0, v119
	v_add_f32_e32 v127, 1.0, v120
	v_add_f32_e32 v145, 1.0, v121
	v_add_f32_e32 v160, 1.0, v122
	v_add_f32_e32 v161, 1.0, v123
	v_add_f32_e32 v162, 1.0, v124
	v_rcp_f32_e32 v118, v113
	v_rcp_f32_e32 v119, v125
	v_rcp_f32_e32 v120, v126
	v_rcp_f32_e32 v121, v127
	v_rcp_f32_e32 v122, v145
	v_rcp_f32_e32 v123, v160
	v_rcp_f32_e32 v124, v161
	v_rcp_f32_e32 v125, v162
	v_mul_f32_e32 v108, v108, v118
	v_mul_f32_e32 v109, v109, v119
	v_mul_f32_e32 v110, v110, v120
	v_mul_f32_e32 v111, v111, v121
	v_mul_f32_e32 v104, v104, v122
	v_mul_f32_e32 v105, v105, v123
	v_mul_f32_e32 v106, v106, v124
	v_mul_f32_e32 v107, v107, v125
	v_mul_f32_e32 v100, v100, v108
	v_mul_f32_e32 v101, v101, v109
	v_mul_f32_e32 v102, v102, v110
	v_mul_f32_e32 v103, v103, v111
	v_mul_f32_e32 v104, v96, v104
	v_mul_f32_e32 v105, v97, v105
	v_mul_f32_e32 v106, v98, v106
	v_mul_f32_e32 v107, v99, v107
	v_cvt_pk_bf16_f32 v96, v100, v101
	v_cvt_pk_bf16_f32 v97, v102, v103
	v_cvt_pk_bf16_f32 v98, v104, v105
	v_cvt_pk_bf16_f32 v99, v106, v107
	global_store_dwordx4 v[114:115], v[96:99], off
	s_nop 1
	v_or_b32_e32 v96, 48, v144
	v_ashrrev_i32_e32 v97, 31, v96
	v_mad_i64_i32 v[98:99], s[0:1], v112, s47, v[146:147]
	v_lshl_add_u64 v[98:99], v[98:99], 0, v[148:149]
	s_nop 0
	v_lshl_add_u64 v[100:101], v[96:97], 2, s[12:13]
	v_mov_b32_e32 v102, v249
	v_mul_f32_e32 v94, v94, v102
	v_mul_f32_e32 v95, v95, v102
	v_mul_f32_e32 v92, v92, v102
	v_mul_f32_e32 v93, v93, v102
	v_mul_f32_e32 v90, v90, v102
	v_mul_f32_e32 v91, v91, v102
	v_mul_f32_e32 v88, v88, v102
	v_mul_f32_e32 v89, v89, v102
	v_mul_f32_e32 v86, v86, v102
	v_mul_f32_e32 v87, v87, v102
	v_mul_f32_e32 v84, v84, v102
	v_mul_f32_e32 v85, v85, v102
	v_mul_f32_e32 v82, v82, v102
	v_mul_f32_e32 v83, v83, v102
	v_mul_f32_e32 v80, v80, v102
	v_mul_f32_e32 v81, v81, v102
	v_mul_f32_e32 v97, 0xbfb8aa3b, v92
	v_mul_f32_e32 v102, 0xbfb8aa3b, v93
	v_mul_f32_e32 v103, 0xbfb8aa3b, v94
	v_mul_f32_e32 v104, 0xbfb8aa3b, v95
	v_mul_f32_e32 v105, 0xbfb8aa3b, v88
	v_mul_f32_e32 v106, 0xbfb8aa3b, v89
	v_mul_f32_e32 v107, 0xbfb8aa3b, v90
	v_mul_f32_e32 v108, 0xbfb8aa3b, v91
	v_exp_f32_e32 v97, v97
	v_exp_f32_e32 v102, v102
	v_exp_f32_e32 v103, v103
	v_exp_f32_e32 v104, v104
	v_exp_f32_e32 v105, v105
	v_exp_f32_e32 v106, v106
	v_exp_f32_e32 v107, v107
	v_exp_f32_e32 v108, v108
	v_add_f32_e32 v97, 1.0, v97
	v_add_f32_e32 v109, 1.0, v102
	v_add_f32_e32 v110, 1.0, v103
	v_add_f32_e32 v111, 1.0, v104
	v_add_f32_e32 v112, 1.0, v105
	v_add_f32_e32 v113, 1.0, v106
	v_add_f32_e32 v114, 1.0, v107
	v_add_f32_e32 v115, 1.0, v108
	v_rcp_f32_e32 v102, v97
	v_rcp_f32_e32 v103, v109
	v_rcp_f32_e32 v104, v110
	v_rcp_f32_e32 v105, v111
	v_rcp_f32_e32 v106, v112
	v_rcp_f32_e32 v107, v113
	v_rcp_f32_e32 v108, v114
	v_rcp_f32_e32 v109, v115
	v_mul_f32_e32 v92, v92, v102
	v_mul_f32_e32 v93, v93, v103
	v_mul_f32_e32 v94, v94, v104
	v_mul_f32_e32 v95, v95, v105
	v_mul_f32_e32 v88, v88, v106
	v_mul_f32_e32 v89, v89, v107
	v_mul_f32_e32 v90, v90, v108
	v_mul_f32_e32 v91, v91, v109
	v_mul_f32_e32 v84, v84, v92
	v_mul_f32_e32 v85, v85, v93
	v_mul_f32_e32 v86, v86, v94
	v_mul_f32_e32 v87, v87, v95
	v_mul_f32_e32 v88, v80, v88
	v_mul_f32_e32 v89, v81, v89
	v_mul_f32_e32 v90, v82, v90
	v_mul_f32_e32 v91, v83, v91
	v_cvt_pk_bf16_f32 v80, v84, v85
	v_cvt_pk_bf16_f32 v81, v86, v87
	v_cvt_pk_bf16_f32 v82, v88, v89
	v_cvt_pk_bf16_f32 v83, v90, v91
	global_store_dwordx4 v[98:99], v[80:83], off
	s_nop 1
	v_mad_i64_i32 v[80:81], s[0:1], v96, s47, v[146:147]
	v_lshl_add_u64 v[80:81], v[80:81], 0, v[148:149]
	v_mov_b32_e32 v82, v251
	v_mul_f32_e32 v78, v78, v82
	v_mul_f32_e32 v79, v79, v82
	v_mul_f32_e32 v76, v76, v82
	v_mul_f32_e32 v77, v77, v82
	v_mul_f32_e32 v74, v74, v82
	v_mul_f32_e32 v75, v75, v82
	v_mul_f32_e32 v72, v72, v82
; __device__ __forceinline__ float silu(float x) { return x * sigm(x); }
; __device__ __forceinline__ unsigned pkbf(float lo, float hi) { const f32x2_m v = {lo, hi}; const bf16x2_m b = __builtin_convertvector(v, bf16x2_m); return __builtin_bit_cast(unsigned, b); }
; template <int RSM> __device__ __forceinline__ float row_scale(const float* p, int row) { const float v = __hip_atomic_load(p + row, __ATOMIC_RELAXED, __HIP_MEMORY_SCOPE_AGENT); return RSM == 0 ? v : 1.0f / sqrtf(v * (1.f / DM) + EPS); }
;     __device__ __forceinline__ void operator()(const f32x4 (&acc)[2][2][4][2], const Unit& u, int wr, int wc, int fr, int fq) const {
;     ...
;             for (int m = 0; m < 4; ++m) { const int row = row0 + ai * HALF + m * 16; bf16* rowp = O + (size_t)row * ldc + col0; const float sc = row_scale<RSM>(rs, row);
;                 const f32x4 g0 = acc[ai][0][m][0] * sc, g1 = acc[ai][0][m][1] * sc, u0 = acc[ai][1][m][0] * sc, u1 = acc[ai][1][m][1] * sc;
;                 v4u w; w.x = pkbf(silu(g0[0]) * u0[0], silu(g0[1]) * u0[1]); w.y = pkbf(silu(g0[2]) * u0[2], silu(g0[3]) * u0[3]);
;                 w.z = pkbf(silu(g1[0]) * u1[0], silu(g1[1]) * u1[1]); w.w = pkbf(silu(g1[2]) * u1[2], silu(g1[3]) * u1[3]);
;                 *(v4u*)rowp = w; }
	v_mul_f32_e32 v73, v73, v82
	v_mul_f32_e32 v70, v70, v82
	v_mul_f32_e32 v71, v71, v82
	v_mul_f32_e32 v68, v68, v82
	v_mul_f32_e32 v69, v69, v82
	v_mul_f32_e32 v66, v66, v82
	v_mul_f32_e32 v67, v67, v82
	v_mul_f32_e32 v64, v64, v82
	v_mul_f32_e32 v65, v65, v82
	v_mul_f32_e32 v82, 0xbfb8aa3b, v76
	v_mul_f32_e32 v83, 0xbfb8aa3b, v77
	v_mul_f32_e32 v84, 0xbfb8aa3b, v78
	v_mul_f32_e32 v85, 0xbfb8aa3b, v79
	v_mul_f32_e32 v86, 0xbfb8aa3b, v72
	v_mul_f32_e32 v87, 0xbfb8aa3b, v73
	v_mul_f32_e32 v88, 0xbfb8aa3b, v74
	v_mul_f32_e32 v89, 0xbfb8aa3b, v75
	v_exp_f32_e32 v82, v82
	v_exp_f32_e32 v83, v83
	v_exp_f32_e32 v84, v84
	v_exp_f32_e32 v85, v85
	v_exp_f32_e32 v86, v86
	v_exp_f32_e32 v87, v87
	v_exp_f32_e32 v88, v88
	v_exp_f32_e32 v89, v89
	v_add_f32_e32 v82, 1.0, v82
	v_add_f32_e32 v83, 1.0, v83
	v_add_f32_e32 v84, 1.0, v84
	v_add_f32_e32 v85, 1.0, v85
	v_add_f32_e32 v86, 1.0, v86
	v_add_f32_e32 v87, 1.0, v87
	v_add_f32_e32 v88, 1.0, v88
	v_add_f32_e32 v89, 1.0, v89
	v_rcp_f32_e32 v82, v82
	v_rcp_f32_e32 v83, v83
	v_rcp_f32_e32 v84, v84
	v_rcp_f32_e32 v85, v85
	v_rcp_f32_e32 v86, v86
	v_rcp_f32_e32 v87, v87
	v_rcp_f32_e32 v88, v88
	v_rcp_f32_e32 v89, v89
	v_mul_f32_e32 v76, v76, v82
	v_mul_f32_e32 v77, v77, v83
	v_mul_f32_e32 v78, v78, v84
	v_mul_f32_e32 v79, v79, v85
	v_mul_f32_e32 v72, v72, v86
	v_mul_f32_e32 v73, v73, v87
	v_mul_f32_e32 v74, v74, v88
	v_mul_f32_e32 v75, v75, v89
	v_mul_f32_e32 v68, v68, v76
	v_mul_f32_e32 v69, v69, v77
	v_mul_f32_e32 v70, v70, v78
	v_mul_f32_e32 v71, v71, v79
	v_mul_f32_e32 v72, v64, v72
	v_mul_f32_e32 v73, v65, v73
	v_mul_f32_e32 v74, v66, v74
	v_mul_f32_e32 v75, v67, v75
	v_cvt_pk_bf16_f32 v64, v68, v69
	v_cvt_pk_bf16_f32 v65, v70, v71
	v_cvt_pk_bf16_f32 v66, v72, v73
	v_cvt_pk_bf16_f32 v67, v74, v75
	global_store_dwordx4 v[80:81], v[64:67], off
	s_nop 1
	v_add_u32_e32 v64, 0x80, v144
	v_mad_i64_i32 v[64:65], s[0:1], v64, s47, v[146:147]
	v_lshl_add_u64 v[64:65], v[64:65], 0, v[148:149]
	s_nop 0
	v_mov_b32_e32 v66, v252
	v_mul_f32_e32 v62, v62, v66
	v_mul_f32_e32 v63, v63, v66
	v_mul_f32_e32 v60, v60, v66
	v_mul_f32_e32 v61, v61, v66
	v_mul_f32_e32 v58, v58, v66
	v_mul_f32_e32 v59, v59, v66
	v_mul_f32_e32 v56, v56, v66
	v_mul_f32_e32 v57, v57, v66
	v_mul_f32_e32 v54, v54, v66
	v_mul_f32_e32 v55, v55, v66
	v_mul_f32_e32 v52, v52, v66
	v_mul_f32_e32 v53, v53, v66
	v_mul_f32_e32 v50, v50, v66
	v_mul_f32_e32 v51, v51, v66
	v_mul_f32_e32 v48, v48, v66
	v_mul_f32_e32 v49, v49, v66
	v_mul_f32_e32 v66, 0xbfb8aa3b, v60
	v_mul_f32_e32 v67, 0xbfb8aa3b, v61
	v_mul_f32_e32 v68, 0xbfb8aa3b, v62
	v_mul_f32_e32 v69, 0xbfb8aa3b, v63
	v_mul_f32_e32 v70, 0xbfb8aa3b, v56
	v_mul_f32_e32 v71, 0xbfb8aa3b, v57
	v_mul_f32_e32 v72, 0xbfb8aa3b, v58
	v_mul_f32_e32 v73, 0xbfb8aa3b, v59
	v_exp_f32_e32 v66, v66
	v_exp_f32_e32 v67, v67
	v_exp_f32_e32 v68, v68
	v_exp_f32_e32 v69, v69
	v_exp_f32_e32 v70, v70
	v_exp_f32_e32 v71, v71
	v_exp_f32_e32 v72, v72
	v_exp_f32_e32 v73, v73
	v_add_f32_e32 v66, 1.0, v66
	v_add_f32_e32 v67, 1.0, v67
	v_add_f32_e32 v68, 1.0, v68
	v_add_f32_e32 v69, 1.0, v69
	v_add_f32_e32 v70, 1.0, v70
	v_add_f32_e32 v71, 1.0, v71
	v_add_f32_e32 v72, 1.0, v72
	v_add_f32_e32 v73, 1.0, v73
	v_rcp_f32_e32 v66, v66
	v_rcp_f32_e32 v67, v67
	v_rcp_f32_e32 v68, v68
	v_rcp_f32_e32 v69, v69
	v_rcp_f32_e32 v70, v70
	v_rcp_f32_e32 v71, v71
	v_rcp_f32_e32 v72, v72
	v_rcp_f32_e32 v73, v73
	v_mul_f32_e32 v60, v60, v66
	v_mul_f32_e32 v61, v61, v67
	v_mul_f32_e32 v62, v62, v68
	v_mul_f32_e32 v63, v63, v69
	v_mul_f32_e32 v56, v56, v70
	v_mul_f32_e32 v57, v57, v71
	v_mul_f32_e32 v58, v58, v72
	v_mul_f32_e32 v59, v59, v73
	v_mul_f32_e32 v52, v52, v60
	v_mul_f32_e32 v53, v53, v61
	v_mul_f32_e32 v54, v54, v62
	v_mul_f32_e32 v55, v55, v63
	v_mul_f32_e32 v56, v48, v56
	v_mul_f32_e32 v57, v49, v57
	v_mul_f32_e32 v58, v50, v58
	v_mul_f32_e32 v59, v51, v59
	v_cvt_pk_bf16_f32 v48, v52, v53
	v_cvt_pk_bf16_f32 v49, v54, v55
	v_cvt_pk_bf16_f32 v50, v56, v57
	v_cvt_pk_bf16_f32 v51, v58, v59
	global_store_dwordx4 v[64:65], v[48:51], off
	s_nop 1
	v_add_u32_e32 v48, 0x90, v144
	v_mad_i64_i32 v[48:49], s[0:1], v48, s47, v[146:147]
	v_lshl_add_u64 v[48:49], v[48:49], 0, v[148:149]
	s_nop 0
	v_mov_b32_e32 v50, v253
	v_mul_f32_e32 v46, v46, v50
	v_mul_f32_e32 v47, v47, v50
	v_mul_f32_e32 v44, v44, v50
	v_mul_f32_e32 v45, v45, v50
	v_mul_f32_e32 v42, v42, v50
	v_mul_f32_e32 v43, v43, v50
	v_mul_f32_e32 v40, v40, v50
	v_mul_f32_e32 v41, v41, v50
	v_mul_f32_e32 v38, v38, v50
	v_mul_f32_e32 v39, v39, v50
	v_mul_f32_e32 v36, v36, v50
	v_mul_f32_e32 v37, v37, v50
	v_mul_f32_e32 v34, v34, v50
	v_mul_f32_e32 v35, v35, v50
	v_mul_f32_e32 v32, v32, v50
	v_mul_f32_e32 v33, v33, v50
	v_mul_f32_e32 v50, 0xbfb8aa3b, v44
	v_mul_f32_e32 v51, 0xbfb8aa3b, v45
	v_mul_f32_e32 v52, 0xbfb8aa3b, v46
	v_mul_f32_e32 v53, 0xbfb8aa3b, v47
	v_mul_f32_e32 v54, 0xbfb8aa3b, v40
	v_mul_f32_e32 v55, 0xbfb8aa3b, v41
	v_mul_f32_e32 v56, 0xbfb8aa3b, v42
	v_mul_f32_e32 v57, 0xbfb8aa3b, v43
	v_exp_f32_e32 v50, v50
	v_exp_f32_e32 v51, v51
	v_exp_f32_e32 v52, v52
	v_exp_f32_e32 v53, v53
	v_exp_f32_e32 v54, v54
	v_exp_f32_e32 v55, v55
	v_exp_f32_e32 v56, v56
	v_exp_f32_e32 v57, v57
	v_add_f32_e32 v50, 1.0, v50
	v_add_f32_e32 v51, 1.0, v51
	v_add_f32_e32 v52, 1.0, v52
	v_add_f32_e32 v53, 1.0, v53
	v_add_f32_e32 v54, 1.0, v54
	v_add_f32_e32 v55, 1.0, v55
	v_add_f32_e32 v56, 1.0, v56
	v_add_f32_e32 v57, 1.0, v57
; #define PG8_BAR __builtin_amdgcn_s_barrier()
; __device__ __forceinline__ float silu(float x) { return x * sigm(x); }
; __device__ __forceinline__ unsigned pkbf(float lo, float hi) { const f32x2_m v = {lo, hi}; const bf16x2_m b = __builtin_convertvector(v, bf16x2_m); return __builtin_bit_cast(unsigned, b); }
; template <int RSM> __device__ __forceinline__ float row_scale(const float* p, int row) { const float v = __hip_atomic_load(p + row, __ATOMIC_RELAXED, __HIP_MEMORY_SCOPE_AGENT); return RSM == 0 ? v : 1.0f / sqrtf(v * (1.f / DM) + EPS); }
; template <class Epi, class Sched, bool ALIGN_EPI = false, bool SP2 = false>
; __device__ __forceinline__ void gemm_phase(PG8_LAS unsigned char* lds, const Gemm g, const Sched& S, const Epi& E) {
;     ...
;         if constexpr (ALIGN_EPI) { if (wr == 0) PG8_BAR; }
;         if constexpr (!Epi::AFTER_DRAIN) { E(acc, cur, wr, wc, fr, fq); S.done(cur); }
;         if (!has_next) break;
; #pragma unroll
;         for (int a = 0; a < 2; ++a)
; #pragma unroll
;             for (int b = 0; b < 2; ++b)
; #pragma unroll
;                 for (int m = 0; m < 4; ++m)
; #pragma unroll
;                     for (int n = 0; n < 2; ++n) acc[a][b][m][n] = (f32x4){0.f, 0.f, 0.f, 0.f};
;         cur = nxt; cA = nA; cB = nB; ++ui;
;         if constexpr (ALIGN_EPI) { if (wr == 1) PG8_BAR; }
;     __device__ __forceinline__ void operator()(const f32x4 (&acc)[2][2][4][2], const Unit& u, int wr, int wc, int fr, int fq) const {
;     ...
;             for (int m = 0; m < 4; ++m) { const int row = row0 + ai * HALF + m * 16; bf16* rowp = O + (size_t)row * ldc + col0; const float sc = row_scale<RSM>(rs, row);
;                 const f32x4 g0 = acc[ai][0][m][0] * sc, g1 = acc[ai][0][m][1] * sc, u0 = acc[ai][1][m][0] * sc, u1 = acc[ai][1][m][1] * sc;
;                 v4u w; w.x = pkbf(silu(g0[0]) * u0[0], silu(g0[1]) * u0[1]); w.y = pkbf(silu(g0[2]) * u0[2], silu(g0[3]) * u0[3]);
;                 w.z = pkbf(silu(g1[0]) * u1[0], silu(g1[1]) * u1[1]); w.w = pkbf(silu(g1[2]) * u1[2], silu(g1[3]) * u1[3]);
;                 *(v4u*)rowp = w; }
	v_rcp_f32_e32 v50, v50
	v_rcp_f32_e32 v51, v51
	v_rcp_f32_e32 v52, v52
	v_rcp_f32_e32 v53, v53
	v_rcp_f32_e32 v54, v54
	v_rcp_f32_e32 v55, v55
	v_rcp_f32_e32 v56, v56
	v_rcp_f32_e32 v57, v57
	v_mul_f32_e32 v44, v44, v50
	v_mul_f32_e32 v45, v45, v51
	v_mul_f32_e32 v46, v46, v52
	v_mul_f32_e32 v47, v47, v53
	v_mul_f32_e32 v40, v40, v54
	v_mul_f32_e32 v41, v41, v55
	v_mul_f32_e32 v42, v42, v56
	v_mul_f32_e32 v43, v43, v57
	v_mul_f32_e32 v36, v36, v44
	v_mul_f32_e32 v37, v37, v45
	v_mul_f32_e32 v38, v38, v46
	v_mul_f32_e32 v39, v39, v47
	v_mul_f32_e32 v40, v32, v40
	v_mul_f32_e32 v41, v33, v41
	v_mul_f32_e32 v42, v34, v42
	v_mul_f32_e32 v43, v35, v43
	v_cvt_pk_bf16_f32 v32, v36, v37
	v_cvt_pk_bf16_f32 v33, v38, v39
	v_cvt_pk_bf16_f32 v34, v40, v41
	v_cvt_pk_bf16_f32 v35, v42, v43
	global_store_dwordx4 v[48:49], v[32:35], off
	s_nop 1
	v_add_u32_e32 v32, 0xa0, v144
	v_mad_i64_i32 v[32:33], s[0:1], v32, s47, v[146:147]
	v_lshl_add_u64 v[32:33], v[32:33], 0, v[148:149]
	s_nop 0
	v_mov_b32_e32 v34, v254
	v_mul_f32_e32 v30, v30, v34
	v_mul_f32_e32 v31, v31, v34
	v_mul_f32_e32 v28, v28, v34
	v_mul_f32_e32 v29, v29, v34
	v_mul_f32_e32 v26, v26, v34
	v_mul_f32_e32 v27, v27, v34
	v_mul_f32_e32 v24, v24, v34
	v_mul_f32_e32 v25, v25, v34
	v_mul_f32_e32 v22, v22, v34
	v_mul_f32_e32 v23, v23, v34
	v_mul_f32_e32 v20, v20, v34
	v_mul_f32_e32 v21, v21, v34
	v_mul_f32_e32 v18, v18, v34
	v_mul_f32_e32 v19, v19, v34
	v_mul_f32_e32 v16, v16, v34
	v_mul_f32_e32 v17, v17, v34
	v_mul_f32_e32 v34, 0xbfb8aa3b, v28
	v_mul_f32_e32 v35, 0xbfb8aa3b, v29
	v_mul_f32_e32 v36, 0xbfb8aa3b, v30
	v_mul_f32_e32 v37, 0xbfb8aa3b, v31
	v_mul_f32_e32 v38, 0xbfb8aa3b, v24
	v_mul_f32_e32 v39, 0xbfb8aa3b, v25
	v_mul_f32_e32 v40, 0xbfb8aa3b, v26
	v_mul_f32_e32 v41, 0xbfb8aa3b, v27
	v_exp_f32_e32 v34, v34
	v_exp_f32_e32 v35, v35
	v_exp_f32_e32 v36, v36
	v_exp_f32_e32 v37, v37
	v_exp_f32_e32 v38, v38
	v_exp_f32_e32 v39, v39
	v_exp_f32_e32 v40, v40
	v_exp_f32_e32 v41, v41
	v_add_f32_e32 v34, 1.0, v34
	v_add_f32_e32 v35, 1.0, v35
	v_add_f32_e32 v36, 1.0, v36
	v_add_f32_e32 v37, 1.0, v37
	v_add_f32_e32 v38, 1.0, v38
	v_add_f32_e32 v39, 1.0, v39
	v_add_f32_e32 v40, 1.0, v40
	v_add_f32_e32 v41, 1.0, v41
	v_rcp_f32_e32 v34, v34
	v_rcp_f32_e32 v35, v35
	v_rcp_f32_e32 v36, v36
	v_rcp_f32_e32 v37, v37
	v_rcp_f32_e32 v38, v38
	v_rcp_f32_e32 v39, v39
	v_rcp_f32_e32 v40, v40
	v_rcp_f32_e32 v41, v41
	v_mul_f32_e32 v28, v28, v34
	v_mul_f32_e32 v29, v29, v35
	v_mul_f32_e32 v30, v30, v36
	v_mul_f32_e32 v31, v31, v37
	v_mul_f32_e32 v24, v24, v38
	v_mul_f32_e32 v25, v25, v39
	v_mul_f32_e32 v26, v26, v40
	v_mul_f32_e32 v27, v27, v41
	v_mul_f32_e32 v20, v20, v28
	v_mul_f32_e32 v21, v21, v29
	v_mul_f32_e32 v22, v22, v30
	v_mul_f32_e32 v23, v23, v31
	v_mul_f32_e32 v24, v16, v24
	v_mul_f32_e32 v25, v17, v25
	v_mul_f32_e32 v26, v18, v26
	v_mul_f32_e32 v27, v19, v27
	v_cvt_pk_bf16_f32 v16, v20, v21
	v_cvt_pk_bf16_f32 v17, v22, v23
	v_cvt_pk_bf16_f32 v18, v24, v25
	v_cvt_pk_bf16_f32 v19, v26, v27
	global_store_dwordx4 v[32:33], v[16:19], off
	s_nop 1
	v_add_u32_e32 v17, 0xb0, v144
	v_mad_i64_i32 v[16:17], s[0:1], v17, s47, v[146:147]
	v_lshl_add_u64 v[16:17], v[16:17], 0, v[148:149]
	s_mov_b64 s[0:1], -1
	v_mov_b32_e32 v18, v255
	v_mul_f32_e32 v14, v14, v18
	v_mul_f32_e32 v15, v15, v18
	v_mul_f32_e32 v12, v12, v18
	v_mul_f32_e32 v13, v13, v18
	v_mul_f32_e32 v10, v10, v18
	v_mul_f32_e32 v11, v11, v18
	v_mul_f32_e32 v8, v8, v18
	v_mul_f32_e32 v9, v9, v18
	v_mul_f32_e32 v6, v6, v18
	v_mul_f32_e32 v7, v7, v18
	v_mul_f32_e32 v4, v4, v18
	v_mul_f32_e32 v5, v5, v18
	v_mul_f32_e32 v2, v2, v18
	v_mul_f32_e32 v3, v3, v18
	v_mul_f32_e32 v0, v0, v18
	v_mul_f32_e32 v1, v1, v18
	v_mul_f32_e32 v18, 0xbfb8aa3b, v12
	v_mul_f32_e32 v19, 0xbfb8aa3b, v13
	v_mul_f32_e32 v20, 0xbfb8aa3b, v14
	v_mul_f32_e32 v21, 0xbfb8aa3b, v15
	v_mul_f32_e32 v22, 0xbfb8aa3b, v8
	v_mul_f32_e32 v23, 0xbfb8aa3b, v9
	v_mul_f32_e32 v24, 0xbfb8aa3b, v10
	v_mul_f32_e32 v25, 0xbfb8aa3b, v11
	v_exp_f32_e32 v18, v18
	v_exp_f32_e32 v19, v19
	v_exp_f32_e32 v20, v20
	v_exp_f32_e32 v21, v21
	v_exp_f32_e32 v22, v22
	v_exp_f32_e32 v23, v23
	v_exp_f32_e32 v24, v24
	v_exp_f32_e32 v25, v25
	v_add_f32_e32 v18, 1.0, v18
	v_add_f32_e32 v19, 1.0, v19
	v_add_f32_e32 v20, 1.0, v20
	v_add_f32_e32 v21, 1.0, v21
	v_add_f32_e32 v22, 1.0, v22
	v_add_f32_e32 v23, 1.0, v23
	v_add_f32_e32 v24, 1.0, v24
	v_add_f32_e32 v25, 1.0, v25
	v_rcp_f32_e32 v18, v18
	v_rcp_f32_e32 v19, v19
	v_rcp_f32_e32 v20, v20
	v_rcp_f32_e32 v21, v21
	v_rcp_f32_e32 v22, v22
	v_rcp_f32_e32 v23, v23
	v_rcp_f32_e32 v24, v24
	v_rcp_f32_e32 v25, v25
	v_mul_f32_e32 v12, v12, v18
	v_mul_f32_e32 v13, v13, v19
	v_mul_f32_e32 v14, v14, v20
	v_mul_f32_e32 v15, v15, v21
	v_mul_f32_e32 v8, v8, v22
	v_mul_f32_e32 v9, v9, v23
	v_mul_f32_e32 v10, v10, v24
	v_mul_f32_e32 v11, v11, v25
	v_mul_f32_e32 v4, v4, v12
	v_mul_f32_e32 v5, v5, v13
	v_mul_f32_e32 v6, v6, v14
	v_mul_f32_e32 v7, v7, v15
	v_mul_f32_e32 v8, v0, v8
	v_mul_f32_e32 v9, v1, v9
	v_mul_f32_e32 v10, v2, v10
	v_mul_f32_e32 v11, v3, v11
	s_andn2_b64 vcc, exec, s[4:5]
	v_cvt_pk_bf16_f32 v0, v4, v5
	v_cvt_pk_bf16_f32 v1, v6, v7
	v_cvt_pk_bf16_f32 v2, v8, v9
	v_cvt_pk_bf16_f32 v3, v10, v11
	global_store_dwordx4 v[16:17], v[0:3], off
	s_cbranch_vccnz .LBB0_1878
	s_andn2_b64 vcc, exec, s[10:11]
	s_cbranch_vccnz .LBB0_1877
	s_barrier
	s_branch .LBB0_1877

; __device__ __forceinline__ unsigned pkbf(float lo, float hi) { const f32x2_m v = {lo, hi}; const bf16x2_m b = __builtin_convertvector(v, bf16x2_m); return __builtin_bit_cast(unsigned, b); }
;     __device__ __forceinline__ void operator()(const f32x4 (&acc)[2][2][4][2], const Unit& u, int wr, int wc, int fr, int fq) const {
;     ...
;         for (int ai = 0; ai < 2; ++ai) { f32x4 pre[4][2][2];
; #pragma unroll
;             for (int m = 0; m < 4; ++m)
; #pragma unroll
;                 for (int bj = 0; bj < 2; ++bj)
; #pragma unroll
;                     for (int n = 0; n < 2; ++n) pre[m][bj][n] = *(const f32x4*)(base + (size_t)(row0 + ai * HALF + m * 16) * ldc + col0 + bj * HALF + n * 16);
;             asm volatile("" ::: "memory");
; #pragma unroll
;             for (int m = 0; m < 4; ++m) { const int row = row0 + ai * HALF + m * 16; const size_t off = (size_t)row * ldc + col0; float sq = 0.f;
; #pragma unroll
;                 for (int bj = 0; bj < 2; ++bj)
; #pragma unroll
;                     for (int n = 0; n < 2; ++n) { const size_t p = off + bj * HALF + n * 16; const f32x4 o = pre[m][bj][n] + acc[ai][bj][m][n] * scale; *(f32x4*)(out + p) = o;
;                         if (NORM == 1) *(v2u*)(xb + p) = (v2u){pkbf(o[0], o[1]), pkbf(o[2], o[3])};
;                         if (NORM) sq += (o[0] * o[0] + o[1] * o[1]) + (o[2] * o[2] + o[3] * o[3]); }
;                 if (NORM) { sq += __shfl_xor(sq, 16); sq += __shfl_xor(sq, 32); if (fq == 0) __hip_atomic_fetch_add(ss + row, sq, __ATOMIC_RELAXED, __HIP_MEMORY_SCOPE_AGENT); } } }
.LBB0_1968:
	v_lshl_or_b32 v188, s47, 8, v208
	v_lshl_add_u32 v192, s46, 8, v206
	v_ashrrev_i32_e32 v189, 31, v188
	v_lshlrev_b64 v[220:221], 2, v[188:189]
	v_ashrrev_i32_e32 v193, 31, v192
	v_lshl_add_u64 v[190:191], s[60:61], 0, v[220:221]
	v_lshlrev_b64 v[224:225], 13, v[192:193]
	v_lshl_add_u64 v[128:129], v[190:191], 0, v[224:225]
	global_load_dwordx4 v[212:215], v[128:129], off
	global_load_dwordx4 v[216:219], v[128:129], off offset:64
	global_load_dwordx4 v[228:231], v[128:129], off offset:512
	global_load_dwordx4 v[232:235], v[128:129], off offset:576
	v_or_b32_e32 v202, 16, v192
	v_or_b32_e32 v198, 32, v192
	v_or_b32_e32 v194, 48, v192
	v_ashrrev_i32_e32 v203, 31, v202
	v_ashrrev_i32_e32 v199, 31, v198
	v_ashrrev_i32_e32 v195, 31, v194
	v_lshlrev_b64 v[204:205], 13, v[202:203]
	v_lshlrev_b64 v[200:201], 13, v[198:199]
	v_lshlrev_b64 v[196:197], 13, v[194:195]
	v_lshl_add_u64 v[128:129], v[190:191], 0, v[204:205]
	v_lshl_add_u64 v[130:131], v[190:191], 0, v[200:201]
	v_lshl_add_u64 v[236:237], v[190:191], 0, v[196:197]
	global_load_dwordx4 v[172:175], v[128:129], off
	global_load_dwordx4 v[168:171], v[128:129], off offset:64
	global_load_dwordx4 v[164:167], v[128:129], off offset:512
	global_load_dwordx4 v[160:163], v[128:129], off offset:576
	global_load_dwordx4 v[156:159], v[130:131], off
	global_load_dwordx4 v[152:155], v[130:131], off offset:64
	global_load_dwordx4 v[148:151], v[130:131], off offset:512
	global_load_dwordx4 v[144:147], v[130:131], off offset:576
	global_load_dwordx4 v[140:143], v[236:237], off
	global_load_dwordx4 v[136:139], v[236:237], off offset:64
	global_load_dwordx4 v[132:135], v[236:237], off offset:512
	s_nop 0
	global_load_dwordx4 v[128:131], v[236:237], off offset:576
	s_waitcnt vmcnt(0)
	v_fma_f32 v126, v126, 0.5, v214
	v_fma_f32 v127, v127, 0.5, v215
	v_fma_f32 v124, v124, 0.5, v212
	v_fma_f32 v125, v125, 0.5, v213
	v_fma_f32 v122, v122, 0.5, v218
	v_fma_f32 v123, v123, 0.5, v219
	v_fma_f32 v120, v120, 0.5, v216
	v_fma_f32 v121, v121, 0.5, v217
	v_fma_f32 v118, v118, 0.5, v230
	v_fma_f32 v119, v119, 0.5, v231
	v_fma_f32 v116, v116, 0.5, v228
	v_fma_f32 v117, v117, 0.5, v229
	v_fma_f32 v214, v114, 0.5, v234
	v_fma_f32 v215, v115, 0.5, v235
	v_fma_f32 v212, v112, 0.5, v232
	v_fma_f32 v213, v113, 0.5, v233
	v_mul_f32_e32 v112, v125, v125
	v_mul_f32_e32 v113, v127, v127
	v_mul_f32_e32 v114, v121, v121
	v_mul_f32_e32 v115, v123, v123
	v_mul_f32_e32 v216, v117, v117
	v_mul_f32_e32 v217, v119, v119
	v_fmac_f32_e32 v112, v124, v124
	v_fmac_f32_e32 v113, v126, v126
	v_fmac_f32_e32 v114, v120, v120
	v_fmac_f32_e32 v115, v122, v122
	v_mul_f32_e32 v218, v213, v213
	v_mul_f32_e32 v219, v215, v215
	v_fmac_f32_e32 v216, v116, v116
	v_fmac_f32_e32 v217, v118, v118
	v_add_f32_e32 v112, v112, v113
	v_add_f32_e32 v113, v114, v115
	v_fmac_f32_e32 v218, v212, v212
	v_fmac_f32_e32 v219, v214, v214
	v_add_f32_e32 v114, v216, v217
	v_add_f32_e32 v112, v112, v113
	v_add_f32_e32 v112, v112, v114
	v_add_f32_e32 v113, v218, v219
	v_add_f32_e32 v216, v112, v113
	ds_bpermute_b32 v217, v226, v216
	v_lshl_add_u64 v[112:113], s[60:61], 0, v[224:225]
	v_lshl_add_u64 v[114:115], v[112:113], 0, v[220:221]
	global_store_dwordx4 v[114:115], v[124:127], off
	global_store_dwordx4 v[114:115], v[120:123], off offset:64
	global_store_dwordx4 v[114:115], v[116:119], off offset:512
	global_store_dwordx4 v[114:115], v[212:215], off offset:576
	s_waitcnt lgkmcnt(0)
	v_add_f32_e32 v112, v216, v217
	ds_bpermute_b32 v113, v227, v112
	s_and_saveexec_b64 s[0:1], s[10:11]
	s_cbranch_execz .LBB0_1970
	v_lshl_add_u64 v[114:115], v[192:193], 2, s[12:13]
	s_waitcnt lgkmcnt(0)
	v_add_f32_e32 v112, v112, v113
	global_atomic_add_f32 v[114:115], v112, off
.LBB0_1970:
	s_or_b64 exec, exec, s[0:1]
	v_fma_f32 v110, v110, 0.5, v174
	v_fma_f32 v111, v111, 0.5, v175
	v_fma_f32 v108, v108, 0.5, v172
	v_fma_f32 v109, v109, 0.5, v173
	s_waitcnt lgkmcnt(0)
	v_mul_f32_e32 v113, v111, v111
	v_mul_f32_e32 v112, v109, v109
	v_fmac_f32_e32 v112, v108, v108
	v_fmac_f32_e32 v113, v110, v110
	v_fma_f32 v106, v106, 0.5, v170
	v_fma_f32 v107, v107, 0.5, v171
	v_fma_f32 v104, v104, 0.5, v168
	v_fma_f32 v105, v105, 0.5, v169
	v_add_f32_e32 v112, v112, v113
	v_mul_f32_e32 v113, v105, v105
	v_mul_f32_e32 v114, v107, v107
	v_fmac_f32_e32 v113, v104, v104
	v_fmac_f32_e32 v114, v106, v106
	v_add_f32_e32 v113, v113, v114
	v_fma_f32 v102, v102, 0.5, v166
	v_fma_f32 v103, v103, 0.5, v167
	v_fma_f32 v100, v100, 0.5, v164
	v_fma_f32 v101, v101, 0.5, v165
	v_add_f32_e32 v112, v112, v113
	v_mul_f32_e32 v113, v101, v101
	v_mul_f32_e32 v114, v103, v103
	v_fmac_f32_e32 v113, v100, v100
	v_fmac_f32_e32 v114, v102, v102
	v_add_f32_e32 v113, v113, v114
	v_add_f32_e32 v116, v112, v113
	v_fma_f32 v114, v98, 0.5, v162
	v_fma_f32 v115, v99, 0.5, v163
	v_fma_f32 v112, v96, 0.5, v160
	v_fma_f32 v113, v97, 0.5, v161
	v_mul_f32_e32 v97, v115, v115
	v_mul_f32_e32 v96, v113, v113
	v_fmac_f32_e32 v96, v112, v112
	v_fmac_f32_e32 v97, v114, v114
	v_add_f32_e32 v96, v96, v97
	v_add_f32_e32 v116, v116, v96
	ds_bpermute_b32 v117, v226, v116
	v_lshl_add_u64 v[96:97], s[60:61], 0, v[204:205]
	v_lshl_add_u64 v[98:99], v[188:189], 2, v[96:97]
	global_store_dwordx4 v[98:99], v[108:111], off
	global_store_dwordx4 v[98:99], v[104:107], off offset:64
	global_store_dwordx4 v[98:99], v[100:103], off offset:512
	global_store_dwordx4 v[98:99], v[112:115], off offset:576
	s_waitcnt lgkmcnt(0)
	v_add_f32_e32 v96, v116, v117
	ds_bpermute_b32 v97, v227, v96
	s_and_saveexec_b64 s[0:1], s[10:11]
	s_cbranch_execz .LBB0_1972
	v_lshl_add_u64 v[98:99], v[202:203], 2, s[12:13]
	s_waitcnt lgkmcnt(0)
	v_add_f32_e32 v96, v96, v97
	global_atomic_add_f32 v[98:99], v96, off
; __device__ __forceinline__ unsigned pkbf(float lo, float hi) { const f32x2_m v = {lo, hi}; const bf16x2_m b = __builtin_convertvector(v, bf16x2_m); return __builtin_bit_cast(unsigned, b); }
;     __device__ __forceinline__ void operator()(const f32x4 (&acc)[2][2][4][2], const Unit& u, int wr, int wc, int fr, int fq) const {
;     ...
;         for (int ai = 0; ai < 2; ++ai) { f32x4 pre[4][2][2];
; #pragma unroll
;             for (int m = 0; m < 4; ++m)
; #pragma unroll
;                 for (int bj = 0; bj < 2; ++bj)
; #pragma unroll
;                     for (int n = 0; n < 2; ++n) pre[m][bj][n] = *(const f32x4*)(base + (size_t)(row0 + ai * HALF + m * 16) * ldc + col0 + bj * HALF + n * 16);
;             asm volatile("" ::: "memory");
; #pragma unroll
;             for (int m = 0; m < 4; ++m) { const int row = row0 + ai * HALF + m * 16; const size_t off = (size_t)row * ldc + col0; float sq = 0.f;
; #pragma unroll
;                 for (int bj = 0; bj < 2; ++bj)
; #pragma unroll
;                     for (int n = 0; n < 2; ++n) { const size_t p = off + bj * HALF + n * 16; const f32x4 o = pre[m][bj][n] + acc[ai][bj][m][n] * scale; *(f32x4*)(out + p) = o;
;                         if (NORM == 1) *(v2u*)(xb + p) = (v2u){pkbf(o[0], o[1]), pkbf(o[2], o[3])};
;                         if (NORM) sq += (o[0] * o[0] + o[1] * o[1]) + (o[2] * o[2] + o[3] * o[3]); }
;                 if (NORM) { sq += __shfl_xor(sq, 16); sq += __shfl_xor(sq, 32); if (fq == 0) __hip_atomic_fetch_add(ss + row, sq, __ATOMIC_RELAXED, __HIP_MEMORY_SCOPE_AGENT); } } }
.LBB0_1972:
	s_or_b64 exec, exec, s[0:1]
	v_fma_f32 v94, v94, 0.5, v158
	v_fma_f32 v95, v95, 0.5, v159
	v_fma_f32 v92, v92, 0.5, v156
	v_fma_f32 v93, v93, 0.5, v157
	s_waitcnt lgkmcnt(0)
	v_mul_f32_e32 v97, v95, v95
	v_mul_f32_e32 v96, v93, v93
	v_fmac_f32_e32 v96, v92, v92
	v_fmac_f32_e32 v97, v94, v94
	v_fma_f32 v90, v90, 0.5, v154
	v_fma_f32 v91, v91, 0.5, v155
	v_fma_f32 v88, v88, 0.5, v152
	v_fma_f32 v89, v89, 0.5, v153
	v_add_f32_e32 v96, v96, v97
	v_mul_f32_e32 v97, v89, v89
	v_mul_f32_e32 v98, v91, v91
	v_fmac_f32_e32 v97, v88, v88
	v_fmac_f32_e32 v98, v90, v90
	v_add_f32_e32 v97, v97, v98
	v_fma_f32 v86, v86, 0.5, v150
	v_fma_f32 v87, v87, 0.5, v151
	v_fma_f32 v84, v84, 0.5, v148
	v_fma_f32 v85, v85, 0.5, v149
	v_add_f32_e32 v96, v96, v97
	v_mul_f32_e32 v97, v85, v85
	v_mul_f32_e32 v98, v87, v87
	v_fmac_f32_e32 v97, v84, v84
	v_fmac_f32_e32 v98, v86, v86
	v_add_f32_e32 v97, v97, v98
	v_add_f32_e32 v100, v96, v97
	v_fma_f32 v98, v82, 0.5, v146
	v_fma_f32 v99, v83, 0.5, v147
	v_fma_f32 v96, v80, 0.5, v144
	v_fma_f32 v97, v81, 0.5, v145
	v_mul_f32_e32 v81, v99, v99
	v_mul_f32_e32 v80, v97, v97
	v_fmac_f32_e32 v80, v96, v96
	v_fmac_f32_e32 v81, v98, v98
	v_add_f32_e32 v80, v80, v81
	v_add_f32_e32 v100, v100, v80
	ds_bpermute_b32 v101, v226, v100
	v_lshl_add_u64 v[80:81], s[60:61], 0, v[200:201]
	v_lshl_add_u64 v[82:83], v[188:189], 2, v[80:81]
	global_store_dwordx4 v[82:83], v[92:95], off
	global_store_dwordx4 v[82:83], v[88:91], off offset:64
	global_store_dwordx4 v[82:83], v[84:87], off offset:512
	global_store_dwordx4 v[82:83], v[96:99], off offset:576
	s_waitcnt lgkmcnt(0)
	v_add_f32_e32 v80, v100, v101
	ds_bpermute_b32 v81, v227, v80
	s_and_saveexec_b64 s[0:1], s[10:11]
	s_cbranch_execz .LBB0_1974
	v_lshl_add_u64 v[82:83], v[198:199], 2, s[12:13]
	s_waitcnt lgkmcnt(0)
	v_add_f32_e32 v80, v80, v81
	global_atomic_add_f32 v[82:83], v80, off
.LBB0_1974:
	s_or_b64 exec, exec, s[0:1]
	v_fma_f32 v78, v78, 0.5, v142
	v_fma_f32 v79, v79, 0.5, v143
	v_fma_f32 v76, v76, 0.5, v140
	v_fma_f32 v77, v77, 0.5, v141
	s_waitcnt lgkmcnt(0)
	v_mul_f32_e32 v81, v79, v79
	v_mul_f32_e32 v80, v77, v77
	v_fmac_f32_e32 v80, v76, v76
	v_fmac_f32_e32 v81, v78, v78
	v_fma_f32 v74, v74, 0.5, v138
	v_fma_f32 v75, v75, 0.5, v139
	v_fma_f32 v72, v72, 0.5, v136
	v_fma_f32 v73, v73, 0.5, v137
	v_add_f32_e32 v80, v80, v81
	v_mul_f32_e32 v81, v73, v73
	v_mul_f32_e32 v82, v75, v75
	v_fmac_f32_e32 v81, v72, v72
	v_fmac_f32_e32 v82, v74, v74
	v_add_f32_e32 v81, v81, v82
	v_fma_f32 v70, v70, 0.5, v134
	v_fma_f32 v71, v71, 0.5, v135
	v_fma_f32 v68, v68, 0.5, v132
	v_fma_f32 v69, v69, 0.5, v133
	v_add_f32_e32 v80, v80, v81
	v_mul_f32_e32 v81, v69, v69
	v_mul_f32_e32 v82, v71, v71
	v_fmac_f32_e32 v81, v68, v68
	v_fmac_f32_e32 v82, v70, v70
	v_add_f32_e32 v81, v81, v82
	v_add_f32_e32 v84, v80, v81
	v_fma_f32 v82, v66, 0.5, v130
	v_fma_f32 v83, v67, 0.5, v131
	v_fma_f32 v80, v64, 0.5, v128
	v_fma_f32 v81, v65, 0.5, v129
	v_mul_f32_e32 v65, v83, v83
	v_mul_f32_e32 v64, v81, v81
	v_fmac_f32_e32 v64, v80, v80
	v_fmac_f32_e32 v65, v82, v82
	v_add_f32_e32 v64, v64, v65
	v_add_f32_e32 v84, v84, v64
	ds_bpermute_b32 v85, v226, v84
	v_lshl_add_u64 v[64:65], s[60:61], 0, v[196:197]
	v_lshl_add_u64 v[66:67], v[188:189], 2, v[64:65]
	global_store_dwordx4 v[66:67], v[76:79], off
	global_store_dwordx4 v[66:67], v[72:75], off offset:64
	global_store_dwordx4 v[66:67], v[68:71], off offset:512
	global_store_dwordx4 v[66:67], v[80:83], off offset:576
	s_waitcnt lgkmcnt(0)
	v_add_f32_e32 v64, v84, v85
	ds_bpermute_b32 v65, v227, v64
	s_and_saveexec_b64 s[0:1], s[10:11]
	s_cbranch_execz .LBB0_1976
	v_lshl_add_u64 v[66:67], v[194:195], 2, s[12:13]
	s_waitcnt lgkmcnt(0)
	v_add_f32_e32 v64, v64, v65
	global_atomic_add_f32 v[66:67], v64, off
.LBB0_1976:
	s_or_b64 exec, exec, s[0:1]
	v_add_u32_e32 v124, 0x80, v192
	v_ashrrev_i32_e32 v125, 31, v124
	v_lshlrev_b64 v[142:143], 13, v[124:125]
	s_waitcnt lgkmcnt(0)
	v_lshl_add_u64 v[64:65], v[190:191], 0, v[142:143]
	global_load_dwordx4 v[126:129], v[64:65], off
	global_load_dwordx4 v[130:133], v[64:65], off offset:64
	global_load_dwordx4 v[134:137], v[64:65], off offset:512
	global_load_dwordx4 v[138:141], v[64:65], off offset:576
	v_add_u32_e32 v120, 0x90, v192
	v_add_u32_e32 v116, 0xa0, v192
	v_add_u32_e32 v112, 0xb0, v192
	v_ashrrev_i32_e32 v121, 31, v120
	v_ashrrev_i32_e32 v117, 31, v116
	v_ashrrev_i32_e32 v113, 31, v112
	v_lshlrev_b64 v[122:123], 13, v[120:121]
	v_lshlrev_b64 v[118:119], 13, v[116:117]
	v_lshlrev_b64 v[114:115], 13, v[112:113]
	v_lshl_add_u64 v[64:65], v[190:191], 0, v[122:123]
	v_lshl_add_u64 v[66:67], v[190:191], 0, v[118:119]
	v_lshl_add_u64 v[144:145], v[190:191], 0, v[114:115]
	global_load_dwordx4 v[108:111], v[64:65], off
	global_load_dwordx4 v[104:107], v[64:65], off offset:64
	global_load_dwordx4 v[100:103], v[64:65], off offset:512
	global_load_dwordx4 v[96:99], v[64:65], off offset:576
	global_load_dwordx4 v[92:95], v[66:67], off
	global_load_dwordx4 v[88:91], v[66:67], off offset:64
	global_load_dwordx4 v[84:87], v[66:67], off offset:512
	global_load_dwordx4 v[80:83], v[66:67], off offset:576
	global_load_dwordx4 v[76:79], v[144:145], off
	global_load_dwordx4 v[72:75], v[144:145], off offset:64
	global_load_dwordx4 v[68:71], v[144:145], off offset:512
	s_nop 0
	global_load_dwordx4 v[64:67], v[144:145], off offset:576
	s_waitcnt vmcnt(15)
	v_fma_f32 v62, v62, 0.5, v128
	v_fma_f32 v63, v63, 0.5, v129
	v_fma_f32 v60, v60, 0.5, v126
	v_fma_f32 v61, v61, 0.5, v127
	s_waitcnt vmcnt(14)
	v_fma_f32 v58, v58, 0.5, v132
	v_fma_f32 v59, v59, 0.5, v133
	v_fma_f32 v56, v56, 0.5, v130
	v_fma_f32 v57, v57, 0.5, v131
	s_waitcnt vmcnt(13)
; __device__ __forceinline__ unsigned pkbf(float lo, float hi) { const f32x2_m v = {lo, hi}; const bf16x2_m b = __builtin_convertvector(v, bf16x2_m); return __builtin_bit_cast(unsigned, b); }
;     __device__ __forceinline__ void operator()(const f32x4 (&acc)[2][2][4][2], const Unit& u, int wr, int wc, int fr, int fq) const {
;     ...
;             for (int m = 0; m < 4; ++m) { const int row = row0 + ai * HALF + m * 16; const size_t off = (size_t)row * ldc + col0; float sq = 0.f;
; #pragma unroll
;                 for (int bj = 0; bj < 2; ++bj)
; #pragma unroll
;                     for (int n = 0; n < 2; ++n) { const size_t p = off + bj * HALF + n * 16; const f32x4 o = pre[m][bj][n] + acc[ai][bj][m][n] * scale; *(f32x4*)(out + p) = o;
;                         if (NORM == 1) *(v2u*)(xb + p) = (v2u){pkbf(o[0], o[1]), pkbf(o[2], o[3])};
;                         if (NORM) sq += (o[0] * o[0] + o[1] * o[1]) + (o[2] * o[2] + o[3] * o[3]); }
;                 if (NORM) { sq += __shfl_xor(sq, 16); sq += __shfl_xor(sq, 32); if (fq == 0) __hip_atomic_fetch_add(ss + row, sq, __ATOMIC_RELAXED, __HIP_MEMORY_SCOPE_AGENT); } } }
	v_fma_f32 v54, v54, 0.5, v136
	v_fma_f32 v55, v55, 0.5, v137
	v_fma_f32 v52, v52, 0.5, v134
	v_fma_f32 v53, v53, 0.5, v135
	s_waitcnt vmcnt(12)
	v_fma_f32 v128, v50, 0.5, v140
	v_fma_f32 v129, v51, 0.5, v141
	v_fma_f32 v126, v48, 0.5, v138
	v_fma_f32 v127, v49, 0.5, v139
	v_mul_f32_e32 v48, v61, v61
	v_mul_f32_e32 v49, v63, v63
	v_mul_f32_e32 v50, v57, v57
	v_mul_f32_e32 v51, v59, v59
	v_mul_f32_e32 v130, v53, v53
	v_mul_f32_e32 v131, v55, v55
	v_fmac_f32_e32 v48, v60, v60
	v_fmac_f32_e32 v49, v62, v62
	v_fmac_f32_e32 v50, v56, v56
	v_fmac_f32_e32 v51, v58, v58
	v_mul_f32_e32 v132, v127, v127
	v_mul_f32_e32 v133, v129, v129
	v_fmac_f32_e32 v130, v52, v52
	v_fmac_f32_e32 v131, v54, v54
	v_add_f32_e32 v48, v48, v49
	v_add_f32_e32 v49, v50, v51
	v_fmac_f32_e32 v132, v126, v126
	v_fmac_f32_e32 v133, v128, v128
	v_add_f32_e32 v50, v130, v131
	v_add_f32_e32 v48, v48, v49
	v_add_f32_e32 v48, v48, v50
	v_add_f32_e32 v49, v132, v133
	v_add_f32_e32 v130, v48, v49
	ds_bpermute_b32 v131, v226, v130
	v_lshl_add_u64 v[48:49], s[60:61], 0, v[142:143]
	v_lshl_add_u64 v[50:51], v[188:189], 2, v[48:49]
	global_store_dwordx4 v[50:51], v[60:63], off
	global_store_dwordx4 v[50:51], v[56:59], off offset:64
	global_store_dwordx4 v[50:51], v[52:55], off offset:512
	global_store_dwordx4 v[50:51], v[126:129], off offset:576
	s_waitcnt lgkmcnt(0)
	v_add_f32_e32 v48, v130, v131
	ds_bpermute_b32 v49, v227, v48
	s_and_saveexec_b64 s[0:1], s[10:11]
	s_cbranch_execz .LBB0_1978
	v_lshl_add_u64 v[50:51], v[124:125], 2, s[12:13]
	s_waitcnt lgkmcnt(0)
	v_add_f32_e32 v48, v48, v49
	global_atomic_add_f32 v[50:51], v48, off
.LBB0_1978:
	s_or_b64 exec, exec, s[0:1]
	s_waitcnt vmcnt(15)
	v_fma_f32 v46, v46, 0.5, v110
	v_fma_f32 v47, v47, 0.5, v111
	v_fma_f32 v44, v44, 0.5, v108
	v_fma_f32 v45, v45, 0.5, v109
	s_waitcnt lgkmcnt(0)
	v_mul_f32_e32 v49, v47, v47
	v_mul_f32_e32 v48, v45, v45
	v_fmac_f32_e32 v48, v44, v44
	v_fmac_f32_e32 v49, v46, v46
	s_waitcnt vmcnt(14)
	v_fma_f32 v42, v42, 0.5, v106
	v_fma_f32 v43, v43, 0.5, v107
	v_fma_f32 v40, v40, 0.5, v104
	v_fma_f32 v41, v41, 0.5, v105
	v_add_f32_e32 v48, v48, v49
	v_mul_f32_e32 v49, v41, v41
	v_mul_f32_e32 v50, v43, v43
	v_fmac_f32_e32 v49, v40, v40
	v_fmac_f32_e32 v50, v42, v42
	v_add_f32_e32 v49, v49, v50
	s_waitcnt vmcnt(13)
	v_fma_f32 v38, v38, 0.5, v102
	v_fma_f32 v39, v39, 0.5, v103
	v_fma_f32 v36, v36, 0.5, v100
	v_fma_f32 v37, v37, 0.5, v101
	v_add_f32_e32 v48, v48, v49
	v_mul_f32_e32 v49, v37, v37
	v_mul_f32_e32 v50, v39, v39
	v_fmac_f32_e32 v49, v36, v36
	v_fmac_f32_e32 v50, v38, v38
	v_add_f32_e32 v49, v49, v50
	v_add_f32_e32 v52, v48, v49
	s_waitcnt vmcnt(12)
	v_fma_f32 v50, v34, 0.5, v98
	v_fma_f32 v51, v35, 0.5, v99
	v_fma_f32 v48, v32, 0.5, v96
	v_fma_f32 v49, v33, 0.5, v97
	v_mul_f32_e32 v33, v51, v51
	v_mul_f32_e32 v32, v49, v49
	v_fmac_f32_e32 v32, v48, v48
	v_fmac_f32_e32 v33, v50, v50
	v_add_f32_e32 v32, v32, v33
	v_add_f32_e32 v52, v52, v32
	ds_bpermute_b32 v53, v226, v52
	v_lshl_add_u64 v[32:33], s[60:61], 0, v[122:123]
	v_lshl_add_u64 v[34:35], v[188:189], 2, v[32:33]
	global_store_dwordx4 v[34:35], v[44:47], off
	global_store_dwordx4 v[34:35], v[40:43], off offset:64
	global_store_dwordx4 v[34:35], v[36:39], off offset:512
	global_store_dwordx4 v[34:35], v[48:51], off offset:576
	s_waitcnt lgkmcnt(0)
	v_add_f32_e32 v32, v52, v53
	ds_bpermute_b32 v33, v227, v32
	s_and_saveexec_b64 s[0:1], s[10:11]
	s_cbranch_execz .LBB0_1980
	v_lshl_add_u64 v[34:35], v[120:121], 2, s[12:13]
	s_waitcnt lgkmcnt(0)
	v_add_f32_e32 v32, v32, v33
	global_atomic_add_f32 v[34:35], v32, off
; __device__ __forceinline__ unsigned pkbf(float lo, float hi) { const f32x2_m v = {lo, hi}; const bf16x2_m b = __builtin_convertvector(v, bf16x2_m); return __builtin_bit_cast(unsigned, b); }
;     __device__ __forceinline__ void operator()(const f32x4 (&acc)[2][2][4][2], const Unit& u, int wr, int wc, int fr, int fq) const {
;     ...
;             for (int m = 0; m < 4; ++m) { const int row = row0 + ai * HALF + m * 16; const size_t off = (size_t)row * ldc + col0; float sq = 0.f;
; #pragma unroll
;                 for (int bj = 0; bj < 2; ++bj)
; #pragma unroll
;                     for (int n = 0; n < 2; ++n) { const size_t p = off + bj * HALF + n * 16; const f32x4 o = pre[m][bj][n] + acc[ai][bj][m][n] * scale; *(f32x4*)(out + p) = o;
;                         if (NORM == 1) *(v2u*)(xb + p) = (v2u){pkbf(o[0], o[1]), pkbf(o[2], o[3])};
;                         if (NORM) sq += (o[0] * o[0] + o[1] * o[1]) + (o[2] * o[2] + o[3] * o[3]); }
;                 if (NORM) { sq += __shfl_xor(sq, 16); sq += __shfl_xor(sq, 32); if (fq == 0) __hip_atomic_fetch_add(ss + row, sq, __ATOMIC_RELAXED, __HIP_MEMORY_SCOPE_AGENT); } } }
.LBB0_1980:
	s_or_b64 exec, exec, s[0:1]
	s_waitcnt vmcnt(15)
	v_fma_f32 v30, v30, 0.5, v94
	v_fma_f32 v31, v31, 0.5, v95
	v_fma_f32 v28, v28, 0.5, v92
	v_fma_f32 v29, v29, 0.5, v93
	s_waitcnt lgkmcnt(0)
	v_mul_f32_e32 v33, v31, v31
	v_mul_f32_e32 v32, v29, v29
	v_fmac_f32_e32 v32, v28, v28
	v_fmac_f32_e32 v33, v30, v30
	s_waitcnt vmcnt(14)
	v_fma_f32 v26, v26, 0.5, v90
	v_fma_f32 v27, v27, 0.5, v91
	v_fma_f32 v24, v24, 0.5, v88
	v_fma_f32 v25, v25, 0.5, v89
	v_add_f32_e32 v32, v32, v33
	v_mul_f32_e32 v33, v25, v25
	v_mul_f32_e32 v34, v27, v27
	v_fmac_f32_e32 v33, v24, v24
	v_fmac_f32_e32 v34, v26, v26
	v_add_f32_e32 v33, v33, v34
	s_waitcnt vmcnt(13)
	v_fma_f32 v22, v22, 0.5, v86
	v_fma_f32 v23, v23, 0.5, v87
	v_fma_f32 v20, v20, 0.5, v84
	v_fma_f32 v21, v21, 0.5, v85
	v_add_f32_e32 v32, v32, v33
	v_mul_f32_e32 v33, v21, v21
	v_mul_f32_e32 v34, v23, v23
	v_fmac_f32_e32 v33, v20, v20
	v_fmac_f32_e32 v34, v22, v22
	v_add_f32_e32 v33, v33, v34
	v_add_f32_e32 v36, v32, v33
	s_waitcnt vmcnt(12)
	v_fma_f32 v34, v18, 0.5, v82
	v_fma_f32 v35, v19, 0.5, v83
	v_fma_f32 v32, v16, 0.5, v80
	v_fma_f32 v33, v17, 0.5, v81
	v_mul_f32_e32 v17, v35, v35
	v_mul_f32_e32 v16, v33, v33
	v_fmac_f32_e32 v16, v32, v32
	v_fmac_f32_e32 v17, v34, v34
	v_add_f32_e32 v16, v16, v17
	v_add_f32_e32 v36, v36, v16
	ds_bpermute_b32 v37, v226, v36
	v_lshl_add_u64 v[16:17], s[60:61], 0, v[118:119]
	v_lshl_add_u64 v[18:19], v[188:189], 2, v[16:17]
	global_store_dwordx4 v[18:19], v[28:31], off
	global_store_dwordx4 v[18:19], v[24:27], off offset:64
	global_store_dwordx4 v[18:19], v[20:23], off offset:512
	global_store_dwordx4 v[18:19], v[32:35], off offset:576
	s_waitcnt lgkmcnt(0)
	v_add_f32_e32 v16, v36, v37
	ds_bpermute_b32 v17, v227, v16
	s_and_saveexec_b64 s[0:1], s[10:11]
	s_cbranch_execz .LBB0_1982
	v_lshl_add_u64 v[18:19], v[116:117], 2, s[12:13]
	s_waitcnt lgkmcnt(0)
	v_add_f32_e32 v16, v16, v17
	global_atomic_add_f32 v[18:19], v16, off
.LBB0_1982:
	s_or_b64 exec, exec, s[0:1]
	s_waitcnt vmcnt(15)
	v_fma_f32 v14, v14, 0.5, v78
	v_fma_f32 v15, v15, 0.5, v79
	v_fma_f32 v12, v12, 0.5, v76
	v_fma_f32 v13, v13, 0.5, v77
	s_waitcnt lgkmcnt(0)
	v_mul_f32_e32 v17, v15, v15
	v_mul_f32_e32 v16, v13, v13
	v_fmac_f32_e32 v16, v12, v12
	v_fmac_f32_e32 v17, v14, v14
	s_waitcnt vmcnt(14)
	v_fma_f32 v10, v10, 0.5, v74
	v_fma_f32 v11, v11, 0.5, v75
	v_fma_f32 v8, v8, 0.5, v72
	v_fma_f32 v9, v9, 0.5, v73
	v_add_f32_e32 v16, v16, v17
	v_mul_f32_e32 v17, v9, v9
	v_mul_f32_e32 v18, v11, v11
	v_fmac_f32_e32 v17, v8, v8
	v_fmac_f32_e32 v18, v10, v10
	v_add_f32_e32 v17, v17, v18
	s_waitcnt vmcnt(13)
	v_fma_f32 v6, v6, 0.5, v70
	v_fma_f32 v7, v7, 0.5, v71
	v_fma_f32 v4, v4, 0.5, v68
	v_fma_f32 v5, v5, 0.5, v69
	v_add_f32_e32 v16, v16, v17
	v_mul_f32_e32 v17, v5, v5
	v_mul_f32_e32 v18, v7, v7
	v_fmac_f32_e32 v17, v4, v4
	v_fmac_f32_e32 v18, v6, v6
	v_add_f32_e32 v17, v17, v18
	v_add_f32_e32 v20, v16, v17
	s_waitcnt vmcnt(12)
	v_fma_f32 v18, v2, 0.5, v66
	v_fma_f32 v19, v3, 0.5, v67
	v_fma_f32 v16, v0, 0.5, v64
	v_fma_f32 v17, v1, 0.5, v65
	v_mul_f32_e32 v1, v19, v19
	v_mul_f32_e32 v0, v17, v17
	v_fmac_f32_e32 v0, v16, v16
	v_fmac_f32_e32 v1, v18, v18
	v_add_f32_e32 v0, v0, v1
	v_add_f32_e32 v20, v20, v0
	ds_bpermute_b32 v21, v226, v20
	v_lshl_add_u64 v[0:1], s[60:61], 0, v[114:115]
	v_lshl_add_u64 v[2:3], v[188:189], 2, v[0:1]
	global_store_dwordx4 v[2:3], v[12:15], off
	global_store_dwordx4 v[2:3], v[8:11], off offset:64
	global_store_dwordx4 v[2:3], v[4:7], off offset:512
	global_store_dwordx4 v[2:3], v[16:19], off offset:576
	s_waitcnt lgkmcnt(0)
	v_add_f32_e32 v0, v20, v21
	ds_bpermute_b32 v1, v227, v0
	s_and_saveexec_b64 s[0:1], s[10:11]
	s_cbranch_execz .LBB0_1984
	v_lshl_add_u64 v[2:3], v[112:113], 2, s[12:13]
	s_waitcnt lgkmcnt(0)
	v_add_f32_e32 v0, v0, v1
	global_atomic_add_f32 v[2:3], v0, off

; template <int RSM> __device__ __forceinline__ float row_scale(const float* p, int row) { const float v = __hip_atomic_load(p + row, __ATOMIC_RELAXED, __HIP_MEMORY_SCOPE_AGENT); return RSM == 0 ? v : 1.0f / sqrtf(v * (1.f / DM) + EPS); }
; __device__ __forceinline__ void norm_rows_f32_inplace(float* X, const float* ss, const float* w, int gw, int NGW, int lane) {
;     for (int m = gw; m < M; m += NGW) { f32x4* xr = (f32x4*)(X + (size_t)m * DM) + lane; f32x4 v[8];
; #pragma unroll
;         for (int j = 0; j < 8; ++j) v[j] = xr[64 * j];
;         const float rstd = epi::row_scale<1>(ss, m);
; #pragma unroll
;         for (int j = 0; j < 8; ++j) { const f32x4 ww = ((const f32x4*)w)[64 * j + lane]; xr[64 * j] = v[j] * rstd * ww; } }
; }
.LBB0_2042:
	global_load_dwordx4 v[16:19], v[12:13], off offset:-4096
	global_load_dwordx4 v[20:23], v[12:13], off offset:-3072
	global_load_dwordx4 v[24:27], v[12:13], off offset:-2048
	global_load_dwordx4 v[28:31], v[12:13], off offset:-1024
	global_load_dwordx4 v[32:35], v[12:13], off
	global_load_dwordx4 v[36:39], v[12:13], off offset:1024
	global_load_dwordx4 v[40:43], v[12:13], off offset:2048
	global_load_dwordx4 v[44:47], v[12:13], off offset:3072
	global_load_dword v15, v1, s[2:3] sc1
	global_load_dwordx4 v[48:51], v[2:3], off
	s_add_i32 s34, s34, s64
	s_add_u32 s2, s2, s4
	s_addc_u32 s3, s3, s5
	s_cmpk_lt_i32 s34, 0x4000
	s_waitcnt vmcnt(1)
	v_fmamk_f32 v15, v15, 0x3a000000, v0
	v_mul_f32_e32 v52, 0x4f800000, v15
	v_cmp_gt_f32_e32 vcc, s8, v15
	s_nop 1
	v_cndmask_b32_e32 v15, v15, v52, vcc
	v_sqrt_f32_e32 v52, v15
	s_nop 0
	v_add_u32_e32 v53, -1, v52
	v_add_u32_e32 v54, 1, v52
	v_fma_f32 v55, -v53, v52, v15
	v_fma_f32 v56, -v54, v52, v15
	v_cmp_ge_f32_e64 s[0:1], 0, v55
	s_nop 1
	v_cndmask_b32_e64 v52, v52, v53, s[0:1]
	v_cmp_lt_f32_e64 s[0:1], 0, v56
	s_nop 1
	v_cndmask_b32_e64 v52, v52, v54, s[0:1]
	v_mul_f32_e32 v53, 0x37800000, v52
	v_cndmask_b32_e32 v52, v52, v53, vcc
	v_cmp_class_f32_e32 vcc, v15, v14
	s_nop 1
	v_cndmask_b32_e32 v15, v52, v15, vcc
	v_div_scale_f32 v52, s[0:1], v15, v15, 1.0
	v_rcp_f32_e32 v53, v52
	v_div_scale_f32 v54, vcc, 1.0, v15, 1.0
	v_fma_f32 v55, -v52, v53, 1.0
	v_fmac_f32_e32 v53, v55, v53
	v_mul_f32_e32 v55, v54, v53
	v_fma_f32 v56, -v52, v55, v54
	v_fmac_f32_e32 v55, v56, v53
	v_fma_f32 v52, -v52, v55, v54
	v_div_fmas_f32 v52, v52, v53, v55
	v_div_fixup_f32 v52, v52, v15, 1.0
	v_mul_f32_e32 v16, v16, v52
	v_mul_f32_e32 v17, v17, v52
	v_mul_f32_e32 v18, v18, v52
	v_mul_f32_e32 v19, v19, v52
	s_waitcnt vmcnt(0)
	v_mul_f32_e32 v16, v48, v16
	v_mul_f32_e32 v17, v49, v17
	v_mul_f32_e32 v18, v50, v18
	v_mul_f32_e32 v19, v51, v19
	global_store_dwordx4 v[12:13], v[16:19], off offset:-4096
	global_load_dwordx4 v[16:19], v[2:3], off offset:1024
	v_mul_f32_e32 v22, v22, v52
	v_mul_f32_e32 v23, v23, v52
	v_mul_f32_e32 v20, v20, v52
	v_mul_f32_e32 v21, v21, v52
	s_waitcnt vmcnt(0)
	v_mul_f32_e32 v18, v18, v22
	v_mul_f32_e32 v19, v19, v23
	v_mul_f32_e32 v16, v16, v20
	v_mul_f32_e32 v17, v17, v21
	global_store_dwordx4 v[12:13], v[16:19], off offset:-3072
	global_load_dwordx4 v[16:19], v[2:3], off offset:2048
	v_mul_f32_e32 v20, v26, v52
	v_mul_f32_e32 v21, v27, v52
	v_mul_f32_e32 v22, v24, v52
	v_mul_f32_e32 v23, v25, v52
	s_waitcnt vmcnt(0)
	v_mul_f32_e32 v18, v18, v20
	v_mul_f32_e32 v19, v19, v21
	v_mul_f32_e32 v16, v16, v22
	v_mul_f32_e32 v17, v17, v23
	global_store_dwordx4 v[12:13], v[16:19], off offset:-2048
	global_load_dwordx4 v[16:19], v[2:3], off offset:3072
	v_mul_f32_e32 v20, v30, v52
	v_mul_f32_e32 v21, v31, v52
	v_mul_f32_e32 v22, v28, v52
	v_mul_f32_e32 v23, v29, v52
	s_waitcnt vmcnt(0)
	v_mul_f32_e32 v18, v18, v20
	v_mul_f32_e32 v19, v19, v21
	v_mul_f32_e32 v16, v16, v22
	v_mul_f32_e32 v17, v17, v23
	global_store_dwordx4 v[12:13], v[16:19], off offset:-1024
	global_load_dwordx4 v[16:19], v[4:5], off
	v_mul_f32_e32 v20, v34, v52
	v_mul_f32_e32 v21, v35, v52
	v_mul_f32_e32 v22, v32, v52
	v_mul_f32_e32 v23, v33, v52
	s_waitcnt vmcnt(0)
	v_mul_f32_e32 v18, v20, v18
	v_mul_f32_e32 v19, v21, v19
	v_mul_f32_e32 v16, v22, v16
	v_mul_f32_e32 v17, v23, v17
	global_store_dwordx4 v[12:13], v[16:19], off
	global_load_dwordx4 v[16:19], v[6:7], off
	v_mul_f32_e32 v20, v38, v52
	v_mul_f32_e32 v21, v39, v52
	v_mul_f32_e32 v22, v36, v52
	v_mul_f32_e32 v23, v37, v52
	s_waitcnt vmcnt(0)
	v_mul_f32_e32 v18, v20, v18
	v_mul_f32_e32 v19, v21, v19
	v_mul_f32_e32 v16, v22, v16
	v_mul_f32_e32 v17, v23, v17
	global_store_dwordx4 v[12:13], v[16:19], off offset:1024
	global_load_dwordx4 v[16:19], v[8:9], off
	v_mul_f32_e32 v20, v42, v52
	v_mul_f32_e32 v21, v43, v52
	v_mul_f32_e32 v22, v40, v52
	v_mul_f32_e32 v23, v41, v52
	s_waitcnt vmcnt(0)
	v_mul_f32_e32 v18, v20, v18
	v_mul_f32_e32 v19, v21, v19
	v_mul_f32_e32 v16, v22, v16
	v_mul_f32_e32 v17, v23, v17
	global_store_dwordx4 v[12:13], v[16:19], off offset:2048
	global_load_dwordx4 v[16:19], v[10:11], off
	v_mul_f32_e32 v20, v46, v52
	v_mul_f32_e32 v21, v47, v52
	v_mul_f32_e32 v22, v44, v52
	v_mul_f32_e32 v23, v45, v52
	s_waitcnt vmcnt(0)
	v_mul_f32_e32 v18, v20, v18
	v_mul_f32_e32 v19, v21, v19
	v_mul_f32_e32 v16, v22, v16
	v_mul_f32_e32 v17, v23, v17
	global_store_dwordx4 v[12:13], v[16:19], off offset:3072
	v_lshl_add_u64 v[12:13], v[12:13], 0, s[6:7]
	s_cbranch_scc1 .LBB0_2042

;     __device__ __forceinline__ void operator()(f32x4 (&acc)[2][2][4][2], const Unit& u, int wr, int wc, int fr, int fq) const {
;     ...
;             for (int m = 0; m < 4; ++m) { const int row = row0 + ai * HALF + m * 16; float sq = 0.f;
; #pragma unroll
;                 for (int bj = 0; bj < 2; ++bj)
; #pragma unroll
;                     for (int n = 0; n < 2; ++n) { const f32x4 o = pre[m][bj][n] + acc[ai][bj][m][n] * 0.5f; acc[ai][bj][m][n] = o;
;                         sq += (o[0] * o[0] + o[1] * o[1]) + (o[2] * o[2] + o[3] * o[3]); }
;                 sq += __shfl_xor(sq, 16); sq += __shfl_xor(sq, 32); if (fq == 0) __hip_atomic_fetch_add(ss + row, sq, __ATOMIC_RELAXED, __HIP_MEMORY_SCOPE_AGENT); } }
.LBB0_2056:
	v_lshl_add_u32 v216, s54, 8, v224
	v_ashrrev_i32_e32 v217, 31, v216
	v_lshlrev_b64 v[128:129], 13, v[216:217]
	v_lshl_add_u64 v[194:195], v[180:181], 0, v[128:129]
	global_load_dwordx4 v[196:199], v[194:195], off
	global_load_dwordx4 v[204:207], v[194:195], off offset:64
	global_load_dwordx4 v[220:223], v[194:195], off offset:512
	global_load_dwordx4 v[234:237], v[194:195], off offset:576
	v_or_b32_e32 v214, 16, v216
	v_or_b32_e32 v212, 32, v216
	v_or_b32_e32 v218, 48, v216
	v_ashrrev_i32_e32 v215, 31, v214
	v_ashrrev_i32_e32 v213, 31, v212
	v_ashrrev_i32_e32 v219, 31, v218
	v_lshlrev_b64 v[128:129], 13, v[214:215]
	v_lshlrev_b64 v[130:131], 13, v[212:213]
	v_lshlrev_b64 v[132:133], 13, v[218:219]
	v_lshl_add_u64 v[192:193], v[180:181], 0, v[128:129]
	v_lshl_add_u64 v[190:191], v[180:181], 0, v[130:131]
	v_lshl_add_u64 v[188:189], v[180:181], 0, v[132:133]
	global_load_dwordx4 v[172:175], v[192:193], off
	global_load_dwordx4 v[168:171], v[192:193], off offset:64
	global_load_dwordx4 v[164:167], v[192:193], off offset:512
	global_load_dwordx4 v[160:163], v[192:193], off offset:576
	global_load_dwordx4 v[156:159], v[190:191], off
	global_load_dwordx4 v[152:155], v[190:191], off offset:64
	global_load_dwordx4 v[148:151], v[190:191], off offset:512
	global_load_dwordx4 v[144:147], v[190:191], off offset:576
	global_load_dwordx4 v[140:143], v[188:189], off
	global_load_dwordx4 v[136:139], v[188:189], off offset:64
	global_load_dwordx4 v[132:135], v[188:189], off offset:512
	global_load_dwordx4 v[128:131], v[188:189], off offset:576
	s_waitcnt vmcnt(0)
	v_fma_f32 v202, v126, 0.5, v198
	v_fma_f32 v203, v127, 0.5, v199
	v_fma_f32 v210, v124, 0.5, v196
	v_fma_f32 v211, v125, 0.5, v197
	v_fma_f32 v200, v122, 0.5, v206
	v_fma_f32 v201, v123, 0.5, v207
	v_fma_f32 v208, v120, 0.5, v204
	v_fma_f32 v209, v121, 0.5, v205
	v_fma_f32 v198, v118, 0.5, v222
	v_fma_f32 v199, v119, 0.5, v223
	v_fma_f32 v206, v116, 0.5, v220
	v_fma_f32 v207, v117, 0.5, v221
	v_fma_f32 v196, v114, 0.5, v236
	v_fma_f32 v197, v115, 0.5, v237
	v_fma_f32 v204, v112, 0.5, v234
	v_fma_f32 v205, v113, 0.5, v235
	v_mul_f32_e32 v112, v211, v211
	v_mul_f32_e32 v113, v203, v203
	v_mul_f32_e32 v114, v209, v209
	v_mul_f32_e32 v115, v201, v201
	v_mul_f32_e32 v116, v207, v207
	v_mul_f32_e32 v117, v199, v199
	v_fmac_f32_e32 v112, v210, v210
	v_fmac_f32_e32 v113, v202, v202
	v_fmac_f32_e32 v114, v208, v208
	v_fmac_f32_e32 v115, v200, v200
	v_mul_f32_e32 v118, v205, v205
	v_mul_f32_e32 v119, v197, v197
	v_fmac_f32_e32 v116, v206, v206
	v_fmac_f32_e32 v117, v198, v198
	v_add_f32_e32 v112, v112, v113
	v_add_f32_e32 v113, v114, v115
	v_fmac_f32_e32 v118, v204, v204
	v_fmac_f32_e32 v119, v196, v196
	v_add_f32_e32 v114, v116, v117
	v_add_f32_e32 v112, v112, v113
	v_add_f32_e32 v112, v112, v114
	v_add_f32_e32 v113, v118, v119
	v_add_f32_e32 v112, v112, v113
	ds_bpermute_b32 v113, v226, v112
	s_waitcnt lgkmcnt(0)
	v_add_f32_e32 v114, v112, v113
	ds_bpermute_b32 v115, v227, v114
	v_lshl_add_u64 v[112:113], v[216:217], 2, s[12:13]
	s_and_saveexec_b64 s[6:7], s[0:1]
	s_cbranch_execz .LBB0_2058
	s_waitcnt lgkmcnt(0)
	v_add_f32_e32 v114, v114, v115
	global_atomic_add_f32 v[112:113], v114, off
.LBB0_2058:
	s_or_b64 exec, exec, s[6:7]
	v_fma_f32 v174, v110, 0.5, v174
	v_fma_f32 v175, v111, 0.5, v175
	v_fma_f32 v172, v108, 0.5, v172
	v_fma_f32 v173, v109, 0.5, v173
	v_fma_f32 v170, v106, 0.5, v170
	v_fma_f32 v171, v107, 0.5, v171
	v_fma_f32 v168, v104, 0.5, v168
	v_fma_f32 v169, v105, 0.5, v169
	v_mul_f32_e32 v108, v173, v173
	v_mul_f32_e32 v109, v175, v175
	v_mul_f32_e32 v104, v169, v169
	v_mul_f32_e32 v105, v171, v171
	v_fma_f32 v166, v102, 0.5, v166
	v_fma_f32 v167, v103, 0.5, v167
	v_fma_f32 v164, v100, 0.5, v164
	v_fma_f32 v165, v101, 0.5, v165
	v_fmac_f32_e32 v108, v172, v172
	v_fmac_f32_e32 v109, v174, v174
	v_fmac_f32_e32 v104, v168, v168
	v_fmac_f32_e32 v105, v170, v170
	v_mul_f32_e32 v100, v165, v165
	v_mul_f32_e32 v101, v167, v167
	v_fma_f32 v162, v94, 0.5, v162
	v_fma_f32 v163, v95, 0.5, v163
	v_fma_f32 v160, v92, 0.5, v160
	v_fma_f32 v161, v93, 0.5, v161
	v_add_f32_e32 v108, v108, v109
	v_add_f32_e32 v104, v104, v105
	v_fmac_f32_e32 v100, v164, v164
	v_fmac_f32_e32 v101, v166, v166
	v_mul_f32_e32 v92, v161, v161
	v_mul_f32_e32 v93, v163, v163
	v_add_f32_e32 v104, v108, v104
	v_add_f32_e32 v100, v100, v101
	v_fmac_f32_e32 v92, v160, v160
	v_fmac_f32_e32 v93, v162, v162
	v_add_f32_e32 v100, v104, v100
	v_add_f32_e32 v92, v92, v93
	v_add_f32_e32 v92, v100, v92
	ds_bpermute_b32 v93, v226, v92
	v_lshl_add_u64 v[214:215], v[214:215], 2, s[12:13]
	s_waitcnt lgkmcnt(0)
	v_add_f32_e32 v92, v92, v93
	ds_bpermute_b32 v93, v227, v92
	s_and_saveexec_b64 s[6:7], s[0:1]
	s_cbranch_execz .LBB0_2060
	s_waitcnt lgkmcnt(0)
	v_add_f32_e32 v92, v92, v93
	global_atomic_add_f32 v[214:215], v92, off
.LBB0_2060:
	s_or_b64 exec, exec, s[6:7]
	v_fma_f32 v158, v98, 0.5, v158
	v_fma_f32 v159, v99, 0.5, v159
	v_fma_f32 v156, v96, 0.5, v156
	v_fma_f32 v157, v97, 0.5, v157
	v_fma_f32 v154, v90, 0.5, v154
	v_fma_f32 v155, v91, 0.5, v155
	v_fma_f32 v152, v88, 0.5, v152
	v_fma_f32 v153, v89, 0.5, v153
	v_mul_f32_e32 v92, v157, v157
	s_waitcnt lgkmcnt(0)
	v_mul_f32_e32 v93, v159, v159
	v_mul_f32_e32 v88, v153, v153
	v_mul_f32_e32 v89, v155, v155
	v_fma_f32 v150, v86, 0.5, v150
	v_fma_f32 v151, v87, 0.5, v151
	v_fma_f32 v148, v84, 0.5, v148
	v_fma_f32 v149, v85, 0.5, v149
	v_fmac_f32_e32 v92, v156, v156
	v_fmac_f32_e32 v93, v158, v158
	v_fmac_f32_e32 v88, v152, v152
	v_fmac_f32_e32 v89, v154, v154
	v_mul_f32_e32 v84, v149, v149
	v_mul_f32_e32 v85, v151, v151
	v_fma_f32 v146, v78, 0.5, v146
	v_fma_f32 v147, v79, 0.5, v147
	v_fma_f32 v144, v76, 0.5, v144
	v_fma_f32 v145, v77, 0.5, v145
	v_add_f32_e32 v92, v92, v93
	v_add_f32_e32 v88, v88, v89
	v_fmac_f32_e32 v84, v148, v148
	v_fmac_f32_e32 v85, v150, v150
	v_mul_f32_e32 v76, v145, v145
	v_mul_f32_e32 v77, v147, v147
	v_add_f32_e32 v88, v92, v88
	v_add_f32_e32 v84, v84, v85
	v_fmac_f32_e32 v76, v144, v144
	v_fmac_f32_e32 v77, v146, v146
	v_add_f32_e32 v84, v88, v84
	v_add_f32_e32 v76, v76, v77
	v_add_f32_e32 v76, v84, v76
	ds_bpermute_b32 v77, v226, v76
	v_lshl_add_u64 v[212:213], v[212:213], 2, s[12:13]
	s_waitcnt lgkmcnt(0)
	v_add_f32_e32 v76, v76, v77
	ds_bpermute_b32 v77, v227, v76
	s_and_saveexec_b64 s[6:7], s[0:1]
	s_cbranch_execz .LBB0_2062
	s_waitcnt lgkmcnt(0)
	v_add_f32_e32 v76, v76, v77
	global_atomic_add_f32 v[212:213], v76, off
;     __device__ __forceinline__ void operator()(f32x4 (&acc)[2][2][4][2], const Unit& u, int wr, int wc, int fr, int fq) const {
;     ...
;         for (int ai = 0; ai < 2; ++ai) { f32x4 pre[4][2][2];
; #pragma unroll
;             for (int m = 0; m < 4; ++m)
; #pragma unroll
;                 for (int bj = 0; bj < 2; ++bj)
; #pragma unroll
;                     for (int n = 0; n < 2; ++n) pre[m][bj][n] = *(const f32x4*)(out + (size_t)(row0 + ai * HALF + m * 16) * ldc + col0 + bj * HALF + n * 16);
;             asm volatile("" ::: "memory");
; #pragma unroll
;             for (int m = 0; m < 4; ++m) { const int row = row0 + ai * HALF + m * 16; float sq = 0.f;
; #pragma unroll
;                 for (int bj = 0; bj < 2; ++bj)
; #pragma unroll
;                     for (int n = 0; n < 2; ++n) { const f32x4 o = pre[m][bj][n] + acc[ai][bj][m][n] * 0.5f; acc[ai][bj][m][n] = o;
;                         sq += (o[0] * o[0] + o[1] * o[1]) + (o[2] * o[2] + o[3] * o[3]); }
;                 sq += __shfl_xor(sq, 16); sq += __shfl_xor(sq, 32); if (fq == 0) __hip_atomic_fetch_add(ss + row, sq, __ATOMIC_RELAXED, __HIP_MEMORY_SCOPE_AGENT); } }
.LBB0_2062:
	s_or_b64 exec, exec, s[6:7]
	v_fma_f32 v142, v82, 0.5, v142
	v_fma_f32 v143, v83, 0.5, v143
	v_fma_f32 v140, v80, 0.5, v140
	v_fma_f32 v141, v81, 0.5, v141
	v_fma_f32 v126, v74, 0.5, v138
	v_fma_f32 v127, v75, 0.5, v139
	v_fma_f32 v136, v72, 0.5, v136
	v_fma_f32 v137, v73, 0.5, v137
	v_mul_f32_e32 v76, v141, v141
	s_waitcnt lgkmcnt(0)
	v_mul_f32_e32 v77, v143, v143
	v_mul_f32_e32 v72, v137, v137
	v_mul_f32_e32 v73, v127, v127
	v_fma_f32 v124, v70, 0.5, v134
	v_fma_f32 v125, v71, 0.5, v135
	v_fma_f32 v132, v68, 0.5, v132
	v_fma_f32 v133, v69, 0.5, v133
	v_fmac_f32_e32 v76, v140, v140
	v_fmac_f32_e32 v77, v142, v142
	v_fmac_f32_e32 v72, v136, v136
	v_fmac_f32_e32 v73, v126, v126
	v_mul_f32_e32 v68, v133, v133
	v_mul_f32_e32 v69, v125, v125
	v_fma_f32 v122, v66, 0.5, v130
	v_fma_f32 v123, v67, 0.5, v131
	v_fma_f32 v128, v64, 0.5, v128
	v_fma_f32 v129, v65, 0.5, v129
	v_add_f32_e32 v76, v76, v77
	v_add_f32_e32 v72, v72, v73
	v_fmac_f32_e32 v68, v132, v132
	v_fmac_f32_e32 v69, v124, v124
	v_mul_f32_e32 v64, v129, v129
	v_mul_f32_e32 v65, v123, v123
	v_add_f32_e32 v72, v76, v72
	v_add_f32_e32 v68, v68, v69
	v_fmac_f32_e32 v64, v128, v128
	v_fmac_f32_e32 v65, v122, v122
	v_add_f32_e32 v68, v72, v68
	v_add_f32_e32 v64, v64, v65
	v_add_f32_e32 v64, v68, v64
	ds_bpermute_b32 v65, v226, v64
	v_lshl_add_u64 v[138:139], v[218:219], 2, s[12:13]
	s_waitcnt lgkmcnt(0)
	v_add_f32_e32 v64, v64, v65
	ds_bpermute_b32 v65, v227, v64
	s_and_saveexec_b64 s[6:7], s[0:1]
	s_cbranch_execz .LBB0_2064
	s_waitcnt lgkmcnt(0)
	v_add_f32_e32 v64, v64, v65
	global_atomic_add_f32 v[138:139], v64, off
.LBB0_2064:
	s_or_b64 exec, exec, s[6:7]
	v_add_u32_e32 v222, 0x80, v216
	v_ashrrev_i32_e32 v223, 31, v222
	s_waitcnt lgkmcnt(0)
	v_lshlrev_b64 v[64:65], 13, v[222:223]
	v_lshl_add_u64 v[120:121], v[180:181], 0, v[64:65]
	global_load_dwordx4 v[234:237], v[120:121], off
	global_load_dwordx4 v[238:241], v[120:121], off offset:64
	global_load_dwordx4 v[242:245], v[120:121], off offset:512
	global_load_dwordx4 v[246:249], v[120:121], off offset:576
	v_add_u32_e32 v220, 0x90, v216
	v_add_u32_e32 v218, 0xa0, v216
	v_add_u32_e32 v216, 0xb0, v216
	v_ashrrev_i32_e32 v221, 31, v220
	v_ashrrev_i32_e32 v219, 31, v218
	v_ashrrev_i32_e32 v217, 31, v216
	v_lshlrev_b64 v[64:65], 13, v[220:221]
	v_lshlrev_b64 v[66:67], 13, v[218:219]
	v_lshlrev_b64 v[68:69], 13, v[216:217]
	v_lshl_add_u64 v[118:119], v[180:181], 0, v[64:65]
	v_lshl_add_u64 v[116:117], v[180:181], 0, v[66:67]
	v_lshl_add_u64 v[114:115], v[180:181], 0, v[68:69]
	global_load_dwordx4 v[108:111], v[118:119], off
	global_load_dwordx4 v[104:107], v[118:119], off offset:64
	global_load_dwordx4 v[100:103], v[118:119], off offset:512
	global_load_dwordx4 v[96:99], v[118:119], off offset:576
	global_load_dwordx4 v[92:95], v[116:117], off
	global_load_dwordx4 v[88:91], v[116:117], off offset:64
	global_load_dwordx4 v[84:87], v[116:117], off offset:512
	global_load_dwordx4 v[80:83], v[116:117], off offset:576
	global_load_dwordx4 v[76:79], v[114:115], off
	global_load_dwordx4 v[72:75], v[114:115], off offset:64
	global_load_dwordx4 v[68:71], v[114:115], off offset:512
	global_load_dwordx4 v[64:67], v[114:115], off offset:576
	s_waitcnt vmcnt(15)
	v_fma_f32 v62, v62, 0.5, v236
	v_fma_f32 v63, v63, 0.5, v237
	v_fma_f32 v134, v60, 0.5, v234
	v_fma_f32 v135, v61, 0.5, v235
	s_waitcnt vmcnt(14)
	v_fma_f32 v58, v58, 0.5, v240
	v_fma_f32 v59, v59, 0.5, v241
	v_fma_f32 v130, v56, 0.5, v238
	v_fma_f32 v131, v57, 0.5, v239
	s_waitcnt vmcnt(13)
	v_fma_f32 v54, v54, 0.5, v244
	v_fma_f32 v55, v55, 0.5, v245
	v_fma_f32 v60, v52, 0.5, v242
	v_fma_f32 v61, v53, 0.5, v243
	s_waitcnt vmcnt(12)
	v_fma_f32 v52, v50, 0.5, v248
	v_fma_f32 v53, v51, 0.5, v249
	v_fma_f32 v56, v48, 0.5, v246
	v_fma_f32 v57, v49, 0.5, v247
	v_mul_f32_e32 v48, v135, v135
	v_mul_f32_e32 v49, v63, v63
	v_mul_f32_e32 v50, v131, v131
	v_mul_f32_e32 v51, v59, v59
	v_mul_f32_e32 v234, v61, v61
	v_mul_f32_e32 v235, v55, v55
	v_fmac_f32_e32 v48, v134, v134
	v_fmac_f32_e32 v49, v62, v62
	v_fmac_f32_e32 v50, v130, v130
	v_fmac_f32_e32 v51, v58, v58
	v_mul_f32_e32 v236, v57, v57
	v_mul_f32_e32 v237, v53, v53
	v_fmac_f32_e32 v234, v60, v60
	v_fmac_f32_e32 v235, v54, v54
	v_add_f32_e32 v48, v48, v49
	v_add_f32_e32 v49, v50, v51
	v_fmac_f32_e32 v236, v56, v56
	v_fmac_f32_e32 v237, v52, v52
	v_add_f32_e32 v50, v234, v235
	v_add_f32_e32 v48, v48, v49
	v_add_f32_e32 v48, v48, v50
	v_add_f32_e32 v49, v236, v237
	v_add_f32_e32 v48, v48, v49
	ds_bpermute_b32 v49, v226, v48
	s_waitcnt lgkmcnt(0)
	v_add_f32_e32 v48, v48, v49
	ds_bpermute_b32 v49, v227, v48
	s_and_saveexec_b64 s[6:7], s[0:1]
	s_cbranch_execz .LBB0_2066
	v_lshl_add_u64 v[50:51], v[222:223], 2, s[12:13]
	s_waitcnt lgkmcnt(0)
	v_add_f32_e32 v48, v48, v49
	global_atomic_add_f32 v[50:51], v48, off
;     __device__ __forceinline__ void operator()(f32x4 (&acc)[2][2][4][2], const Unit& u, int wr, int wc, int fr, int fq) const {
;     ...
;             for (int m = 0; m < 4; ++m) { const int row = row0 + ai * HALF + m * 16; float sq = 0.f;
; #pragma unroll
;                 for (int bj = 0; bj < 2; ++bj)
; #pragma unroll
;                     for (int n = 0; n < 2; ++n) { const f32x4 o = pre[m][bj][n] + acc[ai][bj][m][n] * 0.5f; acc[ai][bj][m][n] = o;
;                         sq += (o[0] * o[0] + o[1] * o[1]) + (o[2] * o[2] + o[3] * o[3]); }
;                 sq += __shfl_xor(sq, 16); sq += __shfl_xor(sq, 32); if (fq == 0) __hip_atomic_fetch_add(ss + row, sq, __ATOMIC_RELAXED, __HIP_MEMORY_SCOPE_AGENT); } }
.LBB0_2066:
	s_or_b64 exec, exec, s[6:7]
	s_waitcnt vmcnt(11)
	v_fma_f32 v46, v46, 0.5, v110
	v_fma_f32 v47, v47, 0.5, v111
	v_fma_f32 v50, v44, 0.5, v108
	v_fma_f32 v51, v45, 0.5, v109
	s_waitcnt vmcnt(10)
	v_fma_f32 v42, v42, 0.5, v106
	v_fma_f32 v43, v43, 0.5, v107
	s_waitcnt lgkmcnt(0)
	v_fma_f32 v48, v40, 0.5, v104
	v_fma_f32 v49, v41, 0.5, v105
	v_mul_f32_e32 v44, v51, v51
	v_mul_f32_e32 v45, v47, v47
	v_mul_f32_e32 v40, v49, v49
	v_mul_f32_e32 v41, v43, v43
	v_fmac_f32_e32 v44, v50, v50
	v_fmac_f32_e32 v45, v46, v46
	v_fmac_f32_e32 v40, v48, v48
	v_fmac_f32_e32 v41, v42, v42
	v_add_f32_e32 v44, v44, v45
	v_add_f32_e32 v40, v40, v41
	v_add_f32_e32 v40, v44, v40
	s_waitcnt vmcnt(9)
	v_fma_f32 v38, v38, 0.5, v102
	v_fma_f32 v39, v39, 0.5, v103
	v_fma_f32 v44, v36, 0.5, v100
	v_fma_f32 v45, v37, 0.5, v101
	v_mul_f32_e32 v37, v39, v39
	v_mul_f32_e32 v36, v45, v45
	v_fmac_f32_e32 v36, v44, v44
	v_fmac_f32_e32 v37, v38, v38
	v_add_f32_e32 v36, v36, v37
	v_add_f32_e32 v100, v40, v36
	s_waitcnt vmcnt(8)
	v_fma_f32 v36, v30, 0.5, v98
	v_fma_f32 v37, v31, 0.5, v99
	v_fma_f32 v40, v28, 0.5, v96
	v_fma_f32 v41, v29, 0.5, v97
	v_mul_f32_e32 v29, v37, v37
	v_mul_f32_e32 v28, v41, v41
	v_fmac_f32_e32 v28, v40, v40
	v_fmac_f32_e32 v29, v36, v36
	v_add_f32_e32 v28, v28, v29
	v_add_f32_e32 v28, v100, v28
	ds_bpermute_b32 v29, v226, v28
	s_waitcnt lgkmcnt(0)
	v_add_f32_e32 v28, v28, v29
	ds_bpermute_b32 v29, v227, v28
	s_and_saveexec_b64 s[6:7], s[0:1]
	s_cbranch_execz .LBB0_2068
	v_lshl_add_u64 v[30:31], v[220:221], 2, s[12:13]
	s_waitcnt lgkmcnt(0)
	v_add_f32_e32 v28, v28, v29
	global_atomic_add_f32 v[30:31], v28, off
.LBB0_2068:
	s_or_b64 exec, exec, s[6:7]
	s_waitcnt vmcnt(7) lgkmcnt(0)
	v_fma_f32 v28, v34, 0.5, v94
	v_fma_f32 v29, v35, 0.5, v95
	v_fma_f32 v34, v32, 0.5, v92
	v_fma_f32 v35, v33, 0.5, v93
	s_waitcnt vmcnt(6)
	v_fma_f32 v26, v26, 0.5, v90
	v_fma_f32 v27, v27, 0.5, v91
	v_fma_f32 v32, v24, 0.5, v88
	v_fma_f32 v33, v25, 0.5, v89
	v_mul_f32_e32 v30, v35, v35
	v_mul_f32_e32 v31, v29, v29
	v_mul_f32_e32 v24, v33, v33
	v_mul_f32_e32 v25, v27, v27
	v_fmac_f32_e32 v30, v34, v34
	v_fmac_f32_e32 v31, v28, v28
	v_fmac_f32_e32 v24, v32, v32
	v_fmac_f32_e32 v25, v26, v26
	v_add_f32_e32 v30, v30, v31
	v_add_f32_e32 v24, v24, v25
	v_add_f32_e32 v24, v30, v24
	s_waitcnt vmcnt(5)
	v_fma_f32 v22, v22, 0.5, v86
	v_fma_f32 v23, v23, 0.5, v87
	v_fma_f32 v30, v20, 0.5, v84
	v_fma_f32 v31, v21, 0.5, v85
	v_mul_f32_e32 v21, v23, v23
	v_mul_f32_e32 v20, v31, v31
	v_fmac_f32_e32 v20, v30, v30
	v_fmac_f32_e32 v21, v22, v22
	v_add_f32_e32 v20, v20, v21
	v_add_f32_e32 v84, v24, v20
	s_waitcnt vmcnt(4)
	v_fma_f32 v20, v14, 0.5, v82
	v_fma_f32 v21, v15, 0.5, v83
	v_fma_f32 v24, v12, 0.5, v80
	v_fma_f32 v25, v13, 0.5, v81
	v_mul_f32_e32 v13, v21, v21
	v_mul_f32_e32 v12, v25, v25
	v_fmac_f32_e32 v12, v24, v24
	v_fmac_f32_e32 v13, v20, v20
	v_add_f32_e32 v12, v12, v13
	v_add_f32_e32 v12, v84, v12
	ds_bpermute_b32 v13, v226, v12
	s_waitcnt lgkmcnt(0)
	v_add_f32_e32 v12, v12, v13
	ds_bpermute_b32 v13, v227, v12
	s_and_saveexec_b64 s[6:7], s[0:1]
	s_cbranch_execz .LBB0_2070
	v_lshl_add_u64 v[14:15], v[218:219], 2, s[12:13]
	s_waitcnt lgkmcnt(0)
	v_add_f32_e32 v12, v12, v13
	global_atomic_add_f32 v[14:15], v12, off
.LBB0_2070:
	s_or_b64 exec, exec, s[6:7]
	s_waitcnt vmcnt(3) lgkmcnt(0)
	v_fma_f32 v12, v18, 0.5, v78
	v_fma_f32 v13, v19, 0.5, v79
	v_fma_f32 v14, v16, 0.5, v76
	v_fma_f32 v15, v17, 0.5, v77
	v_mul_f32_e32 v17, v13, v13
	v_mul_f32_e32 v16, v15, v15
	v_fmac_f32_e32 v16, v14, v14
	v_fmac_f32_e32 v17, v12, v12
	s_waitcnt vmcnt(2)
	v_fma_f32 v10, v10, 0.5, v74
	v_fma_f32 v11, v11, 0.5, v75
	v_fma_f32 v8, v8, 0.5, v72
	v_fma_f32 v9, v9, 0.5, v73
	v_add_f32_e32 v16, v16, v17
	v_mul_f32_e32 v17, v9, v9
	v_mul_f32_e32 v18, v11, v11
	v_fmac_f32_e32 v17, v8, v8
	v_fmac_f32_e32 v18, v10, v10
	v_add_f32_e32 v17, v17, v18
	s_waitcnt vmcnt(1)
	v_fma_f32 v6, v6, 0.5, v70
	v_fma_f32 v7, v7, 0.5, v71
	v_fma_f32 v4, v4, 0.5, v68
	v_fma_f32 v5, v5, 0.5, v69
	v_add_f32_e32 v16, v16, v17
	v_mul_f32_e32 v17, v5, v5
	v_mul_f32_e32 v18, v7, v7
	v_fmac_f32_e32 v17, v4, v4
	v_fmac_f32_e32 v18, v6, v6
	v_add_f32_e32 v17, v17, v18
	s_waitcnt vmcnt(0)
	v_fma_f32 v2, v2, 0.5, v66
	v_fma_f32 v3, v3, 0.5, v67
	v_fma_f32 v0, v0, 0.5, v64
	v_fma_f32 v1, v1, 0.5, v65
	v_add_f32_e32 v16, v16, v17
	v_mul_f32_e32 v17, v1, v1
	v_mul_f32_e32 v18, v3, v3
	v_fmac_f32_e32 v17, v0, v0
	v_fmac_f32_e32 v18, v2, v2
	v_add_f32_e32 v17, v17, v18
	v_add_f32_e32 v16, v16, v17
	ds_bpermute_b32 v17, v226, v16
	s_waitcnt lgkmcnt(0)
	v_add_f32_e32 v16, v16, v17
	ds_bpermute_b32 v17, v227, v16
	s_and_saveexec_b64 s[6:7], s[0:1]
	s_cbranch_execz .LBB0_2072
	v_lshl_add_u64 v[18:19], v[216:217], 2, s[12:13]
	s_waitcnt lgkmcnt(0)
	v_add_f32_e32 v16, v16, v17
	global_atomic_add_f32 v[18:19], v16, off

; template <int RSM> __device__ __forceinline__ float row_scale(const float* p, int row) { const float v = __hip_atomic_load(p + row, __ATOMIC_RELAXED, __HIP_MEMORY_SCOPE_AGENT); return RSM == 0 ? v : 1.0f / sqrtf(v * (1.f / DM) + EPS); }
;     __device__ __forceinline__ void operator()(f32x4 (&acc)[2][2][4][2], const Unit& u, int wr, int wc, int fr, int fq) const {
;     ...
;         for (int ai = 0; ai < 2; ++ai)
; #pragma unroll
;             for (int m = 0; m < 4; ++m) { const int row = row0 + ai * HALF + m * 16; const size_t off = (size_t)row * ldc + col0; const float rs = row_scale<1>(ss, row);
; #pragma unroll
;                 for (int bj = 0; bj < 2; ++bj)
; #pragma unroll
;                     for (int n = 0; n < 2; ++n) { const size_t p = off + bj * HALF + n * 16; const f32x4 w4 = *(const f32x4*)(wfin + col0 + bj * HALF + n * 16); *(f32x4*)(out + p) = acc[ai][bj][m][n] * rs * w4; } }
.LBB0_2086:
	s_or_b64 exec, exec, s[6:7]
	global_load_dword v64, v[112:113], off sc1
	s_waitcnt lgkmcnt(0)
	global_load_dwordx4 v[16:19], v[182:183], off
	s_waitcnt vmcnt(1)
	v_fmamk_f32 v64, v64, 0x3a000000, v230
	v_mul_f32_e32 v65, 0x4f800000, v64
	v_cmp_gt_f32_e32 vcc, s42, v64
	s_nop 1
	v_cndmask_b32_e32 v64, v64, v65, vcc
	v_sqrt_f32_e32 v65, v64
	s_nop 0
	v_add_u32_e32 v66, -1, v65
	v_add_u32_e32 v67, 1, v65
	v_fma_f32 v68, -v66, v65, v64
	v_fma_f32 v69, -v67, v65, v64
	v_cmp_ge_f32_e64 s[6:7], 0, v68
	s_nop 1
	v_cndmask_b32_e64 v65, v65, v66, s[6:7]
	v_cmp_lt_f32_e64 s[6:7], 0, v69
	s_nop 1
	v_cndmask_b32_e64 v65, v65, v67, s[6:7]
	v_mul_f32_e32 v66, 0x37800000, v65
	v_cndmask_b32_e32 v65, v65, v66, vcc
	v_cmp_class_f32_e32 vcc, v64, v231
	s_nop 1
	v_cndmask_b32_e32 v64, v65, v64, vcc
	v_div_scale_f32 v65, s[6:7], v64, v64, 1.0
	v_rcp_f32_e32 v66, v65
	v_div_scale_f32 v67, vcc, 1.0, v64, 1.0
	v_fma_f32 v68, -v65, v66, 1.0
	v_fmac_f32_e32 v66, v68, v66
	v_mul_f32_e32 v68, v67, v66
	v_fma_f32 v69, -v65, v68, v67
	v_fmac_f32_e32 v68, v69, v66
	v_fma_f32 v65, -v65, v68, v67
	v_div_fmas_f32 v65, v65, v66, v68
	v_div_fixup_f32 v64, v65, v64, 1.0
	v_mul_f32_e32 v66, v210, v64
	v_mul_f32_e32 v67, v211, v64
	v_mul_f32_e32 v68, v202, v64
	v_mul_f32_e32 v69, v203, v64
	s_waitcnt vmcnt(0)
	v_mul_f32_e32 v16, v16, v66
	v_mul_f32_e32 v17, v17, v67
	v_mul_f32_e32 v18, v18, v68
	v_mul_f32_e32 v19, v19, v69
	global_store_dwordx4 v[194:195], v[16:19], off
	global_load_dwordx4 v[16:19], v[182:183], off offset:64
	v_mul_f32_e32 v66, v200, v64
	v_mul_f32_e32 v67, v201, v64
	v_mul_f32_e32 v68, v208, v64
	v_mul_f32_e32 v69, v209, v64
	s_waitcnt vmcnt(0)
	v_mul_f32_e32 v18, v18, v66
	v_mul_f32_e32 v19, v19, v67
	v_mul_f32_e32 v16, v16, v68
	v_mul_f32_e32 v17, v17, v69
	global_store_dwordx4 v[194:195], v[16:19], off offset:64
	global_load_dwordx4 v[16:19], v[182:183], off offset:512
	v_mul_f32_e32 v66, v198, v64
	v_mul_f32_e32 v67, v199, v64
	v_mul_f32_e32 v68, v206, v64
	v_mul_f32_e32 v69, v207, v64
	s_waitcnt vmcnt(0)
	v_mul_f32_e32 v18, v18, v66
	v_mul_f32_e32 v19, v19, v67
	v_mul_f32_e32 v16, v16, v68
	v_mul_f32_e32 v17, v17, v69
	global_store_dwordx4 v[194:195], v[16:19], off offset:512
	global_load_dwordx4 v[16:19], v[182:183], off offset:576
	v_mul_f32_e32 v66, v196, v64
	v_mul_f32_e32 v67, v197, v64
	v_mul_f32_e32 v65, v205, v64
	v_mul_f32_e32 v64, v204, v64
	s_waitcnt vmcnt(0)
	v_mul_f32_e32 v18, v18, v66
	v_mul_f32_e32 v19, v19, v67
	v_mul_f32_e32 v16, v16, v64
	v_mul_f32_e32 v17, v17, v65
	global_store_dwordx4 v[194:195], v[16:19], off offset:576
	global_load_dword v64, v[214:215], off sc1
	s_nop 0
	global_load_dwordx4 v[16:19], v[182:183], off
	s_waitcnt vmcnt(1)
	v_fmamk_f32 v64, v64, 0x3a000000, v230
	v_mul_f32_e32 v65, 0x4f800000, v64
	v_cmp_gt_f32_e32 vcc, s42, v64
	s_nop 1
	v_cndmask_b32_e32 v64, v64, v65, vcc
	v_sqrt_f32_e32 v65, v64
	s_nop 0
	v_add_u32_e32 v66, -1, v65
	v_add_u32_e32 v67, 1, v65
	v_fma_f32 v68, -v66, v65, v64
	v_fma_f32 v69, -v67, v65, v64
	v_cmp_ge_f32_e64 s[6:7], 0, v68
	s_nop 1
	v_cndmask_b32_e64 v65, v65, v66, s[6:7]
	v_cmp_lt_f32_e64 s[6:7], 0, v69
	s_nop 1
	v_cndmask_b32_e64 v65, v65, v67, s[6:7]
	v_mul_f32_e32 v66, 0x37800000, v65
	v_cndmask_b32_e32 v65, v65, v66, vcc
	v_cmp_class_f32_e32 vcc, v64, v231
	s_nop 1
	v_cndmask_b32_e32 v64, v65, v64, vcc
	v_div_scale_f32 v65, s[6:7], v64, v64, 1.0
	v_rcp_f32_e32 v66, v65
	v_div_scale_f32 v67, vcc, 1.0, v64, 1.0
	v_fma_f32 v68, -v65, v66, 1.0
	v_fmac_f32_e32 v66, v68, v66
	v_mul_f32_e32 v68, v67, v66
	v_fma_f32 v69, -v65, v68, v67
	v_fmac_f32_e32 v68, v69, v66
	v_fma_f32 v65, -v65, v68, v67
	v_div_fmas_f32 v65, v65, v66, v68
	v_div_fixup_f32 v64, v65, v64, 1.0
	v_mul_f32_e32 v66, v172, v64
	v_mul_f32_e32 v67, v173, v64
	v_mul_f32_e32 v68, v174, v64
	v_mul_f32_e32 v69, v175, v64
	s_waitcnt vmcnt(0)
	v_mul_f32_e32 v16, v16, v66
	v_mul_f32_e32 v17, v17, v67
	v_mul_f32_e32 v18, v18, v68
	v_mul_f32_e32 v19, v19, v69
	global_store_dwordx4 v[192:193], v[16:19], off
	global_load_dwordx4 v[16:19], v[182:183], off offset:64
	v_mul_f32_e32 v66, v170, v64
	v_mul_f32_e32 v67, v171, v64
	v_mul_f32_e32 v68, v168, v64
	v_mul_f32_e32 v69, v169, v64
	s_waitcnt vmcnt(0)
	v_mul_f32_e32 v18, v18, v66
	v_mul_f32_e32 v19, v19, v67
	v_mul_f32_e32 v16, v16, v68
	v_mul_f32_e32 v17, v17, v69
	global_store_dwordx4 v[192:193], v[16:19], off offset:64
	global_load_dwordx4 v[16:19], v[182:183], off offset:512
	v_mul_f32_e32 v66, v166, v64
	v_mul_f32_e32 v67, v167, v64
	v_mul_f32_e32 v68, v164, v64
	v_mul_f32_e32 v69, v165, v64
	s_waitcnt vmcnt(0)
	v_mul_f32_e32 v18, v18, v66
	v_mul_f32_e32 v19, v19, v67
	v_mul_f32_e32 v16, v16, v68
	v_mul_f32_e32 v17, v17, v69
	global_store_dwordx4 v[192:193], v[16:19], off offset:512
	global_load_dwordx4 v[16:19], v[182:183], off offset:576
	v_mul_f32_e32 v66, v162, v64
	v_mul_f32_e32 v67, v163, v64
	v_mul_f32_e32 v65, v161, v64
	v_mul_f32_e32 v64, v160, v64
	s_waitcnt vmcnt(0)
	v_mul_f32_e32 v18, v18, v66
	v_mul_f32_e32 v19, v19, v67
	v_mul_f32_e32 v16, v16, v64
	v_mul_f32_e32 v17, v17, v65
	global_store_dwordx4 v[192:193], v[16:19], off offset:576
	global_load_dword v64, v[212:213], off sc1
	s_nop 0
	global_load_dwordx4 v[16:19], v[182:183], off
	s_waitcnt vmcnt(1)
; template <int RSM> __device__ __forceinline__ float row_scale(const float* p, int row) { const float v = __hip_atomic_load(p + row, __ATOMIC_RELAXED, __HIP_MEMORY_SCOPE_AGENT); return RSM == 0 ? v : 1.0f / sqrtf(v * (1.f / DM) + EPS); }
;     __device__ __forceinline__ void operator()(f32x4 (&acc)[2][2][4][2], const Unit& u, int wr, int wc, int fr, int fq) const {
;     ...
;         for (int ai = 0; ai < 2; ++ai)
; #pragma unroll
;             for (int m = 0; m < 4; ++m) { const int row = row0 + ai * HALF + m * 16; const size_t off = (size_t)row * ldc + col0; const float rs = row_scale<1>(ss, row);
; #pragma unroll
;                 for (int bj = 0; bj < 2; ++bj)
; #pragma unroll
;                     for (int n = 0; n < 2; ++n) { const size_t p = off + bj * HALF + n * 16; const f32x4 w4 = *(const f32x4*)(wfin + col0 + bj * HALF + n * 16); *(f32x4*)(out + p) = acc[ai][bj][m][n] * rs * w4; } }
	v_fmamk_f32 v64, v64, 0x3a000000, v230
	v_mul_f32_e32 v65, 0x4f800000, v64
	v_cmp_gt_f32_e32 vcc, s42, v64
	s_nop 1
	v_cndmask_b32_e32 v64, v64, v65, vcc
	v_sqrt_f32_e32 v65, v64
	s_nop 0
	v_add_u32_e32 v66, -1, v65
	v_add_u32_e32 v67, 1, v65
	v_fma_f32 v68, -v66, v65, v64
	v_fma_f32 v69, -v67, v65, v64
	v_cmp_ge_f32_e64 s[6:7], 0, v68
	s_nop 1
	v_cndmask_b32_e64 v65, v65, v66, s[6:7]
	v_cmp_lt_f32_e64 s[6:7], 0, v69
	s_nop 1
	v_cndmask_b32_e64 v65, v65, v67, s[6:7]
	v_mul_f32_e32 v66, 0x37800000, v65
	v_cndmask_b32_e32 v65, v65, v66, vcc
	v_cmp_class_f32_e32 vcc, v64, v231
	s_nop 1
	v_cndmask_b32_e32 v64, v65, v64, vcc
	v_div_scale_f32 v65, s[6:7], v64, v64, 1.0
	v_rcp_f32_e32 v66, v65
	v_div_scale_f32 v67, vcc, 1.0, v64, 1.0
	v_fma_f32 v68, -v65, v66, 1.0
	v_fmac_f32_e32 v66, v68, v66
	v_mul_f32_e32 v68, v67, v66
	v_fma_f32 v69, -v65, v68, v67
	v_fmac_f32_e32 v68, v69, v66
	v_fma_f32 v65, -v65, v68, v67
	v_div_fmas_f32 v65, v65, v66, v68
	v_div_fixup_f32 v64, v65, v64, 1.0
	v_mul_f32_e32 v66, v156, v64
	v_mul_f32_e32 v67, v157, v64
	v_mul_f32_e32 v68, v158, v64
	v_mul_f32_e32 v69, v159, v64
	s_waitcnt vmcnt(0)
	v_mul_f32_e32 v16, v16, v66
	v_mul_f32_e32 v17, v17, v67
	v_mul_f32_e32 v18, v18, v68
	v_mul_f32_e32 v19, v19, v69
	global_store_dwordx4 v[190:191], v[16:19], off
	global_load_dwordx4 v[16:19], v[182:183], off offset:64
	v_mul_f32_e32 v66, v154, v64
	v_mul_f32_e32 v67, v155, v64
	v_mul_f32_e32 v68, v152, v64
	v_mul_f32_e32 v69, v153, v64
	s_waitcnt vmcnt(0)
	v_mul_f32_e32 v18, v18, v66
	v_mul_f32_e32 v19, v19, v67
	v_mul_f32_e32 v16, v16, v68
	v_mul_f32_e32 v17, v17, v69
	global_store_dwordx4 v[190:191], v[16:19], off offset:64
	global_load_dwordx4 v[16:19], v[182:183], off offset:512
	v_mul_f32_e32 v66, v150, v64
	v_mul_f32_e32 v67, v151, v64
	v_mul_f32_e32 v68, v148, v64
	v_mul_f32_e32 v69, v149, v64
	s_waitcnt vmcnt(0)
	v_mul_f32_e32 v18, v18, v66
	v_mul_f32_e32 v19, v19, v67
	v_mul_f32_e32 v16, v16, v68
	v_mul_f32_e32 v17, v17, v69
	global_store_dwordx4 v[190:191], v[16:19], off offset:512
	global_load_dwordx4 v[16:19], v[182:183], off offset:576
	v_mul_f32_e32 v66, v146, v64
	v_mul_f32_e32 v67, v147, v64
	v_mul_f32_e32 v65, v145, v64
	v_mul_f32_e32 v64, v144, v64
	s_waitcnt vmcnt(0)
	v_mul_f32_e32 v18, v18, v66
	v_mul_f32_e32 v19, v19, v67
	v_mul_f32_e32 v16, v16, v64
	v_mul_f32_e32 v17, v17, v65
	global_store_dwordx4 v[190:191], v[16:19], off offset:576
	global_load_dword v64, v[138:139], off sc1
	s_nop 0
	global_load_dwordx4 v[16:19], v[182:183], off
	s_waitcnt vmcnt(1)
	v_fmamk_f32 v64, v64, 0x3a000000, v230
	v_mul_f32_e32 v65, 0x4f800000, v64
	v_cmp_gt_f32_e32 vcc, s42, v64
	s_nop 1
	v_cndmask_b32_e32 v64, v64, v65, vcc
	v_sqrt_f32_e32 v65, v64
	s_nop 0
	v_add_u32_e32 v66, -1, v65
	v_add_u32_e32 v67, 1, v65
	v_fma_f32 v68, -v66, v65, v64
	v_fma_f32 v69, -v67, v65, v64
	v_cmp_ge_f32_e64 s[6:7], 0, v68
	s_nop 1
	v_cndmask_b32_e64 v65, v65, v66, s[6:7]
	v_cmp_lt_f32_e64 s[6:7], 0, v69
	s_nop 1
	v_cndmask_b32_e64 v65, v65, v67, s[6:7]
	v_mul_f32_e32 v66, 0x37800000, v65
	v_cndmask_b32_e32 v65, v65, v66, vcc
	v_cmp_class_f32_e32 vcc, v64, v231
	s_nop 1
	v_cndmask_b32_e32 v64, v65, v64, vcc
	v_div_scale_f32 v65, s[6:7], v64, v64, 1.0
	v_rcp_f32_e32 v66, v65
	v_div_scale_f32 v67, vcc, 1.0, v64, 1.0
	v_fma_f32 v68, -v65, v66, 1.0
	v_fmac_f32_e32 v66, v68, v66
	v_mul_f32_e32 v68, v67, v66
	v_fma_f32 v69, -v65, v68, v67
	v_fmac_f32_e32 v68, v69, v66
	v_fma_f32 v65, -v65, v68, v67
	v_div_fmas_f32 v65, v65, v66, v68
	v_div_fixup_f32 v64, v65, v64, 1.0
	v_mul_f32_e32 v66, v140, v64
	v_mul_f32_e32 v67, v141, v64
	v_mul_f32_e32 v68, v142, v64
	v_mul_f32_e32 v69, v143, v64
	s_waitcnt vmcnt(0)
	v_mul_f32_e32 v16, v16, v66
	v_mul_f32_e32 v17, v17, v67
	v_mul_f32_e32 v18, v18, v68
	v_mul_f32_e32 v19, v19, v69
	global_store_dwordx4 v[188:189], v[16:19], off
	global_load_dwordx4 v[16:19], v[182:183], off offset:64
	v_mul_f32_e32 v66, v126, v64
	v_mul_f32_e32 v67, v127, v64
	v_mul_f32_e32 v68, v136, v64
	v_mul_f32_e32 v69, v137, v64
	s_waitcnt vmcnt(0)
	v_mul_f32_e32 v18, v18, v66
	v_mul_f32_e32 v19, v19, v67
	v_mul_f32_e32 v16, v16, v68
	v_mul_f32_e32 v17, v17, v69
	global_store_dwordx4 v[188:189], v[16:19], off offset:64
	global_load_dwordx4 v[16:19], v[182:183], off offset:512
	v_mul_f32_e32 v66, v124, v64
	v_mul_f32_e32 v67, v125, v64
	v_mul_f32_e32 v68, v132, v64
	v_mul_f32_e32 v69, v133, v64
	s_waitcnt vmcnt(0)
	v_mul_f32_e32 v18, v18, v66
	v_mul_f32_e32 v19, v19, v67
	v_mul_f32_e32 v16, v16, v68
	v_mul_f32_e32 v17, v17, v69
	global_store_dwordx4 v[188:189], v[16:19], off offset:512
	global_load_dwordx4 v[16:19], v[182:183], off offset:576
	v_mul_f32_e32 v66, v122, v64
	v_mul_f32_e32 v67, v123, v64
	v_mul_f32_e32 v65, v129, v64
	v_mul_f32_e32 v64, v128, v64
	s_waitcnt vmcnt(0)
	v_mul_f32_e32 v18, v18, v66
	v_mul_f32_e32 v19, v19, v67
	v_mul_f32_e32 v16, v16, v64
	v_mul_f32_e32 v17, v17, v65
	global_store_dwordx4 v[188:189], v[16:19], off offset:576
	global_load_dword v64, v[112:113], off offset:512 sc1
	s_nop 0
	global_load_dwordx4 v[16:19], v[182:183], off
	s_waitcnt vmcnt(1)
	v_fmamk_f32 v64, v64, 0x3a000000, v230
	v_mul_f32_e32 v65, 0x4f800000, v64
	v_cmp_gt_f32_e32 vcc, s42, v64
	s_nop 1
	v_cndmask_b32_e32 v64, v64, v65, vcc
	v_sqrt_f32_e32 v65, v64
	s_nop 0
	v_add_u32_e32 v66, -1, v65
	v_add_u32_e32 v67, 1, v65
	v_fma_f32 v68, -v66, v65, v64
	v_fma_f32 v69, -v67, v65, v64
	v_cmp_ge_f32_e64 s[6:7], 0, v68
	s_nop 1
	v_cndmask_b32_e64 v65, v65, v66, s[6:7]
	v_cmp_lt_f32_e64 s[6:7], 0, v69
	s_nop 1
	v_cndmask_b32_e64 v65, v65, v67, s[6:7]
	v_mul_f32_e32 v66, 0x37800000, v65
	v_cndmask_b32_e32 v65, v65, v66, vcc
	v_cmp_class_f32_e32 vcc, v64, v231
	s_nop 1
	v_cndmask_b32_e32 v64, v65, v64, vcc
	v_div_scale_f32 v65, s[6:7], v64, v64, 1.0
	v_rcp_f32_e32 v66, v65
	v_div_scale_f32 v67, vcc, 1.0, v64, 1.0
	v_fma_f32 v68, -v65, v66, 1.0
	v_fmac_f32_e32 v66, v68, v66
	v_mul_f32_e32 v68, v67, v66
	v_fma_f32 v69, -v65, v68, v67
	v_fmac_f32_e32 v68, v69, v66
	v_fma_f32 v65, -v65, v68, v67
	v_div_fmas_f32 v65, v65, v66, v68
	v_div_fixup_f32 v64, v65, v64, 1.0
	v_mul_f32_e32 v66, v134, v64
	v_mul_f32_e32 v67, v135, v64
	v_mul_f32_e32 v62, v62, v64
	v_mul_f32_e32 v63, v63, v64
	s_waitcnt vmcnt(0)
; template <int RSM> __device__ __forceinline__ float row_scale(const float* p, int row) { const float v = __hip_atomic_load(p + row, __ATOMIC_RELAXED, __HIP_MEMORY_SCOPE_AGENT); return RSM == 0 ? v : 1.0f / sqrtf(v * (1.f / DM) + EPS); }
;     __device__ __forceinline__ void operator()(f32x4 (&acc)[2][2][4][2], const Unit& u, int wr, int wc, int fr, int fq) const {
;     ...
;         for (int ai = 0; ai < 2; ++ai)
; #pragma unroll
;             for (int m = 0; m < 4; ++m) { const int row = row0 + ai * HALF + m * 16; const size_t off = (size_t)row * ldc + col0; const float rs = row_scale<1>(ss, row);
; #pragma unroll
;                 for (int bj = 0; bj < 2; ++bj)
; #pragma unroll
;                     for (int n = 0; n < 2; ++n) { const size_t p = off + bj * HALF + n * 16; const f32x4 w4 = *(const f32x4*)(wfin + col0 + bj * HALF + n * 16); *(f32x4*)(out + p) = acc[ai][bj][m][n] * rs * w4; } }
	v_mul_f32_e32 v16, v16, v66
	v_mul_f32_e32 v17, v17, v67
	v_mul_f32_e32 v18, v18, v62
	v_mul_f32_e32 v19, v19, v63
	global_store_dwordx4 v[120:121], v[16:19], off
	global_load_dwordx4 v[16:19], v[182:183], off offset:64
	v_mul_f32_e32 v58, v58, v64
	v_mul_f32_e32 v59, v59, v64
	v_mul_f32_e32 v62, v130, v64
	v_mul_f32_e32 v63, v131, v64
	v_mul_f32_e32 v54, v54, v64
	v_mul_f32_e32 v55, v55, v64
	v_mul_f32_e32 v52, v52, v64
	v_mul_f32_e32 v53, v53, v64
	s_waitcnt vmcnt(0)
	v_mul_f32_e32 v16, v16, v62
	v_mul_f32_e32 v17, v17, v63
	v_mul_f32_e32 v18, v18, v58
	v_mul_f32_e32 v19, v19, v59
	global_store_dwordx4 v[120:121], v[16:19], off offset:64
	global_load_dwordx4 v[16:19], v[182:183], off offset:512
	v_mul_f32_e32 v58, v60, v64
	v_mul_f32_e32 v59, v61, v64
	s_waitcnt vmcnt(0)
	v_mul_f32_e32 v18, v18, v54
	v_mul_f32_e32 v19, v19, v55
	v_mul_f32_e32 v16, v16, v58
	v_mul_f32_e32 v17, v17, v59
	global_store_dwordx4 v[120:121], v[16:19], off offset:512
	global_load_dwordx4 v[16:19], v[182:183], off offset:576
	v_mul_f32_e32 v54, v56, v64
	v_mul_f32_e32 v55, v57, v64
	s_waitcnt vmcnt(0)
	v_mul_f32_e32 v18, v18, v52
	v_mul_f32_e32 v19, v19, v53
	v_mul_f32_e32 v16, v16, v54
	v_mul_f32_e32 v17, v17, v55
	global_store_dwordx4 v[120:121], v[16:19], off offset:576
	global_load_dword v52, v[112:113], off offset:576 sc1
	s_nop 0
	global_load_dwordx4 v[16:19], v[182:183], off
	s_waitcnt vmcnt(1)
	v_fmamk_f32 v52, v52, 0x3a000000, v230
	v_mul_f32_e32 v53, 0x4f800000, v52
	v_cmp_gt_f32_e32 vcc, s42, v52
	s_nop 1
	v_cndmask_b32_e32 v52, v52, v53, vcc
	v_sqrt_f32_e32 v53, v52
	s_nop 0
	v_add_u32_e32 v54, -1, v53
	v_add_u32_e32 v55, 1, v53
	v_fma_f32 v56, -v54, v53, v52
	v_fma_f32 v57, -v55, v53, v52
	v_cmp_ge_f32_e64 s[6:7], 0, v56
	s_nop 1
	v_cndmask_b32_e64 v53, v53, v54, s[6:7]
	v_cmp_lt_f32_e64 s[6:7], 0, v57
	s_nop 1
	v_cndmask_b32_e64 v53, v53, v55, s[6:7]
	v_mul_f32_e32 v54, 0x37800000, v53
	v_cndmask_b32_e32 v53, v53, v54, vcc
	v_cmp_class_f32_e32 vcc, v52, v231
	s_nop 1
	v_cndmask_b32_e32 v52, v53, v52, vcc
	v_div_scale_f32 v53, s[6:7], v52, v52, 1.0
	v_rcp_f32_e32 v54, v53
	v_div_scale_f32 v55, vcc, 1.0, v52, 1.0
	v_fma_f32 v56, -v53, v54, 1.0
	v_fmac_f32_e32 v54, v56, v54
	v_mul_f32_e32 v56, v55, v54
	v_fma_f32 v57, -v53, v56, v55
	v_fmac_f32_e32 v56, v57, v54
	v_fma_f32 v53, -v53, v56, v55
	v_div_fmas_f32 v53, v53, v54, v56
	v_div_fixup_f32 v52, v53, v52, 1.0
	v_mul_f32_e32 v50, v50, v52
	v_mul_f32_e32 v51, v51, v52
	v_mul_f32_e32 v46, v46, v52
	v_mul_f32_e32 v47, v47, v52
	s_waitcnt vmcnt(0)
	v_mul_f32_e32 v16, v16, v50
	v_mul_f32_e32 v17, v17, v51
	v_mul_f32_e32 v18, v18, v46
	v_mul_f32_e32 v19, v19, v47
	global_store_dwordx4 v[118:119], v[16:19], off
	global_load_dwordx4 v[16:19], v[182:183], off offset:64
	v_mul_f32_e32 v42, v42, v52
	v_mul_f32_e32 v43, v43, v52
	v_mul_f32_e32 v46, v48, v52
	v_mul_f32_e32 v47, v49, v52
	v_mul_f32_e32 v38, v38, v52
	v_mul_f32_e32 v39, v39, v52
	v_mul_f32_e32 v36, v36, v52
	v_mul_f32_e32 v37, v37, v52
	s_waitcnt vmcnt(0)
	v_mul_f32_e32 v16, v16, v46
	v_mul_f32_e32 v17, v17, v47
	v_mul_f32_e32 v18, v18, v42
	v_mul_f32_e32 v19, v19, v43
	global_store_dwordx4 v[118:119], v[16:19], off offset:64
	global_load_dwordx4 v[16:19], v[182:183], off offset:512
	v_mul_f32_e32 v42, v44, v52
	v_mul_f32_e32 v43, v45, v52
	s_waitcnt vmcnt(0)
	v_mul_f32_e32 v18, v18, v38
	v_mul_f32_e32 v19, v19, v39
	v_mul_f32_e32 v16, v16, v42
	v_mul_f32_e32 v17, v17, v43
	global_store_dwordx4 v[118:119], v[16:19], off offset:512
	global_load_dwordx4 v[16:19], v[182:183], off offset:576
	v_mul_f32_e32 v38, v40, v52
	v_mul_f32_e32 v39, v41, v52
	s_waitcnt vmcnt(0)
	v_mul_f32_e32 v18, v18, v36
	v_mul_f32_e32 v19, v19, v37
	v_mul_f32_e32 v16, v16, v38
	v_mul_f32_e32 v17, v17, v39
	global_store_dwordx4 v[118:119], v[16:19], off offset:576
	global_load_dword v36, v[112:113], off offset:640 sc1
	s_nop 0
	global_load_dwordx4 v[16:19], v[182:183], off
	s_waitcnt vmcnt(1)
; template <int RSM> __device__ __forceinline__ float row_scale(const float* p, int row) { const float v = __hip_atomic_load(p + row, __ATOMIC_RELAXED, __HIP_MEMORY_SCOPE_AGENT); return RSM == 0 ? v : 1.0f / sqrtf(v * (1.f / DM) + EPS); }
;     __device__ __forceinline__ void operator()(f32x4 (&acc)[2][2][4][2], const Unit& u, int wr, int wc, int fr, int fq) const {
;     ...
;         for (int ai = 0; ai < 2; ++ai)
; #pragma unroll
;             for (int m = 0; m < 4; ++m) { const int row = row0 + ai * HALF + m * 16; const size_t off = (size_t)row * ldc + col0; const float rs = row_scale<1>(ss, row);
; #pragma unroll
;                 for (int bj = 0; bj < 2; ++bj)
; #pragma unroll
;                     for (int n = 0; n < 2; ++n) { const size_t p = off + bj * HALF + n * 16; const f32x4 w4 = *(const f32x4*)(wfin + col0 + bj * HALF + n * 16); *(f32x4*)(out + p) = acc[ai][bj][m][n] * rs * w4; } }
	v_fmamk_f32 v36, v36, 0x3a000000, v230
	v_mul_f32_e32 v37, 0x4f800000, v36
	v_cmp_gt_f32_e32 vcc, s42, v36
	s_nop 1
	v_cndmask_b32_e32 v36, v36, v37, vcc
	v_sqrt_f32_e32 v37, v36
	s_nop 0
	v_add_u32_e32 v38, -1, v37
	v_add_u32_e32 v39, 1, v37
	v_fma_f32 v40, -v38, v37, v36
	v_fma_f32 v41, -v39, v37, v36
	v_cmp_ge_f32_e64 s[6:7], 0, v40
	s_nop 1
	v_cndmask_b32_e64 v37, v37, v38, s[6:7]
	v_cmp_lt_f32_e64 s[6:7], 0, v41
	s_nop 1
	v_cndmask_b32_e64 v37, v37, v39, s[6:7]
	v_mul_f32_e32 v38, 0x37800000, v37
	v_cndmask_b32_e32 v37, v37, v38, vcc
	v_cmp_class_f32_e32 vcc, v36, v231
	s_nop 1
	v_cndmask_b32_e32 v36, v37, v36, vcc
	v_div_scale_f32 v37, s[6:7], v36, v36, 1.0
	v_rcp_f32_e32 v38, v37
	v_div_scale_f32 v39, vcc, 1.0, v36, 1.0
	v_fma_f32 v40, -v37, v38, 1.0
	v_fmac_f32_e32 v38, v40, v38
	v_mul_f32_e32 v40, v39, v38
	v_fma_f32 v41, -v37, v40, v39
	v_fmac_f32_e32 v40, v41, v38
	v_fma_f32 v37, -v37, v40, v39
	v_div_fmas_f32 v37, v37, v38, v40
	v_div_fixup_f32 v36, v37, v36, 1.0
	v_mul_f32_e32 v34, v34, v36
	v_mul_f32_e32 v35, v35, v36
	v_mul_f32_e32 v28, v28, v36
	v_mul_f32_e32 v29, v29, v36
	s_waitcnt vmcnt(0)
	v_mul_f32_e32 v16, v16, v34
	v_mul_f32_e32 v17, v17, v35
	v_mul_f32_e32 v18, v18, v28
	v_mul_f32_e32 v19, v19, v29
	global_store_dwordx4 v[116:117], v[16:19], off
	global_load_dwordx4 v[16:19], v[182:183], off offset:64
	v_mul_f32_e32 v26, v26, v36
	v_mul_f32_e32 v27, v27, v36
	v_mul_f32_e32 v28, v32, v36
	v_mul_f32_e32 v29, v33, v36
	v_mul_f32_e32 v22, v22, v36
	v_mul_f32_e32 v23, v23, v36
	v_mul_f32_e32 v20, v20, v36
	v_mul_f32_e32 v21, v21, v36
	s_waitcnt vmcnt(0)
	v_mul_f32_e32 v16, v16, v28
	v_mul_f32_e32 v17, v17, v29
	v_mul_f32_e32 v18, v18, v26
	v_mul_f32_e32 v19, v19, v27
	global_store_dwordx4 v[116:117], v[16:19], off offset:64
	global_load_dwordx4 v[16:19], v[182:183], off offset:512
	v_mul_f32_e32 v26, v30, v36
	v_mul_f32_e32 v27, v31, v36
	s_waitcnt vmcnt(0)
	v_mul_f32_e32 v18, v18, v22
	v_mul_f32_e32 v19, v19, v23
	v_mul_f32_e32 v16, v16, v26
	v_mul_f32_e32 v17, v17, v27
	global_store_dwordx4 v[116:117], v[16:19], off offset:512
	global_load_dwordx4 v[16:19], v[182:183], off offset:576
	v_mul_f32_e32 v22, v24, v36
	v_mul_f32_e32 v23, v25, v36
	s_waitcnt vmcnt(0)
	v_mul_f32_e32 v18, v18, v20
	v_mul_f32_e32 v19, v19, v21
	v_mul_f32_e32 v16, v16, v22
	v_mul_f32_e32 v17, v17, v23
	global_store_dwordx4 v[116:117], v[16:19], off offset:576
	global_load_dword v20, v[112:113], off offset:704 sc1
	s_nop 0
	global_load_dwordx4 v[16:19], v[182:183], off
	s_waitcnt vmcnt(1)
	v_fmamk_f32 v20, v20, 0x3a000000, v230
	v_mul_f32_e32 v21, 0x4f800000, v20
	v_cmp_gt_f32_e32 vcc, s42, v20
	s_nop 1
	v_cndmask_b32_e32 v20, v20, v21, vcc
	v_sqrt_f32_e32 v21, v20
	s_nop 0
	v_add_u32_e32 v22, -1, v21
	v_add_u32_e32 v23, 1, v21
	v_fma_f32 v24, -v22, v21, v20
	v_fma_f32 v25, -v23, v21, v20
	v_cmp_ge_f32_e64 s[6:7], 0, v24
	s_nop 1
	v_cndmask_b32_e64 v21, v21, v22, s[6:7]
	v_cmp_lt_f32_e64 s[6:7], 0, v25
	s_nop 1
	v_cndmask_b32_e64 v21, v21, v23, s[6:7]
	v_mul_f32_e32 v22, 0x37800000, v21
	v_cndmask_b32_e32 v21, v21, v22, vcc
	v_cmp_class_f32_e32 vcc, v20, v231
	s_nop 1
	v_cndmask_b32_e32 v20, v21, v20, vcc
	v_div_scale_f32 v21, s[6:7], v20, v20, 1.0
	v_rcp_f32_e32 v22, v21
	v_div_scale_f32 v23, vcc, 1.0, v20, 1.0
	v_fma_f32 v24, -v21, v22, 1.0
	v_fmac_f32_e32 v22, v24, v22
	v_mul_f32_e32 v24, v23, v22
	v_fma_f32 v25, -v21, v24, v23
	v_fmac_f32_e32 v24, v25, v22
	v_fma_f32 v21, -v21, v24, v23
	v_div_fmas_f32 v21, v21, v22, v24
	v_div_fixup_f32 v20, v21, v20, 1.0
	v_mul_f32_e32 v22, v14, v20
	v_mul_f32_e32 v23, v15, v20
	v_mul_f32_e32 v12, v12, v20
	v_mul_f32_e32 v13, v13, v20
	v_mul_f32_e32 v10, v10, v20
	v_mul_f32_e32 v11, v11, v20
	s_waitcnt vmcnt(0)
	v_mul_f32_e32 v14, v18, v12
	v_mul_f32_e32 v15, v19, v13
	v_mul_f32_e32 v12, v16, v22
	v_mul_f32_e32 v13, v17, v23
	global_store_dwordx4 v[114:115], v[12:15], off
	global_load_dwordx4 v[12:15], v[182:183], off offset:64
	v_mul_f32_e32 v8, v8, v20
	v_mul_f32_e32 v9, v9, v20
	v_mul_f32_e32 v6, v6, v20
	v_mul_f32_e32 v7, v7, v20
	v_mul_f32_e32 v4, v4, v20
	v_mul_f32_e32 v5, v5, v20
	v_mul_f32_e32 v2, v2, v20
	v_mul_f32_e32 v3, v3, v20
	v_mul_f32_e32 v0, v0, v20
	v_mul_f32_e32 v1, v1, v20
	s_and_b64 vcc, exec, s[4:5]
	s_mov_b64 s[4:5], -1
	s_waitcnt vmcnt(0)
	v_mul_f32_e32 v8, v12, v8
	v_mul_f32_e32 v9, v13, v9
	v_mul_f32_e32 v10, v14, v10
	v_mul_f32_e32 v11, v15, v11
	global_store_dwordx4 v[114:115], v[8:11], off offset:64
	global_load_dwordx4 v[8:11], v[182:183], off offset:512
	s_waitcnt vmcnt(0)
	v_mul_f32_e32 v4, v8, v4
	v_mul_f32_e32 v5, v9, v5
	v_mul_f32_e32 v6, v10, v6
	v_mul_f32_e32 v7, v11, v7
	global_store_dwordx4 v[114:115], v[4:7], off offset:512
	global_load_dwordx4 v[4:7], v[182:183], off offset:576
	s_waitcnt vmcnt(0)
	v_mul_f32_e32 v0, v4, v0
	v_mul_f32_e32 v1, v5, v1
	v_mul_f32_e32 v2, v6, v2
	v_mul_f32_e32 v3, v7, v3
	global_store_dwordx4 v[114:115], v[0:3], off offset:576
	s_cbranch_vccnz .LBB0_2049
	s_andn2_b64 vcc, exec, s[10:11]
	s_cbranch_vccnz .LBB0_2048
	s_barrier
	s_branch .LBB0_2048
